# HNAQP2S + removed the s_setprio 0 / s_setprio 1 toggle between the two 16-MFMA halves of every GEMM K-loop phase
# baseline (speedup 1.0000x reference)
; __device__ __forceinline__ float row_rstd(const float* ss, int row) { return 1.0f / sqrtf(ss[row] * (1.0f / DM) + 1e-6f); }
; #define PG8_STAGE(bufoff, gbase, voff) do { _Pragma("unroll") for (int _i = 0; _i < 2; ++_i) \
;         __builtin_amdgcn_global_load_lds((const unsigned*)((const char*)(gbase) + (voff)[_i]), (LAS unsigned*)(lds + (bufoff) + ldsw + _i * 8192), 16, 0, 0); } while (0)
; #define PG8_LDA(dst, b, h) do { _Pragma("unroll") for (int m = 0; m < 4; ++m) _Pragma("unroll") for (int k = 0; k < 2; ++k) dst[m][k] = *(const LAS bf16x8*)(lds + PG8_SA(b, h) + aoff + m * 2048 + k * 1024); } while (0)
; #define PG8_LDB(dst, b, h) do { _Pragma("unroll") for (int n = 0; n < 2; ++n) _Pragma("unroll") for (int k = 0; k < 2; ++k) dst[n][k] = *(const LAS bf16x8*)(lds + PG8_SB(b, h) + boff + n * 2048 + k * 1024); } while (0)
; #define PG8_WAIT_V(n) asm volatile("s_waitcnt vmcnt(" #n ")" ::: "memory")
; #define PG8_WAIT_L(n) asm volatile("s_waitcnt lgkmcnt(" #n ")" ::: "memory")
; #define PG8_BAR __builtin_amdgcn_s_barrier()
; #define PG8_SCHED __builtin_amdgcn_sched_barrier(0)
;     __device__ __forceinline__ void operator()(const f32x4 (&acc)[2][2][4][2], const Unit& u, int wr, int wc, int fr, int fq) const {
;         const int row0 = u.pm * BM + wr * 64 + fr, col0 = u.pn * HALF + wc * 32 + 8 * fq;
;         const int s = (u.pm < ML / BM) ? (u.pm >> 5) : 4;
;         const float* bp = bias + (size_t)s * BIAS_N + u.pn * BM + wc * 32 + 8 * fq;
;         const f32x4 ba0 = *(const f32x4*)bp, ba1 = *(const f32x4*)(bp + 4), bb0 = *(const f32x4*)(bp + HALF), bb1 = *(const f32x4*)(bp + HALF + 4);
;         const int lane = fq * 16 + fr;
;         const float rsl0 = row_rstd(ss, u.pm * BM + wr * 64 + lane), rsl1 = row_rstd(ss, u.pm * BM + HALF + wr * 64 + lane);
; template <class Epi, class Sched, bool ALIGN_EPI = false, bool SP2 = false>
; __device__ __forceinline__ void gemm_phase(LAS unsigned char* lds, const Gemm g, const Sched& S, const Epi& E) {
;     ...
;             PG8_LDB(B0, 0, 0); PG8_LDB(B1, 0, 1); PG8_SCHED; PG8_LDA(At, 0, 0); PG8_STAGE(PG8_SA(1, 1), a1 + hstep, voffA);
;             PG8_WAIT_V(8); PG8_WAIT_L(0); PG8_BAR; PG8_MMA(0, 0, At, B0); PG8_MMA(0, 1, At, B1); PG8_BAR; PG8_SCHED;
;             PG8_LDA(At, 0, 1); PG8_STAGE(PG8_SB(0, 0), b2, voffB); PG8_STAGE(PG8_SB(0, 1), b2 + hstepB, voffB); PG8_STAGE(PG8_SA(0, 0), a2, voffA);
.Lpre_up1l0:
	s_lshl_b64 s[98:99], s[98:99], 2
	s_add_u32 s98, s68, s98
	s_addc_u32 s99, s69, s99
	s_lshl_b32 s100, s0, 8
	s_ashr_i32 s101, s100, 31
	s_lshl_b64 s[100:101], s[100:101], 2
	s_add_u32 s98, s98, s100
	s_addc_u32 s99, s99, s101
	s_add_u32 s98, s98, s60
	s_addc_u32 s99, s99, 0
	s_lshl_b32 s100, s2, 8
	s_add_i32 s100, s100, s54
	v_or_b32_e32 v162, s100, v171
	v_ashrrev_i32_e32 v163, 31, v162
	v_lshl_add_u64 v[162:163], v[162:163], 2, s[8:9]
	v_add_u32_e32 v164, s100, v172
	v_ashrrev_i32_e32 v165, 31, v164
	v_lshl_add_u64 v[164:165], v[164:165], 2, s[8:9]
	global_load_dwordx4 v[234:237], v177, s[98:99] offset:16
	global_load_dwordx4 v[238:241], v177, s[98:99]
	global_load_dwordx4 v[242:245], v177, s[98:99] offset:528
	global_load_dwordx4 v[246:249], v177, s[98:99] offset:512
	global_load_dword v250, v[162:163], off
	global_load_dword v251, v[164:165], off
	ds_read_b128 v[66:69], v174
	ds_read_b128 v[70:73], v174 offset:1024
	ds_read_b128 v[74:77], v174 offset:2048
	ds_read_b128 v[78:81], v174 offset:3072
	ds_read_b128 v[162:165], v175
	ds_read_b128 v[182:185], v175 offset:1024
	ds_read_b128 v[186:189], v175 offset:2048
	ds_read_b128 v[190:193], v175 offset:3072
	s_add_u32 s20, s16, 0xfff80080
	s_addc_u32 s21, s17, -1
	s_cmp_eq_u32 s19, 28
	s_cselect_b32 s53, s3, s21
	s_cselect_b32 s52, s12, s20
	s_cselect_b32 s51, s13, s18
	s_cselect_b32 s50, s14, s15
	v_lshl_add_u64 v[166:167], s[16:17], 0, v[154:155]
	s_add_i32 m0, s33, 0xc000
	ds_read_b128 v[194:197], v176
	ds_read_b128 v[198:201], v176 offset:1024
	ds_read_b128 v[202:205], v176 offset:2048
	ds_read_b128 v[206:209], v176 offset:3072
	ds_read_b128 v[210:213], v176 offset:4096
	ds_read_b128 v[214:217], v176 offset:5120
	ds_read_b128 v[218:221], v176 offset:6144
	ds_read_b128 v[222:225], v176 offset:7168
	global_load_lds_dwordx4 v[166:167], off
	v_lshl_add_u64 v[166:167], s[16:17], 0, v[156:157]
	s_add_i32 m0, s33, 0xe000
	s_nop 0
	global_load_lds_dwordx4 v[166:167], off
	s_waitcnt lgkmcnt(0)
	s_barrier
	s_setprio 1
	s_waitcnt lgkmcnt(0)
	v_mfma_f32_16x16x32_bf16 v[142:145], v[66:69], v[194:197], 0
	v_mfma_f32_16x16x32_bf16 v[138:141], v[74:77], v[194:197], 0
	v_mfma_f32_16x16x32_bf16 v[126:129], v[66:69], v[202:205], 0
	v_mfma_f32_16x16x32_bf16 v[122:125], v[74:77], v[202:205], 0
	v_mfma_f32_16x16x32_bf16 v[110:113], v[66:69], v[210:213], 0
	v_mfma_f32_16x16x32_bf16 v[106:109], v[74:77], v[210:213], 0
	v_mfma_f32_16x16x32_bf16 v[94:97], v[66:69], v[218:221], 0
	v_mfma_f32_16x16x32_bf16 v[90:93], v[74:77], v[218:221], 0
	v_mfma_f32_16x16x32_bf16 v[142:145], v[70:73], v[198:201], v[142:145]
	v_mfma_f32_16x16x32_bf16 v[138:141], v[78:81], v[198:201], v[138:141]
	v_mfma_f32_16x16x32_bf16 v[126:129], v[70:73], v[206:209], v[126:129]
	v_mfma_f32_16x16x32_bf16 v[122:125], v[78:81], v[206:209], v[122:125]
	v_mfma_f32_16x16x32_bf16 v[110:113], v[70:73], v[214:217], v[110:113]
	v_mfma_f32_16x16x32_bf16 v[106:109], v[78:81], v[214:217], v[106:109]
	v_mfma_f32_16x16x32_bf16 v[94:97], v[70:73], v[222:225], v[94:97]
	v_mfma_f32_16x16x32_bf16 v[90:93], v[78:81], v[222:225], v[90:93]
	v_mfma_f32_16x16x32_bf16 v[134:137], v[162:165], v[194:197], 0
	v_mfma_f32_16x16x32_bf16 v[130:133], v[186:189], v[194:197], 0
	v_mfma_f32_16x16x32_bf16 v[118:121], v[162:165], v[202:205], 0
	v_mfma_f32_16x16x32_bf16 v[114:117], v[186:189], v[202:205], 0
	v_mfma_f32_16x16x32_bf16 v[102:105], v[162:165], v[210:213], 0
	v_mfma_f32_16x16x32_bf16 v[98:101], v[186:189], v[210:213], 0
	v_mfma_f32_16x16x32_bf16 v[86:89], v[162:165], v[218:221], 0
	v_mfma_f32_16x16x32_bf16 v[82:85], v[186:189], v[218:221], 0
	v_mfma_f32_16x16x32_bf16 v[134:137], v[182:185], v[198:201], v[134:137]
	v_mfma_f32_16x16x32_bf16 v[130:133], v[190:193], v[198:201], v[130:133]
	v_mfma_f32_16x16x32_bf16 v[118:121], v[182:185], v[206:209], v[118:121]
	v_mfma_f32_16x16x32_bf16 v[114:117], v[190:193], v[206:209], v[114:117]
	v_mfma_f32_16x16x32_bf16 v[102:105], v[182:185], v[214:217], v[102:105]
	v_mfma_f32_16x16x32_bf16 v[98:101], v[190:193], v[214:217], v[98:101]
	v_mfma_f32_16x16x32_bf16 v[86:89], v[182:185], v[222:225], v[86:89]
	v_mfma_f32_16x16x32_bf16 v[82:85], v[190:193], v[222:225], v[82:85]
	s_setprio 0
	s_barrier
	s_add_i32 s20, s57, s27
	v_lshl_add_u64 v[166:167], s[50:51], 0, v[150:151]
	s_mov_b32 m0, s20
	ds_read_b128 v[194:197], v176 offset:16384
	ds_read_b128 v[198:201], v176 offset:17408
	ds_read_b128 v[202:205], v176 offset:18432
	ds_read_b128 v[206:209], v176 offset:19456
	ds_read_b128 v[210:213], v176 offset:20480
	ds_read_b128 v[214:217], v176 offset:21504
	ds_read_b128 v[218:221], v176 offset:22528
	ds_read_b128 v[222:225], v176 offset:23552
	global_load_lds_dwordx4 v[166:167], off
	s_add_i32 m0, s20, 0x2000
	s_add_u32 s20, s50, 0x80000
	v_lshl_add_u64 v[226:227], s[50:51], 0, v[146:147]
	s_addc_u32 s21, s51, 0
	s_add_i32 s22, s58, s27
	global_load_lds_dwordx4 v[226:227], off
	v_lshl_add_u64 v[228:229], s[20:21], 0, v[150:151]
	s_mov_b32 m0, s22
	v_lshl_add_u64 v[230:231], s[52:53], 0, v[148:149]
	global_load_lds_dwordx4 v[228:229], off
	v_lshl_add_u64 v[228:229], s[20:21], 0, v[146:147]
	s_add_i32 m0, s22, 0x2000
	s_nop 0
	global_load_lds_dwordx4 v[228:229], off
	v_lshl_add_u64 v[228:229], s[52:53], 0, v[152:153]
	s_mov_b32 m0, s33
	s_nop 0
	global_load_lds_dwordx4 v[228:229], off
	s_mov_b32 m0, s34
	s_nop 0
	global_load_lds_dwordx4 v[230:231], off
	s_waitcnt lgkmcnt(0)
	s_barrier
; #define PG8_STAGE(bufoff, gbase, voff) do { _Pragma("unroll") for (int _i = 0; _i < 2; ++_i) \
;         __builtin_amdgcn_global_load_lds((const unsigned*)((const char*)(gbase) + (voff)[_i]), (LAS unsigned*)(lds + (bufoff) + ldsw + _i * 8192), 16, 0, 0); } while (0)
; #define PG8_LDA(dst, b, h) do { _Pragma("unroll") for (int m = 0; m < 4; ++m) _Pragma("unroll") for (int k = 0; k < 2; ++k) dst[m][k] = *(const LAS bf16x8*)(lds + PG8_SA(b, h) + aoff + m * 2048 + k * 1024); } while (0)
; #define PG8_LDB(dst, b, h) do { _Pragma("unroll") for (int n = 0; n < 2; ++n) _Pragma("unroll") for (int k = 0; k < 2; ++k) dst[n][k] = *(const LAS bf16x8*)(lds + PG8_SB(b, h) + boff + n * 2048 + k * 1024); } while (0)
; #define PG8_MMA(ai, bj, At, Bt) do { __builtin_amdgcn_s_setprio(1); _Pragma("unroll") for (int m = 0; m < 4; ++m) _Pragma("unroll") for (int n = 0; n < 2; ++n) _Pragma("unroll") for (int k = 0; k < 2; ++k) \
;         acc[ai][bj][m][n] = __builtin_amdgcn_mfma_f32_16x16x32_bf16(Bt[n][k], At[m][k], acc[ai][bj][m][n], 0, 0, 0); __builtin_amdgcn_s_setprio(0); } while (0)
; #define PG8_WAIT_V(n) asm volatile("s_waitcnt vmcnt(" #n ")" ::: "memory")
; #define PG8_WAIT_L(n) asm volatile("s_waitcnt lgkmcnt(" #n ")" ::: "memory")
; #define PG8_BAR __builtin_amdgcn_s_barrier()
; #define PG8_SCHED __builtin_amdgcn_sched_barrier(0)
; template <class Epi, class Sched, bool ALIGN_EPI = false, bool SP2 = false>
; __device__ __forceinline__ void gemm_phase(LAS unsigned char* lds, const Gemm g, const Sched& S, const Epi& E) {
;     ...
;             PG8_WAIT_V(8); PG8_WAIT_L(0); PG8_BAR; PG8_MMA(1, 0, At, B0); PG8_MMA(1, 1, At, B1); PG8_BAR; PG8_SCHED;
;             PG8_LDB(B0, 1, 0); PG8_LDB(B1, 1, 1); PG8_SCHED; PG8_LDA(At, 1, 0); PG8_STAGE(PG8_SA(0, 1), a2 + hstep, voffA);
;             PG8_WAIT_V(8); PG8_WAIT_L(0); PG8_BAR; PG8_MMA(0, 0, At, B0); PG8_MMA(0, 1, At, B1); PG8_BAR; PG8_SCHED;
	s_setprio 1
	s_waitcnt lgkmcnt(0)
	v_mfma_f32_16x16x32_bf16 v[62:65], v[66:69], v[194:197], 0
	v_mfma_f32_16x16x32_bf16 v[58:61], v[74:77], v[194:197], 0
	v_mfma_f32_16x16x32_bf16 v[46:49], v[66:69], v[202:205], 0
	v_mfma_f32_16x16x32_bf16 v[42:45], v[74:77], v[202:205], 0
	v_mfma_f32_16x16x32_bf16 v[30:33], v[66:69], v[210:213], 0
	v_mfma_f32_16x16x32_bf16 v[26:29], v[74:77], v[210:213], 0
	v_mfma_f32_16x16x32_bf16 v[14:17], v[66:69], v[218:221], 0
	v_mfma_f32_16x16x32_bf16 v[10:13], v[74:77], v[218:221], 0
	v_mfma_f32_16x16x32_bf16 v[62:65], v[70:73], v[198:201], v[62:65]
	v_mfma_f32_16x16x32_bf16 v[58:61], v[78:81], v[198:201], v[58:61]
	v_mfma_f32_16x16x32_bf16 v[46:49], v[70:73], v[206:209], v[46:49]
	v_mfma_f32_16x16x32_bf16 v[42:45], v[78:81], v[206:209], v[42:45]
	v_mfma_f32_16x16x32_bf16 v[30:33], v[70:73], v[214:217], v[30:33]
	v_mfma_f32_16x16x32_bf16 v[26:29], v[78:81], v[214:217], v[26:29]
	v_mfma_f32_16x16x32_bf16 v[14:17], v[70:73], v[222:225], v[14:17]
	v_mfma_f32_16x16x32_bf16 v[10:13], v[78:81], v[222:225], v[10:13]
	v_mfma_f32_16x16x32_bf16 v[54:57], v[162:165], v[194:197], 0
	v_mfma_f32_16x16x32_bf16 v[50:53], v[186:189], v[194:197], 0
	v_mfma_f32_16x16x32_bf16 v[38:41], v[162:165], v[202:205], 0
	v_mfma_f32_16x16x32_bf16 v[34:37], v[186:189], v[202:205], 0
	v_mfma_f32_16x16x32_bf16 v[22:25], v[162:165], v[210:213], 0
	v_mfma_f32_16x16x32_bf16 v[18:21], v[186:189], v[210:213], 0
	v_mfma_f32_16x16x32_bf16 v[6:9], v[162:165], v[218:221], 0
	v_mfma_f32_16x16x32_bf16 v[2:5], v[186:189], v[218:221], 0
	v_mfma_f32_16x16x32_bf16 v[54:57], v[182:185], v[198:201], v[54:57]
	v_mfma_f32_16x16x32_bf16 v[50:53], v[190:193], v[198:201], v[50:53]
	v_mfma_f32_16x16x32_bf16 v[38:41], v[182:185], v[206:209], v[38:41]
	v_mfma_f32_16x16x32_bf16 v[34:37], v[190:193], v[206:209], v[34:37]
	v_mfma_f32_16x16x32_bf16 v[22:25], v[182:185], v[214:217], v[22:25]
	v_mfma_f32_16x16x32_bf16 v[18:21], v[190:193], v[214:217], v[18:21]
	v_mfma_f32_16x16x32_bf16 v[6:9], v[182:185], v[222:225], v[6:9]
	v_mfma_f32_16x16x32_bf16 v[2:5], v[190:193], v[222:225], v[2:5]
	s_setprio 0
	s_barrier
	s_add_i32 s22, 0, 0x18000
	s_add_i32 s23, 0, 0x1c000
	v_add_u32_e32 v78, s22, v170
	v_add_u32_e32 v168, s23, v170
	ds_read_b128 v[66:69], v78
	ds_read_b128 v[70:73], v78 offset:1024
	ds_read_b128 v[74:77], v78 offset:2048
	ds_read_b128 v[78:81], v78 offset:3072
	ds_read_b128 v[162:165], v168
	ds_read_b128 v[182:185], v168 offset:1024
	ds_read_b128 v[186:189], v168 offset:2048
	ds_read_b128 v[190:193], v168 offset:3072
	s_add_u32 s20, s52, 0x80000
	s_addc_u32 s21, s53, 0
	s_mov_b32 m0, s35
	v_lshl_add_u64 v[232:233], s[20:21], 0, v[152:153]
	ds_read_b128 v[194:197], v176 offset:32768
	ds_read_b128 v[198:201], v176 offset:33792
	ds_read_b128 v[202:205], v176 offset:34816
	ds_read_b128 v[206:209], v176 offset:35840
	ds_read_b128 v[210:213], v176 offset:36864
	ds_read_b128 v[214:217], v176 offset:37888
	ds_read_b128 v[218:221], v176 offset:38912
	ds_read_b128 v[222:225], v176 offset:39936
	global_load_lds_dwordx4 v[232:233], off
	v_lshl_add_u64 v[232:233], s[20:21], 0, v[148:149]
	s_mov_b32 m0, s36
	s_nop 0
	global_load_lds_dwordx4 v[232:233], off
	s_waitcnt vmcnt(8)
	s_waitcnt lgkmcnt(0)
	s_barrier
	s_setprio 1
	s_waitcnt lgkmcnt(0)
	v_mfma_f32_16x16x32_bf16 v[142:145], v[66:69], v[194:197], v[142:145]
	v_mfma_f32_16x16x32_bf16 v[138:141], v[74:77], v[194:197], v[138:141]
	v_mfma_f32_16x16x32_bf16 v[126:129], v[66:69], v[202:205], v[126:129]
	v_mfma_f32_16x16x32_bf16 v[122:125], v[74:77], v[202:205], v[122:125]
	v_mfma_f32_16x16x32_bf16 v[110:113], v[66:69], v[210:213], v[110:113]
	v_mfma_f32_16x16x32_bf16 v[106:109], v[74:77], v[210:213], v[106:109]
	v_mfma_f32_16x16x32_bf16 v[94:97], v[66:69], v[218:221], v[94:97]
	v_mfma_f32_16x16x32_bf16 v[90:93], v[74:77], v[218:221], v[90:93]
	v_mfma_f32_16x16x32_bf16 v[142:145], v[70:73], v[198:201], v[142:145]
	v_mfma_f32_16x16x32_bf16 v[138:141], v[78:81], v[198:201], v[138:141]
	v_mfma_f32_16x16x32_bf16 v[126:129], v[70:73], v[206:209], v[126:129]
	v_mfma_f32_16x16x32_bf16 v[122:125], v[78:81], v[206:209], v[122:125]
	v_mfma_f32_16x16x32_bf16 v[110:113], v[70:73], v[214:217], v[110:113]
	v_mfma_f32_16x16x32_bf16 v[106:109], v[78:81], v[214:217], v[106:109]
	v_mfma_f32_16x16x32_bf16 v[94:97], v[70:73], v[222:225], v[94:97]
	v_mfma_f32_16x16x32_bf16 v[90:93], v[78:81], v[222:225], v[90:93]
	v_mfma_f32_16x16x32_bf16 v[134:137], v[162:165], v[194:197], v[134:137]
	v_mfma_f32_16x16x32_bf16 v[130:133], v[186:189], v[194:197], v[130:133]
	v_mfma_f32_16x16x32_bf16 v[118:121], v[162:165], v[202:205], v[118:121]
	v_mfma_f32_16x16x32_bf16 v[114:117], v[186:189], v[202:205], v[114:117]
	v_mfma_f32_16x16x32_bf16 v[102:105], v[162:165], v[210:213], v[102:105]
	v_mfma_f32_16x16x32_bf16 v[98:101], v[186:189], v[210:213], v[98:101]
	v_mfma_f32_16x16x32_bf16 v[86:89], v[162:165], v[218:221], v[86:89]
	v_mfma_f32_16x16x32_bf16 v[82:85], v[186:189], v[218:221], v[82:85]
	v_mfma_f32_16x16x32_bf16 v[134:137], v[182:185], v[198:201], v[134:137]
	v_mfma_f32_16x16x32_bf16 v[130:133], v[190:193], v[198:201], v[130:133]
	v_mfma_f32_16x16x32_bf16 v[118:121], v[182:185], v[206:209], v[118:121]
	v_mfma_f32_16x16x32_bf16 v[114:117], v[190:193], v[206:209], v[114:117]
	v_mfma_f32_16x16x32_bf16 v[102:105], v[182:185], v[214:217], v[102:105]
	v_mfma_f32_16x16x32_bf16 v[98:101], v[190:193], v[214:217], v[98:101]
	v_mfma_f32_16x16x32_bf16 v[86:89], v[182:185], v[222:225], v[86:89]
	v_mfma_f32_16x16x32_bf16 v[82:85], v[190:193], v[222:225], v[82:85]
	s_setprio 0
	s_barrier
; #define PG8_STAGE(bufoff, gbase, voff) do { _Pragma("unroll") for (int _i = 0; _i < 2; ++_i) \
;         __builtin_amdgcn_global_load_lds((const unsigned*)((const char*)(gbase) + (voff)[_i]), (LAS unsigned*)(lds + (bufoff) + ldsw + _i * 8192), 16, 0, 0); } while (0)
; #define PG8_LDA(dst, b, h) do { _Pragma("unroll") for (int m = 0; m < 4; ++m) _Pragma("unroll") for (int k = 0; k < 2; ++k) dst[m][k] = *(const LAS bf16x8*)(lds + PG8_SA(b, h) + aoff + m * 2048 + k * 1024); } while (0)
; #define PG8_LDB(dst, b, h) do { _Pragma("unroll") for (int n = 0; n < 2; ++n) _Pragma("unroll") for (int k = 0; k < 2; ++k) dst[n][k] = *(const LAS bf16x8*)(lds + PG8_SB(b, h) + boff + n * 2048 + k * 1024); } while (0)
; #define PG8_MMA(ai, bj, At, Bt) do { __builtin_amdgcn_s_setprio(1); _Pragma("unroll") for (int m = 0; m < 4; ++m) _Pragma("unroll") for (int n = 0; n < 2; ++n) _Pragma("unroll") for (int k = 0; k < 2; ++k) \
;         acc[ai][bj][m][n] = __builtin_amdgcn_mfma_f32_16x16x32_bf16(Bt[n][k], At[m][k], acc[ai][bj][m][n], 0, 0, 0); __builtin_amdgcn_s_setprio(0); } while (0)
; #define PG8_WAIT_V(n) asm volatile("s_waitcnt vmcnt(" #n ")" ::: "memory")
; #define PG8_WAIT_L(n) asm volatile("s_waitcnt lgkmcnt(" #n ")" ::: "memory")
; #define PG8_BAR __builtin_amdgcn_s_barrier()
; #define PG8_SCHED __builtin_amdgcn_sched_barrier(0)
; template <class Epi, class Sched, bool ALIGN_EPI = false, bool SP2 = false>
; __device__ __forceinline__ void gemm_phase(LAS unsigned char* lds, const Gemm g, const Sched& S, const Epi& E) {
;     ...
;         for (int t = 0; t < nt; t += 2) {
;             const bool last = (t == nt - 2);
;             const char* a1 = cA + (size_t)(t + 1) * kstep;
;             const char* a2 = last ? nA : cA + (size_t)(t + 2) * kstep; const char* b2 = last ? nB : cB + (size_t)(t + 2) * kstep;
;             const char* a3 = a2 + kstep; const char* b3 = b2 + kstep;
;             if (last && has_next) S.a_ready(nxt);
;             if constexpr (SP2) {
;             PG8_LDB(B0, 0, 0); PG8_LDB(B1, 0, 1); PG8_SCHED; PG8_LDA(At, 0, 0); PG8_STAGE(PG8_SA(1, 1), a1 + hstep, voffA);
;     ...
;             PG8_LDA(At, 1, 1); PG8_STAGE(PG8_SB(1, 0), b3, voffB); PG8_STAGE(PG8_SB(1, 1), b3 + hstepB, voffB); PG8_STAGE(PG8_SA(1, 0), a3, voffA);
;             PG8_WAIT_V(8); PG8_WAIT_L(0); PG8_BAR; PG8_MMA(1, 0, At, B0); PG8_MMA(1, 1, At, B1); PG8_BAR; PG8_SCHED;
	s_add_i32 s20, s22, s27
	v_lshl_add_u64 v[166:167], v[166:167], 0, s[10:11]
	s_mov_b32 m0, s20
	ds_read_b128 v[194:197], v176 offset:49152
	ds_read_b128 v[198:201], v176 offset:50176
	ds_read_b128 v[202:205], v176 offset:51200
	ds_read_b128 v[206:209], v176 offset:52224
	ds_read_b128 v[210:213], v176 offset:53248
	ds_read_b128 v[214:217], v176 offset:54272
	ds_read_b128 v[218:221], v176 offset:55296
	ds_read_b128 v[222:225], v176 offset:56320
	global_load_lds_dwordx4 v[166:167], off
	s_add_i32 m0, s20, 0x2000
	s_add_u32 s20, s50, 0x80080
	v_lshl_add_u64 v[166:167], v[226:227], 0, s[10:11]
	s_addc_u32 s21, s51, 0
	s_add_i32 s22, s23, s27
	global_load_lds_dwordx4 v[166:167], off
	v_lshl_add_u64 v[166:167], s[20:21], 0, v[150:151]
	s_mov_b32 m0, s22
	s_nop 0
	global_load_lds_dwordx4 v[166:167], off
	v_lshl_add_u64 v[166:167], s[20:21], 0, v[146:147]
	s_add_i32 m0, s22, 0x2000
	s_nop 0
	global_load_lds_dwordx4 v[166:167], off
	v_lshl_add_u64 v[166:167], v[228:229], 0, s[10:11]
	s_mov_b32 m0, s55
	s_nop 0
	global_load_lds_dwordx4 v[166:167], off
	v_lshl_add_u64 v[166:167], v[230:231], 0, s[10:11]
	s_mov_b32 m0, s56
	s_nop 0
	global_load_lds_dwordx4 v[166:167], off
	s_waitcnt vmcnt(8)
	s_waitcnt lgkmcnt(0)
	s_barrier
	s_setprio 1
	s_waitcnt lgkmcnt(0)
	v_mfma_f32_16x16x32_bf16 v[62:65], v[66:69], v[194:197], v[62:65]
	v_mfma_f32_16x16x32_bf16 v[58:61], v[74:77], v[194:197], v[58:61]
	v_mfma_f32_16x16x32_bf16 v[46:49], v[66:69], v[202:205], v[46:49]
	v_mfma_f32_16x16x32_bf16 v[42:45], v[74:77], v[202:205], v[42:45]
	v_mfma_f32_16x16x32_bf16 v[30:33], v[66:69], v[210:213], v[30:33]
	v_mfma_f32_16x16x32_bf16 v[26:29], v[74:77], v[210:213], v[26:29]
	v_mfma_f32_16x16x32_bf16 v[14:17], v[66:69], v[218:221], v[14:17]
	v_mfma_f32_16x16x32_bf16 v[10:13], v[74:77], v[218:221], v[10:13]
	v_mfma_f32_16x16x32_bf16 v[62:65], v[70:73], v[198:201], v[62:65]
	v_mfma_f32_16x16x32_bf16 v[58:61], v[78:81], v[198:201], v[58:61]
	v_mfma_f32_16x16x32_bf16 v[46:49], v[70:73], v[206:209], v[46:49]
	v_mfma_f32_16x16x32_bf16 v[42:45], v[78:81], v[206:209], v[42:45]
	v_mfma_f32_16x16x32_bf16 v[30:33], v[70:73], v[214:217], v[30:33]
	v_mfma_f32_16x16x32_bf16 v[26:29], v[78:81], v[214:217], v[26:29]
	v_mfma_f32_16x16x32_bf16 v[14:17], v[70:73], v[222:225], v[14:17]
	v_mfma_f32_16x16x32_bf16 v[10:13], v[78:81], v[222:225], v[10:13]
	v_mfma_f32_16x16x32_bf16 v[54:57], v[162:165], v[194:197], v[54:57]
	v_mfma_f32_16x16x32_bf16 v[50:53], v[186:189], v[194:197], v[50:53]
	v_mfma_f32_16x16x32_bf16 v[38:41], v[162:165], v[202:205], v[38:41]
	v_mfma_f32_16x16x32_bf16 v[34:37], v[186:189], v[202:205], v[34:37]
	v_mfma_f32_16x16x32_bf16 v[22:25], v[162:165], v[210:213], v[22:25]
	v_mfma_f32_16x16x32_bf16 v[18:21], v[186:189], v[210:213], v[18:21]
	v_mfma_f32_16x16x32_bf16 v[6:9], v[162:165], v[218:221], v[6:9]
	v_mfma_f32_16x16x32_bf16 v[2:5], v[186:189], v[218:221], v[2:5]
	v_mfma_f32_16x16x32_bf16 v[54:57], v[182:185], v[198:201], v[54:57]
	v_mfma_f32_16x16x32_bf16 v[50:53], v[190:193], v[198:201], v[50:53]
	v_mfma_f32_16x16x32_bf16 v[38:41], v[182:185], v[206:209], v[38:41]
	v_mfma_f32_16x16x32_bf16 v[34:37], v[190:193], v[206:209], v[34:37]
	v_mfma_f32_16x16x32_bf16 v[22:25], v[182:185], v[214:217], v[22:25]
	v_mfma_f32_16x16x32_bf16 v[18:21], v[190:193], v[214:217], v[18:21]
	v_mfma_f32_16x16x32_bf16 v[6:9], v[182:185], v[222:225], v[6:9]
	v_mfma_f32_16x16x32_bf16 v[2:5], v[190:193], v[222:225], v[2:5]
	s_setprio 0
	s_barrier
	s_add_i32 s19, s19, 2
	s_add_u32 s16, s16, 0x100
	s_addc_u32 s17, s17, 0
	s_add_u32 s15, s15, 0x100
	s_addc_u32 s18, s18, 0
	s_cmp_gt_u32 s19, 29
.LBB0_188:
	ds_read_b128 v[66:69], v174
	ds_read_b128 v[70:73], v174 offset:1024
	ds_read_b128 v[74:77], v174 offset:2048
	ds_read_b128 v[78:81], v174 offset:3072
	ds_read_b128 v[162:165], v175
	ds_read_b128 v[182:185], v175 offset:1024
	ds_read_b128 v[186:189], v175 offset:2048
	ds_read_b128 v[190:193], v175 offset:3072
	s_add_u32 s20, s16, 0xfff80080
	s_addc_u32 s21, s17, -1
	s_cmp_eq_u32 s19, 28
	s_cselect_b32 s53, s3, s21
	s_cselect_b32 s52, s12, s20
	s_cselect_b32 s51, s13, s18
	s_cselect_b32 s50, s14, s15
	v_lshl_add_u64 v[166:167], s[16:17], 0, v[154:155]
	s_add_i32 m0, s33, 0xc000
	ds_read_b128 v[194:197], v176
	ds_read_b128 v[198:201], v176 offset:1024
	ds_read_b128 v[202:205], v176 offset:2048
	ds_read_b128 v[206:209], v176 offset:3072
	ds_read_b128 v[210:213], v176 offset:4096
	ds_read_b128 v[214:217], v176 offset:5120
	ds_read_b128 v[218:221], v176 offset:6144
	ds_read_b128 v[222:225], v176 offset:7168
	global_load_lds_dwordx4 v[166:167], off
	v_lshl_add_u64 v[166:167], s[16:17], 0, v[156:157]
	s_add_i32 m0, s33, 0xe000
	s_nop 0
	global_load_lds_dwordx4 v[166:167], off
	s_waitcnt vmcnt(8)
	s_waitcnt lgkmcnt(0)
	s_barrier
; #define PG8_STAGE(bufoff, gbase, voff) do { _Pragma("unroll") for (int _i = 0; _i < 2; ++_i) \
;         __builtin_amdgcn_global_load_lds((const unsigned*)((const char*)(gbase) + (voff)[_i]), (LAS unsigned*)(lds + (bufoff) + ldsw + _i * 8192), 16, 0, 0); } while (0)
; #define PG8_LDA(dst, b, h) do { _Pragma("unroll") for (int m = 0; m < 4; ++m) _Pragma("unroll") for (int k = 0; k < 2; ++k) dst[m][k] = *(const LAS bf16x8*)(lds + PG8_SA(b, h) + aoff + m * 2048 + k * 1024); } while (0)
; #define PG8_MMA(ai, bj, At, Bt) do { __builtin_amdgcn_s_setprio(1); _Pragma("unroll") for (int m = 0; m < 4; ++m) _Pragma("unroll") for (int n = 0; n < 2; ++n) _Pragma("unroll") for (int k = 0; k < 2; ++k) \
;         acc[ai][bj][m][n] = __builtin_amdgcn_mfma_f32_16x16x32_bf16(Bt[n][k], At[m][k], acc[ai][bj][m][n], 0, 0, 0); __builtin_amdgcn_s_setprio(0); } while (0)
; #define PG8_WAIT_V(n) asm volatile("s_waitcnt vmcnt(" #n ")" ::: "memory")
; #define PG8_WAIT_L(n) asm volatile("s_waitcnt lgkmcnt(" #n ")" ::: "memory")
; #define PG8_BAR __builtin_amdgcn_s_barrier()
; #define PG8_SCHED __builtin_amdgcn_sched_barrier(0)
; template <class Epi, class Sched, bool ALIGN_EPI = false, bool SP2 = false>
; __device__ __forceinline__ void gemm_phase(LAS unsigned char* lds, const Gemm g, const Sched& S, const Epi& E) {
;     ...
;             PG8_WAIT_V(8); PG8_WAIT_L(0); PG8_BAR; PG8_MMA(0, 0, At, B0); PG8_MMA(0, 1, At, B1); PG8_BAR; PG8_SCHED;
;             PG8_LDA(At, 0, 1); PG8_STAGE(PG8_SB(0, 0), b2, voffB); PG8_STAGE(PG8_SB(0, 1), b2 + hstepB, voffB); PG8_STAGE(PG8_SA(0, 0), a2, voffA);
;             PG8_WAIT_V(8); PG8_WAIT_L(0); PG8_BAR; PG8_MMA(1, 0, At, B0); PG8_MMA(1, 1, At, B1); PG8_BAR; PG8_SCHED;
	s_setprio 1
	s_waitcnt lgkmcnt(0)
	v_mfma_f32_16x16x32_bf16 v[142:145], v[66:69], v[194:197], v[142:145]
	v_mfma_f32_16x16x32_bf16 v[138:141], v[74:77], v[194:197], v[138:141]
	v_mfma_f32_16x16x32_bf16 v[126:129], v[66:69], v[202:205], v[126:129]
	v_mfma_f32_16x16x32_bf16 v[122:125], v[74:77], v[202:205], v[122:125]
	v_mfma_f32_16x16x32_bf16 v[110:113], v[66:69], v[210:213], v[110:113]
	v_mfma_f32_16x16x32_bf16 v[106:109], v[74:77], v[210:213], v[106:109]
	v_mfma_f32_16x16x32_bf16 v[94:97], v[66:69], v[218:221], v[94:97]
	v_mfma_f32_16x16x32_bf16 v[90:93], v[74:77], v[218:221], v[90:93]
	v_mfma_f32_16x16x32_bf16 v[142:145], v[70:73], v[198:201], v[142:145]
	v_mfma_f32_16x16x32_bf16 v[138:141], v[78:81], v[198:201], v[138:141]
	v_mfma_f32_16x16x32_bf16 v[126:129], v[70:73], v[206:209], v[126:129]
	v_mfma_f32_16x16x32_bf16 v[122:125], v[78:81], v[206:209], v[122:125]
	v_mfma_f32_16x16x32_bf16 v[110:113], v[70:73], v[214:217], v[110:113]
	v_mfma_f32_16x16x32_bf16 v[106:109], v[78:81], v[214:217], v[106:109]
	v_mfma_f32_16x16x32_bf16 v[94:97], v[70:73], v[222:225], v[94:97]
	v_mfma_f32_16x16x32_bf16 v[90:93], v[78:81], v[222:225], v[90:93]
	v_mfma_f32_16x16x32_bf16 v[134:137], v[162:165], v[194:197], v[134:137]
	v_mfma_f32_16x16x32_bf16 v[130:133], v[186:189], v[194:197], v[130:133]
	v_mfma_f32_16x16x32_bf16 v[118:121], v[162:165], v[202:205], v[118:121]
	v_mfma_f32_16x16x32_bf16 v[114:117], v[186:189], v[202:205], v[114:117]
	v_mfma_f32_16x16x32_bf16 v[102:105], v[162:165], v[210:213], v[102:105]
	v_mfma_f32_16x16x32_bf16 v[98:101], v[186:189], v[210:213], v[98:101]
	v_mfma_f32_16x16x32_bf16 v[86:89], v[162:165], v[218:221], v[86:89]
	v_mfma_f32_16x16x32_bf16 v[82:85], v[186:189], v[218:221], v[82:85]
	v_mfma_f32_16x16x32_bf16 v[134:137], v[182:185], v[198:201], v[134:137]
	v_mfma_f32_16x16x32_bf16 v[130:133], v[190:193], v[198:201], v[130:133]
	v_mfma_f32_16x16x32_bf16 v[118:121], v[182:185], v[206:209], v[118:121]
	v_mfma_f32_16x16x32_bf16 v[114:117], v[190:193], v[206:209], v[114:117]
	v_mfma_f32_16x16x32_bf16 v[102:105], v[182:185], v[214:217], v[102:105]
	v_mfma_f32_16x16x32_bf16 v[98:101], v[190:193], v[214:217], v[98:101]
	v_mfma_f32_16x16x32_bf16 v[86:89], v[182:185], v[222:225], v[86:89]
	v_mfma_f32_16x16x32_bf16 v[82:85], v[190:193], v[222:225], v[82:85]
	s_setprio 0
	s_barrier
	s_add_i32 s20, s57, s27
	v_lshl_add_u64 v[166:167], s[50:51], 0, v[150:151]
	s_mov_b32 m0, s20
	ds_read_b128 v[194:197], v176 offset:16384
	ds_read_b128 v[198:201], v176 offset:17408
	ds_read_b128 v[202:205], v176 offset:18432
	ds_read_b128 v[206:209], v176 offset:19456
	ds_read_b128 v[210:213], v176 offset:20480
	ds_read_b128 v[214:217], v176 offset:21504
	ds_read_b128 v[218:221], v176 offset:22528
	ds_read_b128 v[222:225], v176 offset:23552
	global_load_lds_dwordx4 v[166:167], off
	s_add_i32 m0, s20, 0x2000
	s_add_u32 s20, s50, 0x80000
	v_lshl_add_u64 v[226:227], s[50:51], 0, v[146:147]
	s_addc_u32 s21, s51, 0
	s_add_i32 s22, s58, s27
	global_load_lds_dwordx4 v[226:227], off
	v_lshl_add_u64 v[228:229], s[20:21], 0, v[150:151]
	s_mov_b32 m0, s22
	v_lshl_add_u64 v[230:231], s[52:53], 0, v[148:149]
	global_load_lds_dwordx4 v[228:229], off
	v_lshl_add_u64 v[228:229], s[20:21], 0, v[146:147]
	s_add_i32 m0, s22, 0x2000
	s_nop 0
	global_load_lds_dwordx4 v[228:229], off
	v_lshl_add_u64 v[228:229], s[52:53], 0, v[152:153]
	s_mov_b32 m0, s33
	s_nop 0
	global_load_lds_dwordx4 v[228:229], off
	s_mov_b32 m0, s34
	s_nop 0
	global_load_lds_dwordx4 v[230:231], off
	s_waitcnt vmcnt(8)
	s_waitcnt lgkmcnt(0)
	s_barrier
	s_setprio 1
	s_waitcnt lgkmcnt(0)
	v_mfma_f32_16x16x32_bf16 v[62:65], v[66:69], v[194:197], v[62:65]
	v_mfma_f32_16x16x32_bf16 v[58:61], v[74:77], v[194:197], v[58:61]
	v_mfma_f32_16x16x32_bf16 v[46:49], v[66:69], v[202:205], v[46:49]
	v_mfma_f32_16x16x32_bf16 v[42:45], v[74:77], v[202:205], v[42:45]
	v_mfma_f32_16x16x32_bf16 v[30:33], v[66:69], v[210:213], v[30:33]
	v_mfma_f32_16x16x32_bf16 v[26:29], v[74:77], v[210:213], v[26:29]
	v_mfma_f32_16x16x32_bf16 v[14:17], v[66:69], v[218:221], v[14:17]
	v_mfma_f32_16x16x32_bf16 v[10:13], v[74:77], v[218:221], v[10:13]
	v_mfma_f32_16x16x32_bf16 v[62:65], v[70:73], v[198:201], v[62:65]
	v_mfma_f32_16x16x32_bf16 v[58:61], v[78:81], v[198:201], v[58:61]
	v_mfma_f32_16x16x32_bf16 v[46:49], v[70:73], v[206:209], v[46:49]
	v_mfma_f32_16x16x32_bf16 v[42:45], v[78:81], v[206:209], v[42:45]
	v_mfma_f32_16x16x32_bf16 v[30:33], v[70:73], v[214:217], v[30:33]
	v_mfma_f32_16x16x32_bf16 v[26:29], v[78:81], v[214:217], v[26:29]
	v_mfma_f32_16x16x32_bf16 v[14:17], v[70:73], v[222:225], v[14:17]
	v_mfma_f32_16x16x32_bf16 v[10:13], v[78:81], v[222:225], v[10:13]
	v_mfma_f32_16x16x32_bf16 v[54:57], v[162:165], v[194:197], v[54:57]
	v_mfma_f32_16x16x32_bf16 v[50:53], v[186:189], v[194:197], v[50:53]
	v_mfma_f32_16x16x32_bf16 v[38:41], v[162:165], v[202:205], v[38:41]
	v_mfma_f32_16x16x32_bf16 v[34:37], v[186:189], v[202:205], v[34:37]
	v_mfma_f32_16x16x32_bf16 v[22:25], v[162:165], v[210:213], v[22:25]
	v_mfma_f32_16x16x32_bf16 v[18:21], v[186:189], v[210:213], v[18:21]
	v_mfma_f32_16x16x32_bf16 v[6:9], v[162:165], v[218:221], v[6:9]
	v_mfma_f32_16x16x32_bf16 v[2:5], v[186:189], v[218:221], v[2:5]
	v_mfma_f32_16x16x32_bf16 v[54:57], v[182:185], v[198:201], v[54:57]
	v_mfma_f32_16x16x32_bf16 v[50:53], v[190:193], v[198:201], v[50:53]
	v_mfma_f32_16x16x32_bf16 v[38:41], v[182:185], v[206:209], v[38:41]
	v_mfma_f32_16x16x32_bf16 v[34:37], v[190:193], v[206:209], v[34:37]
	v_mfma_f32_16x16x32_bf16 v[22:25], v[182:185], v[214:217], v[22:25]
	v_mfma_f32_16x16x32_bf16 v[18:21], v[190:193], v[214:217], v[18:21]
	v_mfma_f32_16x16x32_bf16 v[6:9], v[182:185], v[222:225], v[6:9]
	v_mfma_f32_16x16x32_bf16 v[2:5], v[190:193], v[222:225], v[2:5]
	s_setprio 0
	s_barrier
; #define PG8_STAGE(bufoff, gbase, voff) do { _Pragma("unroll") for (int _i = 0; _i < 2; ++_i) \
;         __builtin_amdgcn_global_load_lds((const unsigned*)((const char*)(gbase) + (voff)[_i]), (LAS unsigned*)(lds + (bufoff) + ldsw + _i * 8192), 16, 0, 0); } while (0)
; #define PG8_LDA(dst, b, h) do { _Pragma("unroll") for (int m = 0; m < 4; ++m) _Pragma("unroll") for (int k = 0; k < 2; ++k) dst[m][k] = *(const LAS bf16x8*)(lds + PG8_SA(b, h) + aoff + m * 2048 + k * 1024); } while (0)
; #define PG8_LDB(dst, b, h) do { _Pragma("unroll") for (int n = 0; n < 2; ++n) _Pragma("unroll") for (int k = 0; k < 2; ++k) dst[n][k] = *(const LAS bf16x8*)(lds + PG8_SB(b, h) + boff + n * 2048 + k * 1024); } while (0)
; #define PG8_MMA(ai, bj, At, Bt) do { __builtin_amdgcn_s_setprio(1); _Pragma("unroll") for (int m = 0; m < 4; ++m) _Pragma("unroll") for (int n = 0; n < 2; ++n) _Pragma("unroll") for (int k = 0; k < 2; ++k) \
;         acc[ai][bj][m][n] = __builtin_amdgcn_mfma_f32_16x16x32_bf16(Bt[n][k], At[m][k], acc[ai][bj][m][n], 0, 0, 0); __builtin_amdgcn_s_setprio(0); } while (0)
; #define PG8_WAIT_V(n) asm volatile("s_waitcnt vmcnt(" #n ")" ::: "memory")
; #define PG8_WAIT_L(n) asm volatile("s_waitcnt lgkmcnt(" #n ")" ::: "memory")
; #define PG8_BAR __builtin_amdgcn_s_barrier()
; #define PG8_SCHED __builtin_amdgcn_sched_barrier(0)
; template <class Epi, class Sched, bool ALIGN_EPI = false, bool SP2 = false>
; __device__ __forceinline__ void gemm_phase(LAS unsigned char* lds, const Gemm g, const Sched& S, const Epi& E) {
;     ...
;             PG8_LDB(B0, 1, 0); PG8_LDB(B1, 1, 1); PG8_SCHED; PG8_LDA(At, 1, 0); PG8_STAGE(PG8_SA(0, 1), a2 + hstep, voffA);
;             PG8_WAIT_V(8); PG8_WAIT_L(0); PG8_BAR; PG8_MMA(0, 0, At, B0); PG8_MMA(0, 1, At, B1); PG8_BAR; PG8_SCHED;
	s_add_i32 s22, 0, 0x18000
	s_add_i32 s23, 0, 0x1c000
	v_add_u32_e32 v78, s22, v170
	v_add_u32_e32 v168, s23, v170
	ds_read_b128 v[66:69], v78
	ds_read_b128 v[70:73], v78 offset:1024
	ds_read_b128 v[74:77], v78 offset:2048
	ds_read_b128 v[78:81], v78 offset:3072
	ds_read_b128 v[162:165], v168
	ds_read_b128 v[182:185], v168 offset:1024
	ds_read_b128 v[186:189], v168 offset:2048
	ds_read_b128 v[190:193], v168 offset:3072
	s_add_u32 s20, s52, 0x80000
	s_addc_u32 s21, s53, 0
	s_mov_b32 m0, s35
	v_lshl_add_u64 v[232:233], s[20:21], 0, v[152:153]
	ds_read_b128 v[194:197], v176 offset:32768
	ds_read_b128 v[198:201], v176 offset:33792
	ds_read_b128 v[202:205], v176 offset:34816
	ds_read_b128 v[206:209], v176 offset:35840
	ds_read_b128 v[210:213], v176 offset:36864
	ds_read_b128 v[214:217], v176 offset:37888
	ds_read_b128 v[218:221], v176 offset:38912
	ds_read_b128 v[222:225], v176 offset:39936
	global_load_lds_dwordx4 v[232:233], off
	v_lshl_add_u64 v[232:233], s[20:21], 0, v[148:149]
	s_mov_b32 m0, s36
	s_nop 0
	global_load_lds_dwordx4 v[232:233], off
	s_waitcnt vmcnt(8)
	s_waitcnt lgkmcnt(0)
	s_barrier
	s_setprio 1
	s_waitcnt lgkmcnt(0)
	v_mfma_f32_16x16x32_bf16 v[142:145], v[66:69], v[194:197], v[142:145]
	v_mfma_f32_16x16x32_bf16 v[138:141], v[74:77], v[194:197], v[138:141]
	v_mfma_f32_16x16x32_bf16 v[126:129], v[66:69], v[202:205], v[126:129]
	v_mfma_f32_16x16x32_bf16 v[122:125], v[74:77], v[202:205], v[122:125]
	v_mfma_f32_16x16x32_bf16 v[110:113], v[66:69], v[210:213], v[110:113]
	v_mfma_f32_16x16x32_bf16 v[106:109], v[74:77], v[210:213], v[106:109]
	v_mfma_f32_16x16x32_bf16 v[94:97], v[66:69], v[218:221], v[94:97]
	v_mfma_f32_16x16x32_bf16 v[90:93], v[74:77], v[218:221], v[90:93]
	v_mfma_f32_16x16x32_bf16 v[142:145], v[70:73], v[198:201], v[142:145]
	v_mfma_f32_16x16x32_bf16 v[138:141], v[78:81], v[198:201], v[138:141]
	v_mfma_f32_16x16x32_bf16 v[126:129], v[70:73], v[206:209], v[126:129]
	v_mfma_f32_16x16x32_bf16 v[122:125], v[78:81], v[206:209], v[122:125]
	v_mfma_f32_16x16x32_bf16 v[110:113], v[70:73], v[214:217], v[110:113]
	v_mfma_f32_16x16x32_bf16 v[106:109], v[78:81], v[214:217], v[106:109]
	v_mfma_f32_16x16x32_bf16 v[94:97], v[70:73], v[222:225], v[94:97]
	v_mfma_f32_16x16x32_bf16 v[90:93], v[78:81], v[222:225], v[90:93]
	v_mfma_f32_16x16x32_bf16 v[134:137], v[162:165], v[194:197], v[134:137]
	v_mfma_f32_16x16x32_bf16 v[130:133], v[186:189], v[194:197], v[130:133]
	v_mfma_f32_16x16x32_bf16 v[118:121], v[162:165], v[202:205], v[118:121]
	v_mfma_f32_16x16x32_bf16 v[114:117], v[186:189], v[202:205], v[114:117]
	v_mfma_f32_16x16x32_bf16 v[102:105], v[162:165], v[210:213], v[102:105]
	v_mfma_f32_16x16x32_bf16 v[98:101], v[186:189], v[210:213], v[98:101]
	v_mfma_f32_16x16x32_bf16 v[86:89], v[162:165], v[218:221], v[86:89]
	v_mfma_f32_16x16x32_bf16 v[82:85], v[186:189], v[218:221], v[82:85]
	v_mfma_f32_16x16x32_bf16 v[134:137], v[182:185], v[198:201], v[134:137]
	v_mfma_f32_16x16x32_bf16 v[130:133], v[190:193], v[198:201], v[130:133]
	v_mfma_f32_16x16x32_bf16 v[118:121], v[182:185], v[206:209], v[118:121]
	v_mfma_f32_16x16x32_bf16 v[114:117], v[190:193], v[206:209], v[114:117]
	v_mfma_f32_16x16x32_bf16 v[102:105], v[182:185], v[214:217], v[102:105]
	v_mfma_f32_16x16x32_bf16 v[98:101], v[190:193], v[214:217], v[98:101]
	v_mfma_f32_16x16x32_bf16 v[86:89], v[182:185], v[222:225], v[86:89]
	v_mfma_f32_16x16x32_bf16 v[82:85], v[190:193], v[222:225], v[82:85]
	s_setprio 0
	s_barrier
; #define PG8_STAGE(bufoff, gbase, voff) do { _Pragma("unroll") for (int _i = 0; _i < 2; ++_i) \
;         __builtin_amdgcn_global_load_lds((const unsigned*)((const char*)(gbase) + (voff)[_i]), (LAS unsigned*)(lds + (bufoff) + ldsw + _i * 8192), 16, 0, 0); } while (0)
; #define PG8_LDA(dst, b, h) do { _Pragma("unroll") for (int m = 0; m < 4; ++m) _Pragma("unroll") for (int k = 0; k < 2; ++k) dst[m][k] = *(const LAS bf16x8*)(lds + PG8_SA(b, h) + aoff + m * 2048 + k * 1024); } while (0)
; #define PG8_MMA(ai, bj, At, Bt) do { __builtin_amdgcn_s_setprio(1); _Pragma("unroll") for (int m = 0; m < 4; ++m) _Pragma("unroll") for (int n = 0; n < 2; ++n) _Pragma("unroll") for (int k = 0; k < 2; ++k) \
;         acc[ai][bj][m][n] = __builtin_amdgcn_mfma_f32_16x16x32_bf16(Bt[n][k], At[m][k], acc[ai][bj][m][n], 0, 0, 0); __builtin_amdgcn_s_setprio(0); } while (0)
; #define PG8_WAIT_V(n) asm volatile("s_waitcnt vmcnt(" #n ")" ::: "memory")
; #define PG8_WAIT_L(n) asm volatile("s_waitcnt lgkmcnt(" #n ")" ::: "memory")
; #define PG8_BAR __builtin_amdgcn_s_barrier()
; #define PG8_SCHED __builtin_amdgcn_sched_barrier(0)
; template <class Epi, class Sched, bool ALIGN_EPI = false, bool SP2 = false>
; __device__ __forceinline__ void gemm_phase(LAS unsigned char* lds, const Gemm g, const Sched& S, const Epi& E) {
;     ...
;             PG8_LDA(At, 1, 1); PG8_STAGE(PG8_SB(1, 0), b3, voffB); PG8_STAGE(PG8_SB(1, 1), b3 + hstepB, voffB); PG8_STAGE(PG8_SA(1, 0), a3, voffA);
;             PG8_WAIT_V(8); PG8_WAIT_L(0); PG8_BAR; PG8_MMA(1, 0, At, B0); PG8_MMA(1, 1, At, B1); PG8_BAR; PG8_SCHED;
	s_add_i32 s20, s22, s27
	v_lshl_add_u64 v[166:167], v[166:167], 0, s[10:11]
	s_mov_b32 m0, s20
	ds_read_b128 v[194:197], v176 offset:49152
	ds_read_b128 v[198:201], v176 offset:50176
	ds_read_b128 v[202:205], v176 offset:51200
	ds_read_b128 v[206:209], v176 offset:52224
	ds_read_b128 v[210:213], v176 offset:53248
	ds_read_b128 v[214:217], v176 offset:54272
	ds_read_b128 v[218:221], v176 offset:55296
	ds_read_b128 v[222:225], v176 offset:56320
	global_load_lds_dwordx4 v[166:167], off
	s_add_i32 m0, s20, 0x2000
	s_add_u32 s20, s50, 0x80080
	v_lshl_add_u64 v[166:167], v[226:227], 0, s[10:11]
	s_addc_u32 s21, s51, 0
	s_add_i32 s22, s23, s27
	global_load_lds_dwordx4 v[166:167], off
	v_lshl_add_u64 v[166:167], s[20:21], 0, v[150:151]
	s_mov_b32 m0, s22
	s_nop 0
	global_load_lds_dwordx4 v[166:167], off
	v_lshl_add_u64 v[166:167], s[20:21], 0, v[146:147]
	s_add_i32 m0, s22, 0x2000
	s_nop 0
	global_load_lds_dwordx4 v[166:167], off
	v_lshl_add_u64 v[166:167], v[228:229], 0, s[10:11]
	s_mov_b32 m0, s55
	s_nop 0
	global_load_lds_dwordx4 v[166:167], off
	v_lshl_add_u64 v[166:167], v[230:231], 0, s[10:11]
	s_mov_b32 m0, s56
	s_nop 0
	global_load_lds_dwordx4 v[166:167], off
	s_waitcnt vmcnt(8)
	s_waitcnt lgkmcnt(0)
	s_barrier
	s_setprio 1
	s_waitcnt lgkmcnt(0)
	v_mfma_f32_16x16x32_bf16 v[62:65], v[66:69], v[194:197], v[62:65]
	v_mfma_f32_16x16x32_bf16 v[58:61], v[74:77], v[194:197], v[58:61]
	v_mfma_f32_16x16x32_bf16 v[46:49], v[66:69], v[202:205], v[46:49]
	v_mfma_f32_16x16x32_bf16 v[42:45], v[74:77], v[202:205], v[42:45]
	v_mfma_f32_16x16x32_bf16 v[30:33], v[66:69], v[210:213], v[30:33]
	v_mfma_f32_16x16x32_bf16 v[26:29], v[74:77], v[210:213], v[26:29]
	v_mfma_f32_16x16x32_bf16 v[14:17], v[66:69], v[218:221], v[14:17]
	v_mfma_f32_16x16x32_bf16 v[10:13], v[74:77], v[218:221], v[10:13]
	v_mfma_f32_16x16x32_bf16 v[62:65], v[70:73], v[198:201], v[62:65]
	v_mfma_f32_16x16x32_bf16 v[58:61], v[78:81], v[198:201], v[58:61]
	v_mfma_f32_16x16x32_bf16 v[46:49], v[70:73], v[206:209], v[46:49]
	v_mfma_f32_16x16x32_bf16 v[42:45], v[78:81], v[206:209], v[42:45]
	v_mfma_f32_16x16x32_bf16 v[30:33], v[70:73], v[214:217], v[30:33]
	v_mfma_f32_16x16x32_bf16 v[26:29], v[78:81], v[214:217], v[26:29]
	v_mfma_f32_16x16x32_bf16 v[14:17], v[70:73], v[222:225], v[14:17]
	v_mfma_f32_16x16x32_bf16 v[10:13], v[78:81], v[222:225], v[10:13]
	v_mfma_f32_16x16x32_bf16 v[54:57], v[162:165], v[194:197], v[54:57]
	v_mfma_f32_16x16x32_bf16 v[50:53], v[186:189], v[194:197], v[50:53]
	v_mfma_f32_16x16x32_bf16 v[38:41], v[162:165], v[202:205], v[38:41]
	v_mfma_f32_16x16x32_bf16 v[34:37], v[186:189], v[202:205], v[34:37]
	v_mfma_f32_16x16x32_bf16 v[22:25], v[162:165], v[210:213], v[22:25]
	v_mfma_f32_16x16x32_bf16 v[18:21], v[186:189], v[210:213], v[18:21]
	v_mfma_f32_16x16x32_bf16 v[6:9], v[162:165], v[218:221], v[6:9]
	v_mfma_f32_16x16x32_bf16 v[2:5], v[186:189], v[218:221], v[2:5]
	v_mfma_f32_16x16x32_bf16 v[54:57], v[182:185], v[198:201], v[54:57]
	v_mfma_f32_16x16x32_bf16 v[50:53], v[190:193], v[198:201], v[50:53]
	v_mfma_f32_16x16x32_bf16 v[38:41], v[182:185], v[206:209], v[38:41]
	v_mfma_f32_16x16x32_bf16 v[34:37], v[190:193], v[206:209], v[34:37]
	v_mfma_f32_16x16x32_bf16 v[22:25], v[182:185], v[214:217], v[22:25]
	v_mfma_f32_16x16x32_bf16 v[18:21], v[190:193], v[214:217], v[18:21]
	v_mfma_f32_16x16x32_bf16 v[6:9], v[182:185], v[222:225], v[6:9]
	v_mfma_f32_16x16x32_bf16 v[2:5], v[190:193], v[222:225], v[2:5]
	s_setprio 0
	s_barrier
	s_add_i32 s19, s19, 2
	s_add_u32 s16, s16, 0x100
	s_addc_u32 s17, s17, 0
	s_add_u32 s15, s15, 0x100
	s_addc_u32 s18, s18, 0
	s_cmp_gt_u32 s19, 29
	s_cbranch_scc0 .LBB0_188
	s_and_b64 vcc, exec, s[40:41]
	s_cbranch_vccz .LBB0_191
	s_barrier

; #define PG8_STAGE(bufoff, gbase, voff) do { _Pragma("unroll") for (int _i = 0; _i < 2; ++_i) \
;         __builtin_amdgcn_global_load_lds((const unsigned*)((const char*)(gbase) + (voff)[_i]), (LAS unsigned*)(lds + (bufoff) + ldsw + _i * 8192), 16, 0, 0); } while (0)
; #define PG8_LDA(dst, b, h) do { _Pragma("unroll") for (int m = 0; m < 4; ++m) _Pragma("unroll") for (int k = 0; k < 2; ++k) dst[m][k] = *(const LAS bf16x8*)(lds + PG8_SA(b, h) + aoff + m * 2048 + k * 1024); } while (0)
; #define PG8_LDB(dst, b, h) do { _Pragma("unroll") for (int n = 0; n < 2; ++n) _Pragma("unroll") for (int k = 0; k < 2; ++k) dst[n][k] = *(const LAS bf16x8*)(lds + PG8_SB(b, h) + boff + n * 2048 + k * 1024); } while (0)
; #define PG8_MMA(ai, bj, At, Bt) do { __builtin_amdgcn_s_setprio(1); _Pragma("unroll") for (int m = 0; m < 4; ++m) _Pragma("unroll") for (int n = 0; n < 2; ++n) _Pragma("unroll") for (int k = 0; k < 2; ++k) \
;         acc[ai][bj][m][n] = __builtin_amdgcn_mfma_f32_16x16x32_bf16(Bt[n][k], At[m][k], acc[ai][bj][m][n], 0, 0, 0); __builtin_amdgcn_s_setprio(0); } while (0)
; #define PG8_WAIT_V(n) asm volatile("s_waitcnt vmcnt(" #n ")" ::: "memory")
; #define PG8_WAIT_L(n) asm volatile("s_waitcnt lgkmcnt(" #n ")" ::: "memory")
; template <class Epi, class Sched, bool ALIGN_EPI = false, bool SP2 = false>
; __device__ __forceinline__ void gemm_phase(LAS unsigned char* lds, const Gemm g, const Sched& S, const Epi& E) {
;     ...
;         for (int t = 0; t < nt; t += 2) {
;             const bool last = (t == nt - 2);
;             const char* a1 = cA + (size_t)(t + 1) * kstep;
;             const char* a2 = last ? nA : cA + (size_t)(t + 2) * kstep; const char* b2 = last ? nB : cB + (size_t)(t + 2) * kstep;
;             const char* a3 = a2 + kstep; const char* b3 = b2 + kstep;
;             if (last && has_next) S.a_ready(nxt);
;             if constexpr (SP2) {
;             PG8_LDB(B0, 0, 0); PG8_LDB(B1, 0, 1); PG8_SCHED; PG8_LDA(At, 0, 0); PG8_STAGE(PG8_SA(1, 1), a1 + hstep, voffA);
;             PG8_WAIT_V(8); PG8_WAIT_L(0); PG8_BAR; PG8_MMA(0, 0, At, B0); PG8_MMA(0, 1, At, B1); PG8_BAR; PG8_SCHED;
;             PG8_LDA(At, 0, 1); PG8_STAGE(PG8_SB(0, 0), b2, voffB); PG8_STAGE(PG8_SB(0, 1), b2 + hstepB, voffB); PG8_STAGE(PG8_SA(0, 0), a2, voffA);
;             PG8_WAIT_V(8); PG8_WAIT_L(0); PG8_BAR; PG8_MMA(1, 0, At, B0); PG8_MMA(1, 1, At, B1); PG8_BAR; PG8_SCHED;
.LBB0_288:
	ds_read_b128 v[144:147], v135
	ds_read_b128 v[148:151], v135 offset:1024
	ds_read_b128 v[152:155], v135 offset:2048
	ds_read_b128 v[156:159], v135 offset:3072
	ds_read_b128 v[160:163], v140
	ds_read_b128 v[164:167], v140 offset:1024
	ds_read_b128 v[168:171], v140 offset:2048
	ds_read_b128 v[172:175], v140 offset:3072
	s_add_i32 s44, s40, 2
	s_cmp_lg_u32 s24, s40
	s_cselect_b32 s40, s16, 0
	s_cselect_b32 s41, s17, 0
	s_add_u32 s42, s4, s40
	s_addc_u32 s43, s5, s41
	s_add_u32 s40, s2, s40
	s_addc_u32 s41, s3, s41
	v_lshl_add_u64 v[208:209], v[136:137], 0, s[16:17]
	s_mov_b32 m0, s25
	v_lshl_add_u64 v[208:209], v[208:209], 0, s[38:39]
	ds_read_b128 v[176:179], v141
	ds_read_b128 v[180:183], v141 offset:1024
	ds_read_b128 v[184:187], v141 offset:2048
	ds_read_b128 v[188:191], v141 offset:3072
	ds_read_b128 v[192:195], v141 offset:4096
	ds_read_b128 v[196:199], v141 offset:5120
	ds_read_b128 v[200:203], v141 offset:6144
	ds_read_b128 v[204:207], v141 offset:7168
	global_load_lds_dwordx4 v[208:209], off
	v_lshl_add_u64 v[208:209], v[138:139], 0, s[16:17]
	v_lshl_add_u64 v[208:209], v[208:209], 0, s[38:39]
	s_mov_b32 m0, s28
	s_nop 0
	global_load_lds_dwordx4 v[208:209], off
	s_waitcnt vmcnt(8)
	s_waitcnt lgkmcnt(0)
	s_barrier
	s_setprio 1
	s_waitcnt lgkmcnt(0)
	v_mfma_f32_16x16x32_bf16 v[126:129], v[144:147], v[176:179], v[126:129]
	v_mfma_f32_16x16x32_bf16 v[94:97], v[152:155], v[176:179], v[94:97]
	v_mfma_f32_16x16x32_bf16 v[122:125], v[144:147], v[184:187], v[122:125]
	v_mfma_f32_16x16x32_bf16 v[90:93], v[152:155], v[184:187], v[90:93]
	v_mfma_f32_16x16x32_bf16 v[118:121], v[144:147], v[192:195], v[118:121]
	v_mfma_f32_16x16x32_bf16 v[86:89], v[152:155], v[192:195], v[86:89]
	v_mfma_f32_16x16x32_bf16 v[114:117], v[144:147], v[200:203], v[114:117]
	v_mfma_f32_16x16x32_bf16 v[82:85], v[152:155], v[200:203], v[82:85]
	v_mfma_f32_16x16x32_bf16 v[126:129], v[148:151], v[180:183], v[126:129]
	v_mfma_f32_16x16x32_bf16 v[94:97], v[156:159], v[180:183], v[94:97]
	v_mfma_f32_16x16x32_bf16 v[122:125], v[148:151], v[188:191], v[122:125]
	v_mfma_f32_16x16x32_bf16 v[90:93], v[156:159], v[188:191], v[90:93]
	v_mfma_f32_16x16x32_bf16 v[118:121], v[148:151], v[196:199], v[118:121]
	v_mfma_f32_16x16x32_bf16 v[86:89], v[156:159], v[196:199], v[86:89]
	v_mfma_f32_16x16x32_bf16 v[114:117], v[148:151], v[204:207], v[114:117]
	v_mfma_f32_16x16x32_bf16 v[82:85], v[156:159], v[204:207], v[82:85]
	v_mfma_f32_16x16x32_bf16 v[70:73], v[160:163], v[176:179], v[70:73]
	v_mfma_f32_16x16x32_bf16 v[42:45], v[168:171], v[176:179], v[42:45]
	v_mfma_f32_16x16x32_bf16 v[62:65], v[160:163], v[184:187], v[62:65]
	v_mfma_f32_16x16x32_bf16 v[34:37], v[168:171], v[184:187], v[34:37]
	v_mfma_f32_16x16x32_bf16 v[54:57], v[160:163], v[192:195], v[54:57]
	v_mfma_f32_16x16x32_bf16 v[26:29], v[168:171], v[192:195], v[26:29]
	v_mfma_f32_16x16x32_bf16 v[50:53], v[160:163], v[200:203], v[50:53]
	v_mfma_f32_16x16x32_bf16 v[18:21], v[168:171], v[200:203], v[18:21]
	v_mfma_f32_16x16x32_bf16 v[70:73], v[164:167], v[180:183], v[70:73]
	v_mfma_f32_16x16x32_bf16 v[42:45], v[172:175], v[180:183], v[42:45]
	v_mfma_f32_16x16x32_bf16 v[62:65], v[164:167], v[188:191], v[62:65]
	v_mfma_f32_16x16x32_bf16 v[34:37], v[172:175], v[188:191], v[34:37]
	v_mfma_f32_16x16x32_bf16 v[54:57], v[164:167], v[196:199], v[54:57]
	v_mfma_f32_16x16x32_bf16 v[26:29], v[172:175], v[196:199], v[26:29]
	v_mfma_f32_16x16x32_bf16 v[50:53], v[164:167], v[204:207], v[50:53]
	v_mfma_f32_16x16x32_bf16 v[18:21], v[172:175], v[204:207], v[18:21]
	s_setprio 0
	s_barrier
	s_mov_b32 m0, s29
	v_lshl_add_u64 v[208:209], s[40:41], 0, v[132:133]
	s_add_u32 s46, s40, 0x160000
	ds_read_b128 v[176:179], v141 offset:16384
	ds_read_b128 v[180:183], v141 offset:17408
	ds_read_b128 v[184:187], v141 offset:18432
	ds_read_b128 v[188:191], v141 offset:19456
	ds_read_b128 v[192:195], v141 offset:20480
	ds_read_b128 v[196:199], v141 offset:21504
	ds_read_b128 v[200:203], v141 offset:22528
	ds_read_b128 v[204:207], v141 offset:23552
	global_load_lds_dwordx4 v[208:209], off
	v_lshl_add_u64 v[210:211], s[40:41], 0, v[130:131]
	s_mov_b32 m0, s30
	s_addc_u32 s47, s41, 0
	global_load_lds_dwordx4 v[210:211], off
	v_lshl_add_u64 v[212:213], s[46:47], 0, v[132:133]
	s_mov_b32 m0, s31
	v_lshl_add_u64 v[214:215], s[42:43], 0, v[130:131]
	global_load_lds_dwordx4 v[212:213], off
	v_lshl_add_u64 v[212:213], s[46:47], 0, v[130:131]
	s_mov_b32 m0, s33
	s_nop 0
	global_load_lds_dwordx4 v[212:213], off
	v_lshl_add_u64 v[212:213], s[42:43], 0, v[132:133]
	s_mov_b32 m0, s14
	s_nop 0
	global_load_lds_dwordx4 v[212:213], off
	s_mov_b32 m0, s18
	s_nop 0
	global_load_lds_dwordx4 v[214:215], off
	s_waitcnt vmcnt(8)
	s_waitcnt lgkmcnt(0)
	s_barrier
; #define PG8_STAGE(bufoff, gbase, voff) do { _Pragma("unroll") for (int _i = 0; _i < 2; ++_i) \
;         __builtin_amdgcn_global_load_lds((const unsigned*)((const char*)(gbase) + (voff)[_i]), (LAS unsigned*)(lds + (bufoff) + ldsw + _i * 8192), 16, 0, 0); } while (0)
; #define PG8_LDA(dst, b, h) do { _Pragma("unroll") for (int m = 0; m < 4; ++m) _Pragma("unroll") for (int k = 0; k < 2; ++k) dst[m][k] = *(const LAS bf16x8*)(lds + PG8_SA(b, h) + aoff + m * 2048 + k * 1024); } while (0)
; #define PG8_LDB(dst, b, h) do { _Pragma("unroll") for (int n = 0; n < 2; ++n) _Pragma("unroll") for (int k = 0; k < 2; ++k) dst[n][k] = *(const LAS bf16x8*)(lds + PG8_SB(b, h) + boff + n * 2048 + k * 1024); } while (0)
; #define PG8_MMA(ai, bj, At, Bt) do { __builtin_amdgcn_s_setprio(1); _Pragma("unroll") for (int m = 0; m < 4; ++m) _Pragma("unroll") for (int n = 0; n < 2; ++n) _Pragma("unroll") for (int k = 0; k < 2; ++k) \
;         acc[ai][bj][m][n] = __builtin_amdgcn_mfma_f32_16x16x32_bf16(Bt[n][k], At[m][k], acc[ai][bj][m][n], 0, 0, 0); __builtin_amdgcn_s_setprio(0); } while (0)
; #define PG8_WAIT_V(n) asm volatile("s_waitcnt vmcnt(" #n ")" ::: "memory")
; #define PG8_WAIT_L(n) asm volatile("s_waitcnt lgkmcnt(" #n ")" ::: "memory")
; #define PG8_BAR __builtin_amdgcn_s_barrier()
; #define PG8_SCHED __builtin_amdgcn_sched_barrier(0)
; template <class Epi, class Sched, bool ALIGN_EPI = false, bool SP2 = false>
; __device__ __forceinline__ void gemm_phase(LAS unsigned char* lds, const Gemm g, const Sched& S, const Epi& E) {
;     ...
;             PG8_WAIT_V(8); PG8_WAIT_L(0); PG8_BAR; PG8_MMA(1, 0, At, B0); PG8_MMA(1, 1, At, B1); PG8_BAR; PG8_SCHED;
;             PG8_LDB(B0, 1, 0); PG8_LDB(B1, 1, 1); PG8_SCHED; PG8_LDA(At, 1, 0); PG8_STAGE(PG8_SA(0, 1), a2 + hstep, voffA);
;             PG8_WAIT_V(8); PG8_WAIT_L(0); PG8_BAR; PG8_MMA(0, 0, At, B0); PG8_MMA(0, 1, At, B1); PG8_BAR; PG8_SCHED;
	s_setprio 1
	s_waitcnt lgkmcnt(0)
	v_mfma_f32_16x16x32_bf16 v[110:113], v[144:147], v[176:179], v[110:113]
	v_mfma_f32_16x16x32_bf16 v[78:81], v[152:155], v[176:179], v[78:81]
	v_mfma_f32_16x16x32_bf16 v[106:109], v[144:147], v[184:187], v[106:109]
	v_mfma_f32_16x16x32_bf16 v[74:77], v[152:155], v[184:187], v[74:77]
	v_mfma_f32_16x16x32_bf16 v[102:105], v[144:147], v[192:195], v[102:105]
	v_mfma_f32_16x16x32_bf16 v[66:69], v[152:155], v[192:195], v[66:69]
	v_mfma_f32_16x16x32_bf16 v[98:101], v[144:147], v[200:203], v[98:101]
	v_mfma_f32_16x16x32_bf16 v[58:61], v[152:155], v[200:203], v[58:61]
	v_mfma_f32_16x16x32_bf16 v[110:113], v[148:151], v[180:183], v[110:113]
	v_mfma_f32_16x16x32_bf16 v[78:81], v[156:159], v[180:183], v[78:81]
	v_mfma_f32_16x16x32_bf16 v[106:109], v[148:151], v[188:191], v[106:109]
	v_mfma_f32_16x16x32_bf16 v[74:77], v[156:159], v[188:191], v[74:77]
	v_mfma_f32_16x16x32_bf16 v[102:105], v[148:151], v[196:199], v[102:105]
	v_mfma_f32_16x16x32_bf16 v[66:69], v[156:159], v[196:199], v[66:69]
	v_mfma_f32_16x16x32_bf16 v[98:101], v[148:151], v[204:207], v[98:101]
	v_mfma_f32_16x16x32_bf16 v[58:61], v[156:159], v[204:207], v[58:61]
	v_mfma_f32_16x16x32_bf16 v[46:49], v[160:163], v[176:179], v[46:49]
	v_mfma_f32_16x16x32_bf16 v[14:17], v[168:171], v[176:179], v[14:17]
	v_mfma_f32_16x16x32_bf16 v[38:41], v[160:163], v[184:187], v[38:41]
	v_mfma_f32_16x16x32_bf16 v[10:13], v[168:171], v[184:187], v[10:13]
	v_mfma_f32_16x16x32_bf16 v[30:33], v[160:163], v[192:195], v[30:33]
	v_mfma_f32_16x16x32_bf16 v[6:9], v[168:171], v[192:195], v[6:9]
	v_mfma_f32_16x16x32_bf16 v[22:25], v[160:163], v[200:203], v[22:25]
	v_mfma_f32_16x16x32_bf16 v[2:5], v[168:171], v[200:203], v[2:5]
	v_mfma_f32_16x16x32_bf16 v[46:49], v[164:167], v[180:183], v[46:49]
	v_mfma_f32_16x16x32_bf16 v[14:17], v[172:175], v[180:183], v[14:17]
	v_mfma_f32_16x16x32_bf16 v[38:41], v[164:167], v[188:191], v[38:41]
	v_mfma_f32_16x16x32_bf16 v[10:13], v[172:175], v[188:191], v[10:13]
	v_mfma_f32_16x16x32_bf16 v[30:33], v[164:167], v[196:199], v[30:33]
	v_mfma_f32_16x16x32_bf16 v[6:9], v[172:175], v[196:199], v[6:9]
	v_mfma_f32_16x16x32_bf16 v[22:25], v[164:167], v[204:207], v[22:25]
	v_mfma_f32_16x16x32_bf16 v[2:5], v[172:175], v[204:207], v[2:5]
	s_setprio 0
	s_barrier
	ds_read_b128 v[144:147], v142
	ds_read_b128 v[148:151], v142 offset:1024
	ds_read_b128 v[152:155], v142 offset:2048
	ds_read_b128 v[156:159], v142 offset:3072
	ds_read_b128 v[160:163], v143
	ds_read_b128 v[164:167], v143 offset:1024
	ds_read_b128 v[168:171], v143 offset:2048
	ds_read_b128 v[172:175], v143 offset:3072
	s_add_u32 s42, s42, 0x160000
	s_addc_u32 s43, s43, 0
	s_mov_b32 m0, s19
	v_lshl_add_u64 v[216:217], s[42:43], 0, v[132:133]
	ds_read_b128 v[176:179], v141 offset:32768
	ds_read_b128 v[180:183], v141 offset:33792
	ds_read_b128 v[184:187], v141 offset:34816
	ds_read_b128 v[188:191], v141 offset:35840
	ds_read_b128 v[192:195], v141 offset:36864
	ds_read_b128 v[196:199], v141 offset:37888
	ds_read_b128 v[200:203], v141 offset:38912
	ds_read_b128 v[204:207], v141 offset:39936
	global_load_lds_dwordx4 v[216:217], off
	v_lshl_add_u64 v[216:217], s[42:43], 0, v[130:131]
	s_mov_b32 m0, s20
	s_nop 0
	global_load_lds_dwordx4 v[216:217], off
	s_waitcnt vmcnt(8)
	s_waitcnt lgkmcnt(0)
	s_barrier
	s_setprio 1
	s_waitcnt lgkmcnt(0)
	v_mfma_f32_16x16x32_bf16 v[126:129], v[144:147], v[176:179], v[126:129]
	v_mfma_f32_16x16x32_bf16 v[94:97], v[152:155], v[176:179], v[94:97]
	v_mfma_f32_16x16x32_bf16 v[122:125], v[144:147], v[184:187], v[122:125]
	v_mfma_f32_16x16x32_bf16 v[90:93], v[152:155], v[184:187], v[90:93]
	v_mfma_f32_16x16x32_bf16 v[118:121], v[144:147], v[192:195], v[118:121]
	v_mfma_f32_16x16x32_bf16 v[86:89], v[152:155], v[192:195], v[86:89]
	v_mfma_f32_16x16x32_bf16 v[114:117], v[144:147], v[200:203], v[114:117]
	v_mfma_f32_16x16x32_bf16 v[82:85], v[152:155], v[200:203], v[82:85]
	v_mfma_f32_16x16x32_bf16 v[126:129], v[148:151], v[180:183], v[126:129]
	v_mfma_f32_16x16x32_bf16 v[94:97], v[156:159], v[180:183], v[94:97]
	v_mfma_f32_16x16x32_bf16 v[122:125], v[148:151], v[188:191], v[122:125]
	v_mfma_f32_16x16x32_bf16 v[90:93], v[156:159], v[188:191], v[90:93]
	v_mfma_f32_16x16x32_bf16 v[118:121], v[148:151], v[196:199], v[118:121]
	v_mfma_f32_16x16x32_bf16 v[86:89], v[156:159], v[196:199], v[86:89]
	v_mfma_f32_16x16x32_bf16 v[114:117], v[148:151], v[204:207], v[114:117]
	v_mfma_f32_16x16x32_bf16 v[82:85], v[156:159], v[204:207], v[82:85]
	v_mfma_f32_16x16x32_bf16 v[70:73], v[160:163], v[176:179], v[70:73]
	v_mfma_f32_16x16x32_bf16 v[42:45], v[168:171], v[176:179], v[42:45]
	v_mfma_f32_16x16x32_bf16 v[62:65], v[160:163], v[184:187], v[62:65]
	v_mfma_f32_16x16x32_bf16 v[34:37], v[168:171], v[184:187], v[34:37]
	v_mfma_f32_16x16x32_bf16 v[54:57], v[160:163], v[192:195], v[54:57]
	v_mfma_f32_16x16x32_bf16 v[26:29], v[168:171], v[192:195], v[26:29]
	v_mfma_f32_16x16x32_bf16 v[50:53], v[160:163], v[200:203], v[50:53]
	v_mfma_f32_16x16x32_bf16 v[18:21], v[168:171], v[200:203], v[18:21]
	v_mfma_f32_16x16x32_bf16 v[70:73], v[164:167], v[180:183], v[70:73]
	v_mfma_f32_16x16x32_bf16 v[42:45], v[172:175], v[180:183], v[42:45]
	v_mfma_f32_16x16x32_bf16 v[62:65], v[164:167], v[188:191], v[62:65]
	v_mfma_f32_16x16x32_bf16 v[34:37], v[172:175], v[188:191], v[34:37]
	v_mfma_f32_16x16x32_bf16 v[54:57], v[164:167], v[196:199], v[54:57]
	v_mfma_f32_16x16x32_bf16 v[26:29], v[172:175], v[196:199], v[26:29]
	v_mfma_f32_16x16x32_bf16 v[50:53], v[164:167], v[204:207], v[50:53]
	v_mfma_f32_16x16x32_bf16 v[18:21], v[172:175], v[204:207], v[18:21]
	s_setprio 0
	s_barrier
; #define PG8_STAGE(bufoff, gbase, voff) do { _Pragma("unroll") for (int _i = 0; _i < 2; ++_i) \
;         __builtin_amdgcn_global_load_lds((const unsigned*)((const char*)(gbase) + (voff)[_i]), (LAS unsigned*)(lds + (bufoff) + ldsw + _i * 8192), 16, 0, 0); } while (0)
; #define PG8_LDA(dst, b, h) do { _Pragma("unroll") for (int m = 0; m < 4; ++m) _Pragma("unroll") for (int k = 0; k < 2; ++k) dst[m][k] = *(const LAS bf16x8*)(lds + PG8_SA(b, h) + aoff + m * 2048 + k * 1024); } while (0)
; #define PG8_MMA(ai, bj, At, Bt) do { __builtin_amdgcn_s_setprio(1); _Pragma("unroll") for (int m = 0; m < 4; ++m) _Pragma("unroll") for (int n = 0; n < 2; ++n) _Pragma("unroll") for (int k = 0; k < 2; ++k) \
;         acc[ai][bj][m][n] = __builtin_amdgcn_mfma_f32_16x16x32_bf16(Bt[n][k], At[m][k], acc[ai][bj][m][n], 0, 0, 0); __builtin_amdgcn_s_setprio(0); } while (0)
; #define PG8_WAIT_V(n) asm volatile("s_waitcnt vmcnt(" #n ")" ::: "memory")
; #define PG8_WAIT_L(n) asm volatile("s_waitcnt lgkmcnt(" #n ")" ::: "memory")
; #define PG8_BAR __builtin_amdgcn_s_barrier()
; #define PG8_SCHED __builtin_amdgcn_sched_barrier(0)
; template <class Epi, class Sched, bool ALIGN_EPI = false, bool SP2 = false>
; __device__ __forceinline__ void gemm_phase(LAS unsigned char* lds, const Gemm g, const Sched& S, const Epi& E) {
;     ...
;             PG8_LDA(At, 1, 1); PG8_STAGE(PG8_SB(1, 0), b3, voffB); PG8_STAGE(PG8_SB(1, 1), b3 + hstepB, voffB); PG8_STAGE(PG8_SA(1, 0), a3, voffA);
;             PG8_WAIT_V(8); PG8_WAIT_L(0); PG8_BAR; PG8_MMA(1, 0, At, B0); PG8_MMA(1, 1, At, B1); PG8_BAR; PG8_SCHED;
	s_mov_b32 m0, s34
	v_lshl_add_u64 v[208:209], v[208:209], 0, s[10:11]
	s_add_u32 s40, s40, 0x160080
	ds_read_b128 v[176:179], v141 offset:49152
	ds_read_b128 v[180:183], v141 offset:50176
	ds_read_b128 v[184:187], v141 offset:51200
	ds_read_b128 v[188:191], v141 offset:52224
	ds_read_b128 v[192:195], v141 offset:53248
	ds_read_b128 v[196:199], v141 offset:54272
	ds_read_b128 v[200:203], v141 offset:55296
	ds_read_b128 v[204:207], v141 offset:56320
	global_load_lds_dwordx4 v[208:209], off
	v_lshl_add_u64 v[208:209], v[210:211], 0, s[10:11]
	s_mov_b32 m0, s35
	s_addc_u32 s41, s41, 0
	global_load_lds_dwordx4 v[208:209], off
	v_lshl_add_u64 v[208:209], s[40:41], 0, v[132:133]
	s_mov_b32 m0, s36
	s_nop 0
	global_load_lds_dwordx4 v[208:209], off
	v_lshl_add_u64 v[208:209], s[40:41], 0, v[130:131]
	s_mov_b32 m0, s37
	s_nop 0
	global_load_lds_dwordx4 v[208:209], off
	v_lshl_add_u64 v[208:209], v[212:213], 0, s[10:11]
	s_mov_b32 m0, s22
	s_nop 0
	global_load_lds_dwordx4 v[208:209], off
	v_lshl_add_u64 v[208:209], v[214:215], 0, s[10:11]
	s_mov_b32 m0, s23
	s_nop 0
	global_load_lds_dwordx4 v[208:209], off
	s_waitcnt vmcnt(8)
	s_waitcnt lgkmcnt(0)
	s_barrier
	s_setprio 1
	s_waitcnt lgkmcnt(0)
	v_mfma_f32_16x16x32_bf16 v[110:113], v[144:147], v[176:179], v[110:113]
	v_mfma_f32_16x16x32_bf16 v[78:81], v[152:155], v[176:179], v[78:81]
	v_mfma_f32_16x16x32_bf16 v[106:109], v[144:147], v[184:187], v[106:109]
	v_mfma_f32_16x16x32_bf16 v[74:77], v[152:155], v[184:187], v[74:77]
	v_mfma_f32_16x16x32_bf16 v[102:105], v[144:147], v[192:195], v[102:105]
	v_mfma_f32_16x16x32_bf16 v[66:69], v[152:155], v[192:195], v[66:69]
	v_mfma_f32_16x16x32_bf16 v[98:101], v[144:147], v[200:203], v[98:101]
	v_mfma_f32_16x16x32_bf16 v[58:61], v[152:155], v[200:203], v[58:61]
	v_mfma_f32_16x16x32_bf16 v[110:113], v[148:151], v[180:183], v[110:113]
	v_mfma_f32_16x16x32_bf16 v[78:81], v[156:159], v[180:183], v[78:81]
	v_mfma_f32_16x16x32_bf16 v[106:109], v[148:151], v[188:191], v[106:109]
	v_mfma_f32_16x16x32_bf16 v[74:77], v[156:159], v[188:191], v[74:77]
	v_mfma_f32_16x16x32_bf16 v[102:105], v[148:151], v[196:199], v[102:105]
	v_mfma_f32_16x16x32_bf16 v[66:69], v[156:159], v[196:199], v[66:69]
	v_mfma_f32_16x16x32_bf16 v[98:101], v[148:151], v[204:207], v[98:101]
	v_mfma_f32_16x16x32_bf16 v[58:61], v[156:159], v[204:207], v[58:61]
	v_mfma_f32_16x16x32_bf16 v[46:49], v[160:163], v[176:179], v[46:49]
	v_mfma_f32_16x16x32_bf16 v[14:17], v[168:171], v[176:179], v[14:17]
	v_mfma_f32_16x16x32_bf16 v[38:41], v[160:163], v[184:187], v[38:41]
	v_mfma_f32_16x16x32_bf16 v[10:13], v[168:171], v[184:187], v[10:13]
	v_mfma_f32_16x16x32_bf16 v[30:33], v[160:163], v[192:195], v[30:33]
	v_mfma_f32_16x16x32_bf16 v[6:9], v[168:171], v[192:195], v[6:9]
	v_mfma_f32_16x16x32_bf16 v[22:25], v[160:163], v[200:203], v[22:25]
	v_mfma_f32_16x16x32_bf16 v[2:5], v[168:171], v[200:203], v[2:5]
	v_mfma_f32_16x16x32_bf16 v[46:49], v[164:167], v[180:183], v[46:49]
	v_mfma_f32_16x16x32_bf16 v[14:17], v[172:175], v[180:183], v[14:17]
	v_mfma_f32_16x16x32_bf16 v[38:41], v[164:167], v[188:191], v[38:41]
	v_mfma_f32_16x16x32_bf16 v[10:13], v[172:175], v[188:191], v[10:13]
	v_mfma_f32_16x16x32_bf16 v[30:33], v[164:167], v[196:199], v[30:33]
	v_mfma_f32_16x16x32_bf16 v[6:9], v[172:175], v[196:199], v[6:9]
	v_mfma_f32_16x16x32_bf16 v[22:25], v[164:167], v[204:207], v[22:25]
	v_mfma_f32_16x16x32_bf16 v[2:5], v[172:175], v[204:207], v[2:5]
	s_setprio 0
	s_barrier
	s_add_u32 s16, s16, 0x100
	s_addc_u32 s17, s17, 0
	s_cmp_ge_u32 s44, s21
	s_mov_b32 s40, s44
	s_cbranch_scc0 .LBB0_288
	v_readlane_b32 s30, v252, 2
	s_cmpk_lt_u32 s13, 0x100
	v_readlane_b32 s31, v252, 3
	s_mov_b64 s[34:35], s[78:79]
	s_cbranch_scc0 .LBB0_291
	s_barrier

; #define PG8_STAGE(bufoff, gbase, voff) do { _Pragma("unroll") for (int _i = 0; _i < 2; ++_i) \
;         __builtin_amdgcn_global_load_lds((const unsigned*)((const char*)(gbase) + (voff)[_i]), (LAS unsigned*)(lds + (bufoff) + ldsw + _i * 8192), 16, 0, 0); } while (0)
; #define PG8_LDA(dst, b, h) do { _Pragma("unroll") for (int m = 0; m < 4; ++m) _Pragma("unroll") for (int k = 0; k < 2; ++k) dst[m][k] = *(const LAS bf16x8*)(lds + PG8_SA(b, h) + aoff + m * 2048 + k * 1024); } while (0)
; #define PG8_LDB(dst, b, h) do { _Pragma("unroll") for (int n = 0; n < 2; ++n) _Pragma("unroll") for (int k = 0; k < 2; ++k) dst[n][k] = *(const LAS bf16x8*)(lds + PG8_SB(b, h) + boff + n * 2048 + k * 1024); } while (0)
; #define PG8_MMA(ai, bj, At, Bt) do { __builtin_amdgcn_s_setprio(1); _Pragma("unroll") for (int m = 0; m < 4; ++m) _Pragma("unroll") for (int n = 0; n < 2; ++n) _Pragma("unroll") for (int k = 0; k < 2; ++k) \
;         acc[ai][bj][m][n] = __builtin_amdgcn_mfma_f32_16x16x32_bf16(Bt[n][k], At[m][k], acc[ai][bj][m][n], 0, 0, 0); __builtin_amdgcn_s_setprio(0); } while (0)
; #define PG8_WAIT_V(n) asm volatile("s_waitcnt vmcnt(" #n ")" ::: "memory")
; #define PG8_WAIT_L(n) asm volatile("s_waitcnt lgkmcnt(" #n ")" ::: "memory")
; #define PG8_BAR __builtin_amdgcn_s_barrier()
; #define PG8_SCHED __builtin_amdgcn_sched_barrier(0)
; template <class Epi, class Sched, bool ALIGN_EPI = false, bool SP2 = false>
; __device__ __forceinline__ void gemm_phase(LAS unsigned char* lds, const Gemm g, const Sched& S, const Epi& E) {
;     ...
;         for (int t = 0; t < nt; t += 2) {
;             const bool last = (t == nt - 2);
;             const char* a1 = cA + (size_t)(t + 1) * kstep;
;             const char* a2 = last ? nA : cA + (size_t)(t + 2) * kstep; const char* b2 = last ? nB : cB + (size_t)(t + 2) * kstep;
;             const char* a3 = a2 + kstep; const char* b3 = b2 + kstep;
;             if (last && has_next) S.a_ready(nxt);
;             if constexpr (SP2) {
;             PG8_LDB(B0, 0, 0); PG8_LDB(B1, 0, 1); PG8_SCHED; PG8_LDA(At, 0, 0); PG8_STAGE(PG8_SA(1, 1), a1 + hstep, voffA);
;             PG8_WAIT_V(8); PG8_WAIT_L(0); PG8_BAR; PG8_MMA(0, 0, At, B0); PG8_MMA(0, 1, At, B1); PG8_BAR; PG8_SCHED;
;             PG8_LDA(At, 0, 1); PG8_STAGE(PG8_SB(0, 0), b2, voffB); PG8_STAGE(PG8_SB(0, 1), b2 + hstepB, voffB); PG8_STAGE(PG8_SA(0, 0), a2, voffA);
.LBB0_316:
	s_add_u32 s5, s22, 0x100
	s_addc_u32 s12, s23, 0
	s_mov_b32 s13, -2
	ds_read_b128 v[130:133], v196
	ds_read_b128 v[134:137], v196 offset:1024
	ds_read_b128 v[138:141], v196 offset:2048
	ds_read_b128 v[142:145], v196 offset:3072
	ds_read_b128 v[166:169], v197
	ds_read_b128 v[170:173], v197 offset:1024
	ds_read_b128 v[174:177], v197 offset:2048
	ds_read_b128 v[178:181], v197 offset:3072
	s_add_u32 s54, s16, 0x100
	s_addc_u32 s55, s17, 0
	s_cmpk_eq_i32 s13, 0x54
	s_cselect_b32 s59, s3, s55
	s_cselect_b32 s58, s2, s54
	s_cselect_b32 s57, s53, s12
	s_cselect_b32 s56, s52, s5
	v_lshl_add_u64 v[190:191], s[16:17], 0, v[158:159]
	s_add_i32 m0, s29, 0xc000
	ds_read_b128 v[182:185], v198
	ds_read_b128 v[186:189], v198 offset:1024
	ds_read_b128 v[202:205], v198 offset:2048
	ds_read_b128 v[206:209], v198 offset:3072
	ds_read_b128 v[210:213], v198 offset:4096
	ds_read_b128 v[214:217], v198 offset:5120
	ds_read_b128 v[218:221], v198 offset:6144
	ds_read_b128 v[222:225], v198 offset:7168
	global_load_lds_dwordx4 v[190:191], off
	v_lshl_add_u64 v[190:191], s[16:17], 0, v[160:161]
	s_add_i32 m0, s29, 0xe000
	s_nop 0
	global_load_lds_dwordx4 v[190:191], off
	s_waitcnt lgkmcnt(0)
	s_barrier
	s_setprio 1
	s_waitcnt lgkmcnt(0)
	v_mfma_f32_16x16x32_bf16 v[126:129], v[130:133], v[182:185], 0
	v_mfma_f32_16x16x32_bf16 v[122:125], v[138:141], v[182:185], 0
	v_mfma_f32_16x16x32_bf16 v[110:113], v[130:133], v[202:205], 0
	v_mfma_f32_16x16x32_bf16 v[106:109], v[138:141], v[202:205], 0
	v_mfma_f32_16x16x32_bf16 v[94:97], v[130:133], v[210:213], 0
	v_mfma_f32_16x16x32_bf16 v[90:93], v[138:141], v[210:213], 0
	v_mfma_f32_16x16x32_bf16 v[78:81], v[130:133], v[218:221], 0
	v_mfma_f32_16x16x32_bf16 v[74:77], v[138:141], v[218:221], 0
	v_mfma_f32_16x16x32_bf16 v[126:129], v[134:137], v[186:189], v[126:129]
	v_mfma_f32_16x16x32_bf16 v[122:125], v[142:145], v[186:189], v[122:125]
	v_mfma_f32_16x16x32_bf16 v[110:113], v[134:137], v[206:209], v[110:113]
	v_mfma_f32_16x16x32_bf16 v[106:109], v[142:145], v[206:209], v[106:109]
	v_mfma_f32_16x16x32_bf16 v[94:97], v[134:137], v[214:217], v[94:97]
	v_mfma_f32_16x16x32_bf16 v[90:93], v[142:145], v[214:217], v[90:93]
	v_mfma_f32_16x16x32_bf16 v[78:81], v[134:137], v[222:225], v[78:81]
	v_mfma_f32_16x16x32_bf16 v[74:77], v[142:145], v[222:225], v[74:77]
	v_mfma_f32_16x16x32_bf16 v[118:121], v[166:169], v[182:185], 0
	v_mfma_f32_16x16x32_bf16 v[114:117], v[174:177], v[182:185], 0
	v_mfma_f32_16x16x32_bf16 v[102:105], v[166:169], v[202:205], 0
	v_mfma_f32_16x16x32_bf16 v[98:101], v[174:177], v[202:205], 0
	v_mfma_f32_16x16x32_bf16 v[86:89], v[166:169], v[210:213], 0
	v_mfma_f32_16x16x32_bf16 v[82:85], v[174:177], v[210:213], 0
	v_mfma_f32_16x16x32_bf16 v[70:73], v[166:169], v[218:221], 0
	v_mfma_f32_16x16x32_bf16 v[66:69], v[174:177], v[218:221], 0
	v_mfma_f32_16x16x32_bf16 v[118:121], v[170:173], v[186:189], v[118:121]
	v_mfma_f32_16x16x32_bf16 v[114:117], v[178:181], v[186:189], v[114:117]
	v_mfma_f32_16x16x32_bf16 v[102:105], v[170:173], v[206:209], v[102:105]
	v_mfma_f32_16x16x32_bf16 v[98:101], v[178:181], v[206:209], v[98:101]
	v_mfma_f32_16x16x32_bf16 v[86:89], v[170:173], v[214:217], v[86:89]
	v_mfma_f32_16x16x32_bf16 v[82:85], v[178:181], v[214:217], v[82:85]
	v_mfma_f32_16x16x32_bf16 v[70:73], v[170:173], v[222:225], v[70:73]
	v_mfma_f32_16x16x32_bf16 v[66:69], v[178:181], v[222:225], v[66:69]
	s_setprio 0
	s_barrier
	s_add_i32 s14, s64, s28
	v_lshl_add_u64 v[190:191], s[56:57], 0, v[148:149]
	s_mov_b32 m0, s14
	ds_read_b128 v[182:185], v198 offset:16384
	ds_read_b128 v[186:189], v198 offset:17408
	ds_read_b128 v[202:205], v198 offset:18432
	ds_read_b128 v[206:209], v198 offset:19456
	ds_read_b128 v[210:213], v198 offset:20480
	ds_read_b128 v[214:217], v198 offset:21504
	ds_read_b128 v[218:221], v198 offset:22528
	ds_read_b128 v[222:225], v198 offset:23552
	global_load_lds_dwordx4 v[190:191], off
	s_add_i32 m0, s14, 0x2000
	s_add_u32 s14, s56, 0x58000
	v_lshl_add_u64 v[226:227], s[56:57], 0, v[152:153]
	s_addc_u32 s15, s57, 0
	s_add_i32 s16, s65, s28
	global_load_lds_dwordx4 v[226:227], off
	v_lshl_add_u64 v[228:229], s[14:15], 0, v[148:149]
	s_mov_b32 m0, s16
	v_lshl_add_u64 v[230:231], s[58:59], 0, v[150:151]
	global_load_lds_dwordx4 v[228:229], off
	v_lshl_add_u64 v[228:229], s[14:15], 0, v[152:153]
	s_add_i32 m0, s16, 0x2000
	s_nop 0
	global_load_lds_dwordx4 v[228:229], off
	v_lshl_add_u64 v[228:229], s[58:59], 0, v[146:147]
	s_mov_b32 m0, s29
	s_nop 0
	global_load_lds_dwordx4 v[228:229], off
	s_mov_b32 m0, s30
	s_nop 0
	global_load_lds_dwordx4 v[230:231], off
	s_waitcnt lgkmcnt(0)
	s_barrier
; #define PG8_STAGE(bufoff, gbase, voff) do { _Pragma("unroll") for (int _i = 0; _i < 2; ++_i) \
;         __builtin_amdgcn_global_load_lds((const unsigned*)((const char*)(gbase) + (voff)[_i]), (LAS unsigned*)(lds + (bufoff) + ldsw + _i * 8192), 16, 0, 0); } while (0)
; #define PG8_LDA(dst, b, h) do { _Pragma("unroll") for (int m = 0; m < 4; ++m) _Pragma("unroll") for (int k = 0; k < 2; ++k) dst[m][k] = *(const LAS bf16x8*)(lds + PG8_SA(b, h) + aoff + m * 2048 + k * 1024); } while (0)
; #define PG8_LDB(dst, b, h) do { _Pragma("unroll") for (int n = 0; n < 2; ++n) _Pragma("unroll") for (int k = 0; k < 2; ++k) dst[n][k] = *(const LAS bf16x8*)(lds + PG8_SB(b, h) + boff + n * 2048 + k * 1024); } while (0)
; #define PG8_MMA(ai, bj, At, Bt) do { __builtin_amdgcn_s_setprio(1); _Pragma("unroll") for (int m = 0; m < 4; ++m) _Pragma("unroll") for (int n = 0; n < 2; ++n) _Pragma("unroll") for (int k = 0; k < 2; ++k) \
;         acc[ai][bj][m][n] = __builtin_amdgcn_mfma_f32_16x16x32_bf16(Bt[n][k], At[m][k], acc[ai][bj][m][n], 0, 0, 0); __builtin_amdgcn_s_setprio(0); } while (0)
; #define PG8_WAIT_V(n) asm volatile("s_waitcnt vmcnt(" #n ")" ::: "memory")
; #define PG8_WAIT_L(n) asm volatile("s_waitcnt lgkmcnt(" #n ")" ::: "memory")
; #define PG8_BAR __builtin_amdgcn_s_barrier()
; #define PG8_SCHED __builtin_amdgcn_sched_barrier(0)
; template <class Epi, class Sched, bool ALIGN_EPI = false, bool SP2 = false>
; __device__ __forceinline__ void gemm_phase(LAS unsigned char* lds, const Gemm g, const Sched& S, const Epi& E) {
;     ...
;             PG8_WAIT_V(8); PG8_WAIT_L(0); PG8_BAR; PG8_MMA(1, 0, At, B0); PG8_MMA(1, 1, At, B1); PG8_BAR; PG8_SCHED;
;             PG8_LDB(B0, 1, 0); PG8_LDB(B1, 1, 1); PG8_SCHED; PG8_LDA(At, 1, 0); PG8_STAGE(PG8_SA(0, 1), a2 + hstep, voffA);
;             PG8_WAIT_V(8); PG8_WAIT_L(0); PG8_BAR; PG8_MMA(0, 0, At, B0); PG8_MMA(0, 1, At, B1); PG8_BAR; PG8_SCHED;
	s_setprio 1
	s_waitcnt lgkmcnt(0)
	v_mfma_f32_16x16x32_bf16 v[62:65], v[130:133], v[182:185], 0
	v_mfma_f32_16x16x32_bf16 v[58:61], v[138:141], v[182:185], 0
	v_mfma_f32_16x16x32_bf16 v[46:49], v[130:133], v[202:205], 0
	v_mfma_f32_16x16x32_bf16 v[42:45], v[138:141], v[202:205], 0
	v_mfma_f32_16x16x32_bf16 v[30:33], v[130:133], v[210:213], 0
	v_mfma_f32_16x16x32_bf16 v[26:29], v[138:141], v[210:213], 0
	v_mfma_f32_16x16x32_bf16 v[14:17], v[130:133], v[218:221], 0
	v_mfma_f32_16x16x32_bf16 v[10:13], v[138:141], v[218:221], 0
	v_mfma_f32_16x16x32_bf16 v[62:65], v[134:137], v[186:189], v[62:65]
	v_mfma_f32_16x16x32_bf16 v[58:61], v[142:145], v[186:189], v[58:61]
	v_mfma_f32_16x16x32_bf16 v[46:49], v[134:137], v[206:209], v[46:49]
	v_mfma_f32_16x16x32_bf16 v[42:45], v[142:145], v[206:209], v[42:45]
	v_mfma_f32_16x16x32_bf16 v[30:33], v[134:137], v[214:217], v[30:33]
	v_mfma_f32_16x16x32_bf16 v[26:29], v[142:145], v[214:217], v[26:29]
	v_mfma_f32_16x16x32_bf16 v[14:17], v[134:137], v[222:225], v[14:17]
	v_mfma_f32_16x16x32_bf16 v[10:13], v[142:145], v[222:225], v[10:13]
	v_mfma_f32_16x16x32_bf16 v[54:57], v[166:169], v[182:185], 0
	v_mfma_f32_16x16x32_bf16 v[50:53], v[174:177], v[182:185], 0
	v_mfma_f32_16x16x32_bf16 v[38:41], v[166:169], v[202:205], 0
	v_mfma_f32_16x16x32_bf16 v[34:37], v[174:177], v[202:205], 0
	v_mfma_f32_16x16x32_bf16 v[22:25], v[166:169], v[210:213], 0
	v_mfma_f32_16x16x32_bf16 v[18:21], v[174:177], v[210:213], 0
	v_mfma_f32_16x16x32_bf16 v[6:9], v[166:169], v[218:221], 0
	v_mfma_f32_16x16x32_bf16 v[2:5], v[174:177], v[218:221], 0
	v_mfma_f32_16x16x32_bf16 v[54:57], v[170:173], v[186:189], v[54:57]
	v_mfma_f32_16x16x32_bf16 v[50:53], v[178:181], v[186:189], v[50:53]
	v_mfma_f32_16x16x32_bf16 v[38:41], v[170:173], v[206:209], v[38:41]
	v_mfma_f32_16x16x32_bf16 v[34:37], v[178:181], v[206:209], v[34:37]
	v_mfma_f32_16x16x32_bf16 v[22:25], v[170:173], v[214:217], v[22:25]
	v_mfma_f32_16x16x32_bf16 v[18:21], v[178:181], v[214:217], v[18:21]
	v_mfma_f32_16x16x32_bf16 v[6:9], v[170:173], v[222:225], v[6:9]
	v_mfma_f32_16x16x32_bf16 v[2:5], v[178:181], v[222:225], v[2:5]
	s_setprio 0
	s_barrier
	s_add_i32 s16, 0, 0x18000
	s_add_i32 s17, 0, 0x1c000
	v_add_u32_e32 v142, s16, v1
	v_add_u32_e32 v154, s17, v1
	ds_read_b128 v[130:133], v142
	ds_read_b128 v[134:137], v142 offset:1024
	ds_read_b128 v[138:141], v142 offset:2048
	ds_read_b128 v[142:145], v142 offset:3072
	ds_read_b128 v[166:169], v154
	ds_read_b128 v[170:173], v154 offset:1024
	ds_read_b128 v[174:177], v154 offset:2048
	ds_read_b128 v[178:181], v154 offset:3072
	s_add_u32 s14, s58, 0x160000
	s_addc_u32 s15, s59, 0
	s_mov_b32 m0, s31
	v_lshl_add_u64 v[232:233], s[14:15], 0, v[146:147]
	ds_read_b128 v[182:185], v198 offset:32768
	ds_read_b128 v[186:189], v198 offset:33792
	ds_read_b128 v[202:205], v198 offset:34816
	ds_read_b128 v[206:209], v198 offset:35840
	ds_read_b128 v[210:213], v198 offset:36864
	ds_read_b128 v[214:217], v198 offset:37888
	ds_read_b128 v[218:221], v198 offset:38912
	ds_read_b128 v[222:225], v198 offset:39936
	global_load_lds_dwordx4 v[232:233], off
	v_lshl_add_u64 v[232:233], s[14:15], 0, v[150:151]
	s_mov_b32 m0, s33
	s_nop 0
	global_load_lds_dwordx4 v[232:233], off
	s_waitcnt vmcnt(8)
	s_waitcnt lgkmcnt(0)
	s_barrier
	s_setprio 1
	s_waitcnt lgkmcnt(0)
	v_mfma_f32_16x16x32_bf16 v[126:129], v[130:133], v[182:185], v[126:129]
	v_mfma_f32_16x16x32_bf16 v[122:125], v[138:141], v[182:185], v[122:125]
	v_mfma_f32_16x16x32_bf16 v[110:113], v[130:133], v[202:205], v[110:113]
	v_mfma_f32_16x16x32_bf16 v[106:109], v[138:141], v[202:205], v[106:109]
	v_mfma_f32_16x16x32_bf16 v[94:97], v[130:133], v[210:213], v[94:97]
	v_mfma_f32_16x16x32_bf16 v[90:93], v[138:141], v[210:213], v[90:93]
	v_mfma_f32_16x16x32_bf16 v[78:81], v[130:133], v[218:221], v[78:81]
	v_mfma_f32_16x16x32_bf16 v[74:77], v[138:141], v[218:221], v[74:77]
	v_mfma_f32_16x16x32_bf16 v[126:129], v[134:137], v[186:189], v[126:129]
	v_mfma_f32_16x16x32_bf16 v[122:125], v[142:145], v[186:189], v[122:125]
	v_mfma_f32_16x16x32_bf16 v[110:113], v[134:137], v[206:209], v[110:113]
	v_mfma_f32_16x16x32_bf16 v[106:109], v[142:145], v[206:209], v[106:109]
	v_mfma_f32_16x16x32_bf16 v[94:97], v[134:137], v[214:217], v[94:97]
	v_mfma_f32_16x16x32_bf16 v[90:93], v[142:145], v[214:217], v[90:93]
	v_mfma_f32_16x16x32_bf16 v[78:81], v[134:137], v[222:225], v[78:81]
	v_mfma_f32_16x16x32_bf16 v[74:77], v[142:145], v[222:225], v[74:77]
	v_mfma_f32_16x16x32_bf16 v[118:121], v[166:169], v[182:185], v[118:121]
	v_mfma_f32_16x16x32_bf16 v[114:117], v[174:177], v[182:185], v[114:117]
	v_mfma_f32_16x16x32_bf16 v[102:105], v[166:169], v[202:205], v[102:105]
	v_mfma_f32_16x16x32_bf16 v[98:101], v[174:177], v[202:205], v[98:101]
	v_mfma_f32_16x16x32_bf16 v[86:89], v[166:169], v[210:213], v[86:89]
	v_mfma_f32_16x16x32_bf16 v[82:85], v[174:177], v[210:213], v[82:85]
	v_mfma_f32_16x16x32_bf16 v[70:73], v[166:169], v[218:221], v[70:73]
	v_mfma_f32_16x16x32_bf16 v[66:69], v[174:177], v[218:221], v[66:69]
	v_mfma_f32_16x16x32_bf16 v[118:121], v[170:173], v[186:189], v[118:121]
	v_mfma_f32_16x16x32_bf16 v[114:117], v[178:181], v[186:189], v[114:117]
	v_mfma_f32_16x16x32_bf16 v[102:105], v[170:173], v[206:209], v[102:105]
	v_mfma_f32_16x16x32_bf16 v[98:101], v[178:181], v[206:209], v[98:101]
	v_mfma_f32_16x16x32_bf16 v[86:89], v[170:173], v[214:217], v[86:89]
	v_mfma_f32_16x16x32_bf16 v[82:85], v[178:181], v[214:217], v[82:85]
	v_mfma_f32_16x16x32_bf16 v[70:73], v[170:173], v[222:225], v[70:73]
	v_mfma_f32_16x16x32_bf16 v[66:69], v[178:181], v[222:225], v[66:69]
	s_setprio 0
	s_barrier
; #define PG8_STAGE(bufoff, gbase, voff) do { _Pragma("unroll") for (int _i = 0; _i < 2; ++_i) \
;         __builtin_amdgcn_global_load_lds((const unsigned*)((const char*)(gbase) + (voff)[_i]), (LAS unsigned*)(lds + (bufoff) + ldsw + _i * 8192), 16, 0, 0); } while (0)
; #define PG8_LDA(dst, b, h) do { _Pragma("unroll") for (int m = 0; m < 4; ++m) _Pragma("unroll") for (int k = 0; k < 2; ++k) dst[m][k] = *(const LAS bf16x8*)(lds + PG8_SA(b, h) + aoff + m * 2048 + k * 1024); } while (0)
; #define PG8_LDB(dst, b, h) do { _Pragma("unroll") for (int n = 0; n < 2; ++n) _Pragma("unroll") for (int k = 0; k < 2; ++k) dst[n][k] = *(const LAS bf16x8*)(lds + PG8_SB(b, h) + boff + n * 2048 + k * 1024); } while (0)
; #define PG8_MMA(ai, bj, At, Bt) do { __builtin_amdgcn_s_setprio(1); _Pragma("unroll") for (int m = 0; m < 4; ++m) _Pragma("unroll") for (int n = 0; n < 2; ++n) _Pragma("unroll") for (int k = 0; k < 2; ++k) \
;         acc[ai][bj][m][n] = __builtin_amdgcn_mfma_f32_16x16x32_bf16(Bt[n][k], At[m][k], acc[ai][bj][m][n], 0, 0, 0); __builtin_amdgcn_s_setprio(0); } while (0)
; #define PG8_WAIT_V(n) asm volatile("s_waitcnt vmcnt(" #n ")" ::: "memory")
; #define PG8_WAIT_L(n) asm volatile("s_waitcnt lgkmcnt(" #n ")" ::: "memory")
; #define PG8_BAR __builtin_amdgcn_s_barrier()
; #define PG8_SCHED __builtin_amdgcn_sched_barrier(0)
; template <class Epi, class Sched, bool ALIGN_EPI = false, bool SP2 = false>
; __device__ __forceinline__ void gemm_phase(LAS unsigned char* lds, const Gemm g, const Sched& S, const Epi& E) {
;     ...
;         for (int t = 0; t < nt; t += 2) {
;             const bool last = (t == nt - 2);
;             const char* a1 = cA + (size_t)(t + 1) * kstep;
;             const char* a2 = last ? nA : cA + (size_t)(t + 2) * kstep; const char* b2 = last ? nB : cB + (size_t)(t + 2) * kstep;
;             const char* a3 = a2 + kstep; const char* b3 = b2 + kstep;
;             if (last && has_next) S.a_ready(nxt);
;             if constexpr (SP2) {
;             PG8_LDB(B0, 0, 0); PG8_LDB(B1, 0, 1); PG8_SCHED; PG8_LDA(At, 0, 0); PG8_STAGE(PG8_SA(1, 1), a1 + hstep, voffA);
;     ...
;             PG8_LDA(At, 1, 1); PG8_STAGE(PG8_SB(1, 0), b3, voffB); PG8_STAGE(PG8_SB(1, 1), b3 + hstepB, voffB); PG8_STAGE(PG8_SA(1, 0), a3, voffA);
;             PG8_WAIT_V(8); PG8_WAIT_L(0); PG8_BAR; PG8_MMA(1, 0, At, B0); PG8_MMA(1, 1, At, B1); PG8_BAR; PG8_SCHED;
	s_add_i32 s14, s16, s28
	v_lshl_add_u64 v[190:191], v[190:191], 0, s[48:49]
	s_mov_b32 m0, s14
	ds_read_b128 v[182:185], v198 offset:49152
	ds_read_b128 v[186:189], v198 offset:50176
	ds_read_b128 v[202:205], v198 offset:51200
	ds_read_b128 v[206:209], v198 offset:52224
	ds_read_b128 v[210:213], v198 offset:53248
	ds_read_b128 v[214:217], v198 offset:54272
	ds_read_b128 v[218:221], v198 offset:55296
	ds_read_b128 v[222:225], v198 offset:56320
	global_load_lds_dwordx4 v[190:191], off
	s_add_i32 m0, s14, 0x2000
	s_add_u32 s14, s56, 0x58080
	v_lshl_add_u64 v[190:191], v[226:227], 0, s[48:49]
	s_addc_u32 s15, s57, 0
	s_add_i32 s16, s17, s28
	global_load_lds_dwordx4 v[190:191], off
	v_lshl_add_u64 v[190:191], s[14:15], 0, v[148:149]
	s_mov_b32 m0, s16
	s_nop 0
	global_load_lds_dwordx4 v[190:191], off
	v_lshl_add_u64 v[190:191], s[14:15], 0, v[152:153]
	s_add_i32 m0, s16, 0x2000
	s_nop 0
	global_load_lds_dwordx4 v[190:191], off
	v_lshl_add_u64 v[190:191], v[228:229], 0, s[48:49]
	s_mov_b32 m0, s61
	s_nop 0
	global_load_lds_dwordx4 v[190:191], off
	v_lshl_add_u64 v[190:191], v[230:231], 0, s[48:49]
	s_mov_b32 m0, s62
	s_nop 0
	global_load_lds_dwordx4 v[190:191], off
	s_waitcnt vmcnt(8)
	s_waitcnt lgkmcnt(0)
	s_barrier
	s_setprio 1
	s_waitcnt lgkmcnt(0)
	v_mfma_f32_16x16x32_bf16 v[62:65], v[130:133], v[182:185], v[62:65]
	v_mfma_f32_16x16x32_bf16 v[58:61], v[138:141], v[182:185], v[58:61]
	v_mfma_f32_16x16x32_bf16 v[46:49], v[130:133], v[202:205], v[46:49]
	v_mfma_f32_16x16x32_bf16 v[42:45], v[138:141], v[202:205], v[42:45]
	v_mfma_f32_16x16x32_bf16 v[30:33], v[130:133], v[210:213], v[30:33]
	v_mfma_f32_16x16x32_bf16 v[26:29], v[138:141], v[210:213], v[26:29]
	v_mfma_f32_16x16x32_bf16 v[14:17], v[130:133], v[218:221], v[14:17]
	v_mfma_f32_16x16x32_bf16 v[10:13], v[138:141], v[218:221], v[10:13]
	v_mfma_f32_16x16x32_bf16 v[62:65], v[134:137], v[186:189], v[62:65]
	v_mfma_f32_16x16x32_bf16 v[58:61], v[142:145], v[186:189], v[58:61]
	v_mfma_f32_16x16x32_bf16 v[46:49], v[134:137], v[206:209], v[46:49]
	v_mfma_f32_16x16x32_bf16 v[42:45], v[142:145], v[206:209], v[42:45]
	v_mfma_f32_16x16x32_bf16 v[30:33], v[134:137], v[214:217], v[30:33]
	v_mfma_f32_16x16x32_bf16 v[26:29], v[142:145], v[214:217], v[26:29]
	v_mfma_f32_16x16x32_bf16 v[14:17], v[134:137], v[222:225], v[14:17]
	v_mfma_f32_16x16x32_bf16 v[10:13], v[142:145], v[222:225], v[10:13]
	v_mfma_f32_16x16x32_bf16 v[54:57], v[166:169], v[182:185], v[54:57]
	v_mfma_f32_16x16x32_bf16 v[50:53], v[174:177], v[182:185], v[50:53]
	v_mfma_f32_16x16x32_bf16 v[38:41], v[166:169], v[202:205], v[38:41]
	v_mfma_f32_16x16x32_bf16 v[34:37], v[174:177], v[202:205], v[34:37]
	v_mfma_f32_16x16x32_bf16 v[22:25], v[166:169], v[210:213], v[22:25]
	v_mfma_f32_16x16x32_bf16 v[18:21], v[174:177], v[210:213], v[18:21]
	v_mfma_f32_16x16x32_bf16 v[6:9], v[166:169], v[218:221], v[6:9]
	v_mfma_f32_16x16x32_bf16 v[2:5], v[174:177], v[218:221], v[2:5]
	v_mfma_f32_16x16x32_bf16 v[54:57], v[170:173], v[186:189], v[54:57]
	v_mfma_f32_16x16x32_bf16 v[50:53], v[178:181], v[186:189], v[50:53]
	v_mfma_f32_16x16x32_bf16 v[38:41], v[170:173], v[206:209], v[38:41]
	v_mfma_f32_16x16x32_bf16 v[34:37], v[178:181], v[206:209], v[34:37]
	v_mfma_f32_16x16x32_bf16 v[22:25], v[170:173], v[214:217], v[22:25]
	v_mfma_f32_16x16x32_bf16 v[18:21], v[178:181], v[214:217], v[18:21]
	v_mfma_f32_16x16x32_bf16 v[6:9], v[170:173], v[222:225], v[6:9]
	v_mfma_f32_16x16x32_bf16 v[2:5], v[178:181], v[222:225], v[2:5]
	s_setprio 0
	s_barrier
	s_add_i32 s13, s13, 2
	s_add_u32 s5, s5, 0x100
	s_addc_u32 s12, s12, 0
	s_cmpk_gt_u32 s13, 0x55
	s_mov_b64 s[16:17], s[54:55]
.LBB0_317:
	ds_read_b128 v[130:133], v196
	ds_read_b128 v[134:137], v196 offset:1024
	ds_read_b128 v[138:141], v196 offset:2048
	ds_read_b128 v[142:145], v196 offset:3072
	ds_read_b128 v[166:169], v197
	ds_read_b128 v[170:173], v197 offset:1024
	ds_read_b128 v[174:177], v197 offset:2048
	ds_read_b128 v[178:181], v197 offset:3072
	s_add_u32 s54, s16, 0x100
	s_addc_u32 s55, s17, 0
	s_cmpk_eq_i32 s13, 0x54
	s_cselect_b32 s59, s3, s55
	s_cselect_b32 s58, s2, s54
	s_cselect_b32 s57, s53, s12
	s_cselect_b32 s56, s52, s5
	v_lshl_add_u64 v[190:191], s[16:17], 0, v[158:159]
	s_add_i32 m0, s29, 0xc000
	ds_read_b128 v[182:185], v198
	ds_read_b128 v[186:189], v198 offset:1024
	ds_read_b128 v[202:205], v198 offset:2048
	ds_read_b128 v[206:209], v198 offset:3072
	ds_read_b128 v[210:213], v198 offset:4096
	ds_read_b128 v[214:217], v198 offset:5120
	ds_read_b128 v[218:221], v198 offset:6144
	ds_read_b128 v[222:225], v198 offset:7168
	global_load_lds_dwordx4 v[190:191], off
	v_lshl_add_u64 v[190:191], s[16:17], 0, v[160:161]
	s_add_i32 m0, s29, 0xe000
	s_nop 0
	global_load_lds_dwordx4 v[190:191], off
	s_waitcnt vmcnt(8)
	s_waitcnt lgkmcnt(0)
	s_barrier
; #define PG8_STAGE(bufoff, gbase, voff) do { _Pragma("unroll") for (int _i = 0; _i < 2; ++_i) \
;         __builtin_amdgcn_global_load_lds((const unsigned*)((const char*)(gbase) + (voff)[_i]), (LAS unsigned*)(lds + (bufoff) + ldsw + _i * 8192), 16, 0, 0); } while (0)
; #define PG8_LDA(dst, b, h) do { _Pragma("unroll") for (int m = 0; m < 4; ++m) _Pragma("unroll") for (int k = 0; k < 2; ++k) dst[m][k] = *(const LAS bf16x8*)(lds + PG8_SA(b, h) + aoff + m * 2048 + k * 1024); } while (0)
; #define PG8_MMA(ai, bj, At, Bt) do { __builtin_amdgcn_s_setprio(1); _Pragma("unroll") for (int m = 0; m < 4; ++m) _Pragma("unroll") for (int n = 0; n < 2; ++n) _Pragma("unroll") for (int k = 0; k < 2; ++k) \
;         acc[ai][bj][m][n] = __builtin_amdgcn_mfma_f32_16x16x32_bf16(Bt[n][k], At[m][k], acc[ai][bj][m][n], 0, 0, 0); __builtin_amdgcn_s_setprio(0); } while (0)
; #define PG8_WAIT_V(n) asm volatile("s_waitcnt vmcnt(" #n ")" ::: "memory")
; #define PG8_WAIT_L(n) asm volatile("s_waitcnt lgkmcnt(" #n ")" ::: "memory")
; #define PG8_BAR __builtin_amdgcn_s_barrier()
; #define PG8_SCHED __builtin_amdgcn_sched_barrier(0)
; template <class Epi, class Sched, bool ALIGN_EPI = false, bool SP2 = false>
; __device__ __forceinline__ void gemm_phase(LAS unsigned char* lds, const Gemm g, const Sched& S, const Epi& E) {
;     ...
;             PG8_WAIT_V(8); PG8_WAIT_L(0); PG8_BAR; PG8_MMA(0, 0, At, B0); PG8_MMA(0, 1, At, B1); PG8_BAR; PG8_SCHED;
;             PG8_LDA(At, 0, 1); PG8_STAGE(PG8_SB(0, 0), b2, voffB); PG8_STAGE(PG8_SB(0, 1), b2 + hstepB, voffB); PG8_STAGE(PG8_SA(0, 0), a2, voffA);
;             PG8_WAIT_V(8); PG8_WAIT_L(0); PG8_BAR; PG8_MMA(1, 0, At, B0); PG8_MMA(1, 1, At, B1); PG8_BAR; PG8_SCHED;
	s_setprio 1
	s_waitcnt lgkmcnt(0)
	v_mfma_f32_16x16x32_bf16 v[126:129], v[130:133], v[182:185], v[126:129]
	v_mfma_f32_16x16x32_bf16 v[122:125], v[138:141], v[182:185], v[122:125]
	v_mfma_f32_16x16x32_bf16 v[110:113], v[130:133], v[202:205], v[110:113]
	v_mfma_f32_16x16x32_bf16 v[106:109], v[138:141], v[202:205], v[106:109]
	v_mfma_f32_16x16x32_bf16 v[94:97], v[130:133], v[210:213], v[94:97]
	v_mfma_f32_16x16x32_bf16 v[90:93], v[138:141], v[210:213], v[90:93]
	v_mfma_f32_16x16x32_bf16 v[78:81], v[130:133], v[218:221], v[78:81]
	v_mfma_f32_16x16x32_bf16 v[74:77], v[138:141], v[218:221], v[74:77]
	v_mfma_f32_16x16x32_bf16 v[126:129], v[134:137], v[186:189], v[126:129]
	v_mfma_f32_16x16x32_bf16 v[122:125], v[142:145], v[186:189], v[122:125]
	v_mfma_f32_16x16x32_bf16 v[110:113], v[134:137], v[206:209], v[110:113]
	v_mfma_f32_16x16x32_bf16 v[106:109], v[142:145], v[206:209], v[106:109]
	v_mfma_f32_16x16x32_bf16 v[94:97], v[134:137], v[214:217], v[94:97]
	v_mfma_f32_16x16x32_bf16 v[90:93], v[142:145], v[214:217], v[90:93]
	v_mfma_f32_16x16x32_bf16 v[78:81], v[134:137], v[222:225], v[78:81]
	v_mfma_f32_16x16x32_bf16 v[74:77], v[142:145], v[222:225], v[74:77]
	v_mfma_f32_16x16x32_bf16 v[118:121], v[166:169], v[182:185], v[118:121]
	v_mfma_f32_16x16x32_bf16 v[114:117], v[174:177], v[182:185], v[114:117]
	v_mfma_f32_16x16x32_bf16 v[102:105], v[166:169], v[202:205], v[102:105]
	v_mfma_f32_16x16x32_bf16 v[98:101], v[174:177], v[202:205], v[98:101]
	v_mfma_f32_16x16x32_bf16 v[86:89], v[166:169], v[210:213], v[86:89]
	v_mfma_f32_16x16x32_bf16 v[82:85], v[174:177], v[210:213], v[82:85]
	v_mfma_f32_16x16x32_bf16 v[70:73], v[166:169], v[218:221], v[70:73]
	v_mfma_f32_16x16x32_bf16 v[66:69], v[174:177], v[218:221], v[66:69]
	v_mfma_f32_16x16x32_bf16 v[118:121], v[170:173], v[186:189], v[118:121]
	v_mfma_f32_16x16x32_bf16 v[114:117], v[178:181], v[186:189], v[114:117]
	v_mfma_f32_16x16x32_bf16 v[102:105], v[170:173], v[206:209], v[102:105]
	v_mfma_f32_16x16x32_bf16 v[98:101], v[178:181], v[206:209], v[98:101]
	v_mfma_f32_16x16x32_bf16 v[86:89], v[170:173], v[214:217], v[86:89]
	v_mfma_f32_16x16x32_bf16 v[82:85], v[178:181], v[214:217], v[82:85]
	v_mfma_f32_16x16x32_bf16 v[70:73], v[170:173], v[222:225], v[70:73]
	v_mfma_f32_16x16x32_bf16 v[66:69], v[178:181], v[222:225], v[66:69]
	s_setprio 0
	s_barrier
	s_add_i32 s14, s64, s28
	v_lshl_add_u64 v[190:191], s[56:57], 0, v[148:149]
	s_mov_b32 m0, s14
	ds_read_b128 v[182:185], v198 offset:16384
	ds_read_b128 v[186:189], v198 offset:17408
	ds_read_b128 v[202:205], v198 offset:18432
	ds_read_b128 v[206:209], v198 offset:19456
	ds_read_b128 v[210:213], v198 offset:20480
	ds_read_b128 v[214:217], v198 offset:21504
	ds_read_b128 v[218:221], v198 offset:22528
	ds_read_b128 v[222:225], v198 offset:23552
	global_load_lds_dwordx4 v[190:191], off
	s_add_i32 m0, s14, 0x2000
	s_add_u32 s14, s56, 0x58000
	v_lshl_add_u64 v[226:227], s[56:57], 0, v[152:153]
	s_addc_u32 s15, s57, 0
	s_add_i32 s16, s65, s28
	global_load_lds_dwordx4 v[226:227], off
	v_lshl_add_u64 v[228:229], s[14:15], 0, v[148:149]
	s_mov_b32 m0, s16
	v_lshl_add_u64 v[230:231], s[58:59], 0, v[150:151]
	global_load_lds_dwordx4 v[228:229], off
	v_lshl_add_u64 v[228:229], s[14:15], 0, v[152:153]
	s_add_i32 m0, s16, 0x2000
	s_nop 0
	global_load_lds_dwordx4 v[228:229], off
	v_lshl_add_u64 v[228:229], s[58:59], 0, v[146:147]
	s_mov_b32 m0, s29
	s_nop 0
	global_load_lds_dwordx4 v[228:229], off
	s_mov_b32 m0, s30
	s_nop 0
	global_load_lds_dwordx4 v[230:231], off
	s_waitcnt vmcnt(8)
	s_waitcnt lgkmcnt(0)
	s_barrier
	s_setprio 1
	s_waitcnt lgkmcnt(0)
	v_mfma_f32_16x16x32_bf16 v[62:65], v[130:133], v[182:185], v[62:65]
	v_mfma_f32_16x16x32_bf16 v[58:61], v[138:141], v[182:185], v[58:61]
	v_mfma_f32_16x16x32_bf16 v[46:49], v[130:133], v[202:205], v[46:49]
	v_mfma_f32_16x16x32_bf16 v[42:45], v[138:141], v[202:205], v[42:45]
	v_mfma_f32_16x16x32_bf16 v[30:33], v[130:133], v[210:213], v[30:33]
	v_mfma_f32_16x16x32_bf16 v[26:29], v[138:141], v[210:213], v[26:29]
	v_mfma_f32_16x16x32_bf16 v[14:17], v[130:133], v[218:221], v[14:17]
	v_mfma_f32_16x16x32_bf16 v[10:13], v[138:141], v[218:221], v[10:13]
	v_mfma_f32_16x16x32_bf16 v[62:65], v[134:137], v[186:189], v[62:65]
	v_mfma_f32_16x16x32_bf16 v[58:61], v[142:145], v[186:189], v[58:61]
	v_mfma_f32_16x16x32_bf16 v[46:49], v[134:137], v[206:209], v[46:49]
	v_mfma_f32_16x16x32_bf16 v[42:45], v[142:145], v[206:209], v[42:45]
	v_mfma_f32_16x16x32_bf16 v[30:33], v[134:137], v[214:217], v[30:33]
	v_mfma_f32_16x16x32_bf16 v[26:29], v[142:145], v[214:217], v[26:29]
	v_mfma_f32_16x16x32_bf16 v[14:17], v[134:137], v[222:225], v[14:17]
	v_mfma_f32_16x16x32_bf16 v[10:13], v[142:145], v[222:225], v[10:13]
	v_mfma_f32_16x16x32_bf16 v[54:57], v[166:169], v[182:185], v[54:57]
	v_mfma_f32_16x16x32_bf16 v[50:53], v[174:177], v[182:185], v[50:53]
	v_mfma_f32_16x16x32_bf16 v[38:41], v[166:169], v[202:205], v[38:41]
	v_mfma_f32_16x16x32_bf16 v[34:37], v[174:177], v[202:205], v[34:37]
	v_mfma_f32_16x16x32_bf16 v[22:25], v[166:169], v[210:213], v[22:25]
	v_mfma_f32_16x16x32_bf16 v[18:21], v[174:177], v[210:213], v[18:21]
	v_mfma_f32_16x16x32_bf16 v[6:9], v[166:169], v[218:221], v[6:9]
	v_mfma_f32_16x16x32_bf16 v[2:5], v[174:177], v[218:221], v[2:5]
	v_mfma_f32_16x16x32_bf16 v[54:57], v[170:173], v[186:189], v[54:57]
	v_mfma_f32_16x16x32_bf16 v[50:53], v[178:181], v[186:189], v[50:53]
	v_mfma_f32_16x16x32_bf16 v[38:41], v[170:173], v[206:209], v[38:41]
	v_mfma_f32_16x16x32_bf16 v[34:37], v[178:181], v[206:209], v[34:37]
	v_mfma_f32_16x16x32_bf16 v[22:25], v[170:173], v[214:217], v[22:25]
	v_mfma_f32_16x16x32_bf16 v[18:21], v[178:181], v[214:217], v[18:21]
	v_mfma_f32_16x16x32_bf16 v[6:9], v[170:173], v[222:225], v[6:9]
	v_mfma_f32_16x16x32_bf16 v[2:5], v[178:181], v[222:225], v[2:5]
	s_setprio 0
	s_barrier
; #define PG8_STAGE(bufoff, gbase, voff) do { _Pragma("unroll") for (int _i = 0; _i < 2; ++_i) \
;         __builtin_amdgcn_global_load_lds((const unsigned*)((const char*)(gbase) + (voff)[_i]), (LAS unsigned*)(lds + (bufoff) + ldsw + _i * 8192), 16, 0, 0); } while (0)
; #define PG8_LDA(dst, b, h) do { _Pragma("unroll") for (int m = 0; m < 4; ++m) _Pragma("unroll") for (int k = 0; k < 2; ++k) dst[m][k] = *(const LAS bf16x8*)(lds + PG8_SA(b, h) + aoff + m * 2048 + k * 1024); } while (0)
; #define PG8_LDB(dst, b, h) do { _Pragma("unroll") for (int n = 0; n < 2; ++n) _Pragma("unroll") for (int k = 0; k < 2; ++k) dst[n][k] = *(const LAS bf16x8*)(lds + PG8_SB(b, h) + boff + n * 2048 + k * 1024); } while (0)
; #define PG8_MMA(ai, bj, At, Bt) do { __builtin_amdgcn_s_setprio(1); _Pragma("unroll") for (int m = 0; m < 4; ++m) _Pragma("unroll") for (int n = 0; n < 2; ++n) _Pragma("unroll") for (int k = 0; k < 2; ++k) \
;         acc[ai][bj][m][n] = __builtin_amdgcn_mfma_f32_16x16x32_bf16(Bt[n][k], At[m][k], acc[ai][bj][m][n], 0, 0, 0); __builtin_amdgcn_s_setprio(0); } while (0)
; #define PG8_WAIT_V(n) asm volatile("s_waitcnt vmcnt(" #n ")" ::: "memory")
; #define PG8_WAIT_L(n) asm volatile("s_waitcnt lgkmcnt(" #n ")" ::: "memory")
; #define PG8_BAR __builtin_amdgcn_s_barrier()
; #define PG8_SCHED __builtin_amdgcn_sched_barrier(0)
; template <class Epi, class Sched, bool ALIGN_EPI = false, bool SP2 = false>
; __device__ __forceinline__ void gemm_phase(LAS unsigned char* lds, const Gemm g, const Sched& S, const Epi& E) {
;     ...
;             PG8_LDB(B0, 1, 0); PG8_LDB(B1, 1, 1); PG8_SCHED; PG8_LDA(At, 1, 0); PG8_STAGE(PG8_SA(0, 1), a2 + hstep, voffA);
;             PG8_WAIT_V(8); PG8_WAIT_L(0); PG8_BAR; PG8_MMA(0, 0, At, B0); PG8_MMA(0, 1, At, B1); PG8_BAR; PG8_SCHED;
	s_add_i32 s16, 0, 0x18000
	s_add_i32 s17, 0, 0x1c000
	v_add_u32_e32 v142, s16, v1
	v_add_u32_e32 v154, s17, v1
	ds_read_b128 v[130:133], v142
	ds_read_b128 v[134:137], v142 offset:1024
	ds_read_b128 v[138:141], v142 offset:2048
	ds_read_b128 v[142:145], v142 offset:3072
	ds_read_b128 v[166:169], v154
	ds_read_b128 v[170:173], v154 offset:1024
	ds_read_b128 v[174:177], v154 offset:2048
	ds_read_b128 v[178:181], v154 offset:3072
	s_add_u32 s14, s58, 0x160000
	s_addc_u32 s15, s59, 0
	s_mov_b32 m0, s31
	v_lshl_add_u64 v[232:233], s[14:15], 0, v[146:147]
	ds_read_b128 v[182:185], v198 offset:32768
	ds_read_b128 v[186:189], v198 offset:33792
	ds_read_b128 v[202:205], v198 offset:34816
	ds_read_b128 v[206:209], v198 offset:35840
	ds_read_b128 v[210:213], v198 offset:36864
	ds_read_b128 v[214:217], v198 offset:37888
	ds_read_b128 v[218:221], v198 offset:38912
	ds_read_b128 v[222:225], v198 offset:39936
	global_load_lds_dwordx4 v[232:233], off
	v_lshl_add_u64 v[232:233], s[14:15], 0, v[150:151]
	s_mov_b32 m0, s33
	s_nop 0
	global_load_lds_dwordx4 v[232:233], off
	s_waitcnt vmcnt(8)
	s_waitcnt lgkmcnt(0)
	s_barrier
	s_setprio 1
	s_waitcnt lgkmcnt(0)
	v_mfma_f32_16x16x32_bf16 v[126:129], v[130:133], v[182:185], v[126:129]
	v_mfma_f32_16x16x32_bf16 v[122:125], v[138:141], v[182:185], v[122:125]
	v_mfma_f32_16x16x32_bf16 v[110:113], v[130:133], v[202:205], v[110:113]
	v_mfma_f32_16x16x32_bf16 v[106:109], v[138:141], v[202:205], v[106:109]
	v_mfma_f32_16x16x32_bf16 v[94:97], v[130:133], v[210:213], v[94:97]
	v_mfma_f32_16x16x32_bf16 v[90:93], v[138:141], v[210:213], v[90:93]
	v_mfma_f32_16x16x32_bf16 v[78:81], v[130:133], v[218:221], v[78:81]
	v_mfma_f32_16x16x32_bf16 v[74:77], v[138:141], v[218:221], v[74:77]
	v_mfma_f32_16x16x32_bf16 v[126:129], v[134:137], v[186:189], v[126:129]
	v_mfma_f32_16x16x32_bf16 v[122:125], v[142:145], v[186:189], v[122:125]
	v_mfma_f32_16x16x32_bf16 v[110:113], v[134:137], v[206:209], v[110:113]
	v_mfma_f32_16x16x32_bf16 v[106:109], v[142:145], v[206:209], v[106:109]
	v_mfma_f32_16x16x32_bf16 v[94:97], v[134:137], v[214:217], v[94:97]
	v_mfma_f32_16x16x32_bf16 v[90:93], v[142:145], v[214:217], v[90:93]
	v_mfma_f32_16x16x32_bf16 v[78:81], v[134:137], v[222:225], v[78:81]
	v_mfma_f32_16x16x32_bf16 v[74:77], v[142:145], v[222:225], v[74:77]
	v_mfma_f32_16x16x32_bf16 v[118:121], v[166:169], v[182:185], v[118:121]
	v_mfma_f32_16x16x32_bf16 v[114:117], v[174:177], v[182:185], v[114:117]
	v_mfma_f32_16x16x32_bf16 v[102:105], v[166:169], v[202:205], v[102:105]
	v_mfma_f32_16x16x32_bf16 v[98:101], v[174:177], v[202:205], v[98:101]
	v_mfma_f32_16x16x32_bf16 v[86:89], v[166:169], v[210:213], v[86:89]
	v_mfma_f32_16x16x32_bf16 v[82:85], v[174:177], v[210:213], v[82:85]
	v_mfma_f32_16x16x32_bf16 v[70:73], v[166:169], v[218:221], v[70:73]
	v_mfma_f32_16x16x32_bf16 v[66:69], v[174:177], v[218:221], v[66:69]
	v_mfma_f32_16x16x32_bf16 v[118:121], v[170:173], v[186:189], v[118:121]
	v_mfma_f32_16x16x32_bf16 v[114:117], v[178:181], v[186:189], v[114:117]
	v_mfma_f32_16x16x32_bf16 v[102:105], v[170:173], v[206:209], v[102:105]
	v_mfma_f32_16x16x32_bf16 v[98:101], v[178:181], v[206:209], v[98:101]
	v_mfma_f32_16x16x32_bf16 v[86:89], v[170:173], v[214:217], v[86:89]
	v_mfma_f32_16x16x32_bf16 v[82:85], v[178:181], v[214:217], v[82:85]
	v_mfma_f32_16x16x32_bf16 v[70:73], v[170:173], v[222:225], v[70:73]
	v_mfma_f32_16x16x32_bf16 v[66:69], v[178:181], v[222:225], v[66:69]
	s_setprio 0
	s_barrier
; #define PG8_STAGE(bufoff, gbase, voff) do { _Pragma("unroll") for (int _i = 0; _i < 2; ++_i) \
;         __builtin_amdgcn_global_load_lds((const unsigned*)((const char*)(gbase) + (voff)[_i]), (LAS unsigned*)(lds + (bufoff) + ldsw + _i * 8192), 16, 0, 0); } while (0)
; #define PG8_LDA(dst, b, h) do { _Pragma("unroll") for (int m = 0; m < 4; ++m) _Pragma("unroll") for (int k = 0; k < 2; ++k) dst[m][k] = *(const LAS bf16x8*)(lds + PG8_SA(b, h) + aoff + m * 2048 + k * 1024); } while (0)
; #define PG8_MMA(ai, bj, At, Bt) do { __builtin_amdgcn_s_setprio(1); _Pragma("unroll") for (int m = 0; m < 4; ++m) _Pragma("unroll") for (int n = 0; n < 2; ++n) _Pragma("unroll") for (int k = 0; k < 2; ++k) \
;         acc[ai][bj][m][n] = __builtin_amdgcn_mfma_f32_16x16x32_bf16(Bt[n][k], At[m][k], acc[ai][bj][m][n], 0, 0, 0); __builtin_amdgcn_s_setprio(0); } while (0)
; #define PG8_WAIT_V(n) asm volatile("s_waitcnt vmcnt(" #n ")" ::: "memory")
; #define PG8_WAIT_L(n) asm volatile("s_waitcnt lgkmcnt(" #n ")" ::: "memory")
; #define PG8_BAR __builtin_amdgcn_s_barrier()
; #define PG8_SCHED __builtin_amdgcn_sched_barrier(0)
; template <class Epi, class Sched, bool ALIGN_EPI = false, bool SP2 = false>
; __device__ __forceinline__ void gemm_phase(LAS unsigned char* lds, const Gemm g, const Sched& S, const Epi& E) {
;     ...
;             PG8_LDA(At, 1, 1); PG8_STAGE(PG8_SB(1, 0), b3, voffB); PG8_STAGE(PG8_SB(1, 1), b3 + hstepB, voffB); PG8_STAGE(PG8_SA(1, 0), a3, voffA);
;             PG8_WAIT_V(8); PG8_WAIT_L(0); PG8_BAR; PG8_MMA(1, 0, At, B0); PG8_MMA(1, 1, At, B1); PG8_BAR; PG8_SCHED;
	s_add_i32 s14, s16, s28
	v_lshl_add_u64 v[190:191], v[190:191], 0, s[48:49]
	s_mov_b32 m0, s14
	ds_read_b128 v[182:185], v198 offset:49152
	ds_read_b128 v[186:189], v198 offset:50176
	ds_read_b128 v[202:205], v198 offset:51200
	ds_read_b128 v[206:209], v198 offset:52224
	ds_read_b128 v[210:213], v198 offset:53248
	ds_read_b128 v[214:217], v198 offset:54272
	ds_read_b128 v[218:221], v198 offset:55296
	ds_read_b128 v[222:225], v198 offset:56320
	global_load_lds_dwordx4 v[190:191], off
	s_add_i32 m0, s14, 0x2000
	s_add_u32 s14, s56, 0x58080
	v_lshl_add_u64 v[190:191], v[226:227], 0, s[48:49]
	s_addc_u32 s15, s57, 0
	s_add_i32 s16, s17, s28
	global_load_lds_dwordx4 v[190:191], off
	v_lshl_add_u64 v[190:191], s[14:15], 0, v[148:149]
	s_mov_b32 m0, s16
	s_nop 0
	global_load_lds_dwordx4 v[190:191], off
	v_lshl_add_u64 v[190:191], s[14:15], 0, v[152:153]
	s_add_i32 m0, s16, 0x2000
	s_nop 0
	global_load_lds_dwordx4 v[190:191], off
	v_lshl_add_u64 v[190:191], v[228:229], 0, s[48:49]
	s_mov_b32 m0, s61
	s_nop 0
	global_load_lds_dwordx4 v[190:191], off
	v_lshl_add_u64 v[190:191], v[230:231], 0, s[48:49]
	s_mov_b32 m0, s62
	s_nop 0
	global_load_lds_dwordx4 v[190:191], off
	s_waitcnt vmcnt(8)
	s_waitcnt lgkmcnt(0)
	s_barrier
	s_setprio 1
	s_waitcnt lgkmcnt(0)
	v_mfma_f32_16x16x32_bf16 v[62:65], v[130:133], v[182:185], v[62:65]
	v_mfma_f32_16x16x32_bf16 v[58:61], v[138:141], v[182:185], v[58:61]
	v_mfma_f32_16x16x32_bf16 v[46:49], v[130:133], v[202:205], v[46:49]
	v_mfma_f32_16x16x32_bf16 v[42:45], v[138:141], v[202:205], v[42:45]
	v_mfma_f32_16x16x32_bf16 v[30:33], v[130:133], v[210:213], v[30:33]
	v_mfma_f32_16x16x32_bf16 v[26:29], v[138:141], v[210:213], v[26:29]
	v_mfma_f32_16x16x32_bf16 v[14:17], v[130:133], v[218:221], v[14:17]
	v_mfma_f32_16x16x32_bf16 v[10:13], v[138:141], v[218:221], v[10:13]
	v_mfma_f32_16x16x32_bf16 v[62:65], v[134:137], v[186:189], v[62:65]
	v_mfma_f32_16x16x32_bf16 v[58:61], v[142:145], v[186:189], v[58:61]
	v_mfma_f32_16x16x32_bf16 v[46:49], v[134:137], v[206:209], v[46:49]
	v_mfma_f32_16x16x32_bf16 v[42:45], v[142:145], v[206:209], v[42:45]
	v_mfma_f32_16x16x32_bf16 v[30:33], v[134:137], v[214:217], v[30:33]
	v_mfma_f32_16x16x32_bf16 v[26:29], v[142:145], v[214:217], v[26:29]
	v_mfma_f32_16x16x32_bf16 v[14:17], v[134:137], v[222:225], v[14:17]
	v_mfma_f32_16x16x32_bf16 v[10:13], v[142:145], v[222:225], v[10:13]
	v_mfma_f32_16x16x32_bf16 v[54:57], v[166:169], v[182:185], v[54:57]
	v_mfma_f32_16x16x32_bf16 v[50:53], v[174:177], v[182:185], v[50:53]
	v_mfma_f32_16x16x32_bf16 v[38:41], v[166:169], v[202:205], v[38:41]
	v_mfma_f32_16x16x32_bf16 v[34:37], v[174:177], v[202:205], v[34:37]
	v_mfma_f32_16x16x32_bf16 v[22:25], v[166:169], v[210:213], v[22:25]
	v_mfma_f32_16x16x32_bf16 v[18:21], v[174:177], v[210:213], v[18:21]
	v_mfma_f32_16x16x32_bf16 v[6:9], v[166:169], v[218:221], v[6:9]
	v_mfma_f32_16x16x32_bf16 v[2:5], v[174:177], v[218:221], v[2:5]
	v_mfma_f32_16x16x32_bf16 v[54:57], v[170:173], v[186:189], v[54:57]
	v_mfma_f32_16x16x32_bf16 v[50:53], v[178:181], v[186:189], v[50:53]
	v_mfma_f32_16x16x32_bf16 v[38:41], v[170:173], v[206:209], v[38:41]
	v_mfma_f32_16x16x32_bf16 v[34:37], v[178:181], v[206:209], v[34:37]
	v_mfma_f32_16x16x32_bf16 v[22:25], v[170:173], v[214:217], v[22:25]
	v_mfma_f32_16x16x32_bf16 v[18:21], v[178:181], v[214:217], v[18:21]
	v_mfma_f32_16x16x32_bf16 v[6:9], v[170:173], v[222:225], v[6:9]
	v_mfma_f32_16x16x32_bf16 v[2:5], v[178:181], v[222:225], v[2:5]
	s_setprio 0
	s_barrier
	s_add_i32 s13, s13, 2
	s_add_u32 s5, s5, 0x100
	s_addc_u32 s12, s12, 0
	s_cmpk_gt_u32 s13, 0x55
	s_mov_b64 s[16:17], s[54:55]
	s_cbranch_scc0 .LBB0_317
	s_and_b64 vcc, exec, s[50:51]
	s_cbranch_vccz .LBB0_320
	s_barrier

;     __device__ bool next(int i, Unit& u) const { if (i != 0 || c >= 128) return false; const int t = c >> 2; u.pm = t & 3; u.pn = t >> 2; u.koff = koff_bytes; u.q = c & 3; return true; }
; #define PG8_STAGE(bufoff, gbase, voff) do { _Pragma("unroll") for (int _i = 0; _i < 2; ++_i) \
;         __builtin_amdgcn_global_load_lds((const unsigned*)((const char*)(gbase) + (voff)[_i]), (LAS unsigned*)(lds + (bufoff) + ldsw + _i * 8192), 16, 0, 0); } while (0)
; #define PG8_LDA(dst, b, h) do { _Pragma("unroll") for (int m = 0; m < 4; ++m) _Pragma("unroll") for (int k = 0; k < 2; ++k) dst[m][k] = *(const LAS bf16x8*)(lds + PG8_SA(b, h) + aoff + m * 2048 + k * 1024); } while (0)
; #define PG8_LDB(dst, b, h) do { _Pragma("unroll") for (int n = 0; n < 2; ++n) _Pragma("unroll") for (int k = 0; k < 2; ++k) dst[n][k] = *(const LAS bf16x8*)(lds + PG8_SB(b, h) + boff + n * 2048 + k * 1024); } while (0)
; #define PG8_WAIT_V(n) asm volatile("s_waitcnt vmcnt(" #n ")" ::: "memory")
; #define PG8_WAIT_L(n) asm volatile("s_waitcnt lgkmcnt(" #n ")" ::: "memory")
; #define PG8_BAR __builtin_amdgcn_s_barrier()
; template <class Epi, class Sched, bool ALIGN_EPI = false, bool SP2 = false>
; __device__ __forceinline__ void gemm_phase(LAS unsigned char* lds, const Gemm g, const Sched& S, const Epi& E) {
;     ...
;         const bool has_next = S.next(ui + 1, nxt);
;         const char* nA = has_next ? (const char*)g.A + (size_t)nxt.pm * tstep + nxt.koff : cA; const char* nB = has_next ? (const char*)g.Bt + (size_t)nxt.pn * tstep + nxt.koff : cB;
;         for (int t = 0; t < nt; t += 2) {
;             const bool last = (t == nt - 2);
;             const char* a1 = cA + (size_t)(t + 1) * kstep;
;             const char* a2 = last ? nA : cA + (size_t)(t + 2) * kstep; const char* b2 = last ? nB : cB + (size_t)(t + 2) * kstep;
;             const char* a3 = a2 + kstep; const char* b3 = b2 + kstep;
;             if (last && has_next) S.a_ready(nxt);
;             if constexpr (SP2) {
;             PG8_LDB(B0, 0, 0); PG8_LDB(B1, 0, 1); PG8_SCHED; PG8_LDA(At, 0, 0); PG8_STAGE(PG8_SA(1, 1), a1 + hstep, voffA);
;             PG8_WAIT_V(8); PG8_WAIT_L(0); PG8_BAR; PG8_MMA(0, 0, At, B0); PG8_MMA(0, 1, At, B1); PG8_BAR; PG8_SCHED;
;             PG8_LDA(At, 0, 1); PG8_STAGE(PG8_SB(0, 0), b2, voffB); PG8_STAGE(PG8_SB(0, 1), b2 + hstepB, voffB); PG8_STAGE(PG8_SA(0, 0), a2, voffA);
.LBB0_534:
	s_ashr_i32 s53, s52, 31
	s_lshl_b64 s[14:15], s[52:53], 20
	s_add_u32 s54, s93, s14
	s_addc_u32 s55, s92, s15
	s_and_b64 s[14:15], s[44:45], exec
	s_cselect_b32 s0, s55, s17
	s_cselect_b32 s3, s54, s16
	s_ashr_i32 s51, s50, 31
	s_lshl_b64 s[14:15], s[50:51], 20
	s_add_u32 s56, s27, s14
	s_addc_u32 s57, s28, s15
	s_and_b64 s[14:15], s[44:45], exec
	s_cselect_b32 s14, s57, s49
	s_cselect_b32 s15, s56, s48
	s_add_u32 s16, s16, 0x80080
	s_addc_u32 s17, s17, 0
	s_add_u32 s18, s48, 0x100
	s_addc_u32 s19, s49, 0
	s_mov_b32 s20, -2
	ds_read_b128 v[34:37], v203
	ds_read_b128 v[38:41], v203 offset:1024
	ds_read_b128 v[42:45], v203 offset:2048
	ds_read_b128 v[46:49], v203 offset:3072
	s_waitcnt vmcnt(0)
	ds_read_b128 v[98:101], v204
	ds_read_b128 v[102:105], v204 offset:1024
	ds_read_b128 v[106:109], v204 offset:2048
	ds_read_b128 v[110:113], v204 offset:3072
	s_add_u32 s21, s16, 0xfff80080
	s_addc_u32 s22, s17, -1
	s_cmp_eq_u32 s20, 28
	s_cselect_b32 s59, s0, s22
	s_cselect_b32 s58, s3, s21
	s_cselect_b32 s49, s14, s19
	s_cselect_b32 s48, s15, s18
	v_lshl_add_u64 v[182:183], s[16:17], 0, v[172:173]
	s_add_i32 m0, s30, 0xc000
	ds_read_b128 v[212:215], v205
	ds_read_b128 v[216:219], v205 offset:1024
	ds_read_b128 v[220:223], v205 offset:2048
	ds_read_b128 v[224:227], v205 offset:3072
	ds_read_b128 v[228:231], v205 offset:4096
	ds_read_b128 v[232:235], v205 offset:5120
	ds_read_b128 v[236:239], v205 offset:6144
	ds_read_b128 v[240:243], v205 offset:7168
	global_load_lds_dwordx4 v[182:183], off
	v_lshl_add_u64 v[182:183], s[16:17], 0, v[174:175]
	s_add_i32 m0, s30, 0xe000
	s_nop 0
	global_load_lds_dwordx4 v[182:183], off
	s_waitcnt lgkmcnt(0)
	s_barrier
	s_setprio 1
	s_waitcnt lgkmcnt(0)
	v_mfma_f32_16x16x32_bf16 v[158:161], v[34:37], v[212:215], 0
	v_mfma_f32_16x16x32_bf16 v[154:157], v[42:45], v[212:215], 0
	v_mfma_f32_16x16x32_bf16 v[142:145], v[34:37], v[220:223], 0
	v_mfma_f32_16x16x32_bf16 v[138:141], v[42:45], v[220:223], 0
	v_mfma_f32_16x16x32_bf16 v[126:129], v[34:37], v[228:231], 0
	v_mfma_f32_16x16x32_bf16 v[122:125], v[42:45], v[228:231], 0
	v_mfma_f32_16x16x32_bf16 v[94:97], v[34:37], v[236:239], 0
	v_mfma_f32_16x16x32_bf16 v[90:93], v[42:45], v[236:239], 0
	v_mfma_f32_16x16x32_bf16 v[158:161], v[38:41], v[216:219], v[158:161]
	v_mfma_f32_16x16x32_bf16 v[154:157], v[46:49], v[216:219], v[154:157]
	v_mfma_f32_16x16x32_bf16 v[142:145], v[38:41], v[224:227], v[142:145]
	v_mfma_f32_16x16x32_bf16 v[138:141], v[46:49], v[224:227], v[138:141]
	v_mfma_f32_16x16x32_bf16 v[126:129], v[38:41], v[232:235], v[126:129]
	v_mfma_f32_16x16x32_bf16 v[122:125], v[46:49], v[232:235], v[122:125]
	v_mfma_f32_16x16x32_bf16 v[94:97], v[38:41], v[240:243], v[94:97]
	v_mfma_f32_16x16x32_bf16 v[90:93], v[46:49], v[240:243], v[90:93]
	v_mfma_f32_16x16x32_bf16 v[150:153], v[98:101], v[212:215], 0
	v_mfma_f32_16x16x32_bf16 v[146:149], v[106:109], v[212:215], 0
	v_mfma_f32_16x16x32_bf16 v[134:137], v[98:101], v[220:223], 0
	v_mfma_f32_16x16x32_bf16 v[130:133], v[106:109], v[220:223], 0
	v_mfma_f32_16x16x32_bf16 v[118:121], v[98:101], v[228:231], 0
	v_mfma_f32_16x16x32_bf16 v[114:117], v[106:109], v[228:231], 0
	v_mfma_f32_16x16x32_bf16 v[86:89], v[98:101], v[236:239], 0
	v_mfma_f32_16x16x32_bf16 v[82:85], v[106:109], v[236:239], 0
	v_mfma_f32_16x16x32_bf16 v[150:153], v[102:105], v[216:219], v[150:153]
	v_mfma_f32_16x16x32_bf16 v[146:149], v[110:113], v[216:219], v[146:149]
	v_mfma_f32_16x16x32_bf16 v[134:137], v[102:105], v[224:227], v[134:137]
	v_mfma_f32_16x16x32_bf16 v[130:133], v[110:113], v[224:227], v[130:133]
	v_mfma_f32_16x16x32_bf16 v[118:121], v[102:105], v[232:235], v[118:121]
	v_mfma_f32_16x16x32_bf16 v[114:117], v[110:113], v[232:235], v[114:117]
	v_mfma_f32_16x16x32_bf16 v[86:89], v[102:105], v[240:243], v[86:89]
	v_mfma_f32_16x16x32_bf16 v[82:85], v[110:113], v[240:243], v[82:85]
	s_setprio 0
	s_barrier
	s_add_i32 s21, s68, s29
	v_lshl_add_u64 v[182:183], s[48:49], 0, v[164:165]
	s_mov_b32 m0, s21
	ds_read_b128 v[212:215], v205 offset:16384
	ds_read_b128 v[216:219], v205 offset:17408
	ds_read_b128 v[220:223], v205 offset:18432
	ds_read_b128 v[224:227], v205 offset:19456
	ds_read_b128 v[228:231], v205 offset:20480
	ds_read_b128 v[232:235], v205 offset:21504
	ds_read_b128 v[236:239], v205 offset:22528
	ds_read_b128 v[240:243], v205 offset:23552
	global_load_lds_dwordx4 v[182:183], off
	s_add_i32 m0, s21, 0x2000
	s_add_u32 s22, s48, 0x20000
	v_lshl_add_u64 v[244:245], s[48:49], 0, v[168:169]
	s_addc_u32 s23, s49, 0
	s_add_i32 s21, s69, s29
	global_load_lds_dwordx4 v[244:245], off
	v_lshl_add_u64 v[246:247], s[22:23], 0, v[164:165]
	s_mov_b32 m0, s21
	v_lshl_add_u64 v[248:249], s[58:59], 0, v[166:167]
	global_load_lds_dwordx4 v[246:247], off
	v_lshl_add_u64 v[246:247], s[22:23], 0, v[168:169]
	s_add_i32 m0, s21, 0x2000
	s_nop 0
	global_load_lds_dwordx4 v[246:247], off
	v_lshl_add_u64 v[246:247], s[58:59], 0, v[162:163]
	s_mov_b32 m0, s30
	s_nop 0
	global_load_lds_dwordx4 v[246:247], off
	s_mov_b32 m0, s31
	s_nop 0
	global_load_lds_dwordx4 v[248:249], off
	s_waitcnt lgkmcnt(0)
	s_barrier
; #define PG8_STAGE(bufoff, gbase, voff) do { _Pragma("unroll") for (int _i = 0; _i < 2; ++_i) \
;         __builtin_amdgcn_global_load_lds((const unsigned*)((const char*)(gbase) + (voff)[_i]), (LAS unsigned*)(lds + (bufoff) + ldsw + _i * 8192), 16, 0, 0); } while (0)
; #define PG8_LDA(dst, b, h) do { _Pragma("unroll") for (int m = 0; m < 4; ++m) _Pragma("unroll") for (int k = 0; k < 2; ++k) dst[m][k] = *(const LAS bf16x8*)(lds + PG8_SA(b, h) + aoff + m * 2048 + k * 1024); } while (0)
; #define PG8_LDB(dst, b, h) do { _Pragma("unroll") for (int n = 0; n < 2; ++n) _Pragma("unroll") for (int k = 0; k < 2; ++k) dst[n][k] = *(const LAS bf16x8*)(lds + PG8_SB(b, h) + boff + n * 2048 + k * 1024); } while (0)
; #define PG8_MMA(ai, bj, At, Bt) do { __builtin_amdgcn_s_setprio(1); _Pragma("unroll") for (int m = 0; m < 4; ++m) _Pragma("unroll") for (int n = 0; n < 2; ++n) _Pragma("unroll") for (int k = 0; k < 2; ++k) \
;         acc[ai][bj][m][n] = __builtin_amdgcn_mfma_f32_16x16x32_bf16(Bt[n][k], At[m][k], acc[ai][bj][m][n], 0, 0, 0); __builtin_amdgcn_s_setprio(0); } while (0)
; #define PG8_WAIT_V(n) asm volatile("s_waitcnt vmcnt(" #n ")" ::: "memory")
; #define PG8_WAIT_L(n) asm volatile("s_waitcnt lgkmcnt(" #n ")" ::: "memory")
; #define PG8_BAR __builtin_amdgcn_s_barrier()
; #define PG8_SCHED __builtin_amdgcn_sched_barrier(0)
; template <class Epi, class Sched, bool ALIGN_EPI = false, bool SP2 = false>
; __device__ __forceinline__ void gemm_phase(LAS unsigned char* lds, const Gemm g, const Sched& S, const Epi& E) {
;     ...
;             PG8_WAIT_V(8); PG8_WAIT_L(0); PG8_BAR; PG8_MMA(1, 0, At, B0); PG8_MMA(1, 1, At, B1); PG8_BAR; PG8_SCHED;
;             PG8_LDB(B0, 1, 0); PG8_LDB(B1, 1, 1); PG8_SCHED; PG8_LDA(At, 1, 0); PG8_STAGE(PG8_SA(0, 1), a2 + hstep, voffA);
;             PG8_WAIT_V(8); PG8_WAIT_L(0); PG8_BAR; PG8_MMA(0, 0, At, B0); PG8_MMA(0, 1, At, B1); PG8_BAR; PG8_SCHED;
	s_setprio 1
	s_waitcnt lgkmcnt(0)
	v_mfma_f32_16x16x32_bf16 v[78:81], v[34:37], v[212:215], 0
	v_mfma_f32_16x16x32_bf16 v[74:77], v[42:45], v[212:215], 0
	v_mfma_f32_16x16x32_bf16 v[62:65], v[34:37], v[220:223], 0
	v_mfma_f32_16x16x32_bf16 v[58:61], v[42:45], v[220:223], 0
	v_mfma_f32_16x16x32_bf16 v[30:33], v[34:37], v[228:231], 0
	v_mfma_f32_16x16x32_bf16 v[26:29], v[42:45], v[228:231], 0
	v_mfma_f32_16x16x32_bf16 v[14:17], v[34:37], v[236:239], 0
	v_mfma_f32_16x16x32_bf16 v[10:13], v[42:45], v[236:239], 0
	v_mfma_f32_16x16x32_bf16 v[78:81], v[38:41], v[216:219], v[78:81]
	v_mfma_f32_16x16x32_bf16 v[74:77], v[46:49], v[216:219], v[74:77]
	v_mfma_f32_16x16x32_bf16 v[62:65], v[38:41], v[224:227], v[62:65]
	v_mfma_f32_16x16x32_bf16 v[58:61], v[46:49], v[224:227], v[58:61]
	v_mfma_f32_16x16x32_bf16 v[30:33], v[38:41], v[232:235], v[30:33]
	v_mfma_f32_16x16x32_bf16 v[26:29], v[46:49], v[232:235], v[26:29]
	v_mfma_f32_16x16x32_bf16 v[14:17], v[38:41], v[240:243], v[14:17]
	v_mfma_f32_16x16x32_bf16 v[10:13], v[46:49], v[240:243], v[10:13]
	v_mfma_f32_16x16x32_bf16 v[22:25], v[98:101], v[228:231], 0
	v_mfma_f32_16x16x32_bf16 v[18:21], v[106:109], v[228:231], 0
	v_mfma_f32_16x16x32_bf16 v[6:9], v[98:101], v[236:239], 0
	v_mfma_f32_16x16x32_bf16 v[2:5], v[106:109], v[236:239], 0
	v_mfma_f32_16x16x32_bf16 v[34:37], v[98:101], v[212:215], 0
	v_mfma_f32_16x16x32_bf16 v[38:41], v[106:109], v[212:215], 0
	v_mfma_f32_16x16x32_bf16 v[42:45], v[98:101], v[220:223], 0
	v_mfma_f32_16x16x32_bf16 v[46:49], v[106:109], v[220:223], 0
	v_mfma_f32_16x16x32_bf16 v[22:25], v[102:105], v[232:235], v[22:25]
	v_mfma_f32_16x16x32_bf16 v[18:21], v[110:113], v[232:235], v[18:21]
	v_mfma_f32_16x16x32_bf16 v[6:9], v[102:105], v[240:243], v[6:9]
	v_mfma_f32_16x16x32_bf16 v[2:5], v[110:113], v[240:243], v[2:5]
	v_mfma_f32_16x16x32_bf16 v[34:37], v[102:105], v[216:219], v[34:37]
	v_mfma_f32_16x16x32_bf16 v[38:41], v[110:113], v[216:219], v[38:41]
	v_mfma_f32_16x16x32_bf16 v[42:45], v[102:105], v[224:227], v[42:45]
	v_mfma_f32_16x16x32_bf16 v[46:49], v[110:113], v[224:227], v[46:49]
	s_setprio 0
	s_barrier
	s_add_i32 s21, 0, 0x18000
	s_add_i32 s24, 0, 0x1c000
	v_add_u32_e32 v70, s21, v186
	v_add_u32_e32 v110, s24, v186
	ds_read_b128 v[50:53], v70
	ds_read_b128 v[54:57], v70 offset:1024
	ds_read_b128 v[66:69], v70 offset:2048
	ds_read_b128 v[70:73], v70 offset:3072
	ds_read_b128 v[98:101], v110
	ds_read_b128 v[102:105], v110 offset:1024
	ds_read_b128 v[106:109], v110 offset:2048
	ds_read_b128 v[110:113], v110 offset:3072
	s_add_u32 s22, s58, 0x80000
	s_addc_u32 s23, s59, 0
	s_mov_b32 m0, s33
	v_lshl_add_u64 v[250:251], s[22:23], 0, v[162:163]
	ds_read_b128 v[212:215], v205 offset:32768
	ds_read_b128 v[216:219], v205 offset:33792
	ds_read_b128 v[220:223], v205 offset:34816
	ds_read_b128 v[224:227], v205 offset:35840
	ds_read_b128 v[228:231], v205 offset:36864
	ds_read_b128 v[232:235], v205 offset:37888
	ds_read_b128 v[236:239], v205 offset:38912
	ds_read_b128 v[240:243], v205 offset:39936
	global_load_lds_dwordx4 v[250:251], off
	v_lshl_add_u64 v[250:251], s[22:23], 0, v[166:167]
	s_mov_b32 m0, s60
	s_nop 0
	global_load_lds_dwordx4 v[250:251], off
	s_waitcnt vmcnt(8)
	s_waitcnt lgkmcnt(0)
	s_barrier
	s_setprio 1
	s_waitcnt lgkmcnt(0)
	v_mfma_f32_16x16x32_bf16 v[158:161], v[50:53], v[212:215], v[158:161]
	v_mfma_f32_16x16x32_bf16 v[154:157], v[66:69], v[212:215], v[154:157]
	v_mfma_f32_16x16x32_bf16 v[142:145], v[50:53], v[220:223], v[142:145]
	v_mfma_f32_16x16x32_bf16 v[138:141], v[66:69], v[220:223], v[138:141]
	v_mfma_f32_16x16x32_bf16 v[126:129], v[50:53], v[228:231], v[126:129]
	v_mfma_f32_16x16x32_bf16 v[122:125], v[66:69], v[228:231], v[122:125]
	v_mfma_f32_16x16x32_bf16 v[94:97], v[50:53], v[236:239], v[94:97]
	v_mfma_f32_16x16x32_bf16 v[90:93], v[66:69], v[236:239], v[90:93]
	v_mfma_f32_16x16x32_bf16 v[158:161], v[54:57], v[216:219], v[158:161]
	v_mfma_f32_16x16x32_bf16 v[154:157], v[70:73], v[216:219], v[154:157]
	v_mfma_f32_16x16x32_bf16 v[142:145], v[54:57], v[224:227], v[142:145]
	v_mfma_f32_16x16x32_bf16 v[138:141], v[70:73], v[224:227], v[138:141]
	v_mfma_f32_16x16x32_bf16 v[126:129], v[54:57], v[232:235], v[126:129]
	v_mfma_f32_16x16x32_bf16 v[122:125], v[70:73], v[232:235], v[122:125]
	v_mfma_f32_16x16x32_bf16 v[94:97], v[54:57], v[240:243], v[94:97]
	v_mfma_f32_16x16x32_bf16 v[90:93], v[70:73], v[240:243], v[90:93]
	v_mfma_f32_16x16x32_bf16 v[150:153], v[98:101], v[212:215], v[150:153]
	v_mfma_f32_16x16x32_bf16 v[146:149], v[106:109], v[212:215], v[146:149]
	v_mfma_f32_16x16x32_bf16 v[134:137], v[98:101], v[220:223], v[134:137]
	v_mfma_f32_16x16x32_bf16 v[130:133], v[106:109], v[220:223], v[130:133]
	v_mfma_f32_16x16x32_bf16 v[118:121], v[98:101], v[228:231], v[118:121]
	v_mfma_f32_16x16x32_bf16 v[114:117], v[106:109], v[228:231], v[114:117]
	v_mfma_f32_16x16x32_bf16 v[86:89], v[98:101], v[236:239], v[86:89]
	v_mfma_f32_16x16x32_bf16 v[82:85], v[106:109], v[236:239], v[82:85]
	v_mfma_f32_16x16x32_bf16 v[150:153], v[102:105], v[216:219], v[150:153]
	v_mfma_f32_16x16x32_bf16 v[146:149], v[110:113], v[216:219], v[146:149]
	v_mfma_f32_16x16x32_bf16 v[134:137], v[102:105], v[224:227], v[134:137]
	v_mfma_f32_16x16x32_bf16 v[130:133], v[110:113], v[224:227], v[130:133]
	v_mfma_f32_16x16x32_bf16 v[118:121], v[102:105], v[232:235], v[118:121]
	v_mfma_f32_16x16x32_bf16 v[114:117], v[110:113], v[232:235], v[114:117]
	v_mfma_f32_16x16x32_bf16 v[86:89], v[102:105], v[240:243], v[86:89]
	v_mfma_f32_16x16x32_bf16 v[82:85], v[110:113], v[240:243], v[82:85]
	s_setprio 0
	s_barrier
; #define PG8_STAGE(bufoff, gbase, voff) do { _Pragma("unroll") for (int _i = 0; _i < 2; ++_i) \
;         __builtin_amdgcn_global_load_lds((const unsigned*)((const char*)(gbase) + (voff)[_i]), (LAS unsigned*)(lds + (bufoff) + ldsw + _i * 8192), 16, 0, 0); } while (0)
; #define PG8_LDA(dst, b, h) do { _Pragma("unroll") for (int m = 0; m < 4; ++m) _Pragma("unroll") for (int k = 0; k < 2; ++k) dst[m][k] = *(const LAS bf16x8*)(lds + PG8_SA(b, h) + aoff + m * 2048 + k * 1024); } while (0)
; #define PG8_LDB(dst, b, h) do { _Pragma("unroll") for (int n = 0; n < 2; ++n) _Pragma("unroll") for (int k = 0; k < 2; ++k) dst[n][k] = *(const LAS bf16x8*)(lds + PG8_SB(b, h) + boff + n * 2048 + k * 1024); } while (0)
; #define PG8_MMA(ai, bj, At, Bt) do { __builtin_amdgcn_s_setprio(1); _Pragma("unroll") for (int m = 0; m < 4; ++m) _Pragma("unroll") for (int n = 0; n < 2; ++n) _Pragma("unroll") for (int k = 0; k < 2; ++k) \
;         acc[ai][bj][m][n] = __builtin_amdgcn_mfma_f32_16x16x32_bf16(Bt[n][k], At[m][k], acc[ai][bj][m][n], 0, 0, 0); __builtin_amdgcn_s_setprio(0); } while (0)
; #define PG8_WAIT_V(n) asm volatile("s_waitcnt vmcnt(" #n ")" ::: "memory")
; #define PG8_WAIT_L(n) asm volatile("s_waitcnt lgkmcnt(" #n ")" ::: "memory")
; #define PG8_BAR __builtin_amdgcn_s_barrier()
; #define PG8_SCHED __builtin_amdgcn_sched_barrier(0)
; template <class Epi, class Sched, bool ALIGN_EPI = false, bool SP2 = false>
; __device__ __forceinline__ void gemm_phase(LAS unsigned char* lds, const Gemm g, const Sched& S, const Epi& E) {
;     ...
;         for (int t = 0; t < nt; t += 2) {
;             const bool last = (t == nt - 2);
;             const char* a1 = cA + (size_t)(t + 1) * kstep;
;             const char* a2 = last ? nA : cA + (size_t)(t + 2) * kstep; const char* b2 = last ? nB : cB + (size_t)(t + 2) * kstep;
;             const char* a3 = a2 + kstep; const char* b3 = b2 + kstep;
;             if (last && has_next) S.a_ready(nxt);
;             if constexpr (SP2) {
;             PG8_LDB(B0, 0, 0); PG8_LDB(B1, 0, 1); PG8_SCHED; PG8_LDA(At, 0, 0); PG8_STAGE(PG8_SA(1, 1), a1 + hstep, voffA);
;     ...
;             PG8_LDA(At, 1, 1); PG8_STAGE(PG8_SB(1, 0), b3, voffB); PG8_STAGE(PG8_SB(1, 1), b3 + hstepB, voffB); PG8_STAGE(PG8_SA(1, 0), a3, voffA);
;             PG8_WAIT_V(8); PG8_WAIT_L(0); PG8_BAR; PG8_MMA(1, 0, At, B0); PG8_MMA(1, 1, At, B1); PG8_BAR; PG8_SCHED;
	s_add_i32 s21, s21, s29
	v_lshl_add_u64 v[182:183], v[182:183], 0, s[34:35]
	s_mov_b32 m0, s21
	ds_read_b128 v[212:215], v205 offset:49152
	ds_read_b128 v[216:219], v205 offset:50176
	ds_read_b128 v[220:223], v205 offset:51200
	ds_read_b128 v[224:227], v205 offset:52224
	ds_read_b128 v[228:231], v205 offset:53248
	ds_read_b128 v[232:235], v205 offset:54272
	ds_read_b128 v[236:239], v205 offset:55296
	ds_read_b128 v[240:243], v205 offset:56320
	global_load_lds_dwordx4 v[182:183], off
	s_add_i32 m0, s21, 0x2000
	s_add_u32 s22, s48, 0x20080
	v_lshl_add_u64 v[182:183], v[244:245], 0, s[34:35]
	s_addc_u32 s23, s49, 0
	s_add_i32 s21, s24, s29
	global_load_lds_dwordx4 v[182:183], off
	v_lshl_add_u64 v[182:183], s[22:23], 0, v[164:165]
	s_mov_b32 m0, s21
	s_nop 0
	global_load_lds_dwordx4 v[182:183], off
	v_lshl_add_u64 v[182:183], s[22:23], 0, v[168:169]
	s_add_i32 m0, s21, 0x2000
	s_nop 0
	global_load_lds_dwordx4 v[182:183], off
	v_lshl_add_u64 v[182:183], v[246:247], 0, s[34:35]
	s_mov_b32 m0, s65
	s_nop 0
	global_load_lds_dwordx4 v[182:183], off
	v_lshl_add_u64 v[182:183], v[248:249], 0, s[34:35]
	s_mov_b32 m0, s66
	s_nop 0
	global_load_lds_dwordx4 v[182:183], off
	s_waitcnt vmcnt(8)
	s_waitcnt lgkmcnt(0)
	s_barrier
	s_setprio 1
	s_waitcnt lgkmcnt(0)
	v_mfma_f32_16x16x32_bf16 v[78:81], v[50:53], v[212:215], v[78:81]
	v_mfma_f32_16x16x32_bf16 v[74:77], v[66:69], v[212:215], v[74:77]
	v_mfma_f32_16x16x32_bf16 v[62:65], v[50:53], v[220:223], v[62:65]
	v_mfma_f32_16x16x32_bf16 v[58:61], v[66:69], v[220:223], v[58:61]
	v_mfma_f32_16x16x32_bf16 v[30:33], v[50:53], v[228:231], v[30:33]
	v_mfma_f32_16x16x32_bf16 v[26:29], v[66:69], v[228:231], v[26:29]
	v_mfma_f32_16x16x32_bf16 v[14:17], v[50:53], v[236:239], v[14:17]
	v_mfma_f32_16x16x32_bf16 v[10:13], v[66:69], v[236:239], v[10:13]
	v_mfma_f32_16x16x32_bf16 v[78:81], v[54:57], v[216:219], v[78:81]
	v_mfma_f32_16x16x32_bf16 v[74:77], v[70:73], v[216:219], v[74:77]
	v_mfma_f32_16x16x32_bf16 v[62:65], v[54:57], v[224:227], v[62:65]
	v_mfma_f32_16x16x32_bf16 v[58:61], v[70:73], v[224:227], v[58:61]
	v_mfma_f32_16x16x32_bf16 v[30:33], v[54:57], v[232:235], v[30:33]
	v_mfma_f32_16x16x32_bf16 v[26:29], v[70:73], v[232:235], v[26:29]
	v_mfma_f32_16x16x32_bf16 v[14:17], v[54:57], v[240:243], v[14:17]
	v_mfma_f32_16x16x32_bf16 v[10:13], v[70:73], v[240:243], v[10:13]
	v_mfma_f32_16x16x32_bf16 v[34:37], v[98:101], v[212:215], v[34:37]
	v_mfma_f32_16x16x32_bf16 v[70:73], v[102:105], v[216:219], v[34:37]
	v_mfma_f32_16x16x32_bf16 v[34:37], v[106:109], v[212:215], v[38:41]
	v_mfma_f32_16x16x32_bf16 v[66:69], v[110:113], v[216:219], v[34:37]
	v_mfma_f32_16x16x32_bf16 v[34:37], v[98:101], v[220:223], v[42:45]
	v_mfma_f32_16x16x32_bf16 v[54:57], v[102:105], v[224:227], v[34:37]
	v_mfma_f32_16x16x32_bf16 v[34:37], v[106:109], v[220:223], v[46:49]
	v_mfma_f32_16x16x32_bf16 v[22:25], v[98:101], v[228:231], v[22:25]
	v_mfma_f32_16x16x32_bf16 v[18:21], v[106:109], v[228:231], v[18:21]
	v_mfma_f32_16x16x32_bf16 v[6:9], v[98:101], v[236:239], v[6:9]
	v_mfma_f32_16x16x32_bf16 v[2:5], v[106:109], v[236:239], v[2:5]
	v_mfma_f32_16x16x32_bf16 v[50:53], v[110:113], v[224:227], v[34:37]
	v_mfma_f32_16x16x32_bf16 v[22:25], v[102:105], v[232:235], v[22:25]
	v_mfma_f32_16x16x32_bf16 v[18:21], v[110:113], v[232:235], v[18:21]
	v_mfma_f32_16x16x32_bf16 v[6:9], v[102:105], v[240:243], v[6:9]
	v_mfma_f32_16x16x32_bf16 v[2:5], v[110:113], v[240:243], v[2:5]
	s_setprio 0
	s_barrier
	s_add_i32 s20, s20, 2
	s_add_u32 s16, s16, 0x100
	s_addc_u32 s17, s17, 0
	s_add_u32 s18, s18, 0x100
	s_addc_u32 s19, s19, 0
	s_cmp_gt_u32 s20, 29
.LBB0_535:
	ds_read_b128 v[34:37], v203
	ds_read_b128 v[38:41], v203 offset:1024
	ds_read_b128 v[42:45], v203 offset:2048
	ds_read_b128 v[46:49], v203 offset:3072
	s_waitcnt vmcnt(0)
	ds_read_b128 v[98:101], v204
	ds_read_b128 v[102:105], v204 offset:1024
	ds_read_b128 v[106:109], v204 offset:2048
	ds_read_b128 v[110:113], v204 offset:3072
	s_add_u32 s21, s16, 0xfff80080
	s_addc_u32 s22, s17, -1
	s_cmp_eq_u32 s20, 28
	s_cselect_b32 s59, s0, s22
	s_cselect_b32 s58, s3, s21
	s_cselect_b32 s49, s14, s19
	s_cselect_b32 s48, s15, s18
	v_lshl_add_u64 v[182:183], s[16:17], 0, v[172:173]
	s_add_i32 m0, s30, 0xc000
	ds_read_b128 v[212:215], v205
	ds_read_b128 v[216:219], v205 offset:1024
	ds_read_b128 v[220:223], v205 offset:2048
	ds_read_b128 v[224:227], v205 offset:3072
	ds_read_b128 v[228:231], v205 offset:4096
	ds_read_b128 v[232:235], v205 offset:5120
	ds_read_b128 v[236:239], v205 offset:6144
	ds_read_b128 v[240:243], v205 offset:7168
	global_load_lds_dwordx4 v[182:183], off
	v_lshl_add_u64 v[182:183], s[16:17], 0, v[174:175]
	s_add_i32 m0, s30, 0xe000
	s_nop 0
	global_load_lds_dwordx4 v[182:183], off
	s_waitcnt vmcnt(8)
	s_waitcnt lgkmcnt(0)
	s_barrier
; #define PG8_STAGE(bufoff, gbase, voff) do { _Pragma("unroll") for (int _i = 0; _i < 2; ++_i) \
;         __builtin_amdgcn_global_load_lds((const unsigned*)((const char*)(gbase) + (voff)[_i]), (LAS unsigned*)(lds + (bufoff) + ldsw + _i * 8192), 16, 0, 0); } while (0)
; #define PG8_LDA(dst, b, h) do { _Pragma("unroll") for (int m = 0; m < 4; ++m) _Pragma("unroll") for (int k = 0; k < 2; ++k) dst[m][k] = *(const LAS bf16x8*)(lds + PG8_SA(b, h) + aoff + m * 2048 + k * 1024); } while (0)
; #define PG8_MMA(ai, bj, At, Bt) do { __builtin_amdgcn_s_setprio(1); _Pragma("unroll") for (int m = 0; m < 4; ++m) _Pragma("unroll") for (int n = 0; n < 2; ++n) _Pragma("unroll") for (int k = 0; k < 2; ++k) \
;         acc[ai][bj][m][n] = __builtin_amdgcn_mfma_f32_16x16x32_bf16(Bt[n][k], At[m][k], acc[ai][bj][m][n], 0, 0, 0); __builtin_amdgcn_s_setprio(0); } while (0)
; #define PG8_WAIT_V(n) asm volatile("s_waitcnt vmcnt(" #n ")" ::: "memory")
; #define PG8_WAIT_L(n) asm volatile("s_waitcnt lgkmcnt(" #n ")" ::: "memory")
; #define PG8_BAR __builtin_amdgcn_s_barrier()
; #define PG8_SCHED __builtin_amdgcn_sched_barrier(0)
; template <class Epi, class Sched, bool ALIGN_EPI = false, bool SP2 = false>
; __device__ __forceinline__ void gemm_phase(LAS unsigned char* lds, const Gemm g, const Sched& S, const Epi& E) {
;     ...
;             PG8_WAIT_V(8); PG8_WAIT_L(0); PG8_BAR; PG8_MMA(0, 0, At, B0); PG8_MMA(0, 1, At, B1); PG8_BAR; PG8_SCHED;
;             PG8_LDA(At, 0, 1); PG8_STAGE(PG8_SB(0, 0), b2, voffB); PG8_STAGE(PG8_SB(0, 1), b2 + hstepB, voffB); PG8_STAGE(PG8_SA(0, 0), a2, voffA);
;             PG8_WAIT_V(8); PG8_WAIT_L(0); PG8_BAR; PG8_MMA(1, 0, At, B0); PG8_MMA(1, 1, At, B1); PG8_BAR; PG8_SCHED;
	s_setprio 1
	s_waitcnt lgkmcnt(0)
	v_mfma_f32_16x16x32_bf16 v[158:161], v[34:37], v[212:215], v[158:161]
	v_mfma_f32_16x16x32_bf16 v[154:157], v[42:45], v[212:215], v[154:157]
	v_mfma_f32_16x16x32_bf16 v[142:145], v[34:37], v[220:223], v[142:145]
	v_mfma_f32_16x16x32_bf16 v[138:141], v[42:45], v[220:223], v[138:141]
	v_mfma_f32_16x16x32_bf16 v[126:129], v[34:37], v[228:231], v[126:129]
	v_mfma_f32_16x16x32_bf16 v[122:125], v[42:45], v[228:231], v[122:125]
	v_mfma_f32_16x16x32_bf16 v[94:97], v[34:37], v[236:239], v[94:97]
	v_mfma_f32_16x16x32_bf16 v[90:93], v[42:45], v[236:239], v[90:93]
	v_mfma_f32_16x16x32_bf16 v[158:161], v[38:41], v[216:219], v[158:161]
	v_mfma_f32_16x16x32_bf16 v[154:157], v[46:49], v[216:219], v[154:157]
	v_mfma_f32_16x16x32_bf16 v[142:145], v[38:41], v[224:227], v[142:145]
	v_mfma_f32_16x16x32_bf16 v[138:141], v[46:49], v[224:227], v[138:141]
	v_mfma_f32_16x16x32_bf16 v[126:129], v[38:41], v[232:235], v[126:129]
	v_mfma_f32_16x16x32_bf16 v[122:125], v[46:49], v[232:235], v[122:125]
	v_mfma_f32_16x16x32_bf16 v[94:97], v[38:41], v[240:243], v[94:97]
	v_mfma_f32_16x16x32_bf16 v[90:93], v[46:49], v[240:243], v[90:93]
	v_mfma_f32_16x16x32_bf16 v[150:153], v[98:101], v[212:215], v[150:153]
	v_mfma_f32_16x16x32_bf16 v[146:149], v[106:109], v[212:215], v[146:149]
	v_mfma_f32_16x16x32_bf16 v[134:137], v[98:101], v[220:223], v[134:137]
	v_mfma_f32_16x16x32_bf16 v[130:133], v[106:109], v[220:223], v[130:133]
	v_mfma_f32_16x16x32_bf16 v[118:121], v[98:101], v[228:231], v[118:121]
	v_mfma_f32_16x16x32_bf16 v[114:117], v[106:109], v[228:231], v[114:117]
	v_mfma_f32_16x16x32_bf16 v[86:89], v[98:101], v[236:239], v[86:89]
	v_mfma_f32_16x16x32_bf16 v[82:85], v[106:109], v[236:239], v[82:85]
	v_mfma_f32_16x16x32_bf16 v[150:153], v[102:105], v[216:219], v[150:153]
	v_mfma_f32_16x16x32_bf16 v[146:149], v[110:113], v[216:219], v[146:149]
	v_mfma_f32_16x16x32_bf16 v[134:137], v[102:105], v[224:227], v[134:137]
	v_mfma_f32_16x16x32_bf16 v[130:133], v[110:113], v[224:227], v[130:133]
	v_mfma_f32_16x16x32_bf16 v[118:121], v[102:105], v[232:235], v[118:121]
	v_mfma_f32_16x16x32_bf16 v[114:117], v[110:113], v[232:235], v[114:117]
	v_mfma_f32_16x16x32_bf16 v[86:89], v[102:105], v[240:243], v[86:89]
	v_mfma_f32_16x16x32_bf16 v[82:85], v[110:113], v[240:243], v[82:85]
	s_setprio 0
	s_barrier
	s_add_i32 s21, s68, s29
	v_lshl_add_u64 v[182:183], s[48:49], 0, v[164:165]
	s_mov_b32 m0, s21
	ds_read_b128 v[212:215], v205 offset:16384
	ds_read_b128 v[216:219], v205 offset:17408
	ds_read_b128 v[220:223], v205 offset:18432
	ds_read_b128 v[224:227], v205 offset:19456
	ds_read_b128 v[228:231], v205 offset:20480
	ds_read_b128 v[232:235], v205 offset:21504
	ds_read_b128 v[236:239], v205 offset:22528
	ds_read_b128 v[240:243], v205 offset:23552
	global_load_lds_dwordx4 v[182:183], off
	s_add_i32 m0, s21, 0x2000
	s_add_u32 s22, s48, 0x20000
	v_lshl_add_u64 v[244:245], s[48:49], 0, v[168:169]
	s_addc_u32 s23, s49, 0
	s_add_i32 s21, s69, s29
	global_load_lds_dwordx4 v[244:245], off
	v_lshl_add_u64 v[246:247], s[22:23], 0, v[164:165]
	s_mov_b32 m0, s21
	v_lshl_add_u64 v[248:249], s[58:59], 0, v[166:167]
	global_load_lds_dwordx4 v[246:247], off
	v_lshl_add_u64 v[246:247], s[22:23], 0, v[168:169]
	s_add_i32 m0, s21, 0x2000
	s_nop 0
	global_load_lds_dwordx4 v[246:247], off
	v_lshl_add_u64 v[246:247], s[58:59], 0, v[162:163]
	s_mov_b32 m0, s30
	s_nop 0
	global_load_lds_dwordx4 v[246:247], off
	s_mov_b32 m0, s31
	s_nop 0
	global_load_lds_dwordx4 v[248:249], off
	s_waitcnt vmcnt(8)
	s_waitcnt lgkmcnt(0)
	s_barrier
	s_setprio 1
	s_waitcnt lgkmcnt(0)
	v_mfma_f32_16x16x32_bf16 v[78:81], v[34:37], v[212:215], v[78:81]
	v_mfma_f32_16x16x32_bf16 v[74:77], v[42:45], v[212:215], v[74:77]
	v_mfma_f32_16x16x32_bf16 v[62:65], v[34:37], v[220:223], v[62:65]
	v_mfma_f32_16x16x32_bf16 v[58:61], v[42:45], v[220:223], v[58:61]
	v_mfma_f32_16x16x32_bf16 v[30:33], v[34:37], v[228:231], v[30:33]
	v_mfma_f32_16x16x32_bf16 v[26:29], v[42:45], v[228:231], v[26:29]
	v_mfma_f32_16x16x32_bf16 v[14:17], v[34:37], v[236:239], v[14:17]
	v_mfma_f32_16x16x32_bf16 v[10:13], v[42:45], v[236:239], v[10:13]
	v_mfma_f32_16x16x32_bf16 v[78:81], v[38:41], v[216:219], v[78:81]
	v_mfma_f32_16x16x32_bf16 v[74:77], v[46:49], v[216:219], v[74:77]
	v_mfma_f32_16x16x32_bf16 v[62:65], v[38:41], v[224:227], v[62:65]
	v_mfma_f32_16x16x32_bf16 v[58:61], v[46:49], v[224:227], v[58:61]
	v_mfma_f32_16x16x32_bf16 v[30:33], v[38:41], v[232:235], v[30:33]
	v_mfma_f32_16x16x32_bf16 v[26:29], v[46:49], v[232:235], v[26:29]
	v_mfma_f32_16x16x32_bf16 v[14:17], v[38:41], v[240:243], v[14:17]
	v_mfma_f32_16x16x32_bf16 v[10:13], v[46:49], v[240:243], v[10:13]
	v_mfma_f32_16x16x32_bf16 v[22:25], v[98:101], v[228:231], v[22:25]
	v_mfma_f32_16x16x32_bf16 v[18:21], v[106:109], v[228:231], v[18:21]
	v_mfma_f32_16x16x32_bf16 v[6:9], v[98:101], v[236:239], v[6:9]
	v_mfma_f32_16x16x32_bf16 v[2:5], v[106:109], v[236:239], v[2:5]
	v_mfma_f32_16x16x32_bf16 v[34:37], v[98:101], v[212:215], v[70:73]
	v_mfma_f32_16x16x32_bf16 v[38:41], v[106:109], v[212:215], v[66:69]
	v_mfma_f32_16x16x32_bf16 v[42:45], v[98:101], v[220:223], v[54:57]
	v_mfma_f32_16x16x32_bf16 v[46:49], v[106:109], v[220:223], v[50:53]
	v_mfma_f32_16x16x32_bf16 v[22:25], v[102:105], v[232:235], v[22:25]
	v_mfma_f32_16x16x32_bf16 v[18:21], v[110:113], v[232:235], v[18:21]
	v_mfma_f32_16x16x32_bf16 v[6:9], v[102:105], v[240:243], v[6:9]
	v_mfma_f32_16x16x32_bf16 v[2:5], v[110:113], v[240:243], v[2:5]
	v_mfma_f32_16x16x32_bf16 v[34:37], v[102:105], v[216:219], v[34:37]
	v_mfma_f32_16x16x32_bf16 v[38:41], v[110:113], v[216:219], v[38:41]
	v_mfma_f32_16x16x32_bf16 v[42:45], v[102:105], v[224:227], v[42:45]
	v_mfma_f32_16x16x32_bf16 v[46:49], v[110:113], v[224:227], v[46:49]
	s_setprio 0
	s_barrier
; #define PG8_STAGE(bufoff, gbase, voff) do { _Pragma("unroll") for (int _i = 0; _i < 2; ++_i) \
;         __builtin_amdgcn_global_load_lds((const unsigned*)((const char*)(gbase) + (voff)[_i]), (LAS unsigned*)(lds + (bufoff) + ldsw + _i * 8192), 16, 0, 0); } while (0)
; #define PG8_LDA(dst, b, h) do { _Pragma("unroll") for (int m = 0; m < 4; ++m) _Pragma("unroll") for (int k = 0; k < 2; ++k) dst[m][k] = *(const LAS bf16x8*)(lds + PG8_SA(b, h) + aoff + m * 2048 + k * 1024); } while (0)
; #define PG8_LDB(dst, b, h) do { _Pragma("unroll") for (int n = 0; n < 2; ++n) _Pragma("unroll") for (int k = 0; k < 2; ++k) dst[n][k] = *(const LAS bf16x8*)(lds + PG8_SB(b, h) + boff + n * 2048 + k * 1024); } while (0)
; #define PG8_MMA(ai, bj, At, Bt) do { __builtin_amdgcn_s_setprio(1); _Pragma("unroll") for (int m = 0; m < 4; ++m) _Pragma("unroll") for (int n = 0; n < 2; ++n) _Pragma("unroll") for (int k = 0; k < 2; ++k) \
;         acc[ai][bj][m][n] = __builtin_amdgcn_mfma_f32_16x16x32_bf16(Bt[n][k], At[m][k], acc[ai][bj][m][n], 0, 0, 0); __builtin_amdgcn_s_setprio(0); } while (0)
; #define PG8_WAIT_V(n) asm volatile("s_waitcnt vmcnt(" #n ")" ::: "memory")
; #define PG8_WAIT_L(n) asm volatile("s_waitcnt lgkmcnt(" #n ")" ::: "memory")
; #define PG8_BAR __builtin_amdgcn_s_barrier()
; #define PG8_SCHED __builtin_amdgcn_sched_barrier(0)
; template <class Epi, class Sched, bool ALIGN_EPI = false, bool SP2 = false>
; __device__ __forceinline__ void gemm_phase(LAS unsigned char* lds, const Gemm g, const Sched& S, const Epi& E) {
;     ...
;             PG8_LDB(B0, 1, 0); PG8_LDB(B1, 1, 1); PG8_SCHED; PG8_LDA(At, 1, 0); PG8_STAGE(PG8_SA(0, 1), a2 + hstep, voffA);
;             PG8_WAIT_V(8); PG8_WAIT_L(0); PG8_BAR; PG8_MMA(0, 0, At, B0); PG8_MMA(0, 1, At, B1); PG8_BAR; PG8_SCHED;
	s_add_i32 s21, 0, 0x18000
	s_add_i32 s24, 0, 0x1c000
	v_add_u32_e32 v70, s21, v186
	v_add_u32_e32 v110, s24, v186
	ds_read_b128 v[50:53], v70
	ds_read_b128 v[54:57], v70 offset:1024
	ds_read_b128 v[66:69], v70 offset:2048
	ds_read_b128 v[70:73], v70 offset:3072
	ds_read_b128 v[98:101], v110
	ds_read_b128 v[102:105], v110 offset:1024
	ds_read_b128 v[106:109], v110 offset:2048
	ds_read_b128 v[110:113], v110 offset:3072
	s_add_u32 s22, s58, 0x80000
	s_addc_u32 s23, s59, 0
	s_mov_b32 m0, s33
	v_lshl_add_u64 v[250:251], s[22:23], 0, v[162:163]
	ds_read_b128 v[212:215], v205 offset:32768
	ds_read_b128 v[216:219], v205 offset:33792
	ds_read_b128 v[220:223], v205 offset:34816
	ds_read_b128 v[224:227], v205 offset:35840
	ds_read_b128 v[228:231], v205 offset:36864
	ds_read_b128 v[232:235], v205 offset:37888
	ds_read_b128 v[236:239], v205 offset:38912
	ds_read_b128 v[240:243], v205 offset:39936
	global_load_lds_dwordx4 v[250:251], off
	v_lshl_add_u64 v[250:251], s[22:23], 0, v[166:167]
	s_mov_b32 m0, s60
	s_nop 0
	global_load_lds_dwordx4 v[250:251], off
	s_waitcnt vmcnt(8)
	s_waitcnt lgkmcnt(0)
	s_barrier
	s_setprio 1
	s_waitcnt lgkmcnt(0)
	v_mfma_f32_16x16x32_bf16 v[158:161], v[50:53], v[212:215], v[158:161]
	v_mfma_f32_16x16x32_bf16 v[154:157], v[66:69], v[212:215], v[154:157]
	v_mfma_f32_16x16x32_bf16 v[142:145], v[50:53], v[220:223], v[142:145]
	v_mfma_f32_16x16x32_bf16 v[138:141], v[66:69], v[220:223], v[138:141]
	v_mfma_f32_16x16x32_bf16 v[126:129], v[50:53], v[228:231], v[126:129]
	v_mfma_f32_16x16x32_bf16 v[122:125], v[66:69], v[228:231], v[122:125]
	v_mfma_f32_16x16x32_bf16 v[94:97], v[50:53], v[236:239], v[94:97]
	v_mfma_f32_16x16x32_bf16 v[90:93], v[66:69], v[236:239], v[90:93]
	v_mfma_f32_16x16x32_bf16 v[158:161], v[54:57], v[216:219], v[158:161]
	v_mfma_f32_16x16x32_bf16 v[154:157], v[70:73], v[216:219], v[154:157]
	v_mfma_f32_16x16x32_bf16 v[142:145], v[54:57], v[224:227], v[142:145]
	v_mfma_f32_16x16x32_bf16 v[138:141], v[70:73], v[224:227], v[138:141]
	v_mfma_f32_16x16x32_bf16 v[126:129], v[54:57], v[232:235], v[126:129]
	v_mfma_f32_16x16x32_bf16 v[122:125], v[70:73], v[232:235], v[122:125]
	v_mfma_f32_16x16x32_bf16 v[94:97], v[54:57], v[240:243], v[94:97]
	v_mfma_f32_16x16x32_bf16 v[90:93], v[70:73], v[240:243], v[90:93]
	v_mfma_f32_16x16x32_bf16 v[150:153], v[98:101], v[212:215], v[150:153]
	v_mfma_f32_16x16x32_bf16 v[146:149], v[106:109], v[212:215], v[146:149]
	v_mfma_f32_16x16x32_bf16 v[134:137], v[98:101], v[220:223], v[134:137]
	v_mfma_f32_16x16x32_bf16 v[130:133], v[106:109], v[220:223], v[130:133]
	v_mfma_f32_16x16x32_bf16 v[118:121], v[98:101], v[228:231], v[118:121]
	v_mfma_f32_16x16x32_bf16 v[114:117], v[106:109], v[228:231], v[114:117]
	v_mfma_f32_16x16x32_bf16 v[86:89], v[98:101], v[236:239], v[86:89]
	v_mfma_f32_16x16x32_bf16 v[82:85], v[106:109], v[236:239], v[82:85]
	v_mfma_f32_16x16x32_bf16 v[150:153], v[102:105], v[216:219], v[150:153]
	v_mfma_f32_16x16x32_bf16 v[146:149], v[110:113], v[216:219], v[146:149]
	v_mfma_f32_16x16x32_bf16 v[134:137], v[102:105], v[224:227], v[134:137]
	v_mfma_f32_16x16x32_bf16 v[130:133], v[110:113], v[224:227], v[130:133]
	v_mfma_f32_16x16x32_bf16 v[118:121], v[102:105], v[232:235], v[118:121]
	v_mfma_f32_16x16x32_bf16 v[114:117], v[110:113], v[232:235], v[114:117]
	v_mfma_f32_16x16x32_bf16 v[86:89], v[102:105], v[240:243], v[86:89]
	v_mfma_f32_16x16x32_bf16 v[82:85], v[110:113], v[240:243], v[82:85]
	s_setprio 0
	s_barrier
; #define PG8_STAGE(bufoff, gbase, voff) do { _Pragma("unroll") for (int _i = 0; _i < 2; ++_i) \
;         __builtin_amdgcn_global_load_lds((const unsigned*)((const char*)(gbase) + (voff)[_i]), (LAS unsigned*)(lds + (bufoff) + ldsw + _i * 8192), 16, 0, 0); } while (0)
; #define PG8_LDA(dst, b, h) do { _Pragma("unroll") for (int m = 0; m < 4; ++m) _Pragma("unroll") for (int k = 0; k < 2; ++k) dst[m][k] = *(const LAS bf16x8*)(lds + PG8_SA(b, h) + aoff + m * 2048 + k * 1024); } while (0)
; #define PG8_MMA(ai, bj, At, Bt) do { __builtin_amdgcn_s_setprio(1); _Pragma("unroll") for (int m = 0; m < 4; ++m) _Pragma("unroll") for (int n = 0; n < 2; ++n) _Pragma("unroll") for (int k = 0; k < 2; ++k) \
;         acc[ai][bj][m][n] = __builtin_amdgcn_mfma_f32_16x16x32_bf16(Bt[n][k], At[m][k], acc[ai][bj][m][n], 0, 0, 0); __builtin_amdgcn_s_setprio(0); } while (0)
; #define PG8_WAIT_V(n) asm volatile("s_waitcnt vmcnt(" #n ")" ::: "memory")
; #define PG8_WAIT_L(n) asm volatile("s_waitcnt lgkmcnt(" #n ")" ::: "memory")
; #define PG8_BAR __builtin_amdgcn_s_barrier()
; #define PG8_SCHED __builtin_amdgcn_sched_barrier(0)
; template <class Epi, class Sched, bool ALIGN_EPI = false, bool SP2 = false>
; __device__ __forceinline__ void gemm_phase(LAS unsigned char* lds, const Gemm g, const Sched& S, const Epi& E) {
;     ...
;             PG8_LDA(At, 1, 1); PG8_STAGE(PG8_SB(1, 0), b3, voffB); PG8_STAGE(PG8_SB(1, 1), b3 + hstepB, voffB); PG8_STAGE(PG8_SA(1, 0), a3, voffA);
;             PG8_WAIT_V(8); PG8_WAIT_L(0); PG8_BAR; PG8_MMA(1, 0, At, B0); PG8_MMA(1, 1, At, B1); PG8_BAR; PG8_SCHED;
	s_add_i32 s21, s21, s29
	v_lshl_add_u64 v[182:183], v[182:183], 0, s[34:35]
	s_mov_b32 m0, s21
	ds_read_b128 v[212:215], v205 offset:49152
	ds_read_b128 v[216:219], v205 offset:50176
	ds_read_b128 v[220:223], v205 offset:51200
	ds_read_b128 v[224:227], v205 offset:52224
	ds_read_b128 v[228:231], v205 offset:53248
	ds_read_b128 v[232:235], v205 offset:54272
	ds_read_b128 v[236:239], v205 offset:55296
	ds_read_b128 v[240:243], v205 offset:56320
	global_load_lds_dwordx4 v[182:183], off
	s_add_i32 m0, s21, 0x2000
	s_add_u32 s22, s48, 0x20080
	v_lshl_add_u64 v[182:183], v[244:245], 0, s[34:35]
	s_addc_u32 s23, s49, 0
	s_add_i32 s21, s24, s29
	global_load_lds_dwordx4 v[182:183], off
	v_lshl_add_u64 v[182:183], s[22:23], 0, v[164:165]
	s_mov_b32 m0, s21
	s_nop 0
	global_load_lds_dwordx4 v[182:183], off
	v_lshl_add_u64 v[182:183], s[22:23], 0, v[168:169]
	s_add_i32 m0, s21, 0x2000
	s_nop 0
	global_load_lds_dwordx4 v[182:183], off
	v_lshl_add_u64 v[182:183], v[246:247], 0, s[34:35]
	s_mov_b32 m0, s65
	s_nop 0
	global_load_lds_dwordx4 v[182:183], off
	v_lshl_add_u64 v[182:183], v[248:249], 0, s[34:35]
	s_mov_b32 m0, s66
	s_nop 0
	global_load_lds_dwordx4 v[182:183], off
	s_waitcnt vmcnt(8)
	s_waitcnt lgkmcnt(0)
	s_barrier
	s_setprio 1
	s_waitcnt lgkmcnt(0)
	v_mfma_f32_16x16x32_bf16 v[78:81], v[50:53], v[212:215], v[78:81]
	v_mfma_f32_16x16x32_bf16 v[74:77], v[66:69], v[212:215], v[74:77]
	v_mfma_f32_16x16x32_bf16 v[62:65], v[50:53], v[220:223], v[62:65]
	v_mfma_f32_16x16x32_bf16 v[58:61], v[66:69], v[220:223], v[58:61]
	v_mfma_f32_16x16x32_bf16 v[30:33], v[50:53], v[228:231], v[30:33]
	v_mfma_f32_16x16x32_bf16 v[26:29], v[66:69], v[228:231], v[26:29]
	v_mfma_f32_16x16x32_bf16 v[14:17], v[50:53], v[236:239], v[14:17]
	v_mfma_f32_16x16x32_bf16 v[10:13], v[66:69], v[236:239], v[10:13]
	v_mfma_f32_16x16x32_bf16 v[78:81], v[54:57], v[216:219], v[78:81]
	v_mfma_f32_16x16x32_bf16 v[74:77], v[70:73], v[216:219], v[74:77]
	v_mfma_f32_16x16x32_bf16 v[62:65], v[54:57], v[224:227], v[62:65]
	v_mfma_f32_16x16x32_bf16 v[58:61], v[70:73], v[224:227], v[58:61]
	v_mfma_f32_16x16x32_bf16 v[30:33], v[54:57], v[232:235], v[30:33]
	v_mfma_f32_16x16x32_bf16 v[26:29], v[70:73], v[232:235], v[26:29]
	v_mfma_f32_16x16x32_bf16 v[14:17], v[54:57], v[240:243], v[14:17]
	v_mfma_f32_16x16x32_bf16 v[10:13], v[70:73], v[240:243], v[10:13]
	v_mfma_f32_16x16x32_bf16 v[34:37], v[98:101], v[212:215], v[34:37]
	v_mfma_f32_16x16x32_bf16 v[70:73], v[102:105], v[216:219], v[34:37]
	v_mfma_f32_16x16x32_bf16 v[34:37], v[106:109], v[212:215], v[38:41]
	v_mfma_f32_16x16x32_bf16 v[66:69], v[110:113], v[216:219], v[34:37]
	v_mfma_f32_16x16x32_bf16 v[34:37], v[98:101], v[220:223], v[42:45]
	v_mfma_f32_16x16x32_bf16 v[54:57], v[102:105], v[224:227], v[34:37]
	v_mfma_f32_16x16x32_bf16 v[34:37], v[106:109], v[220:223], v[46:49]
	v_mfma_f32_16x16x32_bf16 v[22:25], v[98:101], v[228:231], v[22:25]
	v_mfma_f32_16x16x32_bf16 v[18:21], v[106:109], v[228:231], v[18:21]
	v_mfma_f32_16x16x32_bf16 v[6:9], v[98:101], v[236:239], v[6:9]
	v_mfma_f32_16x16x32_bf16 v[2:5], v[106:109], v[236:239], v[2:5]
	v_mfma_f32_16x16x32_bf16 v[50:53], v[110:113], v[224:227], v[34:37]
	v_mfma_f32_16x16x32_bf16 v[22:25], v[102:105], v[232:235], v[22:25]
	v_mfma_f32_16x16x32_bf16 v[18:21], v[110:113], v[232:235], v[18:21]
	v_mfma_f32_16x16x32_bf16 v[6:9], v[102:105], v[240:243], v[6:9]
	v_mfma_f32_16x16x32_bf16 v[2:5], v[110:113], v[240:243], v[2:5]
	s_setprio 0
	s_barrier
	s_add_i32 s20, s20, 2
	s_add_u32 s16, s16, 0x100
	s_addc_u32 s17, s17, 0
	s_add_u32 s18, s18, 0x100
	s_addc_u32 s19, s19, 0
	s_cmp_gt_u32 s20, 29
	s_cbranch_scc0 .LBB0_535
	s_and_b64 vcc, exec, s[76:77]
	s_cbranch_vccz .LBB0_538
	s_barrier

; #define PG8_STAGE(bufoff, gbase, voff) do { _Pragma("unroll") for (int _i = 0; _i < 2; ++_i) \
;         __builtin_amdgcn_global_load_lds((const unsigned*)((const char*)(gbase) + (voff)[_i]), (LAS unsigned*)(lds + (bufoff) + ldsw + _i * 8192), 16, 0, 0); } while (0)
; #define PG8_LDA(dst, b, h) do { _Pragma("unroll") for (int m = 0; m < 4; ++m) _Pragma("unroll") for (int k = 0; k < 2; ++k) dst[m][k] = *(const LAS bf16x8*)(lds + PG8_SA(b, h) + aoff + m * 2048 + k * 1024); } while (0)
; #define PG8_LDB(dst, b, h) do { _Pragma("unroll") for (int n = 0; n < 2; ++n) _Pragma("unroll") for (int k = 0; k < 2; ++k) dst[n][k] = *(const LAS bf16x8*)(lds + PG8_SB(b, h) + boff + n * 2048 + k * 1024); } while (0)
; #define PG8_MMA(ai, bj, At, Bt) do { __builtin_amdgcn_s_setprio(1); _Pragma("unroll") for (int m = 0; m < 4; ++m) _Pragma("unroll") for (int n = 0; n < 2; ++n) _Pragma("unroll") for (int k = 0; k < 2; ++k) \
;         acc[ai][bj][m][n] = __builtin_amdgcn_mfma_f32_16x16x32_bf16(Bt[n][k], At[m][k], acc[ai][bj][m][n], 0, 0, 0); __builtin_amdgcn_s_setprio(0); } while (0)
; #define PG8_WAIT_V(n) asm volatile("s_waitcnt vmcnt(" #n ")" ::: "memory")
; #define PG8_WAIT_L(n) asm volatile("s_waitcnt lgkmcnt(" #n ")" ::: "memory")
; template <class Epi, class Sched, bool ALIGN_EPI = false, bool SP2 = false>
; __device__ __forceinline__ void gemm_phase(LAS unsigned char* lds, const Gemm g, const Sched& S, const Epi& E) {
;     ...
;         for (int t = 0; t < nt; t += 2) {
;             const bool last = (t == nt - 2);
;             const char* a1 = cA + (size_t)(t + 1) * kstep;
;             const char* a2 = last ? nA : cA + (size_t)(t + 2) * kstep; const char* b2 = last ? nB : cB + (size_t)(t + 2) * kstep;
;             const char* a3 = a2 + kstep; const char* b3 = b2 + kstep;
;             if (last && has_next) S.a_ready(nxt);
;             if constexpr (SP2) {
;             PG8_LDB(B0, 0, 0); PG8_LDB(B1, 0, 1); PG8_SCHED; PG8_LDA(At, 0, 0); PG8_STAGE(PG8_SA(1, 1), a1 + hstep, voffA);
;             PG8_WAIT_V(8); PG8_WAIT_L(0); PG8_BAR; PG8_MMA(0, 0, At, B0); PG8_MMA(0, 1, At, B1); PG8_BAR; PG8_SCHED;
;             PG8_LDA(At, 0, 1); PG8_STAGE(PG8_SB(0, 0), b2, voffB); PG8_STAGE(PG8_SB(0, 1), b2 + hstepB, voffB); PG8_STAGE(PG8_SA(0, 0), a2, voffA);
;             PG8_WAIT_V(8); PG8_WAIT_L(0); PG8_BAR; PG8_MMA(1, 0, At, B0); PG8_MMA(1, 1, At, B1); PG8_BAR; PG8_SCHED;
.LBB0_1225:
	ds_read_b128 v[140:143], v135
	ds_read_b128 v[144:147], v135 offset:1024
	ds_read_b128 v[148:151], v135 offset:2048
	ds_read_b128 v[152:155], v135 offset:3072
	ds_read_b128 v[156:159], v136
	ds_read_b128 v[160:163], v136 offset:1024
	ds_read_b128 v[164:167], v136 offset:2048
	ds_read_b128 v[168:171], v136 offset:3072
	s_add_i32 s16, s18, 2
	s_mov_b32 s17, s13
	s_or_b32 s12, s18, 1
	s_lshl_b64 s[20:21], s[16:17], 7
	s_cmp_lg_u32 s18, s33
	s_cselect_b32 s18, s20, 0
	s_cselect_b32 s17, s21, 0
	s_add_u32 s20, s8, s18
	s_addc_u32 s21, s9, s17
	s_add_u32 s18, s4, s18
	s_addc_u32 s19, s5, s17
	s_lshl_b64 s[44:45], s[12:13], 7
	s_add_u32 s44, s10, s44
	s_addc_u32 s45, s11, s45
	s_mov_b32 m0, s34
	v_lshl_add_u64 v[204:205], s[44:45], 0, v[132:133]
	ds_read_b128 v[172:175], v137
	ds_read_b128 v[176:179], v137 offset:1024
	ds_read_b128 v[180:183], v137 offset:2048
	ds_read_b128 v[184:187], v137 offset:3072
	ds_read_b128 v[188:191], v137 offset:4096
	ds_read_b128 v[192:195], v137 offset:5120
	ds_read_b128 v[196:199], v137 offset:6144
	ds_read_b128 v[200:203], v137 offset:7168
	global_load_lds_dwordx4 v[204:205], off
	v_lshl_add_u64 v[204:205], s[44:45], 0, v[130:131]
	s_mov_b32 m0, s35
	s_nop 0
	global_load_lds_dwordx4 v[204:205], off
	s_waitcnt vmcnt(8)
	s_waitcnt lgkmcnt(0)
	s_barrier
	s_setprio 1
	s_waitcnt lgkmcnt(0)
	v_mfma_f32_16x16x32_bf16 v[126:129], v[140:143], v[172:175], v[126:129]
	v_mfma_f32_16x16x32_bf16 v[94:97], v[148:151], v[172:175], v[94:97]
	v_mfma_f32_16x16x32_bf16 v[122:125], v[140:143], v[180:183], v[122:125]
	v_mfma_f32_16x16x32_bf16 v[90:93], v[148:151], v[180:183], v[90:93]
	v_mfma_f32_16x16x32_bf16 v[118:121], v[140:143], v[188:191], v[118:121]
	v_mfma_f32_16x16x32_bf16 v[86:89], v[148:151], v[188:191], v[86:89]
	v_mfma_f32_16x16x32_bf16 v[114:117], v[140:143], v[196:199], v[114:117]
	v_mfma_f32_16x16x32_bf16 v[82:85], v[148:151], v[196:199], v[82:85]
	v_mfma_f32_16x16x32_bf16 v[126:129], v[144:147], v[176:179], v[126:129]
	v_mfma_f32_16x16x32_bf16 v[94:97], v[152:155], v[176:179], v[94:97]
	v_mfma_f32_16x16x32_bf16 v[122:125], v[144:147], v[184:187], v[122:125]
	v_mfma_f32_16x16x32_bf16 v[90:93], v[152:155], v[184:187], v[90:93]
	v_mfma_f32_16x16x32_bf16 v[118:121], v[144:147], v[192:195], v[118:121]
	v_mfma_f32_16x16x32_bf16 v[86:89], v[152:155], v[192:195], v[86:89]
	v_mfma_f32_16x16x32_bf16 v[114:117], v[144:147], v[200:203], v[114:117]
	v_mfma_f32_16x16x32_bf16 v[82:85], v[152:155], v[200:203], v[82:85]
	v_mfma_f32_16x16x32_bf16 v[70:73], v[156:159], v[172:175], v[70:73]
	v_mfma_f32_16x16x32_bf16 v[42:45], v[164:167], v[172:175], v[42:45]
	v_mfma_f32_16x16x32_bf16 v[62:65], v[156:159], v[180:183], v[62:65]
	v_mfma_f32_16x16x32_bf16 v[34:37], v[164:167], v[180:183], v[34:37]
	v_mfma_f32_16x16x32_bf16 v[54:57], v[156:159], v[188:191], v[54:57]
	v_mfma_f32_16x16x32_bf16 v[26:29], v[164:167], v[188:191], v[26:29]
	v_mfma_f32_16x16x32_bf16 v[50:53], v[156:159], v[196:199], v[50:53]
	v_mfma_f32_16x16x32_bf16 v[18:21], v[164:167], v[196:199], v[18:21]
	v_mfma_f32_16x16x32_bf16 v[70:73], v[160:163], v[176:179], v[70:73]
	v_mfma_f32_16x16x32_bf16 v[42:45], v[168:171], v[176:179], v[42:45]
	v_mfma_f32_16x16x32_bf16 v[62:65], v[160:163], v[184:187], v[62:65]
	v_mfma_f32_16x16x32_bf16 v[34:37], v[168:171], v[184:187], v[34:37]
	v_mfma_f32_16x16x32_bf16 v[54:57], v[160:163], v[192:195], v[54:57]
	v_mfma_f32_16x16x32_bf16 v[26:29], v[168:171], v[192:195], v[26:29]
	v_mfma_f32_16x16x32_bf16 v[50:53], v[160:163], v[200:203], v[50:53]
	v_mfma_f32_16x16x32_bf16 v[18:21], v[168:171], v[200:203], v[18:21]
	s_setprio 0
	s_barrier
	s_mov_b32 m0, s36
	v_lshl_add_u64 v[204:205], s[18:19], 0, v[132:133]
	s_add_u32 s44, s18, 0x80000
	ds_read_b128 v[172:175], v137 offset:16384
	ds_read_b128 v[176:179], v137 offset:17408
	ds_read_b128 v[180:183], v137 offset:18432
	ds_read_b128 v[184:187], v137 offset:19456
	ds_read_b128 v[188:191], v137 offset:20480
	ds_read_b128 v[192:195], v137 offset:21504
	ds_read_b128 v[196:199], v137 offset:22528
	ds_read_b128 v[200:203], v137 offset:23552
	global_load_lds_dwordx4 v[204:205], off
	v_lshl_add_u64 v[206:207], s[18:19], 0, v[130:131]
	s_mov_b32 m0, s37
	s_addc_u32 s45, s19, 0
	global_load_lds_dwordx4 v[206:207], off
	v_lshl_add_u64 v[208:209], s[44:45], 0, v[132:133]
	s_mov_b32 m0, s38
	v_lshl_add_u64 v[210:211], s[20:21], 0, v[130:131]
	global_load_lds_dwordx4 v[208:209], off
	v_lshl_add_u64 v[208:209], s[44:45], 0, v[130:131]
	s_mov_b32 m0, s39
	s_nop 0
	global_load_lds_dwordx4 v[208:209], off
	v_lshl_add_u64 v[208:209], s[20:21], 0, v[132:133]
	s_mov_b32 m0, s3
	s_nop 0
	global_load_lds_dwordx4 v[208:209], off
	s_mov_b32 m0, s24
	s_nop 0
	global_load_lds_dwordx4 v[210:211], off
	s_waitcnt vmcnt(8)
	s_waitcnt lgkmcnt(0)
	s_barrier
; #define PG8_STAGE(bufoff, gbase, voff) do { _Pragma("unroll") for (int _i = 0; _i < 2; ++_i) \
;         __builtin_amdgcn_global_load_lds((const unsigned*)((const char*)(gbase) + (voff)[_i]), (LAS unsigned*)(lds + (bufoff) + ldsw + _i * 8192), 16, 0, 0); } while (0)
; #define PG8_LDA(dst, b, h) do { _Pragma("unroll") for (int m = 0; m < 4; ++m) _Pragma("unroll") for (int k = 0; k < 2; ++k) dst[m][k] = *(const LAS bf16x8*)(lds + PG8_SA(b, h) + aoff + m * 2048 + k * 1024); } while (0)
; #define PG8_LDB(dst, b, h) do { _Pragma("unroll") for (int n = 0; n < 2; ++n) _Pragma("unroll") for (int k = 0; k < 2; ++k) dst[n][k] = *(const LAS bf16x8*)(lds + PG8_SB(b, h) + boff + n * 2048 + k * 1024); } while (0)
; #define PG8_MMA(ai, bj, At, Bt) do { __builtin_amdgcn_s_setprio(1); _Pragma("unroll") for (int m = 0; m < 4; ++m) _Pragma("unroll") for (int n = 0; n < 2; ++n) _Pragma("unroll") for (int k = 0; k < 2; ++k) \
;         acc[ai][bj][m][n] = __builtin_amdgcn_mfma_f32_16x16x32_bf16(Bt[n][k], At[m][k], acc[ai][bj][m][n], 0, 0, 0); __builtin_amdgcn_s_setprio(0); } while (0)
; #define PG8_WAIT_V(n) asm volatile("s_waitcnt vmcnt(" #n ")" ::: "memory")
; #define PG8_WAIT_L(n) asm volatile("s_waitcnt lgkmcnt(" #n ")" ::: "memory")
; #define PG8_BAR __builtin_amdgcn_s_barrier()
; #define PG8_SCHED __builtin_amdgcn_sched_barrier(0)
; template <class Epi, class Sched, bool ALIGN_EPI = false, bool SP2 = false>
; __device__ __forceinline__ void gemm_phase(LAS unsigned char* lds, const Gemm g, const Sched& S, const Epi& E) {
;     ...
;             PG8_WAIT_V(8); PG8_WAIT_L(0); PG8_BAR; PG8_MMA(1, 0, At, B0); PG8_MMA(1, 1, At, B1); PG8_BAR; PG8_SCHED;
;             PG8_LDB(B0, 1, 0); PG8_LDB(B1, 1, 1); PG8_SCHED; PG8_LDA(At, 1, 0); PG8_STAGE(PG8_SA(0, 1), a2 + hstep, voffA);
;             PG8_WAIT_V(8); PG8_WAIT_L(0); PG8_BAR; PG8_MMA(0, 0, At, B0); PG8_MMA(0, 1, At, B1); PG8_BAR; PG8_SCHED;
	s_setprio 1
	s_waitcnt lgkmcnt(0)
	v_mfma_f32_16x16x32_bf16 v[110:113], v[140:143], v[172:175], v[110:113]
	v_mfma_f32_16x16x32_bf16 v[78:81], v[148:151], v[172:175], v[78:81]
	v_mfma_f32_16x16x32_bf16 v[106:109], v[140:143], v[180:183], v[106:109]
	v_mfma_f32_16x16x32_bf16 v[74:77], v[148:151], v[180:183], v[74:77]
	v_mfma_f32_16x16x32_bf16 v[102:105], v[140:143], v[188:191], v[102:105]
	v_mfma_f32_16x16x32_bf16 v[66:69], v[148:151], v[188:191], v[66:69]
	v_mfma_f32_16x16x32_bf16 v[98:101], v[140:143], v[196:199], v[98:101]
	v_mfma_f32_16x16x32_bf16 v[58:61], v[148:151], v[196:199], v[58:61]
	v_mfma_f32_16x16x32_bf16 v[110:113], v[144:147], v[176:179], v[110:113]
	v_mfma_f32_16x16x32_bf16 v[78:81], v[152:155], v[176:179], v[78:81]
	v_mfma_f32_16x16x32_bf16 v[106:109], v[144:147], v[184:187], v[106:109]
	v_mfma_f32_16x16x32_bf16 v[74:77], v[152:155], v[184:187], v[74:77]
	v_mfma_f32_16x16x32_bf16 v[102:105], v[144:147], v[192:195], v[102:105]
	v_mfma_f32_16x16x32_bf16 v[66:69], v[152:155], v[192:195], v[66:69]
	v_mfma_f32_16x16x32_bf16 v[98:101], v[144:147], v[200:203], v[98:101]
	v_mfma_f32_16x16x32_bf16 v[58:61], v[152:155], v[200:203], v[58:61]
	v_mfma_f32_16x16x32_bf16 v[46:49], v[156:159], v[172:175], v[46:49]
	v_mfma_f32_16x16x32_bf16 v[14:17], v[164:167], v[172:175], v[14:17]
	v_mfma_f32_16x16x32_bf16 v[38:41], v[156:159], v[180:183], v[38:41]
	v_mfma_f32_16x16x32_bf16 v[10:13], v[164:167], v[180:183], v[10:13]
	v_mfma_f32_16x16x32_bf16 v[30:33], v[156:159], v[188:191], v[30:33]
	v_mfma_f32_16x16x32_bf16 v[6:9], v[164:167], v[188:191], v[6:9]
	v_mfma_f32_16x16x32_bf16 v[22:25], v[156:159], v[196:199], v[22:25]
	v_mfma_f32_16x16x32_bf16 v[2:5], v[164:167], v[196:199], v[2:5]
	v_mfma_f32_16x16x32_bf16 v[46:49], v[160:163], v[176:179], v[46:49]
	v_mfma_f32_16x16x32_bf16 v[14:17], v[168:171], v[176:179], v[14:17]
	v_mfma_f32_16x16x32_bf16 v[38:41], v[160:163], v[184:187], v[38:41]
	v_mfma_f32_16x16x32_bf16 v[10:13], v[168:171], v[184:187], v[10:13]
	v_mfma_f32_16x16x32_bf16 v[30:33], v[160:163], v[192:195], v[30:33]
	v_mfma_f32_16x16x32_bf16 v[6:9], v[168:171], v[192:195], v[6:9]
	v_mfma_f32_16x16x32_bf16 v[22:25], v[160:163], v[200:203], v[22:25]
	v_mfma_f32_16x16x32_bf16 v[2:5], v[168:171], v[200:203], v[2:5]
	s_setprio 0
	s_barrier
	ds_read_b128 v[140:143], v138
	ds_read_b128 v[144:147], v138 offset:1024
	ds_read_b128 v[148:151], v138 offset:2048
	ds_read_b128 v[152:155], v138 offset:3072
	ds_read_b128 v[156:159], v139
	ds_read_b128 v[160:163], v139 offset:1024
	ds_read_b128 v[164:167], v139 offset:2048
	ds_read_b128 v[168:171], v139 offset:3072
	s_add_u32 s20, s20, 0x80000
	s_addc_u32 s21, s21, 0
	s_mov_b32 m0, s25
	v_lshl_add_u64 v[212:213], s[20:21], 0, v[132:133]
	ds_read_b128 v[172:175], v137 offset:32768
	ds_read_b128 v[176:179], v137 offset:33792
	ds_read_b128 v[180:183], v137 offset:34816
	ds_read_b128 v[184:187], v137 offset:35840
	ds_read_b128 v[188:191], v137 offset:36864
	ds_read_b128 v[192:195], v137 offset:37888
	ds_read_b128 v[196:199], v137 offset:38912
	ds_read_b128 v[200:203], v137 offset:39936
	global_load_lds_dwordx4 v[212:213], off
	v_lshl_add_u64 v[212:213], s[20:21], 0, v[130:131]
	s_mov_b32 m0, s28
	s_nop 0
	global_load_lds_dwordx4 v[212:213], off
	s_waitcnt vmcnt(8)
	s_waitcnt lgkmcnt(0)
	s_barrier
	s_setprio 1
	s_waitcnt lgkmcnt(0)
	v_mfma_f32_16x16x32_bf16 v[126:129], v[140:143], v[172:175], v[126:129]
	v_mfma_f32_16x16x32_bf16 v[94:97], v[148:151], v[172:175], v[94:97]
	v_mfma_f32_16x16x32_bf16 v[122:125], v[140:143], v[180:183], v[122:125]
	v_mfma_f32_16x16x32_bf16 v[90:93], v[148:151], v[180:183], v[90:93]
	v_mfma_f32_16x16x32_bf16 v[118:121], v[140:143], v[188:191], v[118:121]
	v_mfma_f32_16x16x32_bf16 v[86:89], v[148:151], v[188:191], v[86:89]
	v_mfma_f32_16x16x32_bf16 v[114:117], v[140:143], v[196:199], v[114:117]
	v_mfma_f32_16x16x32_bf16 v[82:85], v[148:151], v[196:199], v[82:85]
	v_mfma_f32_16x16x32_bf16 v[126:129], v[144:147], v[176:179], v[126:129]
	v_mfma_f32_16x16x32_bf16 v[94:97], v[152:155], v[176:179], v[94:97]
	v_mfma_f32_16x16x32_bf16 v[122:125], v[144:147], v[184:187], v[122:125]
	v_mfma_f32_16x16x32_bf16 v[90:93], v[152:155], v[184:187], v[90:93]
	v_mfma_f32_16x16x32_bf16 v[118:121], v[144:147], v[192:195], v[118:121]
	v_mfma_f32_16x16x32_bf16 v[86:89], v[152:155], v[192:195], v[86:89]
	v_mfma_f32_16x16x32_bf16 v[114:117], v[144:147], v[200:203], v[114:117]
	v_mfma_f32_16x16x32_bf16 v[82:85], v[152:155], v[200:203], v[82:85]
	v_mfma_f32_16x16x32_bf16 v[70:73], v[156:159], v[172:175], v[70:73]
	v_mfma_f32_16x16x32_bf16 v[42:45], v[164:167], v[172:175], v[42:45]
	v_mfma_f32_16x16x32_bf16 v[62:65], v[156:159], v[180:183], v[62:65]
	v_mfma_f32_16x16x32_bf16 v[34:37], v[164:167], v[180:183], v[34:37]
	v_mfma_f32_16x16x32_bf16 v[54:57], v[156:159], v[188:191], v[54:57]
	v_mfma_f32_16x16x32_bf16 v[26:29], v[164:167], v[188:191], v[26:29]
	v_mfma_f32_16x16x32_bf16 v[50:53], v[156:159], v[196:199], v[50:53]
	v_mfma_f32_16x16x32_bf16 v[18:21], v[164:167], v[196:199], v[18:21]
	v_mfma_f32_16x16x32_bf16 v[70:73], v[160:163], v[176:179], v[70:73]
	v_mfma_f32_16x16x32_bf16 v[42:45], v[168:171], v[176:179], v[42:45]
	v_mfma_f32_16x16x32_bf16 v[62:65], v[160:163], v[184:187], v[62:65]
	v_mfma_f32_16x16x32_bf16 v[34:37], v[168:171], v[184:187], v[34:37]
	v_mfma_f32_16x16x32_bf16 v[54:57], v[160:163], v[192:195], v[54:57]
	v_mfma_f32_16x16x32_bf16 v[26:29], v[168:171], v[192:195], v[26:29]
	v_mfma_f32_16x16x32_bf16 v[50:53], v[160:163], v[200:203], v[50:53]
	v_mfma_f32_16x16x32_bf16 v[18:21], v[168:171], v[200:203], v[18:21]
	s_setprio 0
	s_barrier
; #define PG8_STAGE(bufoff, gbase, voff) do { _Pragma("unroll") for (int _i = 0; _i < 2; ++_i) \
;         __builtin_amdgcn_global_load_lds((const unsigned*)((const char*)(gbase) + (voff)[_i]), (LAS unsigned*)(lds + (bufoff) + ldsw + _i * 8192), 16, 0, 0); } while (0)
; #define PG8_LDA(dst, b, h) do { _Pragma("unroll") for (int m = 0; m < 4; ++m) _Pragma("unroll") for (int k = 0; k < 2; ++k) dst[m][k] = *(const LAS bf16x8*)(lds + PG8_SA(b, h) + aoff + m * 2048 + k * 1024); } while (0)
; #define PG8_MMA(ai, bj, At, Bt) do { __builtin_amdgcn_s_setprio(1); _Pragma("unroll") for (int m = 0; m < 4; ++m) _Pragma("unroll") for (int n = 0; n < 2; ++n) _Pragma("unroll") for (int k = 0; k < 2; ++k) \
;         acc[ai][bj][m][n] = __builtin_amdgcn_mfma_f32_16x16x32_bf16(Bt[n][k], At[m][k], acc[ai][bj][m][n], 0, 0, 0); __builtin_amdgcn_s_setprio(0); } while (0)
; #define PG8_WAIT_V(n) asm volatile("s_waitcnt vmcnt(" #n ")" ::: "memory")
; #define PG8_WAIT_L(n) asm volatile("s_waitcnt lgkmcnt(" #n ")" ::: "memory")
; #define PG8_BAR __builtin_amdgcn_s_barrier()
; #define PG8_SCHED __builtin_amdgcn_sched_barrier(0)
; template <class Epi, class Sched, bool ALIGN_EPI = false, bool SP2 = false>
; __device__ __forceinline__ void gemm_phase(LAS unsigned char* lds, const Gemm g, const Sched& S, const Epi& E) {
;     ...
;             PG8_LDA(At, 1, 1); PG8_STAGE(PG8_SB(1, 0), b3, voffB); PG8_STAGE(PG8_SB(1, 1), b3 + hstepB, voffB); PG8_STAGE(PG8_SA(1, 0), a3, voffA);
;             PG8_WAIT_V(8); PG8_WAIT_L(0); PG8_BAR; PG8_MMA(1, 0, At, B0); PG8_MMA(1, 1, At, B1); PG8_BAR; PG8_SCHED;
	s_mov_b32 m0, s40
	v_lshl_add_u64 v[204:205], v[204:205], 0, s[14:15]
	s_add_u32 s18, s18, 0x80080
	ds_read_b128 v[172:175], v137 offset:49152
	ds_read_b128 v[176:179], v137 offset:50176
	ds_read_b128 v[180:183], v137 offset:51200
	ds_read_b128 v[184:187], v137 offset:52224
	ds_read_b128 v[188:191], v137 offset:53248
	ds_read_b128 v[192:195], v137 offset:54272
	ds_read_b128 v[196:199], v137 offset:55296
	ds_read_b128 v[200:203], v137 offset:56320
	global_load_lds_dwordx4 v[204:205], off
	v_lshl_add_u64 v[204:205], v[206:207], 0, s[14:15]
	s_mov_b32 m0, s41
	s_addc_u32 s19, s19, 0
	global_load_lds_dwordx4 v[204:205], off
	v_lshl_add_u64 v[204:205], s[18:19], 0, v[132:133]
	s_mov_b32 m0, s42
	s_nop 0
	global_load_lds_dwordx4 v[204:205], off
	v_lshl_add_u64 v[204:205], s[18:19], 0, v[130:131]
	s_mov_b32 m0, s43
	s_nop 0
	global_load_lds_dwordx4 v[204:205], off
	v_lshl_add_u64 v[204:205], v[208:209], 0, s[14:15]
	s_mov_b32 m0, s30
	s_nop 0
	global_load_lds_dwordx4 v[204:205], off
	v_lshl_add_u64 v[204:205], v[210:211], 0, s[14:15]
	s_mov_b32 m0, s31
	s_nop 0
	global_load_lds_dwordx4 v[204:205], off
	s_waitcnt vmcnt(8)
	s_waitcnt lgkmcnt(0)
	s_barrier
	s_setprio 1
	s_waitcnt lgkmcnt(0)
	v_mfma_f32_16x16x32_bf16 v[110:113], v[140:143], v[172:175], v[110:113]
	v_mfma_f32_16x16x32_bf16 v[78:81], v[148:151], v[172:175], v[78:81]
	v_mfma_f32_16x16x32_bf16 v[106:109], v[140:143], v[180:183], v[106:109]
	v_mfma_f32_16x16x32_bf16 v[74:77], v[148:151], v[180:183], v[74:77]
	v_mfma_f32_16x16x32_bf16 v[102:105], v[140:143], v[188:191], v[102:105]
	v_mfma_f32_16x16x32_bf16 v[66:69], v[148:151], v[188:191], v[66:69]
	v_mfma_f32_16x16x32_bf16 v[98:101], v[140:143], v[196:199], v[98:101]
	v_mfma_f32_16x16x32_bf16 v[58:61], v[148:151], v[196:199], v[58:61]
	v_mfma_f32_16x16x32_bf16 v[110:113], v[144:147], v[176:179], v[110:113]
	v_mfma_f32_16x16x32_bf16 v[78:81], v[152:155], v[176:179], v[78:81]
	v_mfma_f32_16x16x32_bf16 v[106:109], v[144:147], v[184:187], v[106:109]
	v_mfma_f32_16x16x32_bf16 v[74:77], v[152:155], v[184:187], v[74:77]
	v_mfma_f32_16x16x32_bf16 v[102:105], v[144:147], v[192:195], v[102:105]
	v_mfma_f32_16x16x32_bf16 v[66:69], v[152:155], v[192:195], v[66:69]
	v_mfma_f32_16x16x32_bf16 v[98:101], v[144:147], v[200:203], v[98:101]
	v_mfma_f32_16x16x32_bf16 v[58:61], v[152:155], v[200:203], v[58:61]
	v_mfma_f32_16x16x32_bf16 v[46:49], v[156:159], v[172:175], v[46:49]
	v_mfma_f32_16x16x32_bf16 v[14:17], v[164:167], v[172:175], v[14:17]
	v_mfma_f32_16x16x32_bf16 v[38:41], v[156:159], v[180:183], v[38:41]
	v_mfma_f32_16x16x32_bf16 v[10:13], v[164:167], v[180:183], v[10:13]
	v_mfma_f32_16x16x32_bf16 v[30:33], v[156:159], v[188:191], v[30:33]
	v_mfma_f32_16x16x32_bf16 v[6:9], v[164:167], v[188:191], v[6:9]
	v_mfma_f32_16x16x32_bf16 v[22:25], v[156:159], v[196:199], v[22:25]
	v_mfma_f32_16x16x32_bf16 v[2:5], v[164:167], v[196:199], v[2:5]
	v_mfma_f32_16x16x32_bf16 v[46:49], v[160:163], v[176:179], v[46:49]
	v_mfma_f32_16x16x32_bf16 v[14:17], v[168:171], v[176:179], v[14:17]
	v_mfma_f32_16x16x32_bf16 v[38:41], v[160:163], v[184:187], v[38:41]
	v_mfma_f32_16x16x32_bf16 v[10:13], v[168:171], v[184:187], v[10:13]
	v_mfma_f32_16x16x32_bf16 v[30:33], v[160:163], v[192:195], v[30:33]
	v_mfma_f32_16x16x32_bf16 v[6:9], v[168:171], v[192:195], v[6:9]
	v_mfma_f32_16x16x32_bf16 v[22:25], v[160:163], v[200:203], v[22:25]
	v_mfma_f32_16x16x32_bf16 v[2:5], v[168:171], v[200:203], v[2:5]
	s_setprio 0
	s_barrier
	s_cmp_ge_u32 s16, s29
	s_mov_b32 s18, s16
	s_cbranch_scc0 .LBB0_1225
	v_readlane_b32 s30, v252, 2
	v_readlane_b32 s34, v252, 37
	s_cmpk_lt_u32 s22, 0x100
	v_readlane_b32 s31, v252, 3
	v_readlane_b32 s35, v252, 38
	s_cbranch_scc0 .LBB0_1228
	s_barrier

;     __device__ bool next(int i, Unit& u) const { if (i != 0 || c >= 128) return false; const int t = c >> 2; u.pm = t & 3; u.pn = t >> 2; u.koff = koff_bytes; u.q = c & 3; return true; }
; #define PG8_STAGE(bufoff, gbase, voff) do { _Pragma("unroll") for (int _i = 0; _i < 2; ++_i) \
;         __builtin_amdgcn_global_load_lds((const unsigned*)((const char*)(gbase) + (voff)[_i]), (LAS unsigned*)(lds + (bufoff) + ldsw + _i * 8192), 16, 0, 0); } while (0)
; #define PG8_LDA(dst, b, h) do { _Pragma("unroll") for (int m = 0; m < 4; ++m) _Pragma("unroll") for (int k = 0; k < 2; ++k) dst[m][k] = *(const LAS bf16x8*)(lds + PG8_SA(b, h) + aoff + m * 2048 + k * 1024); } while (0)
; #define PG8_LDB(dst, b, h) do { _Pragma("unroll") for (int n = 0; n < 2; ++n) _Pragma("unroll") for (int k = 0; k < 2; ++k) dst[n][k] = *(const LAS bf16x8*)(lds + PG8_SB(b, h) + boff + n * 2048 + k * 1024); } while (0)
; #define PG8_WAIT_V(n) asm volatile("s_waitcnt vmcnt(" #n ")" ::: "memory")
; #define PG8_WAIT_L(n) asm volatile("s_waitcnt lgkmcnt(" #n ")" ::: "memory")
; #define PG8_BAR __builtin_amdgcn_s_barrier()
; template <class Epi, class Sched, bool ALIGN_EPI = false, bool SP2 = false>
; __device__ __forceinline__ void gemm_phase(LAS unsigned char* lds, const Gemm g, const Sched& S, const Epi& E) {
;     ...
;         const bool has_next = S.next(ui + 1, nxt);
;         const char* nA = has_next ? (const char*)g.A + (size_t)nxt.pm * tstep + nxt.koff : cA; const char* nB = has_next ? (const char*)g.Bt + (size_t)nxt.pn * tstep + nxt.koff : cB;
;         for (int t = 0; t < nt; t += 2) {
;             const bool last = (t == nt - 2);
;             const char* a1 = cA + (size_t)(t + 1) * kstep;
;             const char* a2 = last ? nA : cA + (size_t)(t + 2) * kstep; const char* b2 = last ? nB : cB + (size_t)(t + 2) * kstep;
;             const char* a3 = a2 + kstep; const char* b3 = b2 + kstep;
;             if (last && has_next) S.a_ready(nxt);
;             if constexpr (SP2) {
;             PG8_LDB(B0, 0, 0); PG8_LDB(B1, 0, 1); PG8_SCHED; PG8_LDA(At, 0, 0); PG8_STAGE(PG8_SA(1, 1), a1 + hstep, voffA);
;             PG8_WAIT_V(8); PG8_WAIT_L(0); PG8_BAR; PG8_MMA(0, 0, At, B0); PG8_MMA(0, 1, At, B1); PG8_BAR; PG8_SCHED;
;             PG8_LDA(At, 0, 1); PG8_STAGE(PG8_SB(0, 0), b2, voffB); PG8_STAGE(PG8_SB(0, 1), b2 + hstepB, voffB); PG8_STAGE(PG8_SA(0, 0), a2, voffA);
.LBB0_1249:
	s_ashr_i32 s19, s18, 31
	s_lshl_b64 s[20:21], s[18:19], 20
	v_readlane_b32 s0, v252, 25
	s_add_u32 s20, s0, s20
	v_readlane_b32 s0, v252, 26
	s_addc_u32 s21, s0, s21
	s_and_b64 s[22:23], s[44:45], exec
	s_cselect_b32 s0, s21, s17
	s_cselect_b32 s3, s20, s16
	s_ashr_i32 s15, s14, 31
	s_lshl_b64 s[22:23], s[14:15], 20
	s_add_u32 s22, s26, s22
	s_addc_u32 s23, s27, s23
	s_and_b64 s[24:25], s[44:45], exec
	s_cselect_b32 s15, s23, s49
	s_cselect_b32 s19, s22, s48
	s_add_u32 s16, s16, 0x80080
	s_addc_u32 s17, s17, 0
	s_add_u32 s24, s48, 0x100
	s_addc_u32 s25, s49, 0
	s_mov_b32 s47, -2
	s_waitcnt vmcnt(0)
	ds_read_b128 v[50:53], v196
	ds_read_b128 v[54:57], v196 offset:1024
	ds_read_b128 v[138:141], v196 offset:2048
	ds_read_b128 v[142:145], v196 offset:3072
	ds_read_b128 v[146:149], v197
	ds_read_b128 v[150:153], v197 offset:1024
	ds_read_b128 v[174:177], v197 offset:2048
	ds_read_b128 v[178:181], v197 offset:3072
	s_add_u32 s48, s16, 0xfff80080
	s_addc_u32 s49, s17, -1
	s_cmp_eq_u32 s47, 28
	s_cselect_b32 s51, s0, s49
	s_cselect_b32 s50, s3, s48
	s_cselect_b32 s49, s15, s25
	s_cselect_b32 s48, s19, s24
	v_lshl_add_u64 v[190:191], s[16:17], 0, v[166:167]
	s_add_i32 m0, s29, 0xc000
	ds_read_b128 v[182:185], v198
	ds_read_b128 v[186:189], v198 offset:1024
	ds_read_b128 v[202:205], v198 offset:2048
	ds_read_b128 v[206:209], v198 offset:3072
	ds_read_b128 v[210:213], v198 offset:4096
	ds_read_b128 v[214:217], v198 offset:5120
	ds_read_b128 v[218:221], v198 offset:6144
	ds_read_b128 v[222:225], v198 offset:7168
	global_load_lds_dwordx4 v[190:191], off
	v_lshl_add_u64 v[190:191], s[16:17], 0, v[168:169]
	s_add_i32 m0, s29, 0xe000
	s_nop 0
	global_load_lds_dwordx4 v[190:191], off
	s_waitcnt lgkmcnt(0)
	s_barrier
	s_setprio 1
	s_waitcnt lgkmcnt(0)
	v_mfma_f32_16x16x32_bf16 v[134:137], v[50:53], v[182:185], 0
	v_mfma_f32_16x16x32_bf16 v[130:133], v[138:141], v[182:185], 0
	v_mfma_f32_16x16x32_bf16 v[118:121], v[50:53], v[202:205], 0
	v_mfma_f32_16x16x32_bf16 v[114:117], v[138:141], v[202:205], 0
	v_mfma_f32_16x16x32_bf16 v[102:105], v[50:53], v[210:213], 0
	v_mfma_f32_16x16x32_bf16 v[98:101], v[138:141], v[210:213], 0
	v_mfma_f32_16x16x32_bf16 v[86:89], v[50:53], v[218:221], 0
	v_mfma_f32_16x16x32_bf16 v[82:85], v[138:141], v[218:221], 0
	v_mfma_f32_16x16x32_bf16 v[134:137], v[54:57], v[186:189], v[134:137]
	v_mfma_f32_16x16x32_bf16 v[130:133], v[142:145], v[186:189], v[130:133]
	v_mfma_f32_16x16x32_bf16 v[118:121], v[54:57], v[206:209], v[118:121]
	v_mfma_f32_16x16x32_bf16 v[114:117], v[142:145], v[206:209], v[114:117]
	v_mfma_f32_16x16x32_bf16 v[102:105], v[54:57], v[214:217], v[102:105]
	v_mfma_f32_16x16x32_bf16 v[98:101], v[142:145], v[214:217], v[98:101]
	v_mfma_f32_16x16x32_bf16 v[86:89], v[54:57], v[222:225], v[86:89]
	v_mfma_f32_16x16x32_bf16 v[82:85], v[142:145], v[222:225], v[82:85]
	v_mfma_f32_16x16x32_bf16 v[126:129], v[146:149], v[182:185], 0
	v_mfma_f32_16x16x32_bf16 v[122:125], v[174:177], v[182:185], 0
	v_mfma_f32_16x16x32_bf16 v[110:113], v[146:149], v[202:205], 0
	v_mfma_f32_16x16x32_bf16 v[106:109], v[174:177], v[202:205], 0
	v_mfma_f32_16x16x32_bf16 v[94:97], v[146:149], v[210:213], 0
	v_mfma_f32_16x16x32_bf16 v[90:93], v[174:177], v[210:213], 0
	v_mfma_f32_16x16x32_bf16 v[78:81], v[146:149], v[218:221], 0
	v_mfma_f32_16x16x32_bf16 v[74:77], v[174:177], v[218:221], 0
	v_mfma_f32_16x16x32_bf16 v[126:129], v[150:153], v[186:189], v[126:129]
	v_mfma_f32_16x16x32_bf16 v[122:125], v[178:181], v[186:189], v[122:125]
	v_mfma_f32_16x16x32_bf16 v[110:113], v[150:153], v[206:209], v[110:113]
	v_mfma_f32_16x16x32_bf16 v[106:109], v[178:181], v[206:209], v[106:109]
	v_mfma_f32_16x16x32_bf16 v[94:97], v[150:153], v[214:217], v[94:97]
	v_mfma_f32_16x16x32_bf16 v[90:93], v[178:181], v[214:217], v[90:93]
	v_mfma_f32_16x16x32_bf16 v[78:81], v[150:153], v[222:225], v[78:81]
	v_mfma_f32_16x16x32_bf16 v[74:77], v[178:181], v[222:225], v[74:77]
	s_setprio 0
	s_barrier
	s_add_i32 s58, s56, s28
	v_lshl_add_u64 v[190:191], s[48:49], 0, v[156:157]
	s_mov_b32 m0, s58
	ds_read_b128 v[182:185], v198 offset:16384
	ds_read_b128 v[186:189], v198 offset:17408
	ds_read_b128 v[202:205], v198 offset:18432
	ds_read_b128 v[206:209], v198 offset:19456
	ds_read_b128 v[210:213], v198 offset:20480
	ds_read_b128 v[214:217], v198 offset:21504
	ds_read_b128 v[218:221], v198 offset:22528
	ds_read_b128 v[222:225], v198 offset:23552
	global_load_lds_dwordx4 v[190:191], off
	s_add_i32 m0, s58, 0x2000
	s_add_u32 s58, s48, 0x20000
	v_lshl_add_u64 v[226:227], s[48:49], 0, v[160:161]
	s_addc_u32 s59, s49, 0
	s_add_i32 s60, s57, s28
	global_load_lds_dwordx4 v[226:227], off
	v_lshl_add_u64 v[228:229], s[58:59], 0, v[156:157]
	s_mov_b32 m0, s60
	v_lshl_add_u64 v[230:231], s[50:51], 0, v[158:159]
	global_load_lds_dwordx4 v[228:229], off
	v_lshl_add_u64 v[228:229], s[58:59], 0, v[160:161]
	s_add_i32 m0, s60, 0x2000
	s_nop 0
	global_load_lds_dwordx4 v[228:229], off
	v_lshl_add_u64 v[228:229], s[50:51], 0, v[154:155]
	s_mov_b32 m0, s29
	s_nop 0
	global_load_lds_dwordx4 v[228:229], off
	s_mov_b32 m0, s30
	s_nop 0
	global_load_lds_dwordx4 v[230:231], off
	s_waitcnt lgkmcnt(0)
	s_barrier
; #define PG8_STAGE(bufoff, gbase, voff) do { _Pragma("unroll") for (int _i = 0; _i < 2; ++_i) \
;         __builtin_amdgcn_global_load_lds((const unsigned*)((const char*)(gbase) + (voff)[_i]), (LAS unsigned*)(lds + (bufoff) + ldsw + _i * 8192), 16, 0, 0); } while (0)
; #define PG8_LDA(dst, b, h) do { _Pragma("unroll") for (int m = 0; m < 4; ++m) _Pragma("unroll") for (int k = 0; k < 2; ++k) dst[m][k] = *(const LAS bf16x8*)(lds + PG8_SA(b, h) + aoff + m * 2048 + k * 1024); } while (0)
; #define PG8_LDB(dst, b, h) do { _Pragma("unroll") for (int n = 0; n < 2; ++n) _Pragma("unroll") for (int k = 0; k < 2; ++k) dst[n][k] = *(const LAS bf16x8*)(lds + PG8_SB(b, h) + boff + n * 2048 + k * 1024); } while (0)
; #define PG8_MMA(ai, bj, At, Bt) do { __builtin_amdgcn_s_setprio(1); _Pragma("unroll") for (int m = 0; m < 4; ++m) _Pragma("unroll") for (int n = 0; n < 2; ++n) _Pragma("unroll") for (int k = 0; k < 2; ++k) \
;         acc[ai][bj][m][n] = __builtin_amdgcn_mfma_f32_16x16x32_bf16(Bt[n][k], At[m][k], acc[ai][bj][m][n], 0, 0, 0); __builtin_amdgcn_s_setprio(0); } while (0)
; #define PG8_BAR __builtin_amdgcn_s_barrier()
; template <class Epi, class Sched, bool ALIGN_EPI = false, bool SP2 = false>
; __device__ __forceinline__ void gemm_phase(LAS unsigned char* lds, const Gemm g, const Sched& S, const Epi& E) {
;     ...
;             if constexpr (SP2) {
;             PG8_LDB(B0, 0, 0); PG8_LDB(B1, 0, 1); PG8_SCHED; PG8_LDA(At, 0, 0); PG8_STAGE(PG8_SA(1, 1), a1 + hstep, voffA);
;             PG8_WAIT_V(8); PG8_WAIT_L(0); PG8_BAR; PG8_MMA(0, 0, At, B0); PG8_MMA(0, 1, At, B1); PG8_BAR; PG8_SCHED;
;             PG8_LDA(At, 0, 1); PG8_STAGE(PG8_SB(0, 0), b2, voffB); PG8_STAGE(PG8_SB(0, 1), b2 + hstepB, voffB); PG8_STAGE(PG8_SA(0, 0), a2, voffA);
;             PG8_WAIT_V(8); PG8_WAIT_L(0); PG8_BAR; PG8_MMA(1, 0, At, B0); PG8_MMA(1, 1, At, B1); PG8_BAR; PG8_SCHED;
;             PG8_LDB(B0, 1, 0); PG8_LDB(B1, 1, 1); PG8_SCHED; PG8_LDA(At, 1, 0); PG8_STAGE(PG8_SA(0, 1), a2 + hstep, voffA);
;             PG8_WAIT_V(8); PG8_WAIT_L(0); PG8_BAR; PG8_MMA(0, 0, At, B0); PG8_MMA(0, 1, At, B1); PG8_BAR; PG8_SCHED;
;             PG8_LDA(At, 1, 1); PG8_STAGE(PG8_SB(1, 0), b3, voffB); PG8_STAGE(PG8_SB(1, 1), b3 + hstepB, voffB); PG8_STAGE(PG8_SA(1, 0), a3, voffA);
;             PG8_WAIT_V(8); PG8_WAIT_L(0); PG8_BAR; PG8_MMA(1, 0, At, B0); PG8_MMA(1, 1, At, B1); PG8_BAR; PG8_SCHED;
	s_setprio 1
	s_waitcnt lgkmcnt(0)
	v_mfma_f32_16x16x32_bf16 v[70:73], v[50:53], v[182:185], 0
	v_mfma_f32_16x16x32_bf16 v[66:69], v[138:141], v[182:185], 0
	v_mfma_f32_16x16x32_bf16 v[46:49], v[50:53], v[202:205], 0
	v_mfma_f32_16x16x32_bf16 v[42:45], v[138:141], v[202:205], 0
	v_mfma_f32_16x16x32_bf16 v[30:33], v[50:53], v[210:213], 0
	v_mfma_f32_16x16x32_bf16 v[26:29], v[138:141], v[210:213], 0
	v_mfma_f32_16x16x32_bf16 v[14:17], v[50:53], v[218:221], 0
	v_mfma_f32_16x16x32_bf16 v[10:13], v[138:141], v[218:221], 0
	v_mfma_f32_16x16x32_bf16 v[70:73], v[54:57], v[186:189], v[70:73]
	v_mfma_f32_16x16x32_bf16 v[66:69], v[142:145], v[186:189], v[66:69]
	v_mfma_f32_16x16x32_bf16 v[46:49], v[54:57], v[206:209], v[46:49]
	v_mfma_f32_16x16x32_bf16 v[42:45], v[142:145], v[206:209], v[42:45]
	v_mfma_f32_16x16x32_bf16 v[30:33], v[54:57], v[214:217], v[30:33]
	v_mfma_f32_16x16x32_bf16 v[26:29], v[142:145], v[214:217], v[26:29]
	v_mfma_f32_16x16x32_bf16 v[14:17], v[54:57], v[222:225], v[14:17]
	v_mfma_f32_16x16x32_bf16 v[10:13], v[142:145], v[222:225], v[10:13]
	v_mfma_f32_16x16x32_bf16 v[38:41], v[146:149], v[202:205], 0
	v_mfma_f32_16x16x32_bf16 v[34:37], v[174:177], v[202:205], 0
	v_mfma_f32_16x16x32_bf16 v[22:25], v[146:149], v[210:213], 0
	v_mfma_f32_16x16x32_bf16 v[18:21], v[174:177], v[210:213], 0
	v_mfma_f32_16x16x32_bf16 v[6:9], v[146:149], v[218:221], 0
	v_mfma_f32_16x16x32_bf16 v[2:5], v[174:177], v[218:221], 0
	v_mfma_f32_16x16x32_bf16 v[50:53], v[146:149], v[182:185], 0
	v_mfma_f32_16x16x32_bf16 v[54:57], v[174:177], v[182:185], 0
	v_mfma_f32_16x16x32_bf16 v[38:41], v[150:153], v[206:209], v[38:41]
	v_mfma_f32_16x16x32_bf16 v[34:37], v[178:181], v[206:209], v[34:37]
	v_mfma_f32_16x16x32_bf16 v[22:25], v[150:153], v[214:217], v[22:25]
	v_mfma_f32_16x16x32_bf16 v[18:21], v[178:181], v[214:217], v[18:21]
	v_mfma_f32_16x16x32_bf16 v[6:9], v[150:153], v[222:225], v[6:9]
	v_mfma_f32_16x16x32_bf16 v[2:5], v[178:181], v[222:225], v[2:5]
	v_mfma_f32_16x16x32_bf16 v[50:53], v[150:153], v[186:189], v[50:53]
	v_mfma_f32_16x16x32_bf16 v[54:57], v[178:181], v[186:189], v[54:57]
	s_setprio 0
	s_barrier
	s_add_i32 s58, 0, 0x18000
	s_add_i32 s59, 0, 0x1c000
	v_add_u32_e32 v142, s58, v1
	v_add_u32_e32 v162, s59, v1
	ds_read_b128 v[58:61], v142
	ds_read_b128 v[62:65], v142 offset:1024
	ds_read_b128 v[138:141], v142 offset:2048
	ds_read_b128 v[142:145], v142 offset:3072
	ds_read_b128 v[146:149], v162
	ds_read_b128 v[150:153], v162 offset:1024
	ds_read_b128 v[174:177], v162 offset:2048
	ds_read_b128 v[178:181], v162 offset:3072
	s_add_u32 s50, s50, 0x80000
	s_addc_u32 s51, s51, 0
	s_mov_b32 m0, s31
	v_lshl_add_u64 v[232:233], s[50:51], 0, v[154:155]
	ds_read_b128 v[182:185], v198 offset:32768
	ds_read_b128 v[186:189], v198 offset:33792
	ds_read_b128 v[202:205], v198 offset:34816
	ds_read_b128 v[206:209], v198 offset:35840
	ds_read_b128 v[210:213], v198 offset:36864
	ds_read_b128 v[214:217], v198 offset:37888
	ds_read_b128 v[218:221], v198 offset:38912
	ds_read_b128 v[222:225], v198 offset:39936
	global_load_lds_dwordx4 v[232:233], off
	v_lshl_add_u64 v[232:233], s[50:51], 0, v[158:159]
	s_mov_b32 m0, s33
	s_nop 0
	global_load_lds_dwordx4 v[232:233], off
	s_waitcnt vmcnt(8)
	s_waitcnt lgkmcnt(0)
	s_barrier
	s_setprio 1
	s_waitcnt lgkmcnt(0)
	v_mfma_f32_16x16x32_bf16 v[134:137], v[58:61], v[182:185], v[134:137]
	v_mfma_f32_16x16x32_bf16 v[130:133], v[138:141], v[182:185], v[130:133]
	v_mfma_f32_16x16x32_bf16 v[118:121], v[58:61], v[202:205], v[118:121]
	v_mfma_f32_16x16x32_bf16 v[114:117], v[138:141], v[202:205], v[114:117]
	v_mfma_f32_16x16x32_bf16 v[102:105], v[58:61], v[210:213], v[102:105]
	v_mfma_f32_16x16x32_bf16 v[98:101], v[138:141], v[210:213], v[98:101]
	v_mfma_f32_16x16x32_bf16 v[86:89], v[58:61], v[218:221], v[86:89]
	v_mfma_f32_16x16x32_bf16 v[82:85], v[138:141], v[218:221], v[82:85]
	v_mfma_f32_16x16x32_bf16 v[134:137], v[62:65], v[186:189], v[134:137]
	v_mfma_f32_16x16x32_bf16 v[130:133], v[142:145], v[186:189], v[130:133]
	v_mfma_f32_16x16x32_bf16 v[118:121], v[62:65], v[206:209], v[118:121]
	v_mfma_f32_16x16x32_bf16 v[114:117], v[142:145], v[206:209], v[114:117]
	v_mfma_f32_16x16x32_bf16 v[102:105], v[62:65], v[214:217], v[102:105]
	v_mfma_f32_16x16x32_bf16 v[98:101], v[142:145], v[214:217], v[98:101]
	v_mfma_f32_16x16x32_bf16 v[86:89], v[62:65], v[222:225], v[86:89]
	v_mfma_f32_16x16x32_bf16 v[82:85], v[142:145], v[222:225], v[82:85]
	v_mfma_f32_16x16x32_bf16 v[126:129], v[146:149], v[182:185], v[126:129]
	v_mfma_f32_16x16x32_bf16 v[122:125], v[174:177], v[182:185], v[122:125]
	v_mfma_f32_16x16x32_bf16 v[110:113], v[146:149], v[202:205], v[110:113]
	v_mfma_f32_16x16x32_bf16 v[106:109], v[174:177], v[202:205], v[106:109]
	v_mfma_f32_16x16x32_bf16 v[94:97], v[146:149], v[210:213], v[94:97]
	v_mfma_f32_16x16x32_bf16 v[90:93], v[174:177], v[210:213], v[90:93]
	v_mfma_f32_16x16x32_bf16 v[78:81], v[146:149], v[218:221], v[78:81]
	v_mfma_f32_16x16x32_bf16 v[74:77], v[174:177], v[218:221], v[74:77]
	v_mfma_f32_16x16x32_bf16 v[126:129], v[150:153], v[186:189], v[126:129]
	v_mfma_f32_16x16x32_bf16 v[122:125], v[178:181], v[186:189], v[122:125]
	v_mfma_f32_16x16x32_bf16 v[110:113], v[150:153], v[206:209], v[110:113]
	v_mfma_f32_16x16x32_bf16 v[106:109], v[178:181], v[206:209], v[106:109]
	v_mfma_f32_16x16x32_bf16 v[94:97], v[150:153], v[214:217], v[94:97]
	v_mfma_f32_16x16x32_bf16 v[90:93], v[178:181], v[214:217], v[90:93]
	v_mfma_f32_16x16x32_bf16 v[78:81], v[150:153], v[222:225], v[78:81]
	v_mfma_f32_16x16x32_bf16 v[74:77], v[178:181], v[222:225], v[74:77]
	s_setprio 0
	s_barrier
; #define PG8_STAGE(bufoff, gbase, voff) do { _Pragma("unroll") for (int _i = 0; _i < 2; ++_i) \
;         __builtin_amdgcn_global_load_lds((const unsigned*)((const char*)(gbase) + (voff)[_i]), (LAS unsigned*)(lds + (bufoff) + ldsw + _i * 8192), 16, 0, 0); } while (0)
; #define PG8_LDA(dst, b, h) do { _Pragma("unroll") for (int m = 0; m < 4; ++m) _Pragma("unroll") for (int k = 0; k < 2; ++k) dst[m][k] = *(const LAS bf16x8*)(lds + PG8_SA(b, h) + aoff + m * 2048 + k * 1024); } while (0)
; #define PG8_LDB(dst, b, h) do { _Pragma("unroll") for (int n = 0; n < 2; ++n) _Pragma("unroll") for (int k = 0; k < 2; ++k) dst[n][k] = *(const LAS bf16x8*)(lds + PG8_SB(b, h) + boff + n * 2048 + k * 1024); } while (0)
; #define PG8_MMA(ai, bj, At, Bt) do { __builtin_amdgcn_s_setprio(1); _Pragma("unroll") for (int m = 0; m < 4; ++m) _Pragma("unroll") for (int n = 0; n < 2; ++n) _Pragma("unroll") for (int k = 0; k < 2; ++k) \
;         acc[ai][bj][m][n] = __builtin_amdgcn_mfma_f32_16x16x32_bf16(Bt[n][k], At[m][k], acc[ai][bj][m][n], 0, 0, 0); __builtin_amdgcn_s_setprio(0); } while (0)
; #define PG8_BAR __builtin_amdgcn_s_barrier()
; template <class Epi, class Sched, bool ALIGN_EPI = false, bool SP2 = false>
; __device__ __forceinline__ void gemm_phase(LAS unsigned char* lds, const Gemm g, const Sched& S, const Epi& E) {
;     ...
;             if constexpr (SP2) {
;             PG8_LDB(B0, 0, 0); PG8_LDB(B1, 0, 1); PG8_SCHED; PG8_LDA(At, 0, 0); PG8_STAGE(PG8_SA(1, 1), a1 + hstep, voffA);
;             PG8_WAIT_V(8); PG8_WAIT_L(0); PG8_BAR; PG8_MMA(0, 0, At, B0); PG8_MMA(0, 1, At, B1); PG8_BAR; PG8_SCHED;
;             PG8_LDA(At, 0, 1); PG8_STAGE(PG8_SB(0, 0), b2, voffB); PG8_STAGE(PG8_SB(0, 1), b2 + hstepB, voffB); PG8_STAGE(PG8_SA(0, 0), a2, voffA);
;             PG8_WAIT_V(8); PG8_WAIT_L(0); PG8_BAR; PG8_MMA(1, 0, At, B0); PG8_MMA(1, 1, At, B1); PG8_BAR; PG8_SCHED;
;             PG8_LDB(B0, 1, 0); PG8_LDB(B1, 1, 1); PG8_SCHED; PG8_LDA(At, 1, 0); PG8_STAGE(PG8_SA(0, 1), a2 + hstep, voffA);
;             PG8_WAIT_V(8); PG8_WAIT_L(0); PG8_BAR; PG8_MMA(0, 0, At, B0); PG8_MMA(0, 1, At, B1); PG8_BAR; PG8_SCHED;
;             PG8_LDA(At, 1, 1); PG8_STAGE(PG8_SB(1, 0), b3, voffB); PG8_STAGE(PG8_SB(1, 1), b3 + hstepB, voffB); PG8_STAGE(PG8_SA(1, 0), a3, voffA);
;             PG8_WAIT_V(8); PG8_WAIT_L(0); PG8_BAR; PG8_MMA(1, 0, At, B0); PG8_MMA(1, 1, At, B1); PG8_BAR; PG8_SCHED;
	s_add_i32 s50, s58, s28
	v_lshl_add_u64 v[190:191], v[190:191], 0, s[10:11]
	s_mov_b32 m0, s50
	ds_read_b128 v[182:185], v198 offset:49152
	ds_read_b128 v[186:189], v198 offset:50176
	ds_read_b128 v[202:205], v198 offset:51200
	ds_read_b128 v[206:209], v198 offset:52224
	ds_read_b128 v[210:213], v198 offset:53248
	ds_read_b128 v[214:217], v198 offset:54272
	ds_read_b128 v[218:221], v198 offset:55296
	ds_read_b128 v[222:225], v198 offset:56320
	global_load_lds_dwordx4 v[190:191], off
	s_add_i32 m0, s50, 0x2000
	s_add_u32 s48, s48, 0x20080
	v_lshl_add_u64 v[190:191], v[226:227], 0, s[10:11]
	s_addc_u32 s49, s49, 0
	s_add_i32 s50, s59, s28
	global_load_lds_dwordx4 v[190:191], off
	v_lshl_add_u64 v[190:191], s[48:49], 0, v[156:157]
	s_mov_b32 m0, s50
	s_nop 0
	global_load_lds_dwordx4 v[190:191], off
	v_lshl_add_u64 v[190:191], s[48:49], 0, v[160:161]
	s_add_i32 m0, s50, 0x2000
	s_nop 0
	global_load_lds_dwordx4 v[190:191], off
	v_lshl_add_u64 v[190:191], v[228:229], 0, s[10:11]
	s_mov_b32 m0, s53
	s_nop 0
	global_load_lds_dwordx4 v[190:191], off
	v_lshl_add_u64 v[190:191], v[230:231], 0, s[10:11]
	s_mov_b32 m0, s54
	s_nop 0
	global_load_lds_dwordx4 v[190:191], off
	s_waitcnt vmcnt(8)
	s_waitcnt lgkmcnt(0)
	s_barrier
	s_setprio 1
	s_waitcnt lgkmcnt(0)
	v_mfma_f32_16x16x32_bf16 v[70:73], v[58:61], v[182:185], v[70:73]
	v_mfma_f32_16x16x32_bf16 v[66:69], v[138:141], v[182:185], v[66:69]
	v_mfma_f32_16x16x32_bf16 v[46:49], v[58:61], v[202:205], v[46:49]
	v_mfma_f32_16x16x32_bf16 v[42:45], v[138:141], v[202:205], v[42:45]
	v_mfma_f32_16x16x32_bf16 v[30:33], v[58:61], v[210:213], v[30:33]
	v_mfma_f32_16x16x32_bf16 v[26:29], v[138:141], v[210:213], v[26:29]
	v_mfma_f32_16x16x32_bf16 v[14:17], v[58:61], v[218:221], v[14:17]
	v_mfma_f32_16x16x32_bf16 v[10:13], v[138:141], v[218:221], v[10:13]
	v_mfma_f32_16x16x32_bf16 v[70:73], v[62:65], v[186:189], v[70:73]
	v_mfma_f32_16x16x32_bf16 v[66:69], v[142:145], v[186:189], v[66:69]
	v_mfma_f32_16x16x32_bf16 v[46:49], v[62:65], v[206:209], v[46:49]
	v_mfma_f32_16x16x32_bf16 v[42:45], v[142:145], v[206:209], v[42:45]
	v_mfma_f32_16x16x32_bf16 v[30:33], v[62:65], v[214:217], v[30:33]
	v_mfma_f32_16x16x32_bf16 v[26:29], v[142:145], v[214:217], v[26:29]
	v_mfma_f32_16x16x32_bf16 v[14:17], v[62:65], v[222:225], v[14:17]
	v_mfma_f32_16x16x32_bf16 v[10:13], v[142:145], v[222:225], v[10:13]
	v_mfma_f32_16x16x32_bf16 v[50:53], v[146:149], v[182:185], v[50:53]
	v_mfma_f32_16x16x32_bf16 v[62:65], v[150:153], v[186:189], v[50:53]
	v_mfma_f32_16x16x32_bf16 v[50:53], v[174:177], v[182:185], v[54:57]
	v_mfma_f32_16x16x32_bf16 v[38:41], v[146:149], v[202:205], v[38:41]
	v_mfma_f32_16x16x32_bf16 v[34:37], v[174:177], v[202:205], v[34:37]
	v_mfma_f32_16x16x32_bf16 v[22:25], v[146:149], v[210:213], v[22:25]
	v_mfma_f32_16x16x32_bf16 v[18:21], v[174:177], v[210:213], v[18:21]
	v_mfma_f32_16x16x32_bf16 v[6:9], v[146:149], v[218:221], v[6:9]
	v_mfma_f32_16x16x32_bf16 v[2:5], v[174:177], v[218:221], v[2:5]
	v_mfma_f32_16x16x32_bf16 v[58:61], v[178:181], v[186:189], v[50:53]
	v_mfma_f32_16x16x32_bf16 v[38:41], v[150:153], v[206:209], v[38:41]
	v_mfma_f32_16x16x32_bf16 v[34:37], v[178:181], v[206:209], v[34:37]
	v_mfma_f32_16x16x32_bf16 v[22:25], v[150:153], v[214:217], v[22:25]
	v_mfma_f32_16x16x32_bf16 v[18:21], v[178:181], v[214:217], v[18:21]
	v_mfma_f32_16x16x32_bf16 v[6:9], v[150:153], v[222:225], v[6:9]
	v_mfma_f32_16x16x32_bf16 v[2:5], v[178:181], v[222:225], v[2:5]
	s_setprio 0
	s_barrier
	s_add_i32 s47, s47, 2
	s_add_u32 s16, s16, 0x100
	s_addc_u32 s17, s17, 0
	s_add_u32 s24, s24, 0x100
	s_addc_u32 s25, s25, 0
	s_cmp_gt_u32 s47, 29
.LBB0_1250:
	ds_read_b128 v[50:53], v196
	ds_read_b128 v[54:57], v196 offset:1024
	ds_read_b128 v[138:141], v196 offset:2048
	ds_read_b128 v[142:145], v196 offset:3072
	ds_read_b128 v[146:149], v197
	ds_read_b128 v[150:153], v197 offset:1024
	ds_read_b128 v[174:177], v197 offset:2048
	ds_read_b128 v[178:181], v197 offset:3072
	s_add_u32 s48, s16, 0xfff80080
	s_addc_u32 s49, s17, -1
	s_cmp_eq_u32 s47, 28
	s_cselect_b32 s51, s0, s49
	s_cselect_b32 s50, s3, s48
	s_cselect_b32 s49, s15, s25
	s_cselect_b32 s48, s19, s24
	v_lshl_add_u64 v[190:191], s[16:17], 0, v[166:167]
	s_add_i32 m0, s29, 0xc000
	ds_read_b128 v[182:185], v198
	ds_read_b128 v[186:189], v198 offset:1024
	ds_read_b128 v[202:205], v198 offset:2048
	ds_read_b128 v[206:209], v198 offset:3072
	ds_read_b128 v[210:213], v198 offset:4096
	ds_read_b128 v[214:217], v198 offset:5120
	ds_read_b128 v[218:221], v198 offset:6144
	ds_read_b128 v[222:225], v198 offset:7168
	global_load_lds_dwordx4 v[190:191], off
	v_lshl_add_u64 v[190:191], s[16:17], 0, v[168:169]
	s_add_i32 m0, s29, 0xe000
	s_nop 0
	global_load_lds_dwordx4 v[190:191], off
	s_waitcnt vmcnt(8)
	s_waitcnt lgkmcnt(0)
	s_barrier
; #define PG8_STAGE(bufoff, gbase, voff) do { _Pragma("unroll") for (int _i = 0; _i < 2; ++_i) \
;         __builtin_amdgcn_global_load_lds((const unsigned*)((const char*)(gbase) + (voff)[_i]), (LAS unsigned*)(lds + (bufoff) + ldsw + _i * 8192), 16, 0, 0); } while (0)
; #define PG8_LDA(dst, b, h) do { _Pragma("unroll") for (int m = 0; m < 4; ++m) _Pragma("unroll") for (int k = 0; k < 2; ++k) dst[m][k] = *(const LAS bf16x8*)(lds + PG8_SA(b, h) + aoff + m * 2048 + k * 1024); } while (0)
; #define PG8_LDB(dst, b, h) do { _Pragma("unroll") for (int n = 0; n < 2; ++n) _Pragma("unroll") for (int k = 0; k < 2; ++k) dst[n][k] = *(const LAS bf16x8*)(lds + PG8_SB(b, h) + boff + n * 2048 + k * 1024); } while (0)
; #define PG8_MMA(ai, bj, At, Bt) do { __builtin_amdgcn_s_setprio(1); _Pragma("unroll") for (int m = 0; m < 4; ++m) _Pragma("unroll") for (int n = 0; n < 2; ++n) _Pragma("unroll") for (int k = 0; k < 2; ++k) \
;         acc[ai][bj][m][n] = __builtin_amdgcn_mfma_f32_16x16x32_bf16(Bt[n][k], At[m][k], acc[ai][bj][m][n], 0, 0, 0); __builtin_amdgcn_s_setprio(0); } while (0)
; #define PG8_BAR __builtin_amdgcn_s_barrier()
; template <class Epi, class Sched, bool ALIGN_EPI = false, bool SP2 = false>
; __device__ __forceinline__ void gemm_phase(LAS unsigned char* lds, const Gemm g, const Sched& S, const Epi& E) {
;     ...
;             if constexpr (SP2) {
;             PG8_LDB(B0, 0, 0); PG8_LDB(B1, 0, 1); PG8_SCHED; PG8_LDA(At, 0, 0); PG8_STAGE(PG8_SA(1, 1), a1 + hstep, voffA);
;             PG8_WAIT_V(8); PG8_WAIT_L(0); PG8_BAR; PG8_MMA(0, 0, At, B0); PG8_MMA(0, 1, At, B1); PG8_BAR; PG8_SCHED;
;             PG8_LDA(At, 0, 1); PG8_STAGE(PG8_SB(0, 0), b2, voffB); PG8_STAGE(PG8_SB(0, 1), b2 + hstepB, voffB); PG8_STAGE(PG8_SA(0, 0), a2, voffA);
;             PG8_WAIT_V(8); PG8_WAIT_L(0); PG8_BAR; PG8_MMA(1, 0, At, B0); PG8_MMA(1, 1, At, B1); PG8_BAR; PG8_SCHED;
;             PG8_LDB(B0, 1, 0); PG8_LDB(B1, 1, 1); PG8_SCHED; PG8_LDA(At, 1, 0); PG8_STAGE(PG8_SA(0, 1), a2 + hstep, voffA);
;             PG8_WAIT_V(8); PG8_WAIT_L(0); PG8_BAR; PG8_MMA(0, 0, At, B0); PG8_MMA(0, 1, At, B1); PG8_BAR; PG8_SCHED;
;             PG8_LDA(At, 1, 1); PG8_STAGE(PG8_SB(1, 0), b3, voffB); PG8_STAGE(PG8_SB(1, 1), b3 + hstepB, voffB); PG8_STAGE(PG8_SA(1, 0), a3, voffA);
;             PG8_WAIT_V(8); PG8_WAIT_L(0); PG8_BAR; PG8_MMA(1, 0, At, B0); PG8_MMA(1, 1, At, B1); PG8_BAR; PG8_SCHED;
	s_setprio 1
	s_waitcnt lgkmcnt(0)
	v_mfma_f32_16x16x32_bf16 v[134:137], v[50:53], v[182:185], v[134:137]
	v_mfma_f32_16x16x32_bf16 v[130:133], v[138:141], v[182:185], v[130:133]
	v_mfma_f32_16x16x32_bf16 v[118:121], v[50:53], v[202:205], v[118:121]
	v_mfma_f32_16x16x32_bf16 v[114:117], v[138:141], v[202:205], v[114:117]
	v_mfma_f32_16x16x32_bf16 v[102:105], v[50:53], v[210:213], v[102:105]
	v_mfma_f32_16x16x32_bf16 v[98:101], v[138:141], v[210:213], v[98:101]
	v_mfma_f32_16x16x32_bf16 v[86:89], v[50:53], v[218:221], v[86:89]
	v_mfma_f32_16x16x32_bf16 v[82:85], v[138:141], v[218:221], v[82:85]
	v_mfma_f32_16x16x32_bf16 v[134:137], v[54:57], v[186:189], v[134:137]
	v_mfma_f32_16x16x32_bf16 v[130:133], v[142:145], v[186:189], v[130:133]
	v_mfma_f32_16x16x32_bf16 v[118:121], v[54:57], v[206:209], v[118:121]
	v_mfma_f32_16x16x32_bf16 v[114:117], v[142:145], v[206:209], v[114:117]
	v_mfma_f32_16x16x32_bf16 v[102:105], v[54:57], v[214:217], v[102:105]
	v_mfma_f32_16x16x32_bf16 v[98:101], v[142:145], v[214:217], v[98:101]
	v_mfma_f32_16x16x32_bf16 v[86:89], v[54:57], v[222:225], v[86:89]
	v_mfma_f32_16x16x32_bf16 v[82:85], v[142:145], v[222:225], v[82:85]
	v_mfma_f32_16x16x32_bf16 v[126:129], v[146:149], v[182:185], v[126:129]
	v_mfma_f32_16x16x32_bf16 v[122:125], v[174:177], v[182:185], v[122:125]
	v_mfma_f32_16x16x32_bf16 v[110:113], v[146:149], v[202:205], v[110:113]
	v_mfma_f32_16x16x32_bf16 v[106:109], v[174:177], v[202:205], v[106:109]
	v_mfma_f32_16x16x32_bf16 v[94:97], v[146:149], v[210:213], v[94:97]
	v_mfma_f32_16x16x32_bf16 v[90:93], v[174:177], v[210:213], v[90:93]
	v_mfma_f32_16x16x32_bf16 v[78:81], v[146:149], v[218:221], v[78:81]
	v_mfma_f32_16x16x32_bf16 v[74:77], v[174:177], v[218:221], v[74:77]
	v_mfma_f32_16x16x32_bf16 v[126:129], v[150:153], v[186:189], v[126:129]
	v_mfma_f32_16x16x32_bf16 v[122:125], v[178:181], v[186:189], v[122:125]
	v_mfma_f32_16x16x32_bf16 v[110:113], v[150:153], v[206:209], v[110:113]
	v_mfma_f32_16x16x32_bf16 v[106:109], v[178:181], v[206:209], v[106:109]
	v_mfma_f32_16x16x32_bf16 v[94:97], v[150:153], v[214:217], v[94:97]
	v_mfma_f32_16x16x32_bf16 v[90:93], v[178:181], v[214:217], v[90:93]
	v_mfma_f32_16x16x32_bf16 v[78:81], v[150:153], v[222:225], v[78:81]
	v_mfma_f32_16x16x32_bf16 v[74:77], v[178:181], v[222:225], v[74:77]
	s_setprio 0
	s_barrier
	s_add_i32 s58, s56, s28
	v_lshl_add_u64 v[190:191], s[48:49], 0, v[156:157]
	s_mov_b32 m0, s58
	ds_read_b128 v[182:185], v198 offset:16384
	ds_read_b128 v[186:189], v198 offset:17408
	ds_read_b128 v[202:205], v198 offset:18432
	ds_read_b128 v[206:209], v198 offset:19456
	ds_read_b128 v[210:213], v198 offset:20480
	ds_read_b128 v[214:217], v198 offset:21504
	ds_read_b128 v[218:221], v198 offset:22528
	ds_read_b128 v[222:225], v198 offset:23552
	global_load_lds_dwordx4 v[190:191], off
	s_add_i32 m0, s58, 0x2000
	s_add_u32 s58, s48, 0x20000
	v_lshl_add_u64 v[226:227], s[48:49], 0, v[160:161]
	s_addc_u32 s59, s49, 0
	s_add_i32 s60, s57, s28
	global_load_lds_dwordx4 v[226:227], off
	v_lshl_add_u64 v[228:229], s[58:59], 0, v[156:157]
	s_mov_b32 m0, s60
	v_lshl_add_u64 v[230:231], s[50:51], 0, v[158:159]
	global_load_lds_dwordx4 v[228:229], off
	v_lshl_add_u64 v[228:229], s[58:59], 0, v[160:161]
	s_add_i32 m0, s60, 0x2000
	s_nop 0
	global_load_lds_dwordx4 v[228:229], off
	v_lshl_add_u64 v[228:229], s[50:51], 0, v[154:155]
	s_mov_b32 m0, s29
	s_nop 0
	global_load_lds_dwordx4 v[228:229], off
	s_mov_b32 m0, s30
	s_nop 0
	global_load_lds_dwordx4 v[230:231], off
	s_waitcnt vmcnt(8)
	s_waitcnt lgkmcnt(0)
	s_barrier
	s_setprio 1
	s_waitcnt lgkmcnt(0)
	v_mfma_f32_16x16x32_bf16 v[70:73], v[50:53], v[182:185], v[70:73]
	v_mfma_f32_16x16x32_bf16 v[66:69], v[138:141], v[182:185], v[66:69]
	v_mfma_f32_16x16x32_bf16 v[46:49], v[50:53], v[202:205], v[46:49]
	v_mfma_f32_16x16x32_bf16 v[42:45], v[138:141], v[202:205], v[42:45]
	v_mfma_f32_16x16x32_bf16 v[30:33], v[50:53], v[210:213], v[30:33]
	v_mfma_f32_16x16x32_bf16 v[26:29], v[138:141], v[210:213], v[26:29]
	v_mfma_f32_16x16x32_bf16 v[14:17], v[50:53], v[218:221], v[14:17]
	v_mfma_f32_16x16x32_bf16 v[10:13], v[138:141], v[218:221], v[10:13]
	v_mfma_f32_16x16x32_bf16 v[70:73], v[54:57], v[186:189], v[70:73]
	v_mfma_f32_16x16x32_bf16 v[66:69], v[142:145], v[186:189], v[66:69]
	v_mfma_f32_16x16x32_bf16 v[46:49], v[54:57], v[206:209], v[46:49]
	v_mfma_f32_16x16x32_bf16 v[42:45], v[142:145], v[206:209], v[42:45]
	v_mfma_f32_16x16x32_bf16 v[30:33], v[54:57], v[214:217], v[30:33]
	v_mfma_f32_16x16x32_bf16 v[26:29], v[142:145], v[214:217], v[26:29]
	v_mfma_f32_16x16x32_bf16 v[14:17], v[54:57], v[222:225], v[14:17]
	v_mfma_f32_16x16x32_bf16 v[10:13], v[142:145], v[222:225], v[10:13]
	v_mfma_f32_16x16x32_bf16 v[38:41], v[146:149], v[202:205], v[38:41]
	v_mfma_f32_16x16x32_bf16 v[34:37], v[174:177], v[202:205], v[34:37]
	v_mfma_f32_16x16x32_bf16 v[22:25], v[146:149], v[210:213], v[22:25]
	v_mfma_f32_16x16x32_bf16 v[18:21], v[174:177], v[210:213], v[18:21]
	v_mfma_f32_16x16x32_bf16 v[6:9], v[146:149], v[218:221], v[6:9]
	v_mfma_f32_16x16x32_bf16 v[2:5], v[174:177], v[218:221], v[2:5]
	v_mfma_f32_16x16x32_bf16 v[50:53], v[146:149], v[182:185], v[62:65]
	v_mfma_f32_16x16x32_bf16 v[54:57], v[174:177], v[182:185], v[58:61]
	v_mfma_f32_16x16x32_bf16 v[38:41], v[150:153], v[206:209], v[38:41]
	v_mfma_f32_16x16x32_bf16 v[34:37], v[178:181], v[206:209], v[34:37]
	v_mfma_f32_16x16x32_bf16 v[22:25], v[150:153], v[214:217], v[22:25]
	v_mfma_f32_16x16x32_bf16 v[18:21], v[178:181], v[214:217], v[18:21]
	v_mfma_f32_16x16x32_bf16 v[6:9], v[150:153], v[222:225], v[6:9]
	v_mfma_f32_16x16x32_bf16 v[2:5], v[178:181], v[222:225], v[2:5]
	v_mfma_f32_16x16x32_bf16 v[50:53], v[150:153], v[186:189], v[50:53]
	v_mfma_f32_16x16x32_bf16 v[54:57], v[178:181], v[186:189], v[54:57]
	s_setprio 0
	s_barrier
; #define PG8_STAGE(bufoff, gbase, voff) do { _Pragma("unroll") for (int _i = 0; _i < 2; ++_i) \
;         __builtin_amdgcn_global_load_lds((const unsigned*)((const char*)(gbase) + (voff)[_i]), (LAS unsigned*)(lds + (bufoff) + ldsw + _i * 8192), 16, 0, 0); } while (0)
; #define PG8_LDA(dst, b, h) do { _Pragma("unroll") for (int m = 0; m < 4; ++m) _Pragma("unroll") for (int k = 0; k < 2; ++k) dst[m][k] = *(const LAS bf16x8*)(lds + PG8_SA(b, h) + aoff + m * 2048 + k * 1024); } while (0)
; #define PG8_LDB(dst, b, h) do { _Pragma("unroll") for (int n = 0; n < 2; ++n) _Pragma("unroll") for (int k = 0; k < 2; ++k) dst[n][k] = *(const LAS bf16x8*)(lds + PG8_SB(b, h) + boff + n * 2048 + k * 1024); } while (0)
; #define PG8_MMA(ai, bj, At, Bt) do { __builtin_amdgcn_s_setprio(1); _Pragma("unroll") for (int m = 0; m < 4; ++m) _Pragma("unroll") for (int n = 0; n < 2; ++n) _Pragma("unroll") for (int k = 0; k < 2; ++k) \
;         acc[ai][bj][m][n] = __builtin_amdgcn_mfma_f32_16x16x32_bf16(Bt[n][k], At[m][k], acc[ai][bj][m][n], 0, 0, 0); __builtin_amdgcn_s_setprio(0); } while (0)
; #define PG8_WAIT_V(n) asm volatile("s_waitcnt vmcnt(" #n ")" ::: "memory")
; #define PG8_WAIT_L(n) asm volatile("s_waitcnt lgkmcnt(" #n ")" ::: "memory")
; #define PG8_BAR __builtin_amdgcn_s_barrier()
; #define PG8_SCHED __builtin_amdgcn_sched_barrier(0)
; template <class Epi, class Sched, bool ALIGN_EPI = false, bool SP2 = false>
; __device__ __forceinline__ void gemm_phase(LAS unsigned char* lds, const Gemm g, const Sched& S, const Epi& E) {
;     ...
;             PG8_LDB(B0, 1, 0); PG8_LDB(B1, 1, 1); PG8_SCHED; PG8_LDA(At, 1, 0); PG8_STAGE(PG8_SA(0, 1), a2 + hstep, voffA);
;             PG8_WAIT_V(8); PG8_WAIT_L(0); PG8_BAR; PG8_MMA(0, 0, At, B0); PG8_MMA(0, 1, At, B1); PG8_BAR; PG8_SCHED;
	s_add_i32 s58, 0, 0x18000
	s_add_i32 s59, 0, 0x1c000
	v_add_u32_e32 v142, s58, v1
	v_add_u32_e32 v162, s59, v1
	ds_read_b128 v[58:61], v142
	ds_read_b128 v[62:65], v142 offset:1024
	ds_read_b128 v[138:141], v142 offset:2048
	ds_read_b128 v[142:145], v142 offset:3072
	ds_read_b128 v[146:149], v162
	ds_read_b128 v[150:153], v162 offset:1024
	ds_read_b128 v[174:177], v162 offset:2048
	ds_read_b128 v[178:181], v162 offset:3072
	s_add_u32 s50, s50, 0x80000
	s_addc_u32 s51, s51, 0
	s_mov_b32 m0, s31
	v_lshl_add_u64 v[232:233], s[50:51], 0, v[154:155]
	ds_read_b128 v[182:185], v198 offset:32768
	ds_read_b128 v[186:189], v198 offset:33792
	ds_read_b128 v[202:205], v198 offset:34816
	ds_read_b128 v[206:209], v198 offset:35840
	ds_read_b128 v[210:213], v198 offset:36864
	ds_read_b128 v[214:217], v198 offset:37888
	ds_read_b128 v[218:221], v198 offset:38912
	ds_read_b128 v[222:225], v198 offset:39936
	global_load_lds_dwordx4 v[232:233], off
	v_lshl_add_u64 v[232:233], s[50:51], 0, v[158:159]
	s_mov_b32 m0, s33
	s_nop 0
	global_load_lds_dwordx4 v[232:233], off
	s_waitcnt vmcnt(8)
	s_waitcnt lgkmcnt(0)
	s_barrier
	s_setprio 1
	s_waitcnt lgkmcnt(0)
	v_mfma_f32_16x16x32_bf16 v[134:137], v[58:61], v[182:185], v[134:137]
	v_mfma_f32_16x16x32_bf16 v[130:133], v[138:141], v[182:185], v[130:133]
	v_mfma_f32_16x16x32_bf16 v[118:121], v[58:61], v[202:205], v[118:121]
	v_mfma_f32_16x16x32_bf16 v[114:117], v[138:141], v[202:205], v[114:117]
	v_mfma_f32_16x16x32_bf16 v[102:105], v[58:61], v[210:213], v[102:105]
	v_mfma_f32_16x16x32_bf16 v[98:101], v[138:141], v[210:213], v[98:101]
	v_mfma_f32_16x16x32_bf16 v[86:89], v[58:61], v[218:221], v[86:89]
	v_mfma_f32_16x16x32_bf16 v[82:85], v[138:141], v[218:221], v[82:85]
	v_mfma_f32_16x16x32_bf16 v[134:137], v[62:65], v[186:189], v[134:137]
	v_mfma_f32_16x16x32_bf16 v[130:133], v[142:145], v[186:189], v[130:133]
	v_mfma_f32_16x16x32_bf16 v[118:121], v[62:65], v[206:209], v[118:121]
	v_mfma_f32_16x16x32_bf16 v[114:117], v[142:145], v[206:209], v[114:117]
	v_mfma_f32_16x16x32_bf16 v[102:105], v[62:65], v[214:217], v[102:105]
	v_mfma_f32_16x16x32_bf16 v[98:101], v[142:145], v[214:217], v[98:101]
	v_mfma_f32_16x16x32_bf16 v[86:89], v[62:65], v[222:225], v[86:89]
	v_mfma_f32_16x16x32_bf16 v[82:85], v[142:145], v[222:225], v[82:85]
	v_mfma_f32_16x16x32_bf16 v[126:129], v[146:149], v[182:185], v[126:129]
	v_mfma_f32_16x16x32_bf16 v[122:125], v[174:177], v[182:185], v[122:125]
	v_mfma_f32_16x16x32_bf16 v[110:113], v[146:149], v[202:205], v[110:113]
	v_mfma_f32_16x16x32_bf16 v[106:109], v[174:177], v[202:205], v[106:109]
	v_mfma_f32_16x16x32_bf16 v[94:97], v[146:149], v[210:213], v[94:97]
	v_mfma_f32_16x16x32_bf16 v[90:93], v[174:177], v[210:213], v[90:93]
	v_mfma_f32_16x16x32_bf16 v[78:81], v[146:149], v[218:221], v[78:81]
	v_mfma_f32_16x16x32_bf16 v[74:77], v[174:177], v[218:221], v[74:77]
	v_mfma_f32_16x16x32_bf16 v[126:129], v[150:153], v[186:189], v[126:129]
	v_mfma_f32_16x16x32_bf16 v[122:125], v[178:181], v[186:189], v[122:125]
	v_mfma_f32_16x16x32_bf16 v[110:113], v[150:153], v[206:209], v[110:113]
	v_mfma_f32_16x16x32_bf16 v[106:109], v[178:181], v[206:209], v[106:109]
	v_mfma_f32_16x16x32_bf16 v[94:97], v[150:153], v[214:217], v[94:97]
	v_mfma_f32_16x16x32_bf16 v[90:93], v[178:181], v[214:217], v[90:93]
	v_mfma_f32_16x16x32_bf16 v[78:81], v[150:153], v[222:225], v[78:81]
	v_mfma_f32_16x16x32_bf16 v[74:77], v[178:181], v[222:225], v[74:77]
	s_setprio 0
	s_barrier
; #define PG8_STAGE(bufoff, gbase, voff) do { _Pragma("unroll") for (int _i = 0; _i < 2; ++_i) \
;         __builtin_amdgcn_global_load_lds((const unsigned*)((const char*)(gbase) + (voff)[_i]), (LAS unsigned*)(lds + (bufoff) + ldsw + _i * 8192), 16, 0, 0); } while (0)
; #define PG8_LDA(dst, b, h) do { _Pragma("unroll") for (int m = 0; m < 4; ++m) _Pragma("unroll") for (int k = 0; k < 2; ++k) dst[m][k] = *(const LAS bf16x8*)(lds + PG8_SA(b, h) + aoff + m * 2048 + k * 1024); } while (0)
; #define PG8_MMA(ai, bj, At, Bt) do { __builtin_amdgcn_s_setprio(1); _Pragma("unroll") for (int m = 0; m < 4; ++m) _Pragma("unroll") for (int n = 0; n < 2; ++n) _Pragma("unroll") for (int k = 0; k < 2; ++k) \
;         acc[ai][bj][m][n] = __builtin_amdgcn_mfma_f32_16x16x32_bf16(Bt[n][k], At[m][k], acc[ai][bj][m][n], 0, 0, 0); __builtin_amdgcn_s_setprio(0); } while (0)
; #define PG8_WAIT_V(n) asm volatile("s_waitcnt vmcnt(" #n ")" ::: "memory")
; #define PG8_WAIT_L(n) asm volatile("s_waitcnt lgkmcnt(" #n ")" ::: "memory")
; #define PG8_BAR __builtin_amdgcn_s_barrier()
; #define PG8_SCHED __builtin_amdgcn_sched_barrier(0)
; template <class Epi, class Sched, bool ALIGN_EPI = false, bool SP2 = false>
; __device__ __forceinline__ void gemm_phase(LAS unsigned char* lds, const Gemm g, const Sched& S, const Epi& E) {
;     ...
;         for (int t = 0; t < nt; t += 2) {
;             const bool last = (t == nt - 2);
;     ...
;             PG8_LDA(At, 1, 1); PG8_STAGE(PG8_SB(1, 0), b3, voffB); PG8_STAGE(PG8_SB(1, 1), b3 + hstepB, voffB); PG8_STAGE(PG8_SA(1, 0), a3, voffA);
;             PG8_WAIT_V(8); PG8_WAIT_L(0); PG8_BAR; PG8_MMA(1, 0, At, B0); PG8_MMA(1, 1, At, B1); PG8_BAR; PG8_SCHED;
	s_add_i32 s50, s58, s28
	v_lshl_add_u64 v[190:191], v[190:191], 0, s[10:11]
	s_mov_b32 m0, s50
	ds_read_b128 v[182:185], v198 offset:49152
	ds_read_b128 v[186:189], v198 offset:50176
	ds_read_b128 v[202:205], v198 offset:51200
	ds_read_b128 v[206:209], v198 offset:52224
	ds_read_b128 v[210:213], v198 offset:53248
	ds_read_b128 v[214:217], v198 offset:54272
	ds_read_b128 v[218:221], v198 offset:55296
	ds_read_b128 v[222:225], v198 offset:56320
	global_load_lds_dwordx4 v[190:191], off
	s_add_i32 m0, s50, 0x2000
	s_add_u32 s48, s48, 0x20080
	v_lshl_add_u64 v[190:191], v[226:227], 0, s[10:11]
	s_addc_u32 s49, s49, 0
	s_add_i32 s50, s59, s28
	global_load_lds_dwordx4 v[190:191], off
	v_lshl_add_u64 v[190:191], s[48:49], 0, v[156:157]
	s_mov_b32 m0, s50
	s_nop 0
	global_load_lds_dwordx4 v[190:191], off
	v_lshl_add_u64 v[190:191], s[48:49], 0, v[160:161]
	s_add_i32 m0, s50, 0x2000
	s_nop 0
	global_load_lds_dwordx4 v[190:191], off
	v_lshl_add_u64 v[190:191], v[228:229], 0, s[10:11]
	s_mov_b32 m0, s53
	s_nop 0
	global_load_lds_dwordx4 v[190:191], off
	v_lshl_add_u64 v[190:191], v[230:231], 0, s[10:11]
	s_mov_b32 m0, s54
	s_nop 0
	global_load_lds_dwordx4 v[190:191], off
	s_waitcnt vmcnt(8)
	s_waitcnt lgkmcnt(0)
	s_barrier
	s_setprio 1
	s_waitcnt lgkmcnt(0)
	v_mfma_f32_16x16x32_bf16 v[70:73], v[58:61], v[182:185], v[70:73]
	v_mfma_f32_16x16x32_bf16 v[66:69], v[138:141], v[182:185], v[66:69]
	v_mfma_f32_16x16x32_bf16 v[46:49], v[58:61], v[202:205], v[46:49]
	v_mfma_f32_16x16x32_bf16 v[42:45], v[138:141], v[202:205], v[42:45]
	v_mfma_f32_16x16x32_bf16 v[30:33], v[58:61], v[210:213], v[30:33]
	v_mfma_f32_16x16x32_bf16 v[26:29], v[138:141], v[210:213], v[26:29]
	v_mfma_f32_16x16x32_bf16 v[14:17], v[58:61], v[218:221], v[14:17]
	v_mfma_f32_16x16x32_bf16 v[10:13], v[138:141], v[218:221], v[10:13]
	v_mfma_f32_16x16x32_bf16 v[70:73], v[62:65], v[186:189], v[70:73]
	v_mfma_f32_16x16x32_bf16 v[66:69], v[142:145], v[186:189], v[66:69]
	v_mfma_f32_16x16x32_bf16 v[46:49], v[62:65], v[206:209], v[46:49]
	v_mfma_f32_16x16x32_bf16 v[42:45], v[142:145], v[206:209], v[42:45]
	v_mfma_f32_16x16x32_bf16 v[30:33], v[62:65], v[214:217], v[30:33]
	v_mfma_f32_16x16x32_bf16 v[26:29], v[142:145], v[214:217], v[26:29]
	v_mfma_f32_16x16x32_bf16 v[14:17], v[62:65], v[222:225], v[14:17]
	v_mfma_f32_16x16x32_bf16 v[10:13], v[142:145], v[222:225], v[10:13]
	v_mfma_f32_16x16x32_bf16 v[50:53], v[146:149], v[182:185], v[50:53]
	v_mfma_f32_16x16x32_bf16 v[62:65], v[150:153], v[186:189], v[50:53]
	v_mfma_f32_16x16x32_bf16 v[50:53], v[174:177], v[182:185], v[54:57]
	v_mfma_f32_16x16x32_bf16 v[38:41], v[146:149], v[202:205], v[38:41]
	v_mfma_f32_16x16x32_bf16 v[34:37], v[174:177], v[202:205], v[34:37]
	v_mfma_f32_16x16x32_bf16 v[22:25], v[146:149], v[210:213], v[22:25]
	v_mfma_f32_16x16x32_bf16 v[18:21], v[174:177], v[210:213], v[18:21]
	v_mfma_f32_16x16x32_bf16 v[6:9], v[146:149], v[218:221], v[6:9]
	v_mfma_f32_16x16x32_bf16 v[2:5], v[174:177], v[218:221], v[2:5]
	v_mfma_f32_16x16x32_bf16 v[58:61], v[178:181], v[186:189], v[50:53]
	v_mfma_f32_16x16x32_bf16 v[38:41], v[150:153], v[206:209], v[38:41]
	v_mfma_f32_16x16x32_bf16 v[34:37], v[178:181], v[206:209], v[34:37]
	v_mfma_f32_16x16x32_bf16 v[22:25], v[150:153], v[214:217], v[22:25]
	v_mfma_f32_16x16x32_bf16 v[18:21], v[178:181], v[214:217], v[18:21]
	v_mfma_f32_16x16x32_bf16 v[6:9], v[150:153], v[222:225], v[6:9]
	v_mfma_f32_16x16x32_bf16 v[2:5], v[178:181], v[222:225], v[2:5]
	s_setprio 0
	s_barrier
	s_add_i32 s47, s47, 2
	s_add_u32 s16, s16, 0x100
	s_addc_u32 s17, s17, 0
	s_add_u32 s24, s24, 0x100
	s_addc_u32 s25, s25, 0
	s_cmp_gt_u32 s47, 29
	s_cbranch_scc0 .LBB0_1250
	s_and_b64 vcc, exec, s[12:13]
	s_cbranch_vccz .LBB0_1253
	s_barrier

; __device__ __forceinline__ float row_rstd(const float* ss, int row) { return 1.0f / sqrtf(ss[row] * (1.0f / DM) + 1e-6f); }
; #define PG8_STAGE(bufoff, gbase, voff) do { _Pragma("unroll") for (int _i = 0; _i < 2; ++_i) \
;         __builtin_amdgcn_global_load_lds((const unsigned*)((const char*)(gbase) + (voff)[_i]), (LAS unsigned*)(lds + (bufoff) + ldsw + _i * 8192), 16, 0, 0); } while (0)
; #define PG8_LDA(dst, b, h) do { _Pragma("unroll") for (int m = 0; m < 4; ++m) _Pragma("unroll") for (int k = 0; k < 2; ++k) dst[m][k] = *(const LAS bf16x8*)(lds + PG8_SA(b, h) + aoff + m * 2048 + k * 1024); } while (0)
; #define PG8_LDB(dst, b, h) do { _Pragma("unroll") for (int n = 0; n < 2; ++n) _Pragma("unroll") for (int k = 0; k < 2; ++k) dst[n][k] = *(const LAS bf16x8*)(lds + PG8_SB(b, h) + boff + n * 2048 + k * 1024); } while (0)
; #define PG8_WAIT_V(n) asm volatile("s_waitcnt vmcnt(" #n ")" ::: "memory")
; #define PG8_WAIT_L(n) asm volatile("s_waitcnt lgkmcnt(" #n ")" ::: "memory")
; #define PG8_BAR __builtin_amdgcn_s_barrier()
; #define PG8_SCHED __builtin_amdgcn_sched_barrier(0)
;     __device__ __forceinline__ void operator()(const f32x4 (&acc)[2][2][4][2], const Unit& u, int wr, int wc, int fr, int fq) const {
;     ...
;         const float* bp = bias + (size_t)s * BIAS_N + u.pn * BM + wc * 32 + 8 * fq;
;         const f32x4 ba0 = *(const f32x4*)bp, ba1 = *(const f32x4*)(bp + 4), bb0 = *(const f32x4*)(bp + HALF), bb1 = *(const f32x4*)(bp + HALF + 4);
;         const int lane = fq * 16 + fr;
;         const float rsl0 = row_rstd(ss, u.pm * BM + wr * 64 + lane), rsl1 = row_rstd(ss, u.pm * BM + HALF + wr * 64 + lane);
; template <class Epi, class Sched, bool ALIGN_EPI = false, bool SP2 = false>
; __device__ __forceinline__ void gemm_phase(LAS unsigned char* lds, const Gemm g, const Sched& S, const Epi& E) {
;     ...
;             PG8_LDB(B0, 0, 0); PG8_LDB(B1, 0, 1); PG8_SCHED; PG8_LDA(At, 0, 0); PG8_STAGE(PG8_SA(1, 1), a1 + hstep, voffA);
;             PG8_WAIT_V(8); PG8_WAIT_L(0); PG8_BAR; PG8_MMA(0, 0, At, B0); PG8_MMA(0, 1, At, B1); PG8_BAR; PG8_SCHED;
;             PG8_LDA(At, 0, 1); PG8_STAGE(PG8_SB(0, 0), b2, voffB); PG8_STAGE(PG8_SB(0, 1), b2 + hstepB, voffB); PG8_STAGE(PG8_SA(0, 0), a2, voffA);
;             PG8_WAIT_V(8); PG8_WAIT_L(0); PG8_BAR; PG8_MMA(1, 0, At, B0); PG8_MMA(1, 1, At, B1); PG8_BAR; PG8_SCHED;
.Lpre_up2l0:
	s_lshl_b64 s[98:99], s[98:99], 2
	s_add_u32 s98, s43, s98
	s_addc_u32 s99, s44, s99
	s_lshl_b32 s100, s0, 8
	s_ashr_i32 s101, s100, 31
	s_lshl_b64 s[100:101], s[100:101], 2
	s_add_u32 s98, s98, s100
	s_addc_u32 s99, s99, s101
	s_add_u32 s98, s98, s50
	s_addc_u32 s99, s99, 0
	s_lshl_b32 s100, s2, 8
	s_add_i32 s100, s100, s42
	v_or_b32_e32 v162, s100, v171
	v_ashrrev_i32_e32 v163, 31, v162
	v_lshl_add_u64 v[162:163], v[162:163], 2, s[64:65]
	v_add_u32_e32 v164, s100, v172
	v_ashrrev_i32_e32 v165, 31, v164
	v_lshl_add_u64 v[164:165], v[164:165], 2, s[64:65]
	global_load_dwordx4 v[234:237], v177, s[98:99] offset:16
	global_load_dwordx4 v[238:241], v177, s[98:99]
	global_load_dwordx4 v[242:245], v177, s[98:99] offset:528
	global_load_dwordx4 v[246:249], v177, s[98:99] offset:512
	global_load_dword v250, v[162:163], off
	global_load_dword v251, v[164:165], off
	ds_read_b128 v[66:69], v174
	ds_read_b128 v[70:73], v174 offset:1024
	ds_read_b128 v[74:77], v174 offset:2048
	ds_read_b128 v[78:81], v174 offset:3072
	ds_read_b128 v[162:165], v175
	ds_read_b128 v[182:185], v175 offset:1024
	ds_read_b128 v[186:189], v175 offset:2048
	ds_read_b128 v[190:193], v175 offset:3072
	s_add_u32 s22, s16, 0xfff80080
	s_addc_u32 s23, s17, -1
	s_cmp_eq_u32 s53, 28
	s_cselect_b32 s41, s3, s23
	s_cselect_b32 s40, s15, s22
	s_cselect_b32 s23, s13, s52
	s_cselect_b32 s22, s24, s25
	v_lshl_add_u64 v[166:167], s[16:17], 0, v[154:155]
	s_add_i32 m0, s33, 0xc000
	ds_read_b128 v[194:197], v176
	ds_read_b128 v[198:201], v176 offset:1024
	ds_read_b128 v[202:205], v176 offset:2048
	ds_read_b128 v[206:209], v176 offset:3072
	ds_read_b128 v[210:213], v176 offset:4096
	ds_read_b128 v[214:217], v176 offset:5120
	ds_read_b128 v[218:221], v176 offset:6144
	ds_read_b128 v[222:225], v176 offset:7168
	global_load_lds_dwordx4 v[166:167], off
	v_lshl_add_u64 v[166:167], s[16:17], 0, v[156:157]
	s_add_i32 m0, s33, 0xe000
	s_nop 0
	global_load_lds_dwordx4 v[166:167], off
	s_waitcnt lgkmcnt(0)
	s_barrier
	s_setprio 1
	s_waitcnt lgkmcnt(0)
	v_mfma_f32_16x16x32_bf16 v[142:145], v[66:69], v[194:197], 0
	v_mfma_f32_16x16x32_bf16 v[138:141], v[74:77], v[194:197], 0
	v_mfma_f32_16x16x32_bf16 v[126:129], v[66:69], v[202:205], 0
	v_mfma_f32_16x16x32_bf16 v[122:125], v[74:77], v[202:205], 0
	v_mfma_f32_16x16x32_bf16 v[110:113], v[66:69], v[210:213], 0
	v_mfma_f32_16x16x32_bf16 v[106:109], v[74:77], v[210:213], 0
	v_mfma_f32_16x16x32_bf16 v[94:97], v[66:69], v[218:221], 0
	v_mfma_f32_16x16x32_bf16 v[90:93], v[74:77], v[218:221], 0
	v_mfma_f32_16x16x32_bf16 v[142:145], v[70:73], v[198:201], v[142:145]
	v_mfma_f32_16x16x32_bf16 v[138:141], v[78:81], v[198:201], v[138:141]
	v_mfma_f32_16x16x32_bf16 v[126:129], v[70:73], v[206:209], v[126:129]
	v_mfma_f32_16x16x32_bf16 v[122:125], v[78:81], v[206:209], v[122:125]
	v_mfma_f32_16x16x32_bf16 v[110:113], v[70:73], v[214:217], v[110:113]
	v_mfma_f32_16x16x32_bf16 v[106:109], v[78:81], v[214:217], v[106:109]
	v_mfma_f32_16x16x32_bf16 v[94:97], v[70:73], v[222:225], v[94:97]
	v_mfma_f32_16x16x32_bf16 v[90:93], v[78:81], v[222:225], v[90:93]
	v_mfma_f32_16x16x32_bf16 v[134:137], v[162:165], v[194:197], 0
	v_mfma_f32_16x16x32_bf16 v[130:133], v[186:189], v[194:197], 0
	v_mfma_f32_16x16x32_bf16 v[118:121], v[162:165], v[202:205], 0
	v_mfma_f32_16x16x32_bf16 v[114:117], v[186:189], v[202:205], 0
	v_mfma_f32_16x16x32_bf16 v[102:105], v[162:165], v[210:213], 0
	v_mfma_f32_16x16x32_bf16 v[98:101], v[186:189], v[210:213], 0
	v_mfma_f32_16x16x32_bf16 v[86:89], v[162:165], v[218:221], 0
	v_mfma_f32_16x16x32_bf16 v[82:85], v[186:189], v[218:221], 0
	v_mfma_f32_16x16x32_bf16 v[134:137], v[182:185], v[198:201], v[134:137]
	v_mfma_f32_16x16x32_bf16 v[130:133], v[190:193], v[198:201], v[130:133]
	v_mfma_f32_16x16x32_bf16 v[118:121], v[182:185], v[206:209], v[118:121]
	v_mfma_f32_16x16x32_bf16 v[114:117], v[190:193], v[206:209], v[114:117]
	v_mfma_f32_16x16x32_bf16 v[102:105], v[182:185], v[214:217], v[102:105]
	v_mfma_f32_16x16x32_bf16 v[98:101], v[190:193], v[214:217], v[98:101]
	v_mfma_f32_16x16x32_bf16 v[86:89], v[182:185], v[222:225], v[86:89]
	v_mfma_f32_16x16x32_bf16 v[82:85], v[190:193], v[222:225], v[82:85]
	s_setprio 0
	s_barrier
	s_add_i32 s54, s47, s29
	v_lshl_add_u64 v[166:167], s[22:23], 0, v[150:151]
	s_mov_b32 m0, s54
	ds_read_b128 v[194:197], v176 offset:16384
	ds_read_b128 v[198:201], v176 offset:17408
	ds_read_b128 v[202:205], v176 offset:18432
	ds_read_b128 v[206:209], v176 offset:19456
	ds_read_b128 v[210:213], v176 offset:20480
	ds_read_b128 v[214:217], v176 offset:21504
	ds_read_b128 v[218:221], v176 offset:22528
	ds_read_b128 v[222:225], v176 offset:23552
	global_load_lds_dwordx4 v[166:167], off
	s_add_i32 m0, s54, 0x2000
	s_add_u32 s54, s22, 0x80000
	v_lshl_add_u64 v[226:227], s[22:23], 0, v[146:147]
	s_addc_u32 s55, s23, 0
	s_add_i32 s56, s48, s29
	global_load_lds_dwordx4 v[226:227], off
	v_lshl_add_u64 v[228:229], s[54:55], 0, v[150:151]
	s_mov_b32 m0, s56
	v_lshl_add_u64 v[230:231], s[40:41], 0, v[148:149]
	global_load_lds_dwordx4 v[228:229], off
	v_lshl_add_u64 v[228:229], s[54:55], 0, v[146:147]
	s_add_i32 m0, s56, 0x2000
	s_nop 0
	global_load_lds_dwordx4 v[228:229], off
	v_lshl_add_u64 v[228:229], s[40:41], 0, v[152:153]
	s_mov_b32 m0, s33
	s_nop 0
	global_load_lds_dwordx4 v[228:229], off
	s_mov_b32 m0, s34
	s_nop 0
	global_load_lds_dwordx4 v[230:231], off
	s_waitcnt lgkmcnt(0)
	s_barrier
; #define PG8_STAGE(bufoff, gbase, voff) do { _Pragma("unroll") for (int _i = 0; _i < 2; ++_i) \
;         __builtin_amdgcn_global_load_lds((const unsigned*)((const char*)(gbase) + (voff)[_i]), (LAS unsigned*)(lds + (bufoff) + ldsw + _i * 8192), 16, 0, 0); } while (0)
; #define PG8_LDA(dst, b, h) do { _Pragma("unroll") for (int m = 0; m < 4; ++m) _Pragma("unroll") for (int k = 0; k < 2; ++k) dst[m][k] = *(const LAS bf16x8*)(lds + PG8_SA(b, h) + aoff + m * 2048 + k * 1024); } while (0)
; #define PG8_LDB(dst, b, h) do { _Pragma("unroll") for (int n = 0; n < 2; ++n) _Pragma("unroll") for (int k = 0; k < 2; ++k) dst[n][k] = *(const LAS bf16x8*)(lds + PG8_SB(b, h) + boff + n * 2048 + k * 1024); } while (0)
; #define PG8_MMA(ai, bj, At, Bt) do { __builtin_amdgcn_s_setprio(1); _Pragma("unroll") for (int m = 0; m < 4; ++m) _Pragma("unroll") for (int n = 0; n < 2; ++n) _Pragma("unroll") for (int k = 0; k < 2; ++k) \
;         acc[ai][bj][m][n] = __builtin_amdgcn_mfma_f32_16x16x32_bf16(Bt[n][k], At[m][k], acc[ai][bj][m][n], 0, 0, 0); __builtin_amdgcn_s_setprio(0); } while (0)
; #define PG8_WAIT_V(n) asm volatile("s_waitcnt vmcnt(" #n ")" ::: "memory")
; #define PG8_WAIT_L(n) asm volatile("s_waitcnt lgkmcnt(" #n ")" ::: "memory")
; #define PG8_BAR __builtin_amdgcn_s_barrier()
; #define PG8_SCHED __builtin_amdgcn_sched_barrier(0)
; template <class Epi, class Sched, bool ALIGN_EPI = false, bool SP2 = false>
; __device__ __forceinline__ void gemm_phase(LAS unsigned char* lds, const Gemm g, const Sched& S, const Epi& E) {
;     ...
;             PG8_LDB(B0, 0, 0); PG8_LDB(B1, 0, 1); PG8_SCHED; PG8_LDA(At, 0, 0); PG8_STAGE(PG8_SA(1, 1), a1 + hstep, voffA);
;             PG8_WAIT_V(8); PG8_WAIT_L(0); PG8_BAR; PG8_MMA(0, 0, At, B0); PG8_MMA(0, 1, At, B1); PG8_BAR; PG8_SCHED;
;             PG8_LDA(At, 0, 1); PG8_STAGE(PG8_SB(0, 0), b2, voffB); PG8_STAGE(PG8_SB(0, 1), b2 + hstepB, voffB); PG8_STAGE(PG8_SA(0, 0), a2, voffA);
;             PG8_WAIT_V(8); PG8_WAIT_L(0); PG8_BAR; PG8_MMA(1, 0, At, B0); PG8_MMA(1, 1, At, B1); PG8_BAR; PG8_SCHED;
;             PG8_LDB(B0, 1, 0); PG8_LDB(B1, 1, 1); PG8_SCHED; PG8_LDA(At, 1, 0); PG8_STAGE(PG8_SA(0, 1), a2 + hstep, voffA);
;             PG8_WAIT_V(8); PG8_WAIT_L(0); PG8_BAR; PG8_MMA(0, 0, At, B0); PG8_MMA(0, 1, At, B1); PG8_BAR; PG8_SCHED;
	s_setprio 1
	s_waitcnt lgkmcnt(0)
	v_mfma_f32_16x16x32_bf16 v[62:65], v[66:69], v[194:197], 0
	v_mfma_f32_16x16x32_bf16 v[58:61], v[74:77], v[194:197], 0
	v_mfma_f32_16x16x32_bf16 v[46:49], v[66:69], v[202:205], 0
	v_mfma_f32_16x16x32_bf16 v[42:45], v[74:77], v[202:205], 0
	v_mfma_f32_16x16x32_bf16 v[30:33], v[66:69], v[210:213], 0
	v_mfma_f32_16x16x32_bf16 v[26:29], v[74:77], v[210:213], 0
	v_mfma_f32_16x16x32_bf16 v[14:17], v[66:69], v[218:221], 0
	v_mfma_f32_16x16x32_bf16 v[10:13], v[74:77], v[218:221], 0
	v_mfma_f32_16x16x32_bf16 v[62:65], v[70:73], v[198:201], v[62:65]
	v_mfma_f32_16x16x32_bf16 v[58:61], v[78:81], v[198:201], v[58:61]
	v_mfma_f32_16x16x32_bf16 v[46:49], v[70:73], v[206:209], v[46:49]
	v_mfma_f32_16x16x32_bf16 v[42:45], v[78:81], v[206:209], v[42:45]
	v_mfma_f32_16x16x32_bf16 v[30:33], v[70:73], v[214:217], v[30:33]
	v_mfma_f32_16x16x32_bf16 v[26:29], v[78:81], v[214:217], v[26:29]
	v_mfma_f32_16x16x32_bf16 v[14:17], v[70:73], v[222:225], v[14:17]
	v_mfma_f32_16x16x32_bf16 v[10:13], v[78:81], v[222:225], v[10:13]
	v_mfma_f32_16x16x32_bf16 v[54:57], v[162:165], v[194:197], 0
	v_mfma_f32_16x16x32_bf16 v[50:53], v[186:189], v[194:197], 0
	v_mfma_f32_16x16x32_bf16 v[38:41], v[162:165], v[202:205], 0
	v_mfma_f32_16x16x32_bf16 v[34:37], v[186:189], v[202:205], 0
	v_mfma_f32_16x16x32_bf16 v[22:25], v[162:165], v[210:213], 0
	v_mfma_f32_16x16x32_bf16 v[18:21], v[186:189], v[210:213], 0
	v_mfma_f32_16x16x32_bf16 v[6:9], v[162:165], v[218:221], 0
	v_mfma_f32_16x16x32_bf16 v[2:5], v[186:189], v[218:221], 0
	v_mfma_f32_16x16x32_bf16 v[54:57], v[182:185], v[198:201], v[54:57]
	v_mfma_f32_16x16x32_bf16 v[50:53], v[190:193], v[198:201], v[50:53]
	v_mfma_f32_16x16x32_bf16 v[38:41], v[182:185], v[206:209], v[38:41]
	v_mfma_f32_16x16x32_bf16 v[34:37], v[190:193], v[206:209], v[34:37]
	v_mfma_f32_16x16x32_bf16 v[22:25], v[182:185], v[214:217], v[22:25]
	v_mfma_f32_16x16x32_bf16 v[18:21], v[190:193], v[214:217], v[18:21]
	v_mfma_f32_16x16x32_bf16 v[6:9], v[182:185], v[222:225], v[6:9]
	v_mfma_f32_16x16x32_bf16 v[2:5], v[190:193], v[222:225], v[2:5]
	s_setprio 0
	s_barrier
	s_add_i32 s54, 0, 0x18000
	s_add_i32 s55, 0, 0x1c000
	v_add_u32_e32 v78, s54, v170
	v_add_u32_e32 v168, s55, v170
	ds_read_b128 v[66:69], v78
	ds_read_b128 v[70:73], v78 offset:1024
	ds_read_b128 v[74:77], v78 offset:2048
	ds_read_b128 v[78:81], v78 offset:3072
	ds_read_b128 v[162:165], v168
	ds_read_b128 v[182:185], v168 offset:1024
	ds_read_b128 v[186:189], v168 offset:2048
	ds_read_b128 v[190:193], v168 offset:3072
	s_add_u32 s40, s40, 0x80000
	s_addc_u32 s41, s41, 0
	s_mov_b32 m0, s35
	v_lshl_add_u64 v[232:233], s[40:41], 0, v[152:153]
	ds_read_b128 v[194:197], v176 offset:32768
	ds_read_b128 v[198:201], v176 offset:33792
	ds_read_b128 v[202:205], v176 offset:34816
	ds_read_b128 v[206:209], v176 offset:35840
	ds_read_b128 v[210:213], v176 offset:36864
	ds_read_b128 v[214:217], v176 offset:37888
	ds_read_b128 v[218:221], v176 offset:38912
	ds_read_b128 v[222:225], v176 offset:39936
	global_load_lds_dwordx4 v[232:233], off
	v_lshl_add_u64 v[232:233], s[40:41], 0, v[148:149]
	s_mov_b32 m0, s36
	s_nop 0
	global_load_lds_dwordx4 v[232:233], off
	s_waitcnt vmcnt(8)
	s_waitcnt lgkmcnt(0)
	s_barrier
	s_setprio 1
	s_waitcnt lgkmcnt(0)
	v_mfma_f32_16x16x32_bf16 v[142:145], v[66:69], v[194:197], v[142:145]
	v_mfma_f32_16x16x32_bf16 v[138:141], v[74:77], v[194:197], v[138:141]
	v_mfma_f32_16x16x32_bf16 v[126:129], v[66:69], v[202:205], v[126:129]
	v_mfma_f32_16x16x32_bf16 v[122:125], v[74:77], v[202:205], v[122:125]
	v_mfma_f32_16x16x32_bf16 v[110:113], v[66:69], v[210:213], v[110:113]
	v_mfma_f32_16x16x32_bf16 v[106:109], v[74:77], v[210:213], v[106:109]
	v_mfma_f32_16x16x32_bf16 v[94:97], v[66:69], v[218:221], v[94:97]
	v_mfma_f32_16x16x32_bf16 v[90:93], v[74:77], v[218:221], v[90:93]
	v_mfma_f32_16x16x32_bf16 v[142:145], v[70:73], v[198:201], v[142:145]
	v_mfma_f32_16x16x32_bf16 v[138:141], v[78:81], v[198:201], v[138:141]
	v_mfma_f32_16x16x32_bf16 v[126:129], v[70:73], v[206:209], v[126:129]
	v_mfma_f32_16x16x32_bf16 v[122:125], v[78:81], v[206:209], v[122:125]
	v_mfma_f32_16x16x32_bf16 v[110:113], v[70:73], v[214:217], v[110:113]
	v_mfma_f32_16x16x32_bf16 v[106:109], v[78:81], v[214:217], v[106:109]
	v_mfma_f32_16x16x32_bf16 v[94:97], v[70:73], v[222:225], v[94:97]
	v_mfma_f32_16x16x32_bf16 v[90:93], v[78:81], v[222:225], v[90:93]
	v_mfma_f32_16x16x32_bf16 v[134:137], v[162:165], v[194:197], v[134:137]
	v_mfma_f32_16x16x32_bf16 v[130:133], v[186:189], v[194:197], v[130:133]
	v_mfma_f32_16x16x32_bf16 v[118:121], v[162:165], v[202:205], v[118:121]
	v_mfma_f32_16x16x32_bf16 v[114:117], v[186:189], v[202:205], v[114:117]
	v_mfma_f32_16x16x32_bf16 v[102:105], v[162:165], v[210:213], v[102:105]
	v_mfma_f32_16x16x32_bf16 v[98:101], v[186:189], v[210:213], v[98:101]
	v_mfma_f32_16x16x32_bf16 v[86:89], v[162:165], v[218:221], v[86:89]
	v_mfma_f32_16x16x32_bf16 v[82:85], v[186:189], v[218:221], v[82:85]
	v_mfma_f32_16x16x32_bf16 v[134:137], v[182:185], v[198:201], v[134:137]
	v_mfma_f32_16x16x32_bf16 v[130:133], v[190:193], v[198:201], v[130:133]
	v_mfma_f32_16x16x32_bf16 v[118:121], v[182:185], v[206:209], v[118:121]
	v_mfma_f32_16x16x32_bf16 v[114:117], v[190:193], v[206:209], v[114:117]
	v_mfma_f32_16x16x32_bf16 v[102:105], v[182:185], v[214:217], v[102:105]
	v_mfma_f32_16x16x32_bf16 v[98:101], v[190:193], v[214:217], v[98:101]
	v_mfma_f32_16x16x32_bf16 v[86:89], v[182:185], v[222:225], v[86:89]
	v_mfma_f32_16x16x32_bf16 v[82:85], v[190:193], v[222:225], v[82:85]
	s_setprio 0
	s_barrier
; #define PG8_STAGE(bufoff, gbase, voff) do { _Pragma("unroll") for (int _i = 0; _i < 2; ++_i) \
;         __builtin_amdgcn_global_load_lds((const unsigned*)((const char*)(gbase) + (voff)[_i]), (LAS unsigned*)(lds + (bufoff) + ldsw + _i * 8192), 16, 0, 0); } while (0)
; #define PG8_LDA(dst, b, h) do { _Pragma("unroll") for (int m = 0; m < 4; ++m) _Pragma("unroll") for (int k = 0; k < 2; ++k) dst[m][k] = *(const LAS bf16x8*)(lds + PG8_SA(b, h) + aoff + m * 2048 + k * 1024); } while (0)
; #define PG8_MMA(ai, bj, At, Bt) do { __builtin_amdgcn_s_setprio(1); _Pragma("unroll") for (int m = 0; m < 4; ++m) _Pragma("unroll") for (int n = 0; n < 2; ++n) _Pragma("unroll") for (int k = 0; k < 2; ++k) \
;         acc[ai][bj][m][n] = __builtin_amdgcn_mfma_f32_16x16x32_bf16(Bt[n][k], At[m][k], acc[ai][bj][m][n], 0, 0, 0); __builtin_amdgcn_s_setprio(0); } while (0)
; #define PG8_WAIT_V(n) asm volatile("s_waitcnt vmcnt(" #n ")" ::: "memory")
; #define PG8_WAIT_L(n) asm volatile("s_waitcnt lgkmcnt(" #n ")" ::: "memory")
; #define PG8_BAR __builtin_amdgcn_s_barrier()
; #define PG8_SCHED __builtin_amdgcn_sched_barrier(0)
; template <class Epi, class Sched, bool ALIGN_EPI = false, bool SP2 = false>
; __device__ __forceinline__ void gemm_phase(LAS unsigned char* lds, const Gemm g, const Sched& S, const Epi& E) {
;     ...
;         for (int t = 0; t < nt; t += 2) {
;             const bool last = (t == nt - 2);
;     ...
;             PG8_LDA(At, 1, 1); PG8_STAGE(PG8_SB(1, 0), b3, voffB); PG8_STAGE(PG8_SB(1, 1), b3 + hstepB, voffB); PG8_STAGE(PG8_SA(1, 0), a3, voffA);
;             PG8_WAIT_V(8); PG8_WAIT_L(0); PG8_BAR; PG8_MMA(1, 0, At, B0); PG8_MMA(1, 1, At, B1); PG8_BAR; PG8_SCHED;
	s_add_i32 s40, s54, s29
	v_lshl_add_u64 v[166:167], v[166:167], 0, s[8:9]
	s_mov_b32 m0, s40
	ds_read_b128 v[194:197], v176 offset:49152
	ds_read_b128 v[198:201], v176 offset:50176
	ds_read_b128 v[202:205], v176 offset:51200
	ds_read_b128 v[206:209], v176 offset:52224
	ds_read_b128 v[210:213], v176 offset:53248
	ds_read_b128 v[214:217], v176 offset:54272
	ds_read_b128 v[218:221], v176 offset:55296
	ds_read_b128 v[222:225], v176 offset:56320
	global_load_lds_dwordx4 v[166:167], off
	s_add_i32 m0, s40, 0x2000
	s_add_u32 s22, s22, 0x80080
	v_lshl_add_u64 v[166:167], v[226:227], 0, s[8:9]
	s_addc_u32 s23, s23, 0
	s_add_i32 s40, s55, s29
	global_load_lds_dwordx4 v[166:167], off
	v_lshl_add_u64 v[166:167], s[22:23], 0, v[150:151]
	s_mov_b32 m0, s40
	s_nop 0
	global_load_lds_dwordx4 v[166:167], off
	v_lshl_add_u64 v[166:167], s[22:23], 0, v[146:147]
	s_add_i32 m0, s40, 0x2000
	s_nop 0
	global_load_lds_dwordx4 v[166:167], off
	v_lshl_add_u64 v[166:167], v[228:229], 0, s[8:9]
	s_mov_b32 m0, s45
	s_nop 0
	global_load_lds_dwordx4 v[166:167], off
	v_lshl_add_u64 v[166:167], v[230:231], 0, s[8:9]
	s_mov_b32 m0, s46
	s_nop 0
	global_load_lds_dwordx4 v[166:167], off
	s_waitcnt vmcnt(8)
	s_waitcnt lgkmcnt(0)
	s_barrier
	s_setprio 1
	s_waitcnt lgkmcnt(0)
	v_mfma_f32_16x16x32_bf16 v[62:65], v[66:69], v[194:197], v[62:65]
	v_mfma_f32_16x16x32_bf16 v[58:61], v[74:77], v[194:197], v[58:61]
	v_mfma_f32_16x16x32_bf16 v[46:49], v[66:69], v[202:205], v[46:49]
	v_mfma_f32_16x16x32_bf16 v[42:45], v[74:77], v[202:205], v[42:45]
	v_mfma_f32_16x16x32_bf16 v[30:33], v[66:69], v[210:213], v[30:33]
	v_mfma_f32_16x16x32_bf16 v[26:29], v[74:77], v[210:213], v[26:29]
	v_mfma_f32_16x16x32_bf16 v[14:17], v[66:69], v[218:221], v[14:17]
	v_mfma_f32_16x16x32_bf16 v[10:13], v[74:77], v[218:221], v[10:13]
	v_mfma_f32_16x16x32_bf16 v[62:65], v[70:73], v[198:201], v[62:65]
	v_mfma_f32_16x16x32_bf16 v[58:61], v[78:81], v[198:201], v[58:61]
	v_mfma_f32_16x16x32_bf16 v[46:49], v[70:73], v[206:209], v[46:49]
	v_mfma_f32_16x16x32_bf16 v[42:45], v[78:81], v[206:209], v[42:45]
	v_mfma_f32_16x16x32_bf16 v[30:33], v[70:73], v[214:217], v[30:33]
	v_mfma_f32_16x16x32_bf16 v[26:29], v[78:81], v[214:217], v[26:29]
	v_mfma_f32_16x16x32_bf16 v[14:17], v[70:73], v[222:225], v[14:17]
	v_mfma_f32_16x16x32_bf16 v[10:13], v[78:81], v[222:225], v[10:13]
	v_mfma_f32_16x16x32_bf16 v[54:57], v[162:165], v[194:197], v[54:57]
	v_mfma_f32_16x16x32_bf16 v[50:53], v[186:189], v[194:197], v[50:53]
	v_mfma_f32_16x16x32_bf16 v[38:41], v[162:165], v[202:205], v[38:41]
	v_mfma_f32_16x16x32_bf16 v[34:37], v[186:189], v[202:205], v[34:37]
	v_mfma_f32_16x16x32_bf16 v[22:25], v[162:165], v[210:213], v[22:25]
	v_mfma_f32_16x16x32_bf16 v[18:21], v[186:189], v[210:213], v[18:21]
	v_mfma_f32_16x16x32_bf16 v[6:9], v[162:165], v[218:221], v[6:9]
	v_mfma_f32_16x16x32_bf16 v[2:5], v[186:189], v[218:221], v[2:5]
	v_mfma_f32_16x16x32_bf16 v[54:57], v[182:185], v[198:201], v[54:57]
	v_mfma_f32_16x16x32_bf16 v[50:53], v[190:193], v[198:201], v[50:53]
	v_mfma_f32_16x16x32_bf16 v[38:41], v[182:185], v[206:209], v[38:41]
	v_mfma_f32_16x16x32_bf16 v[34:37], v[190:193], v[206:209], v[34:37]
	v_mfma_f32_16x16x32_bf16 v[22:25], v[182:185], v[214:217], v[22:25]
	v_mfma_f32_16x16x32_bf16 v[18:21], v[190:193], v[214:217], v[18:21]
	v_mfma_f32_16x16x32_bf16 v[6:9], v[182:185], v[222:225], v[6:9]
	v_mfma_f32_16x16x32_bf16 v[2:5], v[190:193], v[222:225], v[2:5]
	s_setprio 0
	s_barrier
	s_add_i32 s53, s53, 2
	s_add_u32 s16, s16, 0x100
	s_addc_u32 s17, s17, 0
	s_add_u32 s25, s25, 0x100
	s_addc_u32 s52, s52, 0
	s_cmp_gt_u32 s53, 29
.LBB0_1465:
	ds_read_b128 v[66:69], v174
	ds_read_b128 v[70:73], v174 offset:1024
	ds_read_b128 v[74:77], v174 offset:2048
	ds_read_b128 v[78:81], v174 offset:3072
	ds_read_b128 v[162:165], v175
	ds_read_b128 v[182:185], v175 offset:1024
	ds_read_b128 v[186:189], v175 offset:2048
	ds_read_b128 v[190:193], v175 offset:3072
	s_add_u32 s22, s16, 0xfff80080
	s_addc_u32 s23, s17, -1
	s_cmp_eq_u32 s53, 28
	s_cselect_b32 s41, s3, s23
	s_cselect_b32 s40, s15, s22
	s_cselect_b32 s23, s13, s52
	s_cselect_b32 s22, s24, s25
	v_lshl_add_u64 v[166:167], s[16:17], 0, v[154:155]
	s_add_i32 m0, s33, 0xc000
	ds_read_b128 v[194:197], v176
	ds_read_b128 v[198:201], v176 offset:1024
	ds_read_b128 v[202:205], v176 offset:2048
	ds_read_b128 v[206:209], v176 offset:3072
	ds_read_b128 v[210:213], v176 offset:4096
	ds_read_b128 v[214:217], v176 offset:5120
	ds_read_b128 v[218:221], v176 offset:6144
	ds_read_b128 v[222:225], v176 offset:7168
	global_load_lds_dwordx4 v[166:167], off
	v_lshl_add_u64 v[166:167], s[16:17], 0, v[156:157]
	s_add_i32 m0, s33, 0xe000
	s_nop 0
	global_load_lds_dwordx4 v[166:167], off
	s_waitcnt vmcnt(8)
	s_waitcnt lgkmcnt(0)
	s_barrier
; #define PG8_STAGE(bufoff, gbase, voff) do { _Pragma("unroll") for (int _i = 0; _i < 2; ++_i) \
;         __builtin_amdgcn_global_load_lds((const unsigned*)((const char*)(gbase) + (voff)[_i]), (LAS unsigned*)(lds + (bufoff) + ldsw + _i * 8192), 16, 0, 0); } while (0)
; #define PG8_LDA(dst, b, h) do { _Pragma("unroll") for (int m = 0; m < 4; ++m) _Pragma("unroll") for (int k = 0; k < 2; ++k) dst[m][k] = *(const LAS bf16x8*)(lds + PG8_SA(b, h) + aoff + m * 2048 + k * 1024); } while (0)
; #define PG8_LDB(dst, b, h) do { _Pragma("unroll") for (int n = 0; n < 2; ++n) _Pragma("unroll") for (int k = 0; k < 2; ++k) dst[n][k] = *(const LAS bf16x8*)(lds + PG8_SB(b, h) + boff + n * 2048 + k * 1024); } while (0)
; #define PG8_MMA(ai, bj, At, Bt) do { __builtin_amdgcn_s_setprio(1); _Pragma("unroll") for (int m = 0; m < 4; ++m) _Pragma("unroll") for (int n = 0; n < 2; ++n) _Pragma("unroll") for (int k = 0; k < 2; ++k) \
;         acc[ai][bj][m][n] = __builtin_amdgcn_mfma_f32_16x16x32_bf16(Bt[n][k], At[m][k], acc[ai][bj][m][n], 0, 0, 0); __builtin_amdgcn_s_setprio(0); } while (0)
; #define PG8_WAIT_V(n) asm volatile("s_waitcnt vmcnt(" #n ")" ::: "memory")
; #define PG8_WAIT_L(n) asm volatile("s_waitcnt lgkmcnt(" #n ")" ::: "memory")
; #define PG8_BAR __builtin_amdgcn_s_barrier()
; #define PG8_SCHED __builtin_amdgcn_sched_barrier(0)
; template <class Epi, class Sched, bool ALIGN_EPI = false, bool SP2 = false>
; __device__ __forceinline__ void gemm_phase(LAS unsigned char* lds, const Gemm g, const Sched& S, const Epi& E) {
;     ...
;             PG8_LDB(B0, 0, 0); PG8_LDB(B1, 0, 1); PG8_SCHED; PG8_LDA(At, 0, 0); PG8_STAGE(PG8_SA(1, 1), a1 + hstep, voffA);
;             PG8_WAIT_V(8); PG8_WAIT_L(0); PG8_BAR; PG8_MMA(0, 0, At, B0); PG8_MMA(0, 1, At, B1); PG8_BAR; PG8_SCHED;
;             PG8_LDA(At, 0, 1); PG8_STAGE(PG8_SB(0, 0), b2, voffB); PG8_STAGE(PG8_SB(0, 1), b2 + hstepB, voffB); PG8_STAGE(PG8_SA(0, 0), a2, voffA);
;             PG8_WAIT_V(8); PG8_WAIT_L(0); PG8_BAR; PG8_MMA(1, 0, At, B0); PG8_MMA(1, 1, At, B1); PG8_BAR; PG8_SCHED;
	s_setprio 1
	s_waitcnt lgkmcnt(0)
	v_mfma_f32_16x16x32_bf16 v[142:145], v[66:69], v[194:197], v[142:145]
	v_mfma_f32_16x16x32_bf16 v[138:141], v[74:77], v[194:197], v[138:141]
	v_mfma_f32_16x16x32_bf16 v[126:129], v[66:69], v[202:205], v[126:129]
	v_mfma_f32_16x16x32_bf16 v[122:125], v[74:77], v[202:205], v[122:125]
	v_mfma_f32_16x16x32_bf16 v[110:113], v[66:69], v[210:213], v[110:113]
	v_mfma_f32_16x16x32_bf16 v[106:109], v[74:77], v[210:213], v[106:109]
	v_mfma_f32_16x16x32_bf16 v[94:97], v[66:69], v[218:221], v[94:97]
	v_mfma_f32_16x16x32_bf16 v[90:93], v[74:77], v[218:221], v[90:93]
	v_mfma_f32_16x16x32_bf16 v[142:145], v[70:73], v[198:201], v[142:145]
	v_mfma_f32_16x16x32_bf16 v[138:141], v[78:81], v[198:201], v[138:141]
	v_mfma_f32_16x16x32_bf16 v[126:129], v[70:73], v[206:209], v[126:129]
	v_mfma_f32_16x16x32_bf16 v[122:125], v[78:81], v[206:209], v[122:125]
	v_mfma_f32_16x16x32_bf16 v[110:113], v[70:73], v[214:217], v[110:113]
	v_mfma_f32_16x16x32_bf16 v[106:109], v[78:81], v[214:217], v[106:109]
	v_mfma_f32_16x16x32_bf16 v[94:97], v[70:73], v[222:225], v[94:97]
	v_mfma_f32_16x16x32_bf16 v[90:93], v[78:81], v[222:225], v[90:93]
	v_mfma_f32_16x16x32_bf16 v[134:137], v[162:165], v[194:197], v[134:137]
	v_mfma_f32_16x16x32_bf16 v[130:133], v[186:189], v[194:197], v[130:133]
	v_mfma_f32_16x16x32_bf16 v[118:121], v[162:165], v[202:205], v[118:121]
	v_mfma_f32_16x16x32_bf16 v[114:117], v[186:189], v[202:205], v[114:117]
	v_mfma_f32_16x16x32_bf16 v[102:105], v[162:165], v[210:213], v[102:105]
	v_mfma_f32_16x16x32_bf16 v[98:101], v[186:189], v[210:213], v[98:101]
	v_mfma_f32_16x16x32_bf16 v[86:89], v[162:165], v[218:221], v[86:89]
	v_mfma_f32_16x16x32_bf16 v[82:85], v[186:189], v[218:221], v[82:85]
	v_mfma_f32_16x16x32_bf16 v[134:137], v[182:185], v[198:201], v[134:137]
	v_mfma_f32_16x16x32_bf16 v[130:133], v[190:193], v[198:201], v[130:133]
	v_mfma_f32_16x16x32_bf16 v[118:121], v[182:185], v[206:209], v[118:121]
	v_mfma_f32_16x16x32_bf16 v[114:117], v[190:193], v[206:209], v[114:117]
	v_mfma_f32_16x16x32_bf16 v[102:105], v[182:185], v[214:217], v[102:105]
	v_mfma_f32_16x16x32_bf16 v[98:101], v[190:193], v[214:217], v[98:101]
	v_mfma_f32_16x16x32_bf16 v[86:89], v[182:185], v[222:225], v[86:89]
	v_mfma_f32_16x16x32_bf16 v[82:85], v[190:193], v[222:225], v[82:85]
	s_setprio 0
	s_barrier
	s_add_i32 s54, s47, s29
	v_lshl_add_u64 v[166:167], s[22:23], 0, v[150:151]
	s_mov_b32 m0, s54
	ds_read_b128 v[194:197], v176 offset:16384
	ds_read_b128 v[198:201], v176 offset:17408
	ds_read_b128 v[202:205], v176 offset:18432
	ds_read_b128 v[206:209], v176 offset:19456
	ds_read_b128 v[210:213], v176 offset:20480
	ds_read_b128 v[214:217], v176 offset:21504
	ds_read_b128 v[218:221], v176 offset:22528
	ds_read_b128 v[222:225], v176 offset:23552
	global_load_lds_dwordx4 v[166:167], off
	s_add_i32 m0, s54, 0x2000
	s_add_u32 s54, s22, 0x80000
	v_lshl_add_u64 v[226:227], s[22:23], 0, v[146:147]
	s_addc_u32 s55, s23, 0
	s_add_i32 s56, s48, s29
	global_load_lds_dwordx4 v[226:227], off
	v_lshl_add_u64 v[228:229], s[54:55], 0, v[150:151]
	s_mov_b32 m0, s56
	v_lshl_add_u64 v[230:231], s[40:41], 0, v[148:149]
	global_load_lds_dwordx4 v[228:229], off
	v_lshl_add_u64 v[228:229], s[54:55], 0, v[146:147]
	s_add_i32 m0, s56, 0x2000
	s_nop 0
	global_load_lds_dwordx4 v[228:229], off
	v_lshl_add_u64 v[228:229], s[40:41], 0, v[152:153]
	s_mov_b32 m0, s33
	s_nop 0
	global_load_lds_dwordx4 v[228:229], off
	s_mov_b32 m0, s34
	s_nop 0
	global_load_lds_dwordx4 v[230:231], off
	s_waitcnt vmcnt(8)
	s_waitcnt lgkmcnt(0)
	s_barrier
	s_setprio 1
	s_waitcnt lgkmcnt(0)
	v_mfma_f32_16x16x32_bf16 v[62:65], v[66:69], v[194:197], v[62:65]
	v_mfma_f32_16x16x32_bf16 v[58:61], v[74:77], v[194:197], v[58:61]
	v_mfma_f32_16x16x32_bf16 v[46:49], v[66:69], v[202:205], v[46:49]
	v_mfma_f32_16x16x32_bf16 v[42:45], v[74:77], v[202:205], v[42:45]
	v_mfma_f32_16x16x32_bf16 v[30:33], v[66:69], v[210:213], v[30:33]
	v_mfma_f32_16x16x32_bf16 v[26:29], v[74:77], v[210:213], v[26:29]
	v_mfma_f32_16x16x32_bf16 v[14:17], v[66:69], v[218:221], v[14:17]
	v_mfma_f32_16x16x32_bf16 v[10:13], v[74:77], v[218:221], v[10:13]
	v_mfma_f32_16x16x32_bf16 v[62:65], v[70:73], v[198:201], v[62:65]
	v_mfma_f32_16x16x32_bf16 v[58:61], v[78:81], v[198:201], v[58:61]
	v_mfma_f32_16x16x32_bf16 v[46:49], v[70:73], v[206:209], v[46:49]
	v_mfma_f32_16x16x32_bf16 v[42:45], v[78:81], v[206:209], v[42:45]
	v_mfma_f32_16x16x32_bf16 v[30:33], v[70:73], v[214:217], v[30:33]
	v_mfma_f32_16x16x32_bf16 v[26:29], v[78:81], v[214:217], v[26:29]
	v_mfma_f32_16x16x32_bf16 v[14:17], v[70:73], v[222:225], v[14:17]
	v_mfma_f32_16x16x32_bf16 v[10:13], v[78:81], v[222:225], v[10:13]
	v_mfma_f32_16x16x32_bf16 v[54:57], v[162:165], v[194:197], v[54:57]
	v_mfma_f32_16x16x32_bf16 v[50:53], v[186:189], v[194:197], v[50:53]
	v_mfma_f32_16x16x32_bf16 v[38:41], v[162:165], v[202:205], v[38:41]
	v_mfma_f32_16x16x32_bf16 v[34:37], v[186:189], v[202:205], v[34:37]
	v_mfma_f32_16x16x32_bf16 v[22:25], v[162:165], v[210:213], v[22:25]
	v_mfma_f32_16x16x32_bf16 v[18:21], v[186:189], v[210:213], v[18:21]
	v_mfma_f32_16x16x32_bf16 v[6:9], v[162:165], v[218:221], v[6:9]
	v_mfma_f32_16x16x32_bf16 v[2:5], v[186:189], v[218:221], v[2:5]
	v_mfma_f32_16x16x32_bf16 v[54:57], v[182:185], v[198:201], v[54:57]
	v_mfma_f32_16x16x32_bf16 v[50:53], v[190:193], v[198:201], v[50:53]
	v_mfma_f32_16x16x32_bf16 v[38:41], v[182:185], v[206:209], v[38:41]
	v_mfma_f32_16x16x32_bf16 v[34:37], v[190:193], v[206:209], v[34:37]
	v_mfma_f32_16x16x32_bf16 v[22:25], v[182:185], v[214:217], v[22:25]
	v_mfma_f32_16x16x32_bf16 v[18:21], v[190:193], v[214:217], v[18:21]
	v_mfma_f32_16x16x32_bf16 v[6:9], v[182:185], v[222:225], v[6:9]
	v_mfma_f32_16x16x32_bf16 v[2:5], v[190:193], v[222:225], v[2:5]
	s_setprio 0
	s_barrier
; #define PG8_STAGE(bufoff, gbase, voff) do { _Pragma("unroll") for (int _i = 0; _i < 2; ++_i) \
;         __builtin_amdgcn_global_load_lds((const unsigned*)((const char*)(gbase) + (voff)[_i]), (LAS unsigned*)(lds + (bufoff) + ldsw + _i * 8192), 16, 0, 0); } while (0)
; #define PG8_LDA(dst, b, h) do { _Pragma("unroll") for (int m = 0; m < 4; ++m) _Pragma("unroll") for (int k = 0; k < 2; ++k) dst[m][k] = *(const LAS bf16x8*)(lds + PG8_SA(b, h) + aoff + m * 2048 + k * 1024); } while (0)
; #define PG8_LDB(dst, b, h) do { _Pragma("unroll") for (int n = 0; n < 2; ++n) _Pragma("unroll") for (int k = 0; k < 2; ++k) dst[n][k] = *(const LAS bf16x8*)(lds + PG8_SB(b, h) + boff + n * 2048 + k * 1024); } while (0)
; #define PG8_MMA(ai, bj, At, Bt) do { __builtin_amdgcn_s_setprio(1); _Pragma("unroll") for (int m = 0; m < 4; ++m) _Pragma("unroll") for (int n = 0; n < 2; ++n) _Pragma("unroll") for (int k = 0; k < 2; ++k) \
;         acc[ai][bj][m][n] = __builtin_amdgcn_mfma_f32_16x16x32_bf16(Bt[n][k], At[m][k], acc[ai][bj][m][n], 0, 0, 0); __builtin_amdgcn_s_setprio(0); } while (0)
; #define PG8_WAIT_V(n) asm volatile("s_waitcnt vmcnt(" #n ")" ::: "memory")
; #define PG8_WAIT_L(n) asm volatile("s_waitcnt lgkmcnt(" #n ")" ::: "memory")
; #define PG8_BAR __builtin_amdgcn_s_barrier()
; #define PG8_SCHED __builtin_amdgcn_sched_barrier(0)
; template <class Epi, class Sched, bool ALIGN_EPI = false, bool SP2 = false>
; __device__ __forceinline__ void gemm_phase(LAS unsigned char* lds, const Gemm g, const Sched& S, const Epi& E) {
;     ...
;             PG8_LDB(B0, 1, 0); PG8_LDB(B1, 1, 1); PG8_SCHED; PG8_LDA(At, 1, 0); PG8_STAGE(PG8_SA(0, 1), a2 + hstep, voffA);
;             PG8_WAIT_V(8); PG8_WAIT_L(0); PG8_BAR; PG8_MMA(0, 0, At, B0); PG8_MMA(0, 1, At, B1); PG8_BAR; PG8_SCHED;
	s_add_i32 s54, 0, 0x18000
	s_add_i32 s55, 0, 0x1c000
	v_add_u32_e32 v78, s54, v170
	v_add_u32_e32 v168, s55, v170
	ds_read_b128 v[66:69], v78
	ds_read_b128 v[70:73], v78 offset:1024
	ds_read_b128 v[74:77], v78 offset:2048
	ds_read_b128 v[78:81], v78 offset:3072
	ds_read_b128 v[162:165], v168
	ds_read_b128 v[182:185], v168 offset:1024
	ds_read_b128 v[186:189], v168 offset:2048
	ds_read_b128 v[190:193], v168 offset:3072
	s_add_u32 s40, s40, 0x80000
	s_addc_u32 s41, s41, 0
	s_mov_b32 m0, s35
	v_lshl_add_u64 v[232:233], s[40:41], 0, v[152:153]
	ds_read_b128 v[194:197], v176 offset:32768
	ds_read_b128 v[198:201], v176 offset:33792
	ds_read_b128 v[202:205], v176 offset:34816
	ds_read_b128 v[206:209], v176 offset:35840
	ds_read_b128 v[210:213], v176 offset:36864
	ds_read_b128 v[214:217], v176 offset:37888
	ds_read_b128 v[218:221], v176 offset:38912
	ds_read_b128 v[222:225], v176 offset:39936
	global_load_lds_dwordx4 v[232:233], off
	v_lshl_add_u64 v[232:233], s[40:41], 0, v[148:149]
	s_mov_b32 m0, s36
	s_nop 0
	global_load_lds_dwordx4 v[232:233], off
	s_waitcnt vmcnt(8)
	s_waitcnt lgkmcnt(0)
	s_barrier
	s_setprio 1
	s_waitcnt lgkmcnt(0)
	v_mfma_f32_16x16x32_bf16 v[142:145], v[66:69], v[194:197], v[142:145]
	v_mfma_f32_16x16x32_bf16 v[138:141], v[74:77], v[194:197], v[138:141]
	v_mfma_f32_16x16x32_bf16 v[126:129], v[66:69], v[202:205], v[126:129]
	v_mfma_f32_16x16x32_bf16 v[122:125], v[74:77], v[202:205], v[122:125]
	v_mfma_f32_16x16x32_bf16 v[110:113], v[66:69], v[210:213], v[110:113]
	v_mfma_f32_16x16x32_bf16 v[106:109], v[74:77], v[210:213], v[106:109]
	v_mfma_f32_16x16x32_bf16 v[94:97], v[66:69], v[218:221], v[94:97]
	v_mfma_f32_16x16x32_bf16 v[90:93], v[74:77], v[218:221], v[90:93]
	v_mfma_f32_16x16x32_bf16 v[142:145], v[70:73], v[198:201], v[142:145]
	v_mfma_f32_16x16x32_bf16 v[138:141], v[78:81], v[198:201], v[138:141]
	v_mfma_f32_16x16x32_bf16 v[126:129], v[70:73], v[206:209], v[126:129]
	v_mfma_f32_16x16x32_bf16 v[122:125], v[78:81], v[206:209], v[122:125]
	v_mfma_f32_16x16x32_bf16 v[110:113], v[70:73], v[214:217], v[110:113]
	v_mfma_f32_16x16x32_bf16 v[106:109], v[78:81], v[214:217], v[106:109]
	v_mfma_f32_16x16x32_bf16 v[94:97], v[70:73], v[222:225], v[94:97]
	v_mfma_f32_16x16x32_bf16 v[90:93], v[78:81], v[222:225], v[90:93]
	v_mfma_f32_16x16x32_bf16 v[134:137], v[162:165], v[194:197], v[134:137]
	v_mfma_f32_16x16x32_bf16 v[130:133], v[186:189], v[194:197], v[130:133]
	v_mfma_f32_16x16x32_bf16 v[118:121], v[162:165], v[202:205], v[118:121]
	v_mfma_f32_16x16x32_bf16 v[114:117], v[186:189], v[202:205], v[114:117]
	v_mfma_f32_16x16x32_bf16 v[102:105], v[162:165], v[210:213], v[102:105]
	v_mfma_f32_16x16x32_bf16 v[98:101], v[186:189], v[210:213], v[98:101]
	v_mfma_f32_16x16x32_bf16 v[86:89], v[162:165], v[218:221], v[86:89]
	v_mfma_f32_16x16x32_bf16 v[82:85], v[186:189], v[218:221], v[82:85]
	v_mfma_f32_16x16x32_bf16 v[134:137], v[182:185], v[198:201], v[134:137]
	v_mfma_f32_16x16x32_bf16 v[130:133], v[190:193], v[198:201], v[130:133]
	v_mfma_f32_16x16x32_bf16 v[118:121], v[182:185], v[206:209], v[118:121]
	v_mfma_f32_16x16x32_bf16 v[114:117], v[190:193], v[206:209], v[114:117]
	v_mfma_f32_16x16x32_bf16 v[102:105], v[182:185], v[214:217], v[102:105]
	v_mfma_f32_16x16x32_bf16 v[98:101], v[190:193], v[214:217], v[98:101]
	v_mfma_f32_16x16x32_bf16 v[86:89], v[182:185], v[222:225], v[86:89]
	v_mfma_f32_16x16x32_bf16 v[82:85], v[190:193], v[222:225], v[82:85]
	s_setprio 0
	s_barrier
; #define PG8_STAGE(bufoff, gbase, voff) do { _Pragma("unroll") for (int _i = 0; _i < 2; ++_i) \
;         __builtin_amdgcn_global_load_lds((const unsigned*)((const char*)(gbase) + (voff)[_i]), (LAS unsigned*)(lds + (bufoff) + ldsw + _i * 8192), 16, 0, 0); } while (0)
; #define PG8_LDA(dst, b, h) do { _Pragma("unroll") for (int m = 0; m < 4; ++m) _Pragma("unroll") for (int k = 0; k < 2; ++k) dst[m][k] = *(const LAS bf16x8*)(lds + PG8_SA(b, h) + aoff + m * 2048 + k * 1024); } while (0)
; #define PG8_MMA(ai, bj, At, Bt) do { __builtin_amdgcn_s_setprio(1); _Pragma("unroll") for (int m = 0; m < 4; ++m) _Pragma("unroll") for (int n = 0; n < 2; ++n) _Pragma("unroll") for (int k = 0; k < 2; ++k) \
;         acc[ai][bj][m][n] = __builtin_amdgcn_mfma_f32_16x16x32_bf16(Bt[n][k], At[m][k], acc[ai][bj][m][n], 0, 0, 0); __builtin_amdgcn_s_setprio(0); } while (0)
; #define PG8_WAIT_V(n) asm volatile("s_waitcnt vmcnt(" #n ")" ::: "memory")
; #define PG8_WAIT_L(n) asm volatile("s_waitcnt lgkmcnt(" #n ")" ::: "memory")
; #define PG8_BAR __builtin_amdgcn_s_barrier()
; #define PG8_SCHED __builtin_amdgcn_sched_barrier(0)
; template <class Epi, class Sched, bool ALIGN_EPI = false, bool SP2 = false>
; __device__ __forceinline__ void gemm_phase(LAS unsigned char* lds, const Gemm g, const Sched& S, const Epi& E) {
;     ...
;         for (int t = 0; t < nt; t += 2) {
;             const bool last = (t == nt - 2);
;     ...
;             PG8_LDA(At, 1, 1); PG8_STAGE(PG8_SB(1, 0), b3, voffB); PG8_STAGE(PG8_SB(1, 1), b3 + hstepB, voffB); PG8_STAGE(PG8_SA(1, 0), a3, voffA);
;             PG8_WAIT_V(8); PG8_WAIT_L(0); PG8_BAR; PG8_MMA(1, 0, At, B0); PG8_MMA(1, 1, At, B1); PG8_BAR; PG8_SCHED;
	s_add_i32 s40, s54, s29
	v_lshl_add_u64 v[166:167], v[166:167], 0, s[8:9]
	s_mov_b32 m0, s40
	ds_read_b128 v[194:197], v176 offset:49152
	ds_read_b128 v[198:201], v176 offset:50176
	ds_read_b128 v[202:205], v176 offset:51200
	ds_read_b128 v[206:209], v176 offset:52224
	ds_read_b128 v[210:213], v176 offset:53248
	ds_read_b128 v[214:217], v176 offset:54272
	ds_read_b128 v[218:221], v176 offset:55296
	ds_read_b128 v[222:225], v176 offset:56320
	global_load_lds_dwordx4 v[166:167], off
	s_add_i32 m0, s40, 0x2000
	s_add_u32 s22, s22, 0x80080
	v_lshl_add_u64 v[166:167], v[226:227], 0, s[8:9]
	s_addc_u32 s23, s23, 0
	s_add_i32 s40, s55, s29
	global_load_lds_dwordx4 v[166:167], off
	v_lshl_add_u64 v[166:167], s[22:23], 0, v[150:151]
	s_mov_b32 m0, s40
	s_nop 0
	global_load_lds_dwordx4 v[166:167], off
	v_lshl_add_u64 v[166:167], s[22:23], 0, v[146:147]
	s_add_i32 m0, s40, 0x2000
	s_nop 0
	global_load_lds_dwordx4 v[166:167], off
	v_lshl_add_u64 v[166:167], v[228:229], 0, s[8:9]
	s_mov_b32 m0, s45
	s_nop 0
	global_load_lds_dwordx4 v[166:167], off
	v_lshl_add_u64 v[166:167], v[230:231], 0, s[8:9]
	s_mov_b32 m0, s46
	s_nop 0
	global_load_lds_dwordx4 v[166:167], off
	s_waitcnt vmcnt(8)
	s_waitcnt lgkmcnt(0)
	s_barrier
	s_setprio 1
	s_waitcnt lgkmcnt(0)
	v_mfma_f32_16x16x32_bf16 v[62:65], v[66:69], v[194:197], v[62:65]
	v_mfma_f32_16x16x32_bf16 v[58:61], v[74:77], v[194:197], v[58:61]
	v_mfma_f32_16x16x32_bf16 v[46:49], v[66:69], v[202:205], v[46:49]
	v_mfma_f32_16x16x32_bf16 v[42:45], v[74:77], v[202:205], v[42:45]
	v_mfma_f32_16x16x32_bf16 v[30:33], v[66:69], v[210:213], v[30:33]
	v_mfma_f32_16x16x32_bf16 v[26:29], v[74:77], v[210:213], v[26:29]
	v_mfma_f32_16x16x32_bf16 v[14:17], v[66:69], v[218:221], v[14:17]
	v_mfma_f32_16x16x32_bf16 v[10:13], v[74:77], v[218:221], v[10:13]
	v_mfma_f32_16x16x32_bf16 v[62:65], v[70:73], v[198:201], v[62:65]
	v_mfma_f32_16x16x32_bf16 v[58:61], v[78:81], v[198:201], v[58:61]
	v_mfma_f32_16x16x32_bf16 v[46:49], v[70:73], v[206:209], v[46:49]
	v_mfma_f32_16x16x32_bf16 v[42:45], v[78:81], v[206:209], v[42:45]
	v_mfma_f32_16x16x32_bf16 v[30:33], v[70:73], v[214:217], v[30:33]
	v_mfma_f32_16x16x32_bf16 v[26:29], v[78:81], v[214:217], v[26:29]
	v_mfma_f32_16x16x32_bf16 v[14:17], v[70:73], v[222:225], v[14:17]
	v_mfma_f32_16x16x32_bf16 v[10:13], v[78:81], v[222:225], v[10:13]
	v_mfma_f32_16x16x32_bf16 v[54:57], v[162:165], v[194:197], v[54:57]
	v_mfma_f32_16x16x32_bf16 v[50:53], v[186:189], v[194:197], v[50:53]
	v_mfma_f32_16x16x32_bf16 v[38:41], v[162:165], v[202:205], v[38:41]
	v_mfma_f32_16x16x32_bf16 v[34:37], v[186:189], v[202:205], v[34:37]
	v_mfma_f32_16x16x32_bf16 v[22:25], v[162:165], v[210:213], v[22:25]
	v_mfma_f32_16x16x32_bf16 v[18:21], v[186:189], v[210:213], v[18:21]
	v_mfma_f32_16x16x32_bf16 v[6:9], v[162:165], v[218:221], v[6:9]
	v_mfma_f32_16x16x32_bf16 v[2:5], v[186:189], v[218:221], v[2:5]
	v_mfma_f32_16x16x32_bf16 v[54:57], v[182:185], v[198:201], v[54:57]
	v_mfma_f32_16x16x32_bf16 v[50:53], v[190:193], v[198:201], v[50:53]
	v_mfma_f32_16x16x32_bf16 v[38:41], v[182:185], v[206:209], v[38:41]
	v_mfma_f32_16x16x32_bf16 v[34:37], v[190:193], v[206:209], v[34:37]
	v_mfma_f32_16x16x32_bf16 v[22:25], v[182:185], v[214:217], v[22:25]
	v_mfma_f32_16x16x32_bf16 v[18:21], v[190:193], v[214:217], v[18:21]
	v_mfma_f32_16x16x32_bf16 v[6:9], v[182:185], v[222:225], v[6:9]
	v_mfma_f32_16x16x32_bf16 v[2:5], v[190:193], v[222:225], v[2:5]
	s_setprio 0
	s_barrier
	s_add_i32 s53, s53, 2
	s_add_u32 s16, s16, 0x100
	s_addc_u32 s17, s17, 0
	s_add_u32 s25, s25, 0x100
	s_addc_u32 s52, s52, 0
	s_cmp_gt_u32 s53, 29
	s_cbranch_scc0 .LBB0_1465
	s_and_b64 vcc, exec, s[10:11]
	s_cbranch_vccz .LBB0_1468
	s_barrier

; #define PG8_STAGE(bufoff, gbase, voff) do { _Pragma("unroll") for (int _i = 0; _i < 2; ++_i) \
;         __builtin_amdgcn_global_load_lds((const unsigned*)((const char*)(gbase) + (voff)[_i]), (LAS unsigned*)(lds + (bufoff) + ldsw + _i * 8192), 16, 0, 0); } while (0)
; #define PG8_LDA(dst, b, h) do { _Pragma("unroll") for (int m = 0; m < 4; ++m) _Pragma("unroll") for (int k = 0; k < 2; ++k) dst[m][k] = *(const LAS bf16x8*)(lds + PG8_SA(b, h) + aoff + m * 2048 + k * 1024); } while (0)
; #define PG8_LDB(dst, b, h) do { _Pragma("unroll") for (int n = 0; n < 2; ++n) _Pragma("unroll") for (int k = 0; k < 2; ++k) dst[n][k] = *(const LAS bf16x8*)(lds + PG8_SB(b, h) + boff + n * 2048 + k * 1024); } while (0)
; #define PG8_MMA(ai, bj, At, Bt) do { __builtin_amdgcn_s_setprio(1); _Pragma("unroll") for (int m = 0; m < 4; ++m) _Pragma("unroll") for (int n = 0; n < 2; ++n) _Pragma("unroll") for (int k = 0; k < 2; ++k) \
;         acc[ai][bj][m][n] = __builtin_amdgcn_mfma_f32_16x16x32_bf16(Bt[n][k], At[m][k], acc[ai][bj][m][n], 0, 0, 0); __builtin_amdgcn_s_setprio(0); } while (0)
; #define PG8_WAIT_V(n) asm volatile("s_waitcnt vmcnt(" #n ")" ::: "memory")
; #define PG8_WAIT_L(n) asm volatile("s_waitcnt lgkmcnt(" #n ")" ::: "memory")
; #define PG8_BAR __builtin_amdgcn_s_barrier()
; #define PG8_SCHED __builtin_amdgcn_sched_barrier(0)
; template <class Epi, class Sched, bool ALIGN_EPI = false, bool SP2 = false>
; __device__ __forceinline__ void gemm_phase(LAS unsigned char* lds, const Gemm g, const Sched& S, const Epi& E) {
;     ...
;             if constexpr (SP2) {
;             PG8_LDB(B0, 0, 0); PG8_LDB(B1, 0, 1); PG8_SCHED; PG8_LDA(At, 0, 0); PG8_STAGE(PG8_SA(1, 1), a1 + hstep, voffA);
;             PG8_WAIT_V(8); PG8_WAIT_L(0); PG8_BAR; PG8_MMA(0, 0, At, B0); PG8_MMA(0, 1, At, B1); PG8_BAR; PG8_SCHED;
;             PG8_LDA(At, 0, 1); PG8_STAGE(PG8_SB(0, 0), b2, voffB); PG8_STAGE(PG8_SB(0, 1), b2 + hstepB, voffB); PG8_STAGE(PG8_SA(0, 0), a2, voffA);
;             PG8_WAIT_V(8); PG8_WAIT_L(0); PG8_BAR; PG8_MMA(1, 0, At, B0); PG8_MMA(1, 1, At, B1); PG8_BAR; PG8_SCHED;
.LBB0_1565:
	ds_read_b128 v[144:147], v135
	ds_read_b128 v[148:151], v135 offset:1024
	ds_read_b128 v[152:155], v135 offset:2048
	ds_read_b128 v[156:159], v135 offset:3072
	ds_read_b128 v[160:163], v140
	ds_read_b128 v[164:167], v140 offset:1024
	ds_read_b128 v[168:171], v140 offset:2048
	ds_read_b128 v[172:175], v140 offset:3072
	s_add_i32 s46, s16, 2
	s_cmp_lg_u32 s35, s16
	s_cselect_b32 s16, s12, 0
	s_cselect_b32 s17, s13, 0
	s_add_u32 s18, s8, s16
	s_addc_u32 s19, s9, s17
	s_add_u32 s16, s2, s16
	s_addc_u32 s17, s3, s17
	v_lshl_add_u64 v[208:209], v[136:137], 0, s[12:13]
	s_mov_b32 m0, s36
	v_lshl_add_u64 v[208:209], v[208:209], 0, s[14:15]
	ds_read_b128 v[176:179], v141
	ds_read_b128 v[180:183], v141 offset:1024
	ds_read_b128 v[184:187], v141 offset:2048
	ds_read_b128 v[188:191], v141 offset:3072
	ds_read_b128 v[192:195], v141 offset:4096
	ds_read_b128 v[196:199], v141 offset:5120
	ds_read_b128 v[200:203], v141 offset:6144
	ds_read_b128 v[204:207], v141 offset:7168
	global_load_lds_dwordx4 v[208:209], off
	v_lshl_add_u64 v[208:209], v[138:139], 0, s[12:13]
	v_lshl_add_u64 v[208:209], v[208:209], 0, s[14:15]
	s_mov_b32 m0, s37
	s_nop 0
	global_load_lds_dwordx4 v[208:209], off
	s_waitcnt vmcnt(8)
	s_waitcnt lgkmcnt(0)
	s_barrier
	s_setprio 1
	s_waitcnt lgkmcnt(0)
	v_mfma_f32_16x16x32_bf16 v[126:129], v[144:147], v[176:179], v[126:129]
	v_mfma_f32_16x16x32_bf16 v[94:97], v[152:155], v[176:179], v[94:97]
	v_mfma_f32_16x16x32_bf16 v[122:125], v[144:147], v[184:187], v[122:125]
	v_mfma_f32_16x16x32_bf16 v[90:93], v[152:155], v[184:187], v[90:93]
	v_mfma_f32_16x16x32_bf16 v[118:121], v[144:147], v[192:195], v[118:121]
	v_mfma_f32_16x16x32_bf16 v[86:89], v[152:155], v[192:195], v[86:89]
	v_mfma_f32_16x16x32_bf16 v[114:117], v[144:147], v[200:203], v[114:117]
	v_mfma_f32_16x16x32_bf16 v[82:85], v[152:155], v[200:203], v[82:85]
	v_mfma_f32_16x16x32_bf16 v[126:129], v[148:151], v[180:183], v[126:129]
	v_mfma_f32_16x16x32_bf16 v[94:97], v[156:159], v[180:183], v[94:97]
	v_mfma_f32_16x16x32_bf16 v[122:125], v[148:151], v[188:191], v[122:125]
	v_mfma_f32_16x16x32_bf16 v[90:93], v[156:159], v[188:191], v[90:93]
	v_mfma_f32_16x16x32_bf16 v[118:121], v[148:151], v[196:199], v[118:121]
	v_mfma_f32_16x16x32_bf16 v[86:89], v[156:159], v[196:199], v[86:89]
	v_mfma_f32_16x16x32_bf16 v[114:117], v[148:151], v[204:207], v[114:117]
	v_mfma_f32_16x16x32_bf16 v[82:85], v[156:159], v[204:207], v[82:85]
	v_mfma_f32_16x16x32_bf16 v[70:73], v[160:163], v[176:179], v[70:73]
	v_mfma_f32_16x16x32_bf16 v[42:45], v[168:171], v[176:179], v[42:45]
	v_mfma_f32_16x16x32_bf16 v[62:65], v[160:163], v[184:187], v[62:65]
	v_mfma_f32_16x16x32_bf16 v[34:37], v[168:171], v[184:187], v[34:37]
	v_mfma_f32_16x16x32_bf16 v[54:57], v[160:163], v[192:195], v[54:57]
	v_mfma_f32_16x16x32_bf16 v[26:29], v[168:171], v[192:195], v[26:29]
	v_mfma_f32_16x16x32_bf16 v[50:53], v[160:163], v[200:203], v[50:53]
	v_mfma_f32_16x16x32_bf16 v[18:21], v[168:171], v[200:203], v[18:21]
	v_mfma_f32_16x16x32_bf16 v[70:73], v[164:167], v[180:183], v[70:73]
	v_mfma_f32_16x16x32_bf16 v[42:45], v[172:175], v[180:183], v[42:45]
	v_mfma_f32_16x16x32_bf16 v[62:65], v[164:167], v[188:191], v[62:65]
	v_mfma_f32_16x16x32_bf16 v[34:37], v[172:175], v[188:191], v[34:37]
	v_mfma_f32_16x16x32_bf16 v[54:57], v[164:167], v[196:199], v[54:57]
	v_mfma_f32_16x16x32_bf16 v[26:29], v[172:175], v[196:199], v[26:29]
	v_mfma_f32_16x16x32_bf16 v[50:53], v[164:167], v[204:207], v[50:53]
	v_mfma_f32_16x16x32_bf16 v[18:21], v[172:175], v[204:207], v[18:21]
	s_setprio 0
	s_barrier
	s_mov_b32 m0, s38
	v_lshl_add_u64 v[208:209], s[16:17], 0, v[132:133]
	s_add_u32 s48, s16, 0x160000
	ds_read_b128 v[176:179], v141 offset:16384
	ds_read_b128 v[180:183], v141 offset:17408
	ds_read_b128 v[184:187], v141 offset:18432
	ds_read_b128 v[188:191], v141 offset:19456
	ds_read_b128 v[192:195], v141 offset:20480
	ds_read_b128 v[196:199], v141 offset:21504
	ds_read_b128 v[200:203], v141 offset:22528
	ds_read_b128 v[204:207], v141 offset:23552
	global_load_lds_dwordx4 v[208:209], off
	v_lshl_add_u64 v[210:211], s[16:17], 0, v[130:131]
	s_mov_b32 m0, s39
	s_addc_u32 s49, s17, 0
	global_load_lds_dwordx4 v[210:211], off
	v_lshl_add_u64 v[212:213], s[48:49], 0, v[132:133]
	s_mov_b32 m0, s40
	v_lshl_add_u64 v[214:215], s[18:19], 0, v[130:131]
	global_load_lds_dwordx4 v[212:213], off
	v_lshl_add_u64 v[212:213], s[48:49], 0, v[130:131]
	s_mov_b32 m0, s41
	s_nop 0
	global_load_lds_dwordx4 v[212:213], off
	v_lshl_add_u64 v[212:213], s[18:19], 0, v[132:133]
	s_mov_b32 m0, s22
	s_nop 0
	global_load_lds_dwordx4 v[212:213], off
	s_mov_b32 m0, s24
	s_nop 0
	global_load_lds_dwordx4 v[214:215], off
	s_waitcnt vmcnt(8)
	s_waitcnt lgkmcnt(0)
	s_barrier
; #define PG8_STAGE(bufoff, gbase, voff) do { _Pragma("unroll") for (int _i = 0; _i < 2; ++_i) \
;         __builtin_amdgcn_global_load_lds((const unsigned*)((const char*)(gbase) + (voff)[_i]), (LAS unsigned*)(lds + (bufoff) + ldsw + _i * 8192), 16, 0, 0); } while (0)
; #define PG8_LDA(dst, b, h) do { _Pragma("unroll") for (int m = 0; m < 4; ++m) _Pragma("unroll") for (int k = 0; k < 2; ++k) dst[m][k] = *(const LAS bf16x8*)(lds + PG8_SA(b, h) + aoff + m * 2048 + k * 1024); } while (0)
; #define PG8_LDB(dst, b, h) do { _Pragma("unroll") for (int n = 0; n < 2; ++n) _Pragma("unroll") for (int k = 0; k < 2; ++k) dst[n][k] = *(const LAS bf16x8*)(lds + PG8_SB(b, h) + boff + n * 2048 + k * 1024); } while (0)
; #define PG8_MMA(ai, bj, At, Bt) do { __builtin_amdgcn_s_setprio(1); _Pragma("unroll") for (int m = 0; m < 4; ++m) _Pragma("unroll") for (int n = 0; n < 2; ++n) _Pragma("unroll") for (int k = 0; k < 2; ++k) \
;         acc[ai][bj][m][n] = __builtin_amdgcn_mfma_f32_16x16x32_bf16(Bt[n][k], At[m][k], acc[ai][bj][m][n], 0, 0, 0); __builtin_amdgcn_s_setprio(0); } while (0)
; #define PG8_WAIT_V(n) asm volatile("s_waitcnt vmcnt(" #n ")" ::: "memory")
; #define PG8_WAIT_L(n) asm volatile("s_waitcnt lgkmcnt(" #n ")" ::: "memory")
; #define PG8_BAR __builtin_amdgcn_s_barrier()
; #define PG8_SCHED __builtin_amdgcn_sched_barrier(0)
; template <class Epi, class Sched, bool ALIGN_EPI = false, bool SP2 = false>
; __device__ __forceinline__ void gemm_phase(LAS unsigned char* lds, const Gemm g, const Sched& S, const Epi& E) {
;     ...
;             PG8_LDA(At, 0, 1); PG8_STAGE(PG8_SB(0, 0), b2, voffB); PG8_STAGE(PG8_SB(0, 1), b2 + hstepB, voffB); PG8_STAGE(PG8_SA(0, 0), a2, voffA);
;             PG8_WAIT_V(8); PG8_WAIT_L(0); PG8_BAR; PG8_MMA(1, 0, At, B0); PG8_MMA(1, 1, At, B1); PG8_BAR; PG8_SCHED;
;             PG8_LDB(B0, 1, 0); PG8_LDB(B1, 1, 1); PG8_SCHED; PG8_LDA(At, 1, 0); PG8_STAGE(PG8_SA(0, 1), a2 + hstep, voffA);
;             PG8_WAIT_V(8); PG8_WAIT_L(0); PG8_BAR; PG8_MMA(0, 0, At, B0); PG8_MMA(0, 1, At, B1); PG8_BAR; PG8_SCHED;
	s_setprio 1
	s_waitcnt lgkmcnt(0)
	v_mfma_f32_16x16x32_bf16 v[110:113], v[144:147], v[176:179], v[110:113]
	v_mfma_f32_16x16x32_bf16 v[78:81], v[152:155], v[176:179], v[78:81]
	v_mfma_f32_16x16x32_bf16 v[106:109], v[144:147], v[184:187], v[106:109]
	v_mfma_f32_16x16x32_bf16 v[74:77], v[152:155], v[184:187], v[74:77]
	v_mfma_f32_16x16x32_bf16 v[102:105], v[144:147], v[192:195], v[102:105]
	v_mfma_f32_16x16x32_bf16 v[66:69], v[152:155], v[192:195], v[66:69]
	v_mfma_f32_16x16x32_bf16 v[98:101], v[144:147], v[200:203], v[98:101]
	v_mfma_f32_16x16x32_bf16 v[58:61], v[152:155], v[200:203], v[58:61]
	v_mfma_f32_16x16x32_bf16 v[110:113], v[148:151], v[180:183], v[110:113]
	v_mfma_f32_16x16x32_bf16 v[78:81], v[156:159], v[180:183], v[78:81]
	v_mfma_f32_16x16x32_bf16 v[106:109], v[148:151], v[188:191], v[106:109]
	v_mfma_f32_16x16x32_bf16 v[74:77], v[156:159], v[188:191], v[74:77]
	v_mfma_f32_16x16x32_bf16 v[102:105], v[148:151], v[196:199], v[102:105]
	v_mfma_f32_16x16x32_bf16 v[66:69], v[156:159], v[196:199], v[66:69]
	v_mfma_f32_16x16x32_bf16 v[98:101], v[148:151], v[204:207], v[98:101]
	v_mfma_f32_16x16x32_bf16 v[58:61], v[156:159], v[204:207], v[58:61]
	v_mfma_f32_16x16x32_bf16 v[46:49], v[160:163], v[176:179], v[46:49]
	v_mfma_f32_16x16x32_bf16 v[14:17], v[168:171], v[176:179], v[14:17]
	v_mfma_f32_16x16x32_bf16 v[38:41], v[160:163], v[184:187], v[38:41]
	v_mfma_f32_16x16x32_bf16 v[10:13], v[168:171], v[184:187], v[10:13]
	v_mfma_f32_16x16x32_bf16 v[30:33], v[160:163], v[192:195], v[30:33]
	v_mfma_f32_16x16x32_bf16 v[6:9], v[168:171], v[192:195], v[6:9]
	v_mfma_f32_16x16x32_bf16 v[22:25], v[160:163], v[200:203], v[22:25]
	v_mfma_f32_16x16x32_bf16 v[2:5], v[168:171], v[200:203], v[2:5]
	v_mfma_f32_16x16x32_bf16 v[46:49], v[164:167], v[180:183], v[46:49]
	v_mfma_f32_16x16x32_bf16 v[14:17], v[172:175], v[180:183], v[14:17]
	v_mfma_f32_16x16x32_bf16 v[38:41], v[164:167], v[188:191], v[38:41]
	v_mfma_f32_16x16x32_bf16 v[10:13], v[172:175], v[188:191], v[10:13]
	v_mfma_f32_16x16x32_bf16 v[30:33], v[164:167], v[196:199], v[30:33]
	v_mfma_f32_16x16x32_bf16 v[6:9], v[172:175], v[196:199], v[6:9]
	v_mfma_f32_16x16x32_bf16 v[22:25], v[164:167], v[204:207], v[22:25]
	v_mfma_f32_16x16x32_bf16 v[2:5], v[172:175], v[204:207], v[2:5]
	s_setprio 0
	s_barrier
	ds_read_b128 v[144:147], v142
	ds_read_b128 v[148:151], v142 offset:1024
	ds_read_b128 v[152:155], v142 offset:2048
	ds_read_b128 v[156:159], v142 offset:3072
	ds_read_b128 v[160:163], v143
	ds_read_b128 v[164:167], v143 offset:1024
	ds_read_b128 v[168:171], v143 offset:2048
	ds_read_b128 v[172:175], v143 offset:3072
	s_add_u32 s18, s18, 0x160000
	s_addc_u32 s19, s19, 0
	s_mov_b32 m0, s25
	v_lshl_add_u64 v[216:217], s[18:19], 0, v[132:133]
	ds_read_b128 v[176:179], v141 offset:32768
	ds_read_b128 v[180:183], v141 offset:33792
	ds_read_b128 v[184:187], v141 offset:34816
	ds_read_b128 v[188:191], v141 offset:35840
	ds_read_b128 v[192:195], v141 offset:36864
	ds_read_b128 v[196:199], v141 offset:37888
	ds_read_b128 v[200:203], v141 offset:38912
	ds_read_b128 v[204:207], v141 offset:39936
	global_load_lds_dwordx4 v[216:217], off
	v_lshl_add_u64 v[216:217], s[18:19], 0, v[130:131]
	s_mov_b32 m0, s30
	s_nop 0
	global_load_lds_dwordx4 v[216:217], off
	s_waitcnt vmcnt(8)
	s_waitcnt lgkmcnt(0)
	s_barrier
	s_setprio 1
	s_waitcnt lgkmcnt(0)
	v_mfma_f32_16x16x32_bf16 v[126:129], v[144:147], v[176:179], v[126:129]
	v_mfma_f32_16x16x32_bf16 v[94:97], v[152:155], v[176:179], v[94:97]
	v_mfma_f32_16x16x32_bf16 v[122:125], v[144:147], v[184:187], v[122:125]
	v_mfma_f32_16x16x32_bf16 v[90:93], v[152:155], v[184:187], v[90:93]
	v_mfma_f32_16x16x32_bf16 v[118:121], v[144:147], v[192:195], v[118:121]
	v_mfma_f32_16x16x32_bf16 v[86:89], v[152:155], v[192:195], v[86:89]
	v_mfma_f32_16x16x32_bf16 v[114:117], v[144:147], v[200:203], v[114:117]
	v_mfma_f32_16x16x32_bf16 v[82:85], v[152:155], v[200:203], v[82:85]
	v_mfma_f32_16x16x32_bf16 v[126:129], v[148:151], v[180:183], v[126:129]
	v_mfma_f32_16x16x32_bf16 v[94:97], v[156:159], v[180:183], v[94:97]
	v_mfma_f32_16x16x32_bf16 v[122:125], v[148:151], v[188:191], v[122:125]
	v_mfma_f32_16x16x32_bf16 v[90:93], v[156:159], v[188:191], v[90:93]
	v_mfma_f32_16x16x32_bf16 v[118:121], v[148:151], v[196:199], v[118:121]
	v_mfma_f32_16x16x32_bf16 v[86:89], v[156:159], v[196:199], v[86:89]
	v_mfma_f32_16x16x32_bf16 v[114:117], v[148:151], v[204:207], v[114:117]
	v_mfma_f32_16x16x32_bf16 v[82:85], v[156:159], v[204:207], v[82:85]
	v_mfma_f32_16x16x32_bf16 v[70:73], v[160:163], v[176:179], v[70:73]
	v_mfma_f32_16x16x32_bf16 v[42:45], v[168:171], v[176:179], v[42:45]
	v_mfma_f32_16x16x32_bf16 v[62:65], v[160:163], v[184:187], v[62:65]
	v_mfma_f32_16x16x32_bf16 v[34:37], v[168:171], v[184:187], v[34:37]
	v_mfma_f32_16x16x32_bf16 v[54:57], v[160:163], v[192:195], v[54:57]
	v_mfma_f32_16x16x32_bf16 v[26:29], v[168:171], v[192:195], v[26:29]
	v_mfma_f32_16x16x32_bf16 v[50:53], v[160:163], v[200:203], v[50:53]
	v_mfma_f32_16x16x32_bf16 v[18:21], v[168:171], v[200:203], v[18:21]
	v_mfma_f32_16x16x32_bf16 v[70:73], v[164:167], v[180:183], v[70:73]
	v_mfma_f32_16x16x32_bf16 v[42:45], v[172:175], v[180:183], v[42:45]
	v_mfma_f32_16x16x32_bf16 v[62:65], v[164:167], v[188:191], v[62:65]
	v_mfma_f32_16x16x32_bf16 v[34:37], v[172:175], v[188:191], v[34:37]
	v_mfma_f32_16x16x32_bf16 v[54:57], v[164:167], v[196:199], v[54:57]
	v_mfma_f32_16x16x32_bf16 v[26:29], v[172:175], v[196:199], v[26:29]
	v_mfma_f32_16x16x32_bf16 v[50:53], v[164:167], v[204:207], v[50:53]
	v_mfma_f32_16x16x32_bf16 v[18:21], v[172:175], v[204:207], v[18:21]
	s_setprio 0
	s_barrier
;     __device__ bool next(int i, Unit& u) const { if (i != 0 || c >= 128) return false; const int t = c >> 2; u.pm = t & 3; u.pn = t >> 2; u.koff = koff_bytes; u.q = c & 3; return true; }
; #define PG8_STAGE(bufoff, gbase, voff) do { _Pragma("unroll") for (int _i = 0; _i < 2; ++_i) \
;         __builtin_amdgcn_global_load_lds((const unsigned*)((const char*)(gbase) + (voff)[_i]), (LAS unsigned*)(lds + (bufoff) + ldsw + _i * 8192), 16, 0, 0); } while (0)
; #define PG8_LDA(dst, b, h) do { _Pragma("unroll") for (int m = 0; m < 4; ++m) _Pragma("unroll") for (int k = 0; k < 2; ++k) dst[m][k] = *(const LAS bf16x8*)(lds + PG8_SA(b, h) + aoff + m * 2048 + k * 1024); } while (0)
; #define PG8_MMA(ai, bj, At, Bt) do { __builtin_amdgcn_s_setprio(1); _Pragma("unroll") for (int m = 0; m < 4; ++m) _Pragma("unroll") for (int n = 0; n < 2; ++n) _Pragma("unroll") for (int k = 0; k < 2; ++k) \
;         acc[ai][bj][m][n] = __builtin_amdgcn_mfma_f32_16x16x32_bf16(Bt[n][k], At[m][k], acc[ai][bj][m][n], 0, 0, 0); __builtin_amdgcn_s_setprio(0); } while (0)
; #define PG8_WAIT_V(n) asm volatile("s_waitcnt vmcnt(" #n ")" ::: "memory")
; #define PG8_WAIT_L(n) asm volatile("s_waitcnt lgkmcnt(" #n ")" ::: "memory")
; #define PG8_BAR __builtin_amdgcn_s_barrier()
; template <class Epi, class Sched, bool ALIGN_EPI = false, bool SP2 = false>
; __device__ __forceinline__ void gemm_phase(LAS unsigned char* lds, const Gemm g, const Sched& S, const Epi& E) {
;     ...
;     for (;;) {
;         const bool has_next = S.next(ui + 1, nxt);
;         const char* nA = has_next ? (const char*)g.A + (size_t)nxt.pm * tstep + nxt.koff : cA; const char* nB = has_next ? (const char*)g.Bt + (size_t)nxt.pn * tstep + nxt.koff : cB;
;         for (int t = 0; t < nt; t += 2) {
;             const bool last = (t == nt - 2);
;             const char* a1 = cA + (size_t)(t + 1) * kstep;
;             const char* a2 = last ? nA : cA + (size_t)(t + 2) * kstep; const char* b2 = last ? nB : cB + (size_t)(t + 2) * kstep;
;             const char* a3 = a2 + kstep; const char* b3 = b2 + kstep;
;             if (last && has_next) S.a_ready(nxt);
;     ...
;             PG8_LDA(At, 1, 1); PG8_STAGE(PG8_SB(1, 0), b3, voffB); PG8_STAGE(PG8_SB(1, 1), b3 + hstepB, voffB); PG8_STAGE(PG8_SA(1, 0), a3, voffA);
;             PG8_WAIT_V(8); PG8_WAIT_L(0); PG8_BAR; PG8_MMA(1, 0, At, B0); PG8_MMA(1, 1, At, B1); PG8_BAR; PG8_SCHED;
	s_mov_b32 m0, s42
	v_lshl_add_u64 v[208:209], v[208:209], 0, s[10:11]
	s_add_u32 s16, s16, 0x160080
	ds_read_b128 v[176:179], v141 offset:49152
	ds_read_b128 v[180:183], v141 offset:50176
	ds_read_b128 v[184:187], v141 offset:51200
	ds_read_b128 v[188:191], v141 offset:52224
	ds_read_b128 v[192:195], v141 offset:53248
	ds_read_b128 v[196:199], v141 offset:54272
	ds_read_b128 v[200:203], v141 offset:55296
	ds_read_b128 v[204:207], v141 offset:56320
	global_load_lds_dwordx4 v[208:209], off
	v_lshl_add_u64 v[208:209], v[210:211], 0, s[10:11]
	s_mov_b32 m0, s43
	s_addc_u32 s17, s17, 0
	global_load_lds_dwordx4 v[208:209], off
	v_lshl_add_u64 v[208:209], s[16:17], 0, v[132:133]
	s_mov_b32 m0, s44
	s_nop 0
	global_load_lds_dwordx4 v[208:209], off
	v_lshl_add_u64 v[208:209], s[16:17], 0, v[130:131]
	s_mov_b32 m0, s45
	s_nop 0
	global_load_lds_dwordx4 v[208:209], off
	v_lshl_add_u64 v[208:209], v[212:213], 0, s[10:11]
	s_mov_b32 m0, s33
	s_nop 0
	global_load_lds_dwordx4 v[208:209], off
	v_lshl_add_u64 v[208:209], v[214:215], 0, s[10:11]
	s_mov_b32 m0, s34
	s_nop 0
	global_load_lds_dwordx4 v[208:209], off
	s_waitcnt vmcnt(8)
	s_waitcnt lgkmcnt(0)
	s_barrier
	s_setprio 1
	s_waitcnt lgkmcnt(0)
	v_mfma_f32_16x16x32_bf16 v[110:113], v[144:147], v[176:179], v[110:113]
	v_mfma_f32_16x16x32_bf16 v[78:81], v[152:155], v[176:179], v[78:81]
	v_mfma_f32_16x16x32_bf16 v[106:109], v[144:147], v[184:187], v[106:109]
	v_mfma_f32_16x16x32_bf16 v[74:77], v[152:155], v[184:187], v[74:77]
	v_mfma_f32_16x16x32_bf16 v[102:105], v[144:147], v[192:195], v[102:105]
	v_mfma_f32_16x16x32_bf16 v[66:69], v[152:155], v[192:195], v[66:69]
	v_mfma_f32_16x16x32_bf16 v[98:101], v[144:147], v[200:203], v[98:101]
	v_mfma_f32_16x16x32_bf16 v[58:61], v[152:155], v[200:203], v[58:61]
	v_mfma_f32_16x16x32_bf16 v[110:113], v[148:151], v[180:183], v[110:113]
	v_mfma_f32_16x16x32_bf16 v[78:81], v[156:159], v[180:183], v[78:81]
	v_mfma_f32_16x16x32_bf16 v[106:109], v[148:151], v[188:191], v[106:109]
	v_mfma_f32_16x16x32_bf16 v[74:77], v[156:159], v[188:191], v[74:77]
	v_mfma_f32_16x16x32_bf16 v[102:105], v[148:151], v[196:199], v[102:105]
	v_mfma_f32_16x16x32_bf16 v[66:69], v[156:159], v[196:199], v[66:69]
	v_mfma_f32_16x16x32_bf16 v[98:101], v[148:151], v[204:207], v[98:101]
	v_mfma_f32_16x16x32_bf16 v[58:61], v[156:159], v[204:207], v[58:61]
	v_mfma_f32_16x16x32_bf16 v[46:49], v[160:163], v[176:179], v[46:49]
	v_mfma_f32_16x16x32_bf16 v[14:17], v[168:171], v[176:179], v[14:17]
	v_mfma_f32_16x16x32_bf16 v[38:41], v[160:163], v[184:187], v[38:41]
	v_mfma_f32_16x16x32_bf16 v[10:13], v[168:171], v[184:187], v[10:13]
	v_mfma_f32_16x16x32_bf16 v[30:33], v[160:163], v[192:195], v[30:33]
	v_mfma_f32_16x16x32_bf16 v[6:9], v[168:171], v[192:195], v[6:9]
	v_mfma_f32_16x16x32_bf16 v[22:25], v[160:163], v[200:203], v[22:25]
	v_mfma_f32_16x16x32_bf16 v[2:5], v[168:171], v[200:203], v[2:5]
	v_mfma_f32_16x16x32_bf16 v[46:49], v[164:167], v[180:183], v[46:49]
	v_mfma_f32_16x16x32_bf16 v[14:17], v[172:175], v[180:183], v[14:17]
	v_mfma_f32_16x16x32_bf16 v[38:41], v[164:167], v[188:191], v[38:41]
	v_mfma_f32_16x16x32_bf16 v[10:13], v[172:175], v[188:191], v[10:13]
	v_mfma_f32_16x16x32_bf16 v[30:33], v[164:167], v[196:199], v[30:33]
	v_mfma_f32_16x16x32_bf16 v[6:9], v[172:175], v[196:199], v[6:9]
	v_mfma_f32_16x16x32_bf16 v[22:25], v[164:167], v[204:207], v[22:25]
	v_mfma_f32_16x16x32_bf16 v[2:5], v[172:175], v[204:207], v[2:5]
	s_setprio 0
	s_barrier
	s_add_u32 s12, s12, 0x100
	s_addc_u32 s13, s13, 0
	s_cmp_ge_u32 s46, s31
	s_mov_b32 s16, s46
	s_cbranch_scc0 .LBB0_1565
	s_cmpk_lt_u32 s21, 0x100
	s_cbranch_scc0 .LBB0_1568
	s_barrier

; #define PG8_STAGE(bufoff, gbase, voff) do { _Pragma("unroll") for (int _i = 0; _i < 2; ++_i) \
;         __builtin_amdgcn_global_load_lds((const unsigned*)((const char*)(gbase) + (voff)[_i]), (LAS unsigned*)(lds + (bufoff) + ldsw + _i * 8192), 16, 0, 0); } while (0)
; #define PG8_LDA(dst, b, h) do { _Pragma("unroll") for (int m = 0; m < 4; ++m) _Pragma("unroll") for (int k = 0; k < 2; ++k) dst[m][k] = *(const LAS bf16x8*)(lds + PG8_SA(b, h) + aoff + m * 2048 + k * 1024); } while (0)
; #define PG8_LDB(dst, b, h) do { _Pragma("unroll") for (int n = 0; n < 2; ++n) _Pragma("unroll") for (int k = 0; k < 2; ++k) dst[n][k] = *(const LAS bf16x8*)(lds + PG8_SB(b, h) + boff + n * 2048 + k * 1024); } while (0)
; #define PG8_MMA(ai, bj, At, Bt) do { __builtin_amdgcn_s_setprio(1); _Pragma("unroll") for (int m = 0; m < 4; ++m) _Pragma("unroll") for (int n = 0; n < 2; ++n) _Pragma("unroll") for (int k = 0; k < 2; ++k) \
;         acc[ai][bj][m][n] = __builtin_amdgcn_mfma_f32_16x16x32_bf16(Bt[n][k], At[m][k], acc[ai][bj][m][n], 0, 0, 0); __builtin_amdgcn_s_setprio(0); } while (0)
; template <class Epi, class Sched, bool ALIGN_EPI = false, bool SP2 = false>
; __device__ __forceinline__ void gemm_phase(LAS unsigned char* lds, const Gemm g, const Sched& S, const Epi& E) {
;     ...
;     const char* cA = (const char*)g.A + (size_t)cur.pm * tstep + cur.koff; const char* cB = (const char*)g.Bt + (size_t)cur.pn * tstep + cur.koff;
;     S.a_ready(cur);
;     if constexpr (SP2) {
;         PG8_STAGE(PG8_SB(0, 0), cB, voffB); PG8_STAGE(PG8_SB(0, 1), cB + hstepB, voffB); PG8_STAGE(PG8_SA(0, 0), cA, voffA); PG8_STAGE(PG8_SA(0, 1), cA + hstep, voffA);
;         if (wr == 1) PG8_BAR;
;         PG8_WAIT_V(2); PG8_BAR;
;         PG8_STAGE(PG8_SB(1, 0), cB + kstep, voffB); PG8_STAGE(PG8_SA(1, 0), cA + kstep, voffA); PG8_STAGE(PG8_SB(1, 1), cB + hstepB + kstep, voffB);
;     ...
;             PG8_LDB(B0, 0, 0); PG8_LDB(B1, 0, 1); PG8_SCHED; PG8_LDA(At, 0, 0); PG8_STAGE(PG8_SA(1, 1), a1 + hstep, voffA);
;             PG8_WAIT_V(8); PG8_WAIT_L(0); PG8_BAR; PG8_MMA(0, 0, At, B0); PG8_MMA(0, 1, At, B1); PG8_BAR; PG8_SCHED;
;             PG8_LDA(At, 0, 1); PG8_STAGE(PG8_SB(0, 0), b2, voffB); PG8_STAGE(PG8_SB(0, 1), b2 + hstepB, voffB); PG8_STAGE(PG8_SA(0, 0), a2, voffA);
;             PG8_WAIT_V(8); PG8_WAIT_L(0); PG8_BAR; PG8_MMA(1, 0, At, B0); PG8_MMA(1, 1, At, B1); PG8_BAR; PG8_SCHED;
.LBB0_1594:
	s_add_u32 s9, s20, 0x100
	s_addc_u32 s24, s21, 0
	s_mov_b32 s25, -2
	s_waitcnt vmcnt(0)
	ds_read_b128 v[130:133], v196
	ds_read_b128 v[134:137], v196 offset:1024
	ds_read_b128 v[138:141], v196 offset:2048
	ds_read_b128 v[142:145], v196 offset:3072
	ds_read_b128 v[166:169], v197
	ds_read_b128 v[170:173], v197 offset:1024
	ds_read_b128 v[174:177], v197 offset:2048
	ds_read_b128 v[178:181], v197 offset:3072
	s_add_u32 s20, s16, 0x100
	s_addc_u32 s21, s17, 0
	s_cmpk_eq_i32 s25, 0x54
	s_cselect_b32 s47, s3, s21
	s_cselect_b32 s46, s2, s20
	s_cselect_b32 s23, s19, s24
	s_cselect_b32 s22, s18, s9
	v_lshl_add_u64 v[190:191], s[16:17], 0, v[158:159]
	s_add_i32 m0, s31, 0xc000
	ds_read_b128 v[182:185], v198
	ds_read_b128 v[186:189], v198 offset:1024
	ds_read_b128 v[202:205], v198 offset:2048
	ds_read_b128 v[206:209], v198 offset:3072
	ds_read_b128 v[210:213], v198 offset:4096
	ds_read_b128 v[214:217], v198 offset:5120
	ds_read_b128 v[218:221], v198 offset:6144
	ds_read_b128 v[222:225], v198 offset:7168
	global_load_lds_dwordx4 v[190:191], off
	v_lshl_add_u64 v[190:191], s[16:17], 0, v[160:161]
	s_add_i32 m0, s31, 0xe000
	s_nop 0
	global_load_lds_dwordx4 v[190:191], off
	s_waitcnt lgkmcnt(0)
	s_barrier
	s_setprio 1
	s_waitcnt lgkmcnt(0)
	v_mfma_f32_16x16x32_bf16 v[126:129], v[130:133], v[182:185], 0
	v_mfma_f32_16x16x32_bf16 v[122:125], v[138:141], v[182:185], 0
	v_mfma_f32_16x16x32_bf16 v[110:113], v[130:133], v[202:205], 0
	v_mfma_f32_16x16x32_bf16 v[106:109], v[138:141], v[202:205], 0
	v_mfma_f32_16x16x32_bf16 v[94:97], v[130:133], v[210:213], 0
	v_mfma_f32_16x16x32_bf16 v[90:93], v[138:141], v[210:213], 0
	v_mfma_f32_16x16x32_bf16 v[78:81], v[130:133], v[218:221], 0
	v_mfma_f32_16x16x32_bf16 v[74:77], v[138:141], v[218:221], 0
	v_mfma_f32_16x16x32_bf16 v[126:129], v[134:137], v[186:189], v[126:129]
	v_mfma_f32_16x16x32_bf16 v[122:125], v[142:145], v[186:189], v[122:125]
	v_mfma_f32_16x16x32_bf16 v[110:113], v[134:137], v[206:209], v[110:113]
	v_mfma_f32_16x16x32_bf16 v[106:109], v[142:145], v[206:209], v[106:109]
	v_mfma_f32_16x16x32_bf16 v[94:97], v[134:137], v[214:217], v[94:97]
	v_mfma_f32_16x16x32_bf16 v[90:93], v[142:145], v[214:217], v[90:93]
	v_mfma_f32_16x16x32_bf16 v[78:81], v[134:137], v[222:225], v[78:81]
	v_mfma_f32_16x16x32_bf16 v[74:77], v[142:145], v[222:225], v[74:77]
	v_mfma_f32_16x16x32_bf16 v[118:121], v[166:169], v[182:185], 0
	v_mfma_f32_16x16x32_bf16 v[114:117], v[174:177], v[182:185], 0
	v_mfma_f32_16x16x32_bf16 v[102:105], v[166:169], v[202:205], 0
	v_mfma_f32_16x16x32_bf16 v[98:101], v[174:177], v[202:205], 0
	v_mfma_f32_16x16x32_bf16 v[86:89], v[166:169], v[210:213], 0
	v_mfma_f32_16x16x32_bf16 v[82:85], v[174:177], v[210:213], 0
	v_mfma_f32_16x16x32_bf16 v[70:73], v[166:169], v[218:221], 0
	v_mfma_f32_16x16x32_bf16 v[66:69], v[174:177], v[218:221], 0
	v_mfma_f32_16x16x32_bf16 v[118:121], v[170:173], v[186:189], v[118:121]
	v_mfma_f32_16x16x32_bf16 v[114:117], v[178:181], v[186:189], v[114:117]
	v_mfma_f32_16x16x32_bf16 v[102:105], v[170:173], v[206:209], v[102:105]
	v_mfma_f32_16x16x32_bf16 v[98:101], v[178:181], v[206:209], v[98:101]
	v_mfma_f32_16x16x32_bf16 v[86:89], v[170:173], v[214:217], v[86:89]
	v_mfma_f32_16x16x32_bf16 v[82:85], v[178:181], v[214:217], v[82:85]
	v_mfma_f32_16x16x32_bf16 v[70:73], v[170:173], v[222:225], v[70:73]
	v_mfma_f32_16x16x32_bf16 v[66:69], v[178:181], v[222:225], v[66:69]
	s_setprio 0
	s_barrier
	s_add_i32 s16, s52, s30
	v_lshl_add_u64 v[190:191], s[22:23], 0, v[148:149]
	s_mov_b32 m0, s16
	ds_read_b128 v[182:185], v198 offset:16384
	ds_read_b128 v[186:189], v198 offset:17408
	ds_read_b128 v[202:205], v198 offset:18432
	ds_read_b128 v[206:209], v198 offset:19456
	ds_read_b128 v[210:213], v198 offset:20480
	ds_read_b128 v[214:217], v198 offset:21504
	ds_read_b128 v[218:221], v198 offset:22528
	ds_read_b128 v[222:225], v198 offset:23552
	global_load_lds_dwordx4 v[190:191], off
	s_add_i32 m0, s16, 0x2000
	s_add_u32 s16, s22, 0x58000
	v_lshl_add_u64 v[226:227], s[22:23], 0, v[152:153]
	s_addc_u32 s17, s23, 0
	s_add_i32 s56, s53, s30
	global_load_lds_dwordx4 v[226:227], off
	v_lshl_add_u64 v[228:229], s[16:17], 0, v[148:149]
	s_mov_b32 m0, s56
	v_lshl_add_u64 v[230:231], s[46:47], 0, v[150:151]
	global_load_lds_dwordx4 v[228:229], off
	v_lshl_add_u64 v[228:229], s[16:17], 0, v[152:153]
	s_add_i32 m0, s56, 0x2000
	s_nop 0
	global_load_lds_dwordx4 v[228:229], off
	v_lshl_add_u64 v[228:229], s[46:47], 0, v[146:147]
	s_mov_b32 m0, s31
	s_nop 0
	global_load_lds_dwordx4 v[228:229], off
	s_mov_b32 m0, s33
	s_nop 0
	global_load_lds_dwordx4 v[230:231], off
	s_waitcnt lgkmcnt(0)
	s_barrier
; #define PG8_STAGE(bufoff, gbase, voff) do { _Pragma("unroll") for (int _i = 0; _i < 2; ++_i) \
;         __builtin_amdgcn_global_load_lds((const unsigned*)((const char*)(gbase) + (voff)[_i]), (LAS unsigned*)(lds + (bufoff) + ldsw + _i * 8192), 16, 0, 0); } while (0)
; #define PG8_LDA(dst, b, h) do { _Pragma("unroll") for (int m = 0; m < 4; ++m) _Pragma("unroll") for (int k = 0; k < 2; ++k) dst[m][k] = *(const LAS bf16x8*)(lds + PG8_SA(b, h) + aoff + m * 2048 + k * 1024); } while (0)
; #define PG8_LDB(dst, b, h) do { _Pragma("unroll") for (int n = 0; n < 2; ++n) _Pragma("unroll") for (int k = 0; k < 2; ++k) dst[n][k] = *(const LAS bf16x8*)(lds + PG8_SB(b, h) + boff + n * 2048 + k * 1024); } while (0)
; #define PG8_MMA(ai, bj, At, Bt) do { __builtin_amdgcn_s_setprio(1); _Pragma("unroll") for (int m = 0; m < 4; ++m) _Pragma("unroll") for (int n = 0; n < 2; ++n) _Pragma("unroll") for (int k = 0; k < 2; ++k) \
;         acc[ai][bj][m][n] = __builtin_amdgcn_mfma_f32_16x16x32_bf16(Bt[n][k], At[m][k], acc[ai][bj][m][n], 0, 0, 0); __builtin_amdgcn_s_setprio(0); } while (0)
; #define PG8_WAIT_V(n) asm volatile("s_waitcnt vmcnt(" #n ")" ::: "memory")
; #define PG8_WAIT_L(n) asm volatile("s_waitcnt lgkmcnt(" #n ")" ::: "memory")
; #define PG8_BAR __builtin_amdgcn_s_barrier()
; #define PG8_SCHED __builtin_amdgcn_sched_barrier(0)
; template <class Epi, class Sched, bool ALIGN_EPI = false, bool SP2 = false>
; __device__ __forceinline__ void gemm_phase(LAS unsigned char* lds, const Gemm g, const Sched& S, const Epi& E) {
;     ...
;             PG8_LDA(At, 0, 1); PG8_STAGE(PG8_SB(0, 0), b2, voffB); PG8_STAGE(PG8_SB(0, 1), b2 + hstepB, voffB); PG8_STAGE(PG8_SA(0, 0), a2, voffA);
;             PG8_WAIT_V(8); PG8_WAIT_L(0); PG8_BAR; PG8_MMA(1, 0, At, B0); PG8_MMA(1, 1, At, B1); PG8_BAR; PG8_SCHED;
;             PG8_LDB(B0, 1, 0); PG8_LDB(B1, 1, 1); PG8_SCHED; PG8_LDA(At, 1, 0); PG8_STAGE(PG8_SA(0, 1), a2 + hstep, voffA);
;             PG8_WAIT_V(8); PG8_WAIT_L(0); PG8_BAR; PG8_MMA(0, 0, At, B0); PG8_MMA(0, 1, At, B1); PG8_BAR; PG8_SCHED;
	s_setprio 1
	s_waitcnt lgkmcnt(0)
	v_mfma_f32_16x16x32_bf16 v[62:65], v[130:133], v[182:185], 0
	v_mfma_f32_16x16x32_bf16 v[58:61], v[138:141], v[182:185], 0
	v_mfma_f32_16x16x32_bf16 v[46:49], v[130:133], v[202:205], 0
	v_mfma_f32_16x16x32_bf16 v[42:45], v[138:141], v[202:205], 0
	v_mfma_f32_16x16x32_bf16 v[30:33], v[130:133], v[210:213], 0
	v_mfma_f32_16x16x32_bf16 v[26:29], v[138:141], v[210:213], 0
	v_mfma_f32_16x16x32_bf16 v[14:17], v[130:133], v[218:221], 0
	v_mfma_f32_16x16x32_bf16 v[10:13], v[138:141], v[218:221], 0
	v_mfma_f32_16x16x32_bf16 v[62:65], v[134:137], v[186:189], v[62:65]
	v_mfma_f32_16x16x32_bf16 v[58:61], v[142:145], v[186:189], v[58:61]
	v_mfma_f32_16x16x32_bf16 v[46:49], v[134:137], v[206:209], v[46:49]
	v_mfma_f32_16x16x32_bf16 v[42:45], v[142:145], v[206:209], v[42:45]
	v_mfma_f32_16x16x32_bf16 v[30:33], v[134:137], v[214:217], v[30:33]
	v_mfma_f32_16x16x32_bf16 v[26:29], v[142:145], v[214:217], v[26:29]
	v_mfma_f32_16x16x32_bf16 v[14:17], v[134:137], v[222:225], v[14:17]
	v_mfma_f32_16x16x32_bf16 v[10:13], v[142:145], v[222:225], v[10:13]
	v_mfma_f32_16x16x32_bf16 v[54:57], v[166:169], v[182:185], 0
	v_mfma_f32_16x16x32_bf16 v[50:53], v[174:177], v[182:185], 0
	v_mfma_f32_16x16x32_bf16 v[38:41], v[166:169], v[202:205], 0
	v_mfma_f32_16x16x32_bf16 v[34:37], v[174:177], v[202:205], 0
	v_mfma_f32_16x16x32_bf16 v[22:25], v[166:169], v[210:213], 0
	v_mfma_f32_16x16x32_bf16 v[18:21], v[174:177], v[210:213], 0
	v_mfma_f32_16x16x32_bf16 v[6:9], v[166:169], v[218:221], 0
	v_mfma_f32_16x16x32_bf16 v[2:5], v[174:177], v[218:221], 0
	v_mfma_f32_16x16x32_bf16 v[54:57], v[170:173], v[186:189], v[54:57]
	v_mfma_f32_16x16x32_bf16 v[50:53], v[178:181], v[186:189], v[50:53]
	v_mfma_f32_16x16x32_bf16 v[38:41], v[170:173], v[206:209], v[38:41]
	v_mfma_f32_16x16x32_bf16 v[34:37], v[178:181], v[206:209], v[34:37]
	v_mfma_f32_16x16x32_bf16 v[22:25], v[170:173], v[214:217], v[22:25]
	v_mfma_f32_16x16x32_bf16 v[18:21], v[178:181], v[214:217], v[18:21]
	v_mfma_f32_16x16x32_bf16 v[6:9], v[170:173], v[222:225], v[6:9]
	v_mfma_f32_16x16x32_bf16 v[2:5], v[178:181], v[222:225], v[2:5]
	s_setprio 0
	s_barrier
	s_add_i32 s56, 0, 0x18000
	s_add_i32 s57, 0, 0x1c000
	v_add_u32_e32 v142, s56, v1
	v_add_u32_e32 v154, s57, v1
	ds_read_b128 v[130:133], v142
	ds_read_b128 v[134:137], v142 offset:1024
	ds_read_b128 v[138:141], v142 offset:2048
	ds_read_b128 v[142:145], v142 offset:3072
	ds_read_b128 v[166:169], v154
	ds_read_b128 v[170:173], v154 offset:1024
	ds_read_b128 v[174:177], v154 offset:2048
	ds_read_b128 v[178:181], v154 offset:3072
	s_add_u32 s16, s46, 0x160000
	s_addc_u32 s17, s47, 0
	s_mov_b32 m0, s34
	v_lshl_add_u64 v[232:233], s[16:17], 0, v[146:147]
	ds_read_b128 v[182:185], v198 offset:32768
	ds_read_b128 v[186:189], v198 offset:33792
	ds_read_b128 v[202:205], v198 offset:34816
	ds_read_b128 v[206:209], v198 offset:35840
	ds_read_b128 v[210:213], v198 offset:36864
	ds_read_b128 v[214:217], v198 offset:37888
	ds_read_b128 v[218:221], v198 offset:38912
	ds_read_b128 v[222:225], v198 offset:39936
	global_load_lds_dwordx4 v[232:233], off
	v_lshl_add_u64 v[232:233], s[16:17], 0, v[150:151]
	s_mov_b32 m0, s35
	s_nop 0
	global_load_lds_dwordx4 v[232:233], off
	s_waitcnt vmcnt(8)
	s_waitcnt lgkmcnt(0)
	s_barrier
	s_setprio 1
	s_waitcnt lgkmcnt(0)
	v_mfma_f32_16x16x32_bf16 v[126:129], v[130:133], v[182:185], v[126:129]
	v_mfma_f32_16x16x32_bf16 v[122:125], v[138:141], v[182:185], v[122:125]
	v_mfma_f32_16x16x32_bf16 v[110:113], v[130:133], v[202:205], v[110:113]
	v_mfma_f32_16x16x32_bf16 v[106:109], v[138:141], v[202:205], v[106:109]
	v_mfma_f32_16x16x32_bf16 v[94:97], v[130:133], v[210:213], v[94:97]
	v_mfma_f32_16x16x32_bf16 v[90:93], v[138:141], v[210:213], v[90:93]
	v_mfma_f32_16x16x32_bf16 v[78:81], v[130:133], v[218:221], v[78:81]
	v_mfma_f32_16x16x32_bf16 v[74:77], v[138:141], v[218:221], v[74:77]
	v_mfma_f32_16x16x32_bf16 v[126:129], v[134:137], v[186:189], v[126:129]
	v_mfma_f32_16x16x32_bf16 v[122:125], v[142:145], v[186:189], v[122:125]
	v_mfma_f32_16x16x32_bf16 v[110:113], v[134:137], v[206:209], v[110:113]
	v_mfma_f32_16x16x32_bf16 v[106:109], v[142:145], v[206:209], v[106:109]
	v_mfma_f32_16x16x32_bf16 v[94:97], v[134:137], v[214:217], v[94:97]
	v_mfma_f32_16x16x32_bf16 v[90:93], v[142:145], v[214:217], v[90:93]
	v_mfma_f32_16x16x32_bf16 v[78:81], v[134:137], v[222:225], v[78:81]
	v_mfma_f32_16x16x32_bf16 v[74:77], v[142:145], v[222:225], v[74:77]
	v_mfma_f32_16x16x32_bf16 v[118:121], v[166:169], v[182:185], v[118:121]
	v_mfma_f32_16x16x32_bf16 v[114:117], v[174:177], v[182:185], v[114:117]
	v_mfma_f32_16x16x32_bf16 v[102:105], v[166:169], v[202:205], v[102:105]
	v_mfma_f32_16x16x32_bf16 v[98:101], v[174:177], v[202:205], v[98:101]
	v_mfma_f32_16x16x32_bf16 v[86:89], v[166:169], v[210:213], v[86:89]
	v_mfma_f32_16x16x32_bf16 v[82:85], v[174:177], v[210:213], v[82:85]
	v_mfma_f32_16x16x32_bf16 v[70:73], v[166:169], v[218:221], v[70:73]
	v_mfma_f32_16x16x32_bf16 v[66:69], v[174:177], v[218:221], v[66:69]
	v_mfma_f32_16x16x32_bf16 v[118:121], v[170:173], v[186:189], v[118:121]
	v_mfma_f32_16x16x32_bf16 v[114:117], v[178:181], v[186:189], v[114:117]
	v_mfma_f32_16x16x32_bf16 v[102:105], v[170:173], v[206:209], v[102:105]
	v_mfma_f32_16x16x32_bf16 v[98:101], v[178:181], v[206:209], v[98:101]
	v_mfma_f32_16x16x32_bf16 v[86:89], v[170:173], v[214:217], v[86:89]
	v_mfma_f32_16x16x32_bf16 v[82:85], v[178:181], v[214:217], v[82:85]
	v_mfma_f32_16x16x32_bf16 v[70:73], v[170:173], v[222:225], v[70:73]
	v_mfma_f32_16x16x32_bf16 v[66:69], v[178:181], v[222:225], v[66:69]
	s_setprio 0
	s_barrier
; #define PG8_STAGE(bufoff, gbase, voff) do { _Pragma("unroll") for (int _i = 0; _i < 2; ++_i) \
;         __builtin_amdgcn_global_load_lds((const unsigned*)((const char*)(gbase) + (voff)[_i]), (LAS unsigned*)(lds + (bufoff) + ldsw + _i * 8192), 16, 0, 0); } while (0)
; #define PG8_LDA(dst, b, h) do { _Pragma("unroll") for (int m = 0; m < 4; ++m) _Pragma("unroll") for (int k = 0; k < 2; ++k) dst[m][k] = *(const LAS bf16x8*)(lds + PG8_SA(b, h) + aoff + m * 2048 + k * 1024); } while (0)
; #define PG8_MMA(ai, bj, At, Bt) do { __builtin_amdgcn_s_setprio(1); _Pragma("unroll") for (int m = 0; m < 4; ++m) _Pragma("unroll") for (int n = 0; n < 2; ++n) _Pragma("unroll") for (int k = 0; k < 2; ++k) \
;         acc[ai][bj][m][n] = __builtin_amdgcn_mfma_f32_16x16x32_bf16(Bt[n][k], At[m][k], acc[ai][bj][m][n], 0, 0, 0); __builtin_amdgcn_s_setprio(0); } while (0)
; #define PG8_WAIT_V(n) asm volatile("s_waitcnt vmcnt(" #n ")" ::: "memory")
; #define PG8_WAIT_L(n) asm volatile("s_waitcnt lgkmcnt(" #n ")" ::: "memory")
; #define PG8_BAR __builtin_amdgcn_s_barrier()
; #define PG8_SCHED __builtin_amdgcn_sched_barrier(0)
; template <class Epi, class Sched, bool ALIGN_EPI = false, bool SP2 = false>
; __device__ __forceinline__ void gemm_phase(LAS unsigned char* lds, const Gemm g, const Sched& S, const Epi& E) {
;     ...
;         for (int t = 0; t < nt; t += 2) {
;             const bool last = (t == nt - 2);
;             const char* a1 = cA + (size_t)(t + 1) * kstep;
;             const char* a2 = last ? nA : cA + (size_t)(t + 2) * kstep; const char* b2 = last ? nB : cB + (size_t)(t + 2) * kstep;
;             const char* a3 = a2 + kstep; const char* b3 = b2 + kstep;
;             if (last && has_next) S.a_ready(nxt);
;     ...
;             PG8_LDA(At, 1, 1); PG8_STAGE(PG8_SB(1, 0), b3, voffB); PG8_STAGE(PG8_SB(1, 1), b3 + hstepB, voffB); PG8_STAGE(PG8_SA(1, 0), a3, voffA);
;             PG8_WAIT_V(8); PG8_WAIT_L(0); PG8_BAR; PG8_MMA(1, 0, At, B0); PG8_MMA(1, 1, At, B1); PG8_BAR; PG8_SCHED;
	s_add_i32 s16, s56, s30
	v_lshl_add_u64 v[190:191], v[190:191], 0, s[12:13]
	s_mov_b32 m0, s16
	ds_read_b128 v[182:185], v198 offset:49152
	ds_read_b128 v[186:189], v198 offset:50176
	ds_read_b128 v[202:205], v198 offset:51200
	ds_read_b128 v[206:209], v198 offset:52224
	ds_read_b128 v[210:213], v198 offset:53248
	ds_read_b128 v[214:217], v198 offset:54272
	ds_read_b128 v[218:221], v198 offset:55296
	ds_read_b128 v[222:225], v198 offset:56320
	global_load_lds_dwordx4 v[190:191], off
	s_add_i32 m0, s16, 0x2000
	s_add_u32 s16, s22, 0x58080
	v_lshl_add_u64 v[190:191], v[226:227], 0, s[12:13]
	s_addc_u32 s17, s23, 0
	s_add_i32 s22, s57, s30
	global_load_lds_dwordx4 v[190:191], off
	v_lshl_add_u64 v[190:191], s[16:17], 0, v[148:149]
	s_mov_b32 m0, s22
	s_nop 0
	global_load_lds_dwordx4 v[190:191], off
	v_lshl_add_u64 v[190:191], s[16:17], 0, v[152:153]
	s_add_i32 m0, s22, 0x2000
	s_nop 0
	global_load_lds_dwordx4 v[190:191], off
	v_lshl_add_u64 v[190:191], v[228:229], 0, s[12:13]
	s_mov_b32 m0, s49
	s_nop 0
	global_load_lds_dwordx4 v[190:191], off
	v_lshl_add_u64 v[190:191], v[230:231], 0, s[12:13]
	s_mov_b32 m0, s50
	s_nop 0
	global_load_lds_dwordx4 v[190:191], off
	s_waitcnt vmcnt(8)
	s_waitcnt lgkmcnt(0)
	s_barrier
	s_setprio 1
	s_waitcnt lgkmcnt(0)
	v_mfma_f32_16x16x32_bf16 v[62:65], v[130:133], v[182:185], v[62:65]
	v_mfma_f32_16x16x32_bf16 v[58:61], v[138:141], v[182:185], v[58:61]
	v_mfma_f32_16x16x32_bf16 v[46:49], v[130:133], v[202:205], v[46:49]
	v_mfma_f32_16x16x32_bf16 v[42:45], v[138:141], v[202:205], v[42:45]
	v_mfma_f32_16x16x32_bf16 v[30:33], v[130:133], v[210:213], v[30:33]
	v_mfma_f32_16x16x32_bf16 v[26:29], v[138:141], v[210:213], v[26:29]
	v_mfma_f32_16x16x32_bf16 v[14:17], v[130:133], v[218:221], v[14:17]
	v_mfma_f32_16x16x32_bf16 v[10:13], v[138:141], v[218:221], v[10:13]
	v_mfma_f32_16x16x32_bf16 v[62:65], v[134:137], v[186:189], v[62:65]
	v_mfma_f32_16x16x32_bf16 v[58:61], v[142:145], v[186:189], v[58:61]
	v_mfma_f32_16x16x32_bf16 v[46:49], v[134:137], v[206:209], v[46:49]
	v_mfma_f32_16x16x32_bf16 v[42:45], v[142:145], v[206:209], v[42:45]
	v_mfma_f32_16x16x32_bf16 v[30:33], v[134:137], v[214:217], v[30:33]
	v_mfma_f32_16x16x32_bf16 v[26:29], v[142:145], v[214:217], v[26:29]
	v_mfma_f32_16x16x32_bf16 v[14:17], v[134:137], v[222:225], v[14:17]
	v_mfma_f32_16x16x32_bf16 v[10:13], v[142:145], v[222:225], v[10:13]
	v_mfma_f32_16x16x32_bf16 v[54:57], v[166:169], v[182:185], v[54:57]
	v_mfma_f32_16x16x32_bf16 v[50:53], v[174:177], v[182:185], v[50:53]
	v_mfma_f32_16x16x32_bf16 v[38:41], v[166:169], v[202:205], v[38:41]
	v_mfma_f32_16x16x32_bf16 v[34:37], v[174:177], v[202:205], v[34:37]
	v_mfma_f32_16x16x32_bf16 v[22:25], v[166:169], v[210:213], v[22:25]
	v_mfma_f32_16x16x32_bf16 v[18:21], v[174:177], v[210:213], v[18:21]
	v_mfma_f32_16x16x32_bf16 v[6:9], v[166:169], v[218:221], v[6:9]
	v_mfma_f32_16x16x32_bf16 v[2:5], v[174:177], v[218:221], v[2:5]
	v_mfma_f32_16x16x32_bf16 v[54:57], v[170:173], v[186:189], v[54:57]
	v_mfma_f32_16x16x32_bf16 v[50:53], v[178:181], v[186:189], v[50:53]
	v_mfma_f32_16x16x32_bf16 v[38:41], v[170:173], v[206:209], v[38:41]
	v_mfma_f32_16x16x32_bf16 v[34:37], v[178:181], v[206:209], v[34:37]
	v_mfma_f32_16x16x32_bf16 v[22:25], v[170:173], v[214:217], v[22:25]
	v_mfma_f32_16x16x32_bf16 v[18:21], v[178:181], v[214:217], v[18:21]
	v_mfma_f32_16x16x32_bf16 v[6:9], v[170:173], v[222:225], v[6:9]
	v_mfma_f32_16x16x32_bf16 v[2:5], v[178:181], v[222:225], v[2:5]
	s_setprio 0
	s_barrier
	s_add_i32 s25, s25, 2
	s_add_u32 s9, s9, 0x100
	s_addc_u32 s24, s24, 0
	s_cmpk_gt_u32 s25, 0x55
	s_mov_b64 s[16:17], s[20:21]
.LBB0_1595:
	ds_read_b128 v[130:133], v196
	ds_read_b128 v[134:137], v196 offset:1024
	ds_read_b128 v[138:141], v196 offset:2048
	ds_read_b128 v[142:145], v196 offset:3072
	ds_read_b128 v[166:169], v197
	ds_read_b128 v[170:173], v197 offset:1024
	ds_read_b128 v[174:177], v197 offset:2048
	ds_read_b128 v[178:181], v197 offset:3072
	s_add_u32 s20, s16, 0x100
	s_addc_u32 s21, s17, 0
	s_cmpk_eq_i32 s25, 0x54
	s_cselect_b32 s47, s3, s21
	s_cselect_b32 s46, s2, s20
	s_cselect_b32 s23, s19, s24
	s_cselect_b32 s22, s18, s9
	v_lshl_add_u64 v[190:191], s[16:17], 0, v[158:159]
	s_add_i32 m0, s31, 0xc000
	ds_read_b128 v[182:185], v198
	ds_read_b128 v[186:189], v198 offset:1024
	ds_read_b128 v[202:205], v198 offset:2048
	ds_read_b128 v[206:209], v198 offset:3072
	ds_read_b128 v[210:213], v198 offset:4096
	ds_read_b128 v[214:217], v198 offset:5120
	ds_read_b128 v[218:221], v198 offset:6144
	ds_read_b128 v[222:225], v198 offset:7168
	global_load_lds_dwordx4 v[190:191], off
	v_lshl_add_u64 v[190:191], s[16:17], 0, v[160:161]
	s_add_i32 m0, s31, 0xe000
	s_nop 0
	global_load_lds_dwordx4 v[190:191], off
	s_waitcnt vmcnt(8)
	s_waitcnt lgkmcnt(0)
	s_barrier
; #define PG8_STAGE(bufoff, gbase, voff) do { _Pragma("unroll") for (int _i = 0; _i < 2; ++_i) \
;         __builtin_amdgcn_global_load_lds((const unsigned*)((const char*)(gbase) + (voff)[_i]), (LAS unsigned*)(lds + (bufoff) + ldsw + _i * 8192), 16, 0, 0); } while (0)
; #define PG8_LDA(dst, b, h) do { _Pragma("unroll") for (int m = 0; m < 4; ++m) _Pragma("unroll") for (int k = 0; k < 2; ++k) dst[m][k] = *(const LAS bf16x8*)(lds + PG8_SA(b, h) + aoff + m * 2048 + k * 1024); } while (0)
; #define PG8_LDB(dst, b, h) do { _Pragma("unroll") for (int n = 0; n < 2; ++n) _Pragma("unroll") for (int k = 0; k < 2; ++k) dst[n][k] = *(const LAS bf16x8*)(lds + PG8_SB(b, h) + boff + n * 2048 + k * 1024); } while (0)
; #define PG8_MMA(ai, bj, At, Bt) do { __builtin_amdgcn_s_setprio(1); _Pragma("unroll") for (int m = 0; m < 4; ++m) _Pragma("unroll") for (int n = 0; n < 2; ++n) _Pragma("unroll") for (int k = 0; k < 2; ++k) \
;         acc[ai][bj][m][n] = __builtin_amdgcn_mfma_f32_16x16x32_bf16(Bt[n][k], At[m][k], acc[ai][bj][m][n], 0, 0, 0); __builtin_amdgcn_s_setprio(0); } while (0)
; #define PG8_WAIT_V(n) asm volatile("s_waitcnt vmcnt(" #n ")" ::: "memory")
; #define PG8_WAIT_L(n) asm volatile("s_waitcnt lgkmcnt(" #n ")" ::: "memory")
; #define PG8_BAR __builtin_amdgcn_s_barrier()
; #define PG8_SCHED __builtin_amdgcn_sched_barrier(0)
; template <class Epi, class Sched, bool ALIGN_EPI = false, bool SP2 = false>
; __device__ __forceinline__ void gemm_phase(LAS unsigned char* lds, const Gemm g, const Sched& S, const Epi& E) {
;     ...
;             PG8_LDB(B0, 0, 0); PG8_LDB(B1, 0, 1); PG8_SCHED; PG8_LDA(At, 0, 0); PG8_STAGE(PG8_SA(1, 1), a1 + hstep, voffA);
;             PG8_WAIT_V(8); PG8_WAIT_L(0); PG8_BAR; PG8_MMA(0, 0, At, B0); PG8_MMA(0, 1, At, B1); PG8_BAR; PG8_SCHED;
;             PG8_LDA(At, 0, 1); PG8_STAGE(PG8_SB(0, 0), b2, voffB); PG8_STAGE(PG8_SB(0, 1), b2 + hstepB, voffB); PG8_STAGE(PG8_SA(0, 0), a2, voffA);
;             PG8_WAIT_V(8); PG8_WAIT_L(0); PG8_BAR; PG8_MMA(1, 0, At, B0); PG8_MMA(1, 1, At, B1); PG8_BAR; PG8_SCHED;
	s_setprio 1
	s_waitcnt lgkmcnt(0)
	v_mfma_f32_16x16x32_bf16 v[126:129], v[130:133], v[182:185], v[126:129]
	v_mfma_f32_16x16x32_bf16 v[122:125], v[138:141], v[182:185], v[122:125]
	v_mfma_f32_16x16x32_bf16 v[110:113], v[130:133], v[202:205], v[110:113]
	v_mfma_f32_16x16x32_bf16 v[106:109], v[138:141], v[202:205], v[106:109]
	v_mfma_f32_16x16x32_bf16 v[94:97], v[130:133], v[210:213], v[94:97]
	v_mfma_f32_16x16x32_bf16 v[90:93], v[138:141], v[210:213], v[90:93]
	v_mfma_f32_16x16x32_bf16 v[78:81], v[130:133], v[218:221], v[78:81]
	v_mfma_f32_16x16x32_bf16 v[74:77], v[138:141], v[218:221], v[74:77]
	v_mfma_f32_16x16x32_bf16 v[126:129], v[134:137], v[186:189], v[126:129]
	v_mfma_f32_16x16x32_bf16 v[122:125], v[142:145], v[186:189], v[122:125]
	v_mfma_f32_16x16x32_bf16 v[110:113], v[134:137], v[206:209], v[110:113]
	v_mfma_f32_16x16x32_bf16 v[106:109], v[142:145], v[206:209], v[106:109]
	v_mfma_f32_16x16x32_bf16 v[94:97], v[134:137], v[214:217], v[94:97]
	v_mfma_f32_16x16x32_bf16 v[90:93], v[142:145], v[214:217], v[90:93]
	v_mfma_f32_16x16x32_bf16 v[78:81], v[134:137], v[222:225], v[78:81]
	v_mfma_f32_16x16x32_bf16 v[74:77], v[142:145], v[222:225], v[74:77]
	v_mfma_f32_16x16x32_bf16 v[118:121], v[166:169], v[182:185], v[118:121]
	v_mfma_f32_16x16x32_bf16 v[114:117], v[174:177], v[182:185], v[114:117]
	v_mfma_f32_16x16x32_bf16 v[102:105], v[166:169], v[202:205], v[102:105]
	v_mfma_f32_16x16x32_bf16 v[98:101], v[174:177], v[202:205], v[98:101]
	v_mfma_f32_16x16x32_bf16 v[86:89], v[166:169], v[210:213], v[86:89]
	v_mfma_f32_16x16x32_bf16 v[82:85], v[174:177], v[210:213], v[82:85]
	v_mfma_f32_16x16x32_bf16 v[70:73], v[166:169], v[218:221], v[70:73]
	v_mfma_f32_16x16x32_bf16 v[66:69], v[174:177], v[218:221], v[66:69]
	v_mfma_f32_16x16x32_bf16 v[118:121], v[170:173], v[186:189], v[118:121]
	v_mfma_f32_16x16x32_bf16 v[114:117], v[178:181], v[186:189], v[114:117]
	v_mfma_f32_16x16x32_bf16 v[102:105], v[170:173], v[206:209], v[102:105]
	v_mfma_f32_16x16x32_bf16 v[98:101], v[178:181], v[206:209], v[98:101]
	v_mfma_f32_16x16x32_bf16 v[86:89], v[170:173], v[214:217], v[86:89]
	v_mfma_f32_16x16x32_bf16 v[82:85], v[178:181], v[214:217], v[82:85]
	v_mfma_f32_16x16x32_bf16 v[70:73], v[170:173], v[222:225], v[70:73]
	v_mfma_f32_16x16x32_bf16 v[66:69], v[178:181], v[222:225], v[66:69]
	s_setprio 0
	s_barrier
	s_add_i32 s16, s52, s30
	v_lshl_add_u64 v[190:191], s[22:23], 0, v[148:149]
	s_mov_b32 m0, s16
	ds_read_b128 v[182:185], v198 offset:16384
	ds_read_b128 v[186:189], v198 offset:17408
	ds_read_b128 v[202:205], v198 offset:18432
	ds_read_b128 v[206:209], v198 offset:19456
	ds_read_b128 v[210:213], v198 offset:20480
	ds_read_b128 v[214:217], v198 offset:21504
	ds_read_b128 v[218:221], v198 offset:22528
	ds_read_b128 v[222:225], v198 offset:23552
	global_load_lds_dwordx4 v[190:191], off
	s_add_i32 m0, s16, 0x2000
	s_add_u32 s16, s22, 0x58000
	v_lshl_add_u64 v[226:227], s[22:23], 0, v[152:153]
	s_addc_u32 s17, s23, 0
	s_add_i32 s56, s53, s30
	global_load_lds_dwordx4 v[226:227], off
	v_lshl_add_u64 v[228:229], s[16:17], 0, v[148:149]
	s_mov_b32 m0, s56
	v_lshl_add_u64 v[230:231], s[46:47], 0, v[150:151]
	global_load_lds_dwordx4 v[228:229], off
	v_lshl_add_u64 v[228:229], s[16:17], 0, v[152:153]
	s_add_i32 m0, s56, 0x2000
	s_nop 0
	global_load_lds_dwordx4 v[228:229], off
	v_lshl_add_u64 v[228:229], s[46:47], 0, v[146:147]
	s_mov_b32 m0, s31
	s_nop 0
	global_load_lds_dwordx4 v[228:229], off
	s_mov_b32 m0, s33
	s_nop 0
	global_load_lds_dwordx4 v[230:231], off
	s_waitcnt vmcnt(8)
	s_waitcnt lgkmcnt(0)
	s_barrier
	s_setprio 1
	s_waitcnt lgkmcnt(0)
	v_mfma_f32_16x16x32_bf16 v[62:65], v[130:133], v[182:185], v[62:65]
	v_mfma_f32_16x16x32_bf16 v[58:61], v[138:141], v[182:185], v[58:61]
	v_mfma_f32_16x16x32_bf16 v[46:49], v[130:133], v[202:205], v[46:49]
	v_mfma_f32_16x16x32_bf16 v[42:45], v[138:141], v[202:205], v[42:45]
	v_mfma_f32_16x16x32_bf16 v[30:33], v[130:133], v[210:213], v[30:33]
	v_mfma_f32_16x16x32_bf16 v[26:29], v[138:141], v[210:213], v[26:29]
	v_mfma_f32_16x16x32_bf16 v[14:17], v[130:133], v[218:221], v[14:17]
	v_mfma_f32_16x16x32_bf16 v[10:13], v[138:141], v[218:221], v[10:13]
	v_mfma_f32_16x16x32_bf16 v[62:65], v[134:137], v[186:189], v[62:65]
	v_mfma_f32_16x16x32_bf16 v[58:61], v[142:145], v[186:189], v[58:61]
	v_mfma_f32_16x16x32_bf16 v[46:49], v[134:137], v[206:209], v[46:49]
	v_mfma_f32_16x16x32_bf16 v[42:45], v[142:145], v[206:209], v[42:45]
	v_mfma_f32_16x16x32_bf16 v[30:33], v[134:137], v[214:217], v[30:33]
	v_mfma_f32_16x16x32_bf16 v[26:29], v[142:145], v[214:217], v[26:29]
	v_mfma_f32_16x16x32_bf16 v[14:17], v[134:137], v[222:225], v[14:17]
	v_mfma_f32_16x16x32_bf16 v[10:13], v[142:145], v[222:225], v[10:13]
	v_mfma_f32_16x16x32_bf16 v[54:57], v[166:169], v[182:185], v[54:57]
	v_mfma_f32_16x16x32_bf16 v[50:53], v[174:177], v[182:185], v[50:53]
	v_mfma_f32_16x16x32_bf16 v[38:41], v[166:169], v[202:205], v[38:41]
	v_mfma_f32_16x16x32_bf16 v[34:37], v[174:177], v[202:205], v[34:37]
	v_mfma_f32_16x16x32_bf16 v[22:25], v[166:169], v[210:213], v[22:25]
	v_mfma_f32_16x16x32_bf16 v[18:21], v[174:177], v[210:213], v[18:21]
	v_mfma_f32_16x16x32_bf16 v[6:9], v[166:169], v[218:221], v[6:9]
	v_mfma_f32_16x16x32_bf16 v[2:5], v[174:177], v[218:221], v[2:5]
	v_mfma_f32_16x16x32_bf16 v[54:57], v[170:173], v[186:189], v[54:57]
	v_mfma_f32_16x16x32_bf16 v[50:53], v[178:181], v[186:189], v[50:53]
	v_mfma_f32_16x16x32_bf16 v[38:41], v[170:173], v[206:209], v[38:41]
	v_mfma_f32_16x16x32_bf16 v[34:37], v[178:181], v[206:209], v[34:37]
	v_mfma_f32_16x16x32_bf16 v[22:25], v[170:173], v[214:217], v[22:25]
	v_mfma_f32_16x16x32_bf16 v[18:21], v[178:181], v[214:217], v[18:21]
	v_mfma_f32_16x16x32_bf16 v[6:9], v[170:173], v[222:225], v[6:9]
	v_mfma_f32_16x16x32_bf16 v[2:5], v[178:181], v[222:225], v[2:5]
	s_setprio 0
	s_barrier
; #define PG8_STAGE(bufoff, gbase, voff) do { _Pragma("unroll") for (int _i = 0; _i < 2; ++_i) \
;         __builtin_amdgcn_global_load_lds((const unsigned*)((const char*)(gbase) + (voff)[_i]), (LAS unsigned*)(lds + (bufoff) + ldsw + _i * 8192), 16, 0, 0); } while (0)
; #define PG8_LDA(dst, b, h) do { _Pragma("unroll") for (int m = 0; m < 4; ++m) _Pragma("unroll") for (int k = 0; k < 2; ++k) dst[m][k] = *(const LAS bf16x8*)(lds + PG8_SA(b, h) + aoff + m * 2048 + k * 1024); } while (0)
; #define PG8_LDB(dst, b, h) do { _Pragma("unroll") for (int n = 0; n < 2; ++n) _Pragma("unroll") for (int k = 0; k < 2; ++k) dst[n][k] = *(const LAS bf16x8*)(lds + PG8_SB(b, h) + boff + n * 2048 + k * 1024); } while (0)
; #define PG8_MMA(ai, bj, At, Bt) do { __builtin_amdgcn_s_setprio(1); _Pragma("unroll") for (int m = 0; m < 4; ++m) _Pragma("unroll") for (int n = 0; n < 2; ++n) _Pragma("unroll") for (int k = 0; k < 2; ++k) \
;         acc[ai][bj][m][n] = __builtin_amdgcn_mfma_f32_16x16x32_bf16(Bt[n][k], At[m][k], acc[ai][bj][m][n], 0, 0, 0); __builtin_amdgcn_s_setprio(0); } while (0)
; #define PG8_WAIT_V(n) asm volatile("s_waitcnt vmcnt(" #n ")" ::: "memory")
; #define PG8_WAIT_L(n) asm volatile("s_waitcnt lgkmcnt(" #n ")" ::: "memory")
; #define PG8_BAR __builtin_amdgcn_s_barrier()
; #define PG8_SCHED __builtin_amdgcn_sched_barrier(0)
; template <class Epi, class Sched, bool ALIGN_EPI = false, bool SP2 = false>
; __device__ __forceinline__ void gemm_phase(LAS unsigned char* lds, const Gemm g, const Sched& S, const Epi& E) {
;     ...
;             PG8_LDB(B0, 1, 0); PG8_LDB(B1, 1, 1); PG8_SCHED; PG8_LDA(At, 1, 0); PG8_STAGE(PG8_SA(0, 1), a2 + hstep, voffA);
;             PG8_WAIT_V(8); PG8_WAIT_L(0); PG8_BAR; PG8_MMA(0, 0, At, B0); PG8_MMA(0, 1, At, B1); PG8_BAR; PG8_SCHED;
	s_add_i32 s56, 0, 0x18000
	s_add_i32 s57, 0, 0x1c000
	v_add_u32_e32 v142, s56, v1
	v_add_u32_e32 v154, s57, v1
	ds_read_b128 v[130:133], v142
	ds_read_b128 v[134:137], v142 offset:1024
	ds_read_b128 v[138:141], v142 offset:2048
	ds_read_b128 v[142:145], v142 offset:3072
	ds_read_b128 v[166:169], v154
	ds_read_b128 v[170:173], v154 offset:1024
	ds_read_b128 v[174:177], v154 offset:2048
	ds_read_b128 v[178:181], v154 offset:3072
	s_add_u32 s16, s46, 0x160000
	s_addc_u32 s17, s47, 0
	s_mov_b32 m0, s34
	v_lshl_add_u64 v[232:233], s[16:17], 0, v[146:147]
	ds_read_b128 v[182:185], v198 offset:32768
	ds_read_b128 v[186:189], v198 offset:33792
	ds_read_b128 v[202:205], v198 offset:34816
	ds_read_b128 v[206:209], v198 offset:35840
	ds_read_b128 v[210:213], v198 offset:36864
	ds_read_b128 v[214:217], v198 offset:37888
	ds_read_b128 v[218:221], v198 offset:38912
	ds_read_b128 v[222:225], v198 offset:39936
	global_load_lds_dwordx4 v[232:233], off
	v_lshl_add_u64 v[232:233], s[16:17], 0, v[150:151]
	s_mov_b32 m0, s35
	s_nop 0
	global_load_lds_dwordx4 v[232:233], off
	s_waitcnt vmcnt(8)
	s_waitcnt lgkmcnt(0)
	s_barrier
	s_setprio 1
	s_waitcnt lgkmcnt(0)
	v_mfma_f32_16x16x32_bf16 v[126:129], v[130:133], v[182:185], v[126:129]
	v_mfma_f32_16x16x32_bf16 v[122:125], v[138:141], v[182:185], v[122:125]
	v_mfma_f32_16x16x32_bf16 v[110:113], v[130:133], v[202:205], v[110:113]
	v_mfma_f32_16x16x32_bf16 v[106:109], v[138:141], v[202:205], v[106:109]
	v_mfma_f32_16x16x32_bf16 v[94:97], v[130:133], v[210:213], v[94:97]
	v_mfma_f32_16x16x32_bf16 v[90:93], v[138:141], v[210:213], v[90:93]
	v_mfma_f32_16x16x32_bf16 v[78:81], v[130:133], v[218:221], v[78:81]
	v_mfma_f32_16x16x32_bf16 v[74:77], v[138:141], v[218:221], v[74:77]
	v_mfma_f32_16x16x32_bf16 v[126:129], v[134:137], v[186:189], v[126:129]
	v_mfma_f32_16x16x32_bf16 v[122:125], v[142:145], v[186:189], v[122:125]
	v_mfma_f32_16x16x32_bf16 v[110:113], v[134:137], v[206:209], v[110:113]
	v_mfma_f32_16x16x32_bf16 v[106:109], v[142:145], v[206:209], v[106:109]
	v_mfma_f32_16x16x32_bf16 v[94:97], v[134:137], v[214:217], v[94:97]
	v_mfma_f32_16x16x32_bf16 v[90:93], v[142:145], v[214:217], v[90:93]
	v_mfma_f32_16x16x32_bf16 v[78:81], v[134:137], v[222:225], v[78:81]
	v_mfma_f32_16x16x32_bf16 v[74:77], v[142:145], v[222:225], v[74:77]
	v_mfma_f32_16x16x32_bf16 v[118:121], v[166:169], v[182:185], v[118:121]
	v_mfma_f32_16x16x32_bf16 v[114:117], v[174:177], v[182:185], v[114:117]
	v_mfma_f32_16x16x32_bf16 v[102:105], v[166:169], v[202:205], v[102:105]
	v_mfma_f32_16x16x32_bf16 v[98:101], v[174:177], v[202:205], v[98:101]
	v_mfma_f32_16x16x32_bf16 v[86:89], v[166:169], v[210:213], v[86:89]
	v_mfma_f32_16x16x32_bf16 v[82:85], v[174:177], v[210:213], v[82:85]
	v_mfma_f32_16x16x32_bf16 v[70:73], v[166:169], v[218:221], v[70:73]
	v_mfma_f32_16x16x32_bf16 v[66:69], v[174:177], v[218:221], v[66:69]
	v_mfma_f32_16x16x32_bf16 v[118:121], v[170:173], v[186:189], v[118:121]
	v_mfma_f32_16x16x32_bf16 v[114:117], v[178:181], v[186:189], v[114:117]
	v_mfma_f32_16x16x32_bf16 v[102:105], v[170:173], v[206:209], v[102:105]
	v_mfma_f32_16x16x32_bf16 v[98:101], v[178:181], v[206:209], v[98:101]
	v_mfma_f32_16x16x32_bf16 v[86:89], v[170:173], v[214:217], v[86:89]
	v_mfma_f32_16x16x32_bf16 v[82:85], v[178:181], v[214:217], v[82:85]
	v_mfma_f32_16x16x32_bf16 v[70:73], v[170:173], v[222:225], v[70:73]
	v_mfma_f32_16x16x32_bf16 v[66:69], v[178:181], v[222:225], v[66:69]
	s_setprio 0
	s_barrier
; #define PG8_STAGE(bufoff, gbase, voff) do { _Pragma("unroll") for (int _i = 0; _i < 2; ++_i) \
;         __builtin_amdgcn_global_load_lds((const unsigned*)((const char*)(gbase) + (voff)[_i]), (LAS unsigned*)(lds + (bufoff) + ldsw + _i * 8192), 16, 0, 0); } while (0)
; #define PG8_LDA(dst, b, h) do { _Pragma("unroll") for (int m = 0; m < 4; ++m) _Pragma("unroll") for (int k = 0; k < 2; ++k) dst[m][k] = *(const LAS bf16x8*)(lds + PG8_SA(b, h) + aoff + m * 2048 + k * 1024); } while (0)
; #define PG8_MMA(ai, bj, At, Bt) do { __builtin_amdgcn_s_setprio(1); _Pragma("unroll") for (int m = 0; m < 4; ++m) _Pragma("unroll") for (int n = 0; n < 2; ++n) _Pragma("unroll") for (int k = 0; k < 2; ++k) \
;         acc[ai][bj][m][n] = __builtin_amdgcn_mfma_f32_16x16x32_bf16(Bt[n][k], At[m][k], acc[ai][bj][m][n], 0, 0, 0); __builtin_amdgcn_s_setprio(0); } while (0)
; #define PG8_WAIT_V(n) asm volatile("s_waitcnt vmcnt(" #n ")" ::: "memory")
; #define PG8_WAIT_L(n) asm volatile("s_waitcnt lgkmcnt(" #n ")" ::: "memory")
; #define PG8_BAR __builtin_amdgcn_s_barrier()
; #define PG8_SCHED __builtin_amdgcn_sched_barrier(0)
; template <class Epi, class Sched, bool ALIGN_EPI = false, bool SP2 = false>
; __device__ __forceinline__ void gemm_phase(LAS unsigned char* lds, const Gemm g, const Sched& S, const Epi& E) {
;     ...
;         for (int t = 0; t < nt; t += 2) {
;             const bool last = (t == nt - 2);
;     ...
;             PG8_LDA(At, 1, 1); PG8_STAGE(PG8_SB(1, 0), b3, voffB); PG8_STAGE(PG8_SB(1, 1), b3 + hstepB, voffB); PG8_STAGE(PG8_SA(1, 0), a3, voffA);
;             PG8_WAIT_V(8); PG8_WAIT_L(0); PG8_BAR; PG8_MMA(1, 0, At, B0); PG8_MMA(1, 1, At, B1); PG8_BAR; PG8_SCHED;
	s_add_i32 s16, s56, s30
	v_lshl_add_u64 v[190:191], v[190:191], 0, s[12:13]
	s_mov_b32 m0, s16
	ds_read_b128 v[182:185], v198 offset:49152
	ds_read_b128 v[186:189], v198 offset:50176
	ds_read_b128 v[202:205], v198 offset:51200
	ds_read_b128 v[206:209], v198 offset:52224
	ds_read_b128 v[210:213], v198 offset:53248
	ds_read_b128 v[214:217], v198 offset:54272
	ds_read_b128 v[218:221], v198 offset:55296
	ds_read_b128 v[222:225], v198 offset:56320
	global_load_lds_dwordx4 v[190:191], off
	s_add_i32 m0, s16, 0x2000
	s_add_u32 s16, s22, 0x58080
	v_lshl_add_u64 v[190:191], v[226:227], 0, s[12:13]
	s_addc_u32 s17, s23, 0
	s_add_i32 s22, s57, s30
	global_load_lds_dwordx4 v[190:191], off
	v_lshl_add_u64 v[190:191], s[16:17], 0, v[148:149]
	s_mov_b32 m0, s22
	s_nop 0
	global_load_lds_dwordx4 v[190:191], off
	v_lshl_add_u64 v[190:191], s[16:17], 0, v[152:153]
	s_add_i32 m0, s22, 0x2000
	s_nop 0
	global_load_lds_dwordx4 v[190:191], off
	v_lshl_add_u64 v[190:191], v[228:229], 0, s[12:13]
	s_mov_b32 m0, s49
	s_nop 0
	global_load_lds_dwordx4 v[190:191], off
	v_lshl_add_u64 v[190:191], v[230:231], 0, s[12:13]
	s_mov_b32 m0, s50
	s_nop 0
	global_load_lds_dwordx4 v[190:191], off
	s_waitcnt vmcnt(8)
	s_waitcnt lgkmcnt(0)
	s_barrier
	s_setprio 1
	s_waitcnt lgkmcnt(0)
	v_mfma_f32_16x16x32_bf16 v[62:65], v[130:133], v[182:185], v[62:65]
	v_mfma_f32_16x16x32_bf16 v[58:61], v[138:141], v[182:185], v[58:61]
	v_mfma_f32_16x16x32_bf16 v[46:49], v[130:133], v[202:205], v[46:49]
	v_mfma_f32_16x16x32_bf16 v[42:45], v[138:141], v[202:205], v[42:45]
	v_mfma_f32_16x16x32_bf16 v[30:33], v[130:133], v[210:213], v[30:33]
	v_mfma_f32_16x16x32_bf16 v[26:29], v[138:141], v[210:213], v[26:29]
	v_mfma_f32_16x16x32_bf16 v[14:17], v[130:133], v[218:221], v[14:17]
	v_mfma_f32_16x16x32_bf16 v[10:13], v[138:141], v[218:221], v[10:13]
	v_mfma_f32_16x16x32_bf16 v[62:65], v[134:137], v[186:189], v[62:65]
	v_mfma_f32_16x16x32_bf16 v[58:61], v[142:145], v[186:189], v[58:61]
	v_mfma_f32_16x16x32_bf16 v[46:49], v[134:137], v[206:209], v[46:49]
	v_mfma_f32_16x16x32_bf16 v[42:45], v[142:145], v[206:209], v[42:45]
	v_mfma_f32_16x16x32_bf16 v[30:33], v[134:137], v[214:217], v[30:33]
	v_mfma_f32_16x16x32_bf16 v[26:29], v[142:145], v[214:217], v[26:29]
	v_mfma_f32_16x16x32_bf16 v[14:17], v[134:137], v[222:225], v[14:17]
	v_mfma_f32_16x16x32_bf16 v[10:13], v[142:145], v[222:225], v[10:13]
	v_mfma_f32_16x16x32_bf16 v[54:57], v[166:169], v[182:185], v[54:57]
	v_mfma_f32_16x16x32_bf16 v[50:53], v[174:177], v[182:185], v[50:53]
	v_mfma_f32_16x16x32_bf16 v[38:41], v[166:169], v[202:205], v[38:41]
	v_mfma_f32_16x16x32_bf16 v[34:37], v[174:177], v[202:205], v[34:37]
	v_mfma_f32_16x16x32_bf16 v[22:25], v[166:169], v[210:213], v[22:25]
	v_mfma_f32_16x16x32_bf16 v[18:21], v[174:177], v[210:213], v[18:21]
	v_mfma_f32_16x16x32_bf16 v[6:9], v[166:169], v[218:221], v[6:9]
	v_mfma_f32_16x16x32_bf16 v[2:5], v[174:177], v[218:221], v[2:5]
	v_mfma_f32_16x16x32_bf16 v[54:57], v[170:173], v[186:189], v[54:57]
	v_mfma_f32_16x16x32_bf16 v[50:53], v[178:181], v[186:189], v[50:53]
	v_mfma_f32_16x16x32_bf16 v[38:41], v[170:173], v[206:209], v[38:41]
	v_mfma_f32_16x16x32_bf16 v[34:37], v[178:181], v[206:209], v[34:37]
	v_mfma_f32_16x16x32_bf16 v[22:25], v[170:173], v[214:217], v[22:25]
	v_mfma_f32_16x16x32_bf16 v[18:21], v[178:181], v[214:217], v[18:21]
	v_mfma_f32_16x16x32_bf16 v[6:9], v[170:173], v[222:225], v[6:9]
	v_mfma_f32_16x16x32_bf16 v[2:5], v[178:181], v[222:225], v[2:5]
	s_setprio 0
	s_barrier
	s_add_i32 s25, s25, 2
	s_add_u32 s9, s9, 0x100
	s_addc_u32 s24, s24, 0
	s_cmpk_gt_u32 s25, 0x55
	s_mov_b64 s[16:17], s[20:21]
	s_cbranch_scc0 .LBB0_1595
	s_and_b64 vcc, exec, s[14:15]
	s_cbranch_vccz .LBB0_1598
	s_barrier

; __device__ __forceinline__ float row_rstd(const float* ss, int row) { return 1.0f / sqrtf(ss[row] * (1.0f / DM) + 1e-6f); }
; #define PG8_STAGE(bufoff, gbase, voff) do { _Pragma("unroll") for (int _i = 0; _i < 2; ++_i) \
;         __builtin_amdgcn_global_load_lds((const unsigned*)((const char*)(gbase) + (voff)[_i]), (LAS unsigned*)(lds + (bufoff) + ldsw + _i * 8192), 16, 0, 0); } while (0)
; #define PG8_LDA(dst, b, h) do { _Pragma("unroll") for (int m = 0; m < 4; ++m) _Pragma("unroll") for (int k = 0; k < 2; ++k) dst[m][k] = *(const LAS bf16x8*)(lds + PG8_SA(b, h) + aoff + m * 2048 + k * 1024); } while (0)
; #define PG8_LDB(dst, b, h) do { _Pragma("unroll") for (int n = 0; n < 2; ++n) _Pragma("unroll") for (int k = 0; k < 2; ++k) dst[n][k] = *(const LAS bf16x8*)(lds + PG8_SB(b, h) + boff + n * 2048 + k * 1024); } while (0)
; #define PG8_WAIT_V(n) asm volatile("s_waitcnt vmcnt(" #n ")" ::: "memory")
; #define PG8_WAIT_L(n) asm volatile("s_waitcnt lgkmcnt(" #n ")" ::: "memory")
; #define PG8_BAR __builtin_amdgcn_s_barrier()
; #define PG8_SCHED __builtin_amdgcn_sched_barrier(0)
;     __device__ __forceinline__ void operator()(const f32x4 (&acc)[2][2][4][2], const Unit& u, int wr, int wc, int fr, int fq) const {
;     ...
;         const float* bp = bias + (size_t)s * BIAS_N + u.pn * BM + wc * 32 + 8 * fq;
;         const f32x4 ba0 = *(const f32x4*)bp, ba1 = *(const f32x4*)(bp + 4), bb0 = *(const f32x4*)(bp + HALF), bb1 = *(const f32x4*)(bp + HALF + 4);
;         const int lane = fq * 16 + fr;
;         const float rsl0 = row_rstd(ss, u.pm * BM + wr * 64 + lane), rsl1 = row_rstd(ss, u.pm * BM + HALF + wr * 64 + lane);
; template <class Epi, class Sched, bool ALIGN_EPI = false, bool SP2 = false>
; __device__ __forceinline__ void gemm_phase(LAS unsigned char* lds, const Gemm g, const Sched& S, const Epi& E) {
;     ...
;             PG8_LDB(B0, 0, 0); PG8_LDB(B1, 0, 1); PG8_SCHED; PG8_LDA(At, 0, 0); PG8_STAGE(PG8_SA(1, 1), a1 + hstep, voffA);
;             PG8_WAIT_V(8); PG8_WAIT_L(0); PG8_BAR; PG8_MMA(0, 0, At, B0); PG8_MMA(0, 1, At, B1); PG8_BAR; PG8_SCHED;
;             PG8_LDA(At, 0, 1); PG8_STAGE(PG8_SB(0, 0), b2, voffB); PG8_STAGE(PG8_SB(0, 1), b2 + hstepB, voffB); PG8_STAGE(PG8_SA(0, 0), a2, voffA);
;             PG8_WAIT_V(8); PG8_WAIT_L(0); PG8_BAR; PG8_MMA(1, 0, At, B0); PG8_MMA(1, 1, At, B1); PG8_BAR; PG8_SCHED;
.Lpre_up1l1:
	s_lshl_b64 s[98:99], s[98:99], 2
	s_add_u32 s98, s36, s98
	s_addc_u32 s99, s37, s99
	s_lshl_b32 s100, s0, 8
	s_ashr_i32 s101, s100, 31
	s_lshl_b64 s[100:101], s[100:101], 2
	s_add_u32 s98, s98, s100
	s_addc_u32 s99, s99, s101
	s_add_u32 s98, s98, s47
	s_addc_u32 s99, s99, 0
	s_lshl_b32 s100, s2, 8
	s_add_i32 s100, s100, s35
	v_or_b32_e32 v162, s100, v170
	v_ashrrev_i32_e32 v163, 31, v162
	v_lshl_add_u64 v[162:163], v[162:163], 2, s[6:7]
	v_add_u32_e32 v164, s100, v171
	v_ashrrev_i32_e32 v165, 31, v164
	v_lshl_add_u64 v[164:165], v[164:165], 2, s[6:7]
	global_load_dwordx4 v[234:237], v176, s[98:99] offset:16
	global_load_dwordx4 v[238:241], v176, s[98:99]
	global_load_dwordx4 v[242:245], v176, s[98:99] offset:528
	global_load_dwordx4 v[246:249], v176, s[98:99] offset:512
	global_load_dword v250, v[162:163], off
	global_load_dword v251, v[164:165], off
	ds_read_b128 v[66:69], v173
	ds_read_b128 v[70:73], v173 offset:1024
	ds_read_b128 v[74:77], v173 offset:2048
	ds_read_b128 v[78:81], v173 offset:3072
	ds_read_b128 v[162:165], v174
	ds_read_b128 v[180:183], v174 offset:1024
	ds_read_b128 v[184:187], v174 offset:2048
	ds_read_b128 v[188:191], v174 offset:3072
	s_add_u32 s22, s16, 0xfff80080
	s_addc_u32 s23, s17, -1
	s_cmp_eq_u32 s50, 28
	s_cselect_b32 s41, s3, s23
	s_cselect_b32 s40, s15, s22
	s_cselect_b32 s23, s13, s49
	s_cselect_b32 s22, s24, s25
	v_lshl_add_u64 v[166:167], s[16:17], 0, v[156:157]
	s_add_i32 m0, s29, 0xc000
	ds_read_b128 v[192:195], v175
	ds_read_b128 v[196:199], v175 offset:1024
	ds_read_b128 v[200:203], v175 offset:2048
	ds_read_b128 v[204:207], v175 offset:3072
	ds_read_b128 v[208:211], v175 offset:4096
	ds_read_b128 v[212:215], v175 offset:5120
	ds_read_b128 v[216:219], v175 offset:6144
	ds_read_b128 v[220:223], v175 offset:7168
	global_load_lds_dwordx4 v[166:167], off
	v_lshl_add_u64 v[166:167], s[16:17], 0, v[154:155]
	s_add_i32 m0, s29, 0xe000
	s_nop 0
	global_load_lds_dwordx4 v[166:167], off
	s_waitcnt lgkmcnt(0)
	s_barrier
	s_setprio 1
	s_waitcnt lgkmcnt(0)
	v_mfma_f32_16x16x32_bf16 v[142:145], v[66:69], v[192:195], 0
	v_mfma_f32_16x16x32_bf16 v[138:141], v[74:77], v[192:195], 0
	v_mfma_f32_16x16x32_bf16 v[126:129], v[66:69], v[200:203], 0
	v_mfma_f32_16x16x32_bf16 v[122:125], v[74:77], v[200:203], 0
	v_mfma_f32_16x16x32_bf16 v[110:113], v[66:69], v[208:211], 0
	v_mfma_f32_16x16x32_bf16 v[106:109], v[74:77], v[208:211], 0
	v_mfma_f32_16x16x32_bf16 v[94:97], v[66:69], v[216:219], 0
	v_mfma_f32_16x16x32_bf16 v[90:93], v[74:77], v[216:219], 0
	v_mfma_f32_16x16x32_bf16 v[142:145], v[70:73], v[196:199], v[142:145]
	v_mfma_f32_16x16x32_bf16 v[138:141], v[78:81], v[196:199], v[138:141]
	v_mfma_f32_16x16x32_bf16 v[126:129], v[70:73], v[204:207], v[126:129]
	v_mfma_f32_16x16x32_bf16 v[122:125], v[78:81], v[204:207], v[122:125]
	v_mfma_f32_16x16x32_bf16 v[110:113], v[70:73], v[212:215], v[110:113]
	v_mfma_f32_16x16x32_bf16 v[106:109], v[78:81], v[212:215], v[106:109]
	v_mfma_f32_16x16x32_bf16 v[94:97], v[70:73], v[220:223], v[94:97]
	v_mfma_f32_16x16x32_bf16 v[90:93], v[78:81], v[220:223], v[90:93]
	v_mfma_f32_16x16x32_bf16 v[134:137], v[162:165], v[192:195], 0
	v_mfma_f32_16x16x32_bf16 v[130:133], v[184:187], v[192:195], 0
	v_mfma_f32_16x16x32_bf16 v[118:121], v[162:165], v[200:203], 0
	v_mfma_f32_16x16x32_bf16 v[114:117], v[184:187], v[200:203], 0
	v_mfma_f32_16x16x32_bf16 v[102:105], v[162:165], v[208:211], 0
	v_mfma_f32_16x16x32_bf16 v[98:101], v[184:187], v[208:211], 0
	v_mfma_f32_16x16x32_bf16 v[86:89], v[162:165], v[216:219], 0
	v_mfma_f32_16x16x32_bf16 v[82:85], v[184:187], v[216:219], 0
	v_mfma_f32_16x16x32_bf16 v[134:137], v[180:183], v[196:199], v[134:137]
	v_mfma_f32_16x16x32_bf16 v[130:133], v[188:191], v[196:199], v[130:133]
	v_mfma_f32_16x16x32_bf16 v[118:121], v[180:183], v[204:207], v[118:121]
	v_mfma_f32_16x16x32_bf16 v[114:117], v[188:191], v[204:207], v[114:117]
	v_mfma_f32_16x16x32_bf16 v[102:105], v[180:183], v[212:215], v[102:105]
	v_mfma_f32_16x16x32_bf16 v[98:101], v[188:191], v[212:215], v[98:101]
	v_mfma_f32_16x16x32_bf16 v[86:89], v[180:183], v[220:223], v[86:89]
	v_mfma_f32_16x16x32_bf16 v[82:85], v[188:191], v[220:223], v[82:85]
	s_setprio 0
	s_barrier
	s_add_i32 s51, s44, s26
	v_lshl_add_u64 v[166:167], s[22:23], 0, v[150:151]
	s_mov_b32 m0, s51
	ds_read_b128 v[192:195], v175 offset:16384
	ds_read_b128 v[196:199], v175 offset:17408
	ds_read_b128 v[200:203], v175 offset:18432
	ds_read_b128 v[204:207], v175 offset:19456
	ds_read_b128 v[208:211], v175 offset:20480
	ds_read_b128 v[212:215], v175 offset:21504
	ds_read_b128 v[216:219], v175 offset:22528
	ds_read_b128 v[220:223], v175 offset:23552
	global_load_lds_dwordx4 v[166:167], off
	s_add_i32 m0, s51, 0x2000
	s_add_u32 s52, s22, 0x80000
	v_lshl_add_u64 v[224:225], s[22:23], 0, v[146:147]
	s_addc_u32 s53, s23, 0
	s_add_i32 s51, s45, s26
	global_load_lds_dwordx4 v[224:225], off
	v_lshl_add_u64 v[226:227], s[52:53], 0, v[150:151]
	s_mov_b32 m0, s51
	v_lshl_add_u64 v[228:229], s[40:41], 0, v[148:149]
	global_load_lds_dwordx4 v[226:227], off
	v_lshl_add_u64 v[226:227], s[52:53], 0, v[146:147]
	s_add_i32 m0, s51, 0x2000
	s_nop 0
	global_load_lds_dwordx4 v[226:227], off
	v_lshl_add_u64 v[226:227], s[40:41], 0, v[152:153]
	s_mov_b32 m0, s29
	s_nop 0
	global_load_lds_dwordx4 v[226:227], off
	s_mov_b32 m0, s30
	s_nop 0
	global_load_lds_dwordx4 v[228:229], off
	s_waitcnt lgkmcnt(0)
	s_barrier
; #define PG8_STAGE(bufoff, gbase, voff) do { _Pragma("unroll") for (int _i = 0; _i < 2; ++_i) \
;         __builtin_amdgcn_global_load_lds((const unsigned*)((const char*)(gbase) + (voff)[_i]), (LAS unsigned*)(lds + (bufoff) + ldsw + _i * 8192), 16, 0, 0); } while (0)
; #define PG8_LDA(dst, b, h) do { _Pragma("unroll") for (int m = 0; m < 4; ++m) _Pragma("unroll") for (int k = 0; k < 2; ++k) dst[m][k] = *(const LAS bf16x8*)(lds + PG8_SA(b, h) + aoff + m * 2048 + k * 1024); } while (0)
; #define PG8_LDB(dst, b, h) do { _Pragma("unroll") for (int n = 0; n < 2; ++n) _Pragma("unroll") for (int k = 0; k < 2; ++k) dst[n][k] = *(const LAS bf16x8*)(lds + PG8_SB(b, h) + boff + n * 2048 + k * 1024); } while (0)
; #define PG8_MMA(ai, bj, At, Bt) do { __builtin_amdgcn_s_setprio(1); _Pragma("unroll") for (int m = 0; m < 4; ++m) _Pragma("unroll") for (int n = 0; n < 2; ++n) _Pragma("unroll") for (int k = 0; k < 2; ++k) \
;         acc[ai][bj][m][n] = __builtin_amdgcn_mfma_f32_16x16x32_bf16(Bt[n][k], At[m][k], acc[ai][bj][m][n], 0, 0, 0); __builtin_amdgcn_s_setprio(0); } while (0)
; #define PG8_WAIT_V(n) asm volatile("s_waitcnt vmcnt(" #n ")" ::: "memory")
; #define PG8_WAIT_L(n) asm volatile("s_waitcnt lgkmcnt(" #n ")" ::: "memory")
; #define PG8_BAR __builtin_amdgcn_s_barrier()
; #define PG8_SCHED __builtin_amdgcn_sched_barrier(0)
; template <class Epi, class Sched, bool ALIGN_EPI = false, bool SP2 = false>
; __device__ __forceinline__ void gemm_phase(LAS unsigned char* lds, const Gemm g, const Sched& S, const Epi& E) {
;     ...
;             PG8_LDA(At, 0, 1); PG8_STAGE(PG8_SB(0, 0), b2, voffB); PG8_STAGE(PG8_SB(0, 1), b2 + hstepB, voffB); PG8_STAGE(PG8_SA(0, 0), a2, voffA);
;             PG8_WAIT_V(8); PG8_WAIT_L(0); PG8_BAR; PG8_MMA(1, 0, At, B0); PG8_MMA(1, 1, At, B1); PG8_BAR; PG8_SCHED;
;             PG8_LDB(B0, 1, 0); PG8_LDB(B1, 1, 1); PG8_SCHED; PG8_LDA(At, 1, 0); PG8_STAGE(PG8_SA(0, 1), a2 + hstep, voffA);
;             PG8_WAIT_V(8); PG8_WAIT_L(0); PG8_BAR; PG8_MMA(0, 0, At, B0); PG8_MMA(0, 1, At, B1); PG8_BAR; PG8_SCHED;
	s_setprio 1
	s_waitcnt lgkmcnt(0)
	v_mfma_f32_16x16x32_bf16 v[62:65], v[66:69], v[192:195], 0
	v_mfma_f32_16x16x32_bf16 v[58:61], v[74:77], v[192:195], 0
	v_mfma_f32_16x16x32_bf16 v[46:49], v[66:69], v[200:203], 0
	v_mfma_f32_16x16x32_bf16 v[42:45], v[74:77], v[200:203], 0
	v_mfma_f32_16x16x32_bf16 v[30:33], v[66:69], v[208:211], 0
	v_mfma_f32_16x16x32_bf16 v[26:29], v[74:77], v[208:211], 0
	v_mfma_f32_16x16x32_bf16 v[14:17], v[66:69], v[216:219], 0
	v_mfma_f32_16x16x32_bf16 v[10:13], v[74:77], v[216:219], 0
	v_mfma_f32_16x16x32_bf16 v[62:65], v[70:73], v[196:199], v[62:65]
	v_mfma_f32_16x16x32_bf16 v[58:61], v[78:81], v[196:199], v[58:61]
	v_mfma_f32_16x16x32_bf16 v[46:49], v[70:73], v[204:207], v[46:49]
	v_mfma_f32_16x16x32_bf16 v[42:45], v[78:81], v[204:207], v[42:45]
	v_mfma_f32_16x16x32_bf16 v[30:33], v[70:73], v[212:215], v[30:33]
	v_mfma_f32_16x16x32_bf16 v[26:29], v[78:81], v[212:215], v[26:29]
	v_mfma_f32_16x16x32_bf16 v[14:17], v[70:73], v[220:223], v[14:17]
	v_mfma_f32_16x16x32_bf16 v[10:13], v[78:81], v[220:223], v[10:13]
	v_mfma_f32_16x16x32_bf16 v[54:57], v[162:165], v[192:195], 0
	v_mfma_f32_16x16x32_bf16 v[50:53], v[184:187], v[192:195], 0
	v_mfma_f32_16x16x32_bf16 v[38:41], v[162:165], v[200:203], 0
	v_mfma_f32_16x16x32_bf16 v[34:37], v[184:187], v[200:203], 0
	v_mfma_f32_16x16x32_bf16 v[22:25], v[162:165], v[208:211], 0
	v_mfma_f32_16x16x32_bf16 v[18:21], v[184:187], v[208:211], 0
	v_mfma_f32_16x16x32_bf16 v[6:9], v[162:165], v[216:219], 0
	v_mfma_f32_16x16x32_bf16 v[2:5], v[184:187], v[216:219], 0
	v_mfma_f32_16x16x32_bf16 v[54:57], v[180:183], v[196:199], v[54:57]
	v_mfma_f32_16x16x32_bf16 v[50:53], v[188:191], v[196:199], v[50:53]
	v_mfma_f32_16x16x32_bf16 v[38:41], v[180:183], v[204:207], v[38:41]
	v_mfma_f32_16x16x32_bf16 v[34:37], v[188:191], v[204:207], v[34:37]
	v_mfma_f32_16x16x32_bf16 v[22:25], v[180:183], v[212:215], v[22:25]
	v_mfma_f32_16x16x32_bf16 v[18:21], v[188:191], v[212:215], v[18:21]
	v_mfma_f32_16x16x32_bf16 v[6:9], v[180:183], v[220:223], v[6:9]
	v_mfma_f32_16x16x32_bf16 v[2:5], v[188:191], v[220:223], v[2:5]
	s_setprio 0
	s_barrier
	s_add_i32 s51, 0, 0x18000
	s_add_i32 s52, 0, 0x1c000
	v_add_u32_e32 v78, s51, v169
	v_add_u32_e32 v168, s52, v169
	ds_read_b128 v[66:69], v78
	ds_read_b128 v[70:73], v78 offset:1024
	ds_read_b128 v[74:77], v78 offset:2048
	ds_read_b128 v[78:81], v78 offset:3072
	ds_read_b128 v[162:165], v168
	ds_read_b128 v[180:183], v168 offset:1024
	ds_read_b128 v[184:187], v168 offset:2048
	ds_read_b128 v[188:191], v168 offset:3072
	s_add_u32 s40, s40, 0x80000
	s_addc_u32 s41, s41, 0
	s_mov_b32 m0, s31
	v_lshl_add_u64 v[230:231], s[40:41], 0, v[152:153]
	ds_read_b128 v[192:195], v175 offset:32768
	ds_read_b128 v[196:199], v175 offset:33792
	ds_read_b128 v[200:203], v175 offset:34816
	ds_read_b128 v[204:207], v175 offset:35840
	ds_read_b128 v[208:211], v175 offset:36864
	ds_read_b128 v[212:215], v175 offset:37888
	ds_read_b128 v[216:219], v175 offset:38912
	ds_read_b128 v[220:223], v175 offset:39936
	global_load_lds_dwordx4 v[230:231], off
	v_lshl_add_u64 v[230:231], s[40:41], 0, v[148:149]
	s_mov_b32 m0, s33
	s_nop 0
	global_load_lds_dwordx4 v[230:231], off
	s_waitcnt vmcnt(8)
	s_waitcnt lgkmcnt(0)
	s_barrier
	s_setprio 1
	s_waitcnt lgkmcnt(0)
	v_mfma_f32_16x16x32_bf16 v[142:145], v[66:69], v[192:195], v[142:145]
	v_mfma_f32_16x16x32_bf16 v[138:141], v[74:77], v[192:195], v[138:141]
	v_mfma_f32_16x16x32_bf16 v[126:129], v[66:69], v[200:203], v[126:129]
	v_mfma_f32_16x16x32_bf16 v[122:125], v[74:77], v[200:203], v[122:125]
	v_mfma_f32_16x16x32_bf16 v[110:113], v[66:69], v[208:211], v[110:113]
	v_mfma_f32_16x16x32_bf16 v[106:109], v[74:77], v[208:211], v[106:109]
	v_mfma_f32_16x16x32_bf16 v[94:97], v[66:69], v[216:219], v[94:97]
	v_mfma_f32_16x16x32_bf16 v[90:93], v[74:77], v[216:219], v[90:93]
	v_mfma_f32_16x16x32_bf16 v[142:145], v[70:73], v[196:199], v[142:145]
	v_mfma_f32_16x16x32_bf16 v[138:141], v[78:81], v[196:199], v[138:141]
	v_mfma_f32_16x16x32_bf16 v[126:129], v[70:73], v[204:207], v[126:129]
	v_mfma_f32_16x16x32_bf16 v[122:125], v[78:81], v[204:207], v[122:125]
	v_mfma_f32_16x16x32_bf16 v[110:113], v[70:73], v[212:215], v[110:113]
	v_mfma_f32_16x16x32_bf16 v[106:109], v[78:81], v[212:215], v[106:109]
	v_mfma_f32_16x16x32_bf16 v[94:97], v[70:73], v[220:223], v[94:97]
	v_mfma_f32_16x16x32_bf16 v[90:93], v[78:81], v[220:223], v[90:93]
	v_mfma_f32_16x16x32_bf16 v[134:137], v[162:165], v[192:195], v[134:137]
	v_mfma_f32_16x16x32_bf16 v[130:133], v[184:187], v[192:195], v[130:133]
	v_mfma_f32_16x16x32_bf16 v[118:121], v[162:165], v[200:203], v[118:121]
	v_mfma_f32_16x16x32_bf16 v[114:117], v[184:187], v[200:203], v[114:117]
	v_mfma_f32_16x16x32_bf16 v[102:105], v[162:165], v[208:211], v[102:105]
	v_mfma_f32_16x16x32_bf16 v[98:101], v[184:187], v[208:211], v[98:101]
	v_mfma_f32_16x16x32_bf16 v[86:89], v[162:165], v[216:219], v[86:89]
	v_mfma_f32_16x16x32_bf16 v[82:85], v[184:187], v[216:219], v[82:85]
	v_mfma_f32_16x16x32_bf16 v[134:137], v[180:183], v[196:199], v[134:137]
	v_mfma_f32_16x16x32_bf16 v[130:133], v[188:191], v[196:199], v[130:133]
	v_mfma_f32_16x16x32_bf16 v[118:121], v[180:183], v[204:207], v[118:121]
	v_mfma_f32_16x16x32_bf16 v[114:117], v[188:191], v[204:207], v[114:117]
	v_mfma_f32_16x16x32_bf16 v[102:105], v[180:183], v[212:215], v[102:105]
	v_mfma_f32_16x16x32_bf16 v[98:101], v[188:191], v[212:215], v[98:101]
	v_mfma_f32_16x16x32_bf16 v[86:89], v[180:183], v[220:223], v[86:89]
	v_mfma_f32_16x16x32_bf16 v[82:85], v[188:191], v[220:223], v[82:85]
	s_setprio 0
	s_barrier
; #define PG8_STAGE(bufoff, gbase, voff) do { _Pragma("unroll") for (int _i = 0; _i < 2; ++_i) \
;         __builtin_amdgcn_global_load_lds((const unsigned*)((const char*)(gbase) + (voff)[_i]), (LAS unsigned*)(lds + (bufoff) + ldsw + _i * 8192), 16, 0, 0); } while (0)
; #define PG8_LDA(dst, b, h) do { _Pragma("unroll") for (int m = 0; m < 4; ++m) _Pragma("unroll") for (int k = 0; k < 2; ++k) dst[m][k] = *(const LAS bf16x8*)(lds + PG8_SA(b, h) + aoff + m * 2048 + k * 1024); } while (0)
; #define PG8_MMA(ai, bj, At, Bt) do { __builtin_amdgcn_s_setprio(1); _Pragma("unroll") for (int m = 0; m < 4; ++m) _Pragma("unroll") for (int n = 0; n < 2; ++n) _Pragma("unroll") for (int k = 0; k < 2; ++k) \
;         acc[ai][bj][m][n] = __builtin_amdgcn_mfma_f32_16x16x32_bf16(Bt[n][k], At[m][k], acc[ai][bj][m][n], 0, 0, 0); __builtin_amdgcn_s_setprio(0); } while (0)
; #define PG8_WAIT_V(n) asm volatile("s_waitcnt vmcnt(" #n ")" ::: "memory")
; #define PG8_WAIT_L(n) asm volatile("s_waitcnt lgkmcnt(" #n ")" ::: "memory")
; #define PG8_BAR __builtin_amdgcn_s_barrier()
; #define PG8_SCHED __builtin_amdgcn_sched_barrier(0)
; template <class Epi, class Sched, bool ALIGN_EPI = false, bool SP2 = false>
; __device__ __forceinline__ void gemm_phase(LAS unsigned char* lds, const Gemm g, const Sched& S, const Epi& E) {
;     ...
;         for (int t = 0; t < nt; t += 2) {
;             const bool last = (t == nt - 2);
;     ...
;             PG8_LDA(At, 1, 1); PG8_STAGE(PG8_SB(1, 0), b3, voffB); PG8_STAGE(PG8_SB(1, 1), b3 + hstepB, voffB); PG8_STAGE(PG8_SA(1, 0), a3, voffA);
;             PG8_WAIT_V(8); PG8_WAIT_L(0); PG8_BAR; PG8_MMA(1, 0, At, B0); PG8_MMA(1, 1, At, B1); PG8_BAR; PG8_SCHED;
	s_add_i32 s40, s51, s26
	v_lshl_add_u64 v[166:167], v[166:167], 0, s[8:9]
	s_mov_b32 m0, s40
	ds_read_b128 v[192:195], v175 offset:49152
	ds_read_b128 v[196:199], v175 offset:50176
	ds_read_b128 v[200:203], v175 offset:51200
	ds_read_b128 v[204:207], v175 offset:52224
	ds_read_b128 v[208:211], v175 offset:53248
	ds_read_b128 v[212:215], v175 offset:54272
	ds_read_b128 v[216:219], v175 offset:55296
	ds_read_b128 v[220:223], v175 offset:56320
	global_load_lds_dwordx4 v[166:167], off
	s_add_i32 m0, s40, 0x2000
	s_add_u32 s22, s22, 0x80080
	v_lshl_add_u64 v[166:167], v[224:225], 0, s[8:9]
	s_addc_u32 s23, s23, 0
	s_add_i32 s40, s52, s26
	global_load_lds_dwordx4 v[166:167], off
	v_lshl_add_u64 v[166:167], s[22:23], 0, v[150:151]
	s_mov_b32 m0, s40
	s_nop 0
	global_load_lds_dwordx4 v[166:167], off
	v_lshl_add_u64 v[166:167], s[22:23], 0, v[146:147]
	s_add_i32 m0, s40, 0x2000
	s_nop 0
	global_load_lds_dwordx4 v[166:167], off
	v_lshl_add_u64 v[166:167], v[226:227], 0, s[8:9]
	s_mov_b32 m0, s42
	s_nop 0
	global_load_lds_dwordx4 v[166:167], off
	v_lshl_add_u64 v[166:167], v[228:229], 0, s[8:9]
	s_mov_b32 m0, s43
	s_nop 0
	global_load_lds_dwordx4 v[166:167], off
	s_waitcnt vmcnt(8)
	s_waitcnt lgkmcnt(0)
	s_barrier
	s_setprio 1
	s_waitcnt lgkmcnt(0)
	v_mfma_f32_16x16x32_bf16 v[62:65], v[66:69], v[192:195], v[62:65]
	v_mfma_f32_16x16x32_bf16 v[58:61], v[74:77], v[192:195], v[58:61]
	v_mfma_f32_16x16x32_bf16 v[46:49], v[66:69], v[200:203], v[46:49]
	v_mfma_f32_16x16x32_bf16 v[42:45], v[74:77], v[200:203], v[42:45]
	v_mfma_f32_16x16x32_bf16 v[30:33], v[66:69], v[208:211], v[30:33]
	v_mfma_f32_16x16x32_bf16 v[26:29], v[74:77], v[208:211], v[26:29]
	v_mfma_f32_16x16x32_bf16 v[14:17], v[66:69], v[216:219], v[14:17]
	v_mfma_f32_16x16x32_bf16 v[10:13], v[74:77], v[216:219], v[10:13]
	v_mfma_f32_16x16x32_bf16 v[62:65], v[70:73], v[196:199], v[62:65]
	v_mfma_f32_16x16x32_bf16 v[58:61], v[78:81], v[196:199], v[58:61]
	v_mfma_f32_16x16x32_bf16 v[46:49], v[70:73], v[204:207], v[46:49]
	v_mfma_f32_16x16x32_bf16 v[42:45], v[78:81], v[204:207], v[42:45]
	v_mfma_f32_16x16x32_bf16 v[30:33], v[70:73], v[212:215], v[30:33]
	v_mfma_f32_16x16x32_bf16 v[26:29], v[78:81], v[212:215], v[26:29]
	v_mfma_f32_16x16x32_bf16 v[14:17], v[70:73], v[220:223], v[14:17]
	v_mfma_f32_16x16x32_bf16 v[10:13], v[78:81], v[220:223], v[10:13]
	v_mfma_f32_16x16x32_bf16 v[54:57], v[162:165], v[192:195], v[54:57]
	v_mfma_f32_16x16x32_bf16 v[50:53], v[184:187], v[192:195], v[50:53]
	v_mfma_f32_16x16x32_bf16 v[38:41], v[162:165], v[200:203], v[38:41]
	v_mfma_f32_16x16x32_bf16 v[34:37], v[184:187], v[200:203], v[34:37]
	v_mfma_f32_16x16x32_bf16 v[22:25], v[162:165], v[208:211], v[22:25]
	v_mfma_f32_16x16x32_bf16 v[18:21], v[184:187], v[208:211], v[18:21]
	v_mfma_f32_16x16x32_bf16 v[6:9], v[162:165], v[216:219], v[6:9]
	v_mfma_f32_16x16x32_bf16 v[2:5], v[184:187], v[216:219], v[2:5]
	v_mfma_f32_16x16x32_bf16 v[54:57], v[180:183], v[196:199], v[54:57]
	v_mfma_f32_16x16x32_bf16 v[50:53], v[188:191], v[196:199], v[50:53]
	v_mfma_f32_16x16x32_bf16 v[38:41], v[180:183], v[204:207], v[38:41]
	v_mfma_f32_16x16x32_bf16 v[34:37], v[188:191], v[204:207], v[34:37]
	v_mfma_f32_16x16x32_bf16 v[22:25], v[180:183], v[212:215], v[22:25]
	v_mfma_f32_16x16x32_bf16 v[18:21], v[188:191], v[212:215], v[18:21]
	v_mfma_f32_16x16x32_bf16 v[6:9], v[180:183], v[220:223], v[6:9]
	v_mfma_f32_16x16x32_bf16 v[2:5], v[188:191], v[220:223], v[2:5]
	s_setprio 0
	s_barrier
	s_add_i32 s50, s50, 2
	s_add_u32 s25, s25, 0x100
	s_addc_u32 s49, s49, 0
	s_add_u32 s16, s16, 0x100
	s_addc_u32 s17, s17, 0
	s_cmp_lt_u32 s50, 30
.LBB0_1822:
	ds_read_b128 v[66:69], v173
	ds_read_b128 v[70:73], v173 offset:1024
	ds_read_b128 v[74:77], v173 offset:2048
	ds_read_b128 v[78:81], v173 offset:3072
	ds_read_b128 v[162:165], v174
	ds_read_b128 v[180:183], v174 offset:1024
	ds_read_b128 v[184:187], v174 offset:2048
	ds_read_b128 v[188:191], v174 offset:3072
	s_add_u32 s22, s16, 0xfff80080
	s_addc_u32 s23, s17, -1
	s_cmp_eq_u32 s50, 28
	s_cselect_b32 s41, s3, s23
	s_cselect_b32 s40, s15, s22
	s_cselect_b32 s23, s13, s49
	s_cselect_b32 s22, s24, s25
	v_lshl_add_u64 v[166:167], s[16:17], 0, v[156:157]
	s_add_i32 m0, s29, 0xc000
	ds_read_b128 v[192:195], v175
	ds_read_b128 v[196:199], v175 offset:1024
	ds_read_b128 v[200:203], v175 offset:2048
	ds_read_b128 v[204:207], v175 offset:3072
	ds_read_b128 v[208:211], v175 offset:4096
	ds_read_b128 v[212:215], v175 offset:5120
	ds_read_b128 v[216:219], v175 offset:6144
	ds_read_b128 v[220:223], v175 offset:7168
	global_load_lds_dwordx4 v[166:167], off
	v_lshl_add_u64 v[166:167], s[16:17], 0, v[154:155]
	s_add_i32 m0, s29, 0xe000
	s_nop 0
	global_load_lds_dwordx4 v[166:167], off
	s_waitcnt vmcnt(8)
	s_waitcnt lgkmcnt(0)
	s_barrier
; #define PG8_STAGE(bufoff, gbase, voff) do { _Pragma("unroll") for (int _i = 0; _i < 2; ++_i) \
;         __builtin_amdgcn_global_load_lds((const unsigned*)((const char*)(gbase) + (voff)[_i]), (LAS unsigned*)(lds + (bufoff) + ldsw + _i * 8192), 16, 0, 0); } while (0)
; #define PG8_LDA(dst, b, h) do { _Pragma("unroll") for (int m = 0; m < 4; ++m) _Pragma("unroll") for (int k = 0; k < 2; ++k) dst[m][k] = *(const LAS bf16x8*)(lds + PG8_SA(b, h) + aoff + m * 2048 + k * 1024); } while (0)
; #define PG8_LDB(dst, b, h) do { _Pragma("unroll") for (int n = 0; n < 2; ++n) _Pragma("unroll") for (int k = 0; k < 2; ++k) dst[n][k] = *(const LAS bf16x8*)(lds + PG8_SB(b, h) + boff + n * 2048 + k * 1024); } while (0)
; #define PG8_MMA(ai, bj, At, Bt) do { __builtin_amdgcn_s_setprio(1); _Pragma("unroll") for (int m = 0; m < 4; ++m) _Pragma("unroll") for (int n = 0; n < 2; ++n) _Pragma("unroll") for (int k = 0; k < 2; ++k) \
;         acc[ai][bj][m][n] = __builtin_amdgcn_mfma_f32_16x16x32_bf16(Bt[n][k], At[m][k], acc[ai][bj][m][n], 0, 0, 0); __builtin_amdgcn_s_setprio(0); } while (0)
; #define PG8_WAIT_V(n) asm volatile("s_waitcnt vmcnt(" #n ")" ::: "memory")
; #define PG8_WAIT_L(n) asm volatile("s_waitcnt lgkmcnt(" #n ")" ::: "memory")
; #define PG8_BAR __builtin_amdgcn_s_barrier()
; #define PG8_SCHED __builtin_amdgcn_sched_barrier(0)
; template <class Epi, class Sched, bool ALIGN_EPI = false, bool SP2 = false>
; __device__ __forceinline__ void gemm_phase(LAS unsigned char* lds, const Gemm g, const Sched& S, const Epi& E) {
;     ...
;             PG8_LDB(B0, 0, 0); PG8_LDB(B1, 0, 1); PG8_SCHED; PG8_LDA(At, 0, 0); PG8_STAGE(PG8_SA(1, 1), a1 + hstep, voffA);
;             PG8_WAIT_V(8); PG8_WAIT_L(0); PG8_BAR; PG8_MMA(0, 0, At, B0); PG8_MMA(0, 1, At, B1); PG8_BAR; PG8_SCHED;
;             PG8_LDA(At, 0, 1); PG8_STAGE(PG8_SB(0, 0), b2, voffB); PG8_STAGE(PG8_SB(0, 1), b2 + hstepB, voffB); PG8_STAGE(PG8_SA(0, 0), a2, voffA);
;             PG8_WAIT_V(8); PG8_WAIT_L(0); PG8_BAR; PG8_MMA(1, 0, At, B0); PG8_MMA(1, 1, At, B1); PG8_BAR; PG8_SCHED;
	s_setprio 1
	s_waitcnt lgkmcnt(0)
	v_mfma_f32_16x16x32_bf16 v[142:145], v[66:69], v[192:195], v[142:145]
	v_mfma_f32_16x16x32_bf16 v[138:141], v[74:77], v[192:195], v[138:141]
	v_mfma_f32_16x16x32_bf16 v[126:129], v[66:69], v[200:203], v[126:129]
	v_mfma_f32_16x16x32_bf16 v[122:125], v[74:77], v[200:203], v[122:125]
	v_mfma_f32_16x16x32_bf16 v[110:113], v[66:69], v[208:211], v[110:113]
	v_mfma_f32_16x16x32_bf16 v[106:109], v[74:77], v[208:211], v[106:109]
	v_mfma_f32_16x16x32_bf16 v[94:97], v[66:69], v[216:219], v[94:97]
	v_mfma_f32_16x16x32_bf16 v[90:93], v[74:77], v[216:219], v[90:93]
	v_mfma_f32_16x16x32_bf16 v[142:145], v[70:73], v[196:199], v[142:145]
	v_mfma_f32_16x16x32_bf16 v[138:141], v[78:81], v[196:199], v[138:141]
	v_mfma_f32_16x16x32_bf16 v[126:129], v[70:73], v[204:207], v[126:129]
	v_mfma_f32_16x16x32_bf16 v[122:125], v[78:81], v[204:207], v[122:125]
	v_mfma_f32_16x16x32_bf16 v[110:113], v[70:73], v[212:215], v[110:113]
	v_mfma_f32_16x16x32_bf16 v[106:109], v[78:81], v[212:215], v[106:109]
	v_mfma_f32_16x16x32_bf16 v[94:97], v[70:73], v[220:223], v[94:97]
	v_mfma_f32_16x16x32_bf16 v[90:93], v[78:81], v[220:223], v[90:93]
	v_mfma_f32_16x16x32_bf16 v[134:137], v[162:165], v[192:195], v[134:137]
	v_mfma_f32_16x16x32_bf16 v[130:133], v[184:187], v[192:195], v[130:133]
	v_mfma_f32_16x16x32_bf16 v[118:121], v[162:165], v[200:203], v[118:121]
	v_mfma_f32_16x16x32_bf16 v[114:117], v[184:187], v[200:203], v[114:117]
	v_mfma_f32_16x16x32_bf16 v[102:105], v[162:165], v[208:211], v[102:105]
	v_mfma_f32_16x16x32_bf16 v[98:101], v[184:187], v[208:211], v[98:101]
	v_mfma_f32_16x16x32_bf16 v[86:89], v[162:165], v[216:219], v[86:89]
	v_mfma_f32_16x16x32_bf16 v[82:85], v[184:187], v[216:219], v[82:85]
	v_mfma_f32_16x16x32_bf16 v[134:137], v[180:183], v[196:199], v[134:137]
	v_mfma_f32_16x16x32_bf16 v[130:133], v[188:191], v[196:199], v[130:133]
	v_mfma_f32_16x16x32_bf16 v[118:121], v[180:183], v[204:207], v[118:121]
	v_mfma_f32_16x16x32_bf16 v[114:117], v[188:191], v[204:207], v[114:117]
	v_mfma_f32_16x16x32_bf16 v[102:105], v[180:183], v[212:215], v[102:105]
	v_mfma_f32_16x16x32_bf16 v[98:101], v[188:191], v[212:215], v[98:101]
	v_mfma_f32_16x16x32_bf16 v[86:89], v[180:183], v[220:223], v[86:89]
	v_mfma_f32_16x16x32_bf16 v[82:85], v[188:191], v[220:223], v[82:85]
	s_setprio 0
	s_barrier
	s_add_i32 s51, s44, s26
	v_lshl_add_u64 v[166:167], s[22:23], 0, v[150:151]
	s_mov_b32 m0, s51
	ds_read_b128 v[192:195], v175 offset:16384
	ds_read_b128 v[196:199], v175 offset:17408
	ds_read_b128 v[200:203], v175 offset:18432
	ds_read_b128 v[204:207], v175 offset:19456
	ds_read_b128 v[208:211], v175 offset:20480
	ds_read_b128 v[212:215], v175 offset:21504
	ds_read_b128 v[216:219], v175 offset:22528
	ds_read_b128 v[220:223], v175 offset:23552
	global_load_lds_dwordx4 v[166:167], off
	s_add_i32 m0, s51, 0x2000
	s_add_u32 s52, s22, 0x80000
	v_lshl_add_u64 v[224:225], s[22:23], 0, v[146:147]
	s_addc_u32 s53, s23, 0
	s_add_i32 s51, s45, s26
	global_load_lds_dwordx4 v[224:225], off
	v_lshl_add_u64 v[226:227], s[52:53], 0, v[150:151]
	s_mov_b32 m0, s51
	v_lshl_add_u64 v[228:229], s[40:41], 0, v[148:149]
	global_load_lds_dwordx4 v[226:227], off
	v_lshl_add_u64 v[226:227], s[52:53], 0, v[146:147]
	s_add_i32 m0, s51, 0x2000
	s_nop 0
	global_load_lds_dwordx4 v[226:227], off
	v_lshl_add_u64 v[226:227], s[40:41], 0, v[152:153]
	s_mov_b32 m0, s29
	s_nop 0
	global_load_lds_dwordx4 v[226:227], off
	s_mov_b32 m0, s30
	s_nop 0
	global_load_lds_dwordx4 v[228:229], off
	s_waitcnt vmcnt(8)
	s_waitcnt lgkmcnt(0)
	s_barrier
	s_setprio 1
	s_waitcnt lgkmcnt(0)
	v_mfma_f32_16x16x32_bf16 v[62:65], v[66:69], v[192:195], v[62:65]
	v_mfma_f32_16x16x32_bf16 v[58:61], v[74:77], v[192:195], v[58:61]
	v_mfma_f32_16x16x32_bf16 v[46:49], v[66:69], v[200:203], v[46:49]
	v_mfma_f32_16x16x32_bf16 v[42:45], v[74:77], v[200:203], v[42:45]
	v_mfma_f32_16x16x32_bf16 v[30:33], v[66:69], v[208:211], v[30:33]
	v_mfma_f32_16x16x32_bf16 v[26:29], v[74:77], v[208:211], v[26:29]
	v_mfma_f32_16x16x32_bf16 v[14:17], v[66:69], v[216:219], v[14:17]
	v_mfma_f32_16x16x32_bf16 v[10:13], v[74:77], v[216:219], v[10:13]
	v_mfma_f32_16x16x32_bf16 v[62:65], v[70:73], v[196:199], v[62:65]
	v_mfma_f32_16x16x32_bf16 v[58:61], v[78:81], v[196:199], v[58:61]
	v_mfma_f32_16x16x32_bf16 v[46:49], v[70:73], v[204:207], v[46:49]
	v_mfma_f32_16x16x32_bf16 v[42:45], v[78:81], v[204:207], v[42:45]
	v_mfma_f32_16x16x32_bf16 v[30:33], v[70:73], v[212:215], v[30:33]
	v_mfma_f32_16x16x32_bf16 v[26:29], v[78:81], v[212:215], v[26:29]
	v_mfma_f32_16x16x32_bf16 v[14:17], v[70:73], v[220:223], v[14:17]
	v_mfma_f32_16x16x32_bf16 v[10:13], v[78:81], v[220:223], v[10:13]
	v_mfma_f32_16x16x32_bf16 v[54:57], v[162:165], v[192:195], v[54:57]
	v_mfma_f32_16x16x32_bf16 v[50:53], v[184:187], v[192:195], v[50:53]
	v_mfma_f32_16x16x32_bf16 v[38:41], v[162:165], v[200:203], v[38:41]
	v_mfma_f32_16x16x32_bf16 v[34:37], v[184:187], v[200:203], v[34:37]
	v_mfma_f32_16x16x32_bf16 v[22:25], v[162:165], v[208:211], v[22:25]
	v_mfma_f32_16x16x32_bf16 v[18:21], v[184:187], v[208:211], v[18:21]
	v_mfma_f32_16x16x32_bf16 v[6:9], v[162:165], v[216:219], v[6:9]
	v_mfma_f32_16x16x32_bf16 v[2:5], v[184:187], v[216:219], v[2:5]
	v_mfma_f32_16x16x32_bf16 v[54:57], v[180:183], v[196:199], v[54:57]
	v_mfma_f32_16x16x32_bf16 v[50:53], v[188:191], v[196:199], v[50:53]
	v_mfma_f32_16x16x32_bf16 v[38:41], v[180:183], v[204:207], v[38:41]
	v_mfma_f32_16x16x32_bf16 v[34:37], v[188:191], v[204:207], v[34:37]
	v_mfma_f32_16x16x32_bf16 v[22:25], v[180:183], v[212:215], v[22:25]
	v_mfma_f32_16x16x32_bf16 v[18:21], v[188:191], v[212:215], v[18:21]
	v_mfma_f32_16x16x32_bf16 v[6:9], v[180:183], v[220:223], v[6:9]
	v_mfma_f32_16x16x32_bf16 v[2:5], v[188:191], v[220:223], v[2:5]
	s_setprio 0
	s_barrier
; #define PG8_STAGE(bufoff, gbase, voff) do { _Pragma("unroll") for (int _i = 0; _i < 2; ++_i) \
;         __builtin_amdgcn_global_load_lds((const unsigned*)((const char*)(gbase) + (voff)[_i]), (LAS unsigned*)(lds + (bufoff) + ldsw + _i * 8192), 16, 0, 0); } while (0)
; #define PG8_LDA(dst, b, h) do { _Pragma("unroll") for (int m = 0; m < 4; ++m) _Pragma("unroll") for (int k = 0; k < 2; ++k) dst[m][k] = *(const LAS bf16x8*)(lds + PG8_SA(b, h) + aoff + m * 2048 + k * 1024); } while (0)
; #define PG8_LDB(dst, b, h) do { _Pragma("unroll") for (int n = 0; n < 2; ++n) _Pragma("unroll") for (int k = 0; k < 2; ++k) dst[n][k] = *(const LAS bf16x8*)(lds + PG8_SB(b, h) + boff + n * 2048 + k * 1024); } while (0)
; #define PG8_MMA(ai, bj, At, Bt) do { __builtin_amdgcn_s_setprio(1); _Pragma("unroll") for (int m = 0; m < 4; ++m) _Pragma("unroll") for (int n = 0; n < 2; ++n) _Pragma("unroll") for (int k = 0; k < 2; ++k) \
;         acc[ai][bj][m][n] = __builtin_amdgcn_mfma_f32_16x16x32_bf16(Bt[n][k], At[m][k], acc[ai][bj][m][n], 0, 0, 0); __builtin_amdgcn_s_setprio(0); } while (0)
; #define PG8_WAIT_V(n) asm volatile("s_waitcnt vmcnt(" #n ")" ::: "memory")
; #define PG8_WAIT_L(n) asm volatile("s_waitcnt lgkmcnt(" #n ")" ::: "memory")
; #define PG8_BAR __builtin_amdgcn_s_barrier()
; #define PG8_SCHED __builtin_amdgcn_sched_barrier(0)
; template <class Epi, class Sched, bool ALIGN_EPI = false, bool SP2 = false>
; __device__ __forceinline__ void gemm_phase(LAS unsigned char* lds, const Gemm g, const Sched& S, const Epi& E) {
;     ...
;             PG8_LDB(B0, 1, 0); PG8_LDB(B1, 1, 1); PG8_SCHED; PG8_LDA(At, 1, 0); PG8_STAGE(PG8_SA(0, 1), a2 + hstep, voffA);
;             PG8_WAIT_V(8); PG8_WAIT_L(0); PG8_BAR; PG8_MMA(0, 0, At, B0); PG8_MMA(0, 1, At, B1); PG8_BAR; PG8_SCHED;
	s_add_i32 s51, 0, 0x18000
	s_add_i32 s52, 0, 0x1c000
	v_add_u32_e32 v78, s51, v169
	v_add_u32_e32 v168, s52, v169
	ds_read_b128 v[66:69], v78
	ds_read_b128 v[70:73], v78 offset:1024
	ds_read_b128 v[74:77], v78 offset:2048
	ds_read_b128 v[78:81], v78 offset:3072
	ds_read_b128 v[162:165], v168
	ds_read_b128 v[180:183], v168 offset:1024
	ds_read_b128 v[184:187], v168 offset:2048
	ds_read_b128 v[188:191], v168 offset:3072
	s_add_u32 s40, s40, 0x80000
	s_addc_u32 s41, s41, 0
	s_mov_b32 m0, s31
	v_lshl_add_u64 v[230:231], s[40:41], 0, v[152:153]
	ds_read_b128 v[192:195], v175 offset:32768
	ds_read_b128 v[196:199], v175 offset:33792
	ds_read_b128 v[200:203], v175 offset:34816
	ds_read_b128 v[204:207], v175 offset:35840
	ds_read_b128 v[208:211], v175 offset:36864
	ds_read_b128 v[212:215], v175 offset:37888
	ds_read_b128 v[216:219], v175 offset:38912
	ds_read_b128 v[220:223], v175 offset:39936
	global_load_lds_dwordx4 v[230:231], off
	v_lshl_add_u64 v[230:231], s[40:41], 0, v[148:149]
	s_mov_b32 m0, s33
	s_nop 0
	global_load_lds_dwordx4 v[230:231], off
	s_waitcnt vmcnt(8)
	s_waitcnt lgkmcnt(0)
	s_barrier
	s_setprio 1
	s_waitcnt lgkmcnt(0)
	v_mfma_f32_16x16x32_bf16 v[142:145], v[66:69], v[192:195], v[142:145]
	v_mfma_f32_16x16x32_bf16 v[138:141], v[74:77], v[192:195], v[138:141]
	v_mfma_f32_16x16x32_bf16 v[126:129], v[66:69], v[200:203], v[126:129]
	v_mfma_f32_16x16x32_bf16 v[122:125], v[74:77], v[200:203], v[122:125]
	v_mfma_f32_16x16x32_bf16 v[110:113], v[66:69], v[208:211], v[110:113]
	v_mfma_f32_16x16x32_bf16 v[106:109], v[74:77], v[208:211], v[106:109]
	v_mfma_f32_16x16x32_bf16 v[94:97], v[66:69], v[216:219], v[94:97]
	v_mfma_f32_16x16x32_bf16 v[90:93], v[74:77], v[216:219], v[90:93]
	v_mfma_f32_16x16x32_bf16 v[142:145], v[70:73], v[196:199], v[142:145]
	v_mfma_f32_16x16x32_bf16 v[138:141], v[78:81], v[196:199], v[138:141]
	v_mfma_f32_16x16x32_bf16 v[126:129], v[70:73], v[204:207], v[126:129]
	v_mfma_f32_16x16x32_bf16 v[122:125], v[78:81], v[204:207], v[122:125]
	v_mfma_f32_16x16x32_bf16 v[110:113], v[70:73], v[212:215], v[110:113]
	v_mfma_f32_16x16x32_bf16 v[106:109], v[78:81], v[212:215], v[106:109]
	v_mfma_f32_16x16x32_bf16 v[94:97], v[70:73], v[220:223], v[94:97]
	v_mfma_f32_16x16x32_bf16 v[90:93], v[78:81], v[220:223], v[90:93]
	v_mfma_f32_16x16x32_bf16 v[134:137], v[162:165], v[192:195], v[134:137]
	v_mfma_f32_16x16x32_bf16 v[130:133], v[184:187], v[192:195], v[130:133]
	v_mfma_f32_16x16x32_bf16 v[118:121], v[162:165], v[200:203], v[118:121]
	v_mfma_f32_16x16x32_bf16 v[114:117], v[184:187], v[200:203], v[114:117]
	v_mfma_f32_16x16x32_bf16 v[102:105], v[162:165], v[208:211], v[102:105]
	v_mfma_f32_16x16x32_bf16 v[98:101], v[184:187], v[208:211], v[98:101]
	v_mfma_f32_16x16x32_bf16 v[86:89], v[162:165], v[216:219], v[86:89]
	v_mfma_f32_16x16x32_bf16 v[82:85], v[184:187], v[216:219], v[82:85]
	v_mfma_f32_16x16x32_bf16 v[134:137], v[180:183], v[196:199], v[134:137]
	v_mfma_f32_16x16x32_bf16 v[130:133], v[188:191], v[196:199], v[130:133]
	v_mfma_f32_16x16x32_bf16 v[118:121], v[180:183], v[204:207], v[118:121]
	v_mfma_f32_16x16x32_bf16 v[114:117], v[188:191], v[204:207], v[114:117]
	v_mfma_f32_16x16x32_bf16 v[102:105], v[180:183], v[212:215], v[102:105]
	v_mfma_f32_16x16x32_bf16 v[98:101], v[188:191], v[212:215], v[98:101]
	v_mfma_f32_16x16x32_bf16 v[86:89], v[180:183], v[220:223], v[86:89]
	v_mfma_f32_16x16x32_bf16 v[82:85], v[188:191], v[220:223], v[82:85]
	s_setprio 0
	s_barrier
; #define PG8_STAGE(bufoff, gbase, voff) do { _Pragma("unroll") for (int _i = 0; _i < 2; ++_i) \
;         __builtin_amdgcn_global_load_lds((const unsigned*)((const char*)(gbase) + (voff)[_i]), (LAS unsigned*)(lds + (bufoff) + ldsw + _i * 8192), 16, 0, 0); } while (0)
; #define PG8_LDA(dst, b, h) do { _Pragma("unroll") for (int m = 0; m < 4; ++m) _Pragma("unroll") for (int k = 0; k < 2; ++k) dst[m][k] = *(const LAS bf16x8*)(lds + PG8_SA(b, h) + aoff + m * 2048 + k * 1024); } while (0)
; #define PG8_MMA(ai, bj, At, Bt) do { __builtin_amdgcn_s_setprio(1); _Pragma("unroll") for (int m = 0; m < 4; ++m) _Pragma("unroll") for (int n = 0; n < 2; ++n) _Pragma("unroll") for (int k = 0; k < 2; ++k) \
;         acc[ai][bj][m][n] = __builtin_amdgcn_mfma_f32_16x16x32_bf16(Bt[n][k], At[m][k], acc[ai][bj][m][n], 0, 0, 0); __builtin_amdgcn_s_setprio(0); } while (0)
; #define PG8_WAIT_V(n) asm volatile("s_waitcnt vmcnt(" #n ")" ::: "memory")
; #define PG8_WAIT_L(n) asm volatile("s_waitcnt lgkmcnt(" #n ")" ::: "memory")
; #define PG8_BAR __builtin_amdgcn_s_barrier()
; #define PG8_SCHED __builtin_amdgcn_sched_barrier(0)
; template <class Epi, class Sched, bool ALIGN_EPI = false, bool SP2 = false>
; __device__ __forceinline__ void gemm_phase(LAS unsigned char* lds, const Gemm g, const Sched& S, const Epi& E) {
;     ...
;         for (int t = 0; t < nt; t += 2) {
;             const bool last = (t == nt - 2);
;     ...
;             PG8_LDA(At, 1, 1); PG8_STAGE(PG8_SB(1, 0), b3, voffB); PG8_STAGE(PG8_SB(1, 1), b3 + hstepB, voffB); PG8_STAGE(PG8_SA(1, 0), a3, voffA);
;             PG8_WAIT_V(8); PG8_WAIT_L(0); PG8_BAR; PG8_MMA(1, 0, At, B0); PG8_MMA(1, 1, At, B1); PG8_BAR; PG8_SCHED;
	s_add_i32 s40, s51, s26
	v_lshl_add_u64 v[166:167], v[166:167], 0, s[8:9]
	s_mov_b32 m0, s40
	ds_read_b128 v[192:195], v175 offset:49152
	ds_read_b128 v[196:199], v175 offset:50176
	ds_read_b128 v[200:203], v175 offset:51200
	ds_read_b128 v[204:207], v175 offset:52224
	ds_read_b128 v[208:211], v175 offset:53248
	ds_read_b128 v[212:215], v175 offset:54272
	ds_read_b128 v[216:219], v175 offset:55296
	ds_read_b128 v[220:223], v175 offset:56320
	global_load_lds_dwordx4 v[166:167], off
	s_add_i32 m0, s40, 0x2000
	s_add_u32 s22, s22, 0x80080
	v_lshl_add_u64 v[166:167], v[224:225], 0, s[8:9]
	s_addc_u32 s23, s23, 0
	s_add_i32 s40, s52, s26
	global_load_lds_dwordx4 v[166:167], off
	v_lshl_add_u64 v[166:167], s[22:23], 0, v[150:151]
	s_mov_b32 m0, s40
	s_nop 0
	global_load_lds_dwordx4 v[166:167], off
	v_lshl_add_u64 v[166:167], s[22:23], 0, v[146:147]
	s_add_i32 m0, s40, 0x2000
	s_nop 0
	global_load_lds_dwordx4 v[166:167], off
	v_lshl_add_u64 v[166:167], v[226:227], 0, s[8:9]
	s_mov_b32 m0, s42
	s_nop 0
	global_load_lds_dwordx4 v[166:167], off
	v_lshl_add_u64 v[166:167], v[228:229], 0, s[8:9]
	s_mov_b32 m0, s43
	s_nop 0
	global_load_lds_dwordx4 v[166:167], off
	s_waitcnt vmcnt(8)
	s_waitcnt lgkmcnt(0)
	s_barrier
	s_setprio 1
	s_waitcnt lgkmcnt(0)
	v_mfma_f32_16x16x32_bf16 v[62:65], v[66:69], v[192:195], v[62:65]
	v_mfma_f32_16x16x32_bf16 v[58:61], v[74:77], v[192:195], v[58:61]
	v_mfma_f32_16x16x32_bf16 v[46:49], v[66:69], v[200:203], v[46:49]
	v_mfma_f32_16x16x32_bf16 v[42:45], v[74:77], v[200:203], v[42:45]
	v_mfma_f32_16x16x32_bf16 v[30:33], v[66:69], v[208:211], v[30:33]
	v_mfma_f32_16x16x32_bf16 v[26:29], v[74:77], v[208:211], v[26:29]
	v_mfma_f32_16x16x32_bf16 v[14:17], v[66:69], v[216:219], v[14:17]
	v_mfma_f32_16x16x32_bf16 v[10:13], v[74:77], v[216:219], v[10:13]
	v_mfma_f32_16x16x32_bf16 v[62:65], v[70:73], v[196:199], v[62:65]
	v_mfma_f32_16x16x32_bf16 v[58:61], v[78:81], v[196:199], v[58:61]
	v_mfma_f32_16x16x32_bf16 v[46:49], v[70:73], v[204:207], v[46:49]
	v_mfma_f32_16x16x32_bf16 v[42:45], v[78:81], v[204:207], v[42:45]
	v_mfma_f32_16x16x32_bf16 v[30:33], v[70:73], v[212:215], v[30:33]
	v_mfma_f32_16x16x32_bf16 v[26:29], v[78:81], v[212:215], v[26:29]
	v_mfma_f32_16x16x32_bf16 v[14:17], v[70:73], v[220:223], v[14:17]
	v_mfma_f32_16x16x32_bf16 v[10:13], v[78:81], v[220:223], v[10:13]
	v_mfma_f32_16x16x32_bf16 v[54:57], v[162:165], v[192:195], v[54:57]
	v_mfma_f32_16x16x32_bf16 v[50:53], v[184:187], v[192:195], v[50:53]
	v_mfma_f32_16x16x32_bf16 v[38:41], v[162:165], v[200:203], v[38:41]
	v_mfma_f32_16x16x32_bf16 v[34:37], v[184:187], v[200:203], v[34:37]
	v_mfma_f32_16x16x32_bf16 v[22:25], v[162:165], v[208:211], v[22:25]
	v_mfma_f32_16x16x32_bf16 v[18:21], v[184:187], v[208:211], v[18:21]
	v_mfma_f32_16x16x32_bf16 v[6:9], v[162:165], v[216:219], v[6:9]
	v_mfma_f32_16x16x32_bf16 v[2:5], v[184:187], v[216:219], v[2:5]
	v_mfma_f32_16x16x32_bf16 v[54:57], v[180:183], v[196:199], v[54:57]
	v_mfma_f32_16x16x32_bf16 v[50:53], v[188:191], v[196:199], v[50:53]
	v_mfma_f32_16x16x32_bf16 v[38:41], v[180:183], v[204:207], v[38:41]
	v_mfma_f32_16x16x32_bf16 v[34:37], v[188:191], v[204:207], v[34:37]
	v_mfma_f32_16x16x32_bf16 v[22:25], v[180:183], v[212:215], v[22:25]
	v_mfma_f32_16x16x32_bf16 v[18:21], v[188:191], v[212:215], v[18:21]
	v_mfma_f32_16x16x32_bf16 v[6:9], v[180:183], v[220:223], v[6:9]
	v_mfma_f32_16x16x32_bf16 v[2:5], v[188:191], v[220:223], v[2:5]
	s_setprio 0
	s_barrier
	s_add_i32 s50, s50, 2
	s_add_u32 s25, s25, 0x100
	s_addc_u32 s49, s49, 0
	s_add_u32 s16, s16, 0x100
	s_addc_u32 s17, s17, 0
	s_cmp_lt_u32 s50, 30
	s_cbranch_scc1 .LBB0_1822
	s_andn2_b64 vcc, exec, s[10:11]
	s_cbranch_vccnz .LBB0_1825
	s_barrier

; #define PG8_STAGE(bufoff, gbase, voff) do { _Pragma("unroll") for (int _i = 0; _i < 2; ++_i) \
;         __builtin_amdgcn_global_load_lds((const unsigned*)((const char*)(gbase) + (voff)[_i]), (LAS unsigned*)(lds + (bufoff) + ldsw + _i * 8192), 16, 0, 0); } while (0)
; #define PG8_LDA(dst, b, h) do { _Pragma("unroll") for (int m = 0; m < 4; ++m) _Pragma("unroll") for (int k = 0; k < 2; ++k) dst[m][k] = *(const LAS bf16x8*)(lds + PG8_SA(b, h) + aoff + m * 2048 + k * 1024); } while (0)
; #define PG8_LDB(dst, b, h) do { _Pragma("unroll") for (int n = 0; n < 2; ++n) _Pragma("unroll") for (int k = 0; k < 2; ++k) dst[n][k] = *(const LAS bf16x8*)(lds + PG8_SB(b, h) + boff + n * 2048 + k * 1024); } while (0)
; #define PG8_MMA(ai, bj, At, Bt) do { __builtin_amdgcn_s_setprio(1); _Pragma("unroll") for (int m = 0; m < 4; ++m) _Pragma("unroll") for (int n = 0; n < 2; ++n) _Pragma("unroll") for (int k = 0; k < 2; ++k) \
;         acc[ai][bj][m][n] = __builtin_amdgcn_mfma_f32_16x16x32_bf16(Bt[n][k], At[m][k], acc[ai][bj][m][n], 0, 0, 0); __builtin_amdgcn_s_setprio(0); } while (0)
; #define PG8_WAIT_V(n) asm volatile("s_waitcnt vmcnt(" #n ")" ::: "memory")
; #define PG8_WAIT_L(n) asm volatile("s_waitcnt lgkmcnt(" #n ")" ::: "memory")
; template <class Epi, class Sched, bool ALIGN_EPI = false, bool SP2 = false>
; __device__ __forceinline__ void gemm_phase(LAS unsigned char* lds, const Gemm g, const Sched& S, const Epi& E) {
;     ...
;         for (int t = 0; t < nt; t += 2) {
;             const bool last = (t == nt - 2);
;             const char* a1 = cA + (size_t)(t + 1) * kstep;
;             const char* a2 = last ? nA : cA + (size_t)(t + 2) * kstep; const char* b2 = last ? nB : cB + (size_t)(t + 2) * kstep;
;             const char* a3 = a2 + kstep; const char* b3 = b2 + kstep;
;             if (last && has_next) S.a_ready(nxt);
;             if constexpr (SP2) {
;             PG8_LDB(B0, 0, 0); PG8_LDB(B1, 0, 1); PG8_SCHED; PG8_LDA(At, 0, 0); PG8_STAGE(PG8_SA(1, 1), a1 + hstep, voffA);
;             PG8_WAIT_V(8); PG8_WAIT_L(0); PG8_BAR; PG8_MMA(0, 0, At, B0); PG8_MMA(0, 1, At, B1); PG8_BAR; PG8_SCHED;
;             PG8_LDA(At, 0, 1); PG8_STAGE(PG8_SB(0, 0), b2, voffB); PG8_STAGE(PG8_SB(0, 1), b2 + hstepB, voffB); PG8_STAGE(PG8_SA(0, 0), a2, voffA);
;             PG8_WAIT_V(8); PG8_WAIT_L(0); PG8_BAR; PG8_MMA(1, 0, At, B0); PG8_MMA(1, 1, At, B1); PG8_BAR; PG8_SCHED;
.LBB0_1896:
	ds_read_b128 v[144:147], v135
	ds_read_b128 v[148:151], v135 offset:1024
	ds_read_b128 v[152:155], v135 offset:2048
	ds_read_b128 v[156:159], v135 offset:3072
	ds_read_b128 v[160:163], v140
	ds_read_b128 v[164:167], v140 offset:1024
	ds_read_b128 v[168:171], v140 offset:2048
	ds_read_b128 v[172:175], v140 offset:3072
	s_add_i32 s40, s14, 2
	s_cmp_lg_u32 s28, s14
	s_cselect_b32 s14, s10, 0
	s_cselect_b32 s15, s11, 0
	s_add_u32 s16, s4, s14
	s_addc_u32 s17, s5, s15
	s_add_u32 s14, s2, s14
	s_addc_u32 s15, s3, s15
	v_lshl_add_u64 v[208:209], v[138:139], 0, s[10:11]
	s_mov_b32 m0, s29
	v_lshl_add_u64 v[208:209], v[208:209], 0, s[12:13]
	ds_read_b128 v[176:179], v141
	ds_read_b128 v[180:183], v141 offset:1024
	ds_read_b128 v[184:187], v141 offset:2048
	ds_read_b128 v[188:191], v141 offset:3072
	ds_read_b128 v[192:195], v141 offset:4096
	ds_read_b128 v[196:199], v141 offset:5120
	ds_read_b128 v[200:203], v141 offset:6144
	ds_read_b128 v[204:207], v141 offset:7168
	global_load_lds_dwordx4 v[208:209], off
	v_lshl_add_u64 v[208:209], v[136:137], 0, s[10:11]
	v_lshl_add_u64 v[208:209], v[208:209], 0, s[12:13]
	s_mov_b32 m0, s30
	s_nop 0
	global_load_lds_dwordx4 v[208:209], off
	s_waitcnt vmcnt(8)
	s_waitcnt lgkmcnt(0)
	s_barrier
	s_setprio 1
	s_waitcnt lgkmcnt(0)
	v_mfma_f32_16x16x32_bf16 v[126:129], v[144:147], v[176:179], v[126:129]
	v_mfma_f32_16x16x32_bf16 v[94:97], v[152:155], v[176:179], v[94:97]
	v_mfma_f32_16x16x32_bf16 v[122:125], v[144:147], v[184:187], v[122:125]
	v_mfma_f32_16x16x32_bf16 v[90:93], v[152:155], v[184:187], v[90:93]
	v_mfma_f32_16x16x32_bf16 v[118:121], v[144:147], v[192:195], v[118:121]
	v_mfma_f32_16x16x32_bf16 v[86:89], v[152:155], v[192:195], v[86:89]
	v_mfma_f32_16x16x32_bf16 v[114:117], v[144:147], v[200:203], v[114:117]
	v_mfma_f32_16x16x32_bf16 v[82:85], v[152:155], v[200:203], v[82:85]
	v_mfma_f32_16x16x32_bf16 v[126:129], v[148:151], v[180:183], v[126:129]
	v_mfma_f32_16x16x32_bf16 v[94:97], v[156:159], v[180:183], v[94:97]
	v_mfma_f32_16x16x32_bf16 v[122:125], v[148:151], v[188:191], v[122:125]
	v_mfma_f32_16x16x32_bf16 v[90:93], v[156:159], v[188:191], v[90:93]
	v_mfma_f32_16x16x32_bf16 v[118:121], v[148:151], v[196:199], v[118:121]
	v_mfma_f32_16x16x32_bf16 v[86:89], v[156:159], v[196:199], v[86:89]
	v_mfma_f32_16x16x32_bf16 v[114:117], v[148:151], v[204:207], v[114:117]
	v_mfma_f32_16x16x32_bf16 v[82:85], v[156:159], v[204:207], v[82:85]
	v_mfma_f32_16x16x32_bf16 v[70:73], v[160:163], v[176:179], v[70:73]
	v_mfma_f32_16x16x32_bf16 v[42:45], v[168:171], v[176:179], v[42:45]
	v_mfma_f32_16x16x32_bf16 v[62:65], v[160:163], v[184:187], v[62:65]
	v_mfma_f32_16x16x32_bf16 v[34:37], v[168:171], v[184:187], v[34:37]
	v_mfma_f32_16x16x32_bf16 v[54:57], v[160:163], v[192:195], v[54:57]
	v_mfma_f32_16x16x32_bf16 v[26:29], v[168:171], v[192:195], v[26:29]
	v_mfma_f32_16x16x32_bf16 v[50:53], v[160:163], v[200:203], v[50:53]
	v_mfma_f32_16x16x32_bf16 v[18:21], v[168:171], v[200:203], v[18:21]
	v_mfma_f32_16x16x32_bf16 v[70:73], v[164:167], v[180:183], v[70:73]
	v_mfma_f32_16x16x32_bf16 v[42:45], v[172:175], v[180:183], v[42:45]
	v_mfma_f32_16x16x32_bf16 v[62:65], v[164:167], v[188:191], v[62:65]
	v_mfma_f32_16x16x32_bf16 v[34:37], v[172:175], v[188:191], v[34:37]
	v_mfma_f32_16x16x32_bf16 v[54:57], v[164:167], v[196:199], v[54:57]
	v_mfma_f32_16x16x32_bf16 v[26:29], v[172:175], v[196:199], v[26:29]
	v_mfma_f32_16x16x32_bf16 v[50:53], v[164:167], v[204:207], v[50:53]
	v_mfma_f32_16x16x32_bf16 v[18:21], v[172:175], v[204:207], v[18:21]
	s_setprio 0
	s_barrier
	s_mov_b32 m0, s31
	v_lshl_add_u64 v[208:209], s[14:15], 0, v[132:133]
	s_add_u32 s42, s14, 0x160000
	ds_read_b128 v[176:179], v141 offset:16384
	ds_read_b128 v[180:183], v141 offset:17408
	ds_read_b128 v[184:187], v141 offset:18432
	ds_read_b128 v[188:191], v141 offset:19456
	ds_read_b128 v[192:195], v141 offset:20480
	ds_read_b128 v[196:199], v141 offset:21504
	ds_read_b128 v[200:203], v141 offset:22528
	ds_read_b128 v[204:207], v141 offset:23552
	global_load_lds_dwordx4 v[208:209], off
	v_lshl_add_u64 v[210:211], s[14:15], 0, v[130:131]
	s_mov_b32 m0, s33
	s_addc_u32 s43, s15, 0
	global_load_lds_dwordx4 v[210:211], off
	v_lshl_add_u64 v[212:213], s[42:43], 0, v[132:133]
	s_mov_b32 m0, s34
	v_lshl_add_u64 v[214:215], s[16:17], 0, v[130:131]
	global_load_lds_dwordx4 v[212:213], off
	v_lshl_add_u64 v[212:213], s[42:43], 0, v[130:131]
	s_mov_b32 m0, s35
	s_nop 0
	global_load_lds_dwordx4 v[212:213], off
	v_lshl_add_u64 v[212:213], s[16:17], 0, v[132:133]
	s_mov_b32 m0, s20
	s_nop 0
	global_load_lds_dwordx4 v[212:213], off
	s_mov_b32 m0, s22
	s_nop 0
	global_load_lds_dwordx4 v[214:215], off
	s_waitcnt vmcnt(8)
	s_waitcnt lgkmcnt(0)
	s_barrier
; #define PG8_STAGE(bufoff, gbase, voff) do { _Pragma("unroll") for (int _i = 0; _i < 2; ++_i) \
;         __builtin_amdgcn_global_load_lds((const unsigned*)((const char*)(gbase) + (voff)[_i]), (LAS unsigned*)(lds + (bufoff) + ldsw + _i * 8192), 16, 0, 0); } while (0)
; #define PG8_LDA(dst, b, h) do { _Pragma("unroll") for (int m = 0; m < 4; ++m) _Pragma("unroll") for (int k = 0; k < 2; ++k) dst[m][k] = *(const LAS bf16x8*)(lds + PG8_SA(b, h) + aoff + m * 2048 + k * 1024); } while (0)
; #define PG8_LDB(dst, b, h) do { _Pragma("unroll") for (int n = 0; n < 2; ++n) _Pragma("unroll") for (int k = 0; k < 2; ++k) dst[n][k] = *(const LAS bf16x8*)(lds + PG8_SB(b, h) + boff + n * 2048 + k * 1024); } while (0)
; #define PG8_MMA(ai, bj, At, Bt) do { __builtin_amdgcn_s_setprio(1); _Pragma("unroll") for (int m = 0; m < 4; ++m) _Pragma("unroll") for (int n = 0; n < 2; ++n) _Pragma("unroll") for (int k = 0; k < 2; ++k) \
;         acc[ai][bj][m][n] = __builtin_amdgcn_mfma_f32_16x16x32_bf16(Bt[n][k], At[m][k], acc[ai][bj][m][n], 0, 0, 0); __builtin_amdgcn_s_setprio(0); } while (0)
; #define PG8_WAIT_V(n) asm volatile("s_waitcnt vmcnt(" #n ")" ::: "memory")
; #define PG8_WAIT_L(n) asm volatile("s_waitcnt lgkmcnt(" #n ")" ::: "memory")
; #define PG8_BAR __builtin_amdgcn_s_barrier()
; #define PG8_SCHED __builtin_amdgcn_sched_barrier(0)
; template <class Epi, class Sched, bool ALIGN_EPI = false, bool SP2 = false>
; __device__ __forceinline__ void gemm_phase(LAS unsigned char* lds, const Gemm g, const Sched& S, const Epi& E) {
;     ...
;             PG8_WAIT_V(8); PG8_WAIT_L(0); PG8_BAR; PG8_MMA(1, 0, At, B0); PG8_MMA(1, 1, At, B1); PG8_BAR; PG8_SCHED;
;             PG8_LDB(B0, 1, 0); PG8_LDB(B1, 1, 1); PG8_SCHED; PG8_LDA(At, 1, 0); PG8_STAGE(PG8_SA(0, 1), a2 + hstep, voffA);
;             PG8_WAIT_V(8); PG8_WAIT_L(0); PG8_BAR; PG8_MMA(0, 0, At, B0); PG8_MMA(0, 1, At, B1); PG8_BAR; PG8_SCHED;
	s_setprio 1
	s_waitcnt lgkmcnt(0)
	v_mfma_f32_16x16x32_bf16 v[110:113], v[144:147], v[176:179], v[110:113]
	v_mfma_f32_16x16x32_bf16 v[78:81], v[152:155], v[176:179], v[78:81]
	v_mfma_f32_16x16x32_bf16 v[106:109], v[144:147], v[184:187], v[106:109]
	v_mfma_f32_16x16x32_bf16 v[74:77], v[152:155], v[184:187], v[74:77]
	v_mfma_f32_16x16x32_bf16 v[102:105], v[144:147], v[192:195], v[102:105]
	v_mfma_f32_16x16x32_bf16 v[66:69], v[152:155], v[192:195], v[66:69]
	v_mfma_f32_16x16x32_bf16 v[98:101], v[144:147], v[200:203], v[98:101]
	v_mfma_f32_16x16x32_bf16 v[58:61], v[152:155], v[200:203], v[58:61]
	v_mfma_f32_16x16x32_bf16 v[110:113], v[148:151], v[180:183], v[110:113]
	v_mfma_f32_16x16x32_bf16 v[78:81], v[156:159], v[180:183], v[78:81]
	v_mfma_f32_16x16x32_bf16 v[106:109], v[148:151], v[188:191], v[106:109]
	v_mfma_f32_16x16x32_bf16 v[74:77], v[156:159], v[188:191], v[74:77]
	v_mfma_f32_16x16x32_bf16 v[102:105], v[148:151], v[196:199], v[102:105]
	v_mfma_f32_16x16x32_bf16 v[66:69], v[156:159], v[196:199], v[66:69]
	v_mfma_f32_16x16x32_bf16 v[98:101], v[148:151], v[204:207], v[98:101]
	v_mfma_f32_16x16x32_bf16 v[58:61], v[156:159], v[204:207], v[58:61]
	v_mfma_f32_16x16x32_bf16 v[46:49], v[160:163], v[176:179], v[46:49]
	v_mfma_f32_16x16x32_bf16 v[14:17], v[168:171], v[176:179], v[14:17]
	v_mfma_f32_16x16x32_bf16 v[38:41], v[160:163], v[184:187], v[38:41]
	v_mfma_f32_16x16x32_bf16 v[10:13], v[168:171], v[184:187], v[10:13]
	v_mfma_f32_16x16x32_bf16 v[30:33], v[160:163], v[192:195], v[30:33]
	v_mfma_f32_16x16x32_bf16 v[6:9], v[168:171], v[192:195], v[6:9]
	v_mfma_f32_16x16x32_bf16 v[22:25], v[160:163], v[200:203], v[22:25]
	v_mfma_f32_16x16x32_bf16 v[2:5], v[168:171], v[200:203], v[2:5]
	v_mfma_f32_16x16x32_bf16 v[46:49], v[164:167], v[180:183], v[46:49]
	v_mfma_f32_16x16x32_bf16 v[14:17], v[172:175], v[180:183], v[14:17]
	v_mfma_f32_16x16x32_bf16 v[38:41], v[164:167], v[188:191], v[38:41]
	v_mfma_f32_16x16x32_bf16 v[10:13], v[172:175], v[188:191], v[10:13]
	v_mfma_f32_16x16x32_bf16 v[30:33], v[164:167], v[196:199], v[30:33]
	v_mfma_f32_16x16x32_bf16 v[6:9], v[172:175], v[196:199], v[6:9]
	v_mfma_f32_16x16x32_bf16 v[22:25], v[164:167], v[204:207], v[22:25]
	v_mfma_f32_16x16x32_bf16 v[2:5], v[172:175], v[204:207], v[2:5]
	s_setprio 0
	s_barrier
	ds_read_b128 v[144:147], v142
	ds_read_b128 v[148:151], v142 offset:1024
	ds_read_b128 v[152:155], v142 offset:2048
	ds_read_b128 v[156:159], v142 offset:3072
	ds_read_b128 v[160:163], v143
	ds_read_b128 v[164:167], v143 offset:1024
	ds_read_b128 v[168:171], v143 offset:2048
	ds_read_b128 v[172:175], v143 offset:3072
	s_add_u32 s16, s16, 0x160000
	s_addc_u32 s17, s17, 0
	s_mov_b32 m0, s23
	v_lshl_add_u64 v[216:217], s[16:17], 0, v[132:133]
	ds_read_b128 v[176:179], v141 offset:32768
	ds_read_b128 v[180:183], v141 offset:33792
	ds_read_b128 v[184:187], v141 offset:34816
	ds_read_b128 v[188:191], v141 offset:35840
	ds_read_b128 v[192:195], v141 offset:36864
	ds_read_b128 v[196:199], v141 offset:37888
	ds_read_b128 v[200:203], v141 offset:38912
	ds_read_b128 v[204:207], v141 offset:39936
	global_load_lds_dwordx4 v[216:217], off
	v_lshl_add_u64 v[216:217], s[16:17], 0, v[130:131]
	s_mov_b32 m0, s24
	s_nop 0
	global_load_lds_dwordx4 v[216:217], off
	s_waitcnt vmcnt(8)
	s_waitcnt lgkmcnt(0)
	s_barrier
	s_setprio 1
	s_waitcnt lgkmcnt(0)
	v_mfma_f32_16x16x32_bf16 v[126:129], v[144:147], v[176:179], v[126:129]
	v_mfma_f32_16x16x32_bf16 v[94:97], v[152:155], v[176:179], v[94:97]
	v_mfma_f32_16x16x32_bf16 v[122:125], v[144:147], v[184:187], v[122:125]
	v_mfma_f32_16x16x32_bf16 v[90:93], v[152:155], v[184:187], v[90:93]
	v_mfma_f32_16x16x32_bf16 v[118:121], v[144:147], v[192:195], v[118:121]
	v_mfma_f32_16x16x32_bf16 v[86:89], v[152:155], v[192:195], v[86:89]
	v_mfma_f32_16x16x32_bf16 v[114:117], v[144:147], v[200:203], v[114:117]
	v_mfma_f32_16x16x32_bf16 v[82:85], v[152:155], v[200:203], v[82:85]
	v_mfma_f32_16x16x32_bf16 v[126:129], v[148:151], v[180:183], v[126:129]
	v_mfma_f32_16x16x32_bf16 v[94:97], v[156:159], v[180:183], v[94:97]
	v_mfma_f32_16x16x32_bf16 v[122:125], v[148:151], v[188:191], v[122:125]
	v_mfma_f32_16x16x32_bf16 v[90:93], v[156:159], v[188:191], v[90:93]
	v_mfma_f32_16x16x32_bf16 v[118:121], v[148:151], v[196:199], v[118:121]
	v_mfma_f32_16x16x32_bf16 v[86:89], v[156:159], v[196:199], v[86:89]
	v_mfma_f32_16x16x32_bf16 v[114:117], v[148:151], v[204:207], v[114:117]
	v_mfma_f32_16x16x32_bf16 v[82:85], v[156:159], v[204:207], v[82:85]
	v_mfma_f32_16x16x32_bf16 v[70:73], v[160:163], v[176:179], v[70:73]
	v_mfma_f32_16x16x32_bf16 v[42:45], v[168:171], v[176:179], v[42:45]
	v_mfma_f32_16x16x32_bf16 v[62:65], v[160:163], v[184:187], v[62:65]
	v_mfma_f32_16x16x32_bf16 v[34:37], v[168:171], v[184:187], v[34:37]
	v_mfma_f32_16x16x32_bf16 v[54:57], v[160:163], v[192:195], v[54:57]
	v_mfma_f32_16x16x32_bf16 v[26:29], v[168:171], v[192:195], v[26:29]
	v_mfma_f32_16x16x32_bf16 v[50:53], v[160:163], v[200:203], v[50:53]
	v_mfma_f32_16x16x32_bf16 v[18:21], v[168:171], v[200:203], v[18:21]
	v_mfma_f32_16x16x32_bf16 v[70:73], v[164:167], v[180:183], v[70:73]
	v_mfma_f32_16x16x32_bf16 v[42:45], v[172:175], v[180:183], v[42:45]
	v_mfma_f32_16x16x32_bf16 v[62:65], v[164:167], v[188:191], v[62:65]
	v_mfma_f32_16x16x32_bf16 v[34:37], v[172:175], v[188:191], v[34:37]
	v_mfma_f32_16x16x32_bf16 v[54:57], v[164:167], v[196:199], v[54:57]
	v_mfma_f32_16x16x32_bf16 v[26:29], v[172:175], v[196:199], v[26:29]
	v_mfma_f32_16x16x32_bf16 v[50:53], v[164:167], v[204:207], v[50:53]
	v_mfma_f32_16x16x32_bf16 v[18:21], v[172:175], v[204:207], v[18:21]
	s_setprio 0
	s_barrier
; #define PG8_STAGE(bufoff, gbase, voff) do { _Pragma("unroll") for (int _i = 0; _i < 2; ++_i) \
;         __builtin_amdgcn_global_load_lds((const unsigned*)((const char*)(gbase) + (voff)[_i]), (LAS unsigned*)(lds + (bufoff) + ldsw + _i * 8192), 16, 0, 0); } while (0)
; #define PG8_LDA(dst, b, h) do { _Pragma("unroll") for (int m = 0; m < 4; ++m) _Pragma("unroll") for (int k = 0; k < 2; ++k) dst[m][k] = *(const LAS bf16x8*)(lds + PG8_SA(b, h) + aoff + m * 2048 + k * 1024); } while (0)
; #define PG8_MMA(ai, bj, At, Bt) do { __builtin_amdgcn_s_setprio(1); _Pragma("unroll") for (int m = 0; m < 4; ++m) _Pragma("unroll") for (int n = 0; n < 2; ++n) _Pragma("unroll") for (int k = 0; k < 2; ++k) \
;         acc[ai][bj][m][n] = __builtin_amdgcn_mfma_f32_16x16x32_bf16(Bt[n][k], At[m][k], acc[ai][bj][m][n], 0, 0, 0); __builtin_amdgcn_s_setprio(0); } while (0)
; #define PG8_WAIT_V(n) asm volatile("s_waitcnt vmcnt(" #n ")" ::: "memory")
; #define PG8_WAIT_L(n) asm volatile("s_waitcnt lgkmcnt(" #n ")" ::: "memory")
; #define PG8_BAR __builtin_amdgcn_s_barrier()
; #define PG8_SCHED __builtin_amdgcn_sched_barrier(0)
; template <class Epi, class Sched, bool ALIGN_EPI = false, bool SP2 = false>
; __device__ __forceinline__ void gemm_phase(LAS unsigned char* lds, const Gemm g, const Sched& S, const Epi& E) {
;     ...
;             PG8_LDA(At, 1, 1); PG8_STAGE(PG8_SB(1, 0), b3, voffB); PG8_STAGE(PG8_SB(1, 1), b3 + hstepB, voffB); PG8_STAGE(PG8_SA(1, 0), a3, voffA);
;             PG8_WAIT_V(8); PG8_WAIT_L(0); PG8_BAR; PG8_MMA(1, 0, At, B0); PG8_MMA(1, 1, At, B1); PG8_BAR; PG8_SCHED;
;     ...
;         if constexpr (ALIGN_EPI) { if (wr == 0) PG8_BAR; }
	s_mov_b32 m0, s36
	v_lshl_add_u64 v[208:209], v[208:209], 0, s[8:9]
	s_add_u32 s14, s14, 0x160080
	ds_read_b128 v[176:179], v141 offset:49152
	ds_read_b128 v[180:183], v141 offset:50176
	ds_read_b128 v[184:187], v141 offset:51200
	ds_read_b128 v[188:191], v141 offset:52224
	ds_read_b128 v[192:195], v141 offset:53248
	ds_read_b128 v[196:199], v141 offset:54272
	ds_read_b128 v[200:203], v141 offset:55296
	ds_read_b128 v[204:207], v141 offset:56320
	global_load_lds_dwordx4 v[208:209], off
	v_lshl_add_u64 v[208:209], v[210:211], 0, s[8:9]
	s_mov_b32 m0, s37
	s_addc_u32 s15, s15, 0
	global_load_lds_dwordx4 v[208:209], off
	v_lshl_add_u64 v[208:209], s[14:15], 0, v[132:133]
	s_mov_b32 m0, s38
	s_nop 0
	global_load_lds_dwordx4 v[208:209], off
	v_lshl_add_u64 v[208:209], s[14:15], 0, v[130:131]
	s_mov_b32 m0, s39
	s_nop 0
	global_load_lds_dwordx4 v[208:209], off
	v_lshl_add_u64 v[208:209], v[212:213], 0, s[8:9]
	s_mov_b32 m0, s26
	s_nop 0
	global_load_lds_dwordx4 v[208:209], off
	v_lshl_add_u64 v[208:209], v[214:215], 0, s[8:9]
	s_mov_b32 m0, s27
	s_nop 0
	global_load_lds_dwordx4 v[208:209], off
	s_waitcnt vmcnt(8)
	s_waitcnt lgkmcnt(0)
	s_barrier
	s_setprio 1
	s_waitcnt lgkmcnt(0)
	v_mfma_f32_16x16x32_bf16 v[110:113], v[144:147], v[176:179], v[110:113]
	v_mfma_f32_16x16x32_bf16 v[78:81], v[152:155], v[176:179], v[78:81]
	v_mfma_f32_16x16x32_bf16 v[106:109], v[144:147], v[184:187], v[106:109]
	v_mfma_f32_16x16x32_bf16 v[74:77], v[152:155], v[184:187], v[74:77]
	v_mfma_f32_16x16x32_bf16 v[102:105], v[144:147], v[192:195], v[102:105]
	v_mfma_f32_16x16x32_bf16 v[66:69], v[152:155], v[192:195], v[66:69]
	v_mfma_f32_16x16x32_bf16 v[98:101], v[144:147], v[200:203], v[98:101]
	v_mfma_f32_16x16x32_bf16 v[58:61], v[152:155], v[200:203], v[58:61]
	v_mfma_f32_16x16x32_bf16 v[110:113], v[148:151], v[180:183], v[110:113]
	v_mfma_f32_16x16x32_bf16 v[78:81], v[156:159], v[180:183], v[78:81]
	v_mfma_f32_16x16x32_bf16 v[106:109], v[148:151], v[188:191], v[106:109]
	v_mfma_f32_16x16x32_bf16 v[74:77], v[156:159], v[188:191], v[74:77]
	v_mfma_f32_16x16x32_bf16 v[102:105], v[148:151], v[196:199], v[102:105]
	v_mfma_f32_16x16x32_bf16 v[66:69], v[156:159], v[196:199], v[66:69]
	v_mfma_f32_16x16x32_bf16 v[98:101], v[148:151], v[204:207], v[98:101]
	v_mfma_f32_16x16x32_bf16 v[58:61], v[156:159], v[204:207], v[58:61]
	v_mfma_f32_16x16x32_bf16 v[46:49], v[160:163], v[176:179], v[46:49]
	v_mfma_f32_16x16x32_bf16 v[14:17], v[168:171], v[176:179], v[14:17]
	v_mfma_f32_16x16x32_bf16 v[38:41], v[160:163], v[184:187], v[38:41]
	v_mfma_f32_16x16x32_bf16 v[10:13], v[168:171], v[184:187], v[10:13]
	v_mfma_f32_16x16x32_bf16 v[30:33], v[160:163], v[192:195], v[30:33]
	v_mfma_f32_16x16x32_bf16 v[6:9], v[168:171], v[192:195], v[6:9]
	v_mfma_f32_16x16x32_bf16 v[22:25], v[160:163], v[200:203], v[22:25]
	v_mfma_f32_16x16x32_bf16 v[2:5], v[168:171], v[200:203], v[2:5]
	v_mfma_f32_16x16x32_bf16 v[46:49], v[164:167], v[180:183], v[46:49]
	v_mfma_f32_16x16x32_bf16 v[14:17], v[172:175], v[180:183], v[14:17]
	v_mfma_f32_16x16x32_bf16 v[38:41], v[164:167], v[188:191], v[38:41]
	v_mfma_f32_16x16x32_bf16 v[10:13], v[172:175], v[188:191], v[10:13]
	v_mfma_f32_16x16x32_bf16 v[30:33], v[164:167], v[196:199], v[30:33]
	v_mfma_f32_16x16x32_bf16 v[6:9], v[172:175], v[196:199], v[6:9]
	v_mfma_f32_16x16x32_bf16 v[22:25], v[164:167], v[204:207], v[22:25]
	v_mfma_f32_16x16x32_bf16 v[2:5], v[172:175], v[204:207], v[2:5]
	s_setprio 0
	s_barrier
	s_add_u32 s10, s10, 0x100
	s_addc_u32 s11, s11, 0
	s_cmp_lt_u32 s40, s25
	s_mov_b32 s14, s40
	s_cbranch_scc1 .LBB0_1896
	v_readlane_b32 s30, v252, 2
	v_readlane_b32 s34, v252, 37
	s_cmpk_gt_u32 s19, 0xff
	v_readlane_b32 s31, v252, 3
	v_readlane_b32 s35, v252, 38
	s_cbranch_scc1 .LBB0_1899
	s_barrier

;     __device__ bool next(int i, Unit& u) const { if (i != 0 || c >= 128) return false; const int t = c >> 2; u.pm = t & 3; u.pn = t >> 2; u.koff = koff_bytes; u.q = c & 3; return true; }
; #define PG8_STAGE(bufoff, gbase, voff) do { _Pragma("unroll") for (int _i = 0; _i < 2; ++_i) \
;         __builtin_amdgcn_global_load_lds((const unsigned*)((const char*)(gbase) + (voff)[_i]), (LAS unsigned*)(lds + (bufoff) + ldsw + _i * 8192), 16, 0, 0); } while (0)
; #define PG8_LDA(dst, b, h) do { _Pragma("unroll") for (int m = 0; m < 4; ++m) _Pragma("unroll") for (int k = 0; k < 2; ++k) dst[m][k] = *(const LAS bf16x8*)(lds + PG8_SA(b, h) + aoff + m * 2048 + k * 1024); } while (0)
; #define PG8_LDB(dst, b, h) do { _Pragma("unroll") for (int n = 0; n < 2; ++n) _Pragma("unroll") for (int k = 0; k < 2; ++k) dst[n][k] = *(const LAS bf16x8*)(lds + PG8_SB(b, h) + boff + n * 2048 + k * 1024); } while (0)
; #define PG8_WAIT_V(n) asm volatile("s_waitcnt vmcnt(" #n ")" ::: "memory")
; template <class Epi, class Sched, bool ALIGN_EPI = false, bool SP2 = false>
; __device__ __forceinline__ void gemm_phase(LAS unsigned char* lds, const Gemm g, const Sched& S, const Epi& E) {
;     ...
;         const bool has_next = S.next(ui + 1, nxt);
;         const char* nA = has_next ? (const char*)g.A + (size_t)nxt.pm * tstep + nxt.koff : cA; const char* nB = has_next ? (const char*)g.Bt + (size_t)nxt.pn * tstep + nxt.koff : cB;
;         for (int t = 0; t < nt; t += 2) {
;             const bool last = (t == nt - 2);
;             const char* a1 = cA + (size_t)(t + 1) * kstep;
;             const char* a2 = last ? nA : cA + (size_t)(t + 2) * kstep; const char* b2 = last ? nB : cB + (size_t)(t + 2) * kstep;
;             const char* a3 = a2 + kstep; const char* b3 = b2 + kstep;
;             if (last && has_next) S.a_ready(nxt);
;             if constexpr (SP2) {
;             PG8_LDB(B0, 0, 0); PG8_LDB(B1, 0, 1); PG8_SCHED; PG8_LDA(At, 0, 0); PG8_STAGE(PG8_SA(1, 1), a1 + hstep, voffA);
;             PG8_WAIT_V(8); PG8_WAIT_L(0); PG8_BAR; PG8_MMA(0, 0, At, B0); PG8_MMA(0, 1, At, B1); PG8_BAR; PG8_SCHED;
;             PG8_LDA(At, 0, 1); PG8_STAGE(PG8_SB(0, 0), b2, voffB); PG8_STAGE(PG8_SB(0, 1), b2 + hstepB, voffB); PG8_STAGE(PG8_SA(0, 0), a2, voffA);
;             PG8_WAIT_V(8); PG8_WAIT_L(0); PG8_BAR; PG8_MMA(1, 0, At, B0); PG8_MMA(1, 1, At, B1); PG8_BAR; PG8_SCHED;
.LBB0_1925:
	s_add_u32 s5, s20, 0x100
	s_addc_u32 s24, s21, 0
	s_mov_b32 s25, -2
	s_waitcnt vmcnt(0)
	ds_read_b128 v[130:133], v196
	ds_read_b128 v[134:137], v196 offset:1024
	ds_read_b128 v[138:141], v196 offset:2048
	ds_read_b128 v[142:145], v196 offset:3072
	ds_read_b128 v[166:169], v197
	ds_read_b128 v[170:173], v197 offset:1024
	ds_read_b128 v[174:177], v197 offset:2048
	ds_read_b128 v[178:181], v197 offset:3072
	s_add_u32 s20, s18, 0x100
	s_addc_u32 s21, s19, 0
	s_cmpk_eq_i32 s25, 0x54
	s_cselect_b32 s47, s17, s21
	s_cselect_b32 s46, s16, s20
	s_cselect_b32 s23, s3, s24
	s_cselect_b32 s22, s2, s5
	v_lshl_add_u64 v[190:191], s[18:19], 0, v[160:161]
	s_add_i32 m0, s27, 0xc000
	ds_read_b128 v[182:185], v198
	ds_read_b128 v[186:189], v198 offset:1024
	ds_read_b128 v[202:205], v198 offset:2048
	ds_read_b128 v[206:209], v198 offset:3072
	ds_read_b128 v[210:213], v198 offset:4096
	ds_read_b128 v[214:217], v198 offset:5120
	ds_read_b128 v[218:221], v198 offset:6144
	ds_read_b128 v[222:225], v198 offset:7168
	global_load_lds_dwordx4 v[190:191], off
	v_lshl_add_u64 v[190:191], s[18:19], 0, v[158:159]
	s_add_i32 m0, s27, 0xe000
	s_nop 0
	global_load_lds_dwordx4 v[190:191], off
	s_waitcnt lgkmcnt(0)
	s_barrier
	s_setprio 1
	s_waitcnt lgkmcnt(0)
	v_mfma_f32_16x16x32_bf16 v[126:129], v[130:133], v[182:185], 0
	v_mfma_f32_16x16x32_bf16 v[122:125], v[138:141], v[182:185], 0
	v_mfma_f32_16x16x32_bf16 v[110:113], v[130:133], v[202:205], 0
	v_mfma_f32_16x16x32_bf16 v[106:109], v[138:141], v[202:205], 0
	v_mfma_f32_16x16x32_bf16 v[94:97], v[130:133], v[210:213], 0
	v_mfma_f32_16x16x32_bf16 v[90:93], v[138:141], v[210:213], 0
	v_mfma_f32_16x16x32_bf16 v[78:81], v[130:133], v[218:221], 0
	v_mfma_f32_16x16x32_bf16 v[74:77], v[138:141], v[218:221], 0
	v_mfma_f32_16x16x32_bf16 v[126:129], v[134:137], v[186:189], v[126:129]
	v_mfma_f32_16x16x32_bf16 v[122:125], v[142:145], v[186:189], v[122:125]
	v_mfma_f32_16x16x32_bf16 v[110:113], v[134:137], v[206:209], v[110:113]
	v_mfma_f32_16x16x32_bf16 v[106:109], v[142:145], v[206:209], v[106:109]
	v_mfma_f32_16x16x32_bf16 v[94:97], v[134:137], v[214:217], v[94:97]
	v_mfma_f32_16x16x32_bf16 v[90:93], v[142:145], v[214:217], v[90:93]
	v_mfma_f32_16x16x32_bf16 v[78:81], v[134:137], v[222:225], v[78:81]
	v_mfma_f32_16x16x32_bf16 v[74:77], v[142:145], v[222:225], v[74:77]
	v_mfma_f32_16x16x32_bf16 v[118:121], v[166:169], v[182:185], 0
	v_mfma_f32_16x16x32_bf16 v[114:117], v[174:177], v[182:185], 0
	v_mfma_f32_16x16x32_bf16 v[102:105], v[166:169], v[202:205], 0
	v_mfma_f32_16x16x32_bf16 v[98:101], v[174:177], v[202:205], 0
	v_mfma_f32_16x16x32_bf16 v[86:89], v[166:169], v[210:213], 0
	v_mfma_f32_16x16x32_bf16 v[82:85], v[174:177], v[210:213], 0
	v_mfma_f32_16x16x32_bf16 v[70:73], v[166:169], v[218:221], 0
	v_mfma_f32_16x16x32_bf16 v[66:69], v[174:177], v[218:221], 0
	v_mfma_f32_16x16x32_bf16 v[118:121], v[170:173], v[186:189], v[118:121]
	v_mfma_f32_16x16x32_bf16 v[114:117], v[178:181], v[186:189], v[114:117]
	v_mfma_f32_16x16x32_bf16 v[102:105], v[170:173], v[206:209], v[102:105]
	v_mfma_f32_16x16x32_bf16 v[98:101], v[178:181], v[206:209], v[98:101]
	v_mfma_f32_16x16x32_bf16 v[86:89], v[170:173], v[214:217], v[86:89]
	v_mfma_f32_16x16x32_bf16 v[82:85], v[178:181], v[214:217], v[82:85]
	v_mfma_f32_16x16x32_bf16 v[70:73], v[170:173], v[222:225], v[70:73]
	v_mfma_f32_16x16x32_bf16 v[66:69], v[178:181], v[222:225], v[66:69]
	s_setprio 0
	s_barrier
	s_add_i32 s18, s50, s26
	v_lshl_add_u64 v[190:191], s[22:23], 0, v[148:149]
	s_mov_b32 m0, s18
	ds_read_b128 v[182:185], v198 offset:16384
	ds_read_b128 v[186:189], v198 offset:17408
	ds_read_b128 v[202:205], v198 offset:18432
	ds_read_b128 v[206:209], v198 offset:19456
	ds_read_b128 v[210:213], v198 offset:20480
	ds_read_b128 v[214:217], v198 offset:21504
	ds_read_b128 v[218:221], v198 offset:22528
	ds_read_b128 v[222:225], v198 offset:23552
	global_load_lds_dwordx4 v[190:191], off
	s_add_i32 m0, s18, 0x2000
	s_add_u32 s18, s22, 0x58000
	v_lshl_add_u64 v[226:227], s[22:23], 0, v[152:153]
	s_addc_u32 s19, s23, 0
	s_add_i32 s54, s51, s26
	global_load_lds_dwordx4 v[226:227], off
	v_lshl_add_u64 v[228:229], s[18:19], 0, v[148:149]
	s_mov_b32 m0, s54
	v_lshl_add_u64 v[230:231], s[46:47], 0, v[150:151]
	global_load_lds_dwordx4 v[228:229], off
	v_lshl_add_u64 v[228:229], s[18:19], 0, v[152:153]
	s_add_i32 m0, s54, 0x2000
	s_nop 0
	global_load_lds_dwordx4 v[228:229], off
	v_lshl_add_u64 v[228:229], s[46:47], 0, v[146:147]
	s_mov_b32 m0, s27
	s_nop 0
	global_load_lds_dwordx4 v[228:229], off
	s_mov_b32 m0, s28
	s_nop 0
	global_load_lds_dwordx4 v[230:231], off
	s_waitcnt lgkmcnt(0)
	s_barrier
; #define PG8_STAGE(bufoff, gbase, voff) do { _Pragma("unroll") for (int _i = 0; _i < 2; ++_i) \
;         __builtin_amdgcn_global_load_lds((const unsigned*)((const char*)(gbase) + (voff)[_i]), (LAS unsigned*)(lds + (bufoff) + ldsw + _i * 8192), 16, 0, 0); } while (0)
; #define PG8_LDA(dst, b, h) do { _Pragma("unroll") for (int m = 0; m < 4; ++m) _Pragma("unroll") for (int k = 0; k < 2; ++k) dst[m][k] = *(const LAS bf16x8*)(lds + PG8_SA(b, h) + aoff + m * 2048 + k * 1024); } while (0)
; #define PG8_LDB(dst, b, h) do { _Pragma("unroll") for (int n = 0; n < 2; ++n) _Pragma("unroll") for (int k = 0; k < 2; ++k) dst[n][k] = *(const LAS bf16x8*)(lds + PG8_SB(b, h) + boff + n * 2048 + k * 1024); } while (0)
; #define PG8_MMA(ai, bj, At, Bt) do { __builtin_amdgcn_s_setprio(1); _Pragma("unroll") for (int m = 0; m < 4; ++m) _Pragma("unroll") for (int n = 0; n < 2; ++n) _Pragma("unroll") for (int k = 0; k < 2; ++k) \
;         acc[ai][bj][m][n] = __builtin_amdgcn_mfma_f32_16x16x32_bf16(Bt[n][k], At[m][k], acc[ai][bj][m][n], 0, 0, 0); __builtin_amdgcn_s_setprio(0); } while (0)
; #define PG8_WAIT_V(n) asm volatile("s_waitcnt vmcnt(" #n ")" ::: "memory")
; #define PG8_WAIT_L(n) asm volatile("s_waitcnt lgkmcnt(" #n ")" ::: "memory")
; #define PG8_BAR __builtin_amdgcn_s_barrier()
; #define PG8_SCHED __builtin_amdgcn_sched_barrier(0)
; template <class Epi, class Sched, bool ALIGN_EPI = false, bool SP2 = false>
; __device__ __forceinline__ void gemm_phase(LAS unsigned char* lds, const Gemm g, const Sched& S, const Epi& E) {
;     ...
;             PG8_WAIT_V(8); PG8_WAIT_L(0); PG8_BAR; PG8_MMA(1, 0, At, B0); PG8_MMA(1, 1, At, B1); PG8_BAR; PG8_SCHED;
;             PG8_LDB(B0, 1, 0); PG8_LDB(B1, 1, 1); PG8_SCHED; PG8_LDA(At, 1, 0); PG8_STAGE(PG8_SA(0, 1), a2 + hstep, voffA);
;             PG8_WAIT_V(8); PG8_WAIT_L(0); PG8_BAR; PG8_MMA(0, 0, At, B0); PG8_MMA(0, 1, At, B1); PG8_BAR; PG8_SCHED;
	s_setprio 1
	s_waitcnt lgkmcnt(0)
	v_mfma_f32_16x16x32_bf16 v[62:65], v[130:133], v[182:185], 0
	v_mfma_f32_16x16x32_bf16 v[58:61], v[138:141], v[182:185], 0
	v_mfma_f32_16x16x32_bf16 v[46:49], v[130:133], v[202:205], 0
	v_mfma_f32_16x16x32_bf16 v[42:45], v[138:141], v[202:205], 0
	v_mfma_f32_16x16x32_bf16 v[30:33], v[130:133], v[210:213], 0
	v_mfma_f32_16x16x32_bf16 v[26:29], v[138:141], v[210:213], 0
	v_mfma_f32_16x16x32_bf16 v[14:17], v[130:133], v[218:221], 0
	v_mfma_f32_16x16x32_bf16 v[10:13], v[138:141], v[218:221], 0
	v_mfma_f32_16x16x32_bf16 v[62:65], v[134:137], v[186:189], v[62:65]
	v_mfma_f32_16x16x32_bf16 v[58:61], v[142:145], v[186:189], v[58:61]
	v_mfma_f32_16x16x32_bf16 v[46:49], v[134:137], v[206:209], v[46:49]
	v_mfma_f32_16x16x32_bf16 v[42:45], v[142:145], v[206:209], v[42:45]
	v_mfma_f32_16x16x32_bf16 v[30:33], v[134:137], v[214:217], v[30:33]
	v_mfma_f32_16x16x32_bf16 v[26:29], v[142:145], v[214:217], v[26:29]
	v_mfma_f32_16x16x32_bf16 v[14:17], v[134:137], v[222:225], v[14:17]
	v_mfma_f32_16x16x32_bf16 v[10:13], v[142:145], v[222:225], v[10:13]
	v_mfma_f32_16x16x32_bf16 v[54:57], v[166:169], v[182:185], 0
	v_mfma_f32_16x16x32_bf16 v[50:53], v[174:177], v[182:185], 0
	v_mfma_f32_16x16x32_bf16 v[38:41], v[166:169], v[202:205], 0
	v_mfma_f32_16x16x32_bf16 v[34:37], v[174:177], v[202:205], 0
	v_mfma_f32_16x16x32_bf16 v[22:25], v[166:169], v[210:213], 0
	v_mfma_f32_16x16x32_bf16 v[18:21], v[174:177], v[210:213], 0
	v_mfma_f32_16x16x32_bf16 v[6:9], v[166:169], v[218:221], 0
	v_mfma_f32_16x16x32_bf16 v[2:5], v[174:177], v[218:221], 0
	v_mfma_f32_16x16x32_bf16 v[54:57], v[170:173], v[186:189], v[54:57]
	v_mfma_f32_16x16x32_bf16 v[50:53], v[178:181], v[186:189], v[50:53]
	v_mfma_f32_16x16x32_bf16 v[38:41], v[170:173], v[206:209], v[38:41]
	v_mfma_f32_16x16x32_bf16 v[34:37], v[178:181], v[206:209], v[34:37]
	v_mfma_f32_16x16x32_bf16 v[22:25], v[170:173], v[214:217], v[22:25]
	v_mfma_f32_16x16x32_bf16 v[18:21], v[178:181], v[214:217], v[18:21]
	v_mfma_f32_16x16x32_bf16 v[6:9], v[170:173], v[222:225], v[6:9]
	v_mfma_f32_16x16x32_bf16 v[2:5], v[178:181], v[222:225], v[2:5]
	s_setprio 0
	s_barrier
	s_add_i32 s54, 0, 0x18000
	s_add_i32 s55, 0, 0x1c000
	v_add_u32_e32 v142, s54, v1
	v_add_u32_e32 v154, s55, v1
	ds_read_b128 v[130:133], v142
	ds_read_b128 v[134:137], v142 offset:1024
	ds_read_b128 v[138:141], v142 offset:2048
	ds_read_b128 v[142:145], v142 offset:3072
	ds_read_b128 v[166:169], v154
	ds_read_b128 v[170:173], v154 offset:1024
	ds_read_b128 v[174:177], v154 offset:2048
	ds_read_b128 v[178:181], v154 offset:3072
	s_add_u32 s18, s46, 0x160000
	s_addc_u32 s19, s47, 0
	s_mov_b32 m0, s29
	v_lshl_add_u64 v[232:233], s[18:19], 0, v[146:147]
	ds_read_b128 v[182:185], v198 offset:32768
	ds_read_b128 v[186:189], v198 offset:33792
	ds_read_b128 v[202:205], v198 offset:34816
	ds_read_b128 v[206:209], v198 offset:35840
	ds_read_b128 v[210:213], v198 offset:36864
	ds_read_b128 v[214:217], v198 offset:37888
	ds_read_b128 v[218:221], v198 offset:38912
	ds_read_b128 v[222:225], v198 offset:39936
	global_load_lds_dwordx4 v[232:233], off
	v_lshl_add_u64 v[232:233], s[18:19], 0, v[150:151]
	s_mov_b32 m0, s30
	s_nop 0
	global_load_lds_dwordx4 v[232:233], off
	s_waitcnt vmcnt(8)
	s_waitcnt lgkmcnt(0)
	s_barrier
	s_setprio 1
	s_waitcnt lgkmcnt(0)
	v_mfma_f32_16x16x32_bf16 v[126:129], v[130:133], v[182:185], v[126:129]
	v_mfma_f32_16x16x32_bf16 v[122:125], v[138:141], v[182:185], v[122:125]
	v_mfma_f32_16x16x32_bf16 v[110:113], v[130:133], v[202:205], v[110:113]
	v_mfma_f32_16x16x32_bf16 v[106:109], v[138:141], v[202:205], v[106:109]
	v_mfma_f32_16x16x32_bf16 v[94:97], v[130:133], v[210:213], v[94:97]
	v_mfma_f32_16x16x32_bf16 v[90:93], v[138:141], v[210:213], v[90:93]
	v_mfma_f32_16x16x32_bf16 v[78:81], v[130:133], v[218:221], v[78:81]
	v_mfma_f32_16x16x32_bf16 v[74:77], v[138:141], v[218:221], v[74:77]
	v_mfma_f32_16x16x32_bf16 v[126:129], v[134:137], v[186:189], v[126:129]
	v_mfma_f32_16x16x32_bf16 v[122:125], v[142:145], v[186:189], v[122:125]
	v_mfma_f32_16x16x32_bf16 v[110:113], v[134:137], v[206:209], v[110:113]
	v_mfma_f32_16x16x32_bf16 v[106:109], v[142:145], v[206:209], v[106:109]
	v_mfma_f32_16x16x32_bf16 v[94:97], v[134:137], v[214:217], v[94:97]
	v_mfma_f32_16x16x32_bf16 v[90:93], v[142:145], v[214:217], v[90:93]
	v_mfma_f32_16x16x32_bf16 v[78:81], v[134:137], v[222:225], v[78:81]
	v_mfma_f32_16x16x32_bf16 v[74:77], v[142:145], v[222:225], v[74:77]
	v_mfma_f32_16x16x32_bf16 v[118:121], v[166:169], v[182:185], v[118:121]
	v_mfma_f32_16x16x32_bf16 v[114:117], v[174:177], v[182:185], v[114:117]
	v_mfma_f32_16x16x32_bf16 v[102:105], v[166:169], v[202:205], v[102:105]
	v_mfma_f32_16x16x32_bf16 v[98:101], v[174:177], v[202:205], v[98:101]
	v_mfma_f32_16x16x32_bf16 v[86:89], v[166:169], v[210:213], v[86:89]
	v_mfma_f32_16x16x32_bf16 v[82:85], v[174:177], v[210:213], v[82:85]
	v_mfma_f32_16x16x32_bf16 v[70:73], v[166:169], v[218:221], v[70:73]
	v_mfma_f32_16x16x32_bf16 v[66:69], v[174:177], v[218:221], v[66:69]
	v_mfma_f32_16x16x32_bf16 v[118:121], v[170:173], v[186:189], v[118:121]
	v_mfma_f32_16x16x32_bf16 v[114:117], v[178:181], v[186:189], v[114:117]
	v_mfma_f32_16x16x32_bf16 v[102:105], v[170:173], v[206:209], v[102:105]
	v_mfma_f32_16x16x32_bf16 v[98:101], v[178:181], v[206:209], v[98:101]
	v_mfma_f32_16x16x32_bf16 v[86:89], v[170:173], v[214:217], v[86:89]
	v_mfma_f32_16x16x32_bf16 v[82:85], v[178:181], v[214:217], v[82:85]
	v_mfma_f32_16x16x32_bf16 v[70:73], v[170:173], v[222:225], v[70:73]
	v_mfma_f32_16x16x32_bf16 v[66:69], v[178:181], v[222:225], v[66:69]
	s_setprio 0
	s_barrier
; #define PG8_STAGE(bufoff, gbase, voff) do { _Pragma("unroll") for (int _i = 0; _i < 2; ++_i) \
;         __builtin_amdgcn_global_load_lds((const unsigned*)((const char*)(gbase) + (voff)[_i]), (LAS unsigned*)(lds + (bufoff) + ldsw + _i * 8192), 16, 0, 0); } while (0)
; #define PG8_LDA(dst, b, h) do { _Pragma("unroll") for (int m = 0; m < 4; ++m) _Pragma("unroll") for (int k = 0; k < 2; ++k) dst[m][k] = *(const LAS bf16x8*)(lds + PG8_SA(b, h) + aoff + m * 2048 + k * 1024); } while (0)
; #define PG8_LDB(dst, b, h) do { _Pragma("unroll") for (int n = 0; n < 2; ++n) _Pragma("unroll") for (int k = 0; k < 2; ++k) dst[n][k] = *(const LAS bf16x8*)(lds + PG8_SB(b, h) + boff + n * 2048 + k * 1024); } while (0)
; template <class Epi, class Sched, bool ALIGN_EPI = false, bool SP2 = false>
; __device__ __forceinline__ void gemm_phase(LAS unsigned char* lds, const Gemm g, const Sched& S, const Epi& E) {
;     ...
;         for (int t = 0; t < nt; t += 2) {
;             const bool last = (t == nt - 2);
;             const char* a1 = cA + (size_t)(t + 1) * kstep;
;             const char* a2 = last ? nA : cA + (size_t)(t + 2) * kstep; const char* b2 = last ? nB : cB + (size_t)(t + 2) * kstep;
;             const char* a3 = a2 + kstep; const char* b3 = b2 + kstep;
;             if (last && has_next) S.a_ready(nxt);
;             if constexpr (SP2) {
;             PG8_LDB(B0, 0, 0); PG8_LDB(B1, 0, 1); PG8_SCHED; PG8_LDA(At, 0, 0); PG8_STAGE(PG8_SA(1, 1), a1 + hstep, voffA);
;             PG8_WAIT_V(8); PG8_WAIT_L(0); PG8_BAR; PG8_MMA(0, 0, At, B0); PG8_MMA(0, 1, At, B1); PG8_BAR; PG8_SCHED;
;             PG8_LDA(At, 0, 1); PG8_STAGE(PG8_SB(0, 0), b2, voffB); PG8_STAGE(PG8_SB(0, 1), b2 + hstepB, voffB); PG8_STAGE(PG8_SA(0, 0), a2, voffA);
;             PG8_WAIT_V(8); PG8_WAIT_L(0); PG8_BAR; PG8_MMA(1, 0, At, B0); PG8_MMA(1, 1, At, B1); PG8_BAR; PG8_SCHED;
;             PG8_LDB(B0, 1, 0); PG8_LDB(B1, 1, 1); PG8_SCHED; PG8_LDA(At, 1, 0); PG8_STAGE(PG8_SA(0, 1), a2 + hstep, voffA);
;             PG8_WAIT_V(8); PG8_WAIT_L(0); PG8_BAR; PG8_MMA(0, 0, At, B0); PG8_MMA(0, 1, At, B1); PG8_BAR; PG8_SCHED;
;             PG8_LDA(At, 1, 1); PG8_STAGE(PG8_SB(1, 0), b3, voffB); PG8_STAGE(PG8_SB(1, 1), b3 + hstepB, voffB); PG8_STAGE(PG8_SA(1, 0), a3, voffA);
;             PG8_WAIT_V(8); PG8_WAIT_L(0); PG8_BAR; PG8_MMA(1, 0, At, B0); PG8_MMA(1, 1, At, B1); PG8_BAR; PG8_SCHED;
	s_add_i32 s18, s54, s26
	v_lshl_add_u64 v[190:191], v[190:191], 0, s[12:13]
	s_mov_b32 m0, s18
	ds_read_b128 v[182:185], v198 offset:49152
	ds_read_b128 v[186:189], v198 offset:50176
	ds_read_b128 v[202:205], v198 offset:51200
	ds_read_b128 v[206:209], v198 offset:52224
	ds_read_b128 v[210:213], v198 offset:53248
	ds_read_b128 v[214:217], v198 offset:54272
	ds_read_b128 v[218:221], v198 offset:55296
	ds_read_b128 v[222:225], v198 offset:56320
	global_load_lds_dwordx4 v[190:191], off
	s_add_i32 m0, s18, 0x2000
	s_add_u32 s18, s22, 0x58080
	v_lshl_add_u64 v[190:191], v[226:227], 0, s[12:13]
	s_addc_u32 s19, s23, 0
	s_add_i32 s22, s55, s26
	global_load_lds_dwordx4 v[190:191], off
	v_lshl_add_u64 v[190:191], s[18:19], 0, v[148:149]
	s_mov_b32 m0, s22
	s_nop 0
	global_load_lds_dwordx4 v[190:191], off
	v_lshl_add_u64 v[190:191], s[18:19], 0, v[152:153]
	s_add_i32 m0, s22, 0x2000
	s_nop 0
	global_load_lds_dwordx4 v[190:191], off
	v_lshl_add_u64 v[190:191], v[228:229], 0, s[12:13]
	s_mov_b32 m0, s37
	s_nop 0
	global_load_lds_dwordx4 v[190:191], off
	v_lshl_add_u64 v[190:191], v[230:231], 0, s[12:13]
	s_mov_b32 m0, s48
	s_nop 0
	global_load_lds_dwordx4 v[190:191], off
	s_waitcnt vmcnt(8)
	s_waitcnt lgkmcnt(0)
	s_barrier
	s_setprio 1
	s_waitcnt lgkmcnt(0)
	v_mfma_f32_16x16x32_bf16 v[62:65], v[130:133], v[182:185], v[62:65]
	v_mfma_f32_16x16x32_bf16 v[58:61], v[138:141], v[182:185], v[58:61]
	v_mfma_f32_16x16x32_bf16 v[46:49], v[130:133], v[202:205], v[46:49]
	v_mfma_f32_16x16x32_bf16 v[42:45], v[138:141], v[202:205], v[42:45]
	v_mfma_f32_16x16x32_bf16 v[30:33], v[130:133], v[210:213], v[30:33]
	v_mfma_f32_16x16x32_bf16 v[26:29], v[138:141], v[210:213], v[26:29]
	v_mfma_f32_16x16x32_bf16 v[14:17], v[130:133], v[218:221], v[14:17]
	v_mfma_f32_16x16x32_bf16 v[10:13], v[138:141], v[218:221], v[10:13]
	v_mfma_f32_16x16x32_bf16 v[62:65], v[134:137], v[186:189], v[62:65]
	v_mfma_f32_16x16x32_bf16 v[58:61], v[142:145], v[186:189], v[58:61]
	v_mfma_f32_16x16x32_bf16 v[46:49], v[134:137], v[206:209], v[46:49]
	v_mfma_f32_16x16x32_bf16 v[42:45], v[142:145], v[206:209], v[42:45]
	v_mfma_f32_16x16x32_bf16 v[30:33], v[134:137], v[214:217], v[30:33]
	v_mfma_f32_16x16x32_bf16 v[26:29], v[142:145], v[214:217], v[26:29]
	v_mfma_f32_16x16x32_bf16 v[14:17], v[134:137], v[222:225], v[14:17]
	v_mfma_f32_16x16x32_bf16 v[10:13], v[142:145], v[222:225], v[10:13]
	v_mfma_f32_16x16x32_bf16 v[54:57], v[166:169], v[182:185], v[54:57]
	v_mfma_f32_16x16x32_bf16 v[50:53], v[174:177], v[182:185], v[50:53]
	v_mfma_f32_16x16x32_bf16 v[38:41], v[166:169], v[202:205], v[38:41]
	v_mfma_f32_16x16x32_bf16 v[34:37], v[174:177], v[202:205], v[34:37]
	v_mfma_f32_16x16x32_bf16 v[22:25], v[166:169], v[210:213], v[22:25]
	v_mfma_f32_16x16x32_bf16 v[18:21], v[174:177], v[210:213], v[18:21]
	v_mfma_f32_16x16x32_bf16 v[6:9], v[166:169], v[218:221], v[6:9]
	v_mfma_f32_16x16x32_bf16 v[2:5], v[174:177], v[218:221], v[2:5]
	v_mfma_f32_16x16x32_bf16 v[54:57], v[170:173], v[186:189], v[54:57]
	v_mfma_f32_16x16x32_bf16 v[50:53], v[178:181], v[186:189], v[50:53]
	v_mfma_f32_16x16x32_bf16 v[38:41], v[170:173], v[206:209], v[38:41]
	v_mfma_f32_16x16x32_bf16 v[34:37], v[178:181], v[206:209], v[34:37]
	v_mfma_f32_16x16x32_bf16 v[22:25], v[170:173], v[214:217], v[22:25]
	v_mfma_f32_16x16x32_bf16 v[18:21], v[178:181], v[214:217], v[18:21]
	v_mfma_f32_16x16x32_bf16 v[6:9], v[170:173], v[222:225], v[6:9]
	v_mfma_f32_16x16x32_bf16 v[2:5], v[178:181], v[222:225], v[2:5]
	s_setprio 0
	s_barrier
	s_add_i32 s25, s25, 2
	s_add_u32 s5, s5, 0x100
	s_addc_u32 s24, s24, 0
	s_cmpk_lt_u32 s25, 0x56
	s_mov_b64 s[18:19], s[20:21]
.LBB0_1926:
	ds_read_b128 v[130:133], v196
	ds_read_b128 v[134:137], v196 offset:1024
	ds_read_b128 v[138:141], v196 offset:2048
	ds_read_b128 v[142:145], v196 offset:3072
	ds_read_b128 v[166:169], v197
	ds_read_b128 v[170:173], v197 offset:1024
	ds_read_b128 v[174:177], v197 offset:2048
	ds_read_b128 v[178:181], v197 offset:3072
	s_add_u32 s20, s18, 0x100
	s_addc_u32 s21, s19, 0
	s_cmpk_eq_i32 s25, 0x54
	s_cselect_b32 s47, s17, s21
	s_cselect_b32 s46, s16, s20
	s_cselect_b32 s23, s3, s24
	s_cselect_b32 s22, s2, s5
	v_lshl_add_u64 v[190:191], s[18:19], 0, v[160:161]
	s_add_i32 m0, s27, 0xc000
	ds_read_b128 v[182:185], v198
	ds_read_b128 v[186:189], v198 offset:1024
	ds_read_b128 v[202:205], v198 offset:2048
	ds_read_b128 v[206:209], v198 offset:3072
	ds_read_b128 v[210:213], v198 offset:4096
	ds_read_b128 v[214:217], v198 offset:5120
	ds_read_b128 v[218:221], v198 offset:6144
	ds_read_b128 v[222:225], v198 offset:7168
	global_load_lds_dwordx4 v[190:191], off
	v_lshl_add_u64 v[190:191], s[18:19], 0, v[158:159]
	s_add_i32 m0, s27, 0xe000
	s_nop 0
	global_load_lds_dwordx4 v[190:191], off
	s_waitcnt vmcnt(8)
	s_waitcnt lgkmcnt(0)
	s_barrier
; #define PG8_STAGE(bufoff, gbase, voff) do { _Pragma("unroll") for (int _i = 0; _i < 2; ++_i) \
;         __builtin_amdgcn_global_load_lds((const unsigned*)((const char*)(gbase) + (voff)[_i]), (LAS unsigned*)(lds + (bufoff) + ldsw + _i * 8192), 16, 0, 0); } while (0)
; #define PG8_LDA(dst, b, h) do { _Pragma("unroll") for (int m = 0; m < 4; ++m) _Pragma("unroll") for (int k = 0; k < 2; ++k) dst[m][k] = *(const LAS bf16x8*)(lds + PG8_SA(b, h) + aoff + m * 2048 + k * 1024); } while (0)
; #define PG8_MMA(ai, bj, At, Bt) do { __builtin_amdgcn_s_setprio(1); _Pragma("unroll") for (int m = 0; m < 4; ++m) _Pragma("unroll") for (int n = 0; n < 2; ++n) _Pragma("unroll") for (int k = 0; k < 2; ++k) \
;         acc[ai][bj][m][n] = __builtin_amdgcn_mfma_f32_16x16x32_bf16(Bt[n][k], At[m][k], acc[ai][bj][m][n], 0, 0, 0); __builtin_amdgcn_s_setprio(0); } while (0)
; #define PG8_WAIT_V(n) asm volatile("s_waitcnt vmcnt(" #n ")" ::: "memory")
; #define PG8_WAIT_L(n) asm volatile("s_waitcnt lgkmcnt(" #n ")" ::: "memory")
; #define PG8_BAR __builtin_amdgcn_s_barrier()
; #define PG8_SCHED __builtin_amdgcn_sched_barrier(0)
; template <class Epi, class Sched, bool ALIGN_EPI = false, bool SP2 = false>
; __device__ __forceinline__ void gemm_phase(LAS unsigned char* lds, const Gemm g, const Sched& S, const Epi& E) {
;     ...
;             PG8_WAIT_V(8); PG8_WAIT_L(0); PG8_BAR; PG8_MMA(0, 0, At, B0); PG8_MMA(0, 1, At, B1); PG8_BAR; PG8_SCHED;
;             PG8_LDA(At, 0, 1); PG8_STAGE(PG8_SB(0, 0), b2, voffB); PG8_STAGE(PG8_SB(0, 1), b2 + hstepB, voffB); PG8_STAGE(PG8_SA(0, 0), a2, voffA);
;             PG8_WAIT_V(8); PG8_WAIT_L(0); PG8_BAR; PG8_MMA(1, 0, At, B0); PG8_MMA(1, 1, At, B1); PG8_BAR; PG8_SCHED;
	s_setprio 1
	s_waitcnt lgkmcnt(0)
	v_mfma_f32_16x16x32_bf16 v[126:129], v[130:133], v[182:185], v[126:129]
	v_mfma_f32_16x16x32_bf16 v[122:125], v[138:141], v[182:185], v[122:125]
	v_mfma_f32_16x16x32_bf16 v[110:113], v[130:133], v[202:205], v[110:113]
	v_mfma_f32_16x16x32_bf16 v[106:109], v[138:141], v[202:205], v[106:109]
	v_mfma_f32_16x16x32_bf16 v[94:97], v[130:133], v[210:213], v[94:97]
	v_mfma_f32_16x16x32_bf16 v[90:93], v[138:141], v[210:213], v[90:93]
	v_mfma_f32_16x16x32_bf16 v[78:81], v[130:133], v[218:221], v[78:81]
	v_mfma_f32_16x16x32_bf16 v[74:77], v[138:141], v[218:221], v[74:77]
	v_mfma_f32_16x16x32_bf16 v[126:129], v[134:137], v[186:189], v[126:129]
	v_mfma_f32_16x16x32_bf16 v[122:125], v[142:145], v[186:189], v[122:125]
	v_mfma_f32_16x16x32_bf16 v[110:113], v[134:137], v[206:209], v[110:113]
	v_mfma_f32_16x16x32_bf16 v[106:109], v[142:145], v[206:209], v[106:109]
	v_mfma_f32_16x16x32_bf16 v[94:97], v[134:137], v[214:217], v[94:97]
	v_mfma_f32_16x16x32_bf16 v[90:93], v[142:145], v[214:217], v[90:93]
	v_mfma_f32_16x16x32_bf16 v[78:81], v[134:137], v[222:225], v[78:81]
	v_mfma_f32_16x16x32_bf16 v[74:77], v[142:145], v[222:225], v[74:77]
	v_mfma_f32_16x16x32_bf16 v[118:121], v[166:169], v[182:185], v[118:121]
	v_mfma_f32_16x16x32_bf16 v[114:117], v[174:177], v[182:185], v[114:117]
	v_mfma_f32_16x16x32_bf16 v[102:105], v[166:169], v[202:205], v[102:105]
	v_mfma_f32_16x16x32_bf16 v[98:101], v[174:177], v[202:205], v[98:101]
	v_mfma_f32_16x16x32_bf16 v[86:89], v[166:169], v[210:213], v[86:89]
	v_mfma_f32_16x16x32_bf16 v[82:85], v[174:177], v[210:213], v[82:85]
	v_mfma_f32_16x16x32_bf16 v[70:73], v[166:169], v[218:221], v[70:73]
	v_mfma_f32_16x16x32_bf16 v[66:69], v[174:177], v[218:221], v[66:69]
	v_mfma_f32_16x16x32_bf16 v[118:121], v[170:173], v[186:189], v[118:121]
	v_mfma_f32_16x16x32_bf16 v[114:117], v[178:181], v[186:189], v[114:117]
	v_mfma_f32_16x16x32_bf16 v[102:105], v[170:173], v[206:209], v[102:105]
	v_mfma_f32_16x16x32_bf16 v[98:101], v[178:181], v[206:209], v[98:101]
	v_mfma_f32_16x16x32_bf16 v[86:89], v[170:173], v[214:217], v[86:89]
	v_mfma_f32_16x16x32_bf16 v[82:85], v[178:181], v[214:217], v[82:85]
	v_mfma_f32_16x16x32_bf16 v[70:73], v[170:173], v[222:225], v[70:73]
	v_mfma_f32_16x16x32_bf16 v[66:69], v[178:181], v[222:225], v[66:69]
	s_setprio 0
	s_barrier
	s_add_i32 s18, s50, s26
	v_lshl_add_u64 v[190:191], s[22:23], 0, v[148:149]
	s_mov_b32 m0, s18
	ds_read_b128 v[182:185], v198 offset:16384
	ds_read_b128 v[186:189], v198 offset:17408
	ds_read_b128 v[202:205], v198 offset:18432
	ds_read_b128 v[206:209], v198 offset:19456
	ds_read_b128 v[210:213], v198 offset:20480
	ds_read_b128 v[214:217], v198 offset:21504
	ds_read_b128 v[218:221], v198 offset:22528
	ds_read_b128 v[222:225], v198 offset:23552
	global_load_lds_dwordx4 v[190:191], off
	s_add_i32 m0, s18, 0x2000
	s_add_u32 s18, s22, 0x58000
	v_lshl_add_u64 v[226:227], s[22:23], 0, v[152:153]
	s_addc_u32 s19, s23, 0
	s_add_i32 s54, s51, s26
	global_load_lds_dwordx4 v[226:227], off
	v_lshl_add_u64 v[228:229], s[18:19], 0, v[148:149]
	s_mov_b32 m0, s54
	v_lshl_add_u64 v[230:231], s[46:47], 0, v[150:151]
	global_load_lds_dwordx4 v[228:229], off
	v_lshl_add_u64 v[228:229], s[18:19], 0, v[152:153]
	s_add_i32 m0, s54, 0x2000
	s_nop 0
	global_load_lds_dwordx4 v[228:229], off
	v_lshl_add_u64 v[228:229], s[46:47], 0, v[146:147]
	s_mov_b32 m0, s27
	s_nop 0
	global_load_lds_dwordx4 v[228:229], off
	s_mov_b32 m0, s28
	s_nop 0
	global_load_lds_dwordx4 v[230:231], off
	s_waitcnt vmcnt(8)
	s_waitcnt lgkmcnt(0)
	s_barrier
	s_setprio 1
	s_waitcnt lgkmcnt(0)
	v_mfma_f32_16x16x32_bf16 v[62:65], v[130:133], v[182:185], v[62:65]
	v_mfma_f32_16x16x32_bf16 v[58:61], v[138:141], v[182:185], v[58:61]
	v_mfma_f32_16x16x32_bf16 v[46:49], v[130:133], v[202:205], v[46:49]
	v_mfma_f32_16x16x32_bf16 v[42:45], v[138:141], v[202:205], v[42:45]
	v_mfma_f32_16x16x32_bf16 v[30:33], v[130:133], v[210:213], v[30:33]
	v_mfma_f32_16x16x32_bf16 v[26:29], v[138:141], v[210:213], v[26:29]
	v_mfma_f32_16x16x32_bf16 v[14:17], v[130:133], v[218:221], v[14:17]
	v_mfma_f32_16x16x32_bf16 v[10:13], v[138:141], v[218:221], v[10:13]
	v_mfma_f32_16x16x32_bf16 v[62:65], v[134:137], v[186:189], v[62:65]
	v_mfma_f32_16x16x32_bf16 v[58:61], v[142:145], v[186:189], v[58:61]
	v_mfma_f32_16x16x32_bf16 v[46:49], v[134:137], v[206:209], v[46:49]
	v_mfma_f32_16x16x32_bf16 v[42:45], v[142:145], v[206:209], v[42:45]
	v_mfma_f32_16x16x32_bf16 v[30:33], v[134:137], v[214:217], v[30:33]
	v_mfma_f32_16x16x32_bf16 v[26:29], v[142:145], v[214:217], v[26:29]
	v_mfma_f32_16x16x32_bf16 v[14:17], v[134:137], v[222:225], v[14:17]
	v_mfma_f32_16x16x32_bf16 v[10:13], v[142:145], v[222:225], v[10:13]
	v_mfma_f32_16x16x32_bf16 v[54:57], v[166:169], v[182:185], v[54:57]
	v_mfma_f32_16x16x32_bf16 v[50:53], v[174:177], v[182:185], v[50:53]
	v_mfma_f32_16x16x32_bf16 v[38:41], v[166:169], v[202:205], v[38:41]
	v_mfma_f32_16x16x32_bf16 v[34:37], v[174:177], v[202:205], v[34:37]
	v_mfma_f32_16x16x32_bf16 v[22:25], v[166:169], v[210:213], v[22:25]
	v_mfma_f32_16x16x32_bf16 v[18:21], v[174:177], v[210:213], v[18:21]
	v_mfma_f32_16x16x32_bf16 v[6:9], v[166:169], v[218:221], v[6:9]
	v_mfma_f32_16x16x32_bf16 v[2:5], v[174:177], v[218:221], v[2:5]
	v_mfma_f32_16x16x32_bf16 v[54:57], v[170:173], v[186:189], v[54:57]
	v_mfma_f32_16x16x32_bf16 v[50:53], v[178:181], v[186:189], v[50:53]
	v_mfma_f32_16x16x32_bf16 v[38:41], v[170:173], v[206:209], v[38:41]
	v_mfma_f32_16x16x32_bf16 v[34:37], v[178:181], v[206:209], v[34:37]
	v_mfma_f32_16x16x32_bf16 v[22:25], v[170:173], v[214:217], v[22:25]
	v_mfma_f32_16x16x32_bf16 v[18:21], v[178:181], v[214:217], v[18:21]
	v_mfma_f32_16x16x32_bf16 v[6:9], v[170:173], v[222:225], v[6:9]
	v_mfma_f32_16x16x32_bf16 v[2:5], v[178:181], v[222:225], v[2:5]
	s_setprio 0
	s_barrier
; #define PG8_STAGE(bufoff, gbase, voff) do { _Pragma("unroll") for (int _i = 0; _i < 2; ++_i) \
;         __builtin_amdgcn_global_load_lds((const unsigned*)((const char*)(gbase) + (voff)[_i]), (LAS unsigned*)(lds + (bufoff) + ldsw + _i * 8192), 16, 0, 0); } while (0)
; #define PG8_LDA(dst, b, h) do { _Pragma("unroll") for (int m = 0; m < 4; ++m) _Pragma("unroll") for (int k = 0; k < 2; ++k) dst[m][k] = *(const LAS bf16x8*)(lds + PG8_SA(b, h) + aoff + m * 2048 + k * 1024); } while (0)
; #define PG8_LDB(dst, b, h) do { _Pragma("unroll") for (int n = 0; n < 2; ++n) _Pragma("unroll") for (int k = 0; k < 2; ++k) dst[n][k] = *(const LAS bf16x8*)(lds + PG8_SB(b, h) + boff + n * 2048 + k * 1024); } while (0)
; #define PG8_MMA(ai, bj, At, Bt) do { __builtin_amdgcn_s_setprio(1); _Pragma("unroll") for (int m = 0; m < 4; ++m) _Pragma("unroll") for (int n = 0; n < 2; ++n) _Pragma("unroll") for (int k = 0; k < 2; ++k) \
;         acc[ai][bj][m][n] = __builtin_amdgcn_mfma_f32_16x16x32_bf16(Bt[n][k], At[m][k], acc[ai][bj][m][n], 0, 0, 0); __builtin_amdgcn_s_setprio(0); } while (0)
; #define PG8_WAIT_V(n) asm volatile("s_waitcnt vmcnt(" #n ")" ::: "memory")
; #define PG8_WAIT_L(n) asm volatile("s_waitcnt lgkmcnt(" #n ")" ::: "memory")
; #define PG8_BAR __builtin_amdgcn_s_barrier()
; #define PG8_SCHED __builtin_amdgcn_sched_barrier(0)
; template <class Epi, class Sched, bool ALIGN_EPI = false, bool SP2 = false>
; __device__ __forceinline__ void gemm_phase(LAS unsigned char* lds, const Gemm g, const Sched& S, const Epi& E) {
;     ...
;             PG8_LDB(B0, 1, 0); PG8_LDB(B1, 1, 1); PG8_SCHED; PG8_LDA(At, 1, 0); PG8_STAGE(PG8_SA(0, 1), a2 + hstep, voffA);
;             PG8_WAIT_V(8); PG8_WAIT_L(0); PG8_BAR; PG8_MMA(0, 0, At, B0); PG8_MMA(0, 1, At, B1); PG8_BAR; PG8_SCHED;
	s_add_i32 s54, 0, 0x18000
	s_add_i32 s55, 0, 0x1c000
	v_add_u32_e32 v142, s54, v1
	v_add_u32_e32 v154, s55, v1
	ds_read_b128 v[130:133], v142
	ds_read_b128 v[134:137], v142 offset:1024
	ds_read_b128 v[138:141], v142 offset:2048
	ds_read_b128 v[142:145], v142 offset:3072
	ds_read_b128 v[166:169], v154
	ds_read_b128 v[170:173], v154 offset:1024
	ds_read_b128 v[174:177], v154 offset:2048
	ds_read_b128 v[178:181], v154 offset:3072
	s_add_u32 s18, s46, 0x160000
	s_addc_u32 s19, s47, 0
	s_mov_b32 m0, s29
	v_lshl_add_u64 v[232:233], s[18:19], 0, v[146:147]
	ds_read_b128 v[182:185], v198 offset:32768
	ds_read_b128 v[186:189], v198 offset:33792
	ds_read_b128 v[202:205], v198 offset:34816
	ds_read_b128 v[206:209], v198 offset:35840
	ds_read_b128 v[210:213], v198 offset:36864
	ds_read_b128 v[214:217], v198 offset:37888
	ds_read_b128 v[218:221], v198 offset:38912
	ds_read_b128 v[222:225], v198 offset:39936
	global_load_lds_dwordx4 v[232:233], off
	v_lshl_add_u64 v[232:233], s[18:19], 0, v[150:151]
	s_mov_b32 m0, s30
	s_nop 0
	global_load_lds_dwordx4 v[232:233], off
	s_waitcnt vmcnt(8)
	s_waitcnt lgkmcnt(0)
	s_barrier
	s_setprio 1
	s_waitcnt lgkmcnt(0)
	v_mfma_f32_16x16x32_bf16 v[126:129], v[130:133], v[182:185], v[126:129]
	v_mfma_f32_16x16x32_bf16 v[122:125], v[138:141], v[182:185], v[122:125]
	v_mfma_f32_16x16x32_bf16 v[110:113], v[130:133], v[202:205], v[110:113]
	v_mfma_f32_16x16x32_bf16 v[106:109], v[138:141], v[202:205], v[106:109]
	v_mfma_f32_16x16x32_bf16 v[94:97], v[130:133], v[210:213], v[94:97]
	v_mfma_f32_16x16x32_bf16 v[90:93], v[138:141], v[210:213], v[90:93]
	v_mfma_f32_16x16x32_bf16 v[78:81], v[130:133], v[218:221], v[78:81]
	v_mfma_f32_16x16x32_bf16 v[74:77], v[138:141], v[218:221], v[74:77]
	v_mfma_f32_16x16x32_bf16 v[126:129], v[134:137], v[186:189], v[126:129]
	v_mfma_f32_16x16x32_bf16 v[122:125], v[142:145], v[186:189], v[122:125]
	v_mfma_f32_16x16x32_bf16 v[110:113], v[134:137], v[206:209], v[110:113]
	v_mfma_f32_16x16x32_bf16 v[106:109], v[142:145], v[206:209], v[106:109]
	v_mfma_f32_16x16x32_bf16 v[94:97], v[134:137], v[214:217], v[94:97]
	v_mfma_f32_16x16x32_bf16 v[90:93], v[142:145], v[214:217], v[90:93]
	v_mfma_f32_16x16x32_bf16 v[78:81], v[134:137], v[222:225], v[78:81]
	v_mfma_f32_16x16x32_bf16 v[74:77], v[142:145], v[222:225], v[74:77]
	v_mfma_f32_16x16x32_bf16 v[118:121], v[166:169], v[182:185], v[118:121]
	v_mfma_f32_16x16x32_bf16 v[114:117], v[174:177], v[182:185], v[114:117]
	v_mfma_f32_16x16x32_bf16 v[102:105], v[166:169], v[202:205], v[102:105]
	v_mfma_f32_16x16x32_bf16 v[98:101], v[174:177], v[202:205], v[98:101]
	v_mfma_f32_16x16x32_bf16 v[86:89], v[166:169], v[210:213], v[86:89]
	v_mfma_f32_16x16x32_bf16 v[82:85], v[174:177], v[210:213], v[82:85]
	v_mfma_f32_16x16x32_bf16 v[70:73], v[166:169], v[218:221], v[70:73]
	v_mfma_f32_16x16x32_bf16 v[66:69], v[174:177], v[218:221], v[66:69]
	v_mfma_f32_16x16x32_bf16 v[118:121], v[170:173], v[186:189], v[118:121]
	v_mfma_f32_16x16x32_bf16 v[114:117], v[178:181], v[186:189], v[114:117]
	v_mfma_f32_16x16x32_bf16 v[102:105], v[170:173], v[206:209], v[102:105]
	v_mfma_f32_16x16x32_bf16 v[98:101], v[178:181], v[206:209], v[98:101]
	v_mfma_f32_16x16x32_bf16 v[86:89], v[170:173], v[214:217], v[86:89]
	v_mfma_f32_16x16x32_bf16 v[82:85], v[178:181], v[214:217], v[82:85]
	v_mfma_f32_16x16x32_bf16 v[70:73], v[170:173], v[222:225], v[70:73]
	v_mfma_f32_16x16x32_bf16 v[66:69], v[178:181], v[222:225], v[66:69]
	s_setprio 0
	s_barrier
; #define PG8_STAGE(bufoff, gbase, voff) do { _Pragma("unroll") for (int _i = 0; _i < 2; ++_i) \
;         __builtin_amdgcn_global_load_lds((const unsigned*)((const char*)(gbase) + (voff)[_i]), (LAS unsigned*)(lds + (bufoff) + ldsw + _i * 8192), 16, 0, 0); } while (0)
; #define PG8_LDA(dst, b, h) do { _Pragma("unroll") for (int m = 0; m < 4; ++m) _Pragma("unroll") for (int k = 0; k < 2; ++k) dst[m][k] = *(const LAS bf16x8*)(lds + PG8_SA(b, h) + aoff + m * 2048 + k * 1024); } while (0)
; #define PG8_MMA(ai, bj, At, Bt) do { __builtin_amdgcn_s_setprio(1); _Pragma("unroll") for (int m = 0; m < 4; ++m) _Pragma("unroll") for (int n = 0; n < 2; ++n) _Pragma("unroll") for (int k = 0; k < 2; ++k) \
;         acc[ai][bj][m][n] = __builtin_amdgcn_mfma_f32_16x16x32_bf16(Bt[n][k], At[m][k], acc[ai][bj][m][n], 0, 0, 0); __builtin_amdgcn_s_setprio(0); } while (0)
; #define PG8_WAIT_V(n) asm volatile("s_waitcnt vmcnt(" #n ")" ::: "memory")
; #define PG8_WAIT_L(n) asm volatile("s_waitcnt lgkmcnt(" #n ")" ::: "memory")
; #define PG8_BAR __builtin_amdgcn_s_barrier()
; #define PG8_SCHED __builtin_amdgcn_sched_barrier(0)
; template <class Epi, class Sched, bool ALIGN_EPI = false, bool SP2 = false>
; __device__ __forceinline__ void gemm_phase(LAS unsigned char* lds, const Gemm g, const Sched& S, const Epi& E) {
;     ...
;             PG8_LDA(At, 1, 1); PG8_STAGE(PG8_SB(1, 0), b3, voffB); PG8_STAGE(PG8_SB(1, 1), b3 + hstepB, voffB); PG8_STAGE(PG8_SA(1, 0), a3, voffA);
;             PG8_WAIT_V(8); PG8_WAIT_L(0); PG8_BAR; PG8_MMA(1, 0, At, B0); PG8_MMA(1, 1, At, B1); PG8_BAR; PG8_SCHED;
;     ...
;         if constexpr (ALIGN_EPI) { if (wr == 0) PG8_BAR; }
	s_add_i32 s18, s54, s26
	v_lshl_add_u64 v[190:191], v[190:191], 0, s[12:13]
	s_mov_b32 m0, s18
	ds_read_b128 v[182:185], v198 offset:49152
	ds_read_b128 v[186:189], v198 offset:50176
	ds_read_b128 v[202:205], v198 offset:51200
	ds_read_b128 v[206:209], v198 offset:52224
	ds_read_b128 v[210:213], v198 offset:53248
	ds_read_b128 v[214:217], v198 offset:54272
	ds_read_b128 v[218:221], v198 offset:55296
	ds_read_b128 v[222:225], v198 offset:56320
	global_load_lds_dwordx4 v[190:191], off
	s_add_i32 m0, s18, 0x2000
	s_add_u32 s18, s22, 0x58080
	v_lshl_add_u64 v[190:191], v[226:227], 0, s[12:13]
	s_addc_u32 s19, s23, 0
	s_add_i32 s22, s55, s26
	global_load_lds_dwordx4 v[190:191], off
	v_lshl_add_u64 v[190:191], s[18:19], 0, v[148:149]
	s_mov_b32 m0, s22
	s_nop 0
	global_load_lds_dwordx4 v[190:191], off
	v_lshl_add_u64 v[190:191], s[18:19], 0, v[152:153]
	s_add_i32 m0, s22, 0x2000
	s_nop 0
	global_load_lds_dwordx4 v[190:191], off
	v_lshl_add_u64 v[190:191], v[228:229], 0, s[12:13]
	s_mov_b32 m0, s37
	s_nop 0
	global_load_lds_dwordx4 v[190:191], off
	v_lshl_add_u64 v[190:191], v[230:231], 0, s[12:13]
	s_mov_b32 m0, s48
	s_nop 0
	global_load_lds_dwordx4 v[190:191], off
	s_waitcnt vmcnt(8)
	s_waitcnt lgkmcnt(0)
	s_barrier
	s_setprio 1
	s_waitcnt lgkmcnt(0)
	v_mfma_f32_16x16x32_bf16 v[62:65], v[130:133], v[182:185], v[62:65]
	v_mfma_f32_16x16x32_bf16 v[58:61], v[138:141], v[182:185], v[58:61]
	v_mfma_f32_16x16x32_bf16 v[46:49], v[130:133], v[202:205], v[46:49]
	v_mfma_f32_16x16x32_bf16 v[42:45], v[138:141], v[202:205], v[42:45]
	v_mfma_f32_16x16x32_bf16 v[30:33], v[130:133], v[210:213], v[30:33]
	v_mfma_f32_16x16x32_bf16 v[26:29], v[138:141], v[210:213], v[26:29]
	v_mfma_f32_16x16x32_bf16 v[14:17], v[130:133], v[218:221], v[14:17]
	v_mfma_f32_16x16x32_bf16 v[10:13], v[138:141], v[218:221], v[10:13]
	v_mfma_f32_16x16x32_bf16 v[62:65], v[134:137], v[186:189], v[62:65]
	v_mfma_f32_16x16x32_bf16 v[58:61], v[142:145], v[186:189], v[58:61]
	v_mfma_f32_16x16x32_bf16 v[46:49], v[134:137], v[206:209], v[46:49]
	v_mfma_f32_16x16x32_bf16 v[42:45], v[142:145], v[206:209], v[42:45]
	v_mfma_f32_16x16x32_bf16 v[30:33], v[134:137], v[214:217], v[30:33]
	v_mfma_f32_16x16x32_bf16 v[26:29], v[142:145], v[214:217], v[26:29]
	v_mfma_f32_16x16x32_bf16 v[14:17], v[134:137], v[222:225], v[14:17]
	v_mfma_f32_16x16x32_bf16 v[10:13], v[142:145], v[222:225], v[10:13]
	v_mfma_f32_16x16x32_bf16 v[54:57], v[166:169], v[182:185], v[54:57]
	v_mfma_f32_16x16x32_bf16 v[50:53], v[174:177], v[182:185], v[50:53]
	v_mfma_f32_16x16x32_bf16 v[38:41], v[166:169], v[202:205], v[38:41]
	v_mfma_f32_16x16x32_bf16 v[34:37], v[174:177], v[202:205], v[34:37]
	v_mfma_f32_16x16x32_bf16 v[22:25], v[166:169], v[210:213], v[22:25]
	v_mfma_f32_16x16x32_bf16 v[18:21], v[174:177], v[210:213], v[18:21]
	v_mfma_f32_16x16x32_bf16 v[6:9], v[166:169], v[218:221], v[6:9]
	v_mfma_f32_16x16x32_bf16 v[2:5], v[174:177], v[218:221], v[2:5]
	v_mfma_f32_16x16x32_bf16 v[54:57], v[170:173], v[186:189], v[54:57]
	v_mfma_f32_16x16x32_bf16 v[50:53], v[178:181], v[186:189], v[50:53]
	v_mfma_f32_16x16x32_bf16 v[38:41], v[170:173], v[206:209], v[38:41]
	v_mfma_f32_16x16x32_bf16 v[34:37], v[178:181], v[206:209], v[34:37]
	v_mfma_f32_16x16x32_bf16 v[22:25], v[170:173], v[214:217], v[22:25]
	v_mfma_f32_16x16x32_bf16 v[18:21], v[178:181], v[214:217], v[18:21]
	v_mfma_f32_16x16x32_bf16 v[6:9], v[170:173], v[222:225], v[6:9]
	v_mfma_f32_16x16x32_bf16 v[2:5], v[178:181], v[222:225], v[2:5]
	s_setprio 0
	s_barrier
	s_add_i32 s25, s25, 2
	s_add_u32 s5, s5, 0x100
	s_addc_u32 s24, s24, 0
	s_cmpk_lt_u32 s25, 0x56
	s_mov_b64 s[18:19], s[20:21]
	s_cbranch_scc1 .LBB0_1926
	s_andn2_b64 vcc, exec, s[14:15]
	s_cbranch_vccnz .LBB0_1929
	s_barrier

;     __device__ bool next(int i, Unit& u) const { if (i != 0 || c >= 128) return false; const int t = c >> 2; u.pm = t & 3; u.pn = t >> 2; u.koff = koff_bytes; u.q = c & 3; return true; }
; #define PG8_STAGE(bufoff, gbase, voff) do { _Pragma("unroll") for (int _i = 0; _i < 2; ++_i) \
;         __builtin_amdgcn_global_load_lds((const unsigned*)((const char*)(gbase) + (voff)[_i]), (LAS unsigned*)(lds + (bufoff) + ldsw + _i * 8192), 16, 0, 0); } while (0)
; #define PG8_LDA(dst, b, h) do { _Pragma("unroll") for (int m = 0; m < 4; ++m) _Pragma("unroll") for (int k = 0; k < 2; ++k) dst[m][k] = *(const LAS bf16x8*)(lds + PG8_SA(b, h) + aoff + m * 2048 + k * 1024); } while (0)
; #define PG8_LDB(dst, b, h) do { _Pragma("unroll") for (int n = 0; n < 2; ++n) _Pragma("unroll") for (int k = 0; k < 2; ++k) dst[n][k] = *(const LAS bf16x8*)(lds + PG8_SB(b, h) + boff + n * 2048 + k * 1024); } while (0)
; #define PG8_WAIT_V(n) asm volatile("s_waitcnt vmcnt(" #n ")" ::: "memory")
; template <class Epi, class Sched, bool ALIGN_EPI = false, bool SP2 = false>
; __device__ __forceinline__ void gemm_phase(LAS unsigned char* lds, const Gemm g, const Sched& S, const Epi& E) {
;     ...
;         const bool has_next = S.next(ui + 1, nxt);
;         const char* nA = has_next ? (const char*)g.A + (size_t)nxt.pm * tstep + nxt.koff : cA; const char* nB = has_next ? (const char*)g.Bt + (size_t)nxt.pn * tstep + nxt.koff : cB;
;         for (int t = 0; t < nt; t += 2) {
;             const bool last = (t == nt - 2);
;             const char* a1 = cA + (size_t)(t + 1) * kstep;
;             const char* a2 = last ? nA : cA + (size_t)(t + 2) * kstep; const char* b2 = last ? nB : cB + (size_t)(t + 2) * kstep;
;             const char* a3 = a2 + kstep; const char* b3 = b2 + kstep;
;             if (last && has_next) S.a_ready(nxt);
;             if constexpr (SP2) {
;             PG8_LDB(B0, 0, 0); PG8_LDB(B1, 0, 1); PG8_SCHED; PG8_LDA(At, 0, 0); PG8_STAGE(PG8_SA(1, 1), a1 + hstep, voffA);
;             PG8_WAIT_V(8); PG8_WAIT_L(0); PG8_BAR; PG8_MMA(0, 0, At, B0); PG8_MMA(0, 1, At, B1); PG8_BAR; PG8_SCHED;
;             PG8_LDA(At, 0, 1); PG8_STAGE(PG8_SB(0, 0), b2, voffB); PG8_STAGE(PG8_SB(0, 1), b2 + hstepB, voffB); PG8_STAGE(PG8_SA(0, 0), a2, voffA);
;             PG8_WAIT_V(8); PG8_WAIT_L(0); PG8_BAR; PG8_MMA(1, 0, At, B0); PG8_MMA(1, 1, At, B1); PG8_BAR; PG8_SCHED;
.LBB0_2142:
	s_ashr_i32 s13, s12, 31
	v_cmp_lt_i64_e64 s[44:45], s[14:15], v[176:177]
	s_lshl_b64 s[14:15], s[12:13], 20
	s_add_u32 s14, s93, s14
	s_addc_u32 s15, s92, s15
	s_and_b64 s[16:17], s[44:45], exec
	s_cselect_b32 s3, s15, s23
	s_cselect_b32 s13, s14, s22
	s_ashr_i32 s11, s10, 31
	s_lshl_b64 s[16:17], s[10:11], 20
	v_readlane_b32 s24, v254, 58
	v_readlane_b32 s25, v254, 59
	s_add_u32 s16, s24, s16
	s_addc_u32 s17, s25, s17
	s_and_b64 s[24:25], s[44:45], exec
	s_cselect_b32 s11, s17, s21
	s_cselect_b32 s19, s16, s20
	s_add_u32 s24, s20, 0x100
	s_addc_u32 s25, s21, 0
	s_add_u32 s20, s22, 0x80080
	s_addc_u32 s21, s23, 0
	s_mov_b32 s34, -2
	s_waitcnt vmcnt(0)
	ds_read_b128 v[34:37], v202
	ds_read_b128 v[38:41], v202 offset:1024
	ds_read_b128 v[42:45], v202 offset:2048
	ds_read_b128 v[46:49], v202 offset:3072
	ds_read_b128 v[98:101], v203
	ds_read_b128 v[102:105], v203 offset:1024
	ds_read_b128 v[106:109], v203 offset:2048
	ds_read_b128 v[110:113], v203 offset:3072
	s_add_u32 s22, s20, 0xfff80080
	s_addc_u32 s23, s21, -1
	s_cmp_eq_u32 s34, 28
	s_cselect_b32 s37, s3, s23
	s_cselect_b32 s36, s13, s22
	s_cselect_b32 s23, s11, s25
	s_cselect_b32 s22, s19, s24
	v_lshl_add_u64 v[182:183], s[20:21], 0, v[174:175]
	s_add_i32 m0, s28, 0xc000
	ds_read_b128 v[210:213], v204
	ds_read_b128 v[214:217], v204 offset:1024
	ds_read_b128 v[218:221], v204 offset:2048
	ds_read_b128 v[222:225], v204 offset:3072
	ds_read_b128 v[226:229], v204 offset:4096
	ds_read_b128 v[230:233], v204 offset:5120
	ds_read_b128 v[234:237], v204 offset:6144
	ds_read_b128 v[238:241], v204 offset:7168
	global_load_lds_dwordx4 v[182:183], off
	v_lshl_add_u64 v[182:183], s[20:21], 0, v[172:173]
	s_add_i32 m0, s28, 0xe000
	s_nop 0
	global_load_lds_dwordx4 v[182:183], off
	s_waitcnt lgkmcnt(0)
	s_barrier
	s_setprio 1
	s_waitcnt lgkmcnt(0)
	v_mfma_f32_16x16x32_bf16 v[158:161], v[34:37], v[210:213], 0
	v_mfma_f32_16x16x32_bf16 v[154:157], v[42:45], v[210:213], 0
	v_mfma_f32_16x16x32_bf16 v[142:145], v[34:37], v[218:221], 0
	v_mfma_f32_16x16x32_bf16 v[138:141], v[42:45], v[218:221], 0
	v_mfma_f32_16x16x32_bf16 v[126:129], v[34:37], v[226:229], 0
	v_mfma_f32_16x16x32_bf16 v[122:125], v[42:45], v[226:229], 0
	v_mfma_f32_16x16x32_bf16 v[94:97], v[34:37], v[234:237], 0
	v_mfma_f32_16x16x32_bf16 v[90:93], v[42:45], v[234:237], 0
	v_mfma_f32_16x16x32_bf16 v[158:161], v[38:41], v[214:217], v[158:161]
	v_mfma_f32_16x16x32_bf16 v[154:157], v[46:49], v[214:217], v[154:157]
	v_mfma_f32_16x16x32_bf16 v[142:145], v[38:41], v[222:225], v[142:145]
	v_mfma_f32_16x16x32_bf16 v[138:141], v[46:49], v[222:225], v[138:141]
	v_mfma_f32_16x16x32_bf16 v[126:129], v[38:41], v[230:233], v[126:129]
	v_mfma_f32_16x16x32_bf16 v[122:125], v[46:49], v[230:233], v[122:125]
	v_mfma_f32_16x16x32_bf16 v[94:97], v[38:41], v[238:241], v[94:97]
	v_mfma_f32_16x16x32_bf16 v[90:93], v[46:49], v[238:241], v[90:93]
	v_mfma_f32_16x16x32_bf16 v[150:153], v[98:101], v[210:213], 0
	v_mfma_f32_16x16x32_bf16 v[146:149], v[106:109], v[210:213], 0
	v_mfma_f32_16x16x32_bf16 v[134:137], v[98:101], v[218:221], 0
	v_mfma_f32_16x16x32_bf16 v[130:133], v[106:109], v[218:221], 0
	v_mfma_f32_16x16x32_bf16 v[118:121], v[98:101], v[226:229], 0
	v_mfma_f32_16x16x32_bf16 v[114:117], v[106:109], v[226:229], 0
	v_mfma_f32_16x16x32_bf16 v[86:89], v[98:101], v[234:237], 0
	v_mfma_f32_16x16x32_bf16 v[82:85], v[106:109], v[234:237], 0
	v_mfma_f32_16x16x32_bf16 v[150:153], v[102:105], v[214:217], v[150:153]
	v_mfma_f32_16x16x32_bf16 v[146:149], v[110:113], v[214:217], v[146:149]
	v_mfma_f32_16x16x32_bf16 v[134:137], v[102:105], v[222:225], v[134:137]
	v_mfma_f32_16x16x32_bf16 v[130:133], v[110:113], v[222:225], v[130:133]
	v_mfma_f32_16x16x32_bf16 v[118:121], v[102:105], v[230:233], v[118:121]
	v_mfma_f32_16x16x32_bf16 v[114:117], v[110:113], v[230:233], v[114:117]
	v_mfma_f32_16x16x32_bf16 v[86:89], v[102:105], v[238:241], v[86:89]
	v_mfma_f32_16x16x32_bf16 v[82:85], v[110:113], v[238:241], v[82:85]
	s_setprio 0
	s_barrier
	s_add_i32 s35, s56, s27
	v_lshl_add_u64 v[182:183], s[22:23], 0, v[164:165]
	s_mov_b32 m0, s35
	ds_read_b128 v[210:213], v204 offset:16384
	ds_read_b128 v[214:217], v204 offset:17408
	ds_read_b128 v[218:221], v204 offset:18432
	ds_read_b128 v[222:225], v204 offset:19456
	ds_read_b128 v[226:229], v204 offset:20480
	ds_read_b128 v[230:233], v204 offset:21504
	ds_read_b128 v[234:237], v204 offset:22528
	ds_read_b128 v[238:241], v204 offset:23552
	global_load_lds_dwordx4 v[182:183], off
	s_add_i32 m0, s35, 0x2000
	s_add_u32 s46, s22, 0x20000
	v_lshl_add_u64 v[242:243], s[22:23], 0, v[168:169]
	s_addc_u32 s47, s23, 0
	s_add_i32 s35, s57, s27
	global_load_lds_dwordx4 v[242:243], off
	v_lshl_add_u64 v[244:245], s[46:47], 0, v[164:165]
	s_mov_b32 m0, s35
	v_lshl_add_u64 v[246:247], s[36:37], 0, v[166:167]
	global_load_lds_dwordx4 v[244:245], off
	v_lshl_add_u64 v[244:245], s[46:47], 0, v[168:169]
	s_add_i32 m0, s35, 0x2000
	s_nop 0
	global_load_lds_dwordx4 v[244:245], off
	v_lshl_add_u64 v[244:245], s[36:37], 0, v[162:163]
	s_mov_b32 m0, s28
	s_nop 0
	global_load_lds_dwordx4 v[244:245], off
	s_mov_b32 m0, s29
	s_nop 0
	global_load_lds_dwordx4 v[246:247], off
	s_waitcnt lgkmcnt(0)
	s_barrier
; #define PG8_STAGE(bufoff, gbase, voff) do { _Pragma("unroll") for (int _i = 0; _i < 2; ++_i) \
;         __builtin_amdgcn_global_load_lds((const unsigned*)((const char*)(gbase) + (voff)[_i]), (LAS unsigned*)(lds + (bufoff) + ldsw + _i * 8192), 16, 0, 0); } while (0)
; #define PG8_LDA(dst, b, h) do { _Pragma("unroll") for (int m = 0; m < 4; ++m) _Pragma("unroll") for (int k = 0; k < 2; ++k) dst[m][k] = *(const LAS bf16x8*)(lds + PG8_SA(b, h) + aoff + m * 2048 + k * 1024); } while (0)
; #define PG8_LDB(dst, b, h) do { _Pragma("unroll") for (int n = 0; n < 2; ++n) _Pragma("unroll") for (int k = 0; k < 2; ++k) dst[n][k] = *(const LAS bf16x8*)(lds + PG8_SB(b, h) + boff + n * 2048 + k * 1024); } while (0)
; #define PG8_MMA(ai, bj, At, Bt) do { __builtin_amdgcn_s_setprio(1); _Pragma("unroll") for (int m = 0; m < 4; ++m) _Pragma("unroll") for (int n = 0; n < 2; ++n) _Pragma("unroll") for (int k = 0; k < 2; ++k) \
;         acc[ai][bj][m][n] = __builtin_amdgcn_mfma_f32_16x16x32_bf16(Bt[n][k], At[m][k], acc[ai][bj][m][n], 0, 0, 0); __builtin_amdgcn_s_setprio(0); } while (0)
; #define PG8_WAIT_V(n) asm volatile("s_waitcnt vmcnt(" #n ")" ::: "memory")
; #define PG8_WAIT_L(n) asm volatile("s_waitcnt lgkmcnt(" #n ")" ::: "memory")
; #define PG8_BAR __builtin_amdgcn_s_barrier()
; #define PG8_SCHED __builtin_amdgcn_sched_barrier(0)
; template <class Epi, class Sched, bool ALIGN_EPI = false, bool SP2 = false>
; __device__ __forceinline__ void gemm_phase(LAS unsigned char* lds, const Gemm g, const Sched& S, const Epi& E) {
;     ...
;             PG8_WAIT_V(8); PG8_WAIT_L(0); PG8_BAR; PG8_MMA(1, 0, At, B0); PG8_MMA(1, 1, At, B1); PG8_BAR; PG8_SCHED;
;             PG8_LDB(B0, 1, 0); PG8_LDB(B1, 1, 1); PG8_SCHED; PG8_LDA(At, 1, 0); PG8_STAGE(PG8_SA(0, 1), a2 + hstep, voffA);
;             PG8_WAIT_V(8); PG8_WAIT_L(0); PG8_BAR; PG8_MMA(0, 0, At, B0); PG8_MMA(0, 1, At, B1); PG8_BAR; PG8_SCHED;
	s_setprio 1
	s_waitcnt lgkmcnt(0)
	v_mfma_f32_16x16x32_bf16 v[78:81], v[34:37], v[210:213], 0
	v_mfma_f32_16x16x32_bf16 v[74:77], v[42:45], v[210:213], 0
	v_mfma_f32_16x16x32_bf16 v[62:65], v[34:37], v[218:221], 0
	v_mfma_f32_16x16x32_bf16 v[58:61], v[42:45], v[218:221], 0
	v_mfma_f32_16x16x32_bf16 v[30:33], v[34:37], v[226:229], 0
	v_mfma_f32_16x16x32_bf16 v[26:29], v[42:45], v[226:229], 0
	v_mfma_f32_16x16x32_bf16 v[14:17], v[34:37], v[234:237], 0
	v_mfma_f32_16x16x32_bf16 v[10:13], v[42:45], v[234:237], 0
	v_mfma_f32_16x16x32_bf16 v[78:81], v[38:41], v[214:217], v[78:81]
	v_mfma_f32_16x16x32_bf16 v[74:77], v[46:49], v[214:217], v[74:77]
	v_mfma_f32_16x16x32_bf16 v[62:65], v[38:41], v[222:225], v[62:65]
	v_mfma_f32_16x16x32_bf16 v[58:61], v[46:49], v[222:225], v[58:61]
	v_mfma_f32_16x16x32_bf16 v[30:33], v[38:41], v[230:233], v[30:33]
	v_mfma_f32_16x16x32_bf16 v[26:29], v[46:49], v[230:233], v[26:29]
	v_mfma_f32_16x16x32_bf16 v[14:17], v[38:41], v[238:241], v[14:17]
	v_mfma_f32_16x16x32_bf16 v[10:13], v[46:49], v[238:241], v[10:13]
	v_mfma_f32_16x16x32_bf16 v[22:25], v[98:101], v[226:229], 0
	v_mfma_f32_16x16x32_bf16 v[18:21], v[106:109], v[226:229], 0
	v_mfma_f32_16x16x32_bf16 v[6:9], v[98:101], v[234:237], 0
	v_mfma_f32_16x16x32_bf16 v[2:5], v[106:109], v[234:237], 0
	v_mfma_f32_16x16x32_bf16 v[34:37], v[98:101], v[210:213], 0
	v_mfma_f32_16x16x32_bf16 v[38:41], v[106:109], v[210:213], 0
	v_mfma_f32_16x16x32_bf16 v[42:45], v[98:101], v[218:221], 0
	v_mfma_f32_16x16x32_bf16 v[46:49], v[106:109], v[218:221], 0
	v_mfma_f32_16x16x32_bf16 v[22:25], v[102:105], v[230:233], v[22:25]
	v_mfma_f32_16x16x32_bf16 v[18:21], v[110:113], v[230:233], v[18:21]
	v_mfma_f32_16x16x32_bf16 v[6:9], v[102:105], v[238:241], v[6:9]
	v_mfma_f32_16x16x32_bf16 v[2:5], v[110:113], v[238:241], v[2:5]
	v_mfma_f32_16x16x32_bf16 v[34:37], v[102:105], v[214:217], v[34:37]
	v_mfma_f32_16x16x32_bf16 v[38:41], v[110:113], v[214:217], v[38:41]
	v_mfma_f32_16x16x32_bf16 v[42:45], v[102:105], v[222:225], v[42:45]
	v_mfma_f32_16x16x32_bf16 v[46:49], v[110:113], v[222:225], v[46:49]
	s_setprio 0
	s_barrier
	s_add_i32 s35, 0, 0x18000
	s_add_i32 s46, 0, 0x1c000
	v_add_u32_e32 v70, s35, v185
	v_add_u32_e32 v110, s46, v185
	ds_read_b128 v[50:53], v70
	ds_read_b128 v[54:57], v70 offset:1024
	ds_read_b128 v[66:69], v70 offset:2048
	ds_read_b128 v[70:73], v70 offset:3072
	ds_read_b128 v[98:101], v110
	ds_read_b128 v[102:105], v110 offset:1024
	ds_read_b128 v[106:109], v110 offset:2048
	ds_read_b128 v[110:113], v110 offset:3072
	s_add_u32 s36, s36, 0x80000
	s_addc_u32 s37, s37, 0
	s_mov_b32 m0, s30
	v_lshl_add_u64 v[248:249], s[36:37], 0, v[162:163]
	ds_read_b128 v[210:213], v204 offset:32768
	ds_read_b128 v[214:217], v204 offset:33792
	ds_read_b128 v[218:221], v204 offset:34816
	ds_read_b128 v[222:225], v204 offset:35840
	ds_read_b128 v[226:229], v204 offset:36864
	ds_read_b128 v[230:233], v204 offset:37888
	ds_read_b128 v[234:237], v204 offset:38912
	ds_read_b128 v[238:241], v204 offset:39936
	global_load_lds_dwordx4 v[248:249], off
	v_lshl_add_u64 v[248:249], s[36:37], 0, v[166:167]
	s_mov_b32 m0, s31
	s_nop 0
	global_load_lds_dwordx4 v[248:249], off
	s_waitcnt vmcnt(8)
	s_waitcnt lgkmcnt(0)
	s_barrier
	s_setprio 1
	s_waitcnt lgkmcnt(0)
	v_mfma_f32_16x16x32_bf16 v[158:161], v[50:53], v[210:213], v[158:161]
	v_mfma_f32_16x16x32_bf16 v[154:157], v[66:69], v[210:213], v[154:157]
	v_mfma_f32_16x16x32_bf16 v[142:145], v[50:53], v[218:221], v[142:145]
	v_mfma_f32_16x16x32_bf16 v[138:141], v[66:69], v[218:221], v[138:141]
	v_mfma_f32_16x16x32_bf16 v[126:129], v[50:53], v[226:229], v[126:129]
	v_mfma_f32_16x16x32_bf16 v[122:125], v[66:69], v[226:229], v[122:125]
	v_mfma_f32_16x16x32_bf16 v[94:97], v[50:53], v[234:237], v[94:97]
	v_mfma_f32_16x16x32_bf16 v[90:93], v[66:69], v[234:237], v[90:93]
	v_mfma_f32_16x16x32_bf16 v[158:161], v[54:57], v[214:217], v[158:161]
	v_mfma_f32_16x16x32_bf16 v[154:157], v[70:73], v[214:217], v[154:157]
	v_mfma_f32_16x16x32_bf16 v[142:145], v[54:57], v[222:225], v[142:145]
	v_mfma_f32_16x16x32_bf16 v[138:141], v[70:73], v[222:225], v[138:141]
	v_mfma_f32_16x16x32_bf16 v[126:129], v[54:57], v[230:233], v[126:129]
	v_mfma_f32_16x16x32_bf16 v[122:125], v[70:73], v[230:233], v[122:125]
	v_mfma_f32_16x16x32_bf16 v[94:97], v[54:57], v[238:241], v[94:97]
	v_mfma_f32_16x16x32_bf16 v[90:93], v[70:73], v[238:241], v[90:93]
	v_mfma_f32_16x16x32_bf16 v[150:153], v[98:101], v[210:213], v[150:153]
	v_mfma_f32_16x16x32_bf16 v[146:149], v[106:109], v[210:213], v[146:149]
	v_mfma_f32_16x16x32_bf16 v[134:137], v[98:101], v[218:221], v[134:137]
	v_mfma_f32_16x16x32_bf16 v[130:133], v[106:109], v[218:221], v[130:133]
	v_mfma_f32_16x16x32_bf16 v[118:121], v[98:101], v[226:229], v[118:121]
	v_mfma_f32_16x16x32_bf16 v[114:117], v[106:109], v[226:229], v[114:117]
	v_mfma_f32_16x16x32_bf16 v[86:89], v[98:101], v[234:237], v[86:89]
	v_mfma_f32_16x16x32_bf16 v[82:85], v[106:109], v[234:237], v[82:85]
	v_mfma_f32_16x16x32_bf16 v[150:153], v[102:105], v[214:217], v[150:153]
	v_mfma_f32_16x16x32_bf16 v[146:149], v[110:113], v[214:217], v[146:149]
	v_mfma_f32_16x16x32_bf16 v[134:137], v[102:105], v[222:225], v[134:137]
	v_mfma_f32_16x16x32_bf16 v[130:133], v[110:113], v[222:225], v[130:133]
	v_mfma_f32_16x16x32_bf16 v[118:121], v[102:105], v[230:233], v[118:121]
	v_mfma_f32_16x16x32_bf16 v[114:117], v[110:113], v[230:233], v[114:117]
	v_mfma_f32_16x16x32_bf16 v[86:89], v[102:105], v[238:241], v[86:89]
	v_mfma_f32_16x16x32_bf16 v[82:85], v[110:113], v[238:241], v[82:85]
	s_setprio 0
	s_barrier
; #define PG8_STAGE(bufoff, gbase, voff) do { _Pragma("unroll") for (int _i = 0; _i < 2; ++_i) \
;         __builtin_amdgcn_global_load_lds((const unsigned*)((const char*)(gbase) + (voff)[_i]), (LAS unsigned*)(lds + (bufoff) + ldsw + _i * 8192), 16, 0, 0); } while (0)
; #define PG8_LDA(dst, b, h) do { _Pragma("unroll") for (int m = 0; m < 4; ++m) _Pragma("unroll") for (int k = 0; k < 2; ++k) dst[m][k] = *(const LAS bf16x8*)(lds + PG8_SA(b, h) + aoff + m * 2048 + k * 1024); } while (0)
; #define PG8_LDB(dst, b, h) do { _Pragma("unroll") for (int n = 0; n < 2; ++n) _Pragma("unroll") for (int k = 0; k < 2; ++k) dst[n][k] = *(const LAS bf16x8*)(lds + PG8_SB(b, h) + boff + n * 2048 + k * 1024); } while (0)
; template <class Epi, class Sched, bool ALIGN_EPI = false, bool SP2 = false>
; __device__ __forceinline__ void gemm_phase(LAS unsigned char* lds, const Gemm g, const Sched& S, const Epi& E) {
;     ...
;         for (int t = 0; t < nt; t += 2) {
;             const bool last = (t == nt - 2);
;             const char* a1 = cA + (size_t)(t + 1) * kstep;
;             const char* a2 = last ? nA : cA + (size_t)(t + 2) * kstep; const char* b2 = last ? nB : cB + (size_t)(t + 2) * kstep;
;             const char* a3 = a2 + kstep; const char* b3 = b2 + kstep;
;             if (last && has_next) S.a_ready(nxt);
;             if constexpr (SP2) {
;             PG8_LDB(B0, 0, 0); PG8_LDB(B1, 0, 1); PG8_SCHED; PG8_LDA(At, 0, 0); PG8_STAGE(PG8_SA(1, 1), a1 + hstep, voffA);
;             PG8_WAIT_V(8); PG8_WAIT_L(0); PG8_BAR; PG8_MMA(0, 0, At, B0); PG8_MMA(0, 1, At, B1); PG8_BAR; PG8_SCHED;
;             PG8_LDA(At, 0, 1); PG8_STAGE(PG8_SB(0, 0), b2, voffB); PG8_STAGE(PG8_SB(0, 1), b2 + hstepB, voffB); PG8_STAGE(PG8_SA(0, 0), a2, voffA);
;             PG8_WAIT_V(8); PG8_WAIT_L(0); PG8_BAR; PG8_MMA(1, 0, At, B0); PG8_MMA(1, 1, At, B1); PG8_BAR; PG8_SCHED;
;             PG8_LDB(B0, 1, 0); PG8_LDB(B1, 1, 1); PG8_SCHED; PG8_LDA(At, 1, 0); PG8_STAGE(PG8_SA(0, 1), a2 + hstep, voffA);
;             PG8_WAIT_V(8); PG8_WAIT_L(0); PG8_BAR; PG8_MMA(0, 0, At, B0); PG8_MMA(0, 1, At, B1); PG8_BAR; PG8_SCHED;
;             PG8_LDA(At, 1, 1); PG8_STAGE(PG8_SB(1, 0), b3, voffB); PG8_STAGE(PG8_SB(1, 1), b3 + hstepB, voffB); PG8_STAGE(PG8_SA(1, 0), a3, voffA);
;             PG8_WAIT_V(8); PG8_WAIT_L(0); PG8_BAR; PG8_MMA(1, 0, At, B0); PG8_MMA(1, 1, At, B1); PG8_BAR; PG8_SCHED;
	s_add_i32 s35, s35, s27
	v_lshl_add_u64 v[182:183], v[182:183], 0, s[4:5]
	s_mov_b32 m0, s35
	ds_read_b128 v[210:213], v204 offset:49152
	ds_read_b128 v[214:217], v204 offset:50176
	ds_read_b128 v[218:221], v204 offset:51200
	ds_read_b128 v[222:225], v204 offset:52224
	ds_read_b128 v[226:229], v204 offset:53248
	ds_read_b128 v[230:233], v204 offset:54272
	ds_read_b128 v[234:237], v204 offset:55296
	ds_read_b128 v[238:241], v204 offset:56320
	global_load_lds_dwordx4 v[182:183], off
	s_add_i32 m0, s35, 0x2000
	s_add_u32 s22, s22, 0x20080
	v_lshl_add_u64 v[182:183], v[242:243], 0, s[4:5]
	s_addc_u32 s23, s23, 0
	s_add_i32 s35, s46, s27
	global_load_lds_dwordx4 v[182:183], off
	v_lshl_add_u64 v[182:183], s[22:23], 0, v[164:165]
	s_mov_b32 m0, s35
	s_nop 0
	global_load_lds_dwordx4 v[182:183], off
	v_lshl_add_u64 v[182:183], s[22:23], 0, v[168:169]
	s_add_i32 m0, s35, 0x2000
	s_nop 0
	global_load_lds_dwordx4 v[182:183], off
	v_lshl_add_u64 v[182:183], v[244:245], 0, s[4:5]
	s_mov_b32 m0, s53
	s_nop 0
	global_load_lds_dwordx4 v[182:183], off
	v_lshl_add_u64 v[182:183], v[246:247], 0, s[4:5]
	s_mov_b32 m0, s54
	s_nop 0
	global_load_lds_dwordx4 v[182:183], off
	s_waitcnt vmcnt(8)
	s_waitcnt lgkmcnt(0)
	s_barrier
	s_setprio 1
	s_waitcnt lgkmcnt(0)
	v_mfma_f32_16x16x32_bf16 v[78:81], v[50:53], v[210:213], v[78:81]
	v_mfma_f32_16x16x32_bf16 v[74:77], v[66:69], v[210:213], v[74:77]
	v_mfma_f32_16x16x32_bf16 v[62:65], v[50:53], v[218:221], v[62:65]
	v_mfma_f32_16x16x32_bf16 v[58:61], v[66:69], v[218:221], v[58:61]
	v_mfma_f32_16x16x32_bf16 v[30:33], v[50:53], v[226:229], v[30:33]
	v_mfma_f32_16x16x32_bf16 v[26:29], v[66:69], v[226:229], v[26:29]
	v_mfma_f32_16x16x32_bf16 v[14:17], v[50:53], v[234:237], v[14:17]
	v_mfma_f32_16x16x32_bf16 v[10:13], v[66:69], v[234:237], v[10:13]
	v_mfma_f32_16x16x32_bf16 v[78:81], v[54:57], v[214:217], v[78:81]
	v_mfma_f32_16x16x32_bf16 v[74:77], v[70:73], v[214:217], v[74:77]
	v_mfma_f32_16x16x32_bf16 v[62:65], v[54:57], v[222:225], v[62:65]
	v_mfma_f32_16x16x32_bf16 v[58:61], v[70:73], v[222:225], v[58:61]
	v_mfma_f32_16x16x32_bf16 v[30:33], v[54:57], v[230:233], v[30:33]
	v_mfma_f32_16x16x32_bf16 v[26:29], v[70:73], v[230:233], v[26:29]
	v_mfma_f32_16x16x32_bf16 v[14:17], v[54:57], v[238:241], v[14:17]
	v_mfma_f32_16x16x32_bf16 v[10:13], v[70:73], v[238:241], v[10:13]
	v_mfma_f32_16x16x32_bf16 v[34:37], v[98:101], v[210:213], v[34:37]
	v_mfma_f32_16x16x32_bf16 v[70:73], v[102:105], v[214:217], v[34:37]
	v_mfma_f32_16x16x32_bf16 v[34:37], v[106:109], v[210:213], v[38:41]
	v_mfma_f32_16x16x32_bf16 v[66:69], v[110:113], v[214:217], v[34:37]
	v_mfma_f32_16x16x32_bf16 v[34:37], v[98:101], v[218:221], v[42:45]
	v_mfma_f32_16x16x32_bf16 v[54:57], v[102:105], v[222:225], v[34:37]
	v_mfma_f32_16x16x32_bf16 v[34:37], v[106:109], v[218:221], v[46:49]
	v_mfma_f32_16x16x32_bf16 v[22:25], v[98:101], v[226:229], v[22:25]
	v_mfma_f32_16x16x32_bf16 v[18:21], v[106:109], v[226:229], v[18:21]
	v_mfma_f32_16x16x32_bf16 v[6:9], v[98:101], v[234:237], v[6:9]
	v_mfma_f32_16x16x32_bf16 v[2:5], v[106:109], v[234:237], v[2:5]
	v_mfma_f32_16x16x32_bf16 v[50:53], v[110:113], v[222:225], v[34:37]
	v_mfma_f32_16x16x32_bf16 v[22:25], v[102:105], v[230:233], v[22:25]
	v_mfma_f32_16x16x32_bf16 v[18:21], v[110:113], v[230:233], v[18:21]
	v_mfma_f32_16x16x32_bf16 v[6:9], v[102:105], v[238:241], v[6:9]
	v_mfma_f32_16x16x32_bf16 v[2:5], v[110:113], v[238:241], v[2:5]
	s_setprio 0
	s_barrier
	s_add_i32 s34, s34, 2
	s_add_u32 s24, s24, 0x100
	s_addc_u32 s25, s25, 0
	s_add_u32 s20, s20, 0x100
	s_addc_u32 s21, s21, 0
	s_cmp_lt_u32 s34, 30
.LBB0_2143:
	ds_read_b128 v[34:37], v202
	ds_read_b128 v[38:41], v202 offset:1024
	ds_read_b128 v[42:45], v202 offset:2048
	ds_read_b128 v[46:49], v202 offset:3072
	ds_read_b128 v[98:101], v203
	ds_read_b128 v[102:105], v203 offset:1024
	ds_read_b128 v[106:109], v203 offset:2048
	ds_read_b128 v[110:113], v203 offset:3072
	s_add_u32 s22, s20, 0xfff80080
	s_addc_u32 s23, s21, -1
	s_cmp_eq_u32 s34, 28
	s_cselect_b32 s37, s3, s23
	s_cselect_b32 s36, s13, s22
	s_cselect_b32 s23, s11, s25
	s_cselect_b32 s22, s19, s24
	v_lshl_add_u64 v[182:183], s[20:21], 0, v[174:175]
	s_add_i32 m0, s28, 0xc000
	ds_read_b128 v[210:213], v204
	ds_read_b128 v[214:217], v204 offset:1024
	ds_read_b128 v[218:221], v204 offset:2048
	ds_read_b128 v[222:225], v204 offset:3072
	ds_read_b128 v[226:229], v204 offset:4096
	ds_read_b128 v[230:233], v204 offset:5120
	ds_read_b128 v[234:237], v204 offset:6144
	ds_read_b128 v[238:241], v204 offset:7168
	global_load_lds_dwordx4 v[182:183], off
	v_lshl_add_u64 v[182:183], s[20:21], 0, v[172:173]
	s_add_i32 m0, s28, 0xe000
	s_nop 0
	global_load_lds_dwordx4 v[182:183], off
	s_waitcnt vmcnt(8)
	s_waitcnt lgkmcnt(0)
	s_barrier
; #define PG8_STAGE(bufoff, gbase, voff) do { _Pragma("unroll") for (int _i = 0; _i < 2; ++_i) \
;         __builtin_amdgcn_global_load_lds((const unsigned*)((const char*)(gbase) + (voff)[_i]), (LAS unsigned*)(lds + (bufoff) + ldsw + _i * 8192), 16, 0, 0); } while (0)
; #define PG8_LDA(dst, b, h) do { _Pragma("unroll") for (int m = 0; m < 4; ++m) _Pragma("unroll") for (int k = 0; k < 2; ++k) dst[m][k] = *(const LAS bf16x8*)(lds + PG8_SA(b, h) + aoff + m * 2048 + k * 1024); } while (0)
; #define PG8_MMA(ai, bj, At, Bt) do { __builtin_amdgcn_s_setprio(1); _Pragma("unroll") for (int m = 0; m < 4; ++m) _Pragma("unroll") for (int n = 0; n < 2; ++n) _Pragma("unroll") for (int k = 0; k < 2; ++k) \
;         acc[ai][bj][m][n] = __builtin_amdgcn_mfma_f32_16x16x32_bf16(Bt[n][k], At[m][k], acc[ai][bj][m][n], 0, 0, 0); __builtin_amdgcn_s_setprio(0); } while (0)
; #define PG8_WAIT_V(n) asm volatile("s_waitcnt vmcnt(" #n ")" ::: "memory")
; #define PG8_WAIT_L(n) asm volatile("s_waitcnt lgkmcnt(" #n ")" ::: "memory")
; #define PG8_BAR __builtin_amdgcn_s_barrier()
; #define PG8_SCHED __builtin_amdgcn_sched_barrier(0)
; template <class Epi, class Sched, bool ALIGN_EPI = false, bool SP2 = false>
; __device__ __forceinline__ void gemm_phase(LAS unsigned char* lds, const Gemm g, const Sched& S, const Epi& E) {
;     ...
;             PG8_WAIT_V(8); PG8_WAIT_L(0); PG8_BAR; PG8_MMA(0, 0, At, B0); PG8_MMA(0, 1, At, B1); PG8_BAR; PG8_SCHED;
;             PG8_LDA(At, 0, 1); PG8_STAGE(PG8_SB(0, 0), b2, voffB); PG8_STAGE(PG8_SB(0, 1), b2 + hstepB, voffB); PG8_STAGE(PG8_SA(0, 0), a2, voffA);
;             PG8_WAIT_V(8); PG8_WAIT_L(0); PG8_BAR; PG8_MMA(1, 0, At, B0); PG8_MMA(1, 1, At, B1); PG8_BAR; PG8_SCHED;
	s_setprio 1
	s_waitcnt lgkmcnt(0)
	v_mfma_f32_16x16x32_bf16 v[158:161], v[34:37], v[210:213], v[158:161]
	v_mfma_f32_16x16x32_bf16 v[154:157], v[42:45], v[210:213], v[154:157]
	v_mfma_f32_16x16x32_bf16 v[142:145], v[34:37], v[218:221], v[142:145]
	v_mfma_f32_16x16x32_bf16 v[138:141], v[42:45], v[218:221], v[138:141]
	v_mfma_f32_16x16x32_bf16 v[126:129], v[34:37], v[226:229], v[126:129]
	v_mfma_f32_16x16x32_bf16 v[122:125], v[42:45], v[226:229], v[122:125]
	v_mfma_f32_16x16x32_bf16 v[94:97], v[34:37], v[234:237], v[94:97]
	v_mfma_f32_16x16x32_bf16 v[90:93], v[42:45], v[234:237], v[90:93]
	v_mfma_f32_16x16x32_bf16 v[158:161], v[38:41], v[214:217], v[158:161]
	v_mfma_f32_16x16x32_bf16 v[154:157], v[46:49], v[214:217], v[154:157]
	v_mfma_f32_16x16x32_bf16 v[142:145], v[38:41], v[222:225], v[142:145]
	v_mfma_f32_16x16x32_bf16 v[138:141], v[46:49], v[222:225], v[138:141]
	v_mfma_f32_16x16x32_bf16 v[126:129], v[38:41], v[230:233], v[126:129]
	v_mfma_f32_16x16x32_bf16 v[122:125], v[46:49], v[230:233], v[122:125]
	v_mfma_f32_16x16x32_bf16 v[94:97], v[38:41], v[238:241], v[94:97]
	v_mfma_f32_16x16x32_bf16 v[90:93], v[46:49], v[238:241], v[90:93]
	v_mfma_f32_16x16x32_bf16 v[150:153], v[98:101], v[210:213], v[150:153]
	v_mfma_f32_16x16x32_bf16 v[146:149], v[106:109], v[210:213], v[146:149]
	v_mfma_f32_16x16x32_bf16 v[134:137], v[98:101], v[218:221], v[134:137]
	v_mfma_f32_16x16x32_bf16 v[130:133], v[106:109], v[218:221], v[130:133]
	v_mfma_f32_16x16x32_bf16 v[118:121], v[98:101], v[226:229], v[118:121]
	v_mfma_f32_16x16x32_bf16 v[114:117], v[106:109], v[226:229], v[114:117]
	v_mfma_f32_16x16x32_bf16 v[86:89], v[98:101], v[234:237], v[86:89]
	v_mfma_f32_16x16x32_bf16 v[82:85], v[106:109], v[234:237], v[82:85]
	v_mfma_f32_16x16x32_bf16 v[150:153], v[102:105], v[214:217], v[150:153]
	v_mfma_f32_16x16x32_bf16 v[146:149], v[110:113], v[214:217], v[146:149]
	v_mfma_f32_16x16x32_bf16 v[134:137], v[102:105], v[222:225], v[134:137]
	v_mfma_f32_16x16x32_bf16 v[130:133], v[110:113], v[222:225], v[130:133]
	v_mfma_f32_16x16x32_bf16 v[118:121], v[102:105], v[230:233], v[118:121]
	v_mfma_f32_16x16x32_bf16 v[114:117], v[110:113], v[230:233], v[114:117]
	v_mfma_f32_16x16x32_bf16 v[86:89], v[102:105], v[238:241], v[86:89]
	v_mfma_f32_16x16x32_bf16 v[82:85], v[110:113], v[238:241], v[82:85]
	s_setprio 0
	s_barrier
	s_add_i32 s35, s56, s27
	v_lshl_add_u64 v[182:183], s[22:23], 0, v[164:165]
	s_mov_b32 m0, s35
	ds_read_b128 v[210:213], v204 offset:16384
	ds_read_b128 v[214:217], v204 offset:17408
	ds_read_b128 v[218:221], v204 offset:18432
	ds_read_b128 v[222:225], v204 offset:19456
	ds_read_b128 v[226:229], v204 offset:20480
	ds_read_b128 v[230:233], v204 offset:21504
	ds_read_b128 v[234:237], v204 offset:22528
	ds_read_b128 v[238:241], v204 offset:23552
	global_load_lds_dwordx4 v[182:183], off
	s_add_i32 m0, s35, 0x2000
	s_add_u32 s46, s22, 0x20000
	v_lshl_add_u64 v[242:243], s[22:23], 0, v[168:169]
	s_addc_u32 s47, s23, 0
	s_add_i32 s35, s57, s27
	global_load_lds_dwordx4 v[242:243], off
	v_lshl_add_u64 v[244:245], s[46:47], 0, v[164:165]
	s_mov_b32 m0, s35
	v_lshl_add_u64 v[246:247], s[36:37], 0, v[166:167]
	global_load_lds_dwordx4 v[244:245], off
	v_lshl_add_u64 v[244:245], s[46:47], 0, v[168:169]
	s_add_i32 m0, s35, 0x2000
	s_nop 0
	global_load_lds_dwordx4 v[244:245], off
	v_lshl_add_u64 v[244:245], s[36:37], 0, v[162:163]
	s_mov_b32 m0, s28
	s_nop 0
	global_load_lds_dwordx4 v[244:245], off
	s_mov_b32 m0, s29
	s_nop 0
	global_load_lds_dwordx4 v[246:247], off
	s_waitcnt vmcnt(8)
	s_waitcnt lgkmcnt(0)
	s_barrier
	s_setprio 1
	s_waitcnt lgkmcnt(0)
	v_mfma_f32_16x16x32_bf16 v[78:81], v[34:37], v[210:213], v[78:81]
	v_mfma_f32_16x16x32_bf16 v[74:77], v[42:45], v[210:213], v[74:77]
	v_mfma_f32_16x16x32_bf16 v[62:65], v[34:37], v[218:221], v[62:65]
	v_mfma_f32_16x16x32_bf16 v[58:61], v[42:45], v[218:221], v[58:61]
	v_mfma_f32_16x16x32_bf16 v[30:33], v[34:37], v[226:229], v[30:33]
	v_mfma_f32_16x16x32_bf16 v[26:29], v[42:45], v[226:229], v[26:29]
	v_mfma_f32_16x16x32_bf16 v[14:17], v[34:37], v[234:237], v[14:17]
	v_mfma_f32_16x16x32_bf16 v[10:13], v[42:45], v[234:237], v[10:13]
	v_mfma_f32_16x16x32_bf16 v[78:81], v[38:41], v[214:217], v[78:81]
	v_mfma_f32_16x16x32_bf16 v[74:77], v[46:49], v[214:217], v[74:77]
	v_mfma_f32_16x16x32_bf16 v[62:65], v[38:41], v[222:225], v[62:65]
	v_mfma_f32_16x16x32_bf16 v[58:61], v[46:49], v[222:225], v[58:61]
	v_mfma_f32_16x16x32_bf16 v[30:33], v[38:41], v[230:233], v[30:33]
	v_mfma_f32_16x16x32_bf16 v[26:29], v[46:49], v[230:233], v[26:29]
	v_mfma_f32_16x16x32_bf16 v[14:17], v[38:41], v[238:241], v[14:17]
	v_mfma_f32_16x16x32_bf16 v[10:13], v[46:49], v[238:241], v[10:13]
	v_mfma_f32_16x16x32_bf16 v[22:25], v[98:101], v[226:229], v[22:25]
	v_mfma_f32_16x16x32_bf16 v[18:21], v[106:109], v[226:229], v[18:21]
	v_mfma_f32_16x16x32_bf16 v[6:9], v[98:101], v[234:237], v[6:9]
	v_mfma_f32_16x16x32_bf16 v[2:5], v[106:109], v[234:237], v[2:5]
	v_mfma_f32_16x16x32_bf16 v[34:37], v[98:101], v[210:213], v[70:73]
	v_mfma_f32_16x16x32_bf16 v[38:41], v[106:109], v[210:213], v[66:69]
	v_mfma_f32_16x16x32_bf16 v[42:45], v[98:101], v[218:221], v[54:57]
	v_mfma_f32_16x16x32_bf16 v[46:49], v[106:109], v[218:221], v[50:53]
	v_mfma_f32_16x16x32_bf16 v[22:25], v[102:105], v[230:233], v[22:25]
	v_mfma_f32_16x16x32_bf16 v[18:21], v[110:113], v[230:233], v[18:21]
	v_mfma_f32_16x16x32_bf16 v[6:9], v[102:105], v[238:241], v[6:9]
	v_mfma_f32_16x16x32_bf16 v[2:5], v[110:113], v[238:241], v[2:5]
	v_mfma_f32_16x16x32_bf16 v[34:37], v[102:105], v[214:217], v[34:37]
	v_mfma_f32_16x16x32_bf16 v[38:41], v[110:113], v[214:217], v[38:41]
	v_mfma_f32_16x16x32_bf16 v[42:45], v[102:105], v[222:225], v[42:45]
	v_mfma_f32_16x16x32_bf16 v[46:49], v[110:113], v[222:225], v[46:49]
	s_setprio 0
	s_barrier
; #define PG8_STAGE(bufoff, gbase, voff) do { _Pragma("unroll") for (int _i = 0; _i < 2; ++_i) \
;         __builtin_amdgcn_global_load_lds((const unsigned*)((const char*)(gbase) + (voff)[_i]), (LAS unsigned*)(lds + (bufoff) + ldsw + _i * 8192), 16, 0, 0); } while (0)
; #define PG8_LDA(dst, b, h) do { _Pragma("unroll") for (int m = 0; m < 4; ++m) _Pragma("unroll") for (int k = 0; k < 2; ++k) dst[m][k] = *(const LAS bf16x8*)(lds + PG8_SA(b, h) + aoff + m * 2048 + k * 1024); } while (0)
; #define PG8_LDB(dst, b, h) do { _Pragma("unroll") for (int n = 0; n < 2; ++n) _Pragma("unroll") for (int k = 0; k < 2; ++k) dst[n][k] = *(const LAS bf16x8*)(lds + PG8_SB(b, h) + boff + n * 2048 + k * 1024); } while (0)
; #define PG8_MMA(ai, bj, At, Bt) do { __builtin_amdgcn_s_setprio(1); _Pragma("unroll") for (int m = 0; m < 4; ++m) _Pragma("unroll") for (int n = 0; n < 2; ++n) _Pragma("unroll") for (int k = 0; k < 2; ++k) \
;         acc[ai][bj][m][n] = __builtin_amdgcn_mfma_f32_16x16x32_bf16(Bt[n][k], At[m][k], acc[ai][bj][m][n], 0, 0, 0); __builtin_amdgcn_s_setprio(0); } while (0)
; #define PG8_WAIT_V(n) asm volatile("s_waitcnt vmcnt(" #n ")" ::: "memory")
; #define PG8_WAIT_L(n) asm volatile("s_waitcnt lgkmcnt(" #n ")" ::: "memory")
; #define PG8_BAR __builtin_amdgcn_s_barrier()
; #define PG8_SCHED __builtin_amdgcn_sched_barrier(0)
; template <class Epi, class Sched, bool ALIGN_EPI = false, bool SP2 = false>
; __device__ __forceinline__ void gemm_phase(LAS unsigned char* lds, const Gemm g, const Sched& S, const Epi& E) {
;     ...
;             PG8_LDB(B0, 1, 0); PG8_LDB(B1, 1, 1); PG8_SCHED; PG8_LDA(At, 1, 0); PG8_STAGE(PG8_SA(0, 1), a2 + hstep, voffA);
;             PG8_WAIT_V(8); PG8_WAIT_L(0); PG8_BAR; PG8_MMA(0, 0, At, B0); PG8_MMA(0, 1, At, B1); PG8_BAR; PG8_SCHED;
	s_add_i32 s35, 0, 0x18000
	s_add_i32 s46, 0, 0x1c000
	v_add_u32_e32 v70, s35, v185
	v_add_u32_e32 v110, s46, v185
	ds_read_b128 v[50:53], v70
	ds_read_b128 v[54:57], v70 offset:1024
	ds_read_b128 v[66:69], v70 offset:2048
	ds_read_b128 v[70:73], v70 offset:3072
	ds_read_b128 v[98:101], v110
	ds_read_b128 v[102:105], v110 offset:1024
	ds_read_b128 v[106:109], v110 offset:2048
	ds_read_b128 v[110:113], v110 offset:3072
	s_add_u32 s36, s36, 0x80000
	s_addc_u32 s37, s37, 0
	s_mov_b32 m0, s30
	v_lshl_add_u64 v[248:249], s[36:37], 0, v[162:163]
	ds_read_b128 v[210:213], v204 offset:32768
	ds_read_b128 v[214:217], v204 offset:33792
	ds_read_b128 v[218:221], v204 offset:34816
	ds_read_b128 v[222:225], v204 offset:35840
	ds_read_b128 v[226:229], v204 offset:36864
	ds_read_b128 v[230:233], v204 offset:37888
	ds_read_b128 v[234:237], v204 offset:38912
	ds_read_b128 v[238:241], v204 offset:39936
	global_load_lds_dwordx4 v[248:249], off
	v_lshl_add_u64 v[248:249], s[36:37], 0, v[166:167]
	s_mov_b32 m0, s31
	s_nop 0
	global_load_lds_dwordx4 v[248:249], off
	s_waitcnt vmcnt(8)
	s_waitcnt lgkmcnt(0)
	s_barrier
	s_setprio 1
	s_waitcnt lgkmcnt(0)
	v_mfma_f32_16x16x32_bf16 v[158:161], v[50:53], v[210:213], v[158:161]
	v_mfma_f32_16x16x32_bf16 v[154:157], v[66:69], v[210:213], v[154:157]
	v_mfma_f32_16x16x32_bf16 v[142:145], v[50:53], v[218:221], v[142:145]
	v_mfma_f32_16x16x32_bf16 v[138:141], v[66:69], v[218:221], v[138:141]
	v_mfma_f32_16x16x32_bf16 v[126:129], v[50:53], v[226:229], v[126:129]
	v_mfma_f32_16x16x32_bf16 v[122:125], v[66:69], v[226:229], v[122:125]
	v_mfma_f32_16x16x32_bf16 v[94:97], v[50:53], v[234:237], v[94:97]
	v_mfma_f32_16x16x32_bf16 v[90:93], v[66:69], v[234:237], v[90:93]
	v_mfma_f32_16x16x32_bf16 v[158:161], v[54:57], v[214:217], v[158:161]
	v_mfma_f32_16x16x32_bf16 v[154:157], v[70:73], v[214:217], v[154:157]
	v_mfma_f32_16x16x32_bf16 v[142:145], v[54:57], v[222:225], v[142:145]
	v_mfma_f32_16x16x32_bf16 v[138:141], v[70:73], v[222:225], v[138:141]
	v_mfma_f32_16x16x32_bf16 v[126:129], v[54:57], v[230:233], v[126:129]
	v_mfma_f32_16x16x32_bf16 v[122:125], v[70:73], v[230:233], v[122:125]
	v_mfma_f32_16x16x32_bf16 v[94:97], v[54:57], v[238:241], v[94:97]
	v_mfma_f32_16x16x32_bf16 v[90:93], v[70:73], v[238:241], v[90:93]
	v_mfma_f32_16x16x32_bf16 v[150:153], v[98:101], v[210:213], v[150:153]
	v_mfma_f32_16x16x32_bf16 v[146:149], v[106:109], v[210:213], v[146:149]
	v_mfma_f32_16x16x32_bf16 v[134:137], v[98:101], v[218:221], v[134:137]
	v_mfma_f32_16x16x32_bf16 v[130:133], v[106:109], v[218:221], v[130:133]
	v_mfma_f32_16x16x32_bf16 v[118:121], v[98:101], v[226:229], v[118:121]
	v_mfma_f32_16x16x32_bf16 v[114:117], v[106:109], v[226:229], v[114:117]
	v_mfma_f32_16x16x32_bf16 v[86:89], v[98:101], v[234:237], v[86:89]
	v_mfma_f32_16x16x32_bf16 v[82:85], v[106:109], v[234:237], v[82:85]
	v_mfma_f32_16x16x32_bf16 v[150:153], v[102:105], v[214:217], v[150:153]
	v_mfma_f32_16x16x32_bf16 v[146:149], v[110:113], v[214:217], v[146:149]
	v_mfma_f32_16x16x32_bf16 v[134:137], v[102:105], v[222:225], v[134:137]
	v_mfma_f32_16x16x32_bf16 v[130:133], v[110:113], v[222:225], v[130:133]
	v_mfma_f32_16x16x32_bf16 v[118:121], v[102:105], v[230:233], v[118:121]
	v_mfma_f32_16x16x32_bf16 v[114:117], v[110:113], v[230:233], v[114:117]
	v_mfma_f32_16x16x32_bf16 v[86:89], v[102:105], v[238:241], v[86:89]
	v_mfma_f32_16x16x32_bf16 v[82:85], v[110:113], v[238:241], v[82:85]
	s_setprio 0
	s_barrier
; #define PG8_STAGE(bufoff, gbase, voff) do { _Pragma("unroll") for (int _i = 0; _i < 2; ++_i) \
;         __builtin_amdgcn_global_load_lds((const unsigned*)((const char*)(gbase) + (voff)[_i]), (LAS unsigned*)(lds + (bufoff) + ldsw + _i * 8192), 16, 0, 0); } while (0)
; #define PG8_LDA(dst, b, h) do { _Pragma("unroll") for (int m = 0; m < 4; ++m) _Pragma("unroll") for (int k = 0; k < 2; ++k) dst[m][k] = *(const LAS bf16x8*)(lds + PG8_SA(b, h) + aoff + m * 2048 + k * 1024); } while (0)
; #define PG8_MMA(ai, bj, At, Bt) do { __builtin_amdgcn_s_setprio(1); _Pragma("unroll") for (int m = 0; m < 4; ++m) _Pragma("unroll") for (int n = 0; n < 2; ++n) _Pragma("unroll") for (int k = 0; k < 2; ++k) \
;         acc[ai][bj][m][n] = __builtin_amdgcn_mfma_f32_16x16x32_bf16(Bt[n][k], At[m][k], acc[ai][bj][m][n], 0, 0, 0); __builtin_amdgcn_s_setprio(0); } while (0)
; #define PG8_WAIT_V(n) asm volatile("s_waitcnt vmcnt(" #n ")" ::: "memory")
; #define PG8_WAIT_L(n) asm volatile("s_waitcnt lgkmcnt(" #n ")" ::: "memory")
; #define PG8_BAR __builtin_amdgcn_s_barrier()
; #define PG8_SCHED __builtin_amdgcn_sched_barrier(0)
; template <class Epi, class Sched, bool ALIGN_EPI = false, bool SP2 = false>
; __device__ __forceinline__ void gemm_phase(LAS unsigned char* lds, const Gemm g, const Sched& S, const Epi& E) {
;     ...
;             PG8_LDA(At, 1, 1); PG8_STAGE(PG8_SB(1, 0), b3, voffB); PG8_STAGE(PG8_SB(1, 1), b3 + hstepB, voffB); PG8_STAGE(PG8_SA(1, 0), a3, voffA);
;             PG8_WAIT_V(8); PG8_WAIT_L(0); PG8_BAR; PG8_MMA(1, 0, At, B0); PG8_MMA(1, 1, At, B1); PG8_BAR; PG8_SCHED;
;     ...
;         if constexpr (ALIGN_EPI) { if (wr == 0) PG8_BAR; }
	s_add_i32 s35, s35, s27
	v_lshl_add_u64 v[182:183], v[182:183], 0, s[4:5]
	s_mov_b32 m0, s35
	ds_read_b128 v[210:213], v204 offset:49152
	ds_read_b128 v[214:217], v204 offset:50176
	ds_read_b128 v[218:221], v204 offset:51200
	ds_read_b128 v[222:225], v204 offset:52224
	ds_read_b128 v[226:229], v204 offset:53248
	ds_read_b128 v[230:233], v204 offset:54272
	ds_read_b128 v[234:237], v204 offset:55296
	ds_read_b128 v[238:241], v204 offset:56320
	global_load_lds_dwordx4 v[182:183], off
	s_add_i32 m0, s35, 0x2000
	s_add_u32 s22, s22, 0x20080
	v_lshl_add_u64 v[182:183], v[242:243], 0, s[4:5]
	s_addc_u32 s23, s23, 0
	s_add_i32 s35, s46, s27
	global_load_lds_dwordx4 v[182:183], off
	v_lshl_add_u64 v[182:183], s[22:23], 0, v[164:165]
	s_mov_b32 m0, s35
	s_nop 0
	global_load_lds_dwordx4 v[182:183], off
	v_lshl_add_u64 v[182:183], s[22:23], 0, v[168:169]
	s_add_i32 m0, s35, 0x2000
	s_nop 0
	global_load_lds_dwordx4 v[182:183], off
	v_lshl_add_u64 v[182:183], v[244:245], 0, s[4:5]
	s_mov_b32 m0, s53
	s_nop 0
	global_load_lds_dwordx4 v[182:183], off
	v_lshl_add_u64 v[182:183], v[246:247], 0, s[4:5]
	s_mov_b32 m0, s54
	s_nop 0
	global_load_lds_dwordx4 v[182:183], off
	s_waitcnt vmcnt(8)
	s_waitcnt lgkmcnt(0)
	s_barrier
	s_setprio 1
	s_waitcnt lgkmcnt(0)
	v_mfma_f32_16x16x32_bf16 v[78:81], v[50:53], v[210:213], v[78:81]
	v_mfma_f32_16x16x32_bf16 v[74:77], v[66:69], v[210:213], v[74:77]
	v_mfma_f32_16x16x32_bf16 v[62:65], v[50:53], v[218:221], v[62:65]
	v_mfma_f32_16x16x32_bf16 v[58:61], v[66:69], v[218:221], v[58:61]
	v_mfma_f32_16x16x32_bf16 v[30:33], v[50:53], v[226:229], v[30:33]
	v_mfma_f32_16x16x32_bf16 v[26:29], v[66:69], v[226:229], v[26:29]
	v_mfma_f32_16x16x32_bf16 v[14:17], v[50:53], v[234:237], v[14:17]
	v_mfma_f32_16x16x32_bf16 v[10:13], v[66:69], v[234:237], v[10:13]
	v_mfma_f32_16x16x32_bf16 v[78:81], v[54:57], v[214:217], v[78:81]
	v_mfma_f32_16x16x32_bf16 v[74:77], v[70:73], v[214:217], v[74:77]
	v_mfma_f32_16x16x32_bf16 v[62:65], v[54:57], v[222:225], v[62:65]
	v_mfma_f32_16x16x32_bf16 v[58:61], v[70:73], v[222:225], v[58:61]
	v_mfma_f32_16x16x32_bf16 v[30:33], v[54:57], v[230:233], v[30:33]
	v_mfma_f32_16x16x32_bf16 v[26:29], v[70:73], v[230:233], v[26:29]
	v_mfma_f32_16x16x32_bf16 v[14:17], v[54:57], v[238:241], v[14:17]
	v_mfma_f32_16x16x32_bf16 v[10:13], v[70:73], v[238:241], v[10:13]
	v_mfma_f32_16x16x32_bf16 v[34:37], v[98:101], v[210:213], v[34:37]
	v_mfma_f32_16x16x32_bf16 v[70:73], v[102:105], v[214:217], v[34:37]
	v_mfma_f32_16x16x32_bf16 v[34:37], v[106:109], v[210:213], v[38:41]
	v_mfma_f32_16x16x32_bf16 v[66:69], v[110:113], v[214:217], v[34:37]
	v_mfma_f32_16x16x32_bf16 v[34:37], v[98:101], v[218:221], v[42:45]
	v_mfma_f32_16x16x32_bf16 v[54:57], v[102:105], v[222:225], v[34:37]
	v_mfma_f32_16x16x32_bf16 v[34:37], v[106:109], v[218:221], v[46:49]
	v_mfma_f32_16x16x32_bf16 v[22:25], v[98:101], v[226:229], v[22:25]
	v_mfma_f32_16x16x32_bf16 v[18:21], v[106:109], v[226:229], v[18:21]
	v_mfma_f32_16x16x32_bf16 v[6:9], v[98:101], v[234:237], v[6:9]
	v_mfma_f32_16x16x32_bf16 v[2:5], v[106:109], v[234:237], v[2:5]
	v_mfma_f32_16x16x32_bf16 v[50:53], v[110:113], v[222:225], v[34:37]
	v_mfma_f32_16x16x32_bf16 v[22:25], v[102:105], v[230:233], v[22:25]
	v_mfma_f32_16x16x32_bf16 v[18:21], v[110:113], v[230:233], v[18:21]
	v_mfma_f32_16x16x32_bf16 v[6:9], v[102:105], v[238:241], v[6:9]
	v_mfma_f32_16x16x32_bf16 v[2:5], v[110:113], v[238:241], v[2:5]
	s_setprio 0
	s_barrier
	s_add_i32 s34, s34, 2
	s_add_u32 s24, s24, 0x100
	s_addc_u32 s25, s25, 0
	s_add_u32 s20, s20, 0x100
	s_addc_u32 s21, s21, 0
	s_cmp_lt_u32 s34, 30
	s_cbranch_scc1 .LBB0_2143
	s_andn2_b64 vcc, exec, s[8:9]
	s_cbranch_vccnz .LBB0_2146
	s_barrier

;     __device__ bool next(int i, Unit& u) const { if (i != 0 || c >= 128) return false; const int t = c >> 2; u.pm = t & 3; u.pn = t >> 2; u.koff = koff_bytes; u.q = c & 3; return true; }
; #define PG8_STAGE(bufoff, gbase, voff) do { _Pragma("unroll") for (int _i = 0; _i < 2; ++_i) \
;         __builtin_amdgcn_global_load_lds((const unsigned*)((const char*)(gbase) + (voff)[_i]), (LAS unsigned*)(lds + (bufoff) + ldsw + _i * 8192), 16, 0, 0); } while (0)
; #define PG8_LDA(dst, b, h) do { _Pragma("unroll") for (int m = 0; m < 4; ++m) _Pragma("unroll") for (int k = 0; k < 2; ++k) dst[m][k] = *(const LAS bf16x8*)(lds + PG8_SA(b, h) + aoff + m * 2048 + k * 1024); } while (0)
; #define PG8_LDB(dst, b, h) do { _Pragma("unroll") for (int n = 0; n < 2; ++n) _Pragma("unroll") for (int k = 0; k < 2; ++k) dst[n][k] = *(const LAS bf16x8*)(lds + PG8_SB(b, h) + boff + n * 2048 + k * 1024); } while (0)
; #define PG8_WAIT_V(n) asm volatile("s_waitcnt vmcnt(" #n ")" ::: "memory")
; template <class Epi, class Sched, bool ALIGN_EPI = false, bool SP2 = false>
; __device__ __forceinline__ void gemm_phase(LAS unsigned char* lds, const Gemm g, const Sched& S, const Epi& E) {
;     ...
;         const bool has_next = S.next(ui + 1, nxt);
;         const char* nA = has_next ? (const char*)g.A + (size_t)nxt.pm * tstep + nxt.koff : cA; const char* nB = has_next ? (const char*)g.Bt + (size_t)nxt.pn * tstep + nxt.koff : cB;
;         for (int t = 0; t < nt; t += 2) {
;             const bool last = (t == nt - 2);
;             const char* a1 = cA + (size_t)(t + 1) * kstep;
;             const char* a2 = last ? nA : cA + (size_t)(t + 2) * kstep; const char* b2 = last ? nB : cB + (size_t)(t + 2) * kstep;
;             const char* a3 = a2 + kstep; const char* b3 = b2 + kstep;
;             if (last && has_next) S.a_ready(nxt);
;             if constexpr (SP2) {
;             PG8_LDB(B0, 0, 0); PG8_LDB(B1, 0, 1); PG8_SCHED; PG8_LDA(At, 0, 0); PG8_STAGE(PG8_SA(1, 1), a1 + hstep, voffA);
;             PG8_WAIT_V(8); PG8_WAIT_L(0); PG8_BAR; PG8_MMA(0, 0, At, B0); PG8_MMA(0, 1, At, B1); PG8_BAR; PG8_SCHED;
;             PG8_LDA(At, 0, 1); PG8_STAGE(PG8_SB(0, 0), b2, voffB); PG8_STAGE(PG8_SB(0, 1), b2 + hstepB, voffB); PG8_STAGE(PG8_SA(0, 0), a2, voffA);
;             PG8_WAIT_V(8); PG8_WAIT_L(0); PG8_BAR; PG8_MMA(1, 0, At, B0); PG8_MMA(1, 1, At, B1); PG8_BAR; PG8_SCHED;
.LBB0_2765:
	s_ashr_i32 s15, s14, 31
	v_cmp_lt_i64_e64 s[42:43], s[16:17], v[170:171]
	s_lshl_b64 s[16:17], s[14:15], 20
	v_readlane_b32 s3, v252, 25
	s_add_u32 s16, s3, s16
	v_readlane_b32 s3, v252, 26
	s_addc_u32 s17, s3, s17
	s_and_b64 s[18:19], s[42:43], exec
	s_cselect_b32 s3, s17, s35
	s_cselect_b32 s15, s16, s34
	s_ashr_i32 s13, s12, 31
	s_lshl_b64 s[18:19], s[12:13], 20
	v_readlane_b32 s4, v254, 56
	v_readlane_b32 s5, v254, 57
	s_add_u32 s18, s4, s18
	s_addc_u32 s19, s5, s19
	s_and_b64 s[24:25], s[42:43], exec
	s_cselect_b32 s13, s19, s23
	s_cselect_b32 s21, s18, s22
	s_add_u32 s53, s22, 0x100
	s_addc_u32 s54, s23, 0
	s_add_u32 s22, s34, 0x80080
	s_mov_b64 s[70:71], s[58:59]
	s_addc_u32 s23, s35, 0
	s_mov_b32 s55, -2
	s_waitcnt vmcnt(0)
	ds_read_b128 v[50:53], v196
	ds_read_b128 v[54:57], v196 offset:1024
	ds_read_b128 v[138:141], v196 offset:2048
	ds_read_b128 v[142:145], v196 offset:3072
	ds_read_b128 v[146:149], v197
	ds_read_b128 v[150:153], v197 offset:1024
	ds_read_b128 v[174:177], v197 offset:2048
	ds_read_b128 v[178:181], v197 offset:3072
	s_add_u32 s24, s22, 0xfff80080
	s_addc_u32 s25, s23, -1
	s_cmp_eq_u32 s55, 28
	s_cselect_b32 s35, s3, s25
	s_cselect_b32 s34, s15, s24
	s_cselect_b32 s25, s13, s54
	s_cselect_b32 s24, s21, s53
	v_lshl_add_u64 v[190:191], s[22:23], 0, v[168:169]
	s_add_i32 m0, s28, 0xc000
	ds_read_b128 v[182:185], v198
	ds_read_b128 v[186:189], v198 offset:1024
	ds_read_b128 v[202:205], v198 offset:2048
	ds_read_b128 v[206:209], v198 offset:3072
	ds_read_b128 v[210:213], v198 offset:4096
	ds_read_b128 v[214:217], v198 offset:5120
	ds_read_b128 v[218:221], v198 offset:6144
	ds_read_b128 v[222:225], v198 offset:7168
	global_load_lds_dwordx4 v[190:191], off
	v_lshl_add_u64 v[190:191], s[22:23], 0, v[166:167]
	s_add_i32 m0, s28, 0xe000
	s_nop 0
	global_load_lds_dwordx4 v[190:191], off
	s_waitcnt lgkmcnt(0)
	s_barrier
	s_setprio 1
	s_waitcnt lgkmcnt(0)
	v_mfma_f32_16x16x32_bf16 v[134:137], v[50:53], v[182:185], 0
	v_mfma_f32_16x16x32_bf16 v[130:133], v[138:141], v[182:185], 0
	v_mfma_f32_16x16x32_bf16 v[118:121], v[50:53], v[202:205], 0
	v_mfma_f32_16x16x32_bf16 v[114:117], v[138:141], v[202:205], 0
	v_mfma_f32_16x16x32_bf16 v[102:105], v[50:53], v[210:213], 0
	v_mfma_f32_16x16x32_bf16 v[98:101], v[138:141], v[210:213], 0
	v_mfma_f32_16x16x32_bf16 v[86:89], v[50:53], v[218:221], 0
	v_mfma_f32_16x16x32_bf16 v[82:85], v[138:141], v[218:221], 0
	v_mfma_f32_16x16x32_bf16 v[134:137], v[54:57], v[186:189], v[134:137]
	v_mfma_f32_16x16x32_bf16 v[130:133], v[142:145], v[186:189], v[130:133]
	v_mfma_f32_16x16x32_bf16 v[118:121], v[54:57], v[206:209], v[118:121]
	v_mfma_f32_16x16x32_bf16 v[114:117], v[142:145], v[206:209], v[114:117]
	v_mfma_f32_16x16x32_bf16 v[102:105], v[54:57], v[214:217], v[102:105]
	v_mfma_f32_16x16x32_bf16 v[98:101], v[142:145], v[214:217], v[98:101]
	v_mfma_f32_16x16x32_bf16 v[86:89], v[54:57], v[222:225], v[86:89]
	v_mfma_f32_16x16x32_bf16 v[82:85], v[142:145], v[222:225], v[82:85]
	v_mfma_f32_16x16x32_bf16 v[126:129], v[146:149], v[182:185], 0
	v_mfma_f32_16x16x32_bf16 v[122:125], v[174:177], v[182:185], 0
	v_mfma_f32_16x16x32_bf16 v[110:113], v[146:149], v[202:205], 0
	v_mfma_f32_16x16x32_bf16 v[106:109], v[174:177], v[202:205], 0
	v_mfma_f32_16x16x32_bf16 v[94:97], v[146:149], v[210:213], 0
	v_mfma_f32_16x16x32_bf16 v[90:93], v[174:177], v[210:213], 0
	v_mfma_f32_16x16x32_bf16 v[78:81], v[146:149], v[218:221], 0
	v_mfma_f32_16x16x32_bf16 v[74:77], v[174:177], v[218:221], 0
	v_mfma_f32_16x16x32_bf16 v[126:129], v[150:153], v[186:189], v[126:129]
	v_mfma_f32_16x16x32_bf16 v[122:125], v[178:181], v[186:189], v[122:125]
	v_mfma_f32_16x16x32_bf16 v[110:113], v[150:153], v[206:209], v[110:113]
	v_mfma_f32_16x16x32_bf16 v[106:109], v[178:181], v[206:209], v[106:109]
	v_mfma_f32_16x16x32_bf16 v[94:97], v[150:153], v[214:217], v[94:97]
	v_mfma_f32_16x16x32_bf16 v[90:93], v[178:181], v[214:217], v[90:93]
	v_mfma_f32_16x16x32_bf16 v[78:81], v[150:153], v[222:225], v[78:81]
	v_mfma_f32_16x16x32_bf16 v[74:77], v[178:181], v[222:225], v[74:77]
	s_setprio 0
	s_barrier
	s_add_i32 s56, s51, s27
	v_lshl_add_u64 v[190:191], s[24:25], 0, v[156:157]
	s_mov_b32 m0, s56
	ds_read_b128 v[182:185], v198 offset:16384
	ds_read_b128 v[186:189], v198 offset:17408
	ds_read_b128 v[202:205], v198 offset:18432
	ds_read_b128 v[206:209], v198 offset:19456
	ds_read_b128 v[210:213], v198 offset:20480
	ds_read_b128 v[214:217], v198 offset:21504
	ds_read_b128 v[218:221], v198 offset:22528
	ds_read_b128 v[222:225], v198 offset:23552
	global_load_lds_dwordx4 v[190:191], off
	s_add_i32 m0, s56, 0x2000
	s_add_u32 s56, s24, 0x20000
	v_lshl_add_u64 v[226:227], s[24:25], 0, v[160:161]
	s_addc_u32 s57, s25, 0
	s_add_i32 s58, s52, s27
	global_load_lds_dwordx4 v[226:227], off
	v_lshl_add_u64 v[228:229], s[56:57], 0, v[156:157]
	s_mov_b32 m0, s58
	v_lshl_add_u64 v[230:231], s[34:35], 0, v[158:159]
	global_load_lds_dwordx4 v[228:229], off
	v_lshl_add_u64 v[228:229], s[56:57], 0, v[160:161]
	s_add_i32 m0, s58, 0x2000
	s_nop 0
	global_load_lds_dwordx4 v[228:229], off
	v_lshl_add_u64 v[228:229], s[34:35], 0, v[154:155]
	s_mov_b32 m0, s28
	s_nop 0
	global_load_lds_dwordx4 v[228:229], off
	s_mov_b32 m0, s29
	s_nop 0
	global_load_lds_dwordx4 v[230:231], off
	s_waitcnt lgkmcnt(0)
	s_barrier
; #define PG8_STAGE(bufoff, gbase, voff) do { _Pragma("unroll") for (int _i = 0; _i < 2; ++_i) \
;         __builtin_amdgcn_global_load_lds((const unsigned*)((const char*)(gbase) + (voff)[_i]), (LAS unsigned*)(lds + (bufoff) + ldsw + _i * 8192), 16, 0, 0); } while (0)
; #define PG8_LDA(dst, b, h) do { _Pragma("unroll") for (int m = 0; m < 4; ++m) _Pragma("unroll") for (int k = 0; k < 2; ++k) dst[m][k] = *(const LAS bf16x8*)(lds + PG8_SA(b, h) + aoff + m * 2048 + k * 1024); } while (0)
; #define PG8_LDB(dst, b, h) do { _Pragma("unroll") for (int n = 0; n < 2; ++n) _Pragma("unroll") for (int k = 0; k < 2; ++k) dst[n][k] = *(const LAS bf16x8*)(lds + PG8_SB(b, h) + boff + n * 2048 + k * 1024); } while (0)
; #define PG8_MMA(ai, bj, At, Bt) do { __builtin_amdgcn_s_setprio(1); _Pragma("unroll") for (int m = 0; m < 4; ++m) _Pragma("unroll") for (int n = 0; n < 2; ++n) _Pragma("unroll") for (int k = 0; k < 2; ++k) \
;         acc[ai][bj][m][n] = __builtin_amdgcn_mfma_f32_16x16x32_bf16(Bt[n][k], At[m][k], acc[ai][bj][m][n], 0, 0, 0); __builtin_amdgcn_s_setprio(0); } while (0)
; #define PG8_WAIT_V(n) asm volatile("s_waitcnt vmcnt(" #n ")" ::: "memory")
; #define PG8_WAIT_L(n) asm volatile("s_waitcnt lgkmcnt(" #n ")" ::: "memory")
; #define PG8_BAR __builtin_amdgcn_s_barrier()
; #define PG8_SCHED __builtin_amdgcn_sched_barrier(0)
; template <class Epi, class Sched, bool ALIGN_EPI = false, bool SP2 = false>
; __device__ __forceinline__ void gemm_phase(LAS unsigned char* lds, const Gemm g, const Sched& S, const Epi& E) {
;     ...
;             PG8_WAIT_V(8); PG8_WAIT_L(0); PG8_BAR; PG8_MMA(1, 0, At, B0); PG8_MMA(1, 1, At, B1); PG8_BAR; PG8_SCHED;
;             PG8_LDB(B0, 1, 0); PG8_LDB(B1, 1, 1); PG8_SCHED; PG8_LDA(At, 1, 0); PG8_STAGE(PG8_SA(0, 1), a2 + hstep, voffA);
;             PG8_WAIT_V(8); PG8_WAIT_L(0); PG8_BAR; PG8_MMA(0, 0, At, B0); PG8_MMA(0, 1, At, B1); PG8_BAR; PG8_SCHED;
	s_setprio 1
	s_waitcnt lgkmcnt(0)
	v_mfma_f32_16x16x32_bf16 v[70:73], v[50:53], v[182:185], 0
	v_mfma_f32_16x16x32_bf16 v[66:69], v[138:141], v[182:185], 0
	v_mfma_f32_16x16x32_bf16 v[46:49], v[50:53], v[202:205], 0
	v_mfma_f32_16x16x32_bf16 v[42:45], v[138:141], v[202:205], 0
	v_mfma_f32_16x16x32_bf16 v[30:33], v[50:53], v[210:213], 0
	v_mfma_f32_16x16x32_bf16 v[26:29], v[138:141], v[210:213], 0
	v_mfma_f32_16x16x32_bf16 v[14:17], v[50:53], v[218:221], 0
	v_mfma_f32_16x16x32_bf16 v[10:13], v[138:141], v[218:221], 0
	v_mfma_f32_16x16x32_bf16 v[70:73], v[54:57], v[186:189], v[70:73]
	v_mfma_f32_16x16x32_bf16 v[66:69], v[142:145], v[186:189], v[66:69]
	v_mfma_f32_16x16x32_bf16 v[46:49], v[54:57], v[206:209], v[46:49]
	v_mfma_f32_16x16x32_bf16 v[42:45], v[142:145], v[206:209], v[42:45]
	v_mfma_f32_16x16x32_bf16 v[30:33], v[54:57], v[214:217], v[30:33]
	v_mfma_f32_16x16x32_bf16 v[26:29], v[142:145], v[214:217], v[26:29]
	v_mfma_f32_16x16x32_bf16 v[14:17], v[54:57], v[222:225], v[14:17]
	v_mfma_f32_16x16x32_bf16 v[10:13], v[142:145], v[222:225], v[10:13]
	v_mfma_f32_16x16x32_bf16 v[38:41], v[146:149], v[202:205], 0
	v_mfma_f32_16x16x32_bf16 v[34:37], v[174:177], v[202:205], 0
	v_mfma_f32_16x16x32_bf16 v[22:25], v[146:149], v[210:213], 0
	v_mfma_f32_16x16x32_bf16 v[18:21], v[174:177], v[210:213], 0
	v_mfma_f32_16x16x32_bf16 v[6:9], v[146:149], v[218:221], 0
	v_mfma_f32_16x16x32_bf16 v[2:5], v[174:177], v[218:221], 0
	v_mfma_f32_16x16x32_bf16 v[50:53], v[146:149], v[182:185], 0
	v_mfma_f32_16x16x32_bf16 v[54:57], v[174:177], v[182:185], 0
	v_mfma_f32_16x16x32_bf16 v[38:41], v[150:153], v[206:209], v[38:41]
	v_mfma_f32_16x16x32_bf16 v[34:37], v[178:181], v[206:209], v[34:37]
	v_mfma_f32_16x16x32_bf16 v[22:25], v[150:153], v[214:217], v[22:25]
	v_mfma_f32_16x16x32_bf16 v[18:21], v[178:181], v[214:217], v[18:21]
	v_mfma_f32_16x16x32_bf16 v[6:9], v[150:153], v[222:225], v[6:9]
	v_mfma_f32_16x16x32_bf16 v[2:5], v[178:181], v[222:225], v[2:5]
	v_mfma_f32_16x16x32_bf16 v[50:53], v[150:153], v[186:189], v[50:53]
	v_mfma_f32_16x16x32_bf16 v[54:57], v[178:181], v[186:189], v[54:57]
	s_setprio 0
	s_barrier
	s_add_i32 s56, 0, 0x18000
	s_add_i32 s57, 0, 0x1c000
	v_add_u32_e32 v142, s56, v1
	v_add_u32_e32 v162, s57, v1
	ds_read_b128 v[58:61], v142
	ds_read_b128 v[62:65], v142 offset:1024
	ds_read_b128 v[138:141], v142 offset:2048
	ds_read_b128 v[142:145], v142 offset:3072
	ds_read_b128 v[146:149], v162
	ds_read_b128 v[150:153], v162 offset:1024
	ds_read_b128 v[174:177], v162 offset:2048
	ds_read_b128 v[178:181], v162 offset:3072
	s_add_u32 s34, s34, 0x80000
	s_addc_u32 s35, s35, 0
	s_mov_b32 m0, s30
	v_lshl_add_u64 v[232:233], s[34:35], 0, v[154:155]
	ds_read_b128 v[182:185], v198 offset:32768
	ds_read_b128 v[186:189], v198 offset:33792
	ds_read_b128 v[202:205], v198 offset:34816
	ds_read_b128 v[206:209], v198 offset:35840
	ds_read_b128 v[210:213], v198 offset:36864
	ds_read_b128 v[214:217], v198 offset:37888
	ds_read_b128 v[218:221], v198 offset:38912
	ds_read_b128 v[222:225], v198 offset:39936
	global_load_lds_dwordx4 v[232:233], off
	v_lshl_add_u64 v[232:233], s[34:35], 0, v[158:159]
	s_mov_b32 m0, s31
	s_nop 0
	global_load_lds_dwordx4 v[232:233], off
	s_waitcnt vmcnt(8)
	s_waitcnt lgkmcnt(0)
	s_barrier
	s_setprio 1
	s_waitcnt lgkmcnt(0)
	v_mfma_f32_16x16x32_bf16 v[134:137], v[58:61], v[182:185], v[134:137]
	v_mfma_f32_16x16x32_bf16 v[130:133], v[138:141], v[182:185], v[130:133]
	v_mfma_f32_16x16x32_bf16 v[118:121], v[58:61], v[202:205], v[118:121]
	v_mfma_f32_16x16x32_bf16 v[114:117], v[138:141], v[202:205], v[114:117]
	v_mfma_f32_16x16x32_bf16 v[102:105], v[58:61], v[210:213], v[102:105]
	v_mfma_f32_16x16x32_bf16 v[98:101], v[138:141], v[210:213], v[98:101]
	v_mfma_f32_16x16x32_bf16 v[86:89], v[58:61], v[218:221], v[86:89]
	v_mfma_f32_16x16x32_bf16 v[82:85], v[138:141], v[218:221], v[82:85]
	v_mfma_f32_16x16x32_bf16 v[134:137], v[62:65], v[186:189], v[134:137]
	v_mfma_f32_16x16x32_bf16 v[130:133], v[142:145], v[186:189], v[130:133]
	v_mfma_f32_16x16x32_bf16 v[118:121], v[62:65], v[206:209], v[118:121]
	v_mfma_f32_16x16x32_bf16 v[114:117], v[142:145], v[206:209], v[114:117]
	v_mfma_f32_16x16x32_bf16 v[102:105], v[62:65], v[214:217], v[102:105]
	v_mfma_f32_16x16x32_bf16 v[98:101], v[142:145], v[214:217], v[98:101]
	v_mfma_f32_16x16x32_bf16 v[86:89], v[62:65], v[222:225], v[86:89]
	v_mfma_f32_16x16x32_bf16 v[82:85], v[142:145], v[222:225], v[82:85]
	v_mfma_f32_16x16x32_bf16 v[126:129], v[146:149], v[182:185], v[126:129]
	v_mfma_f32_16x16x32_bf16 v[122:125], v[174:177], v[182:185], v[122:125]
	v_mfma_f32_16x16x32_bf16 v[110:113], v[146:149], v[202:205], v[110:113]
	v_mfma_f32_16x16x32_bf16 v[106:109], v[174:177], v[202:205], v[106:109]
	v_mfma_f32_16x16x32_bf16 v[94:97], v[146:149], v[210:213], v[94:97]
	v_mfma_f32_16x16x32_bf16 v[90:93], v[174:177], v[210:213], v[90:93]
	v_mfma_f32_16x16x32_bf16 v[78:81], v[146:149], v[218:221], v[78:81]
	v_mfma_f32_16x16x32_bf16 v[74:77], v[174:177], v[218:221], v[74:77]
	v_mfma_f32_16x16x32_bf16 v[126:129], v[150:153], v[186:189], v[126:129]
	v_mfma_f32_16x16x32_bf16 v[122:125], v[178:181], v[186:189], v[122:125]
	v_mfma_f32_16x16x32_bf16 v[110:113], v[150:153], v[206:209], v[110:113]
	v_mfma_f32_16x16x32_bf16 v[106:109], v[178:181], v[206:209], v[106:109]
	v_mfma_f32_16x16x32_bf16 v[94:97], v[150:153], v[214:217], v[94:97]
	v_mfma_f32_16x16x32_bf16 v[90:93], v[178:181], v[214:217], v[90:93]
	v_mfma_f32_16x16x32_bf16 v[78:81], v[150:153], v[222:225], v[78:81]
	v_mfma_f32_16x16x32_bf16 v[74:77], v[178:181], v[222:225], v[74:77]
	s_setprio 0
	s_barrier
; #define PG8_STAGE(bufoff, gbase, voff) do { _Pragma("unroll") for (int _i = 0; _i < 2; ++_i) \
;         __builtin_amdgcn_global_load_lds((const unsigned*)((const char*)(gbase) + (voff)[_i]), (LAS unsigned*)(lds + (bufoff) + ldsw + _i * 8192), 16, 0, 0); } while (0)
; #define PG8_LDA(dst, b, h) do { _Pragma("unroll") for (int m = 0; m < 4; ++m) _Pragma("unroll") for (int k = 0; k < 2; ++k) dst[m][k] = *(const LAS bf16x8*)(lds + PG8_SA(b, h) + aoff + m * 2048 + k * 1024); } while (0)
; #define PG8_LDB(dst, b, h) do { _Pragma("unroll") for (int n = 0; n < 2; ++n) _Pragma("unroll") for (int k = 0; k < 2; ++k) dst[n][k] = *(const LAS bf16x8*)(lds + PG8_SB(b, h) + boff + n * 2048 + k * 1024); } while (0)
; template <class Epi, class Sched, bool ALIGN_EPI = false, bool SP2 = false>
; __device__ __forceinline__ void gemm_phase(LAS unsigned char* lds, const Gemm g, const Sched& S, const Epi& E) {
;     ...
;         for (int t = 0; t < nt; t += 2) {
;             const bool last = (t == nt - 2);
;             const char* a1 = cA + (size_t)(t + 1) * kstep;
;             const char* a2 = last ? nA : cA + (size_t)(t + 2) * kstep; const char* b2 = last ? nB : cB + (size_t)(t + 2) * kstep;
;             const char* a3 = a2 + kstep; const char* b3 = b2 + kstep;
;             if (last && has_next) S.a_ready(nxt);
;             if constexpr (SP2) {
;             PG8_LDB(B0, 0, 0); PG8_LDB(B1, 0, 1); PG8_SCHED; PG8_LDA(At, 0, 0); PG8_STAGE(PG8_SA(1, 1), a1 + hstep, voffA);
;             PG8_WAIT_V(8); PG8_WAIT_L(0); PG8_BAR; PG8_MMA(0, 0, At, B0); PG8_MMA(0, 1, At, B1); PG8_BAR; PG8_SCHED;
;             PG8_LDA(At, 0, 1); PG8_STAGE(PG8_SB(0, 0), b2, voffB); PG8_STAGE(PG8_SB(0, 1), b2 + hstepB, voffB); PG8_STAGE(PG8_SA(0, 0), a2, voffA);
;             PG8_WAIT_V(8); PG8_WAIT_L(0); PG8_BAR; PG8_MMA(1, 0, At, B0); PG8_MMA(1, 1, At, B1); PG8_BAR; PG8_SCHED;
;             PG8_LDB(B0, 1, 0); PG8_LDB(B1, 1, 1); PG8_SCHED; PG8_LDA(At, 1, 0); PG8_STAGE(PG8_SA(0, 1), a2 + hstep, voffA);
;             PG8_WAIT_V(8); PG8_WAIT_L(0); PG8_BAR; PG8_MMA(0, 0, At, B0); PG8_MMA(0, 1, At, B1); PG8_BAR; PG8_SCHED;
;             PG8_LDA(At, 1, 1); PG8_STAGE(PG8_SB(1, 0), b3, voffB); PG8_STAGE(PG8_SB(1, 1), b3 + hstepB, voffB); PG8_STAGE(PG8_SA(1, 0), a3, voffA);
;             PG8_WAIT_V(8); PG8_WAIT_L(0); PG8_BAR; PG8_MMA(1, 0, At, B0); PG8_MMA(1, 1, At, B1); PG8_BAR; PG8_SCHED;
	s_add_i32 s34, s56, s27
	v_lshl_add_u64 v[190:191], v[190:191], 0, s[8:9]
	s_mov_b32 m0, s34
	ds_read_b128 v[182:185], v198 offset:49152
	ds_read_b128 v[186:189], v198 offset:50176
	ds_read_b128 v[202:205], v198 offset:51200
	ds_read_b128 v[206:209], v198 offset:52224
	ds_read_b128 v[210:213], v198 offset:53248
	ds_read_b128 v[214:217], v198 offset:54272
	ds_read_b128 v[218:221], v198 offset:55296
	ds_read_b128 v[222:225], v198 offset:56320
	global_load_lds_dwordx4 v[190:191], off
	s_add_i32 m0, s34, 0x2000
	s_add_u32 s24, s24, 0x20080
	v_lshl_add_u64 v[190:191], v[226:227], 0, s[8:9]
	s_addc_u32 s25, s25, 0
	s_add_i32 s34, s57, s27
	global_load_lds_dwordx4 v[190:191], off
	v_lshl_add_u64 v[190:191], s[24:25], 0, v[156:157]
	s_mov_b32 m0, s34
	s_nop 0
	global_load_lds_dwordx4 v[190:191], off
	v_lshl_add_u64 v[190:191], s[24:25], 0, v[160:161]
	s_add_i32 m0, s34, 0x2000
	s_nop 0
	global_load_lds_dwordx4 v[190:191], off
	v_lshl_add_u64 v[190:191], v[228:229], 0, s[8:9]
	s_mov_b32 m0, s48
	s_nop 0
	global_load_lds_dwordx4 v[190:191], off
	v_lshl_add_u64 v[190:191], v[230:231], 0, s[8:9]
	s_mov_b32 m0, s49
	s_nop 0
	global_load_lds_dwordx4 v[190:191], off
	s_waitcnt vmcnt(8)
	s_waitcnt lgkmcnt(0)
	s_barrier
	s_setprio 1
	s_waitcnt lgkmcnt(0)
	v_mfma_f32_16x16x32_bf16 v[70:73], v[58:61], v[182:185], v[70:73]
	v_mfma_f32_16x16x32_bf16 v[66:69], v[138:141], v[182:185], v[66:69]
	v_mfma_f32_16x16x32_bf16 v[46:49], v[58:61], v[202:205], v[46:49]
	v_mfma_f32_16x16x32_bf16 v[42:45], v[138:141], v[202:205], v[42:45]
	v_mfma_f32_16x16x32_bf16 v[30:33], v[58:61], v[210:213], v[30:33]
	v_mfma_f32_16x16x32_bf16 v[26:29], v[138:141], v[210:213], v[26:29]
	v_mfma_f32_16x16x32_bf16 v[14:17], v[58:61], v[218:221], v[14:17]
	v_mfma_f32_16x16x32_bf16 v[10:13], v[138:141], v[218:221], v[10:13]
	v_mfma_f32_16x16x32_bf16 v[70:73], v[62:65], v[186:189], v[70:73]
	v_mfma_f32_16x16x32_bf16 v[66:69], v[142:145], v[186:189], v[66:69]
	v_mfma_f32_16x16x32_bf16 v[46:49], v[62:65], v[206:209], v[46:49]
	v_mfma_f32_16x16x32_bf16 v[42:45], v[142:145], v[206:209], v[42:45]
	v_mfma_f32_16x16x32_bf16 v[30:33], v[62:65], v[214:217], v[30:33]
	v_mfma_f32_16x16x32_bf16 v[26:29], v[142:145], v[214:217], v[26:29]
	v_mfma_f32_16x16x32_bf16 v[14:17], v[62:65], v[222:225], v[14:17]
	v_mfma_f32_16x16x32_bf16 v[10:13], v[142:145], v[222:225], v[10:13]
	v_mfma_f32_16x16x32_bf16 v[50:53], v[146:149], v[182:185], v[50:53]
	v_mfma_f32_16x16x32_bf16 v[62:65], v[150:153], v[186:189], v[50:53]
	v_mfma_f32_16x16x32_bf16 v[50:53], v[174:177], v[182:185], v[54:57]
	v_mfma_f32_16x16x32_bf16 v[38:41], v[146:149], v[202:205], v[38:41]
	v_mfma_f32_16x16x32_bf16 v[34:37], v[174:177], v[202:205], v[34:37]
	v_mfma_f32_16x16x32_bf16 v[22:25], v[146:149], v[210:213], v[22:25]
	v_mfma_f32_16x16x32_bf16 v[18:21], v[174:177], v[210:213], v[18:21]
	v_mfma_f32_16x16x32_bf16 v[6:9], v[146:149], v[218:221], v[6:9]
	v_mfma_f32_16x16x32_bf16 v[2:5], v[174:177], v[218:221], v[2:5]
	v_mfma_f32_16x16x32_bf16 v[58:61], v[178:181], v[186:189], v[50:53]
	v_mfma_f32_16x16x32_bf16 v[38:41], v[150:153], v[206:209], v[38:41]
	v_mfma_f32_16x16x32_bf16 v[34:37], v[178:181], v[206:209], v[34:37]
	v_mfma_f32_16x16x32_bf16 v[22:25], v[150:153], v[214:217], v[22:25]
	v_mfma_f32_16x16x32_bf16 v[18:21], v[178:181], v[214:217], v[18:21]
	v_mfma_f32_16x16x32_bf16 v[6:9], v[150:153], v[222:225], v[6:9]
	v_mfma_f32_16x16x32_bf16 v[2:5], v[178:181], v[222:225], v[2:5]
	s_setprio 0
	s_barrier
	s_add_i32 s55, s55, 2
	s_add_u32 s53, s53, 0x100
	s_addc_u32 s54, s54, 0
	s_add_u32 s22, s22, 0x100
	s_addc_u32 s23, s23, 0
	s_cmp_lt_u32 s55, 30
.LBB0_2766:
	ds_read_b128 v[50:53], v196
	ds_read_b128 v[54:57], v196 offset:1024
	ds_read_b128 v[138:141], v196 offset:2048
	ds_read_b128 v[142:145], v196 offset:3072
	ds_read_b128 v[146:149], v197
	ds_read_b128 v[150:153], v197 offset:1024
	ds_read_b128 v[174:177], v197 offset:2048
	ds_read_b128 v[178:181], v197 offset:3072
	s_add_u32 s24, s22, 0xfff80080
	s_addc_u32 s25, s23, -1
	s_cmp_eq_u32 s55, 28
	s_cselect_b32 s35, s3, s25
	s_cselect_b32 s34, s15, s24
	s_cselect_b32 s25, s13, s54
	s_cselect_b32 s24, s21, s53
	v_lshl_add_u64 v[190:191], s[22:23], 0, v[168:169]
	s_add_i32 m0, s28, 0xc000
	ds_read_b128 v[182:185], v198
	ds_read_b128 v[186:189], v198 offset:1024
	ds_read_b128 v[202:205], v198 offset:2048
	ds_read_b128 v[206:209], v198 offset:3072
	ds_read_b128 v[210:213], v198 offset:4096
	ds_read_b128 v[214:217], v198 offset:5120
	ds_read_b128 v[218:221], v198 offset:6144
	ds_read_b128 v[222:225], v198 offset:7168
	global_load_lds_dwordx4 v[190:191], off
	v_lshl_add_u64 v[190:191], s[22:23], 0, v[166:167]
	s_add_i32 m0, s28, 0xe000
	s_nop 0
	global_load_lds_dwordx4 v[190:191], off
	s_waitcnt vmcnt(8)
	s_waitcnt lgkmcnt(0)
	s_barrier
; #define PG8_STAGE(bufoff, gbase, voff) do { _Pragma("unroll") for (int _i = 0; _i < 2; ++_i) \
;         __builtin_amdgcn_global_load_lds((const unsigned*)((const char*)(gbase) + (voff)[_i]), (LAS unsigned*)(lds + (bufoff) + ldsw + _i * 8192), 16, 0, 0); } while (0)
; #define PG8_LDA(dst, b, h) do { _Pragma("unroll") for (int m = 0; m < 4; ++m) _Pragma("unroll") for (int k = 0; k < 2; ++k) dst[m][k] = *(const LAS bf16x8*)(lds + PG8_SA(b, h) + aoff + m * 2048 + k * 1024); } while (0)
; #define PG8_MMA(ai, bj, At, Bt) do { __builtin_amdgcn_s_setprio(1); _Pragma("unroll") for (int m = 0; m < 4; ++m) _Pragma("unroll") for (int n = 0; n < 2; ++n) _Pragma("unroll") for (int k = 0; k < 2; ++k) \
;         acc[ai][bj][m][n] = __builtin_amdgcn_mfma_f32_16x16x32_bf16(Bt[n][k], At[m][k], acc[ai][bj][m][n], 0, 0, 0); __builtin_amdgcn_s_setprio(0); } while (0)
; #define PG8_WAIT_V(n) asm volatile("s_waitcnt vmcnt(" #n ")" ::: "memory")
; #define PG8_WAIT_L(n) asm volatile("s_waitcnt lgkmcnt(" #n ")" ::: "memory")
; #define PG8_BAR __builtin_amdgcn_s_barrier()
; #define PG8_SCHED __builtin_amdgcn_sched_barrier(0)
; template <class Epi, class Sched, bool ALIGN_EPI = false, bool SP2 = false>
; __device__ __forceinline__ void gemm_phase(LAS unsigned char* lds, const Gemm g, const Sched& S, const Epi& E) {
;     ...
;             PG8_WAIT_V(8); PG8_WAIT_L(0); PG8_BAR; PG8_MMA(0, 0, At, B0); PG8_MMA(0, 1, At, B1); PG8_BAR; PG8_SCHED;
;             PG8_LDA(At, 0, 1); PG8_STAGE(PG8_SB(0, 0), b2, voffB); PG8_STAGE(PG8_SB(0, 1), b2 + hstepB, voffB); PG8_STAGE(PG8_SA(0, 0), a2, voffA);
;             PG8_WAIT_V(8); PG8_WAIT_L(0); PG8_BAR; PG8_MMA(1, 0, At, B0); PG8_MMA(1, 1, At, B1); PG8_BAR; PG8_SCHED;
	s_setprio 1
	s_waitcnt lgkmcnt(0)
	v_mfma_f32_16x16x32_bf16 v[134:137], v[50:53], v[182:185], v[134:137]
	v_mfma_f32_16x16x32_bf16 v[130:133], v[138:141], v[182:185], v[130:133]
	v_mfma_f32_16x16x32_bf16 v[118:121], v[50:53], v[202:205], v[118:121]
	v_mfma_f32_16x16x32_bf16 v[114:117], v[138:141], v[202:205], v[114:117]
	v_mfma_f32_16x16x32_bf16 v[102:105], v[50:53], v[210:213], v[102:105]
	v_mfma_f32_16x16x32_bf16 v[98:101], v[138:141], v[210:213], v[98:101]
	v_mfma_f32_16x16x32_bf16 v[86:89], v[50:53], v[218:221], v[86:89]
	v_mfma_f32_16x16x32_bf16 v[82:85], v[138:141], v[218:221], v[82:85]
	v_mfma_f32_16x16x32_bf16 v[134:137], v[54:57], v[186:189], v[134:137]
	v_mfma_f32_16x16x32_bf16 v[130:133], v[142:145], v[186:189], v[130:133]
	v_mfma_f32_16x16x32_bf16 v[118:121], v[54:57], v[206:209], v[118:121]
	v_mfma_f32_16x16x32_bf16 v[114:117], v[142:145], v[206:209], v[114:117]
	v_mfma_f32_16x16x32_bf16 v[102:105], v[54:57], v[214:217], v[102:105]
	v_mfma_f32_16x16x32_bf16 v[98:101], v[142:145], v[214:217], v[98:101]
	v_mfma_f32_16x16x32_bf16 v[86:89], v[54:57], v[222:225], v[86:89]
	v_mfma_f32_16x16x32_bf16 v[82:85], v[142:145], v[222:225], v[82:85]
	v_mfma_f32_16x16x32_bf16 v[126:129], v[146:149], v[182:185], v[126:129]
	v_mfma_f32_16x16x32_bf16 v[122:125], v[174:177], v[182:185], v[122:125]
	v_mfma_f32_16x16x32_bf16 v[110:113], v[146:149], v[202:205], v[110:113]
	v_mfma_f32_16x16x32_bf16 v[106:109], v[174:177], v[202:205], v[106:109]
	v_mfma_f32_16x16x32_bf16 v[94:97], v[146:149], v[210:213], v[94:97]
	v_mfma_f32_16x16x32_bf16 v[90:93], v[174:177], v[210:213], v[90:93]
	v_mfma_f32_16x16x32_bf16 v[78:81], v[146:149], v[218:221], v[78:81]
	v_mfma_f32_16x16x32_bf16 v[74:77], v[174:177], v[218:221], v[74:77]
	v_mfma_f32_16x16x32_bf16 v[126:129], v[150:153], v[186:189], v[126:129]
	v_mfma_f32_16x16x32_bf16 v[122:125], v[178:181], v[186:189], v[122:125]
	v_mfma_f32_16x16x32_bf16 v[110:113], v[150:153], v[206:209], v[110:113]
	v_mfma_f32_16x16x32_bf16 v[106:109], v[178:181], v[206:209], v[106:109]
	v_mfma_f32_16x16x32_bf16 v[94:97], v[150:153], v[214:217], v[94:97]
	v_mfma_f32_16x16x32_bf16 v[90:93], v[178:181], v[214:217], v[90:93]
	v_mfma_f32_16x16x32_bf16 v[78:81], v[150:153], v[222:225], v[78:81]
	v_mfma_f32_16x16x32_bf16 v[74:77], v[178:181], v[222:225], v[74:77]
	s_setprio 0
	s_barrier
	s_add_i32 s56, s51, s27
	v_lshl_add_u64 v[190:191], s[24:25], 0, v[156:157]
	s_mov_b32 m0, s56
	ds_read_b128 v[182:185], v198 offset:16384
	ds_read_b128 v[186:189], v198 offset:17408
	ds_read_b128 v[202:205], v198 offset:18432
	ds_read_b128 v[206:209], v198 offset:19456
	ds_read_b128 v[210:213], v198 offset:20480
	ds_read_b128 v[214:217], v198 offset:21504
	ds_read_b128 v[218:221], v198 offset:22528
	ds_read_b128 v[222:225], v198 offset:23552
	global_load_lds_dwordx4 v[190:191], off
	s_add_i32 m0, s56, 0x2000
	s_add_u32 s56, s24, 0x20000
	v_lshl_add_u64 v[226:227], s[24:25], 0, v[160:161]
	s_addc_u32 s57, s25, 0
	s_add_i32 s58, s52, s27
	global_load_lds_dwordx4 v[226:227], off
	v_lshl_add_u64 v[228:229], s[56:57], 0, v[156:157]
	s_mov_b32 m0, s58
	v_lshl_add_u64 v[230:231], s[34:35], 0, v[158:159]
	global_load_lds_dwordx4 v[228:229], off
	v_lshl_add_u64 v[228:229], s[56:57], 0, v[160:161]
	s_add_i32 m0, s58, 0x2000
	s_nop 0
	global_load_lds_dwordx4 v[228:229], off
	v_lshl_add_u64 v[228:229], s[34:35], 0, v[154:155]
	s_mov_b32 m0, s28
	s_nop 0
	global_load_lds_dwordx4 v[228:229], off
	s_mov_b32 m0, s29
	s_nop 0
	global_load_lds_dwordx4 v[230:231], off
	s_waitcnt vmcnt(8)
	s_waitcnt lgkmcnt(0)
	s_barrier
	s_setprio 1
	s_waitcnt lgkmcnt(0)
	v_mfma_f32_16x16x32_bf16 v[70:73], v[50:53], v[182:185], v[70:73]
	v_mfma_f32_16x16x32_bf16 v[66:69], v[138:141], v[182:185], v[66:69]
	v_mfma_f32_16x16x32_bf16 v[46:49], v[50:53], v[202:205], v[46:49]
	v_mfma_f32_16x16x32_bf16 v[42:45], v[138:141], v[202:205], v[42:45]
	v_mfma_f32_16x16x32_bf16 v[30:33], v[50:53], v[210:213], v[30:33]
	v_mfma_f32_16x16x32_bf16 v[26:29], v[138:141], v[210:213], v[26:29]
	v_mfma_f32_16x16x32_bf16 v[14:17], v[50:53], v[218:221], v[14:17]
	v_mfma_f32_16x16x32_bf16 v[10:13], v[138:141], v[218:221], v[10:13]
	v_mfma_f32_16x16x32_bf16 v[70:73], v[54:57], v[186:189], v[70:73]
	v_mfma_f32_16x16x32_bf16 v[66:69], v[142:145], v[186:189], v[66:69]
	v_mfma_f32_16x16x32_bf16 v[46:49], v[54:57], v[206:209], v[46:49]
	v_mfma_f32_16x16x32_bf16 v[42:45], v[142:145], v[206:209], v[42:45]
	v_mfma_f32_16x16x32_bf16 v[30:33], v[54:57], v[214:217], v[30:33]
	v_mfma_f32_16x16x32_bf16 v[26:29], v[142:145], v[214:217], v[26:29]
	v_mfma_f32_16x16x32_bf16 v[14:17], v[54:57], v[222:225], v[14:17]
	v_mfma_f32_16x16x32_bf16 v[10:13], v[142:145], v[222:225], v[10:13]
	v_mfma_f32_16x16x32_bf16 v[38:41], v[146:149], v[202:205], v[38:41]
	v_mfma_f32_16x16x32_bf16 v[34:37], v[174:177], v[202:205], v[34:37]
	v_mfma_f32_16x16x32_bf16 v[22:25], v[146:149], v[210:213], v[22:25]
	v_mfma_f32_16x16x32_bf16 v[18:21], v[174:177], v[210:213], v[18:21]
	v_mfma_f32_16x16x32_bf16 v[6:9], v[146:149], v[218:221], v[6:9]
	v_mfma_f32_16x16x32_bf16 v[2:5], v[174:177], v[218:221], v[2:5]
	v_mfma_f32_16x16x32_bf16 v[50:53], v[146:149], v[182:185], v[62:65]
	v_mfma_f32_16x16x32_bf16 v[54:57], v[174:177], v[182:185], v[58:61]
	v_mfma_f32_16x16x32_bf16 v[38:41], v[150:153], v[206:209], v[38:41]
	v_mfma_f32_16x16x32_bf16 v[34:37], v[178:181], v[206:209], v[34:37]
	v_mfma_f32_16x16x32_bf16 v[22:25], v[150:153], v[214:217], v[22:25]
	v_mfma_f32_16x16x32_bf16 v[18:21], v[178:181], v[214:217], v[18:21]
	v_mfma_f32_16x16x32_bf16 v[6:9], v[150:153], v[222:225], v[6:9]
	v_mfma_f32_16x16x32_bf16 v[2:5], v[178:181], v[222:225], v[2:5]
	v_mfma_f32_16x16x32_bf16 v[50:53], v[150:153], v[186:189], v[50:53]
	v_mfma_f32_16x16x32_bf16 v[54:57], v[178:181], v[186:189], v[54:57]
	s_setprio 0
	s_barrier
; #define PG8_STAGE(bufoff, gbase, voff) do { _Pragma("unroll") for (int _i = 0; _i < 2; ++_i) \
;         __builtin_amdgcn_global_load_lds((const unsigned*)((const char*)(gbase) + (voff)[_i]), (LAS unsigned*)(lds + (bufoff) + ldsw + _i * 8192), 16, 0, 0); } while (0)
; #define PG8_LDA(dst, b, h) do { _Pragma("unroll") for (int m = 0; m < 4; ++m) _Pragma("unroll") for (int k = 0; k < 2; ++k) dst[m][k] = *(const LAS bf16x8*)(lds + PG8_SA(b, h) + aoff + m * 2048 + k * 1024); } while (0)
; #define PG8_LDB(dst, b, h) do { _Pragma("unroll") for (int n = 0; n < 2; ++n) _Pragma("unroll") for (int k = 0; k < 2; ++k) dst[n][k] = *(const LAS bf16x8*)(lds + PG8_SB(b, h) + boff + n * 2048 + k * 1024); } while (0)
; #define PG8_MMA(ai, bj, At, Bt) do { __builtin_amdgcn_s_setprio(1); _Pragma("unroll") for (int m = 0; m < 4; ++m) _Pragma("unroll") for (int n = 0; n < 2; ++n) _Pragma("unroll") for (int k = 0; k < 2; ++k) \
;         acc[ai][bj][m][n] = __builtin_amdgcn_mfma_f32_16x16x32_bf16(Bt[n][k], At[m][k], acc[ai][bj][m][n], 0, 0, 0); __builtin_amdgcn_s_setprio(0); } while (0)
; #define PG8_WAIT_V(n) asm volatile("s_waitcnt vmcnt(" #n ")" ::: "memory")
; #define PG8_WAIT_L(n) asm volatile("s_waitcnt lgkmcnt(" #n ")" ::: "memory")
; #define PG8_BAR __builtin_amdgcn_s_barrier()
; #define PG8_SCHED __builtin_amdgcn_sched_barrier(0)
; template <class Epi, class Sched, bool ALIGN_EPI = false, bool SP2 = false>
; __device__ __forceinline__ void gemm_phase(LAS unsigned char* lds, const Gemm g, const Sched& S, const Epi& E) {
;     ...
;             PG8_LDB(B0, 1, 0); PG8_LDB(B1, 1, 1); PG8_SCHED; PG8_LDA(At, 1, 0); PG8_STAGE(PG8_SA(0, 1), a2 + hstep, voffA);
;             PG8_WAIT_V(8); PG8_WAIT_L(0); PG8_BAR; PG8_MMA(0, 0, At, B0); PG8_MMA(0, 1, At, B1); PG8_BAR; PG8_SCHED;
	s_add_i32 s56, 0, 0x18000
	s_add_i32 s57, 0, 0x1c000
	v_add_u32_e32 v142, s56, v1
	v_add_u32_e32 v162, s57, v1
	ds_read_b128 v[58:61], v142
	ds_read_b128 v[62:65], v142 offset:1024
	ds_read_b128 v[138:141], v142 offset:2048
	ds_read_b128 v[142:145], v142 offset:3072
	ds_read_b128 v[146:149], v162
	ds_read_b128 v[150:153], v162 offset:1024
	ds_read_b128 v[174:177], v162 offset:2048
	ds_read_b128 v[178:181], v162 offset:3072
	s_add_u32 s34, s34, 0x80000
	s_addc_u32 s35, s35, 0
	s_mov_b32 m0, s30
	v_lshl_add_u64 v[232:233], s[34:35], 0, v[154:155]
	ds_read_b128 v[182:185], v198 offset:32768
	ds_read_b128 v[186:189], v198 offset:33792
	ds_read_b128 v[202:205], v198 offset:34816
	ds_read_b128 v[206:209], v198 offset:35840
	ds_read_b128 v[210:213], v198 offset:36864
	ds_read_b128 v[214:217], v198 offset:37888
	ds_read_b128 v[218:221], v198 offset:38912
	ds_read_b128 v[222:225], v198 offset:39936
	global_load_lds_dwordx4 v[232:233], off
	v_lshl_add_u64 v[232:233], s[34:35], 0, v[158:159]
	s_mov_b32 m0, s31
	s_nop 0
	global_load_lds_dwordx4 v[232:233], off
	s_waitcnt vmcnt(8)
	s_waitcnt lgkmcnt(0)
	s_barrier
	s_setprio 1
	s_waitcnt lgkmcnt(0)
	v_mfma_f32_16x16x32_bf16 v[134:137], v[58:61], v[182:185], v[134:137]
	v_mfma_f32_16x16x32_bf16 v[130:133], v[138:141], v[182:185], v[130:133]
	v_mfma_f32_16x16x32_bf16 v[118:121], v[58:61], v[202:205], v[118:121]
	v_mfma_f32_16x16x32_bf16 v[114:117], v[138:141], v[202:205], v[114:117]
	v_mfma_f32_16x16x32_bf16 v[102:105], v[58:61], v[210:213], v[102:105]
	v_mfma_f32_16x16x32_bf16 v[98:101], v[138:141], v[210:213], v[98:101]
	v_mfma_f32_16x16x32_bf16 v[86:89], v[58:61], v[218:221], v[86:89]
	v_mfma_f32_16x16x32_bf16 v[82:85], v[138:141], v[218:221], v[82:85]
	v_mfma_f32_16x16x32_bf16 v[134:137], v[62:65], v[186:189], v[134:137]
	v_mfma_f32_16x16x32_bf16 v[130:133], v[142:145], v[186:189], v[130:133]
	v_mfma_f32_16x16x32_bf16 v[118:121], v[62:65], v[206:209], v[118:121]
	v_mfma_f32_16x16x32_bf16 v[114:117], v[142:145], v[206:209], v[114:117]
	v_mfma_f32_16x16x32_bf16 v[102:105], v[62:65], v[214:217], v[102:105]
	v_mfma_f32_16x16x32_bf16 v[98:101], v[142:145], v[214:217], v[98:101]
	v_mfma_f32_16x16x32_bf16 v[86:89], v[62:65], v[222:225], v[86:89]
	v_mfma_f32_16x16x32_bf16 v[82:85], v[142:145], v[222:225], v[82:85]
	v_mfma_f32_16x16x32_bf16 v[126:129], v[146:149], v[182:185], v[126:129]
	v_mfma_f32_16x16x32_bf16 v[122:125], v[174:177], v[182:185], v[122:125]
	v_mfma_f32_16x16x32_bf16 v[110:113], v[146:149], v[202:205], v[110:113]
	v_mfma_f32_16x16x32_bf16 v[106:109], v[174:177], v[202:205], v[106:109]
	v_mfma_f32_16x16x32_bf16 v[94:97], v[146:149], v[210:213], v[94:97]
	v_mfma_f32_16x16x32_bf16 v[90:93], v[174:177], v[210:213], v[90:93]
	v_mfma_f32_16x16x32_bf16 v[78:81], v[146:149], v[218:221], v[78:81]
	v_mfma_f32_16x16x32_bf16 v[74:77], v[174:177], v[218:221], v[74:77]
	v_mfma_f32_16x16x32_bf16 v[126:129], v[150:153], v[186:189], v[126:129]
	v_mfma_f32_16x16x32_bf16 v[122:125], v[178:181], v[186:189], v[122:125]
	v_mfma_f32_16x16x32_bf16 v[110:113], v[150:153], v[206:209], v[110:113]
	v_mfma_f32_16x16x32_bf16 v[106:109], v[178:181], v[206:209], v[106:109]
	v_mfma_f32_16x16x32_bf16 v[94:97], v[150:153], v[214:217], v[94:97]
	v_mfma_f32_16x16x32_bf16 v[90:93], v[178:181], v[214:217], v[90:93]
	v_mfma_f32_16x16x32_bf16 v[78:81], v[150:153], v[222:225], v[78:81]
	v_mfma_f32_16x16x32_bf16 v[74:77], v[178:181], v[222:225], v[74:77]
	s_setprio 0
	s_barrier
; #define PG8_STAGE(bufoff, gbase, voff) do { _Pragma("unroll") for (int _i = 0; _i < 2; ++_i) \
;         __builtin_amdgcn_global_load_lds((const unsigned*)((const char*)(gbase) + (voff)[_i]), (LAS unsigned*)(lds + (bufoff) + ldsw + _i * 8192), 16, 0, 0); } while (0)
; #define PG8_LDA(dst, b, h) do { _Pragma("unroll") for (int m = 0; m < 4; ++m) _Pragma("unroll") for (int k = 0; k < 2; ++k) dst[m][k] = *(const LAS bf16x8*)(lds + PG8_SA(b, h) + aoff + m * 2048 + k * 1024); } while (0)
; #define PG8_MMA(ai, bj, At, Bt) do { __builtin_amdgcn_s_setprio(1); _Pragma("unroll") for (int m = 0; m < 4; ++m) _Pragma("unroll") for (int n = 0; n < 2; ++n) _Pragma("unroll") for (int k = 0; k < 2; ++k) \
;         acc[ai][bj][m][n] = __builtin_amdgcn_mfma_f32_16x16x32_bf16(Bt[n][k], At[m][k], acc[ai][bj][m][n], 0, 0, 0); __builtin_amdgcn_s_setprio(0); } while (0)
; #define PG8_WAIT_V(n) asm volatile("s_waitcnt vmcnt(" #n ")" ::: "memory")
; #define PG8_WAIT_L(n) asm volatile("s_waitcnt lgkmcnt(" #n ")" ::: "memory")
; #define PG8_BAR __builtin_amdgcn_s_barrier()
; #define PG8_SCHED __builtin_amdgcn_sched_barrier(0)
; template <class Epi, class Sched, bool ALIGN_EPI = false, bool SP2 = false>
; __device__ __forceinline__ void gemm_phase(LAS unsigned char* lds, const Gemm g, const Sched& S, const Epi& E) {
;     ...
;             PG8_LDA(At, 1, 1); PG8_STAGE(PG8_SB(1, 0), b3, voffB); PG8_STAGE(PG8_SB(1, 1), b3 + hstepB, voffB); PG8_STAGE(PG8_SA(1, 0), a3, voffA);
;             PG8_WAIT_V(8); PG8_WAIT_L(0); PG8_BAR; PG8_MMA(1, 0, At, B0); PG8_MMA(1, 1, At, B1); PG8_BAR; PG8_SCHED;
;     ...
;         if constexpr (ALIGN_EPI) { if (wr == 0) PG8_BAR; }
	s_add_i32 s34, s56, s27
	v_lshl_add_u64 v[190:191], v[190:191], 0, s[8:9]
	s_mov_b32 m0, s34
	ds_read_b128 v[182:185], v198 offset:49152
	ds_read_b128 v[186:189], v198 offset:50176
	ds_read_b128 v[202:205], v198 offset:51200
	ds_read_b128 v[206:209], v198 offset:52224
	ds_read_b128 v[210:213], v198 offset:53248
	ds_read_b128 v[214:217], v198 offset:54272
	ds_read_b128 v[218:221], v198 offset:55296
	ds_read_b128 v[222:225], v198 offset:56320
	global_load_lds_dwordx4 v[190:191], off
	s_add_i32 m0, s34, 0x2000
	s_add_u32 s24, s24, 0x20080
	v_lshl_add_u64 v[190:191], v[226:227], 0, s[8:9]
	s_addc_u32 s25, s25, 0
	s_add_i32 s34, s57, s27
	global_load_lds_dwordx4 v[190:191], off
	v_lshl_add_u64 v[190:191], s[24:25], 0, v[156:157]
	s_mov_b32 m0, s34
	s_nop 0
	global_load_lds_dwordx4 v[190:191], off
	v_lshl_add_u64 v[190:191], s[24:25], 0, v[160:161]
	s_add_i32 m0, s34, 0x2000
	s_nop 0
	global_load_lds_dwordx4 v[190:191], off
	v_lshl_add_u64 v[190:191], v[228:229], 0, s[8:9]
	s_mov_b32 m0, s48
	s_nop 0
	global_load_lds_dwordx4 v[190:191], off
	v_lshl_add_u64 v[190:191], v[230:231], 0, s[8:9]
	s_mov_b32 m0, s49
	s_nop 0
	global_load_lds_dwordx4 v[190:191], off
	s_waitcnt vmcnt(8)
	s_waitcnt lgkmcnt(0)
	s_barrier
	s_setprio 1
	s_waitcnt lgkmcnt(0)
	v_mfma_f32_16x16x32_bf16 v[70:73], v[58:61], v[182:185], v[70:73]
	v_mfma_f32_16x16x32_bf16 v[66:69], v[138:141], v[182:185], v[66:69]
	v_mfma_f32_16x16x32_bf16 v[46:49], v[58:61], v[202:205], v[46:49]
	v_mfma_f32_16x16x32_bf16 v[42:45], v[138:141], v[202:205], v[42:45]
	v_mfma_f32_16x16x32_bf16 v[30:33], v[58:61], v[210:213], v[30:33]
	v_mfma_f32_16x16x32_bf16 v[26:29], v[138:141], v[210:213], v[26:29]
	v_mfma_f32_16x16x32_bf16 v[14:17], v[58:61], v[218:221], v[14:17]
	v_mfma_f32_16x16x32_bf16 v[10:13], v[138:141], v[218:221], v[10:13]
	v_mfma_f32_16x16x32_bf16 v[70:73], v[62:65], v[186:189], v[70:73]
	v_mfma_f32_16x16x32_bf16 v[66:69], v[142:145], v[186:189], v[66:69]
	v_mfma_f32_16x16x32_bf16 v[46:49], v[62:65], v[206:209], v[46:49]
	v_mfma_f32_16x16x32_bf16 v[42:45], v[142:145], v[206:209], v[42:45]
	v_mfma_f32_16x16x32_bf16 v[30:33], v[62:65], v[214:217], v[30:33]
	v_mfma_f32_16x16x32_bf16 v[26:29], v[142:145], v[214:217], v[26:29]
	v_mfma_f32_16x16x32_bf16 v[14:17], v[62:65], v[222:225], v[14:17]
	v_mfma_f32_16x16x32_bf16 v[10:13], v[142:145], v[222:225], v[10:13]
	v_mfma_f32_16x16x32_bf16 v[50:53], v[146:149], v[182:185], v[50:53]
	v_mfma_f32_16x16x32_bf16 v[62:65], v[150:153], v[186:189], v[50:53]
	v_mfma_f32_16x16x32_bf16 v[50:53], v[174:177], v[182:185], v[54:57]
	v_mfma_f32_16x16x32_bf16 v[38:41], v[146:149], v[202:205], v[38:41]
	v_mfma_f32_16x16x32_bf16 v[34:37], v[174:177], v[202:205], v[34:37]
	v_mfma_f32_16x16x32_bf16 v[22:25], v[146:149], v[210:213], v[22:25]
	v_mfma_f32_16x16x32_bf16 v[18:21], v[174:177], v[210:213], v[18:21]
	v_mfma_f32_16x16x32_bf16 v[6:9], v[146:149], v[218:221], v[6:9]
	v_mfma_f32_16x16x32_bf16 v[2:5], v[174:177], v[218:221], v[2:5]
	v_mfma_f32_16x16x32_bf16 v[58:61], v[178:181], v[186:189], v[50:53]
	v_mfma_f32_16x16x32_bf16 v[38:41], v[150:153], v[206:209], v[38:41]
	v_mfma_f32_16x16x32_bf16 v[34:37], v[178:181], v[206:209], v[34:37]
	v_mfma_f32_16x16x32_bf16 v[22:25], v[150:153], v[214:217], v[22:25]
	v_mfma_f32_16x16x32_bf16 v[18:21], v[178:181], v[214:217], v[18:21]
	v_mfma_f32_16x16x32_bf16 v[6:9], v[150:153], v[222:225], v[6:9]
	v_mfma_f32_16x16x32_bf16 v[2:5], v[178:181], v[222:225], v[2:5]
	s_setprio 0
	s_barrier
	s_add_i32 s55, s55, 2
	s_add_u32 s53, s53, 0x100
	s_addc_u32 s54, s54, 0
	s_add_u32 s22, s22, 0x100
	s_addc_u32 s23, s23, 0
	s_cmp_lt_u32 s55, 30
	s_cbranch_scc1 .LBB0_2766
	s_andn2_b64 vcc, exec, s[10:11]
	s_cbranch_vccnz .LBB0_2769
	s_barrier

; __device__ __forceinline__ float row_rstd(const float* ss, int row) { return 1.0f / sqrtf(ss[row] * (1.0f / DM) + 1e-6f); }
; #define PG8_STAGE(bufoff, gbase, voff) do { _Pragma("unroll") for (int _i = 0; _i < 2; ++_i) \
;         __builtin_amdgcn_global_load_lds((const unsigned*)((const char*)(gbase) + (voff)[_i]), (LAS unsigned*)(lds + (bufoff) + ldsw + _i * 8192), 16, 0, 0); } while (0)
; #define PG8_LDA(dst, b, h) do { _Pragma("unroll") for (int m = 0; m < 4; ++m) _Pragma("unroll") for (int k = 0; k < 2; ++k) dst[m][k] = *(const LAS bf16x8*)(lds + PG8_SA(b, h) + aoff + m * 2048 + k * 1024); } while (0)
; #define PG8_LDB(dst, b, h) do { _Pragma("unroll") for (int n = 0; n < 2; ++n) _Pragma("unroll") for (int k = 0; k < 2; ++k) dst[n][k] = *(const LAS bf16x8*)(lds + PG8_SB(b, h) + boff + n * 2048 + k * 1024); } while (0)
; #define PG8_WAIT_V(n) asm volatile("s_waitcnt vmcnt(" #n ")" ::: "memory")
; #define PG8_WAIT_L(n) asm volatile("s_waitcnt lgkmcnt(" #n ")" ::: "memory")
; #define PG8_BAR __builtin_amdgcn_s_barrier()
; #define PG8_SCHED __builtin_amdgcn_sched_barrier(0)
;     __device__ __forceinline__ void operator()(const f32x4 (&acc)[2][2][4][2], const Unit& u, int wr, int wc, int fr, int fq) const {
;     ...
;         const float* bp = bias + (size_t)s * BIAS_N + u.pn * BM + wc * 32 + 8 * fq;
;         const f32x4 ba0 = *(const f32x4*)bp, ba1 = *(const f32x4*)(bp + 4), bb0 = *(const f32x4*)(bp + HALF), bb1 = *(const f32x4*)(bp + HALF + 4);
;         const int lane = fq * 16 + fr;
;         const float rsl0 = row_rstd(ss, u.pm * BM + wr * 64 + lane), rsl1 = row_rstd(ss, u.pm * BM + HALF + wr * 64 + lane);
; template <class Epi, class Sched, bool ALIGN_EPI = false, bool SP2 = false>
; __device__ __forceinline__ void gemm_phase(LAS unsigned char* lds, const Gemm g, const Sched& S, const Epi& E) {
;     ...
;             PG8_LDB(B0, 0, 0); PG8_LDB(B1, 0, 1); PG8_SCHED; PG8_LDA(At, 0, 0); PG8_STAGE(PG8_SA(1, 1), a1 + hstep, voffA);
;             PG8_WAIT_V(8); PG8_WAIT_L(0); PG8_BAR; PG8_MMA(0, 0, At, B0); PG8_MMA(0, 1, At, B1); PG8_BAR; PG8_SCHED;
;             PG8_LDA(At, 0, 1); PG8_STAGE(PG8_SB(0, 0), b2, voffB); PG8_STAGE(PG8_SB(0, 1), b2 + hstepB, voffB); PG8_STAGE(PG8_SA(0, 0), a2, voffA);
;             PG8_WAIT_V(8); PG8_WAIT_L(0); PG8_BAR; PG8_MMA(1, 0, At, B0); PG8_MMA(1, 1, At, B1); PG8_BAR; PG8_SCHED;
.Lpre_up2l1:
	s_lshl_b64 s[98:99], s[98:99], 2
	s_add_u32 s98, s35, s98
	s_addc_u32 s99, s38, s99
	s_lshl_b32 s100, s3, 8
	s_ashr_i32 s101, s100, 31
	s_lshl_b64 s[100:101], s[100:101], 2
	s_add_u32 s98, s98, s100
	s_addc_u32 s99, s99, s101
	s_add_u32 s98, s98, s44
	s_addc_u32 s99, s99, 0
	s_lshl_b32 s100, s2, 8
	s_add_i32 s100, s100, s34
	v_or_b32_e32 v162, s100, v170
	v_ashrrev_i32_e32 v163, 31, v162
	v_lshl_add_u64 v[162:163], v[162:163], 2, s[0:1]
	v_add_u32_e32 v164, s100, v171
	v_ashrrev_i32_e32 v165, 31, v164
	v_lshl_add_u64 v[164:165], v[164:165], 2, s[0:1]
	global_load_dwordx4 v[234:237], v176, s[98:99] offset:16
	global_load_dwordx4 v[238:241], v176, s[98:99]
	global_load_dwordx4 v[242:245], v176, s[98:99] offset:528
	global_load_dwordx4 v[246:249], v176, s[98:99] offset:512
	global_load_dword v250, v[162:163], off
	global_load_dword v251, v[164:165], off
	ds_read_b128 v[66:69], v173
	ds_read_b128 v[70:73], v173 offset:1024
	ds_read_b128 v[74:77], v173 offset:2048
	ds_read_b128 v[78:81], v173 offset:3072
	ds_read_b128 v[162:165], v174
	ds_read_b128 v[180:183], v174 offset:1024
	ds_read_b128 v[184:187], v174 offset:2048
	ds_read_b128 v[188:191], v174 offset:3072
	s_add_u32 s20, s18, 0xfff80080
	s_addc_u32 s21, s19, -1
	s_cmp_eq_u32 s50, 28
	s_cselect_b32 s23, s13, s21
	s_cselect_b32 s22, s46, s20
	s_cselect_b32 s21, s11, s49
	s_cselect_b32 s20, s47, s48
	v_lshl_add_u64 v[166:167], s[18:19], 0, v[156:157]
	s_add_i32 m0, s28, 0xc000
	ds_read_b128 v[192:195], v175
	ds_read_b128 v[196:199], v175 offset:1024
	ds_read_b128 v[200:203], v175 offset:2048
	ds_read_b128 v[204:207], v175 offset:3072
	ds_read_b128 v[208:211], v175 offset:4096
	ds_read_b128 v[212:215], v175 offset:5120
	ds_read_b128 v[216:219], v175 offset:6144
	ds_read_b128 v[220:223], v175 offset:7168
	global_load_lds_dwordx4 v[166:167], off
	v_lshl_add_u64 v[166:167], s[18:19], 0, v[154:155]
	s_add_i32 m0, s28, 0xe000
	s_nop 0
	global_load_lds_dwordx4 v[166:167], off
	s_waitcnt lgkmcnt(0)
	s_barrier
	s_setprio 1
	s_waitcnt lgkmcnt(0)
	v_mfma_f32_16x16x32_bf16 v[142:145], v[66:69], v[192:195], 0
	v_mfma_f32_16x16x32_bf16 v[138:141], v[74:77], v[192:195], 0
	v_mfma_f32_16x16x32_bf16 v[126:129], v[66:69], v[200:203], 0
	v_mfma_f32_16x16x32_bf16 v[122:125], v[74:77], v[200:203], 0
	v_mfma_f32_16x16x32_bf16 v[110:113], v[66:69], v[208:211], 0
	v_mfma_f32_16x16x32_bf16 v[106:109], v[74:77], v[208:211], 0
	v_mfma_f32_16x16x32_bf16 v[94:97], v[66:69], v[216:219], 0
	v_mfma_f32_16x16x32_bf16 v[90:93], v[74:77], v[216:219], 0
	v_mfma_f32_16x16x32_bf16 v[142:145], v[70:73], v[196:199], v[142:145]
	v_mfma_f32_16x16x32_bf16 v[138:141], v[78:81], v[196:199], v[138:141]
	v_mfma_f32_16x16x32_bf16 v[126:129], v[70:73], v[204:207], v[126:129]
	v_mfma_f32_16x16x32_bf16 v[122:125], v[78:81], v[204:207], v[122:125]
	v_mfma_f32_16x16x32_bf16 v[110:113], v[70:73], v[212:215], v[110:113]
	v_mfma_f32_16x16x32_bf16 v[106:109], v[78:81], v[212:215], v[106:109]
	v_mfma_f32_16x16x32_bf16 v[94:97], v[70:73], v[220:223], v[94:97]
	v_mfma_f32_16x16x32_bf16 v[90:93], v[78:81], v[220:223], v[90:93]
	v_mfma_f32_16x16x32_bf16 v[134:137], v[162:165], v[192:195], 0
	v_mfma_f32_16x16x32_bf16 v[130:133], v[184:187], v[192:195], 0
	v_mfma_f32_16x16x32_bf16 v[118:121], v[162:165], v[200:203], 0
	v_mfma_f32_16x16x32_bf16 v[114:117], v[184:187], v[200:203], 0
	v_mfma_f32_16x16x32_bf16 v[102:105], v[162:165], v[208:211], 0
	v_mfma_f32_16x16x32_bf16 v[98:101], v[184:187], v[208:211], 0
	v_mfma_f32_16x16x32_bf16 v[86:89], v[162:165], v[216:219], 0
	v_mfma_f32_16x16x32_bf16 v[82:85], v[184:187], v[216:219], 0
	v_mfma_f32_16x16x32_bf16 v[134:137], v[180:183], v[196:199], v[134:137]
	v_mfma_f32_16x16x32_bf16 v[130:133], v[188:191], v[196:199], v[130:133]
	v_mfma_f32_16x16x32_bf16 v[118:121], v[180:183], v[204:207], v[118:121]
	v_mfma_f32_16x16x32_bf16 v[114:117], v[188:191], v[204:207], v[114:117]
	v_mfma_f32_16x16x32_bf16 v[102:105], v[180:183], v[212:215], v[102:105]
	v_mfma_f32_16x16x32_bf16 v[98:101], v[188:191], v[212:215], v[98:101]
	v_mfma_f32_16x16x32_bf16 v[86:89], v[180:183], v[220:223], v[86:89]
	v_mfma_f32_16x16x32_bf16 v[82:85], v[188:191], v[220:223], v[82:85]
	s_setprio 0
	s_barrier
	s_add_i32 s51, s41, s25
	v_lshl_add_u64 v[166:167], s[20:21], 0, v[150:151]
	s_mov_b32 m0, s51
	ds_read_b128 v[192:195], v175 offset:16384
	ds_read_b128 v[196:199], v175 offset:17408
	ds_read_b128 v[200:203], v175 offset:18432
	ds_read_b128 v[204:207], v175 offset:19456
	ds_read_b128 v[208:211], v175 offset:20480
	ds_read_b128 v[212:215], v175 offset:21504
	ds_read_b128 v[216:219], v175 offset:22528
	ds_read_b128 v[220:223], v175 offset:23552
	global_load_lds_dwordx4 v[166:167], off
	s_add_i32 m0, s51, 0x2000
	s_add_u32 s52, s20, 0x80000
	v_lshl_add_u64 v[224:225], s[20:21], 0, v[146:147]
	s_addc_u32 s53, s21, 0
	s_add_i32 s51, s42, s25
	global_load_lds_dwordx4 v[224:225], off
	v_lshl_add_u64 v[226:227], s[52:53], 0, v[150:151]
	s_mov_b32 m0, s51
	v_lshl_add_u64 v[228:229], s[22:23], 0, v[148:149]
	global_load_lds_dwordx4 v[226:227], off
	v_lshl_add_u64 v[226:227], s[52:53], 0, v[146:147]
	s_add_i32 m0, s51, 0x2000
	s_nop 0
	global_load_lds_dwordx4 v[226:227], off
	v_lshl_add_u64 v[226:227], s[22:23], 0, v[152:153]
	s_mov_b32 m0, s28
	s_nop 0
	global_load_lds_dwordx4 v[226:227], off
	s_mov_b32 m0, s29
	s_nop 0
	global_load_lds_dwordx4 v[228:229], off
	s_waitcnt lgkmcnt(0)
	s_barrier
; #define PG8_STAGE(bufoff, gbase, voff) do { _Pragma("unroll") for (int _i = 0; _i < 2; ++_i) \
;         __builtin_amdgcn_global_load_lds((const unsigned*)((const char*)(gbase) + (voff)[_i]), (LAS unsigned*)(lds + (bufoff) + ldsw + _i * 8192), 16, 0, 0); } while (0)
; #define PG8_LDA(dst, b, h) do { _Pragma("unroll") for (int m = 0; m < 4; ++m) _Pragma("unroll") for (int k = 0; k < 2; ++k) dst[m][k] = *(const LAS bf16x8*)(lds + PG8_SA(b, h) + aoff + m * 2048 + k * 1024); } while (0)
; #define PG8_LDB(dst, b, h) do { _Pragma("unroll") for (int n = 0; n < 2; ++n) _Pragma("unroll") for (int k = 0; k < 2; ++k) dst[n][k] = *(const LAS bf16x8*)(lds + PG8_SB(b, h) + boff + n * 2048 + k * 1024); } while (0)
; #define PG8_MMA(ai, bj, At, Bt) do { __builtin_amdgcn_s_setprio(1); _Pragma("unroll") for (int m = 0; m < 4; ++m) _Pragma("unroll") for (int n = 0; n < 2; ++n) _Pragma("unroll") for (int k = 0; k < 2; ++k) \
;         acc[ai][bj][m][n] = __builtin_amdgcn_mfma_f32_16x16x32_bf16(Bt[n][k], At[m][k], acc[ai][bj][m][n], 0, 0, 0); __builtin_amdgcn_s_setprio(0); } while (0)
; #define PG8_WAIT_V(n) asm volatile("s_waitcnt vmcnt(" #n ")" ::: "memory")
; #define PG8_WAIT_L(n) asm volatile("s_waitcnt lgkmcnt(" #n ")" ::: "memory")
; #define PG8_BAR __builtin_amdgcn_s_barrier()
; #define PG8_SCHED __builtin_amdgcn_sched_barrier(0)
; template <class Epi, class Sched, bool ALIGN_EPI = false, bool SP2 = false>
; __device__ __forceinline__ void gemm_phase(LAS unsigned char* lds, const Gemm g, const Sched& S, const Epi& E) {
;     ...
;             PG8_WAIT_V(8); PG8_WAIT_L(0); PG8_BAR; PG8_MMA(1, 0, At, B0); PG8_MMA(1, 1, At, B1); PG8_BAR; PG8_SCHED;
;             PG8_LDB(B0, 1, 0); PG8_LDB(B1, 1, 1); PG8_SCHED; PG8_LDA(At, 1, 0); PG8_STAGE(PG8_SA(0, 1), a2 + hstep, voffA);
;             PG8_WAIT_V(8); PG8_WAIT_L(0); PG8_BAR; PG8_MMA(0, 0, At, B0); PG8_MMA(0, 1, At, B1); PG8_BAR; PG8_SCHED;
	s_setprio 1
	s_waitcnt lgkmcnt(0)
	v_mfma_f32_16x16x32_bf16 v[62:65], v[66:69], v[192:195], 0
	v_mfma_f32_16x16x32_bf16 v[58:61], v[74:77], v[192:195], 0
	v_mfma_f32_16x16x32_bf16 v[46:49], v[66:69], v[200:203], 0
	v_mfma_f32_16x16x32_bf16 v[42:45], v[74:77], v[200:203], 0
	v_mfma_f32_16x16x32_bf16 v[30:33], v[66:69], v[208:211], 0
	v_mfma_f32_16x16x32_bf16 v[26:29], v[74:77], v[208:211], 0
	v_mfma_f32_16x16x32_bf16 v[14:17], v[66:69], v[216:219], 0
	v_mfma_f32_16x16x32_bf16 v[10:13], v[74:77], v[216:219], 0
	v_mfma_f32_16x16x32_bf16 v[62:65], v[70:73], v[196:199], v[62:65]
	v_mfma_f32_16x16x32_bf16 v[58:61], v[78:81], v[196:199], v[58:61]
	v_mfma_f32_16x16x32_bf16 v[46:49], v[70:73], v[204:207], v[46:49]
	v_mfma_f32_16x16x32_bf16 v[42:45], v[78:81], v[204:207], v[42:45]
	v_mfma_f32_16x16x32_bf16 v[30:33], v[70:73], v[212:215], v[30:33]
	v_mfma_f32_16x16x32_bf16 v[26:29], v[78:81], v[212:215], v[26:29]
	v_mfma_f32_16x16x32_bf16 v[14:17], v[70:73], v[220:223], v[14:17]
	v_mfma_f32_16x16x32_bf16 v[10:13], v[78:81], v[220:223], v[10:13]
	v_mfma_f32_16x16x32_bf16 v[54:57], v[162:165], v[192:195], 0
	v_mfma_f32_16x16x32_bf16 v[50:53], v[184:187], v[192:195], 0
	v_mfma_f32_16x16x32_bf16 v[38:41], v[162:165], v[200:203], 0
	v_mfma_f32_16x16x32_bf16 v[34:37], v[184:187], v[200:203], 0
	v_mfma_f32_16x16x32_bf16 v[22:25], v[162:165], v[208:211], 0
	v_mfma_f32_16x16x32_bf16 v[18:21], v[184:187], v[208:211], 0
	v_mfma_f32_16x16x32_bf16 v[6:9], v[162:165], v[216:219], 0
	v_mfma_f32_16x16x32_bf16 v[2:5], v[184:187], v[216:219], 0
	v_mfma_f32_16x16x32_bf16 v[54:57], v[180:183], v[196:199], v[54:57]
	v_mfma_f32_16x16x32_bf16 v[50:53], v[188:191], v[196:199], v[50:53]
	v_mfma_f32_16x16x32_bf16 v[38:41], v[180:183], v[204:207], v[38:41]
	v_mfma_f32_16x16x32_bf16 v[34:37], v[188:191], v[204:207], v[34:37]
	v_mfma_f32_16x16x32_bf16 v[22:25], v[180:183], v[212:215], v[22:25]
	v_mfma_f32_16x16x32_bf16 v[18:21], v[188:191], v[212:215], v[18:21]
	v_mfma_f32_16x16x32_bf16 v[6:9], v[180:183], v[220:223], v[6:9]
	v_mfma_f32_16x16x32_bf16 v[2:5], v[188:191], v[220:223], v[2:5]
	s_setprio 0
	s_barrier
	s_add_i32 s51, 0, 0x18000
	s_add_i32 s52, 0, 0x1c000
	v_add_u32_e32 v78, s51, v169
	v_add_u32_e32 v168, s52, v169
	ds_read_b128 v[66:69], v78
	ds_read_b128 v[70:73], v78 offset:1024
	ds_read_b128 v[74:77], v78 offset:2048
	ds_read_b128 v[78:81], v78 offset:3072
	ds_read_b128 v[162:165], v168
	ds_read_b128 v[180:183], v168 offset:1024
	ds_read_b128 v[184:187], v168 offset:2048
	ds_read_b128 v[188:191], v168 offset:3072
	s_add_u32 s22, s22, 0x80000
	s_addc_u32 s23, s23, 0
	s_mov_b32 m0, s30
	v_lshl_add_u64 v[230:231], s[22:23], 0, v[152:153]
	ds_read_b128 v[192:195], v175 offset:32768
	ds_read_b128 v[196:199], v175 offset:33792
	ds_read_b128 v[200:203], v175 offset:34816
	ds_read_b128 v[204:207], v175 offset:35840
	ds_read_b128 v[208:211], v175 offset:36864
	ds_read_b128 v[212:215], v175 offset:37888
	ds_read_b128 v[216:219], v175 offset:38912
	ds_read_b128 v[220:223], v175 offset:39936
	global_load_lds_dwordx4 v[230:231], off
	v_lshl_add_u64 v[230:231], s[22:23], 0, v[148:149]
	s_mov_b32 m0, s31
	s_nop 0
	global_load_lds_dwordx4 v[230:231], off
	s_waitcnt vmcnt(8)
	s_waitcnt lgkmcnt(0)
	s_barrier
	s_setprio 1
	s_waitcnt lgkmcnt(0)
	v_mfma_f32_16x16x32_bf16 v[142:145], v[66:69], v[192:195], v[142:145]
	v_mfma_f32_16x16x32_bf16 v[138:141], v[74:77], v[192:195], v[138:141]
	v_mfma_f32_16x16x32_bf16 v[126:129], v[66:69], v[200:203], v[126:129]
	v_mfma_f32_16x16x32_bf16 v[122:125], v[74:77], v[200:203], v[122:125]
	v_mfma_f32_16x16x32_bf16 v[110:113], v[66:69], v[208:211], v[110:113]
	v_mfma_f32_16x16x32_bf16 v[106:109], v[74:77], v[208:211], v[106:109]
	v_mfma_f32_16x16x32_bf16 v[94:97], v[66:69], v[216:219], v[94:97]
	v_mfma_f32_16x16x32_bf16 v[90:93], v[74:77], v[216:219], v[90:93]
	v_mfma_f32_16x16x32_bf16 v[142:145], v[70:73], v[196:199], v[142:145]
	v_mfma_f32_16x16x32_bf16 v[138:141], v[78:81], v[196:199], v[138:141]
	v_mfma_f32_16x16x32_bf16 v[126:129], v[70:73], v[204:207], v[126:129]
	v_mfma_f32_16x16x32_bf16 v[122:125], v[78:81], v[204:207], v[122:125]
	v_mfma_f32_16x16x32_bf16 v[110:113], v[70:73], v[212:215], v[110:113]
	v_mfma_f32_16x16x32_bf16 v[106:109], v[78:81], v[212:215], v[106:109]
	v_mfma_f32_16x16x32_bf16 v[94:97], v[70:73], v[220:223], v[94:97]
	v_mfma_f32_16x16x32_bf16 v[90:93], v[78:81], v[220:223], v[90:93]
	v_mfma_f32_16x16x32_bf16 v[134:137], v[162:165], v[192:195], v[134:137]
	v_mfma_f32_16x16x32_bf16 v[130:133], v[184:187], v[192:195], v[130:133]
	v_mfma_f32_16x16x32_bf16 v[118:121], v[162:165], v[200:203], v[118:121]
	v_mfma_f32_16x16x32_bf16 v[114:117], v[184:187], v[200:203], v[114:117]
	v_mfma_f32_16x16x32_bf16 v[102:105], v[162:165], v[208:211], v[102:105]
	v_mfma_f32_16x16x32_bf16 v[98:101], v[184:187], v[208:211], v[98:101]
	v_mfma_f32_16x16x32_bf16 v[86:89], v[162:165], v[216:219], v[86:89]
	v_mfma_f32_16x16x32_bf16 v[82:85], v[184:187], v[216:219], v[82:85]
	v_mfma_f32_16x16x32_bf16 v[134:137], v[180:183], v[196:199], v[134:137]
	v_mfma_f32_16x16x32_bf16 v[130:133], v[188:191], v[196:199], v[130:133]
	v_mfma_f32_16x16x32_bf16 v[118:121], v[180:183], v[204:207], v[118:121]
	v_mfma_f32_16x16x32_bf16 v[114:117], v[188:191], v[204:207], v[114:117]
	v_mfma_f32_16x16x32_bf16 v[102:105], v[180:183], v[212:215], v[102:105]
	v_mfma_f32_16x16x32_bf16 v[98:101], v[188:191], v[212:215], v[98:101]
	v_mfma_f32_16x16x32_bf16 v[86:89], v[180:183], v[220:223], v[86:89]
	v_mfma_f32_16x16x32_bf16 v[82:85], v[188:191], v[220:223], v[82:85]
	s_setprio 0
	s_barrier
; #define PG8_STAGE(bufoff, gbase, voff) do { _Pragma("unroll") for (int _i = 0; _i < 2; ++_i) \
;         __builtin_amdgcn_global_load_lds((const unsigned*)((const char*)(gbase) + (voff)[_i]), (LAS unsigned*)(lds + (bufoff) + ldsw + _i * 8192), 16, 0, 0); } while (0)
; #define PG8_LDA(dst, b, h) do { _Pragma("unroll") for (int m = 0; m < 4; ++m) _Pragma("unroll") for (int k = 0; k < 2; ++k) dst[m][k] = *(const LAS bf16x8*)(lds + PG8_SA(b, h) + aoff + m * 2048 + k * 1024); } while (0)
; #define PG8_LDB(dst, b, h) do { _Pragma("unroll") for (int n = 0; n < 2; ++n) _Pragma("unroll") for (int k = 0; k < 2; ++k) dst[n][k] = *(const LAS bf16x8*)(lds + PG8_SB(b, h) + boff + n * 2048 + k * 1024); } while (0)
; template <class Epi, class Sched, bool ALIGN_EPI = false, bool SP2 = false>
; __device__ __forceinline__ void gemm_phase(LAS unsigned char* lds, const Gemm g, const Sched& S, const Epi& E) {
;     ...
;         for (int t = 0; t < nt; t += 2) {
;             const bool last = (t == nt - 2);
;             const char* a1 = cA + (size_t)(t + 1) * kstep;
;             const char* a2 = last ? nA : cA + (size_t)(t + 2) * kstep; const char* b2 = last ? nB : cB + (size_t)(t + 2) * kstep;
;             const char* a3 = a2 + kstep; const char* b3 = b2 + kstep;
;             if (last && has_next) S.a_ready(nxt);
;             if constexpr (SP2) {
;             PG8_LDB(B0, 0, 0); PG8_LDB(B1, 0, 1); PG8_SCHED; PG8_LDA(At, 0, 0); PG8_STAGE(PG8_SA(1, 1), a1 + hstep, voffA);
;             PG8_WAIT_V(8); PG8_WAIT_L(0); PG8_BAR; PG8_MMA(0, 0, At, B0); PG8_MMA(0, 1, At, B1); PG8_BAR; PG8_SCHED;
;             PG8_LDA(At, 0, 1); PG8_STAGE(PG8_SB(0, 0), b2, voffB); PG8_STAGE(PG8_SB(0, 1), b2 + hstepB, voffB); PG8_STAGE(PG8_SA(0, 0), a2, voffA);
;             PG8_WAIT_V(8); PG8_WAIT_L(0); PG8_BAR; PG8_MMA(1, 0, At, B0); PG8_MMA(1, 1, At, B1); PG8_BAR; PG8_SCHED;
;             PG8_LDB(B0, 1, 0); PG8_LDB(B1, 1, 1); PG8_SCHED; PG8_LDA(At, 1, 0); PG8_STAGE(PG8_SA(0, 1), a2 + hstep, voffA);
;             PG8_WAIT_V(8); PG8_WAIT_L(0); PG8_BAR; PG8_MMA(0, 0, At, B0); PG8_MMA(0, 1, At, B1); PG8_BAR; PG8_SCHED;
;             PG8_LDA(At, 1, 1); PG8_STAGE(PG8_SB(1, 0), b3, voffB); PG8_STAGE(PG8_SB(1, 1), b3 + hstepB, voffB); PG8_STAGE(PG8_SA(1, 0), a3, voffA);
;             PG8_WAIT_V(8); PG8_WAIT_L(0); PG8_BAR; PG8_MMA(1, 0, At, B0); PG8_MMA(1, 1, At, B1); PG8_BAR; PG8_SCHED;
	s_add_i32 s22, s51, s25
	v_lshl_add_u64 v[166:167], v[166:167], 0, s[6:7]
	s_mov_b32 m0, s22
	ds_read_b128 v[192:195], v175 offset:49152
	ds_read_b128 v[196:199], v175 offset:50176
	ds_read_b128 v[200:203], v175 offset:51200
	ds_read_b128 v[204:207], v175 offset:52224
	ds_read_b128 v[208:211], v175 offset:53248
	ds_read_b128 v[212:215], v175 offset:54272
	ds_read_b128 v[216:219], v175 offset:55296
	ds_read_b128 v[220:223], v175 offset:56320
	global_load_lds_dwordx4 v[166:167], off
	s_add_i32 m0, s22, 0x2000
	s_add_u32 s20, s20, 0x80080
	v_lshl_add_u64 v[166:167], v[224:225], 0, s[6:7]
	s_addc_u32 s21, s21, 0
	s_add_i32 s22, s52, s25
	global_load_lds_dwordx4 v[166:167], off
	v_lshl_add_u64 v[166:167], s[20:21], 0, v[150:151]
	s_mov_b32 m0, s22
	s_nop 0
	global_load_lds_dwordx4 v[166:167], off
	v_lshl_add_u64 v[166:167], s[20:21], 0, v[146:147]
	s_add_i32 m0, s22, 0x2000
	s_nop 0
	global_load_lds_dwordx4 v[166:167], off
	v_lshl_add_u64 v[166:167], v[226:227], 0, s[6:7]
	s_mov_b32 m0, s39
	s_nop 0
	global_load_lds_dwordx4 v[166:167], off
	v_lshl_add_u64 v[166:167], v[228:229], 0, s[6:7]
	s_mov_b32 m0, s40
	s_nop 0
	global_load_lds_dwordx4 v[166:167], off
	s_waitcnt vmcnt(8)
	s_waitcnt lgkmcnt(0)
	s_barrier
	s_setprio 1
	s_waitcnt lgkmcnt(0)
	v_mfma_f32_16x16x32_bf16 v[62:65], v[66:69], v[192:195], v[62:65]
	v_mfma_f32_16x16x32_bf16 v[58:61], v[74:77], v[192:195], v[58:61]
	v_mfma_f32_16x16x32_bf16 v[46:49], v[66:69], v[200:203], v[46:49]
	v_mfma_f32_16x16x32_bf16 v[42:45], v[74:77], v[200:203], v[42:45]
	v_mfma_f32_16x16x32_bf16 v[30:33], v[66:69], v[208:211], v[30:33]
	v_mfma_f32_16x16x32_bf16 v[26:29], v[74:77], v[208:211], v[26:29]
	v_mfma_f32_16x16x32_bf16 v[14:17], v[66:69], v[216:219], v[14:17]
	v_mfma_f32_16x16x32_bf16 v[10:13], v[74:77], v[216:219], v[10:13]
	v_mfma_f32_16x16x32_bf16 v[62:65], v[70:73], v[196:199], v[62:65]
	v_mfma_f32_16x16x32_bf16 v[58:61], v[78:81], v[196:199], v[58:61]
	v_mfma_f32_16x16x32_bf16 v[46:49], v[70:73], v[204:207], v[46:49]
	v_mfma_f32_16x16x32_bf16 v[42:45], v[78:81], v[204:207], v[42:45]
	v_mfma_f32_16x16x32_bf16 v[30:33], v[70:73], v[212:215], v[30:33]
	v_mfma_f32_16x16x32_bf16 v[26:29], v[78:81], v[212:215], v[26:29]
	v_mfma_f32_16x16x32_bf16 v[14:17], v[70:73], v[220:223], v[14:17]
	v_mfma_f32_16x16x32_bf16 v[10:13], v[78:81], v[220:223], v[10:13]
	v_mfma_f32_16x16x32_bf16 v[54:57], v[162:165], v[192:195], v[54:57]
	v_mfma_f32_16x16x32_bf16 v[50:53], v[184:187], v[192:195], v[50:53]
	v_mfma_f32_16x16x32_bf16 v[38:41], v[162:165], v[200:203], v[38:41]
	v_mfma_f32_16x16x32_bf16 v[34:37], v[184:187], v[200:203], v[34:37]
	v_mfma_f32_16x16x32_bf16 v[22:25], v[162:165], v[208:211], v[22:25]
	v_mfma_f32_16x16x32_bf16 v[18:21], v[184:187], v[208:211], v[18:21]
	v_mfma_f32_16x16x32_bf16 v[6:9], v[162:165], v[216:219], v[6:9]
	v_mfma_f32_16x16x32_bf16 v[2:5], v[184:187], v[216:219], v[2:5]
	v_mfma_f32_16x16x32_bf16 v[54:57], v[180:183], v[196:199], v[54:57]
	v_mfma_f32_16x16x32_bf16 v[50:53], v[188:191], v[196:199], v[50:53]
	v_mfma_f32_16x16x32_bf16 v[38:41], v[180:183], v[204:207], v[38:41]
	v_mfma_f32_16x16x32_bf16 v[34:37], v[188:191], v[204:207], v[34:37]
	v_mfma_f32_16x16x32_bf16 v[22:25], v[180:183], v[212:215], v[22:25]
	v_mfma_f32_16x16x32_bf16 v[18:21], v[188:191], v[212:215], v[18:21]
	v_mfma_f32_16x16x32_bf16 v[6:9], v[180:183], v[220:223], v[6:9]
	v_mfma_f32_16x16x32_bf16 v[2:5], v[188:191], v[220:223], v[2:5]
	s_setprio 0
	s_barrier
	s_add_i32 s50, s50, 2
	s_add_u32 s48, s48, 0x100
	s_addc_u32 s49, s49, 0
	s_add_u32 s18, s18, 0x100
	s_addc_u32 s19, s19, 0
	s_cmp_lt_u32 s50, 30
.LBB0_2916:
	ds_read_b128 v[66:69], v173
	ds_read_b128 v[70:73], v173 offset:1024
	ds_read_b128 v[74:77], v173 offset:2048
	ds_read_b128 v[78:81], v173 offset:3072
	ds_read_b128 v[162:165], v174
	ds_read_b128 v[180:183], v174 offset:1024
	ds_read_b128 v[184:187], v174 offset:2048
	ds_read_b128 v[188:191], v174 offset:3072
	s_add_u32 s20, s18, 0xfff80080
	s_addc_u32 s21, s19, -1
	s_cmp_eq_u32 s50, 28
	s_cselect_b32 s23, s13, s21
	s_cselect_b32 s22, s46, s20
	s_cselect_b32 s21, s11, s49
	s_cselect_b32 s20, s47, s48
	v_lshl_add_u64 v[166:167], s[18:19], 0, v[156:157]
	s_add_i32 m0, s28, 0xc000
	ds_read_b128 v[192:195], v175
	ds_read_b128 v[196:199], v175 offset:1024
	ds_read_b128 v[200:203], v175 offset:2048
	ds_read_b128 v[204:207], v175 offset:3072
	ds_read_b128 v[208:211], v175 offset:4096
	ds_read_b128 v[212:215], v175 offset:5120
	ds_read_b128 v[216:219], v175 offset:6144
	ds_read_b128 v[220:223], v175 offset:7168
	global_load_lds_dwordx4 v[166:167], off
	v_lshl_add_u64 v[166:167], s[18:19], 0, v[154:155]
	s_add_i32 m0, s28, 0xe000
	s_nop 0
	global_load_lds_dwordx4 v[166:167], off
	s_waitcnt vmcnt(8)
	s_waitcnt lgkmcnt(0)
	s_barrier
; #define PG8_STAGE(bufoff, gbase, voff) do { _Pragma("unroll") for (int _i = 0; _i < 2; ++_i) \
;         __builtin_amdgcn_global_load_lds((const unsigned*)((const char*)(gbase) + (voff)[_i]), (LAS unsigned*)(lds + (bufoff) + ldsw + _i * 8192), 16, 0, 0); } while (0)
; #define PG8_LDA(dst, b, h) do { _Pragma("unroll") for (int m = 0; m < 4; ++m) _Pragma("unroll") for (int k = 0; k < 2; ++k) dst[m][k] = *(const LAS bf16x8*)(lds + PG8_SA(b, h) + aoff + m * 2048 + k * 1024); } while (0)
; #define PG8_MMA(ai, bj, At, Bt) do { __builtin_amdgcn_s_setprio(1); _Pragma("unroll") for (int m = 0; m < 4; ++m) _Pragma("unroll") for (int n = 0; n < 2; ++n) _Pragma("unroll") for (int k = 0; k < 2; ++k) \
;         acc[ai][bj][m][n] = __builtin_amdgcn_mfma_f32_16x16x32_bf16(Bt[n][k], At[m][k], acc[ai][bj][m][n], 0, 0, 0); __builtin_amdgcn_s_setprio(0); } while (0)
; #define PG8_WAIT_V(n) asm volatile("s_waitcnt vmcnt(" #n ")" ::: "memory")
; #define PG8_WAIT_L(n) asm volatile("s_waitcnt lgkmcnt(" #n ")" ::: "memory")
; #define PG8_BAR __builtin_amdgcn_s_barrier()
; #define PG8_SCHED __builtin_amdgcn_sched_barrier(0)
; template <class Epi, class Sched, bool ALIGN_EPI = false, bool SP2 = false>
; __device__ __forceinline__ void gemm_phase(LAS unsigned char* lds, const Gemm g, const Sched& S, const Epi& E) {
;     ...
;             PG8_WAIT_V(8); PG8_WAIT_L(0); PG8_BAR; PG8_MMA(0, 0, At, B0); PG8_MMA(0, 1, At, B1); PG8_BAR; PG8_SCHED;
;             PG8_LDA(At, 0, 1); PG8_STAGE(PG8_SB(0, 0), b2, voffB); PG8_STAGE(PG8_SB(0, 1), b2 + hstepB, voffB); PG8_STAGE(PG8_SA(0, 0), a2, voffA);
;             PG8_WAIT_V(8); PG8_WAIT_L(0); PG8_BAR; PG8_MMA(1, 0, At, B0); PG8_MMA(1, 1, At, B1); PG8_BAR; PG8_SCHED;
	s_setprio 1
	s_waitcnt lgkmcnt(0)
	v_mfma_f32_16x16x32_bf16 v[142:145], v[66:69], v[192:195], v[142:145]
	v_mfma_f32_16x16x32_bf16 v[138:141], v[74:77], v[192:195], v[138:141]
	v_mfma_f32_16x16x32_bf16 v[126:129], v[66:69], v[200:203], v[126:129]
	v_mfma_f32_16x16x32_bf16 v[122:125], v[74:77], v[200:203], v[122:125]
	v_mfma_f32_16x16x32_bf16 v[110:113], v[66:69], v[208:211], v[110:113]
	v_mfma_f32_16x16x32_bf16 v[106:109], v[74:77], v[208:211], v[106:109]
	v_mfma_f32_16x16x32_bf16 v[94:97], v[66:69], v[216:219], v[94:97]
	v_mfma_f32_16x16x32_bf16 v[90:93], v[74:77], v[216:219], v[90:93]
	v_mfma_f32_16x16x32_bf16 v[142:145], v[70:73], v[196:199], v[142:145]
	v_mfma_f32_16x16x32_bf16 v[138:141], v[78:81], v[196:199], v[138:141]
	v_mfma_f32_16x16x32_bf16 v[126:129], v[70:73], v[204:207], v[126:129]
	v_mfma_f32_16x16x32_bf16 v[122:125], v[78:81], v[204:207], v[122:125]
	v_mfma_f32_16x16x32_bf16 v[110:113], v[70:73], v[212:215], v[110:113]
	v_mfma_f32_16x16x32_bf16 v[106:109], v[78:81], v[212:215], v[106:109]
	v_mfma_f32_16x16x32_bf16 v[94:97], v[70:73], v[220:223], v[94:97]
	v_mfma_f32_16x16x32_bf16 v[90:93], v[78:81], v[220:223], v[90:93]
	v_mfma_f32_16x16x32_bf16 v[134:137], v[162:165], v[192:195], v[134:137]
	v_mfma_f32_16x16x32_bf16 v[130:133], v[184:187], v[192:195], v[130:133]
	v_mfma_f32_16x16x32_bf16 v[118:121], v[162:165], v[200:203], v[118:121]
	v_mfma_f32_16x16x32_bf16 v[114:117], v[184:187], v[200:203], v[114:117]
	v_mfma_f32_16x16x32_bf16 v[102:105], v[162:165], v[208:211], v[102:105]
	v_mfma_f32_16x16x32_bf16 v[98:101], v[184:187], v[208:211], v[98:101]
	v_mfma_f32_16x16x32_bf16 v[86:89], v[162:165], v[216:219], v[86:89]
	v_mfma_f32_16x16x32_bf16 v[82:85], v[184:187], v[216:219], v[82:85]
	v_mfma_f32_16x16x32_bf16 v[134:137], v[180:183], v[196:199], v[134:137]
	v_mfma_f32_16x16x32_bf16 v[130:133], v[188:191], v[196:199], v[130:133]
	v_mfma_f32_16x16x32_bf16 v[118:121], v[180:183], v[204:207], v[118:121]
	v_mfma_f32_16x16x32_bf16 v[114:117], v[188:191], v[204:207], v[114:117]
	v_mfma_f32_16x16x32_bf16 v[102:105], v[180:183], v[212:215], v[102:105]
	v_mfma_f32_16x16x32_bf16 v[98:101], v[188:191], v[212:215], v[98:101]
	v_mfma_f32_16x16x32_bf16 v[86:89], v[180:183], v[220:223], v[86:89]
	v_mfma_f32_16x16x32_bf16 v[82:85], v[188:191], v[220:223], v[82:85]
	s_setprio 0
	s_barrier
	s_add_i32 s51, s41, s25
	v_lshl_add_u64 v[166:167], s[20:21], 0, v[150:151]
	s_mov_b32 m0, s51
	ds_read_b128 v[192:195], v175 offset:16384
	ds_read_b128 v[196:199], v175 offset:17408
	ds_read_b128 v[200:203], v175 offset:18432
	ds_read_b128 v[204:207], v175 offset:19456
	ds_read_b128 v[208:211], v175 offset:20480
	ds_read_b128 v[212:215], v175 offset:21504
	ds_read_b128 v[216:219], v175 offset:22528
	ds_read_b128 v[220:223], v175 offset:23552
	global_load_lds_dwordx4 v[166:167], off
	s_add_i32 m0, s51, 0x2000
	s_add_u32 s52, s20, 0x80000
	v_lshl_add_u64 v[224:225], s[20:21], 0, v[146:147]
	s_addc_u32 s53, s21, 0
	s_add_i32 s51, s42, s25
	global_load_lds_dwordx4 v[224:225], off
	v_lshl_add_u64 v[226:227], s[52:53], 0, v[150:151]
	s_mov_b32 m0, s51
	v_lshl_add_u64 v[228:229], s[22:23], 0, v[148:149]
	global_load_lds_dwordx4 v[226:227], off
	v_lshl_add_u64 v[226:227], s[52:53], 0, v[146:147]
	s_add_i32 m0, s51, 0x2000
	s_nop 0
	global_load_lds_dwordx4 v[226:227], off
	v_lshl_add_u64 v[226:227], s[22:23], 0, v[152:153]
	s_mov_b32 m0, s28
	s_nop 0
	global_load_lds_dwordx4 v[226:227], off
	s_mov_b32 m0, s29
	s_nop 0
	global_load_lds_dwordx4 v[228:229], off
	s_waitcnt vmcnt(8)
	s_waitcnt lgkmcnt(0)
	s_barrier
	s_setprio 1
	s_waitcnt lgkmcnt(0)
	v_mfma_f32_16x16x32_bf16 v[62:65], v[66:69], v[192:195], v[62:65]
	v_mfma_f32_16x16x32_bf16 v[58:61], v[74:77], v[192:195], v[58:61]
	v_mfma_f32_16x16x32_bf16 v[46:49], v[66:69], v[200:203], v[46:49]
	v_mfma_f32_16x16x32_bf16 v[42:45], v[74:77], v[200:203], v[42:45]
	v_mfma_f32_16x16x32_bf16 v[30:33], v[66:69], v[208:211], v[30:33]
	v_mfma_f32_16x16x32_bf16 v[26:29], v[74:77], v[208:211], v[26:29]
	v_mfma_f32_16x16x32_bf16 v[14:17], v[66:69], v[216:219], v[14:17]
	v_mfma_f32_16x16x32_bf16 v[10:13], v[74:77], v[216:219], v[10:13]
	v_mfma_f32_16x16x32_bf16 v[62:65], v[70:73], v[196:199], v[62:65]
	v_mfma_f32_16x16x32_bf16 v[58:61], v[78:81], v[196:199], v[58:61]
	v_mfma_f32_16x16x32_bf16 v[46:49], v[70:73], v[204:207], v[46:49]
	v_mfma_f32_16x16x32_bf16 v[42:45], v[78:81], v[204:207], v[42:45]
	v_mfma_f32_16x16x32_bf16 v[30:33], v[70:73], v[212:215], v[30:33]
	v_mfma_f32_16x16x32_bf16 v[26:29], v[78:81], v[212:215], v[26:29]
	v_mfma_f32_16x16x32_bf16 v[14:17], v[70:73], v[220:223], v[14:17]
	v_mfma_f32_16x16x32_bf16 v[10:13], v[78:81], v[220:223], v[10:13]
	v_mfma_f32_16x16x32_bf16 v[54:57], v[162:165], v[192:195], v[54:57]
	v_mfma_f32_16x16x32_bf16 v[50:53], v[184:187], v[192:195], v[50:53]
	v_mfma_f32_16x16x32_bf16 v[38:41], v[162:165], v[200:203], v[38:41]
	v_mfma_f32_16x16x32_bf16 v[34:37], v[184:187], v[200:203], v[34:37]
	v_mfma_f32_16x16x32_bf16 v[22:25], v[162:165], v[208:211], v[22:25]
	v_mfma_f32_16x16x32_bf16 v[18:21], v[184:187], v[208:211], v[18:21]
	v_mfma_f32_16x16x32_bf16 v[6:9], v[162:165], v[216:219], v[6:9]
	v_mfma_f32_16x16x32_bf16 v[2:5], v[184:187], v[216:219], v[2:5]
	v_mfma_f32_16x16x32_bf16 v[54:57], v[180:183], v[196:199], v[54:57]
	v_mfma_f32_16x16x32_bf16 v[50:53], v[188:191], v[196:199], v[50:53]
	v_mfma_f32_16x16x32_bf16 v[38:41], v[180:183], v[204:207], v[38:41]
	v_mfma_f32_16x16x32_bf16 v[34:37], v[188:191], v[204:207], v[34:37]
	v_mfma_f32_16x16x32_bf16 v[22:25], v[180:183], v[212:215], v[22:25]
	v_mfma_f32_16x16x32_bf16 v[18:21], v[188:191], v[212:215], v[18:21]
	v_mfma_f32_16x16x32_bf16 v[6:9], v[180:183], v[220:223], v[6:9]
	v_mfma_f32_16x16x32_bf16 v[2:5], v[188:191], v[220:223], v[2:5]
	s_setprio 0
	s_barrier
; #define PG8_STAGE(bufoff, gbase, voff) do { _Pragma("unroll") for (int _i = 0; _i < 2; ++_i) \
;         __builtin_amdgcn_global_load_lds((const unsigned*)((const char*)(gbase) + (voff)[_i]), (LAS unsigned*)(lds + (bufoff) + ldsw + _i * 8192), 16, 0, 0); } while (0)
; #define PG8_LDA(dst, b, h) do { _Pragma("unroll") for (int m = 0; m < 4; ++m) _Pragma("unroll") for (int k = 0; k < 2; ++k) dst[m][k] = *(const LAS bf16x8*)(lds + PG8_SA(b, h) + aoff + m * 2048 + k * 1024); } while (0)
; #define PG8_LDB(dst, b, h) do { _Pragma("unroll") for (int n = 0; n < 2; ++n) _Pragma("unroll") for (int k = 0; k < 2; ++k) dst[n][k] = *(const LAS bf16x8*)(lds + PG8_SB(b, h) + boff + n * 2048 + k * 1024); } while (0)
; #define PG8_MMA(ai, bj, At, Bt) do { __builtin_amdgcn_s_setprio(1); _Pragma("unroll") for (int m = 0; m < 4; ++m) _Pragma("unroll") for (int n = 0; n < 2; ++n) _Pragma("unroll") for (int k = 0; k < 2; ++k) \
;         acc[ai][bj][m][n] = __builtin_amdgcn_mfma_f32_16x16x32_bf16(Bt[n][k], At[m][k], acc[ai][bj][m][n], 0, 0, 0); __builtin_amdgcn_s_setprio(0); } while (0)
; #define PG8_WAIT_V(n) asm volatile("s_waitcnt vmcnt(" #n ")" ::: "memory")
; #define PG8_WAIT_L(n) asm volatile("s_waitcnt lgkmcnt(" #n ")" ::: "memory")
; #define PG8_BAR __builtin_amdgcn_s_barrier()
; #define PG8_SCHED __builtin_amdgcn_sched_barrier(0)
; template <class Epi, class Sched, bool ALIGN_EPI = false, bool SP2 = false>
; __device__ __forceinline__ void gemm_phase(LAS unsigned char* lds, const Gemm g, const Sched& S, const Epi& E) {
;     ...
;             PG8_LDB(B0, 1, 0); PG8_LDB(B1, 1, 1); PG8_SCHED; PG8_LDA(At, 1, 0); PG8_STAGE(PG8_SA(0, 1), a2 + hstep, voffA);
;             PG8_WAIT_V(8); PG8_WAIT_L(0); PG8_BAR; PG8_MMA(0, 0, At, B0); PG8_MMA(0, 1, At, B1); PG8_BAR; PG8_SCHED;
	s_add_i32 s51, 0, 0x18000
	s_add_i32 s52, 0, 0x1c000
	v_add_u32_e32 v78, s51, v169
	v_add_u32_e32 v168, s52, v169
	ds_read_b128 v[66:69], v78
	ds_read_b128 v[70:73], v78 offset:1024
	ds_read_b128 v[74:77], v78 offset:2048
	ds_read_b128 v[78:81], v78 offset:3072
	ds_read_b128 v[162:165], v168
	ds_read_b128 v[180:183], v168 offset:1024
	ds_read_b128 v[184:187], v168 offset:2048
	ds_read_b128 v[188:191], v168 offset:3072
	s_add_u32 s22, s22, 0x80000
	s_addc_u32 s23, s23, 0
	s_mov_b32 m0, s30
	v_lshl_add_u64 v[230:231], s[22:23], 0, v[152:153]
	ds_read_b128 v[192:195], v175 offset:32768
	ds_read_b128 v[196:199], v175 offset:33792
	ds_read_b128 v[200:203], v175 offset:34816
	ds_read_b128 v[204:207], v175 offset:35840
	ds_read_b128 v[208:211], v175 offset:36864
	ds_read_b128 v[212:215], v175 offset:37888
	ds_read_b128 v[216:219], v175 offset:38912
	ds_read_b128 v[220:223], v175 offset:39936
	global_load_lds_dwordx4 v[230:231], off
	v_lshl_add_u64 v[230:231], s[22:23], 0, v[148:149]
	s_mov_b32 m0, s31
	s_nop 0
	global_load_lds_dwordx4 v[230:231], off
	s_waitcnt vmcnt(8)
	s_waitcnt lgkmcnt(0)
	s_barrier
	s_setprio 1
	s_waitcnt lgkmcnt(0)
	v_mfma_f32_16x16x32_bf16 v[142:145], v[66:69], v[192:195], v[142:145]
	v_mfma_f32_16x16x32_bf16 v[138:141], v[74:77], v[192:195], v[138:141]
	v_mfma_f32_16x16x32_bf16 v[126:129], v[66:69], v[200:203], v[126:129]
	v_mfma_f32_16x16x32_bf16 v[122:125], v[74:77], v[200:203], v[122:125]
	v_mfma_f32_16x16x32_bf16 v[110:113], v[66:69], v[208:211], v[110:113]
	v_mfma_f32_16x16x32_bf16 v[106:109], v[74:77], v[208:211], v[106:109]
	v_mfma_f32_16x16x32_bf16 v[94:97], v[66:69], v[216:219], v[94:97]
	v_mfma_f32_16x16x32_bf16 v[90:93], v[74:77], v[216:219], v[90:93]
	v_mfma_f32_16x16x32_bf16 v[142:145], v[70:73], v[196:199], v[142:145]
	v_mfma_f32_16x16x32_bf16 v[138:141], v[78:81], v[196:199], v[138:141]
	v_mfma_f32_16x16x32_bf16 v[126:129], v[70:73], v[204:207], v[126:129]
	v_mfma_f32_16x16x32_bf16 v[122:125], v[78:81], v[204:207], v[122:125]
	v_mfma_f32_16x16x32_bf16 v[110:113], v[70:73], v[212:215], v[110:113]
	v_mfma_f32_16x16x32_bf16 v[106:109], v[78:81], v[212:215], v[106:109]
	v_mfma_f32_16x16x32_bf16 v[94:97], v[70:73], v[220:223], v[94:97]
	v_mfma_f32_16x16x32_bf16 v[90:93], v[78:81], v[220:223], v[90:93]
	v_mfma_f32_16x16x32_bf16 v[134:137], v[162:165], v[192:195], v[134:137]
	v_mfma_f32_16x16x32_bf16 v[130:133], v[184:187], v[192:195], v[130:133]
	v_mfma_f32_16x16x32_bf16 v[118:121], v[162:165], v[200:203], v[118:121]
	v_mfma_f32_16x16x32_bf16 v[114:117], v[184:187], v[200:203], v[114:117]
	v_mfma_f32_16x16x32_bf16 v[102:105], v[162:165], v[208:211], v[102:105]
	v_mfma_f32_16x16x32_bf16 v[98:101], v[184:187], v[208:211], v[98:101]
	v_mfma_f32_16x16x32_bf16 v[86:89], v[162:165], v[216:219], v[86:89]
	v_mfma_f32_16x16x32_bf16 v[82:85], v[184:187], v[216:219], v[82:85]
	v_mfma_f32_16x16x32_bf16 v[134:137], v[180:183], v[196:199], v[134:137]
	v_mfma_f32_16x16x32_bf16 v[130:133], v[188:191], v[196:199], v[130:133]
	v_mfma_f32_16x16x32_bf16 v[118:121], v[180:183], v[204:207], v[118:121]
	v_mfma_f32_16x16x32_bf16 v[114:117], v[188:191], v[204:207], v[114:117]
	v_mfma_f32_16x16x32_bf16 v[102:105], v[180:183], v[212:215], v[102:105]
	v_mfma_f32_16x16x32_bf16 v[98:101], v[188:191], v[212:215], v[98:101]
	v_mfma_f32_16x16x32_bf16 v[86:89], v[180:183], v[220:223], v[86:89]
	v_mfma_f32_16x16x32_bf16 v[82:85], v[188:191], v[220:223], v[82:85]
	s_setprio 0
	s_barrier
; #define PG8_STAGE(bufoff, gbase, voff) do { _Pragma("unroll") for (int _i = 0; _i < 2; ++_i) \
;         __builtin_amdgcn_global_load_lds((const unsigned*)((const char*)(gbase) + (voff)[_i]), (LAS unsigned*)(lds + (bufoff) + ldsw + _i * 8192), 16, 0, 0); } while (0)
; #define PG8_LDA(dst, b, h) do { _Pragma("unroll") for (int m = 0; m < 4; ++m) _Pragma("unroll") for (int k = 0; k < 2; ++k) dst[m][k] = *(const LAS bf16x8*)(lds + PG8_SA(b, h) + aoff + m * 2048 + k * 1024); } while (0)
; #define PG8_MMA(ai, bj, At, Bt) do { __builtin_amdgcn_s_setprio(1); _Pragma("unroll") for (int m = 0; m < 4; ++m) _Pragma("unroll") for (int n = 0; n < 2; ++n) _Pragma("unroll") for (int k = 0; k < 2; ++k) \
;         acc[ai][bj][m][n] = __builtin_amdgcn_mfma_f32_16x16x32_bf16(Bt[n][k], At[m][k], acc[ai][bj][m][n], 0, 0, 0); __builtin_amdgcn_s_setprio(0); } while (0)
; #define PG8_WAIT_V(n) asm volatile("s_waitcnt vmcnt(" #n ")" ::: "memory")
; #define PG8_WAIT_L(n) asm volatile("s_waitcnt lgkmcnt(" #n ")" ::: "memory")
; #define PG8_BAR __builtin_amdgcn_s_barrier()
; #define PG8_SCHED __builtin_amdgcn_sched_barrier(0)
; template <class Epi, class Sched, bool ALIGN_EPI = false, bool SP2 = false>
; __device__ __forceinline__ void gemm_phase(LAS unsigned char* lds, const Gemm g, const Sched& S, const Epi& E) {
;     ...
;             PG8_LDA(At, 1, 1); PG8_STAGE(PG8_SB(1, 0), b3, voffB); PG8_STAGE(PG8_SB(1, 1), b3 + hstepB, voffB); PG8_STAGE(PG8_SA(1, 0), a3, voffA);
;             PG8_WAIT_V(8); PG8_WAIT_L(0); PG8_BAR; PG8_MMA(1, 0, At, B0); PG8_MMA(1, 1, At, B1); PG8_BAR; PG8_SCHED;
	s_add_i32 s22, s51, s25
	v_lshl_add_u64 v[166:167], v[166:167], 0, s[6:7]
	s_mov_b32 m0, s22
	ds_read_b128 v[192:195], v175 offset:49152
	ds_read_b128 v[196:199], v175 offset:50176
	ds_read_b128 v[200:203], v175 offset:51200
	ds_read_b128 v[204:207], v175 offset:52224
	ds_read_b128 v[208:211], v175 offset:53248
	ds_read_b128 v[212:215], v175 offset:54272
	ds_read_b128 v[216:219], v175 offset:55296
	ds_read_b128 v[220:223], v175 offset:56320
	global_load_lds_dwordx4 v[166:167], off
	s_add_i32 m0, s22, 0x2000
	s_add_u32 s20, s20, 0x80080
	v_lshl_add_u64 v[166:167], v[224:225], 0, s[6:7]
	s_addc_u32 s21, s21, 0
	s_add_i32 s22, s52, s25
	global_load_lds_dwordx4 v[166:167], off
	v_lshl_add_u64 v[166:167], s[20:21], 0, v[150:151]
	s_mov_b32 m0, s22
	s_nop 0
	global_load_lds_dwordx4 v[166:167], off
	v_lshl_add_u64 v[166:167], s[20:21], 0, v[146:147]
	s_add_i32 m0, s22, 0x2000
	s_nop 0
	global_load_lds_dwordx4 v[166:167], off
	v_lshl_add_u64 v[166:167], v[226:227], 0, s[6:7]
	s_mov_b32 m0, s39
	s_nop 0
	global_load_lds_dwordx4 v[166:167], off
	v_lshl_add_u64 v[166:167], v[228:229], 0, s[6:7]
	s_mov_b32 m0, s40
	s_nop 0
	global_load_lds_dwordx4 v[166:167], off
	s_waitcnt vmcnt(8)
	s_waitcnt lgkmcnt(0)
	s_barrier
	s_setprio 1
	s_waitcnt lgkmcnt(0)
	v_mfma_f32_16x16x32_bf16 v[62:65], v[66:69], v[192:195], v[62:65]
	v_mfma_f32_16x16x32_bf16 v[58:61], v[74:77], v[192:195], v[58:61]
	v_mfma_f32_16x16x32_bf16 v[46:49], v[66:69], v[200:203], v[46:49]
	v_mfma_f32_16x16x32_bf16 v[42:45], v[74:77], v[200:203], v[42:45]
	v_mfma_f32_16x16x32_bf16 v[30:33], v[66:69], v[208:211], v[30:33]
	v_mfma_f32_16x16x32_bf16 v[26:29], v[74:77], v[208:211], v[26:29]
	v_mfma_f32_16x16x32_bf16 v[14:17], v[66:69], v[216:219], v[14:17]
	v_mfma_f32_16x16x32_bf16 v[10:13], v[74:77], v[216:219], v[10:13]
	v_mfma_f32_16x16x32_bf16 v[62:65], v[70:73], v[196:199], v[62:65]
	v_mfma_f32_16x16x32_bf16 v[58:61], v[78:81], v[196:199], v[58:61]
	v_mfma_f32_16x16x32_bf16 v[46:49], v[70:73], v[204:207], v[46:49]
	v_mfma_f32_16x16x32_bf16 v[42:45], v[78:81], v[204:207], v[42:45]
	v_mfma_f32_16x16x32_bf16 v[30:33], v[70:73], v[212:215], v[30:33]
	v_mfma_f32_16x16x32_bf16 v[26:29], v[78:81], v[212:215], v[26:29]
	v_mfma_f32_16x16x32_bf16 v[14:17], v[70:73], v[220:223], v[14:17]
	v_mfma_f32_16x16x32_bf16 v[10:13], v[78:81], v[220:223], v[10:13]
	v_mfma_f32_16x16x32_bf16 v[54:57], v[162:165], v[192:195], v[54:57]
	v_mfma_f32_16x16x32_bf16 v[50:53], v[184:187], v[192:195], v[50:53]
	v_mfma_f32_16x16x32_bf16 v[38:41], v[162:165], v[200:203], v[38:41]
	v_mfma_f32_16x16x32_bf16 v[34:37], v[184:187], v[200:203], v[34:37]
	v_mfma_f32_16x16x32_bf16 v[22:25], v[162:165], v[208:211], v[22:25]
	v_mfma_f32_16x16x32_bf16 v[18:21], v[184:187], v[208:211], v[18:21]
	v_mfma_f32_16x16x32_bf16 v[6:9], v[162:165], v[216:219], v[6:9]
	v_mfma_f32_16x16x32_bf16 v[2:5], v[184:187], v[216:219], v[2:5]
	v_mfma_f32_16x16x32_bf16 v[54:57], v[180:183], v[196:199], v[54:57]
	v_mfma_f32_16x16x32_bf16 v[50:53], v[188:191], v[196:199], v[50:53]
	v_mfma_f32_16x16x32_bf16 v[38:41], v[180:183], v[204:207], v[38:41]
	v_mfma_f32_16x16x32_bf16 v[34:37], v[188:191], v[204:207], v[34:37]
	v_mfma_f32_16x16x32_bf16 v[22:25], v[180:183], v[212:215], v[22:25]
	v_mfma_f32_16x16x32_bf16 v[18:21], v[188:191], v[212:215], v[18:21]
	v_mfma_f32_16x16x32_bf16 v[6:9], v[180:183], v[220:223], v[6:9]
	v_mfma_f32_16x16x32_bf16 v[2:5], v[188:191], v[220:223], v[2:5]
	s_setprio 0
	s_barrier
	s_add_i32 s50, s50, 2
	s_add_u32 s48, s48, 0x100
	s_addc_u32 s49, s49, 0
	s_add_u32 s18, s18, 0x100
	s_addc_u32 s19, s19, 0
	s_cmp_lt_u32 s50, 30
	s_cbranch_scc1 .LBB0_2916
	s_andn2_b64 vcc, exec, s[8:9]
	s_cbranch_vccnz .LBB0_2919
	s_barrier

; #define PG8_STAGE(bufoff, gbase, voff) do { _Pragma("unroll") for (int _i = 0; _i < 2; ++_i) \
;         __builtin_amdgcn_global_load_lds((const unsigned*)((const char*)(gbase) + (voff)[_i]), (LAS unsigned*)(lds + (bufoff) + ldsw + _i * 8192), 16, 0, 0); } while (0)
; #define PG8_LDA(dst, b, h) do { _Pragma("unroll") for (int m = 0; m < 4; ++m) _Pragma("unroll") for (int k = 0; k < 2; ++k) dst[m][k] = *(const LAS bf16x8*)(lds + PG8_SA(b, h) + aoff + m * 2048 + k * 1024); } while (0)
; #define PG8_LDB(dst, b, h) do { _Pragma("unroll") for (int n = 0; n < 2; ++n) _Pragma("unroll") for (int k = 0; k < 2; ++k) dst[n][k] = *(const LAS bf16x8*)(lds + PG8_SB(b, h) + boff + n * 2048 + k * 1024); } while (0)
; #define PG8_WAIT_V(n) asm volatile("s_waitcnt vmcnt(" #n ")" ::: "memory")
; #define PG8_WAIT_L(n) asm volatile("s_waitcnt lgkmcnt(" #n ")" ::: "memory")
; #define PG8_BAR __builtin_amdgcn_s_barrier()
; #define PG8_SCHED __builtin_amdgcn_sched_barrier(0)
; template <class Epi, class Sched, bool ALIGN_EPI = false, bool SP2 = false>
; __device__ __forceinline__ void gemm_phase(LAS unsigned char* lds, const Gemm g, const Sched& S, const Epi& E) {
;     ...
;         const char* nA = has_next ? (const char*)g.A + (size_t)nxt.pm * tstep + nxt.koff : cA; const char* nB = has_next ? (const char*)g.Bt + (size_t)nxt.pn * tstep + nxt.koff : cB;
;         for (int t = 0; t < nt; t += 2) {
;             const bool last = (t == nt - 2);
;             const char* a1 = cA + (size_t)(t + 1) * kstep;
;             const char* a2 = last ? nA : cA + (size_t)(t + 2) * kstep; const char* b2 = last ? nB : cB + (size_t)(t + 2) * kstep;
;             const char* a3 = a2 + kstep; const char* b3 = b2 + kstep;
;             if (last && has_next) S.a_ready(nxt);
;             if constexpr (SP2) {
;             PG8_LDB(B0, 0, 0); PG8_LDB(B1, 0, 1); PG8_SCHED; PG8_LDA(At, 0, 0); PG8_STAGE(PG8_SA(1, 1), a1 + hstep, voffA);
;             PG8_WAIT_V(8); PG8_WAIT_L(0); PG8_BAR; PG8_MMA(0, 0, At, B0); PG8_MMA(0, 1, At, B1); PG8_BAR; PG8_SCHED;
;             PG8_LDA(At, 0, 1); PG8_STAGE(PG8_SB(0, 0), b2, voffB); PG8_STAGE(PG8_SB(0, 1), b2 + hstepB, voffB); PG8_STAGE(PG8_SA(0, 0), a2, voffA);
;             PG8_WAIT_V(8); PG8_WAIT_L(0); PG8_BAR; PG8_MMA(1, 0, At, B0); PG8_MMA(1, 1, At, B1); PG8_BAR; PG8_SCHED;
.LBB0_3001:
	s_add_u32 s13, s16, 0x100
	s_addc_u32 s39, s17, 0
	s_mov_b32 s40, -2
	s_waitcnt vmcnt(0)
	ds_read_b128 v[152:155], v147
	ds_read_b128 v[156:159], v147 offset:1024
	ds_read_b128 v[160:163], v147 offset:2048
	ds_read_b128 v[164:167], v147 offset:3072
	ds_read_b128 v[168:171], v148
	ds_read_b128 v[172:175], v148 offset:1024
	ds_read_b128 v[176:179], v148 offset:2048
	ds_read_b128 v[180:183], v148 offset:3072
	s_add_u32 s16, s14, 0x100
	s_addc_u32 s17, s15, 0
	s_cmpk_eq_i32 s40, 0x54
	s_cselect_b32 s21, s11, s17
	s_cselect_b32 s20, s10, s16
	s_cselect_b32 s19, s3, s39
	s_cselect_b32 s18, s2, s13
	v_lshl_add_u64 v[216:217], s[14:15], 0, v[138:139]
	s_add_i32 m0, s24, 0xc000
	ds_read_b128 v[184:187], v149
	ds_read_b128 v[188:191], v149 offset:1024
	ds_read_b128 v[192:195], v149 offset:2048
	ds_read_b128 v[196:199], v149 offset:3072
	ds_read_b128 v[200:203], v149 offset:4096
	ds_read_b128 v[204:207], v149 offset:5120
	ds_read_b128 v[208:211], v149 offset:6144
	ds_read_b128 v[212:215], v149 offset:7168
	global_load_lds_dwordx4 v[216:217], off
	v_lshl_add_u64 v[216:217], s[14:15], 0, v[136:137]
	s_add_i32 m0, s24, 0xe000
	s_nop 0
	global_load_lds_dwordx4 v[216:217], off
	s_waitcnt lgkmcnt(0)
	s_barrier
	s_setprio 1
	s_waitcnt lgkmcnt(0)
	v_mfma_f32_16x16x32_bf16 v[124:127], v[152:155], v[184:187], 0
	v_mfma_f32_16x16x32_bf16 v[120:123], v[160:163], v[184:187], 0
	v_mfma_f32_16x16x32_bf16 v[112:115], v[152:155], v[192:195], 0
	v_mfma_f32_16x16x32_bf16 v[104:107], v[160:163], v[192:195], 0
	v_mfma_f32_16x16x32_bf16 v[92:95], v[152:155], v[200:203], 0
	v_mfma_f32_16x16x32_bf16 v[88:91], v[160:163], v[200:203], 0
	v_mfma_f32_16x16x32_bf16 v[76:79], v[152:155], v[208:211], 0
	v_mfma_f32_16x16x32_bf16 v[72:75], v[160:163], v[208:211], 0
	v_mfma_f32_16x16x32_bf16 v[124:127], v[156:159], v[188:191], v[124:127]
	v_mfma_f32_16x16x32_bf16 v[120:123], v[164:167], v[188:191], v[120:123]
	v_mfma_f32_16x16x32_bf16 v[112:115], v[156:159], v[196:199], v[112:115]
	v_mfma_f32_16x16x32_bf16 v[104:107], v[164:167], v[196:199], v[104:107]
	v_mfma_f32_16x16x32_bf16 v[92:95], v[156:159], v[204:207], v[92:95]
	v_mfma_f32_16x16x32_bf16 v[88:91], v[164:167], v[204:207], v[88:91]
	v_mfma_f32_16x16x32_bf16 v[76:79], v[156:159], v[212:215], v[76:79]
	v_mfma_f32_16x16x32_bf16 v[72:75], v[164:167], v[212:215], v[72:75]
	v_mfma_f32_16x16x32_bf16 v[116:119], v[168:171], v[184:187], 0
	v_mfma_f32_16x16x32_bf16 v[108:111], v[176:179], v[184:187], 0
	v_mfma_f32_16x16x32_bf16 v[100:103], v[168:171], v[192:195], 0
	v_mfma_f32_16x16x32_bf16 v[96:99], v[176:179], v[192:195], 0
	v_mfma_f32_16x16x32_bf16 v[84:87], v[168:171], v[200:203], 0
	v_mfma_f32_16x16x32_bf16 v[80:83], v[176:179], v[200:203], 0
	v_mfma_f32_16x16x32_bf16 v[68:71], v[168:171], v[208:211], 0
	v_mfma_f32_16x16x32_bf16 v[64:67], v[176:179], v[208:211], 0
	v_mfma_f32_16x16x32_bf16 v[116:119], v[172:175], v[188:191], v[116:119]
	v_mfma_f32_16x16x32_bf16 v[108:111], v[180:183], v[188:191], v[108:111]
	v_mfma_f32_16x16x32_bf16 v[100:103], v[172:175], v[196:199], v[100:103]
	v_mfma_f32_16x16x32_bf16 v[96:99], v[180:183], v[196:199], v[96:99]
	v_mfma_f32_16x16x32_bf16 v[84:87], v[172:175], v[204:207], v[84:87]
	v_mfma_f32_16x16x32_bf16 v[80:83], v[180:183], v[204:207], v[80:83]
	v_mfma_f32_16x16x32_bf16 v[68:71], v[172:175], v[212:215], v[68:71]
	v_mfma_f32_16x16x32_bf16 v[64:67], v[180:183], v[212:215], v[64:67]
	s_setprio 0
	s_barrier
	s_add_i32 s14, s34, s23
	v_lshl_add_u64 v[216:217], s[18:19], 0, v[130:131]
	s_mov_b32 m0, s14
	ds_read_b128 v[184:187], v149 offset:16384
	ds_read_b128 v[188:191], v149 offset:17408
	ds_read_b128 v[192:195], v149 offset:18432
	ds_read_b128 v[196:199], v149 offset:19456
	ds_read_b128 v[200:203], v149 offset:20480
	ds_read_b128 v[204:207], v149 offset:21504
	ds_read_b128 v[208:211], v149 offset:22528
	ds_read_b128 v[212:215], v149 offset:23552
	global_load_lds_dwordx4 v[216:217], off
	s_add_i32 m0, s14, 0x2000
	s_add_u32 s14, s18, 0x58000
	v_lshl_add_u64 v[218:219], s[18:19], 0, v[134:135]
	s_addc_u32 s15, s19, 0
	s_add_i32 s41, s35, s23
	global_load_lds_dwordx4 v[218:219], off
	v_lshl_add_u64 v[220:221], s[14:15], 0, v[130:131]
	s_mov_b32 m0, s41
	v_lshl_add_u64 v[222:223], s[20:21], 0, v[132:133]
	global_load_lds_dwordx4 v[220:221], off
	v_lshl_add_u64 v[220:221], s[14:15], 0, v[134:135]
	s_add_i32 m0, s41, 0x2000
	s_nop 0
	global_load_lds_dwordx4 v[220:221], off
	v_lshl_add_u64 v[220:221], s[20:21], 0, v[128:129]
	s_mov_b32 m0, s24
	s_nop 0
	global_load_lds_dwordx4 v[220:221], off
	s_mov_b32 m0, s25
	s_nop 0
	global_load_lds_dwordx4 v[222:223], off
	s_waitcnt lgkmcnt(0)
	s_barrier
; #define PG8_STAGE(bufoff, gbase, voff) do { _Pragma("unroll") for (int _i = 0; _i < 2; ++_i) \
;         __builtin_amdgcn_global_load_lds((const unsigned*)((const char*)(gbase) + (voff)[_i]), (LAS unsigned*)(lds + (bufoff) + ldsw + _i * 8192), 16, 0, 0); } while (0)
; #define PG8_LDA(dst, b, h) do { _Pragma("unroll") for (int m = 0; m < 4; ++m) _Pragma("unroll") for (int k = 0; k < 2; ++k) dst[m][k] = *(const LAS bf16x8*)(lds + PG8_SA(b, h) + aoff + m * 2048 + k * 1024); } while (0)
; #define PG8_LDB(dst, b, h) do { _Pragma("unroll") for (int n = 0; n < 2; ++n) _Pragma("unroll") for (int k = 0; k < 2; ++k) dst[n][k] = *(const LAS bf16x8*)(lds + PG8_SB(b, h) + boff + n * 2048 + k * 1024); } while (0)
; #define PG8_MMA(ai, bj, At, Bt) do { __builtin_amdgcn_s_setprio(1); _Pragma("unroll") for (int m = 0; m < 4; ++m) _Pragma("unroll") for (int n = 0; n < 2; ++n) _Pragma("unroll") for (int k = 0; k < 2; ++k) \
;         acc[ai][bj][m][n] = __builtin_amdgcn_mfma_f32_16x16x32_bf16(Bt[n][k], At[m][k], acc[ai][bj][m][n], 0, 0, 0); __builtin_amdgcn_s_setprio(0); } while (0)
; #define PG8_WAIT_V(n) asm volatile("s_waitcnt vmcnt(" #n ")" ::: "memory")
; #define PG8_WAIT_L(n) asm volatile("s_waitcnt lgkmcnt(" #n ")" ::: "memory")
; #define PG8_BAR __builtin_amdgcn_s_barrier()
; #define PG8_SCHED __builtin_amdgcn_sched_barrier(0)
; template <class Epi, class Sched, bool ALIGN_EPI = false, bool SP2 = false>
; __device__ __forceinline__ void gemm_phase(LAS unsigned char* lds, const Gemm g, const Sched& S, const Epi& E) {
;     ...
;             PG8_WAIT_V(8); PG8_WAIT_L(0); PG8_BAR; PG8_MMA(1, 0, At, B0); PG8_MMA(1, 1, At, B1); PG8_BAR; PG8_SCHED;
;             PG8_LDB(B0, 1, 0); PG8_LDB(B1, 1, 1); PG8_SCHED; PG8_LDA(At, 1, 0); PG8_STAGE(PG8_SA(0, 1), a2 + hstep, voffA);
;             PG8_WAIT_V(8); PG8_WAIT_L(0); PG8_BAR; PG8_MMA(0, 0, At, B0); PG8_MMA(0, 1, At, B1); PG8_BAR; PG8_SCHED;
	s_setprio 1
	s_waitcnt lgkmcnt(0)
	v_mfma_f32_16x16x32_bf16 v[60:63], v[152:155], v[184:187], 0
	v_mfma_f32_16x16x32_bf16 v[56:59], v[160:163], v[184:187], 0
	v_mfma_f32_16x16x32_bf16 v[44:47], v[152:155], v[192:195], 0
	v_mfma_f32_16x16x32_bf16 v[40:43], v[160:163], v[192:195], 0
	v_mfma_f32_16x16x32_bf16 v[28:31], v[152:155], v[200:203], 0
	v_mfma_f32_16x16x32_bf16 v[24:27], v[160:163], v[200:203], 0
	v_mfma_f32_16x16x32_bf16 v[12:15], v[152:155], v[208:211], 0
	v_mfma_f32_16x16x32_bf16 v[8:11], v[160:163], v[208:211], 0
	v_mfma_f32_16x16x32_bf16 v[60:63], v[156:159], v[188:191], v[60:63]
	v_mfma_f32_16x16x32_bf16 v[56:59], v[164:167], v[188:191], v[56:59]
	v_mfma_f32_16x16x32_bf16 v[44:47], v[156:159], v[196:199], v[44:47]
	v_mfma_f32_16x16x32_bf16 v[40:43], v[164:167], v[196:199], v[40:43]
	v_mfma_f32_16x16x32_bf16 v[28:31], v[156:159], v[204:207], v[28:31]
	v_mfma_f32_16x16x32_bf16 v[24:27], v[164:167], v[204:207], v[24:27]
	v_mfma_f32_16x16x32_bf16 v[12:15], v[156:159], v[212:215], v[12:15]
	v_mfma_f32_16x16x32_bf16 v[8:11], v[164:167], v[212:215], v[8:11]
	v_mfma_f32_16x16x32_bf16 v[52:55], v[168:171], v[184:187], 0
	v_mfma_f32_16x16x32_bf16 v[48:51], v[176:179], v[184:187], 0
	v_mfma_f32_16x16x32_bf16 v[36:39], v[168:171], v[192:195], 0
	v_mfma_f32_16x16x32_bf16 v[32:35], v[176:179], v[192:195], 0
	v_mfma_f32_16x16x32_bf16 v[20:23], v[168:171], v[200:203], 0
	v_mfma_f32_16x16x32_bf16 v[16:19], v[176:179], v[200:203], 0
	v_mfma_f32_16x16x32_bf16 v[4:7], v[168:171], v[208:211], 0
	v_mfma_f32_16x16x32_bf16 v[0:3], v[176:179], v[208:211], 0
	v_mfma_f32_16x16x32_bf16 v[52:55], v[172:175], v[188:191], v[52:55]
	v_mfma_f32_16x16x32_bf16 v[48:51], v[180:183], v[188:191], v[48:51]
	v_mfma_f32_16x16x32_bf16 v[36:39], v[172:175], v[196:199], v[36:39]
	v_mfma_f32_16x16x32_bf16 v[32:35], v[180:183], v[196:199], v[32:35]
	v_mfma_f32_16x16x32_bf16 v[20:23], v[172:175], v[204:207], v[20:23]
	v_mfma_f32_16x16x32_bf16 v[16:19], v[180:183], v[204:207], v[16:19]
	v_mfma_f32_16x16x32_bf16 v[4:7], v[172:175], v[212:215], v[4:7]
	v_mfma_f32_16x16x32_bf16 v[0:3], v[180:183], v[212:215], v[0:3]
	s_setprio 0
	s_barrier
	s_add_i32 s41, 0, 0x18000
	s_add_i32 s42, 0, 0x1c000
	v_add_u32_e32 v164, s41, v144
	v_add_u32_e32 v180, s42, v144
	ds_read_b128 v[152:155], v164
	ds_read_b128 v[156:159], v164 offset:1024
	ds_read_b128 v[160:163], v164 offset:2048
	ds_read_b128 v[164:167], v164 offset:3072
	ds_read_b128 v[168:171], v180
	ds_read_b128 v[172:175], v180 offset:1024
	ds_read_b128 v[176:179], v180 offset:2048
	ds_read_b128 v[180:183], v180 offset:3072
	s_add_u32 s14, s20, 0x160000
	s_addc_u32 s15, s21, 0
	s_mov_b32 m0, s26
	v_lshl_add_u64 v[224:225], s[14:15], 0, v[128:129]
	ds_read_b128 v[184:187], v149 offset:32768
	ds_read_b128 v[188:191], v149 offset:33792
	ds_read_b128 v[192:195], v149 offset:34816
	ds_read_b128 v[196:199], v149 offset:35840
	ds_read_b128 v[200:203], v149 offset:36864
	ds_read_b128 v[204:207], v149 offset:37888
	ds_read_b128 v[208:211], v149 offset:38912
	ds_read_b128 v[212:215], v149 offset:39936
	global_load_lds_dwordx4 v[224:225], off
	v_lshl_add_u64 v[224:225], s[14:15], 0, v[132:133]
	s_mov_b32 m0, s27
	s_nop 0
	global_load_lds_dwordx4 v[224:225], off
	s_waitcnt vmcnt(8)
	s_waitcnt lgkmcnt(0)
	s_barrier
	s_setprio 1
	s_waitcnt lgkmcnt(0)
	v_mfma_f32_16x16x32_bf16 v[124:127], v[152:155], v[184:187], v[124:127]
	v_mfma_f32_16x16x32_bf16 v[120:123], v[160:163], v[184:187], v[120:123]
	v_mfma_f32_16x16x32_bf16 v[112:115], v[152:155], v[192:195], v[112:115]
	v_mfma_f32_16x16x32_bf16 v[104:107], v[160:163], v[192:195], v[104:107]
	v_mfma_f32_16x16x32_bf16 v[92:95], v[152:155], v[200:203], v[92:95]
	v_mfma_f32_16x16x32_bf16 v[88:91], v[160:163], v[200:203], v[88:91]
	v_mfma_f32_16x16x32_bf16 v[76:79], v[152:155], v[208:211], v[76:79]
	v_mfma_f32_16x16x32_bf16 v[72:75], v[160:163], v[208:211], v[72:75]
	v_mfma_f32_16x16x32_bf16 v[124:127], v[156:159], v[188:191], v[124:127]
	v_mfma_f32_16x16x32_bf16 v[120:123], v[164:167], v[188:191], v[120:123]
	v_mfma_f32_16x16x32_bf16 v[112:115], v[156:159], v[196:199], v[112:115]
	v_mfma_f32_16x16x32_bf16 v[104:107], v[164:167], v[196:199], v[104:107]
	v_mfma_f32_16x16x32_bf16 v[92:95], v[156:159], v[204:207], v[92:95]
	v_mfma_f32_16x16x32_bf16 v[88:91], v[164:167], v[204:207], v[88:91]
	v_mfma_f32_16x16x32_bf16 v[76:79], v[156:159], v[212:215], v[76:79]
	v_mfma_f32_16x16x32_bf16 v[72:75], v[164:167], v[212:215], v[72:75]
	v_mfma_f32_16x16x32_bf16 v[116:119], v[168:171], v[184:187], v[116:119]
	v_mfma_f32_16x16x32_bf16 v[108:111], v[176:179], v[184:187], v[108:111]
	v_mfma_f32_16x16x32_bf16 v[100:103], v[168:171], v[192:195], v[100:103]
	v_mfma_f32_16x16x32_bf16 v[96:99], v[176:179], v[192:195], v[96:99]
	v_mfma_f32_16x16x32_bf16 v[84:87], v[168:171], v[200:203], v[84:87]
	v_mfma_f32_16x16x32_bf16 v[80:83], v[176:179], v[200:203], v[80:83]
	v_mfma_f32_16x16x32_bf16 v[68:71], v[168:171], v[208:211], v[68:71]
	v_mfma_f32_16x16x32_bf16 v[64:67], v[176:179], v[208:211], v[64:67]
	v_mfma_f32_16x16x32_bf16 v[116:119], v[172:175], v[188:191], v[116:119]
	v_mfma_f32_16x16x32_bf16 v[108:111], v[180:183], v[188:191], v[108:111]
	v_mfma_f32_16x16x32_bf16 v[100:103], v[172:175], v[196:199], v[100:103]
	v_mfma_f32_16x16x32_bf16 v[96:99], v[180:183], v[196:199], v[96:99]
	v_mfma_f32_16x16x32_bf16 v[84:87], v[172:175], v[204:207], v[84:87]
	v_mfma_f32_16x16x32_bf16 v[80:83], v[180:183], v[204:207], v[80:83]
	v_mfma_f32_16x16x32_bf16 v[68:71], v[172:175], v[212:215], v[68:71]
	v_mfma_f32_16x16x32_bf16 v[64:67], v[180:183], v[212:215], v[64:67]
	s_setprio 0
	s_barrier
; #define PG8_STAGE(bufoff, gbase, voff) do { _Pragma("unroll") for (int _i = 0; _i < 2; ++_i) \
;         __builtin_amdgcn_global_load_lds((const unsigned*)((const char*)(gbase) + (voff)[_i]), (LAS unsigned*)(lds + (bufoff) + ldsw + _i * 8192), 16, 0, 0); } while (0)
; #define PG8_LDA(dst, b, h) do { _Pragma("unroll") for (int m = 0; m < 4; ++m) _Pragma("unroll") for (int k = 0; k < 2; ++k) dst[m][k] = *(const LAS bf16x8*)(lds + PG8_SA(b, h) + aoff + m * 2048 + k * 1024); } while (0)
; #define PG8_LDB(dst, b, h) do { _Pragma("unroll") for (int n = 0; n < 2; ++n) _Pragma("unroll") for (int k = 0; k < 2; ++k) dst[n][k] = *(const LAS bf16x8*)(lds + PG8_SB(b, h) + boff + n * 2048 + k * 1024); } while (0)
; #define PG8_MMA(ai, bj, At, Bt) do { __builtin_amdgcn_s_setprio(1); _Pragma("unroll") for (int m = 0; m < 4; ++m) _Pragma("unroll") for (int n = 0; n < 2; ++n) _Pragma("unroll") for (int k = 0; k < 2; ++k) \
;         acc[ai][bj][m][n] = __builtin_amdgcn_mfma_f32_16x16x32_bf16(Bt[n][k], At[m][k], acc[ai][bj][m][n], 0, 0, 0); __builtin_amdgcn_s_setprio(0); } while (0)
; #define PG8_WAIT_V(n) asm volatile("s_waitcnt vmcnt(" #n ")" ::: "memory")
; template <class Epi, class Sched, bool ALIGN_EPI = false, bool SP2 = false>
; __device__ __forceinline__ void gemm_phase(LAS unsigned char* lds, const Gemm g, const Sched& S, const Epi& E) {
;     ...
;             PG8_LDB(B0, 0, 0); PG8_LDB(B1, 0, 1); PG8_SCHED; PG8_LDA(At, 0, 0); PG8_STAGE(PG8_SA(1, 1), a1 + hstep, voffA);
;             PG8_WAIT_V(8); PG8_WAIT_L(0); PG8_BAR; PG8_MMA(0, 0, At, B0); PG8_MMA(0, 1, At, B1); PG8_BAR; PG8_SCHED;
;             PG8_LDA(At, 0, 1); PG8_STAGE(PG8_SB(0, 0), b2, voffB); PG8_STAGE(PG8_SB(0, 1), b2 + hstepB, voffB); PG8_STAGE(PG8_SA(0, 0), a2, voffA);
;             PG8_WAIT_V(8); PG8_WAIT_L(0); PG8_BAR; PG8_MMA(1, 0, At, B0); PG8_MMA(1, 1, At, B1); PG8_BAR; PG8_SCHED;
;             PG8_LDB(B0, 1, 0); PG8_LDB(B1, 1, 1); PG8_SCHED; PG8_LDA(At, 1, 0); PG8_STAGE(PG8_SA(0, 1), a2 + hstep, voffA);
;             PG8_WAIT_V(8); PG8_WAIT_L(0); PG8_BAR; PG8_MMA(0, 0, At, B0); PG8_MMA(0, 1, At, B1); PG8_BAR; PG8_SCHED;
;             PG8_LDA(At, 1, 1); PG8_STAGE(PG8_SB(1, 0), b3, voffB); PG8_STAGE(PG8_SB(1, 1), b3 + hstepB, voffB); PG8_STAGE(PG8_SA(1, 0), a3, voffA);
;             PG8_WAIT_V(8); PG8_WAIT_L(0); PG8_BAR; PG8_MMA(1, 0, At, B0); PG8_MMA(1, 1, At, B1); PG8_BAR; PG8_SCHED;
	s_add_i32 s14, s41, s23
	v_lshl_add_u64 v[216:217], v[216:217], 0, s[6:7]
	s_mov_b32 m0, s14
	ds_read_b128 v[184:187], v149 offset:49152
	ds_read_b128 v[188:191], v149 offset:50176
	ds_read_b128 v[192:195], v149 offset:51200
	ds_read_b128 v[196:199], v149 offset:52224
	ds_read_b128 v[200:203], v149 offset:53248
	ds_read_b128 v[204:207], v149 offset:54272
	ds_read_b128 v[208:211], v149 offset:55296
	ds_read_b128 v[212:215], v149 offset:56320
	global_load_lds_dwordx4 v[216:217], off
	s_add_i32 m0, s14, 0x2000
	s_add_u32 s14, s18, 0x58080
	v_lshl_add_u64 v[216:217], v[218:219], 0, s[6:7]
	s_addc_u32 s15, s19, 0
	s_add_i32 s18, s42, s23
	global_load_lds_dwordx4 v[216:217], off
	v_lshl_add_u64 v[216:217], s[14:15], 0, v[130:131]
	s_mov_b32 m0, s18
	s_nop 0
	global_load_lds_dwordx4 v[216:217], off
	v_lshl_add_u64 v[216:217], s[14:15], 0, v[134:135]
	s_add_i32 m0, s18, 0x2000
	s_nop 0
	global_load_lds_dwordx4 v[216:217], off
	v_lshl_add_u64 v[216:217], v[220:221], 0, s[6:7]
	s_mov_b32 m0, s31
	s_nop 0
	global_load_lds_dwordx4 v[216:217], off
	v_lshl_add_u64 v[216:217], v[222:223], 0, s[6:7]
	s_mov_b32 m0, s33
	s_nop 0
	global_load_lds_dwordx4 v[216:217], off
	s_waitcnt vmcnt(8)
	s_waitcnt lgkmcnt(0)
	s_barrier
	s_setprio 1
	s_waitcnt lgkmcnt(0)
	v_mfma_f32_16x16x32_bf16 v[60:63], v[152:155], v[184:187], v[60:63]
	v_mfma_f32_16x16x32_bf16 v[56:59], v[160:163], v[184:187], v[56:59]
	v_mfma_f32_16x16x32_bf16 v[44:47], v[152:155], v[192:195], v[44:47]
	v_mfma_f32_16x16x32_bf16 v[40:43], v[160:163], v[192:195], v[40:43]
	v_mfma_f32_16x16x32_bf16 v[28:31], v[152:155], v[200:203], v[28:31]
	v_mfma_f32_16x16x32_bf16 v[24:27], v[160:163], v[200:203], v[24:27]
	v_mfma_f32_16x16x32_bf16 v[12:15], v[152:155], v[208:211], v[12:15]
	v_mfma_f32_16x16x32_bf16 v[8:11], v[160:163], v[208:211], v[8:11]
	v_mfma_f32_16x16x32_bf16 v[60:63], v[156:159], v[188:191], v[60:63]
	v_mfma_f32_16x16x32_bf16 v[56:59], v[164:167], v[188:191], v[56:59]
	v_mfma_f32_16x16x32_bf16 v[44:47], v[156:159], v[196:199], v[44:47]
	v_mfma_f32_16x16x32_bf16 v[40:43], v[164:167], v[196:199], v[40:43]
	v_mfma_f32_16x16x32_bf16 v[28:31], v[156:159], v[204:207], v[28:31]
	v_mfma_f32_16x16x32_bf16 v[24:27], v[164:167], v[204:207], v[24:27]
	v_mfma_f32_16x16x32_bf16 v[12:15], v[156:159], v[212:215], v[12:15]
	v_mfma_f32_16x16x32_bf16 v[8:11], v[164:167], v[212:215], v[8:11]
	v_mfma_f32_16x16x32_bf16 v[52:55], v[168:171], v[184:187], v[52:55]
	v_mfma_f32_16x16x32_bf16 v[48:51], v[176:179], v[184:187], v[48:51]
	v_mfma_f32_16x16x32_bf16 v[36:39], v[168:171], v[192:195], v[36:39]
	v_mfma_f32_16x16x32_bf16 v[32:35], v[176:179], v[192:195], v[32:35]
	v_mfma_f32_16x16x32_bf16 v[20:23], v[168:171], v[200:203], v[20:23]
	v_mfma_f32_16x16x32_bf16 v[16:19], v[176:179], v[200:203], v[16:19]
	v_mfma_f32_16x16x32_bf16 v[4:7], v[168:171], v[208:211], v[4:7]
	v_mfma_f32_16x16x32_bf16 v[0:3], v[176:179], v[208:211], v[0:3]
	v_mfma_f32_16x16x32_bf16 v[52:55], v[172:175], v[188:191], v[52:55]
	v_mfma_f32_16x16x32_bf16 v[48:51], v[180:183], v[188:191], v[48:51]
	v_mfma_f32_16x16x32_bf16 v[36:39], v[172:175], v[196:199], v[36:39]
	v_mfma_f32_16x16x32_bf16 v[32:35], v[180:183], v[196:199], v[32:35]
	v_mfma_f32_16x16x32_bf16 v[20:23], v[172:175], v[204:207], v[20:23]
	v_mfma_f32_16x16x32_bf16 v[16:19], v[180:183], v[204:207], v[16:19]
	v_mfma_f32_16x16x32_bf16 v[4:7], v[172:175], v[212:215], v[4:7]
	v_mfma_f32_16x16x32_bf16 v[0:3], v[180:183], v[212:215], v[0:3]
	s_setprio 0
	s_barrier
	s_add_i32 s40, s40, 2
	s_add_u32 s13, s13, 0x100
	s_addc_u32 s39, s39, 0
	s_cmpk_lt_u32 s40, 0x56
	s_mov_b64 s[14:15], s[16:17]
.LBB0_3002:
	ds_read_b128 v[152:155], v147
	ds_read_b128 v[156:159], v147 offset:1024
	ds_read_b128 v[160:163], v147 offset:2048
	ds_read_b128 v[164:167], v147 offset:3072
	ds_read_b128 v[168:171], v148
	ds_read_b128 v[172:175], v148 offset:1024
	ds_read_b128 v[176:179], v148 offset:2048
	ds_read_b128 v[180:183], v148 offset:3072
	s_add_u32 s16, s14, 0x100
	s_addc_u32 s17, s15, 0
	s_cmpk_eq_i32 s40, 0x54
	s_cselect_b32 s21, s11, s17
	s_cselect_b32 s20, s10, s16
	s_cselect_b32 s19, s3, s39
	s_cselect_b32 s18, s2, s13
	v_lshl_add_u64 v[216:217], s[14:15], 0, v[138:139]
	s_add_i32 m0, s24, 0xc000
	ds_read_b128 v[184:187], v149
	ds_read_b128 v[188:191], v149 offset:1024
	ds_read_b128 v[192:195], v149 offset:2048
	ds_read_b128 v[196:199], v149 offset:3072
	ds_read_b128 v[200:203], v149 offset:4096
	ds_read_b128 v[204:207], v149 offset:5120
	ds_read_b128 v[208:211], v149 offset:6144
	ds_read_b128 v[212:215], v149 offset:7168
	global_load_lds_dwordx4 v[216:217], off
	v_lshl_add_u64 v[216:217], s[14:15], 0, v[136:137]
	s_add_i32 m0, s24, 0xe000
	s_nop 0
	global_load_lds_dwordx4 v[216:217], off
	s_waitcnt vmcnt(8)
	s_waitcnt lgkmcnt(0)
	s_barrier
; #define PG8_STAGE(bufoff, gbase, voff) do { _Pragma("unroll") for (int _i = 0; _i < 2; ++_i) \
;         __builtin_amdgcn_global_load_lds((const unsigned*)((const char*)(gbase) + (voff)[_i]), (LAS unsigned*)(lds + (bufoff) + ldsw + _i * 8192), 16, 0, 0); } while (0)
; #define PG8_LDA(dst, b, h) do { _Pragma("unroll") for (int m = 0; m < 4; ++m) _Pragma("unroll") for (int k = 0; k < 2; ++k) dst[m][k] = *(const LAS bf16x8*)(lds + PG8_SA(b, h) + aoff + m * 2048 + k * 1024); } while (0)
; #define PG8_MMA(ai, bj, At, Bt) do { __builtin_amdgcn_s_setprio(1); _Pragma("unroll") for (int m = 0; m < 4; ++m) _Pragma("unroll") for (int n = 0; n < 2; ++n) _Pragma("unroll") for (int k = 0; k < 2; ++k) \
;         acc[ai][bj][m][n] = __builtin_amdgcn_mfma_f32_16x16x32_bf16(Bt[n][k], At[m][k], acc[ai][bj][m][n], 0, 0, 0); __builtin_amdgcn_s_setprio(0); } while (0)
; #define PG8_WAIT_V(n) asm volatile("s_waitcnt vmcnt(" #n ")" ::: "memory")
; #define PG8_WAIT_L(n) asm volatile("s_waitcnt lgkmcnt(" #n ")" ::: "memory")
; #define PG8_BAR __builtin_amdgcn_s_barrier()
; #define PG8_SCHED __builtin_amdgcn_sched_barrier(0)
; template <class Epi, class Sched, bool ALIGN_EPI = false, bool SP2 = false>
; __device__ __forceinline__ void gemm_phase(LAS unsigned char* lds, const Gemm g, const Sched& S, const Epi& E) {
;     ...
;             PG8_WAIT_V(8); PG8_WAIT_L(0); PG8_BAR; PG8_MMA(0, 0, At, B0); PG8_MMA(0, 1, At, B1); PG8_BAR; PG8_SCHED;
;             PG8_LDA(At, 0, 1); PG8_STAGE(PG8_SB(0, 0), b2, voffB); PG8_STAGE(PG8_SB(0, 1), b2 + hstepB, voffB); PG8_STAGE(PG8_SA(0, 0), a2, voffA);
;             PG8_WAIT_V(8); PG8_WAIT_L(0); PG8_BAR; PG8_MMA(1, 0, At, B0); PG8_MMA(1, 1, At, B1); PG8_BAR; PG8_SCHED;
	s_setprio 1
	s_waitcnt lgkmcnt(0)
	v_mfma_f32_16x16x32_bf16 v[124:127], v[152:155], v[184:187], v[124:127]
	v_mfma_f32_16x16x32_bf16 v[120:123], v[160:163], v[184:187], v[120:123]
	v_mfma_f32_16x16x32_bf16 v[112:115], v[152:155], v[192:195], v[112:115]
	v_mfma_f32_16x16x32_bf16 v[104:107], v[160:163], v[192:195], v[104:107]
	v_mfma_f32_16x16x32_bf16 v[92:95], v[152:155], v[200:203], v[92:95]
	v_mfma_f32_16x16x32_bf16 v[88:91], v[160:163], v[200:203], v[88:91]
	v_mfma_f32_16x16x32_bf16 v[76:79], v[152:155], v[208:211], v[76:79]
	v_mfma_f32_16x16x32_bf16 v[72:75], v[160:163], v[208:211], v[72:75]
	v_mfma_f32_16x16x32_bf16 v[124:127], v[156:159], v[188:191], v[124:127]
	v_mfma_f32_16x16x32_bf16 v[120:123], v[164:167], v[188:191], v[120:123]
	v_mfma_f32_16x16x32_bf16 v[112:115], v[156:159], v[196:199], v[112:115]
	v_mfma_f32_16x16x32_bf16 v[104:107], v[164:167], v[196:199], v[104:107]
	v_mfma_f32_16x16x32_bf16 v[92:95], v[156:159], v[204:207], v[92:95]
	v_mfma_f32_16x16x32_bf16 v[88:91], v[164:167], v[204:207], v[88:91]
	v_mfma_f32_16x16x32_bf16 v[76:79], v[156:159], v[212:215], v[76:79]
	v_mfma_f32_16x16x32_bf16 v[72:75], v[164:167], v[212:215], v[72:75]
	v_mfma_f32_16x16x32_bf16 v[116:119], v[168:171], v[184:187], v[116:119]
	v_mfma_f32_16x16x32_bf16 v[108:111], v[176:179], v[184:187], v[108:111]
	v_mfma_f32_16x16x32_bf16 v[100:103], v[168:171], v[192:195], v[100:103]
	v_mfma_f32_16x16x32_bf16 v[96:99], v[176:179], v[192:195], v[96:99]
	v_mfma_f32_16x16x32_bf16 v[84:87], v[168:171], v[200:203], v[84:87]
	v_mfma_f32_16x16x32_bf16 v[80:83], v[176:179], v[200:203], v[80:83]
	v_mfma_f32_16x16x32_bf16 v[68:71], v[168:171], v[208:211], v[68:71]
	v_mfma_f32_16x16x32_bf16 v[64:67], v[176:179], v[208:211], v[64:67]
	v_mfma_f32_16x16x32_bf16 v[116:119], v[172:175], v[188:191], v[116:119]
	v_mfma_f32_16x16x32_bf16 v[108:111], v[180:183], v[188:191], v[108:111]
	v_mfma_f32_16x16x32_bf16 v[100:103], v[172:175], v[196:199], v[100:103]
	v_mfma_f32_16x16x32_bf16 v[96:99], v[180:183], v[196:199], v[96:99]
	v_mfma_f32_16x16x32_bf16 v[84:87], v[172:175], v[204:207], v[84:87]
	v_mfma_f32_16x16x32_bf16 v[80:83], v[180:183], v[204:207], v[80:83]
	v_mfma_f32_16x16x32_bf16 v[68:71], v[172:175], v[212:215], v[68:71]
	v_mfma_f32_16x16x32_bf16 v[64:67], v[180:183], v[212:215], v[64:67]
	s_setprio 0
	s_barrier
	s_add_i32 s14, s34, s23
	v_lshl_add_u64 v[216:217], s[18:19], 0, v[130:131]
	s_mov_b32 m0, s14
	ds_read_b128 v[184:187], v149 offset:16384
	ds_read_b128 v[188:191], v149 offset:17408
	ds_read_b128 v[192:195], v149 offset:18432
	ds_read_b128 v[196:199], v149 offset:19456
	ds_read_b128 v[200:203], v149 offset:20480
	ds_read_b128 v[204:207], v149 offset:21504
	ds_read_b128 v[208:211], v149 offset:22528
	ds_read_b128 v[212:215], v149 offset:23552
	global_load_lds_dwordx4 v[216:217], off
	s_add_i32 m0, s14, 0x2000
	s_add_u32 s14, s18, 0x58000
	v_lshl_add_u64 v[218:219], s[18:19], 0, v[134:135]
	s_addc_u32 s15, s19, 0
	s_add_i32 s41, s35, s23
	global_load_lds_dwordx4 v[218:219], off
	v_lshl_add_u64 v[220:221], s[14:15], 0, v[130:131]
	s_mov_b32 m0, s41
	v_lshl_add_u64 v[222:223], s[20:21], 0, v[132:133]
	global_load_lds_dwordx4 v[220:221], off
	v_lshl_add_u64 v[220:221], s[14:15], 0, v[134:135]
	s_add_i32 m0, s41, 0x2000
	s_nop 0
	global_load_lds_dwordx4 v[220:221], off
	v_lshl_add_u64 v[220:221], s[20:21], 0, v[128:129]
	s_mov_b32 m0, s24
	s_nop 0
	global_load_lds_dwordx4 v[220:221], off
	s_mov_b32 m0, s25
	s_nop 0
	global_load_lds_dwordx4 v[222:223], off
	s_waitcnt vmcnt(8)
	s_waitcnt lgkmcnt(0)
	s_barrier
	s_setprio 1
	s_waitcnt lgkmcnt(0)
	v_mfma_f32_16x16x32_bf16 v[60:63], v[152:155], v[184:187], v[60:63]
	v_mfma_f32_16x16x32_bf16 v[56:59], v[160:163], v[184:187], v[56:59]
	v_mfma_f32_16x16x32_bf16 v[44:47], v[152:155], v[192:195], v[44:47]
	v_mfma_f32_16x16x32_bf16 v[40:43], v[160:163], v[192:195], v[40:43]
	v_mfma_f32_16x16x32_bf16 v[28:31], v[152:155], v[200:203], v[28:31]
	v_mfma_f32_16x16x32_bf16 v[24:27], v[160:163], v[200:203], v[24:27]
	v_mfma_f32_16x16x32_bf16 v[12:15], v[152:155], v[208:211], v[12:15]
	v_mfma_f32_16x16x32_bf16 v[8:11], v[160:163], v[208:211], v[8:11]
	v_mfma_f32_16x16x32_bf16 v[60:63], v[156:159], v[188:191], v[60:63]
	v_mfma_f32_16x16x32_bf16 v[56:59], v[164:167], v[188:191], v[56:59]
	v_mfma_f32_16x16x32_bf16 v[44:47], v[156:159], v[196:199], v[44:47]
	v_mfma_f32_16x16x32_bf16 v[40:43], v[164:167], v[196:199], v[40:43]
	v_mfma_f32_16x16x32_bf16 v[28:31], v[156:159], v[204:207], v[28:31]
	v_mfma_f32_16x16x32_bf16 v[24:27], v[164:167], v[204:207], v[24:27]
	v_mfma_f32_16x16x32_bf16 v[12:15], v[156:159], v[212:215], v[12:15]
	v_mfma_f32_16x16x32_bf16 v[8:11], v[164:167], v[212:215], v[8:11]
	v_mfma_f32_16x16x32_bf16 v[52:55], v[168:171], v[184:187], v[52:55]
	v_mfma_f32_16x16x32_bf16 v[48:51], v[176:179], v[184:187], v[48:51]
	v_mfma_f32_16x16x32_bf16 v[36:39], v[168:171], v[192:195], v[36:39]
	v_mfma_f32_16x16x32_bf16 v[32:35], v[176:179], v[192:195], v[32:35]
	v_mfma_f32_16x16x32_bf16 v[20:23], v[168:171], v[200:203], v[20:23]
	v_mfma_f32_16x16x32_bf16 v[16:19], v[176:179], v[200:203], v[16:19]
	v_mfma_f32_16x16x32_bf16 v[4:7], v[168:171], v[208:211], v[4:7]
	v_mfma_f32_16x16x32_bf16 v[0:3], v[176:179], v[208:211], v[0:3]
	v_mfma_f32_16x16x32_bf16 v[52:55], v[172:175], v[188:191], v[52:55]
	v_mfma_f32_16x16x32_bf16 v[48:51], v[180:183], v[188:191], v[48:51]
	v_mfma_f32_16x16x32_bf16 v[36:39], v[172:175], v[196:199], v[36:39]
	v_mfma_f32_16x16x32_bf16 v[32:35], v[180:183], v[196:199], v[32:35]
	v_mfma_f32_16x16x32_bf16 v[20:23], v[172:175], v[204:207], v[20:23]
	v_mfma_f32_16x16x32_bf16 v[16:19], v[180:183], v[204:207], v[16:19]
	v_mfma_f32_16x16x32_bf16 v[4:7], v[172:175], v[212:215], v[4:7]
	v_mfma_f32_16x16x32_bf16 v[0:3], v[180:183], v[212:215], v[0:3]
	s_setprio 0
	s_barrier
; #define PG8_STAGE(bufoff, gbase, voff) do { _Pragma("unroll") for (int _i = 0; _i < 2; ++_i) \
;         __builtin_amdgcn_global_load_lds((const unsigned*)((const char*)(gbase) + (voff)[_i]), (LAS unsigned*)(lds + (bufoff) + ldsw + _i * 8192), 16, 0, 0); } while (0)
; #define PG8_LDA(dst, b, h) do { _Pragma("unroll") for (int m = 0; m < 4; ++m) _Pragma("unroll") for (int k = 0; k < 2; ++k) dst[m][k] = *(const LAS bf16x8*)(lds + PG8_SA(b, h) + aoff + m * 2048 + k * 1024); } while (0)
; #define PG8_LDB(dst, b, h) do { _Pragma("unroll") for (int n = 0; n < 2; ++n) _Pragma("unroll") for (int k = 0; k < 2; ++k) dst[n][k] = *(const LAS bf16x8*)(lds + PG8_SB(b, h) + boff + n * 2048 + k * 1024); } while (0)
; #define PG8_MMA(ai, bj, At, Bt) do { __builtin_amdgcn_s_setprio(1); _Pragma("unroll") for (int m = 0; m < 4; ++m) _Pragma("unroll") for (int n = 0; n < 2; ++n) _Pragma("unroll") for (int k = 0; k < 2; ++k) \
;         acc[ai][bj][m][n] = __builtin_amdgcn_mfma_f32_16x16x32_bf16(Bt[n][k], At[m][k], acc[ai][bj][m][n], 0, 0, 0); __builtin_amdgcn_s_setprio(0); } while (0)
; #define PG8_WAIT_V(n) asm volatile("s_waitcnt vmcnt(" #n ")" ::: "memory")
; #define PG8_WAIT_L(n) asm volatile("s_waitcnt lgkmcnt(" #n ")" ::: "memory")
; #define PG8_BAR __builtin_amdgcn_s_barrier()
; #define PG8_SCHED __builtin_amdgcn_sched_barrier(0)
; template <class Epi, class Sched, bool ALIGN_EPI = false, bool SP2 = false>
; __device__ __forceinline__ void gemm_phase(LAS unsigned char* lds, const Gemm g, const Sched& S, const Epi& E) {
;     ...
;             PG8_LDB(B0, 1, 0); PG8_LDB(B1, 1, 1); PG8_SCHED; PG8_LDA(At, 1, 0); PG8_STAGE(PG8_SA(0, 1), a2 + hstep, voffA);
;             PG8_WAIT_V(8); PG8_WAIT_L(0); PG8_BAR; PG8_MMA(0, 0, At, B0); PG8_MMA(0, 1, At, B1); PG8_BAR; PG8_SCHED;
	s_add_i32 s41, 0, 0x18000
	s_add_i32 s42, 0, 0x1c000
	v_add_u32_e32 v164, s41, v144
	v_add_u32_e32 v180, s42, v144
	ds_read_b128 v[152:155], v164
	ds_read_b128 v[156:159], v164 offset:1024
	ds_read_b128 v[160:163], v164 offset:2048
	ds_read_b128 v[164:167], v164 offset:3072
	ds_read_b128 v[168:171], v180
	ds_read_b128 v[172:175], v180 offset:1024
	ds_read_b128 v[176:179], v180 offset:2048
	ds_read_b128 v[180:183], v180 offset:3072
	s_add_u32 s14, s20, 0x160000
	s_addc_u32 s15, s21, 0
	s_mov_b32 m0, s26
	v_lshl_add_u64 v[224:225], s[14:15], 0, v[128:129]
	ds_read_b128 v[184:187], v149 offset:32768
	ds_read_b128 v[188:191], v149 offset:33792
	ds_read_b128 v[192:195], v149 offset:34816
	ds_read_b128 v[196:199], v149 offset:35840
	ds_read_b128 v[200:203], v149 offset:36864
	ds_read_b128 v[204:207], v149 offset:37888
	ds_read_b128 v[208:211], v149 offset:38912
	ds_read_b128 v[212:215], v149 offset:39936
	global_load_lds_dwordx4 v[224:225], off
	v_lshl_add_u64 v[224:225], s[14:15], 0, v[132:133]
	s_mov_b32 m0, s27
	s_nop 0
	global_load_lds_dwordx4 v[224:225], off
	s_waitcnt vmcnt(8)
	s_waitcnt lgkmcnt(0)
	s_barrier
	s_setprio 1
	s_waitcnt lgkmcnt(0)
	v_mfma_f32_16x16x32_bf16 v[124:127], v[152:155], v[184:187], v[124:127]
	v_mfma_f32_16x16x32_bf16 v[120:123], v[160:163], v[184:187], v[120:123]
	v_mfma_f32_16x16x32_bf16 v[112:115], v[152:155], v[192:195], v[112:115]
	v_mfma_f32_16x16x32_bf16 v[104:107], v[160:163], v[192:195], v[104:107]
	v_mfma_f32_16x16x32_bf16 v[92:95], v[152:155], v[200:203], v[92:95]
	v_mfma_f32_16x16x32_bf16 v[88:91], v[160:163], v[200:203], v[88:91]
	v_mfma_f32_16x16x32_bf16 v[76:79], v[152:155], v[208:211], v[76:79]
	v_mfma_f32_16x16x32_bf16 v[72:75], v[160:163], v[208:211], v[72:75]
	v_mfma_f32_16x16x32_bf16 v[124:127], v[156:159], v[188:191], v[124:127]
	v_mfma_f32_16x16x32_bf16 v[120:123], v[164:167], v[188:191], v[120:123]
	v_mfma_f32_16x16x32_bf16 v[112:115], v[156:159], v[196:199], v[112:115]
	v_mfma_f32_16x16x32_bf16 v[104:107], v[164:167], v[196:199], v[104:107]
	v_mfma_f32_16x16x32_bf16 v[92:95], v[156:159], v[204:207], v[92:95]
	v_mfma_f32_16x16x32_bf16 v[88:91], v[164:167], v[204:207], v[88:91]
	v_mfma_f32_16x16x32_bf16 v[76:79], v[156:159], v[212:215], v[76:79]
	v_mfma_f32_16x16x32_bf16 v[72:75], v[164:167], v[212:215], v[72:75]
	v_mfma_f32_16x16x32_bf16 v[116:119], v[168:171], v[184:187], v[116:119]
	v_mfma_f32_16x16x32_bf16 v[108:111], v[176:179], v[184:187], v[108:111]
	v_mfma_f32_16x16x32_bf16 v[100:103], v[168:171], v[192:195], v[100:103]
	v_mfma_f32_16x16x32_bf16 v[96:99], v[176:179], v[192:195], v[96:99]
	v_mfma_f32_16x16x32_bf16 v[84:87], v[168:171], v[200:203], v[84:87]
	v_mfma_f32_16x16x32_bf16 v[80:83], v[176:179], v[200:203], v[80:83]
	v_mfma_f32_16x16x32_bf16 v[68:71], v[168:171], v[208:211], v[68:71]
	v_mfma_f32_16x16x32_bf16 v[64:67], v[176:179], v[208:211], v[64:67]
	v_mfma_f32_16x16x32_bf16 v[116:119], v[172:175], v[188:191], v[116:119]
	v_mfma_f32_16x16x32_bf16 v[108:111], v[180:183], v[188:191], v[108:111]
	v_mfma_f32_16x16x32_bf16 v[100:103], v[172:175], v[196:199], v[100:103]
	v_mfma_f32_16x16x32_bf16 v[96:99], v[180:183], v[196:199], v[96:99]
	v_mfma_f32_16x16x32_bf16 v[84:87], v[172:175], v[204:207], v[84:87]
	v_mfma_f32_16x16x32_bf16 v[80:83], v[180:183], v[204:207], v[80:83]
	v_mfma_f32_16x16x32_bf16 v[68:71], v[172:175], v[212:215], v[68:71]
	v_mfma_f32_16x16x32_bf16 v[64:67], v[180:183], v[212:215], v[64:67]
	s_setprio 0
	s_barrier
; #define PG8_STAGE(bufoff, gbase, voff) do { _Pragma("unroll") for (int _i = 0; _i < 2; ++_i) \
;         __builtin_amdgcn_global_load_lds((const unsigned*)((const char*)(gbase) + (voff)[_i]), (LAS unsigned*)(lds + (bufoff) + ldsw + _i * 8192), 16, 0, 0); } while (0)
; #define PG8_LDA(dst, b, h) do { _Pragma("unroll") for (int m = 0; m < 4; ++m) _Pragma("unroll") for (int k = 0; k < 2; ++k) dst[m][k] = *(const LAS bf16x8*)(lds + PG8_SA(b, h) + aoff + m * 2048 + k * 1024); } while (0)
; #define PG8_MMA(ai, bj, At, Bt) do { __builtin_amdgcn_s_setprio(1); _Pragma("unroll") for (int m = 0; m < 4; ++m) _Pragma("unroll") for (int n = 0; n < 2; ++n) _Pragma("unroll") for (int k = 0; k < 2; ++k) \
;         acc[ai][bj][m][n] = __builtin_amdgcn_mfma_f32_16x16x32_bf16(Bt[n][k], At[m][k], acc[ai][bj][m][n], 0, 0, 0); __builtin_amdgcn_s_setprio(0); } while (0)
; #define PG8_WAIT_V(n) asm volatile("s_waitcnt vmcnt(" #n ")" ::: "memory")
; #define PG8_WAIT_L(n) asm volatile("s_waitcnt lgkmcnt(" #n ")" ::: "memory")
; #define PG8_BAR __builtin_amdgcn_s_barrier()
; #define PG8_SCHED __builtin_amdgcn_sched_barrier(0)
; template <class Epi, class Sched, bool ALIGN_EPI = false, bool SP2 = false>
; __device__ __forceinline__ void gemm_phase(LAS unsigned char* lds, const Gemm g, const Sched& S, const Epi& E) {
;     ...
;             PG8_LDA(At, 1, 1); PG8_STAGE(PG8_SB(1, 0), b3, voffB); PG8_STAGE(PG8_SB(1, 1), b3 + hstepB, voffB); PG8_STAGE(PG8_SA(1, 0), a3, voffA);
;             PG8_WAIT_V(8); PG8_WAIT_L(0); PG8_BAR; PG8_MMA(1, 0, At, B0); PG8_MMA(1, 1, At, B1); PG8_BAR; PG8_SCHED;
;     ...
;         if constexpr (ALIGN_EPI) { if (wr == 0) PG8_BAR; }
;         if constexpr (!Epi::AFTER_DRAIN) { E(acc, cur, wr, wc, fr, fq); S.done(cur); }
;         if (!has_next) break;
	s_add_i32 s14, s41, s23
	v_lshl_add_u64 v[216:217], v[216:217], 0, s[6:7]
	s_mov_b32 m0, s14
	ds_read_b128 v[184:187], v149 offset:49152
	ds_read_b128 v[188:191], v149 offset:50176
	ds_read_b128 v[192:195], v149 offset:51200
	ds_read_b128 v[196:199], v149 offset:52224
	ds_read_b128 v[200:203], v149 offset:53248
	ds_read_b128 v[204:207], v149 offset:54272
	ds_read_b128 v[208:211], v149 offset:55296
	ds_read_b128 v[212:215], v149 offset:56320
	global_load_lds_dwordx4 v[216:217], off
	s_add_i32 m0, s14, 0x2000
	s_add_u32 s14, s18, 0x58080
	v_lshl_add_u64 v[216:217], v[218:219], 0, s[6:7]
	s_addc_u32 s15, s19, 0
	s_add_i32 s18, s42, s23
	global_load_lds_dwordx4 v[216:217], off
	v_lshl_add_u64 v[216:217], s[14:15], 0, v[130:131]
	s_mov_b32 m0, s18
	s_nop 0
	global_load_lds_dwordx4 v[216:217], off
	v_lshl_add_u64 v[216:217], s[14:15], 0, v[134:135]
	s_add_i32 m0, s18, 0x2000
	s_nop 0
	global_load_lds_dwordx4 v[216:217], off
	v_lshl_add_u64 v[216:217], v[220:221], 0, s[6:7]
	s_mov_b32 m0, s31
	s_nop 0
	global_load_lds_dwordx4 v[216:217], off
	v_lshl_add_u64 v[216:217], v[222:223], 0, s[6:7]
	s_mov_b32 m0, s33
	s_nop 0
	global_load_lds_dwordx4 v[216:217], off
	s_waitcnt vmcnt(8)
	s_waitcnt lgkmcnt(0)
	s_barrier
	s_setprio 1
	s_waitcnt lgkmcnt(0)
	v_mfma_f32_16x16x32_bf16 v[60:63], v[152:155], v[184:187], v[60:63]
	v_mfma_f32_16x16x32_bf16 v[56:59], v[160:163], v[184:187], v[56:59]
	v_mfma_f32_16x16x32_bf16 v[44:47], v[152:155], v[192:195], v[44:47]
	v_mfma_f32_16x16x32_bf16 v[40:43], v[160:163], v[192:195], v[40:43]
	v_mfma_f32_16x16x32_bf16 v[28:31], v[152:155], v[200:203], v[28:31]
	v_mfma_f32_16x16x32_bf16 v[24:27], v[160:163], v[200:203], v[24:27]
	v_mfma_f32_16x16x32_bf16 v[12:15], v[152:155], v[208:211], v[12:15]
	v_mfma_f32_16x16x32_bf16 v[8:11], v[160:163], v[208:211], v[8:11]
	v_mfma_f32_16x16x32_bf16 v[60:63], v[156:159], v[188:191], v[60:63]
	v_mfma_f32_16x16x32_bf16 v[56:59], v[164:167], v[188:191], v[56:59]
	v_mfma_f32_16x16x32_bf16 v[44:47], v[156:159], v[196:199], v[44:47]
	v_mfma_f32_16x16x32_bf16 v[40:43], v[164:167], v[196:199], v[40:43]
	v_mfma_f32_16x16x32_bf16 v[28:31], v[156:159], v[204:207], v[28:31]
	v_mfma_f32_16x16x32_bf16 v[24:27], v[164:167], v[204:207], v[24:27]
	v_mfma_f32_16x16x32_bf16 v[12:15], v[156:159], v[212:215], v[12:15]
	v_mfma_f32_16x16x32_bf16 v[8:11], v[164:167], v[212:215], v[8:11]
	v_mfma_f32_16x16x32_bf16 v[52:55], v[168:171], v[184:187], v[52:55]
	v_mfma_f32_16x16x32_bf16 v[48:51], v[176:179], v[184:187], v[48:51]
	v_mfma_f32_16x16x32_bf16 v[36:39], v[168:171], v[192:195], v[36:39]
	v_mfma_f32_16x16x32_bf16 v[32:35], v[176:179], v[192:195], v[32:35]
	v_mfma_f32_16x16x32_bf16 v[20:23], v[168:171], v[200:203], v[20:23]
	v_mfma_f32_16x16x32_bf16 v[16:19], v[176:179], v[200:203], v[16:19]
	v_mfma_f32_16x16x32_bf16 v[4:7], v[168:171], v[208:211], v[4:7]
	v_mfma_f32_16x16x32_bf16 v[0:3], v[176:179], v[208:211], v[0:3]
	v_mfma_f32_16x16x32_bf16 v[52:55], v[172:175], v[188:191], v[52:55]
	v_mfma_f32_16x16x32_bf16 v[48:51], v[180:183], v[188:191], v[48:51]
	v_mfma_f32_16x16x32_bf16 v[36:39], v[172:175], v[196:199], v[36:39]
	v_mfma_f32_16x16x32_bf16 v[32:35], v[180:183], v[196:199], v[32:35]
	v_mfma_f32_16x16x32_bf16 v[20:23], v[172:175], v[204:207], v[20:23]
	v_mfma_f32_16x16x32_bf16 v[16:19], v[180:183], v[204:207], v[16:19]
	v_mfma_f32_16x16x32_bf16 v[4:7], v[172:175], v[212:215], v[4:7]
	v_mfma_f32_16x16x32_bf16 v[0:3], v[180:183], v[212:215], v[0:3]
	s_setprio 0
	s_barrier
	s_add_i32 s40, s40, 2
	s_add_u32 s13, s13, 0x100
	s_addc_u32 s39, s39, 0
	s_cmpk_lt_u32 s40, 0x56
	s_mov_b64 s[14:15], s[16:17]
	s_cbranch_scc1 .LBB0_3002
	s_andn2_b64 vcc, exec, s[8:9]
	s_cbranch_vccnz .LBB0_3005
	s_barrier
